# v038noprio
# speedup vs baseline: 1.0032x; 1.0032x over previous
;   #define STAGE(P,BASE,LD,br,kt) do{ const HALF* _u=(BASE)+(long)(br)*(((&(LD))==&lda)?lda_u:(LD))+(long)(kt)*G_BK; \
;     for(int _i=0;_i<2;++_i){ \
;       __builtin_amdgcn_global_load_lds((const unsigned*)(_u+(long)_i*(((&(LD))==&lda)?stepa:stepb)+((&(LD))==&lda?oa0:ob0)), \
;         (unsigned*)((char*)(P)+t5*16+_i*8192),16,0,0);}}while(0)
;   #define LDA(dst,b,h) for(int m=0;m<4;++m)for(int k=0;k<2;++k) \
;     dst[m][k]=*reinterpret_cast<const h8*>(la+(((b)*2+(h))*16384+m*2048+k*1024))
;   #define LDB(dst,b,h) for(int n=0;n<2;++n)for(int k=0;k<2;++k) \
;     dst[n][k]=*reinterpret_cast<const h8*>(lb+(((b)*2+(h))*16384+n*2048+k*1024))
;   #define MMA(ai,bj,At,Bt_) do{__builtin_amdgcn_s_setprio(1); \
;     for(int m=0;m<4;++m)for(int n=0;n<2;++n)for(int k=0;k<2;++k) \
;       acc[ai][bj][m][n]=__builtin_amdgcn_mfma_f32_16x16x32_f16(At[m][k],Bt_[n][k],acc[ai][bj][m][n],0,0,0); \
;     __builtin_amdgcn_s_setprio(0);}while(0)
;   #define WAIT_L(n) asm volatile("s_waitcnt lgkmcnt(" #n ")":::"memory")
;   #define BAR __builtin_amdgcn_s_barrier()
;   #define SCHED __builtin_amdgcn_sched_barrier(0)
;     ...
;     LDB(B0,0,0); SCHED; LDA(At,0,0); STAGE(SA(1,1),A,lda,G_HALF,t+1);
;     WAIT_L(8); BAR; WAIT_L(0); MMA(0,0,At,B0); BAR; SCHED;
;     LDB(B1,0,1); STAGE(SB(0,0),Bt,ldb,0,t+2);
;     BAR; WAIT_L(0); MMA(0,1,At,B1); BAR;
;     LDA(At,0,1); STAGE(SA(0,0),A,lda,0,t+2);
;     BAR; WAIT_L(0); MMA(1,0,At,B0); BAR; SCHED;
.LBB0_127:
	ds_read_b128 v[158:161], v133
	ds_read_b128 v[162:165], v133 offset:1024
	ds_read_b128 v[186:189], v133 offset:2048
	ds_read_b128 v[190:193], v133 offset:3072
	v_add_u32_e32 v148, 0xc000, v136
	v_lshl_add_u64 v[150:151], s[4:5], 0, v[128:129]
	s_mov_b64 s[14:15], 0x29ef0080
	v_readfirstlane_b32 s13, v148
	v_add_u32_e32 v149, 0xe000, v136
	v_lshl_add_u64 v[166:167], v[150:151], 0, s[14:15]
	s_mov_b32 m0, s13
	s_mov_b64 s[14:15], 0x29f10080
	v_readfirstlane_b32 s13, v149
	ds_read_b128 v[194:197], v132
	ds_read_b128 v[198:201], v132 offset:1024
	ds_read_b128 v[202:205], v132 offset:2048
	ds_read_b128 v[206:209], v132 offset:3072
	ds_read_b128 v[210:213], v132 offset:4096
	ds_read_b128 v[214:217], v132 offset:5120
	ds_read_b128 v[218:221], v132 offset:6144
	ds_read_b128 v[222:225], v132 offset:7168
	global_load_lds_dwordx4 v[166:167], off
	v_lshl_add_u64 v[166:167], v[150:151], 0, s[14:15]
	s_mov_b32 m0, s13
	s_nop 0
	global_load_lds_dwordx4 v[166:167], off
	s_waitcnt lgkmcnt(8)
	s_barrier
	s_waitcnt lgkmcnt(0)
	s_waitcnt lgkmcnt(0)
	v_mfma_f32_16x16x32_f16 v[124:127], v[194:197], v[158:161], v[124:127]
	v_mfma_f32_16x16x32_f16 v[120:123], v[194:197], v[186:189], v[120:123]
	v_mfma_f32_16x16x32_f16 v[116:119], v[202:205], v[158:161], v[116:119]
	v_mfma_f32_16x16x32_f16 v[112:115], v[202:205], v[186:189], v[112:115]
	v_mfma_f32_16x16x32_f16 v[108:111], v[210:213], v[158:161], v[108:111]
	v_mfma_f32_16x16x32_f16 v[104:107], v[210:213], v[186:189], v[104:107]
	v_mfma_f32_16x16x32_f16 v[100:103], v[218:221], v[158:161], v[100:103]
	v_mfma_f32_16x16x32_f16 v[96:99], v[218:221], v[186:189], v[96:99]
	v_mfma_f32_16x16x32_f16 v[124:127], v[198:201], v[162:165], v[124:127]
	v_mfma_f32_16x16x32_f16 v[120:123], v[198:201], v[190:193], v[120:123]
	v_mfma_f32_16x16x32_f16 v[116:119], v[206:209], v[162:165], v[116:119]
	v_mfma_f32_16x16x32_f16 v[112:115], v[206:209], v[190:193], v[112:115]
	v_mfma_f32_16x16x32_f16 v[108:111], v[214:217], v[162:165], v[108:111]
	v_mfma_f32_16x16x32_f16 v[104:107], v[214:217], v[190:193], v[104:107]
	v_mfma_f32_16x16x32_f16 v[100:103], v[222:225], v[162:165], v[100:103]
	v_mfma_f32_16x16x32_f16 v[96:99], v[222:225], v[190:193], v[96:99]
	s_barrier
	v_lshl_add_u64 v[166:167], s[6:7], 0, v[128:129]
	s_mov_b64 s[14:15], 0x1c00100
	v_readfirstlane_b32 s13, v134
	v_lshl_add_u64 v[168:169], v[166:167], 0, s[14:15]
	s_mov_b32 m0, s13
	s_mov_b64 s[14:15], 0x1c20100
	v_readfirstlane_b32 s13, v135
	ds_read_b128 v[226:229], v133 offset:16384
	ds_read_b128 v[230:233], v133 offset:17408
	ds_read_b128 v[234:237], v133 offset:18432
	ds_read_b128 v[238:241], v133 offset:19456
	global_load_lds_dwordx4 v[168:169], off
	v_lshl_add_u64 v[168:169], v[166:167], 0, s[14:15]
	s_mov_b32 m0, s13
	s_nop 0
	global_load_lds_dwordx4 v[168:169], off
	s_barrier
	s_waitcnt lgkmcnt(0)
	s_waitcnt lgkmcnt(0)
	v_mfma_f32_16x16x32_f16 v[92:95], v[194:197], v[226:229], v[92:95]
	v_mfma_f32_16x16x32_f16 v[88:91], v[194:197], v[234:237], v[88:91]
	v_mfma_f32_16x16x32_f16 v[84:87], v[202:205], v[226:229], v[84:87]
	v_mfma_f32_16x16x32_f16 v[80:83], v[202:205], v[234:237], v[80:83]
	v_mfma_f32_16x16x32_f16 v[76:79], v[210:213], v[226:229], v[76:79]
	v_mfma_f32_16x16x32_f16 v[68:71], v[210:213], v[234:237], v[68:71]
	v_mfma_f32_16x16x32_f16 v[64:67], v[218:221], v[226:229], v[64:67]
	v_mfma_f32_16x16x32_f16 v[60:63], v[218:221], v[234:237], v[60:63]
	v_mfma_f32_16x16x32_f16 v[92:95], v[198:201], v[230:233], v[92:95]
	v_mfma_f32_16x16x32_f16 v[88:91], v[198:201], v[238:241], v[88:91]
	v_mfma_f32_16x16x32_f16 v[84:87], v[206:209], v[230:233], v[84:87]
	v_mfma_f32_16x16x32_f16 v[80:83], v[206:209], v[238:241], v[80:83]
	v_mfma_f32_16x16x32_f16 v[76:79], v[214:217], v[230:233], v[76:79]
	v_mfma_f32_16x16x32_f16 v[68:71], v[214:217], v[238:241], v[68:71]
	v_mfma_f32_16x16x32_f16 v[64:67], v[222:225], v[230:233], v[64:67]
	v_mfma_f32_16x16x32_f16 v[60:63], v[222:225], v[238:241], v[60:63]
	s_mov_b64 s[14:15], 0x29eb0100
	v_readfirstlane_b32 s13, v136
	v_lshl_add_u64 v[168:169], v[150:151], 0, s[14:15]
	s_mov_b32 m0, s13
	s_mov_b64 s[14:15], 0x29ed0100
	v_readfirstlane_b32 s13, v137
	s_barrier
	ds_read_b128 v[194:197], v132 offset:16384
	ds_read_b128 v[198:201], v132 offset:17408
	ds_read_b128 v[202:205], v132 offset:18432
	ds_read_b128 v[206:209], v132 offset:19456
	ds_read_b128 v[210:213], v132 offset:20480
	ds_read_b128 v[214:217], v132 offset:21504
	ds_read_b128 v[218:221], v132 offset:22528
	ds_read_b128 v[222:225], v132 offset:23552
	global_load_lds_dwordx4 v[168:169], off
	v_lshl_add_u64 v[168:169], v[150:151], 0, s[14:15]
	s_mov_b32 m0, s13
	s_nop 0
	global_load_lds_dwordx4 v[168:169], off
	s_barrier
	s_waitcnt lgkmcnt(0)
	s_waitcnt lgkmcnt(0)
	v_mfma_f32_16x16x32_f16 v[56:59], v[194:197], v[158:161], v[56:59]
	v_mfma_f32_16x16x32_f16 v[52:55], v[194:197], v[186:189], v[52:55]
	v_mfma_f32_16x16x32_f16 v[48:51], v[202:205], v[158:161], v[48:51]
	v_mfma_f32_16x16x32_f16 v[44:47], v[202:205], v[186:189], v[44:47]
	v_mfma_f32_16x16x32_f16 v[40:43], v[210:213], v[158:161], v[40:43]
	v_mfma_f32_16x16x32_f16 v[36:39], v[210:213], v[186:189], v[36:39]
	v_mfma_f32_16x16x32_f16 v[32:35], v[218:221], v[158:161], v[32:35]
	v_mfma_f32_16x16x32_f16 v[28:31], v[218:221], v[186:189], v[28:31]
	v_mfma_f32_16x16x32_f16 v[56:59], v[198:201], v[162:165], v[56:59]
	v_mfma_f32_16x16x32_f16 v[52:55], v[198:201], v[190:193], v[52:55]
	v_mfma_f32_16x16x32_f16 v[48:51], v[206:209], v[162:165], v[48:51]
	v_mfma_f32_16x16x32_f16 v[44:47], v[206:209], v[190:193], v[44:47]
	v_mfma_f32_16x16x32_f16 v[40:43], v[214:217], v[162:165], v[40:43]
	v_mfma_f32_16x16x32_f16 v[36:39], v[214:217], v[190:193], v[36:39]
	v_mfma_f32_16x16x32_f16 v[32:35], v[222:225], v[162:165], v[32:35]
	v_mfma_f32_16x16x32_f16 v[28:31], v[222:225], v[190:193], v[28:31]
	s_barrier
;   #define STAGE(P,BASE,LD,br,kt) do{ const HALF* _u=(BASE)+(long)(br)*(((&(LD))==&lda)?lda_u:(LD))+(long)(kt)*G_BK; \
;     for(int _i=0;_i<2;++_i){ \
;       __builtin_amdgcn_global_load_lds((const unsigned*)(_u+(long)_i*(((&(LD))==&lda)?stepa:stepb)+((&(LD))==&lda?oa0:ob0)), \
;         (unsigned*)((char*)(P)+t5*16+_i*8192),16,0,0);}}while(0)
;   #define LDA(dst,b,h) for(int m=0;m<4;++m)for(int k=0;k<2;++k) \
;     dst[m][k]=*reinterpret_cast<const h8*>(la+(((b)*2+(h))*16384+m*2048+k*1024))
;   #define LDB(dst,b,h) for(int n=0;n<2;++n)for(int k=0;k<2;++k) \
;     dst[n][k]=*reinterpret_cast<const h8*>(lb+(((b)*2+(h))*16384+n*2048+k*1024))
;   #define MMA(ai,bj,At,Bt_) do{__builtin_amdgcn_s_setprio(1); \
;     for(int m=0;m<4;++m)for(int n=0;n<2;++n)for(int k=0;k<2;++k) \
;       acc[ai][bj][m][n]=__builtin_amdgcn_mfma_f32_16x16x32_f16(At[m][k],Bt_[n][k],acc[ai][bj][m][n],0,0,0); \
;     __builtin_amdgcn_s_setprio(0);}while(0)
;   #define WAIT_V(n) asm volatile("s_waitcnt vmcnt(" #n ")":::"memory")
;   #define WAIT_L(n) asm volatile("s_waitcnt lgkmcnt(" #n ")":::"memory")
;   #define BAR __builtin_amdgcn_s_barrier()
;   #define SCHED __builtin_amdgcn_sched_barrier(0)
;     ...
;     STAGE(SB(0,1),Bt,ldb,G_HALF,t+2);
;     WAIT_V(6); BAR; MMA(1,1,At,B1); BAR;
;     LDB(B0,1,0); SCHED; LDA(At,1,0); STAGE(SA(0,1),A,lda,G_HALF,t+2);
;     WAIT_L(8); BAR; WAIT_L(0); MMA(0,0,At,B0); BAR; SCHED;
;     LDB(B1,1,1); STAGE(SB(1,0),Bt,ldb,0,t+3);
;     BAR; WAIT_L(0); MMA(0,1,At,B1); BAR;
;     LDA(At,1,1); STAGE(SA(1,0),A,lda,0,t+3);
	s_mov_b64 s[14:15], 0x1c40100
	v_readfirstlane_b32 s13, v138
	v_lshl_add_u64 v[158:159], v[166:167], 0, s[14:15]
	s_mov_b32 m0, s13
	s_mov_b64 s[14:15], 0x1c60100
	v_readfirstlane_b32 s13, v139
	global_load_lds_dwordx4 v[158:159], off
	v_lshl_add_u64 v[158:159], v[166:167], 0, s[14:15]
	s_mov_b32 m0, s13
	s_nop 0
	global_load_lds_dwordx4 v[158:159], off
	s_waitcnt vmcnt(6)
	s_barrier
	v_mfma_f32_16x16x32_f16 v[24:27], v[194:197], v[226:229], v[24:27]
	v_mfma_f32_16x16x32_f16 v[20:23], v[194:197], v[234:237], v[20:23]
	v_mfma_f32_16x16x32_f16 v[16:19], v[202:205], v[226:229], v[16:19]
	v_mfma_f32_16x16x32_f16 v[12:15], v[202:205], v[234:237], v[12:15]
	v_mfma_f32_16x16x32_f16 v[8:11], v[210:213], v[226:229], v[8:11]
	v_mfma_f32_16x16x32_f16 v[4:7], v[210:213], v[234:237], v[4:7]
	v_mfma_f32_16x16x32_f16 v[0:3], v[218:221], v[226:229], v[0:3]
	v_mfma_f32_16x16x32_f16 v[72:75], v[218:221], v[234:237], v[72:75]
	v_mfma_f32_16x16x32_f16 v[24:27], v[198:201], v[230:233], v[24:27]
	v_mfma_f32_16x16x32_f16 v[20:23], v[198:201], v[238:241], v[20:23]
	v_mfma_f32_16x16x32_f16 v[16:19], v[206:209], v[230:233], v[16:19]
	v_mfma_f32_16x16x32_f16 v[12:15], v[206:209], v[238:241], v[12:15]
	v_mfma_f32_16x16x32_f16 v[8:11], v[214:217], v[230:233], v[8:11]
	v_mfma_f32_16x16x32_f16 v[4:7], v[214:217], v[238:241], v[4:7]
	v_mfma_f32_16x16x32_f16 v[0:3], v[222:225], v[230:233], v[0:3]
	v_mfma_f32_16x16x32_f16 v[72:75], v[222:225], v[238:241], v[72:75]
	s_barrier
	ds_read_b128 v[158:161], v133 offset:32768
	ds_read_b128 v[162:165], v133 offset:33792
	ds_read_b128 v[186:189], v133 offset:34816
	ds_read_b128 v[190:193], v133 offset:35840
	s_mov_b64 s[14:15], 0x29ef0100
	v_readfirstlane_b32 s13, v140
	v_lshl_add_u64 v[168:169], v[150:151], 0, s[14:15]
	s_mov_b32 m0, s13
	s_mov_b64 s[14:15], 0x29f10100
	v_readfirstlane_b32 s13, v141
	ds_read_b128 v[194:197], v132 offset:32768
	ds_read_b128 v[198:201], v132 offset:33792
	ds_read_b128 v[202:205], v132 offset:34816
	ds_read_b128 v[206:209], v132 offset:35840
	ds_read_b128 v[210:213], v132 offset:36864
	ds_read_b128 v[214:217], v132 offset:37888
	ds_read_b128 v[218:221], v132 offset:38912
	ds_read_b128 v[222:225], v132 offset:39936
	global_load_lds_dwordx4 v[168:169], off
	v_lshl_add_u64 v[168:169], v[150:151], 0, s[14:15]
	s_mov_b32 m0, s13
	s_nop 0
	global_load_lds_dwordx4 v[168:169], off
	s_waitcnt lgkmcnt(8)
	s_barrier
	s_waitcnt lgkmcnt(0)
	s_waitcnt lgkmcnt(0)
	v_mfma_f32_16x16x32_f16 v[124:127], v[194:197], v[158:161], v[124:127]
	v_mfma_f32_16x16x32_f16 v[120:123], v[194:197], v[186:189], v[120:123]
	v_mfma_f32_16x16x32_f16 v[116:119], v[202:205], v[158:161], v[116:119]
	v_mfma_f32_16x16x32_f16 v[112:115], v[202:205], v[186:189], v[112:115]
	v_mfma_f32_16x16x32_f16 v[108:111], v[210:213], v[158:161], v[108:111]
	v_mfma_f32_16x16x32_f16 v[104:107], v[210:213], v[186:189], v[104:107]
	v_mfma_f32_16x16x32_f16 v[100:103], v[218:221], v[158:161], v[100:103]
	v_mfma_f32_16x16x32_f16 v[96:99], v[218:221], v[186:189], v[96:99]
	v_mfma_f32_16x16x32_f16 v[124:127], v[198:201], v[162:165], v[124:127]
	v_mfma_f32_16x16x32_f16 v[120:123], v[198:201], v[190:193], v[120:123]
	v_mfma_f32_16x16x32_f16 v[116:119], v[206:209], v[162:165], v[116:119]
	v_mfma_f32_16x16x32_f16 v[112:115], v[206:209], v[190:193], v[112:115]
	v_mfma_f32_16x16x32_f16 v[108:111], v[214:217], v[162:165], v[108:111]
	v_mfma_f32_16x16x32_f16 v[104:107], v[214:217], v[190:193], v[104:107]
	v_mfma_f32_16x16x32_f16 v[100:103], v[222:225], v[162:165], v[100:103]
	v_mfma_f32_16x16x32_f16 v[96:99], v[222:225], v[190:193], v[96:99]
	s_barrier
	s_mov_b64 s[14:15], 0x1c00180
	v_readfirstlane_b32 s13, v142
	v_lshl_add_u64 v[168:169], v[166:167], 0, s[14:15]
	s_mov_b32 m0, s13
	s_mov_b64 s[14:15], 0x1c20180
	v_readfirstlane_b32 s13, v143
	ds_read_b128 v[226:229], v133 offset:49152
	ds_read_b128 v[230:233], v133 offset:50176
	ds_read_b128 v[234:237], v133 offset:51200
	ds_read_b128 v[238:241], v133 offset:52224
	global_load_lds_dwordx4 v[168:169], off
	v_lshl_add_u64 v[168:169], v[166:167], 0, s[14:15]
	s_mov_b32 m0, s13
	s_nop 0
	global_load_lds_dwordx4 v[168:169], off
	s_barrier
	s_waitcnt lgkmcnt(0)
	s_waitcnt lgkmcnt(0)
	v_mfma_f32_16x16x32_f16 v[92:95], v[194:197], v[226:229], v[92:95]
	v_mfma_f32_16x16x32_f16 v[88:91], v[194:197], v[234:237], v[88:91]
	v_mfma_f32_16x16x32_f16 v[84:87], v[202:205], v[226:229], v[84:87]
	v_mfma_f32_16x16x32_f16 v[80:83], v[202:205], v[234:237], v[80:83]
	v_mfma_f32_16x16x32_f16 v[76:79], v[210:213], v[226:229], v[76:79]
	v_mfma_f32_16x16x32_f16 v[68:71], v[210:213], v[234:237], v[68:71]
	v_mfma_f32_16x16x32_f16 v[64:67], v[218:221], v[226:229], v[64:67]
	v_mfma_f32_16x16x32_f16 v[60:63], v[218:221], v[234:237], v[60:63]
	v_mfma_f32_16x16x32_f16 v[92:95], v[198:201], v[230:233], v[92:95]
	v_mfma_f32_16x16x32_f16 v[88:91], v[198:201], v[238:241], v[88:91]
	v_mfma_f32_16x16x32_f16 v[84:87], v[206:209], v[230:233], v[84:87]
	v_mfma_f32_16x16x32_f16 v[80:83], v[206:209], v[238:241], v[80:83]
	v_mfma_f32_16x16x32_f16 v[76:79], v[214:217], v[230:233], v[76:79]
	v_mfma_f32_16x16x32_f16 v[68:71], v[214:217], v[238:241], v[68:71]
	v_mfma_f32_16x16x32_f16 v[64:67], v[222:225], v[230:233], v[64:67]
	v_mfma_f32_16x16x32_f16 v[60:63], v[222:225], v[238:241], v[60:63]
	s_mov_b64 s[14:15], 0x29eb0180
	v_readfirstlane_b32 s13, v144
	v_lshl_add_u64 v[168:169], v[150:151], 0, s[14:15]
	s_mov_b32 m0, s13
	s_mov_b64 s[14:15], 0x29ed0180
	v_readfirstlane_b32 s13, v145
	s_barrier
;   #define STAGE(P,BASE,LD,br,kt) do{ const HALF* _u=(BASE)+(long)(br)*(((&(LD))==&lda)?lda_u:(LD))+(long)(kt)*G_BK; \
;     for(int _i=0;_i<2;++_i){ \
;       __builtin_amdgcn_global_load_lds((const unsigned*)(_u+(long)_i*(((&(LD))==&lda)?stepa:stepb)+((&(LD))==&lda?oa0:ob0)), \
;         (unsigned*)((char*)(P)+t5*16+_i*8192),16,0,0);}}while(0)
;   #define LDA(dst,b,h) for(int m=0;m<4;++m)for(int k=0;k<2;++k) \
;     dst[m][k]=*reinterpret_cast<const h8*>(la+(((b)*2+(h))*16384+m*2048+k*1024))
;   #define LDB(dst,b,h) for(int n=0;n<2;++n)for(int k=0;k<2;++k) \
;     dst[n][k]=*reinterpret_cast<const h8*>(lb+(((b)*2+(h))*16384+n*2048+k*1024))
;   #define MMA(ai,bj,At,Bt_) do{__builtin_amdgcn_s_setprio(1); \
;     for(int m=0;m<4;++m)for(int n=0;n<2;++n)for(int k=0;k<2;++k) \
;       acc[ai][bj][m][n]=__builtin_amdgcn_mfma_f32_16x16x32_f16(At[m][k],Bt_[n][k],acc[ai][bj][m][n],0,0,0); \
;     __builtin_amdgcn_s_setprio(0);}while(0)
;   #define WAIT_V(n) asm volatile("s_waitcnt vmcnt(" #n ")":::"memory")
;   #define WAIT_L(n) asm volatile("s_waitcnt lgkmcnt(" #n ")":::"memory")
;   #define BAR __builtin_amdgcn_s_barrier()
;   #define SCHED __builtin_amdgcn_sched_barrier(0)
;     ...
;     LDA(At,1,1); STAGE(SA(1,0),A,lda,0,t+3);
;     BAR; WAIT_L(0); MMA(1,0,At,B0); BAR; SCHED;
;     STAGE(SB(1,1),Bt,ldb,G_HALF,t+3);
;     WAIT_V(6); BAR; MMA(1,1,At,B1); BAR;
;   }
;   { LDB(B0,0,0); LDA(At,0,0); STAGE(SA(1,1),A,lda,G_HALF,nt-1);
;     BAR; WAIT_L(0); MMA(0,0,At,B0); BAR;
;     LDB(B1,0,1); BAR; WAIT_L(0); MMA(0,1,At,B1); BAR;
	ds_read_b128 v[194:197], v132 offset:49152
	ds_read_b128 v[198:201], v132 offset:50176
	ds_read_b128 v[202:205], v132 offset:51200
	ds_read_b128 v[206:209], v132 offset:52224
	ds_read_b128 v[210:213], v132 offset:53248
	ds_read_b128 v[214:217], v132 offset:54272
	ds_read_b128 v[218:221], v132 offset:55296
	ds_read_b128 v[222:225], v132 offset:56320
	global_load_lds_dwordx4 v[168:169], off
	v_lshl_add_u64 v[150:151], v[150:151], 0, s[14:15]
	s_mov_b32 m0, s13
	s_nop 0
	global_load_lds_dwordx4 v[150:151], off
	s_barrier
	s_waitcnt lgkmcnt(0)
	s_waitcnt lgkmcnt(0)
	v_mfma_f32_16x16x32_f16 v[56:59], v[194:197], v[158:161], v[56:59]
	v_mfma_f32_16x16x32_f16 v[52:55], v[194:197], v[186:189], v[52:55]
	v_mfma_f32_16x16x32_f16 v[48:51], v[202:205], v[158:161], v[48:51]
	v_mfma_f32_16x16x32_f16 v[44:47], v[202:205], v[186:189], v[44:47]
	v_mfma_f32_16x16x32_f16 v[40:43], v[210:213], v[158:161], v[40:43]
	v_mfma_f32_16x16x32_f16 v[36:39], v[210:213], v[186:189], v[36:39]
	v_mfma_f32_16x16x32_f16 v[32:35], v[218:221], v[158:161], v[32:35]
	v_mfma_f32_16x16x32_f16 v[28:31], v[218:221], v[186:189], v[28:31]
	v_mfma_f32_16x16x32_f16 v[56:59], v[198:201], v[162:165], v[56:59]
	v_mfma_f32_16x16x32_f16 v[52:55], v[198:201], v[190:193], v[52:55]
	v_mfma_f32_16x16x32_f16 v[48:51], v[206:209], v[162:165], v[48:51]
	v_mfma_f32_16x16x32_f16 v[44:47], v[206:209], v[190:193], v[44:47]
	v_mfma_f32_16x16x32_f16 v[40:43], v[214:217], v[162:165], v[40:43]
	v_mfma_f32_16x16x32_f16 v[36:39], v[214:217], v[190:193], v[36:39]
	v_mfma_f32_16x16x32_f16 v[32:35], v[222:225], v[162:165], v[32:35]
	v_mfma_f32_16x16x32_f16 v[28:31], v[222:225], v[190:193], v[28:31]
	s_barrier
	s_mov_b64 s[14:15], 0x1c40180
	v_readfirstlane_b32 s13, v146
	v_lshl_add_u64 v[150:151], v[166:167], 0, s[14:15]
	s_mov_b32 m0, s13
	s_mov_b64 s[14:15], 0x1c60180
	v_readfirstlane_b32 s13, v147
	global_load_lds_dwordx4 v[150:151], off
	v_lshl_add_u64 v[150:151], v[166:167], 0, s[14:15]
	s_mov_b32 m0, s13
	s_nop 0
	global_load_lds_dwordx4 v[150:151], off
	s_waitcnt vmcnt(6)
	s_barrier
	v_mfma_f32_16x16x32_f16 v[24:27], v[194:197], v[226:229], v[24:27]
	v_mfma_f32_16x16x32_f16 v[20:23], v[194:197], v[234:237], v[20:23]
	v_mfma_f32_16x16x32_f16 v[16:19], v[202:205], v[226:229], v[16:19]
	v_mfma_f32_16x16x32_f16 v[12:15], v[202:205], v[234:237], v[12:15]
	v_mfma_f32_16x16x32_f16 v[8:11], v[210:213], v[226:229], v[8:11]
	v_mfma_f32_16x16x32_f16 v[4:7], v[210:213], v[234:237], v[4:7]
	v_mfma_f32_16x16x32_f16 v[0:3], v[218:221], v[226:229], v[0:3]
	v_mfma_f32_16x16x32_f16 v[72:75], v[218:221], v[234:237], v[72:75]
	v_mfma_f32_16x16x32_f16 v[24:27], v[198:201], v[230:233], v[24:27]
	v_mfma_f32_16x16x32_f16 v[20:23], v[198:201], v[238:241], v[20:23]
	v_mfma_f32_16x16x32_f16 v[16:19], v[206:209], v[230:233], v[16:19]
	v_mfma_f32_16x16x32_f16 v[12:15], v[206:209], v[238:241], v[12:15]
	v_mfma_f32_16x16x32_f16 v[8:11], v[214:217], v[230:233], v[8:11]
	v_mfma_f32_16x16x32_f16 v[4:7], v[214:217], v[238:241], v[4:7]
	v_mfma_f32_16x16x32_f16 v[0:3], v[222:225], v[230:233], v[0:3]
	v_mfma_f32_16x16x32_f16 v[72:75], v[222:225], v[238:241], v[72:75]
	s_add_i32 s12, s12, 2
	s_add_u32 s6, s6, 0x100
	s_addc_u32 s7, s7, 0
	s_add_u32 s4, s4, 0x100
	s_addc_u32 s5, s5, 0
	s_cmp_lt_u32 s12, 12
	s_barrier
	s_cbranch_scc1 .LBB0_127
	v_lshl_add_u64 v[128:129], v[152:153], 1, s[2:3]
	s_mov_b64 s[2:3], 0x40780
	v_lshl_add_u64 v[146:147], v[128:129], 0, s[2:3]
	v_readfirstlane_b32 s2, v148
	s_mov_b32 m0, s2
	s_mov_b64 s[2:3], 0x60780
	v_lshl_add_u64 v[128:129], v[128:129], 0, s[2:3]
	v_readfirstlane_b32 s2, v149
	ds_read_b128 v[134:137], v133
	ds_read_b128 v[138:141], v133 offset:1024
	ds_read_b128 v[142:145], v133 offset:2048
	ds_read_b128 v[158:161], v133 offset:3072
	ds_read_b128 v[162:165], v132
	ds_read_b128 v[186:189], v132 offset:1024
	ds_read_b128 v[190:193], v132 offset:2048
	ds_read_b128 v[194:197], v132 offset:3072
	ds_read_b128 v[198:201], v132 offset:4096
	ds_read_b128 v[202:205], v132 offset:5120
	ds_read_b128 v[206:209], v132 offset:6144
	ds_read_b128 v[210:213], v132 offset:7168
	global_load_lds_dwordx4 v[146:147], off
	s_mov_b32 m0, s2
	s_nop 0
	global_load_lds_dwordx4 v[128:129], off
	s_barrier
	s_waitcnt lgkmcnt(0)
	s_waitcnt lgkmcnt(0)
	v_mfma_f32_16x16x32_f16 v[124:127], v[162:165], v[134:137], v[124:127]
	v_mfma_f32_16x16x32_f16 v[120:123], v[162:165], v[142:145], v[120:123]
	v_mfma_f32_16x16x32_f16 v[116:119], v[190:193], v[134:137], v[116:119]
	v_mfma_f32_16x16x32_f16 v[112:115], v[190:193], v[142:145], v[112:115]
	v_mfma_f32_16x16x32_f16 v[108:111], v[198:201], v[134:137], v[108:111]
	v_mfma_f32_16x16x32_f16 v[104:107], v[198:201], v[142:145], v[104:107]
	v_mfma_f32_16x16x32_f16 v[100:103], v[206:209], v[134:137], v[100:103]
	v_mfma_f32_16x16x32_f16 v[96:99], v[206:209], v[142:145], v[96:99]
	v_mfma_f32_16x16x32_f16 v[124:127], v[186:189], v[138:141], v[124:127]
	v_mfma_f32_16x16x32_f16 v[120:123], v[186:189], v[158:161], v[120:123]
	v_mfma_f32_16x16x32_f16 v[116:119], v[194:197], v[138:141], v[116:119]
	v_mfma_f32_16x16x32_f16 v[112:115], v[194:197], v[158:161], v[112:115]
	v_mfma_f32_16x16x32_f16 v[108:111], v[202:205], v[138:141], v[108:111]
	v_mfma_f32_16x16x32_f16 v[104:107], v[202:205], v[158:161], v[104:107]
	v_mfma_f32_16x16x32_f16 v[100:103], v[210:213], v[138:141], v[100:103]
	v_mfma_f32_16x16x32_f16 v[96:99], v[210:213], v[158:161], v[96:99]
	s_barrier
	ds_read_b128 v[146:149], v133 offset:16384
	ds_read_b128 v[214:217], v133 offset:17408
	ds_read_b128 v[218:221], v133 offset:18432
	ds_read_b128 v[222:225], v133 offset:19456
	s_barrier
;   #define LDA(dst,b,h) for(int m=0;m<4;++m)for(int k=0;k<2;++k) \
;     dst[m][k]=*reinterpret_cast<const h8*>(la+(((b)*2+(h))*16384+m*2048+k*1024))
;   #define LDB(dst,b,h) for(int n=0;n<2;++n)for(int k=0;k<2;++k) \
;     dst[n][k]=*reinterpret_cast<const h8*>(lb+(((b)*2+(h))*16384+n*2048+k*1024))
;   #define MMA(ai,bj,At,Bt_) do{__builtin_amdgcn_s_setprio(1); \
;     for(int m=0;m<4;++m)for(int n=0;n<2;++n)for(int k=0;k<2;++k) \
;       acc[ai][bj][m][n]=__builtin_amdgcn_mfma_f32_16x16x32_f16(At[m][k],Bt_[n][k],acc[ai][bj][m][n],0,0,0); \
;     __builtin_amdgcn_s_setprio(0);}while(0)
;   #define WAIT_V(n) asm volatile("s_waitcnt vmcnt(" #n ")":::"memory")
;   #define WAIT_L(n) asm volatile("s_waitcnt lgkmcnt(" #n ")":::"memory")
;   #define BAR __builtin_amdgcn_s_barrier()
;     ...
;     LDB(B1,0,1); BAR; WAIT_L(0); MMA(0,1,At,B1); BAR;
;     LDA(At,0,1); WAIT_V(4); BAR; WAIT_L(0); MMA(1,0,At,B0); MMA(1,1,At,B1); BAR; }
;   { LDB(B0,1,0); LDA(At,1,0); WAIT_V(2); BAR; WAIT_L(0); MMA(0,0,At,B0); BAR;
	s_waitcnt lgkmcnt(0)
	s_waitcnt lgkmcnt(0)
	v_mfma_f32_16x16x32_f16 v[92:95], v[162:165], v[146:149], v[92:95]
	v_mfma_f32_16x16x32_f16 v[88:91], v[162:165], v[218:221], v[88:91]
	v_mfma_f32_16x16x32_f16 v[84:87], v[190:193], v[146:149], v[84:87]
	v_mfma_f32_16x16x32_f16 v[80:83], v[190:193], v[218:221], v[80:83]
	v_mfma_f32_16x16x32_f16 v[76:79], v[198:201], v[146:149], v[76:79]
	v_mfma_f32_16x16x32_f16 v[68:71], v[198:201], v[218:221], v[68:71]
	v_mfma_f32_16x16x32_f16 v[64:67], v[206:209], v[146:149], v[64:67]
	v_mfma_f32_16x16x32_f16 v[60:63], v[206:209], v[218:221], v[60:63]
	v_mfma_f32_16x16x32_f16 v[92:95], v[186:189], v[214:217], v[92:95]
	v_mfma_f32_16x16x32_f16 v[88:91], v[186:189], v[222:225], v[88:91]
	v_mfma_f32_16x16x32_f16 v[84:87], v[194:197], v[214:217], v[84:87]
	v_mfma_f32_16x16x32_f16 v[80:83], v[194:197], v[222:225], v[80:83]
	v_mfma_f32_16x16x32_f16 v[76:79], v[202:205], v[214:217], v[76:79]
	v_mfma_f32_16x16x32_f16 v[68:71], v[202:205], v[222:225], v[68:71]
	v_mfma_f32_16x16x32_f16 v[64:67], v[210:213], v[214:217], v[64:67]
	v_mfma_f32_16x16x32_f16 v[60:63], v[210:213], v[222:225], v[60:63]
	s_barrier
	ds_read_b128 v[162:165], v132 offset:16384
	ds_read_b128 v[186:189], v132 offset:17408
	ds_read_b128 v[190:193], v132 offset:18432
	ds_read_b128 v[194:197], v132 offset:19456
	ds_read_b128 v[198:201], v132 offset:20480
	ds_read_b128 v[202:205], v132 offset:21504
	ds_read_b128 v[206:209], v132 offset:22528
	ds_read_b128 v[210:213], v132 offset:23552
	s_waitcnt vmcnt(4)
	s_barrier
	s_waitcnt lgkmcnt(0)
	s_waitcnt lgkmcnt(0)
	v_mfma_f32_16x16x32_f16 v[56:59], v[162:165], v[134:137], v[56:59]
	v_mfma_f32_16x16x32_f16 v[52:55], v[162:165], v[142:145], v[52:55]
	v_mfma_f32_16x16x32_f16 v[48:51], v[190:193], v[134:137], v[48:51]
	v_mfma_f32_16x16x32_f16 v[44:47], v[190:193], v[142:145], v[44:47]
	v_mfma_f32_16x16x32_f16 v[40:43], v[198:201], v[134:137], v[40:43]
	v_mfma_f32_16x16x32_f16 v[36:39], v[198:201], v[142:145], v[36:39]
	v_mfma_f32_16x16x32_f16 v[32:35], v[206:209], v[134:137], v[32:35]
	v_mfma_f32_16x16x32_f16 v[28:31], v[206:209], v[142:145], v[28:31]
	v_mfma_f32_16x16x32_f16 v[56:59], v[186:189], v[138:141], v[56:59]
	v_mfma_f32_16x16x32_f16 v[52:55], v[186:189], v[158:161], v[52:55]
	v_mfma_f32_16x16x32_f16 v[48:51], v[194:197], v[138:141], v[48:51]
	v_mfma_f32_16x16x32_f16 v[44:47], v[194:197], v[158:161], v[44:47]
	v_mfma_f32_16x16x32_f16 v[40:43], v[202:205], v[138:141], v[40:43]
	v_mfma_f32_16x16x32_f16 v[36:39], v[202:205], v[158:161], v[36:39]
	v_mfma_f32_16x16x32_f16 v[32:35], v[210:213], v[138:141], v[32:35]
	v_mfma_f32_16x16x32_f16 v[28:31], v[210:213], v[158:161], v[28:31]
	v_mfma_f32_16x16x32_f16 v[24:27], v[162:165], v[146:149], v[24:27]
	v_mfma_f32_16x16x32_f16 v[20:23], v[162:165], v[218:221], v[20:23]
	v_mfma_f32_16x16x32_f16 v[16:19], v[190:193], v[146:149], v[16:19]
	v_mfma_f32_16x16x32_f16 v[12:15], v[190:193], v[218:221], v[12:15]
	v_mfma_f32_16x16x32_f16 v[8:11], v[198:201], v[146:149], v[8:11]
	v_mfma_f32_16x16x32_f16 v[4:7], v[198:201], v[218:221], v[4:7]
	v_mfma_f32_16x16x32_f16 v[0:3], v[206:209], v[146:149], v[0:3]
	v_mfma_f32_16x16x32_f16 v[24:27], v[186:189], v[214:217], v[24:27]
	v_mfma_f32_16x16x32_f16 v[20:23], v[186:189], v[222:225], v[20:23]
	v_mfma_f32_16x16x32_f16 v[16:19], v[194:197], v[214:217], v[16:19]
	v_mfma_f32_16x16x32_f16 v[12:15], v[194:197], v[222:225], v[12:15]
	v_mfma_f32_16x16x32_f16 v[8:11], v[202:205], v[214:217], v[8:11]
	v_mfma_f32_16x16x32_f16 v[4:7], v[202:205], v[222:225], v[4:7]
	v_mfma_f32_16x16x32_f16 v[0:3], v[210:213], v[214:217], v[0:3]
	v_mfma_f32_16x16x32_f16 v[72:75], v[206:209], v[218:221], v[72:75]
	v_mfma_f32_16x16x32_f16 v[134:137], v[210:213], v[222:225], v[72:75]
	s_barrier
	ds_read_b128 v[138:141], v133 offset:32768
	ds_read_b128 v[142:145], v133 offset:33792
	ds_read_b128 v[146:149], v133 offset:34816
	ds_read_b128 v[158:161], v133 offset:35840
	s_nop 0
	ds_read_b128 v[72:75], v132 offset:32768
	ds_read_b128 v[162:165], v132 offset:33792
	ds_read_b128 v[186:189], v132 offset:34816
	ds_read_b128 v[190:193], v132 offset:35840
	ds_read_b128 v[194:197], v132 offset:36864
	ds_read_b128 v[198:201], v132 offset:37888
	ds_read_b128 v[202:205], v132 offset:38912
	ds_read_b128 v[206:209], v132 offset:39936
	s_waitcnt vmcnt(2)
	s_barrier
;   #define LDA(dst,b,h) for(int m=0;m<4;++m)for(int k=0;k<2;++k) \
;     dst[m][k]=*reinterpret_cast<const h8*>(la+(((b)*2+(h))*16384+m*2048+k*1024))
;   #define LDB(dst,b,h) for(int n=0;n<2;++n)for(int k=0;k<2;++k) \
;     dst[n][k]=*reinterpret_cast<const h8*>(lb+(((b)*2+(h))*16384+n*2048+k*1024))
;   #define MMA(ai,bj,At,Bt_) do{__builtin_amdgcn_s_setprio(1); \
;     for(int m=0;m<4;++m)for(int n=0;n<2;++n)for(int k=0;k<2;++k) \
;       acc[ai][bj][m][n]=__builtin_amdgcn_mfma_f32_16x16x32_f16(At[m][k],Bt_[n][k],acc[ai][bj][m][n],0,0,0); \
;     __builtin_amdgcn_s_setprio(0);}while(0)
;   #define WAIT_V(n) asm volatile("s_waitcnt vmcnt(" #n ")":::"memory")
;   #define WAIT_L(n) asm volatile("s_waitcnt lgkmcnt(" #n ")":::"memory")
;   #define BAR __builtin_amdgcn_s_barrier()
;     ...
;   { LDB(B0,1,0); LDA(At,1,0); WAIT_V(2); BAR; WAIT_L(0); MMA(0,0,At,B0); BAR;
;     LDB(B1,1,1); WAIT_V(0); BAR; WAIT_L(0); MMA(0,1,At,B1); BAR;
;     LDA(At,1,1); BAR; WAIT_L(0); MMA(1,0,At,B0); MMA(1,1,At,B1); BAR; }
;   if(wr==0)BAR;
	s_waitcnt lgkmcnt(0)
	s_waitcnt lgkmcnt(0)
	v_mfma_f32_16x16x32_f16 v[124:127], v[72:75], v[138:141], v[124:127]
	v_mfma_f32_16x16x32_f16 v[120:123], v[72:75], v[146:149], v[120:123]
	v_mfma_f32_16x16x32_f16 v[116:119], v[186:189], v[138:141], v[116:119]
	v_mfma_f32_16x16x32_f16 v[112:115], v[186:189], v[146:149], v[112:115]
	v_mfma_f32_16x16x32_f16 v[108:111], v[194:197], v[138:141], v[108:111]
	v_mfma_f32_16x16x32_f16 v[104:107], v[194:197], v[146:149], v[104:107]
	v_mfma_f32_16x16x32_f16 v[100:103], v[202:205], v[138:141], v[100:103]
	v_mfma_f32_16x16x32_f16 v[96:99], v[202:205], v[146:149], v[96:99]
	v_mfma_f32_16x16x32_f16 v[124:127], v[162:165], v[142:145], v[124:127]
	v_mfma_f32_16x16x32_f16 v[120:123], v[162:165], v[158:161], v[120:123]
	v_mfma_f32_16x16x32_f16 v[116:119], v[190:193], v[142:145], v[116:119]
	v_mfma_f32_16x16x32_f16 v[112:115], v[190:193], v[158:161], v[112:115]
	v_mfma_f32_16x16x32_f16 v[108:111], v[198:201], v[142:145], v[108:111]
	v_mfma_f32_16x16x32_f16 v[104:107], v[198:201], v[158:161], v[104:107]
	v_mfma_f32_16x16x32_f16 v[100:103], v[206:209], v[142:145], v[100:103]
	v_mfma_f32_16x16x32_f16 v[96:99], v[206:209], v[158:161], v[96:99]
	s_barrier
	ds_read_b128 v[210:213], v133 offset:49152
	ds_read_b128 v[214:217], v133 offset:50176
	ds_read_b128 v[218:221], v133 offset:51200
	ds_read_b128 v[222:225], v133 offset:52224
	s_waitcnt vmcnt(0)
	s_barrier
	s_waitcnt lgkmcnt(0)
	s_waitcnt lgkmcnt(0)
	v_mfma_f32_16x16x32_f16 v[92:95], v[72:75], v[210:213], v[92:95]
	v_mfma_f32_16x16x32_f16 v[72:75], v[72:75], v[218:221], v[88:91]
	v_mfma_f32_16x16x32_f16 v[88:91], v[162:165], v[222:225], v[72:75]
	v_mfma_f32_16x16x32_f16 v[72:75], v[186:189], v[210:213], v[84:87]
	v_mfma_f32_16x16x32_f16 v[84:87], v[190:193], v[214:217], v[72:75]
	v_mfma_f32_16x16x32_f16 v[72:75], v[186:189], v[218:221], v[80:83]
	v_mfma_f32_16x16x32_f16 v[80:83], v[190:193], v[222:225], v[72:75]
	v_mfma_f32_16x16x32_f16 v[72:75], v[194:197], v[210:213], v[76:79]
	v_mfma_f32_16x16x32_f16 v[68:71], v[194:197], v[218:221], v[68:71]
	v_mfma_f32_16x16x32_f16 v[64:67], v[202:205], v[210:213], v[64:67]
	v_mfma_f32_16x16x32_f16 v[60:63], v[202:205], v[218:221], v[60:63]
	v_mfma_f32_16x16x32_f16 v[92:95], v[162:165], v[214:217], v[92:95]
	v_mfma_f32_16x16x32_f16 v[76:79], v[198:201], v[214:217], v[72:75]
	v_mfma_f32_16x16x32_f16 v[72:75], v[198:201], v[222:225], v[68:71]
	v_mfma_f32_16x16x32_f16 v[68:71], v[206:209], v[214:217], v[64:67]
	v_mfma_f32_16x16x32_f16 v[64:67], v[206:209], v[222:225], v[60:63]
	s_barrier
	ds_read_b128 v[162:165], v132 offset:49152
	ds_read_b128 v[186:189], v132 offset:50176
	ds_read_b128 v[190:193], v132 offset:51200
	ds_read_b128 v[194:197], v132 offset:52224
	ds_read_b128 v[198:201], v132 offset:53248
	ds_read_b128 v[202:205], v132 offset:54272
	ds_read_b128 v[206:209], v132 offset:55296
	ds_read_b128 v[226:229], v132 offset:56320
	s_barrier
	s_waitcnt lgkmcnt(0)
	s_waitcnt lgkmcnt(0)
	v_mfma_f32_16x16x32_f16 v[56:59], v[162:165], v[138:141], v[56:59]
	v_mfma_f32_16x16x32_f16 v[52:55], v[162:165], v[146:149], v[52:55]
	v_mfma_f32_16x16x32_f16 v[48:51], v[190:193], v[138:141], v[48:51]
	v_mfma_f32_16x16x32_f16 v[44:47], v[190:193], v[146:149], v[44:47]
	v_mfma_f32_16x16x32_f16 v[40:43], v[198:201], v[138:141], v[40:43]
	v_mfma_f32_16x16x32_f16 v[36:39], v[198:201], v[146:149], v[36:39]
	v_mfma_f32_16x16x32_f16 v[32:35], v[206:209], v[138:141], v[32:35]
	v_mfma_f32_16x16x32_f16 v[28:31], v[206:209], v[146:149], v[28:31]
	v_mfma_f32_16x16x32_f16 v[60:63], v[186:189], v[142:145], v[56:59]
	v_mfma_f32_16x16x32_f16 v[56:59], v[186:189], v[158:161], v[52:55]
	v_mfma_f32_16x16x32_f16 v[52:55], v[194:197], v[142:145], v[48:51]
	v_mfma_f32_16x16x32_f16 v[48:51], v[194:197], v[158:161], v[44:47]
	v_mfma_f32_16x16x32_f16 v[44:47], v[202:205], v[142:145], v[40:43]
	v_mfma_f32_16x16x32_f16 v[40:43], v[202:205], v[158:161], v[36:39]
	v_mfma_f32_16x16x32_f16 v[36:39], v[226:229], v[142:145], v[32:35]
	v_mfma_f32_16x16x32_f16 v[32:35], v[226:229], v[158:161], v[28:31]
	v_mfma_f32_16x16x32_f16 v[24:27], v[162:165], v[210:213], v[24:27]
	v_mfma_f32_16x16x32_f16 v[20:23], v[162:165], v[218:221], v[20:23]
	v_mfma_f32_16x16x32_f16 v[16:19], v[190:193], v[210:213], v[16:19]
	v_mfma_f32_16x16x32_f16 v[12:15], v[190:193], v[218:221], v[12:15]
	v_mfma_f32_16x16x32_f16 v[8:11], v[198:201], v[210:213], v[8:11]
	v_mfma_f32_16x16x32_f16 v[4:7], v[198:201], v[218:221], v[4:7]
	v_mfma_f32_16x16x32_f16 v[0:3], v[206:209], v[210:213], v[0:3]
	v_mfma_f32_16x16x32_f16 v[28:31], v[186:189], v[214:217], v[24:27]
	v_mfma_f32_16x16x32_f16 v[24:27], v[186:189], v[222:225], v[20:23]
	v_mfma_f32_16x16x32_f16 v[20:23], v[194:197], v[214:217], v[16:19]
	v_mfma_f32_16x16x32_f16 v[16:19], v[194:197], v[222:225], v[12:15]
	v_mfma_f32_16x16x32_f16 v[12:15], v[202:205], v[214:217], v[8:11]
	v_mfma_f32_16x16x32_f16 v[8:11], v[202:205], v[222:225], v[4:7]
	v_mfma_f32_16x16x32_f16 v[4:7], v[226:229], v[214:217], v[0:3]
	v_mfma_f32_16x16x32_f16 v[0:3], v[206:209], v[218:221], v[134:137]
	v_mfma_f32_16x16x32_f16 v[0:3], v[226:229], v[222:225], v[0:3]
	s_movk_i32 s2, 0x100
	v_cmp_gt_u32_e32 vcc, s2, v131
	s_barrier
	s_and_saveexec_b64 s[2:3], vcc
	s_cbranch_execz .LBB0_130
	s_barrier

;   #define STAGE(P,BASE,LD,br,kt) do{ const HALF* _u=(BASE)+(long)(br)*(((&(LD))==&lda)?lda_u:(LD))+(long)(kt)*G_BK; \
;     for(int _i=0;_i<2;++_i){ \
;       __builtin_amdgcn_global_load_lds((const unsigned*)(_u+(long)_i*(((&(LD))==&lda)?stepa:stepb)+((&(LD))==&lda?oa0:ob0)), \
;         (unsigned*)((char*)(P)+t5*16+_i*8192),16,0,0);}}while(0)
;   #define LDA(dst,b,h) for(int m=0;m<4;++m)for(int k=0;k<2;++k) \
;     dst[m][k]=*reinterpret_cast<const h8*>(la+(((b)*2+(h))*16384+m*2048+k*1024))
;   #define LDB(dst,b,h) for(int n=0;n<2;++n)for(int k=0;k<2;++k) \
;     dst[n][k]=*reinterpret_cast<const h8*>(lb+(((b)*2+(h))*16384+n*2048+k*1024))
;   #define MMA(ai,bj,At,Bt_) do{__builtin_amdgcn_s_setprio(1); \
;     for(int m=0;m<4;++m)for(int n=0;n<2;++n)for(int k=0;k<2;++k) \
;       acc[ai][bj][m][n]=__builtin_amdgcn_mfma_f32_16x16x32_f16(At[m][k],Bt_[n][k],acc[ai][bj][m][n],0,0,0); \
;     __builtin_amdgcn_s_setprio(0);}while(0)
;   #define WAIT_L(n) asm volatile("s_waitcnt lgkmcnt(" #n ")":::"memory")
;   #define BAR __builtin_amdgcn_s_barrier()
;   #define SCHED __builtin_amdgcn_sched_barrier(0)
;     ...
;     LDB(B0,0,0); SCHED; LDA(At,0,0); STAGE(SA(1,1),A,lda,G_HALF,t+1);
;     WAIT_L(8); BAR; WAIT_L(0); MMA(0,0,At,B0); BAR; SCHED;
;     LDB(B1,0,1); STAGE(SB(0,0),Bt,ldb,0,t+2);
;     BAR; WAIT_L(0); MMA(0,1,At,B1); BAR;
;     LDA(At,0,1); STAGE(SA(0,0),A,lda,0,t+2);
;     BAR; WAIT_L(0); MMA(1,0,At,B0); BAR; SCHED;
.LBB0_139:
	ds_read_b128 v[158:161], v135
	ds_read_b128 v[162:165], v135 offset:1024
	ds_read_b128 v[186:189], v135 offset:2048
	ds_read_b128 v[190:193], v135 offset:3072
	v_add_u32_e32 v150, 0xc000, v138
	v_lshl_add_u64 v[166:167], vcc, 0, v[128:129]
	s_mov_b64 s[14:15], 0x2ff30080
	v_readfirstlane_b32 s13, v150
	v_add_u32_e32 v151, 0xe000, v138
	v_lshl_add_u64 v[168:169], v[166:167], 0, s[14:15]
	s_mov_b32 m0, s13
	s_mov_b64 s[14:15], 0x2ff70080
	v_readfirstlane_b32 s13, v151
	ds_read_b128 v[194:197], v134
	ds_read_b128 v[198:201], v134 offset:1024
	ds_read_b128 v[202:205], v134 offset:2048
	ds_read_b128 v[206:209], v134 offset:3072
	ds_read_b128 v[210:213], v134 offset:4096
	ds_read_b128 v[214:217], v134 offset:5120
	ds_read_b128 v[218:221], v134 offset:6144
	ds_read_b128 v[222:225], v134 offset:7168
	global_load_lds_dwordx4 v[168:169], off
	v_lshl_add_u64 v[168:169], v[166:167], 0, s[14:15]
	s_mov_b32 m0, s13
	s_nop 0
	global_load_lds_dwordx4 v[168:169], off
	s_waitcnt lgkmcnt(8)
	s_barrier
	s_waitcnt lgkmcnt(0)
	s_waitcnt lgkmcnt(0)
	v_mfma_f32_16x16x32_f16 v[124:127], v[194:197], v[158:161], v[124:127]
	v_mfma_f32_16x16x32_f16 v[120:123], v[194:197], v[186:189], v[120:123]
	v_mfma_f32_16x16x32_f16 v[116:119], v[202:205], v[158:161], v[116:119]
	v_mfma_f32_16x16x32_f16 v[112:115], v[202:205], v[186:189], v[112:115]
	v_mfma_f32_16x16x32_f16 v[108:111], v[210:213], v[158:161], v[108:111]
	v_mfma_f32_16x16x32_f16 v[104:107], v[210:213], v[186:189], v[104:107]
	v_mfma_f32_16x16x32_f16 v[100:103], v[218:221], v[158:161], v[100:103]
	v_mfma_f32_16x16x32_f16 v[96:99], v[218:221], v[186:189], v[96:99]
	v_mfma_f32_16x16x32_f16 v[124:127], v[198:201], v[162:165], v[124:127]
	v_mfma_f32_16x16x32_f16 v[120:123], v[198:201], v[190:193], v[120:123]
	v_mfma_f32_16x16x32_f16 v[116:119], v[206:209], v[162:165], v[116:119]
	v_mfma_f32_16x16x32_f16 v[112:115], v[206:209], v[190:193], v[112:115]
	v_mfma_f32_16x16x32_f16 v[108:111], v[214:217], v[162:165], v[108:111]
	v_mfma_f32_16x16x32_f16 v[104:107], v[214:217], v[190:193], v[104:107]
	v_mfma_f32_16x16x32_f16 v[100:103], v[222:225], v[162:165], v[100:103]
	v_mfma_f32_16x16x32_f16 v[96:99], v[222:225], v[190:193], v[96:99]
	s_barrier
	v_lshl_add_u64 v[168:169], s[76:77], 0, v[128:129]
	s_mov_b64 s[14:15], 0x1e00100
	v_readfirstlane_b32 s13, v136
	v_lshl_add_u64 v[170:171], v[168:169], 0, s[14:15]
	s_mov_b32 m0, s13
	s_mov_b64 s[14:15], 0x1e40100
	v_readfirstlane_b32 s13, v137
	ds_read_b128 v[226:229], v135 offset:16384
	ds_read_b128 v[230:233], v135 offset:17408
	ds_read_b128 v[234:237], v135 offset:18432
	ds_read_b128 v[238:241], v135 offset:19456
	global_load_lds_dwordx4 v[170:171], off
	v_lshl_add_u64 v[170:171], v[168:169], 0, s[14:15]
	s_mov_b32 m0, s13
	s_nop 0
	global_load_lds_dwordx4 v[170:171], off
	s_barrier
	s_waitcnt lgkmcnt(0)
	s_waitcnt lgkmcnt(0)
	v_mfma_f32_16x16x32_f16 v[92:95], v[194:197], v[226:229], v[92:95]
	v_mfma_f32_16x16x32_f16 v[88:91], v[194:197], v[234:237], v[88:91]
	v_mfma_f32_16x16x32_f16 v[84:87], v[202:205], v[226:229], v[84:87]
	v_mfma_f32_16x16x32_f16 v[80:83], v[202:205], v[234:237], v[80:83]
	v_mfma_f32_16x16x32_f16 v[76:79], v[210:213], v[226:229], v[76:79]
	v_mfma_f32_16x16x32_f16 v[68:71], v[210:213], v[234:237], v[68:71]
	v_mfma_f32_16x16x32_f16 v[64:67], v[218:221], v[226:229], v[64:67]
	v_mfma_f32_16x16x32_f16 v[60:63], v[218:221], v[234:237], v[60:63]
	v_mfma_f32_16x16x32_f16 v[92:95], v[198:201], v[230:233], v[92:95]
	v_mfma_f32_16x16x32_f16 v[88:91], v[198:201], v[238:241], v[88:91]
	v_mfma_f32_16x16x32_f16 v[84:87], v[206:209], v[230:233], v[84:87]
	v_mfma_f32_16x16x32_f16 v[80:83], v[206:209], v[238:241], v[80:83]
	v_mfma_f32_16x16x32_f16 v[76:79], v[214:217], v[230:233], v[76:79]
	v_mfma_f32_16x16x32_f16 v[68:71], v[214:217], v[238:241], v[68:71]
	v_mfma_f32_16x16x32_f16 v[64:67], v[222:225], v[230:233], v[64:67]
	v_mfma_f32_16x16x32_f16 v[60:63], v[222:225], v[238:241], v[60:63]
	s_mov_b64 s[14:15], 0x2feb0100
	v_readfirstlane_b32 s13, v138
	v_lshl_add_u64 v[170:171], v[166:167], 0, s[14:15]
	s_mov_b32 m0, s13
	s_mov_b64 s[14:15], 0x2fef0100
	v_readfirstlane_b32 s13, v139
	s_barrier
	ds_read_b128 v[194:197], v134 offset:16384
	ds_read_b128 v[198:201], v134 offset:17408
	ds_read_b128 v[202:205], v134 offset:18432
	ds_read_b128 v[206:209], v134 offset:19456
	ds_read_b128 v[210:213], v134 offset:20480
	ds_read_b128 v[214:217], v134 offset:21504
	ds_read_b128 v[218:221], v134 offset:22528
	ds_read_b128 v[222:225], v134 offset:23552
	global_load_lds_dwordx4 v[170:171], off
	v_lshl_add_u64 v[170:171], v[166:167], 0, s[14:15]
	s_mov_b32 m0, s13
	s_nop 0
	global_load_lds_dwordx4 v[170:171], off
	s_barrier
	s_waitcnt lgkmcnt(0)
	s_waitcnt lgkmcnt(0)
	v_mfma_f32_16x16x32_f16 v[56:59], v[194:197], v[158:161], v[56:59]
	v_mfma_f32_16x16x32_f16 v[52:55], v[194:197], v[186:189], v[52:55]
	v_mfma_f32_16x16x32_f16 v[48:51], v[202:205], v[158:161], v[48:51]
	v_mfma_f32_16x16x32_f16 v[44:47], v[202:205], v[186:189], v[44:47]
	v_mfma_f32_16x16x32_f16 v[40:43], v[210:213], v[158:161], v[40:43]
	v_mfma_f32_16x16x32_f16 v[36:39], v[210:213], v[186:189], v[36:39]
	v_mfma_f32_16x16x32_f16 v[32:35], v[218:221], v[158:161], v[32:35]
	v_mfma_f32_16x16x32_f16 v[28:31], v[218:221], v[186:189], v[28:31]
	v_mfma_f32_16x16x32_f16 v[56:59], v[198:201], v[162:165], v[56:59]
	v_mfma_f32_16x16x32_f16 v[52:55], v[198:201], v[190:193], v[52:55]
	v_mfma_f32_16x16x32_f16 v[48:51], v[206:209], v[162:165], v[48:51]
	v_mfma_f32_16x16x32_f16 v[44:47], v[206:209], v[190:193], v[44:47]
	v_mfma_f32_16x16x32_f16 v[40:43], v[214:217], v[162:165], v[40:43]
	v_mfma_f32_16x16x32_f16 v[36:39], v[214:217], v[190:193], v[36:39]
	v_mfma_f32_16x16x32_f16 v[32:35], v[222:225], v[162:165], v[32:35]
	v_mfma_f32_16x16x32_f16 v[28:31], v[222:225], v[190:193], v[28:31]
	s_barrier
;   #define STAGE(P,BASE,LD,br,kt) do{ const HALF* _u=(BASE)+(long)(br)*(((&(LD))==&lda)?lda_u:(LD))+(long)(kt)*G_BK; \
;     for(int _i=0;_i<2;++_i){ \
;       __builtin_amdgcn_global_load_lds((const unsigned*)(_u+(long)_i*(((&(LD))==&lda)?stepa:stepb)+((&(LD))==&lda?oa0:ob0)), \
;         (unsigned*)((char*)(P)+t5*16+_i*8192),16,0,0);}}while(0)
;   #define LDA(dst,b,h) for(int m=0;m<4;++m)for(int k=0;k<2;++k) \
;     dst[m][k]=*reinterpret_cast<const h8*>(la+(((b)*2+(h))*16384+m*2048+k*1024))
;   #define LDB(dst,b,h) for(int n=0;n<2;++n)for(int k=0;k<2;++k) \
;     dst[n][k]=*reinterpret_cast<const h8*>(lb+(((b)*2+(h))*16384+n*2048+k*1024))
;   #define MMA(ai,bj,At,Bt_) do{__builtin_amdgcn_s_setprio(1); \
;     for(int m=0;m<4;++m)for(int n=0;n<2;++n)for(int k=0;k<2;++k) \
;       acc[ai][bj][m][n]=__builtin_amdgcn_mfma_f32_16x16x32_f16(At[m][k],Bt_[n][k],acc[ai][bj][m][n],0,0,0); \
;     __builtin_amdgcn_s_setprio(0);}while(0)
;   #define WAIT_V(n) asm volatile("s_waitcnt vmcnt(" #n ")":::"memory")
;   #define WAIT_L(n) asm volatile("s_waitcnt lgkmcnt(" #n ")":::"memory")
;   #define BAR __builtin_amdgcn_s_barrier()
;   #define SCHED __builtin_amdgcn_sched_barrier(0)
;     ...
;     STAGE(SB(0,1),Bt,ldb,G_HALF,t+2);
;     WAIT_V(6); BAR; MMA(1,1,At,B1); BAR;
;     LDB(B0,1,0); SCHED; LDA(At,1,0); STAGE(SA(0,1),A,lda,G_HALF,t+2);
;     WAIT_L(8); BAR; WAIT_L(0); MMA(0,0,At,B0); BAR; SCHED;
;     LDB(B1,1,1); STAGE(SB(1,0),Bt,ldb,0,t+3);
;     BAR; WAIT_L(0); MMA(0,1,At,B1); BAR;
;     LDA(At,1,1); STAGE(SA(1,0),A,lda,0,t+3);
	s_mov_b64 s[14:15], 0x1e80100
	v_readfirstlane_b32 s13, v140
	v_lshl_add_u64 v[158:159], v[168:169], 0, s[14:15]
	s_mov_b32 m0, s13
	s_mov_b64 s[14:15], 0x1ec0100
	v_readfirstlane_b32 s13, v141
	global_load_lds_dwordx4 v[158:159], off
	v_lshl_add_u64 v[158:159], v[168:169], 0, s[14:15]
	s_mov_b32 m0, s13
	s_nop 0
	global_load_lds_dwordx4 v[158:159], off
	s_waitcnt vmcnt(6)
	s_barrier
	v_mfma_f32_16x16x32_f16 v[24:27], v[194:197], v[226:229], v[24:27]
	v_mfma_f32_16x16x32_f16 v[20:23], v[194:197], v[234:237], v[20:23]
	v_mfma_f32_16x16x32_f16 v[16:19], v[202:205], v[226:229], v[16:19]
	v_mfma_f32_16x16x32_f16 v[12:15], v[202:205], v[234:237], v[12:15]
	v_mfma_f32_16x16x32_f16 v[8:11], v[210:213], v[226:229], v[8:11]
	v_mfma_f32_16x16x32_f16 v[4:7], v[210:213], v[234:237], v[4:7]
	v_mfma_f32_16x16x32_f16 v[0:3], v[218:221], v[226:229], v[0:3]
	v_mfma_f32_16x16x32_f16 v[72:75], v[218:221], v[234:237], v[72:75]
	v_mfma_f32_16x16x32_f16 v[24:27], v[198:201], v[230:233], v[24:27]
	v_mfma_f32_16x16x32_f16 v[20:23], v[198:201], v[238:241], v[20:23]
	v_mfma_f32_16x16x32_f16 v[16:19], v[206:209], v[230:233], v[16:19]
	v_mfma_f32_16x16x32_f16 v[12:15], v[206:209], v[238:241], v[12:15]
	v_mfma_f32_16x16x32_f16 v[8:11], v[214:217], v[230:233], v[8:11]
	v_mfma_f32_16x16x32_f16 v[4:7], v[214:217], v[238:241], v[4:7]
	v_mfma_f32_16x16x32_f16 v[0:3], v[222:225], v[230:233], v[0:3]
	v_mfma_f32_16x16x32_f16 v[72:75], v[222:225], v[238:241], v[72:75]
	s_barrier
	ds_read_b128 v[158:161], v135 offset:32768
	ds_read_b128 v[162:165], v135 offset:33792
	ds_read_b128 v[186:189], v135 offset:34816
	ds_read_b128 v[190:193], v135 offset:35840
	s_mov_b64 s[14:15], 0x2ff30100
	v_readfirstlane_b32 s13, v142
	v_lshl_add_u64 v[170:171], v[166:167], 0, s[14:15]
	s_mov_b32 m0, s13
	s_mov_b64 s[14:15], 0x2ff70100
	v_readfirstlane_b32 s13, v143
	ds_read_b128 v[194:197], v134 offset:32768
	ds_read_b128 v[198:201], v134 offset:33792
	ds_read_b128 v[202:205], v134 offset:34816
	ds_read_b128 v[206:209], v134 offset:35840
	ds_read_b128 v[210:213], v134 offset:36864
	ds_read_b128 v[214:217], v134 offset:37888
	ds_read_b128 v[218:221], v134 offset:38912
	ds_read_b128 v[222:225], v134 offset:39936
	global_load_lds_dwordx4 v[170:171], off
	v_lshl_add_u64 v[170:171], v[166:167], 0, s[14:15]
	s_mov_b32 m0, s13
	s_nop 0
	global_load_lds_dwordx4 v[170:171], off
	s_waitcnt lgkmcnt(8)
	s_barrier
	s_waitcnt lgkmcnt(0)
	s_waitcnt lgkmcnt(0)
	v_mfma_f32_16x16x32_f16 v[124:127], v[194:197], v[158:161], v[124:127]
	v_mfma_f32_16x16x32_f16 v[120:123], v[194:197], v[186:189], v[120:123]
	v_mfma_f32_16x16x32_f16 v[116:119], v[202:205], v[158:161], v[116:119]
	v_mfma_f32_16x16x32_f16 v[112:115], v[202:205], v[186:189], v[112:115]
	v_mfma_f32_16x16x32_f16 v[108:111], v[210:213], v[158:161], v[108:111]
	v_mfma_f32_16x16x32_f16 v[104:107], v[210:213], v[186:189], v[104:107]
	v_mfma_f32_16x16x32_f16 v[100:103], v[218:221], v[158:161], v[100:103]
	v_mfma_f32_16x16x32_f16 v[96:99], v[218:221], v[186:189], v[96:99]
	v_mfma_f32_16x16x32_f16 v[124:127], v[198:201], v[162:165], v[124:127]
	v_mfma_f32_16x16x32_f16 v[120:123], v[198:201], v[190:193], v[120:123]
	v_mfma_f32_16x16x32_f16 v[116:119], v[206:209], v[162:165], v[116:119]
	v_mfma_f32_16x16x32_f16 v[112:115], v[206:209], v[190:193], v[112:115]
	v_mfma_f32_16x16x32_f16 v[108:111], v[214:217], v[162:165], v[108:111]
	v_mfma_f32_16x16x32_f16 v[104:107], v[214:217], v[190:193], v[104:107]
	v_mfma_f32_16x16x32_f16 v[100:103], v[222:225], v[162:165], v[100:103]
	v_mfma_f32_16x16x32_f16 v[96:99], v[222:225], v[190:193], v[96:99]
	s_barrier
	s_mov_b64 s[14:15], 0x1e00180
	v_readfirstlane_b32 s13, v144
	v_lshl_add_u64 v[170:171], v[168:169], 0, s[14:15]
	s_mov_b32 m0, s13
	s_mov_b64 s[14:15], 0x1e40180
	v_readfirstlane_b32 s13, v145
	ds_read_b128 v[226:229], v135 offset:49152
	ds_read_b128 v[230:233], v135 offset:50176
	ds_read_b128 v[234:237], v135 offset:51200
	ds_read_b128 v[238:241], v135 offset:52224
	global_load_lds_dwordx4 v[170:171], off
	v_lshl_add_u64 v[170:171], v[168:169], 0, s[14:15]
	s_mov_b32 m0, s13
	s_nop 0
	global_load_lds_dwordx4 v[170:171], off
	s_barrier
	s_waitcnt lgkmcnt(0)
	s_waitcnt lgkmcnt(0)
	v_mfma_f32_16x16x32_f16 v[92:95], v[194:197], v[226:229], v[92:95]
	v_mfma_f32_16x16x32_f16 v[88:91], v[194:197], v[234:237], v[88:91]
	v_mfma_f32_16x16x32_f16 v[84:87], v[202:205], v[226:229], v[84:87]
	v_mfma_f32_16x16x32_f16 v[80:83], v[202:205], v[234:237], v[80:83]
	v_mfma_f32_16x16x32_f16 v[76:79], v[210:213], v[226:229], v[76:79]
	v_mfma_f32_16x16x32_f16 v[68:71], v[210:213], v[234:237], v[68:71]
	v_mfma_f32_16x16x32_f16 v[64:67], v[218:221], v[226:229], v[64:67]
	v_mfma_f32_16x16x32_f16 v[60:63], v[218:221], v[234:237], v[60:63]
	v_mfma_f32_16x16x32_f16 v[92:95], v[198:201], v[230:233], v[92:95]
	v_mfma_f32_16x16x32_f16 v[88:91], v[198:201], v[238:241], v[88:91]
	v_mfma_f32_16x16x32_f16 v[84:87], v[206:209], v[230:233], v[84:87]
	v_mfma_f32_16x16x32_f16 v[80:83], v[206:209], v[238:241], v[80:83]
	v_mfma_f32_16x16x32_f16 v[76:79], v[214:217], v[230:233], v[76:79]
	v_mfma_f32_16x16x32_f16 v[68:71], v[214:217], v[238:241], v[68:71]
	v_mfma_f32_16x16x32_f16 v[64:67], v[222:225], v[230:233], v[64:67]
	v_mfma_f32_16x16x32_f16 v[60:63], v[222:225], v[238:241], v[60:63]
	s_mov_b64 s[14:15], 0x2feb0180
	v_readfirstlane_b32 s13, v146
	v_lshl_add_u64 v[170:171], v[166:167], 0, s[14:15]
	s_mov_b32 m0, s13
	s_mov_b64 s[14:15], 0x2fef0180
	v_readfirstlane_b32 s13, v147
	s_barrier
;   #define STAGE(P,BASE,LD,br,kt) do{ const HALF* _u=(BASE)+(long)(br)*(((&(LD))==&lda)?lda_u:(LD))+(long)(kt)*G_BK; \
;     for(int _i=0;_i<2;++_i){ \
;       __builtin_amdgcn_global_load_lds((const unsigned*)(_u+(long)_i*(((&(LD))==&lda)?stepa:stepb)+((&(LD))==&lda?oa0:ob0)), \
;         (unsigned*)((char*)(P)+t5*16+_i*8192),16,0,0);}}while(0)
;   #define LDA(dst,b,h) for(int m=0;m<4;++m)for(int k=0;k<2;++k) \
;     dst[m][k]=*reinterpret_cast<const h8*>(la+(((b)*2+(h))*16384+m*2048+k*1024))
;   #define LDB(dst,b,h) for(int n=0;n<2;++n)for(int k=0;k<2;++k) \
;     dst[n][k]=*reinterpret_cast<const h8*>(lb+(((b)*2+(h))*16384+n*2048+k*1024))
;   #define MMA(ai,bj,At,Bt_) do{__builtin_amdgcn_s_setprio(1); \
;     for(int m=0;m<4;++m)for(int n=0;n<2;++n)for(int k=0;k<2;++k) \
;       acc[ai][bj][m][n]=__builtin_amdgcn_mfma_f32_16x16x32_f16(At[m][k],Bt_[n][k],acc[ai][bj][m][n],0,0,0); \
;     __builtin_amdgcn_s_setprio(0);}while(0)
;   #define WAIT_V(n) asm volatile("s_waitcnt vmcnt(" #n ")":::"memory")
;   #define WAIT_L(n) asm volatile("s_waitcnt lgkmcnt(" #n ")":::"memory")
;   #define BAR __builtin_amdgcn_s_barrier()
;   #define SCHED __builtin_amdgcn_sched_barrier(0)
;     ...
;     LDA(At,1,1); STAGE(SA(1,0),A,lda,0,t+3);
;     BAR; WAIT_L(0); MMA(1,0,At,B0); BAR; SCHED;
;     STAGE(SB(1,1),Bt,ldb,G_HALF,t+3);
;     WAIT_V(6); BAR; MMA(1,1,At,B1); BAR;
;   }
;   { LDB(B0,0,0); LDA(At,0,0); STAGE(SA(1,1),A,lda,G_HALF,nt-1);
;     BAR; WAIT_L(0); MMA(0,0,At,B0); BAR;
;     LDB(B1,0,1); BAR; WAIT_L(0); MMA(0,1,At,B1); BAR;
	ds_read_b128 v[194:197], v134 offset:49152
	ds_read_b128 v[198:201], v134 offset:50176
	ds_read_b128 v[202:205], v134 offset:51200
	ds_read_b128 v[206:209], v134 offset:52224
	ds_read_b128 v[210:213], v134 offset:53248
	ds_read_b128 v[214:217], v134 offset:54272
	ds_read_b128 v[218:221], v134 offset:55296
	ds_read_b128 v[222:225], v134 offset:56320
	global_load_lds_dwordx4 v[170:171], off
	v_lshl_add_u64 v[166:167], v[166:167], 0, s[14:15]
	s_mov_b32 m0, s13
	s_nop 0
	global_load_lds_dwordx4 v[166:167], off
	s_barrier
	s_waitcnt lgkmcnt(0)
	s_waitcnt lgkmcnt(0)
	v_mfma_f32_16x16x32_f16 v[56:59], v[194:197], v[158:161], v[56:59]
	v_mfma_f32_16x16x32_f16 v[52:55], v[194:197], v[186:189], v[52:55]
	v_mfma_f32_16x16x32_f16 v[48:51], v[202:205], v[158:161], v[48:51]
	v_mfma_f32_16x16x32_f16 v[44:47], v[202:205], v[186:189], v[44:47]
	v_mfma_f32_16x16x32_f16 v[40:43], v[210:213], v[158:161], v[40:43]
	v_mfma_f32_16x16x32_f16 v[36:39], v[210:213], v[186:189], v[36:39]
	v_mfma_f32_16x16x32_f16 v[32:35], v[218:221], v[158:161], v[32:35]
	v_mfma_f32_16x16x32_f16 v[28:31], v[218:221], v[186:189], v[28:31]
	v_mfma_f32_16x16x32_f16 v[56:59], v[198:201], v[162:165], v[56:59]
	v_mfma_f32_16x16x32_f16 v[52:55], v[198:201], v[190:193], v[52:55]
	v_mfma_f32_16x16x32_f16 v[48:51], v[206:209], v[162:165], v[48:51]
	v_mfma_f32_16x16x32_f16 v[44:47], v[206:209], v[190:193], v[44:47]
	v_mfma_f32_16x16x32_f16 v[40:43], v[214:217], v[162:165], v[40:43]
	v_mfma_f32_16x16x32_f16 v[36:39], v[214:217], v[190:193], v[36:39]
	v_mfma_f32_16x16x32_f16 v[32:35], v[222:225], v[162:165], v[32:35]
	v_mfma_f32_16x16x32_f16 v[28:31], v[222:225], v[190:193], v[28:31]
	s_barrier
	s_mov_b64 s[14:15], 0x1e80180
	v_readfirstlane_b32 s13, v148
	v_lshl_add_u64 v[158:159], v[168:169], 0, s[14:15]
	s_mov_b32 m0, s13
	s_mov_b64 s[14:15], 0x1ec0180
	v_readfirstlane_b32 s13, v149
	global_load_lds_dwordx4 v[158:159], off
	v_lshl_add_u64 v[158:159], v[168:169], 0, s[14:15]
	s_mov_b32 m0, s13
	s_nop 0
	global_load_lds_dwordx4 v[158:159], off
	s_waitcnt vmcnt(6)
	s_barrier
	v_mfma_f32_16x16x32_f16 v[24:27], v[194:197], v[226:229], v[24:27]
	v_mfma_f32_16x16x32_f16 v[20:23], v[194:197], v[234:237], v[20:23]
	v_mfma_f32_16x16x32_f16 v[16:19], v[202:205], v[226:229], v[16:19]
	v_mfma_f32_16x16x32_f16 v[12:15], v[202:205], v[234:237], v[12:15]
	v_mfma_f32_16x16x32_f16 v[8:11], v[210:213], v[226:229], v[8:11]
	v_mfma_f32_16x16x32_f16 v[4:7], v[210:213], v[234:237], v[4:7]
	v_mfma_f32_16x16x32_f16 v[0:3], v[218:221], v[226:229], v[0:3]
	v_mfma_f32_16x16x32_f16 v[72:75], v[218:221], v[234:237], v[72:75]
	v_mfma_f32_16x16x32_f16 v[24:27], v[198:201], v[230:233], v[24:27]
	v_mfma_f32_16x16x32_f16 v[20:23], v[198:201], v[238:241], v[20:23]
	v_mfma_f32_16x16x32_f16 v[16:19], v[206:209], v[230:233], v[16:19]
	v_mfma_f32_16x16x32_f16 v[12:15], v[206:209], v[238:241], v[12:15]
	v_mfma_f32_16x16x32_f16 v[8:11], v[214:217], v[230:233], v[8:11]
	v_mfma_f32_16x16x32_f16 v[4:7], v[214:217], v[238:241], v[4:7]
	v_mfma_f32_16x16x32_f16 v[0:3], v[222:225], v[230:233], v[0:3]
	v_mfma_f32_16x16x32_f16 v[72:75], v[222:225], v[238:241], v[72:75]
	s_add_i32 s12, s12, 2
	s_add_u32 s76, s76, 0x100
	s_addc_u32 s77, s77, 0
	s_add_u32 vcc_lo, vcc_lo, 0x100
	s_addc_u32 vcc_hi, vcc_hi, 0
	s_cmp_lt_u32 s12, 28
	s_barrier
	s_cbranch_scc1 .LBB0_139
	v_lshl_add_u64 v[128:129], v[152:153], 1, s[58:59]
	s_mov_b64 s[12:13], 0x80f80
	v_lshl_add_u64 v[148:149], v[128:129], 0, s[12:13]
	v_readfirstlane_b32 s12, v150
	s_mov_b32 m0, s12
	s_mov_b64 s[12:13], 0xc0f80
	v_lshl_add_u64 v[128:129], v[128:129], 0, s[12:13]
	v_readfirstlane_b32 s12, v151
	ds_read_b128 v[136:139], v135
	ds_read_b128 v[140:143], v135 offset:1024
	ds_read_b128 v[144:147], v135 offset:2048
	ds_read_b128 v[158:161], v135 offset:3072
	ds_read_b128 v[162:165], v134
	ds_read_b128 v[186:189], v134 offset:1024
	ds_read_b128 v[190:193], v134 offset:2048
	ds_read_b128 v[194:197], v134 offset:3072
	ds_read_b128 v[198:201], v134 offset:4096
	ds_read_b128 v[202:205], v134 offset:5120
	ds_read_b128 v[206:209], v134 offset:6144
	ds_read_b128 v[210:213], v134 offset:7168
	global_load_lds_dwordx4 v[148:149], off
	s_mov_b32 m0, s12
	s_nop 0
	global_load_lds_dwordx4 v[128:129], off
	s_barrier
	s_waitcnt lgkmcnt(0)
	s_waitcnt lgkmcnt(0)
	v_mfma_f32_16x16x32_f16 v[124:127], v[162:165], v[136:139], v[124:127]
	v_mfma_f32_16x16x32_f16 v[120:123], v[162:165], v[144:147], v[120:123]
	v_mfma_f32_16x16x32_f16 v[116:119], v[190:193], v[136:139], v[116:119]
	v_mfma_f32_16x16x32_f16 v[112:115], v[190:193], v[144:147], v[112:115]
	v_mfma_f32_16x16x32_f16 v[108:111], v[198:201], v[136:139], v[108:111]
	v_mfma_f32_16x16x32_f16 v[104:107], v[198:201], v[144:147], v[104:107]
	v_mfma_f32_16x16x32_f16 v[100:103], v[206:209], v[136:139], v[100:103]
	v_mfma_f32_16x16x32_f16 v[96:99], v[206:209], v[144:147], v[96:99]
	v_mfma_f32_16x16x32_f16 v[124:127], v[186:189], v[140:143], v[124:127]
	v_mfma_f32_16x16x32_f16 v[120:123], v[186:189], v[158:161], v[120:123]
	v_mfma_f32_16x16x32_f16 v[116:119], v[194:197], v[140:143], v[116:119]
	v_mfma_f32_16x16x32_f16 v[112:115], v[194:197], v[158:161], v[112:115]
	v_mfma_f32_16x16x32_f16 v[108:111], v[202:205], v[140:143], v[108:111]
	v_mfma_f32_16x16x32_f16 v[104:107], v[202:205], v[158:161], v[104:107]
	v_mfma_f32_16x16x32_f16 v[100:103], v[210:213], v[140:143], v[100:103]
	v_mfma_f32_16x16x32_f16 v[96:99], v[210:213], v[158:161], v[96:99]
	s_barrier
	ds_read_b128 v[148:151], v135 offset:16384
	ds_read_b128 v[214:217], v135 offset:17408
	ds_read_b128 v[218:221], v135 offset:18432
	ds_read_b128 v[222:225], v135 offset:19456
	s_barrier
;   #define LDA(dst,b,h) for(int m=0;m<4;++m)for(int k=0;k<2;++k) \
;     dst[m][k]=*reinterpret_cast<const h8*>(la+(((b)*2+(h))*16384+m*2048+k*1024))
;   #define LDB(dst,b,h) for(int n=0;n<2;++n)for(int k=0;k<2;++k) \
;     dst[n][k]=*reinterpret_cast<const h8*>(lb+(((b)*2+(h))*16384+n*2048+k*1024))
;   #define MMA(ai,bj,At,Bt_) do{__builtin_amdgcn_s_setprio(1); \
;     for(int m=0;m<4;++m)for(int n=0;n<2;++n)for(int k=0;k<2;++k) \
;       acc[ai][bj][m][n]=__builtin_amdgcn_mfma_f32_16x16x32_f16(At[m][k],Bt_[n][k],acc[ai][bj][m][n],0,0,0); \
;     __builtin_amdgcn_s_setprio(0);}while(0)
;   #define WAIT_V(n) asm volatile("s_waitcnt vmcnt(" #n ")":::"memory")
;   #define WAIT_L(n) asm volatile("s_waitcnt lgkmcnt(" #n ")":::"memory")
;   #define BAR __builtin_amdgcn_s_barrier()
;     ...
;     LDB(B1,0,1); BAR; WAIT_L(0); MMA(0,1,At,B1); BAR;
;     LDA(At,0,1); WAIT_V(4); BAR; WAIT_L(0); MMA(1,0,At,B0); MMA(1,1,At,B1); BAR; }
;   { LDB(B0,1,0); LDA(At,1,0); WAIT_V(2); BAR; WAIT_L(0); MMA(0,0,At,B0); BAR;
	s_waitcnt lgkmcnt(0)
	s_waitcnt lgkmcnt(0)
	v_mfma_f32_16x16x32_f16 v[92:95], v[162:165], v[148:151], v[92:95]
	v_mfma_f32_16x16x32_f16 v[88:91], v[162:165], v[218:221], v[88:91]
	v_mfma_f32_16x16x32_f16 v[84:87], v[190:193], v[148:151], v[84:87]
	v_mfma_f32_16x16x32_f16 v[80:83], v[190:193], v[218:221], v[80:83]
	v_mfma_f32_16x16x32_f16 v[76:79], v[198:201], v[148:151], v[76:79]
	v_mfma_f32_16x16x32_f16 v[68:71], v[198:201], v[218:221], v[68:71]
	v_mfma_f32_16x16x32_f16 v[64:67], v[206:209], v[148:151], v[64:67]
	v_mfma_f32_16x16x32_f16 v[60:63], v[206:209], v[218:221], v[60:63]
	v_mfma_f32_16x16x32_f16 v[92:95], v[186:189], v[214:217], v[92:95]
	v_mfma_f32_16x16x32_f16 v[88:91], v[186:189], v[222:225], v[88:91]
	v_mfma_f32_16x16x32_f16 v[84:87], v[194:197], v[214:217], v[84:87]
	v_mfma_f32_16x16x32_f16 v[80:83], v[194:197], v[222:225], v[80:83]
	v_mfma_f32_16x16x32_f16 v[76:79], v[202:205], v[214:217], v[76:79]
	v_mfma_f32_16x16x32_f16 v[68:71], v[202:205], v[222:225], v[68:71]
	v_mfma_f32_16x16x32_f16 v[64:67], v[210:213], v[214:217], v[64:67]
	v_mfma_f32_16x16x32_f16 v[60:63], v[210:213], v[222:225], v[60:63]
	s_barrier
	ds_read_b128 v[162:165], v134 offset:16384
	ds_read_b128 v[186:189], v134 offset:17408
	ds_read_b128 v[190:193], v134 offset:18432
	ds_read_b128 v[194:197], v134 offset:19456
	ds_read_b128 v[198:201], v134 offset:20480
	ds_read_b128 v[202:205], v134 offset:21504
	ds_read_b128 v[206:209], v134 offset:22528
	ds_read_b128 v[210:213], v134 offset:23552
	s_waitcnt vmcnt(4)
	s_barrier
	s_waitcnt lgkmcnt(0)
	s_waitcnt lgkmcnt(0)
	v_mfma_f32_16x16x32_f16 v[56:59], v[162:165], v[136:139], v[56:59]
	v_mfma_f32_16x16x32_f16 v[52:55], v[162:165], v[144:147], v[52:55]
	v_mfma_f32_16x16x32_f16 v[48:51], v[190:193], v[136:139], v[48:51]
	v_mfma_f32_16x16x32_f16 v[44:47], v[190:193], v[144:147], v[44:47]
	v_mfma_f32_16x16x32_f16 v[40:43], v[198:201], v[136:139], v[40:43]
	v_mfma_f32_16x16x32_f16 v[36:39], v[198:201], v[144:147], v[36:39]
	v_mfma_f32_16x16x32_f16 v[32:35], v[206:209], v[136:139], v[32:35]
	v_mfma_f32_16x16x32_f16 v[28:31], v[206:209], v[144:147], v[28:31]
	v_mfma_f32_16x16x32_f16 v[56:59], v[186:189], v[140:143], v[56:59]
	v_mfma_f32_16x16x32_f16 v[52:55], v[186:189], v[158:161], v[52:55]
	v_mfma_f32_16x16x32_f16 v[48:51], v[194:197], v[140:143], v[48:51]
	v_mfma_f32_16x16x32_f16 v[44:47], v[194:197], v[158:161], v[44:47]
	v_mfma_f32_16x16x32_f16 v[40:43], v[202:205], v[140:143], v[40:43]
	v_mfma_f32_16x16x32_f16 v[36:39], v[202:205], v[158:161], v[36:39]
	v_mfma_f32_16x16x32_f16 v[32:35], v[210:213], v[140:143], v[32:35]
	v_mfma_f32_16x16x32_f16 v[28:31], v[210:213], v[158:161], v[28:31]
	v_mfma_f32_16x16x32_f16 v[24:27], v[162:165], v[148:151], v[24:27]
	v_mfma_f32_16x16x32_f16 v[20:23], v[162:165], v[218:221], v[20:23]
	v_mfma_f32_16x16x32_f16 v[16:19], v[190:193], v[148:151], v[16:19]
	v_mfma_f32_16x16x32_f16 v[12:15], v[190:193], v[218:221], v[12:15]
	v_mfma_f32_16x16x32_f16 v[8:11], v[198:201], v[148:151], v[8:11]
	v_mfma_f32_16x16x32_f16 v[4:7], v[198:201], v[218:221], v[4:7]
	v_mfma_f32_16x16x32_f16 v[0:3], v[206:209], v[148:151], v[0:3]
	v_mfma_f32_16x16x32_f16 v[24:27], v[186:189], v[214:217], v[24:27]
	v_mfma_f32_16x16x32_f16 v[20:23], v[186:189], v[222:225], v[20:23]
	v_mfma_f32_16x16x32_f16 v[16:19], v[194:197], v[214:217], v[16:19]
	v_mfma_f32_16x16x32_f16 v[12:15], v[194:197], v[222:225], v[12:15]
	v_mfma_f32_16x16x32_f16 v[8:11], v[202:205], v[214:217], v[8:11]
	v_mfma_f32_16x16x32_f16 v[4:7], v[202:205], v[222:225], v[4:7]
	v_mfma_f32_16x16x32_f16 v[0:3], v[210:213], v[214:217], v[0:3]
	v_mfma_f32_16x16x32_f16 v[72:75], v[206:209], v[218:221], v[72:75]
	v_mfma_f32_16x16x32_f16 v[136:139], v[210:213], v[222:225], v[72:75]
	s_barrier
	ds_read_b128 v[140:143], v135 offset:32768
	ds_read_b128 v[144:147], v135 offset:33792
	ds_read_b128 v[148:151], v135 offset:34816
	ds_read_b128 v[158:161], v135 offset:35840
	s_nop 0
	ds_read_b128 v[72:75], v134 offset:32768
	ds_read_b128 v[162:165], v134 offset:33792
	ds_read_b128 v[186:189], v134 offset:34816
	ds_read_b128 v[190:193], v134 offset:35840
	ds_read_b128 v[194:197], v134 offset:36864
	ds_read_b128 v[198:201], v134 offset:37888
	ds_read_b128 v[202:205], v134 offset:38912
	ds_read_b128 v[206:209], v134 offset:39936
	s_waitcnt vmcnt(2)
	s_barrier
;   #define LDA(dst,b,h) for(int m=0;m<4;++m)for(int k=0;k<2;++k) \
;     dst[m][k]=*reinterpret_cast<const h8*>(la+(((b)*2+(h))*16384+m*2048+k*1024))
;   #define LDB(dst,b,h) for(int n=0;n<2;++n)for(int k=0;k<2;++k) \
;     dst[n][k]=*reinterpret_cast<const h8*>(lb+(((b)*2+(h))*16384+n*2048+k*1024))
;   #define MMA(ai,bj,At,Bt_) do{__builtin_amdgcn_s_setprio(1); \
;     for(int m=0;m<4;++m)for(int n=0;n<2;++n)for(int k=0;k<2;++k) \
;       acc[ai][bj][m][n]=__builtin_amdgcn_mfma_f32_16x16x32_f16(At[m][k],Bt_[n][k],acc[ai][bj][m][n],0,0,0); \
;     __builtin_amdgcn_s_setprio(0);}while(0)
;   #define WAIT_V(n) asm volatile("s_waitcnt vmcnt(" #n ")":::"memory")
;   #define WAIT_L(n) asm volatile("s_waitcnt lgkmcnt(" #n ")":::"memory")
;   #define BAR __builtin_amdgcn_s_barrier()
;     ...
;   { LDB(B0,1,0); LDA(At,1,0); WAIT_V(2); BAR; WAIT_L(0); MMA(0,0,At,B0); BAR;
;     LDB(B1,1,1); WAIT_V(0); BAR; WAIT_L(0); MMA(0,1,At,B1); BAR;
;     LDA(At,1,1); BAR; WAIT_L(0); MMA(1,0,At,B0); MMA(1,1,At,B1); BAR; }
;   if(wr==0)BAR;
	s_waitcnt lgkmcnt(0)
	s_waitcnt lgkmcnt(0)
	v_mfma_f32_16x16x32_f16 v[124:127], v[72:75], v[140:143], v[124:127]
	v_mfma_f32_16x16x32_f16 v[120:123], v[72:75], v[148:151], v[120:123]
	v_mfma_f32_16x16x32_f16 v[116:119], v[186:189], v[140:143], v[116:119]
	v_mfma_f32_16x16x32_f16 v[112:115], v[186:189], v[148:151], v[112:115]
	v_mfma_f32_16x16x32_f16 v[108:111], v[194:197], v[140:143], v[108:111]
	v_mfma_f32_16x16x32_f16 v[104:107], v[194:197], v[148:151], v[104:107]
	v_mfma_f32_16x16x32_f16 v[100:103], v[202:205], v[140:143], v[100:103]
	v_mfma_f32_16x16x32_f16 v[96:99], v[202:205], v[148:151], v[96:99]
	v_mfma_f32_16x16x32_f16 v[124:127], v[162:165], v[144:147], v[124:127]
	v_mfma_f32_16x16x32_f16 v[120:123], v[162:165], v[158:161], v[120:123]
	v_mfma_f32_16x16x32_f16 v[116:119], v[190:193], v[144:147], v[116:119]
	v_mfma_f32_16x16x32_f16 v[112:115], v[190:193], v[158:161], v[112:115]
	v_mfma_f32_16x16x32_f16 v[108:111], v[198:201], v[144:147], v[108:111]
	v_mfma_f32_16x16x32_f16 v[104:107], v[198:201], v[158:161], v[104:107]
	v_mfma_f32_16x16x32_f16 v[100:103], v[206:209], v[144:147], v[100:103]
	v_mfma_f32_16x16x32_f16 v[96:99], v[206:209], v[158:161], v[96:99]
	s_barrier
	ds_read_b128 v[210:213], v135 offset:49152
	ds_read_b128 v[214:217], v135 offset:50176
	ds_read_b128 v[218:221], v135 offset:51200
	ds_read_b128 v[222:225], v135 offset:52224
	s_waitcnt vmcnt(0)
	s_barrier
	s_waitcnt lgkmcnt(0)
	s_waitcnt lgkmcnt(0)
	v_mfma_f32_16x16x32_f16 v[92:95], v[72:75], v[210:213], v[92:95]
	v_mfma_f32_16x16x32_f16 v[72:75], v[72:75], v[218:221], v[88:91]
	v_mfma_f32_16x16x32_f16 v[88:91], v[162:165], v[222:225], v[72:75]
	v_mfma_f32_16x16x32_f16 v[72:75], v[186:189], v[210:213], v[84:87]
	v_mfma_f32_16x16x32_f16 v[84:87], v[190:193], v[214:217], v[72:75]
	v_mfma_f32_16x16x32_f16 v[72:75], v[186:189], v[218:221], v[80:83]
	v_mfma_f32_16x16x32_f16 v[80:83], v[190:193], v[222:225], v[72:75]
	v_mfma_f32_16x16x32_f16 v[72:75], v[194:197], v[210:213], v[76:79]
	v_mfma_f32_16x16x32_f16 v[68:71], v[194:197], v[218:221], v[68:71]
	v_mfma_f32_16x16x32_f16 v[64:67], v[202:205], v[210:213], v[64:67]
	v_mfma_f32_16x16x32_f16 v[60:63], v[202:205], v[218:221], v[60:63]
	v_mfma_f32_16x16x32_f16 v[92:95], v[162:165], v[214:217], v[92:95]
	v_mfma_f32_16x16x32_f16 v[76:79], v[198:201], v[214:217], v[72:75]
	v_mfma_f32_16x16x32_f16 v[72:75], v[198:201], v[222:225], v[68:71]
	v_mfma_f32_16x16x32_f16 v[68:71], v[206:209], v[214:217], v[64:67]
	v_mfma_f32_16x16x32_f16 v[64:67], v[206:209], v[222:225], v[60:63]
	s_barrier
	ds_read_b128 v[162:165], v134 offset:49152
	ds_read_b128 v[186:189], v134 offset:50176
	ds_read_b128 v[190:193], v134 offset:51200
	ds_read_b128 v[194:197], v134 offset:52224
	ds_read_b128 v[198:201], v134 offset:53248
	ds_read_b128 v[202:205], v134 offset:54272
	ds_read_b128 v[206:209], v134 offset:55296
	ds_read_b128 v[226:229], v134 offset:56320
	s_barrier
	s_waitcnt lgkmcnt(0)
	s_waitcnt lgkmcnt(0)
	v_mfma_f32_16x16x32_f16 v[56:59], v[162:165], v[140:143], v[56:59]
	v_mfma_f32_16x16x32_f16 v[52:55], v[162:165], v[148:151], v[52:55]
	v_mfma_f32_16x16x32_f16 v[48:51], v[190:193], v[140:143], v[48:51]
	v_mfma_f32_16x16x32_f16 v[44:47], v[190:193], v[148:151], v[44:47]
	v_mfma_f32_16x16x32_f16 v[40:43], v[198:201], v[140:143], v[40:43]
	v_mfma_f32_16x16x32_f16 v[36:39], v[198:201], v[148:151], v[36:39]
	v_mfma_f32_16x16x32_f16 v[32:35], v[206:209], v[140:143], v[32:35]
	v_mfma_f32_16x16x32_f16 v[28:31], v[206:209], v[148:151], v[28:31]
	v_mfma_f32_16x16x32_f16 v[60:63], v[186:189], v[144:147], v[56:59]
	v_mfma_f32_16x16x32_f16 v[56:59], v[186:189], v[158:161], v[52:55]
	v_mfma_f32_16x16x32_f16 v[52:55], v[194:197], v[144:147], v[48:51]
	v_mfma_f32_16x16x32_f16 v[48:51], v[194:197], v[158:161], v[44:47]
	v_mfma_f32_16x16x32_f16 v[44:47], v[202:205], v[144:147], v[40:43]
	v_mfma_f32_16x16x32_f16 v[40:43], v[202:205], v[158:161], v[36:39]
	v_mfma_f32_16x16x32_f16 v[36:39], v[226:229], v[144:147], v[32:35]
	v_mfma_f32_16x16x32_f16 v[32:35], v[226:229], v[158:161], v[28:31]
	v_mfma_f32_16x16x32_f16 v[24:27], v[162:165], v[210:213], v[24:27]
	v_mfma_f32_16x16x32_f16 v[20:23], v[162:165], v[218:221], v[20:23]
	v_mfma_f32_16x16x32_f16 v[16:19], v[190:193], v[210:213], v[16:19]
	v_mfma_f32_16x16x32_f16 v[12:15], v[190:193], v[218:221], v[12:15]
	v_mfma_f32_16x16x32_f16 v[8:11], v[198:201], v[210:213], v[8:11]
	v_mfma_f32_16x16x32_f16 v[4:7], v[198:201], v[218:221], v[4:7]
	v_mfma_f32_16x16x32_f16 v[0:3], v[206:209], v[210:213], v[0:3]
	v_mfma_f32_16x16x32_f16 v[28:31], v[186:189], v[214:217], v[24:27]
	v_mfma_f32_16x16x32_f16 v[24:27], v[186:189], v[222:225], v[20:23]
	v_mfma_f32_16x16x32_f16 v[20:23], v[194:197], v[214:217], v[16:19]
	v_mfma_f32_16x16x32_f16 v[16:19], v[194:197], v[222:225], v[12:15]
	v_mfma_f32_16x16x32_f16 v[12:15], v[202:205], v[214:217], v[8:11]
	v_mfma_f32_16x16x32_f16 v[8:11], v[202:205], v[222:225], v[4:7]
	v_mfma_f32_16x16x32_f16 v[4:7], v[226:229], v[214:217], v[0:3]
	v_mfma_f32_16x16x32_f16 v[0:3], v[206:209], v[218:221], v[136:139]
	v_mfma_f32_16x16x32_f16 v[0:3], v[226:229], v[222:225], v[0:3]
	s_movk_i32 s12, 0x100
	v_cmp_gt_u32_e32 vcc, s12, v133
	s_barrier
	s_and_saveexec_b64 s[12:13], vcc
	s_cbranch_execz .LBB0_142
	s_barrier

;   #define STAGE(P,BASE,LD,br,kt) do{ const HALF* _u=(BASE)+(long)(br)*(((&(LD))==&lda)?lda_u:(LD))+(long)(kt)*G_BK; \
;     for(int _i=0;_i<2;++_i){ \
;       __builtin_amdgcn_global_load_lds((const unsigned*)(_u+(long)_i*(((&(LD))==&lda)?stepa:stepb)+((&(LD))==&lda?oa0:ob0)), \
;         (unsigned*)((char*)(P)+t5*16+_i*8192),16,0,0);}}while(0)
;   #define LDA(dst,b,h) for(int m=0;m<4;++m)for(int k=0;k<2;++k) \
;     dst[m][k]=*reinterpret_cast<const h8*>(la+(((b)*2+(h))*16384+m*2048+k*1024))
;   #define LDB(dst,b,h) for(int n=0;n<2;++n)for(int k=0;k<2;++k) \
;     dst[n][k]=*reinterpret_cast<const h8*>(lb+(((b)*2+(h))*16384+n*2048+k*1024))
;   #define MMA(ai,bj,At,Bt_) do{__builtin_amdgcn_s_setprio(1); \
;     for(int m=0;m<4;++m)for(int n=0;n<2;++n)for(int k=0;k<2;++k) \
;       acc[ai][bj][m][n]=__builtin_amdgcn_mfma_f32_16x16x32_f16(At[m][k],Bt_[n][k],acc[ai][bj][m][n],0,0,0); \
;     __builtin_amdgcn_s_setprio(0);}while(0)
;   #define WAIT_L(n) asm volatile("s_waitcnt lgkmcnt(" #n ")":::"memory")
;   #define BAR __builtin_amdgcn_s_barrier()
;   #define SCHED __builtin_amdgcn_sched_barrier(0)
;     ...
;   for(int t=0;t<nt-2;t+=2){
;     LDB(B0,0,0); SCHED; LDA(At,0,0); STAGE(SA(1,1),A,lda,G_HALF,t+1);
;     WAIT_L(8); BAR; WAIT_L(0); MMA(0,0,At,B0); BAR; SCHED;
;     LDB(B1,0,1); STAGE(SB(0,0),Bt,ldb,0,t+2);
;     BAR; WAIT_L(0); MMA(0,1,At,B1); BAR;
;     LDA(At,0,1); STAGE(SA(0,0),A,lda,0,t+2);
;     BAR; WAIT_L(0); MMA(1,0,At,B0); BAR; SCHED;
.LBB0_151:
	ds_read_b128 v[158:161], v135
	ds_read_b128 v[162:165], v135 offset:1024
	ds_read_b128 v[186:189], v135 offset:2048
	ds_read_b128 v[190:193], v135 offset:3072
	v_add_u32_e32 v150, 0xc000, v138
	v_lshl_add_u64 v[166:167], s[10:11], 0, v[128:129]
	s_mov_b64 s[12:13], 0x31ef0080
	v_readfirstlane_b32 s1, v150
	v_add_u32_e32 v151, 0xe000, v138
	v_lshl_add_u64 v[168:169], v[166:167], 0, s[12:13]
	s_mov_b32 m0, s1
	s_mov_b64 s[12:13], 0x31f10080
	v_readfirstlane_b32 s1, v151
	ds_read_b128 v[194:197], v134
	ds_read_b128 v[198:201], v134 offset:1024
	ds_read_b128 v[202:205], v134 offset:2048
	ds_read_b128 v[206:209], v134 offset:3072
	ds_read_b128 v[210:213], v134 offset:4096
	ds_read_b128 v[214:217], v134 offset:5120
	ds_read_b128 v[218:221], v134 offset:6144
	ds_read_b128 v[222:225], v134 offset:7168
	global_load_lds_dwordx4 v[168:169], off
	v_lshl_add_u64 v[168:169], v[166:167], 0, s[12:13]
	s_mov_b32 m0, s1
	s_nop 0
	global_load_lds_dwordx4 v[168:169], off
	s_waitcnt lgkmcnt(8)
	s_barrier
	s_waitcnt lgkmcnt(0)
	s_waitcnt lgkmcnt(0)
	v_mfma_f32_16x16x32_f16 v[124:127], v[194:197], v[158:161], v[124:127]
	v_mfma_f32_16x16x32_f16 v[120:123], v[194:197], v[186:189], v[120:123]
	v_mfma_f32_16x16x32_f16 v[116:119], v[202:205], v[158:161], v[116:119]
	v_mfma_f32_16x16x32_f16 v[112:115], v[202:205], v[186:189], v[112:115]
	v_mfma_f32_16x16x32_f16 v[108:111], v[210:213], v[158:161], v[108:111]
	v_mfma_f32_16x16x32_f16 v[104:107], v[210:213], v[186:189], v[104:107]
	v_mfma_f32_16x16x32_f16 v[100:103], v[218:221], v[158:161], v[100:103]
	v_mfma_f32_16x16x32_f16 v[96:99], v[218:221], v[186:189], v[96:99]
	v_mfma_f32_16x16x32_f16 v[124:127], v[198:201], v[162:165], v[124:127]
	v_mfma_f32_16x16x32_f16 v[120:123], v[198:201], v[190:193], v[120:123]
	v_mfma_f32_16x16x32_f16 v[116:119], v[206:209], v[162:165], v[116:119]
	v_mfma_f32_16x16x32_f16 v[112:115], v[206:209], v[190:193], v[112:115]
	v_mfma_f32_16x16x32_f16 v[108:111], v[214:217], v[162:165], v[108:111]
	v_mfma_f32_16x16x32_f16 v[104:107], v[214:217], v[190:193], v[104:107]
	v_mfma_f32_16x16x32_f16 v[100:103], v[222:225], v[162:165], v[100:103]
	v_mfma_f32_16x16x32_f16 v[96:99], v[222:225], v[190:193], v[96:99]
	s_barrier
	v_lshl_add_u64 v[168:169], s[8:9], 0, v[128:129]
	s_mov_b64 s[12:13], 0x2200100
	v_readfirstlane_b32 s1, v136
	v_lshl_add_u64 v[170:171], v[168:169], 0, s[12:13]
	s_mov_b32 m0, s1
	s_mov_b64 s[12:13], 0x2220100
	v_readfirstlane_b32 s1, v137
	ds_read_b128 v[226:229], v135 offset:16384
	ds_read_b128 v[230:233], v135 offset:17408
	ds_read_b128 v[234:237], v135 offset:18432
	ds_read_b128 v[238:241], v135 offset:19456
	global_load_lds_dwordx4 v[170:171], off
	v_lshl_add_u64 v[170:171], v[168:169], 0, s[12:13]
	s_mov_b32 m0, s1
	s_nop 0
	global_load_lds_dwordx4 v[170:171], off
	s_barrier
	s_waitcnt lgkmcnt(0)
	s_waitcnt lgkmcnt(0)
	v_mfma_f32_16x16x32_f16 v[92:95], v[194:197], v[226:229], v[92:95]
	v_mfma_f32_16x16x32_f16 v[88:91], v[194:197], v[234:237], v[88:91]
	v_mfma_f32_16x16x32_f16 v[84:87], v[202:205], v[226:229], v[84:87]
	v_mfma_f32_16x16x32_f16 v[80:83], v[202:205], v[234:237], v[80:83]
	v_mfma_f32_16x16x32_f16 v[76:79], v[210:213], v[226:229], v[76:79]
	v_mfma_f32_16x16x32_f16 v[68:71], v[210:213], v[234:237], v[68:71]
	v_mfma_f32_16x16x32_f16 v[64:67], v[218:221], v[226:229], v[64:67]
	v_mfma_f32_16x16x32_f16 v[60:63], v[218:221], v[234:237], v[60:63]
	v_mfma_f32_16x16x32_f16 v[92:95], v[198:201], v[230:233], v[92:95]
	v_mfma_f32_16x16x32_f16 v[88:91], v[198:201], v[238:241], v[88:91]
	v_mfma_f32_16x16x32_f16 v[84:87], v[206:209], v[230:233], v[84:87]
	v_mfma_f32_16x16x32_f16 v[80:83], v[206:209], v[238:241], v[80:83]
	v_mfma_f32_16x16x32_f16 v[76:79], v[214:217], v[230:233], v[76:79]
	v_mfma_f32_16x16x32_f16 v[68:71], v[214:217], v[238:241], v[68:71]
	v_mfma_f32_16x16x32_f16 v[64:67], v[222:225], v[230:233], v[64:67]
	v_mfma_f32_16x16x32_f16 v[60:63], v[222:225], v[238:241], v[60:63]
	s_mov_b64 s[12:13], 0x31eb0100
	v_readfirstlane_b32 s1, v138
	v_lshl_add_u64 v[170:171], v[166:167], 0, s[12:13]
	s_mov_b32 m0, s1
	s_mov_b64 s[12:13], 0x31ed0100
	v_readfirstlane_b32 s1, v139
	s_barrier
	ds_read_b128 v[194:197], v134 offset:16384
	ds_read_b128 v[198:201], v134 offset:17408
	ds_read_b128 v[202:205], v134 offset:18432
	ds_read_b128 v[206:209], v134 offset:19456
	ds_read_b128 v[210:213], v134 offset:20480
	ds_read_b128 v[214:217], v134 offset:21504
	ds_read_b128 v[218:221], v134 offset:22528
	ds_read_b128 v[222:225], v134 offset:23552
	global_load_lds_dwordx4 v[170:171], off
	v_lshl_add_u64 v[170:171], v[166:167], 0, s[12:13]
	s_mov_b32 m0, s1
	s_nop 0
	global_load_lds_dwordx4 v[170:171], off
	s_barrier
	s_waitcnt lgkmcnt(0)
	s_waitcnt lgkmcnt(0)
	v_mfma_f32_16x16x32_f16 v[56:59], v[194:197], v[158:161], v[56:59]
	v_mfma_f32_16x16x32_f16 v[52:55], v[194:197], v[186:189], v[52:55]
	v_mfma_f32_16x16x32_f16 v[48:51], v[202:205], v[158:161], v[48:51]
	v_mfma_f32_16x16x32_f16 v[44:47], v[202:205], v[186:189], v[44:47]
	v_mfma_f32_16x16x32_f16 v[40:43], v[210:213], v[158:161], v[40:43]
	v_mfma_f32_16x16x32_f16 v[36:39], v[210:213], v[186:189], v[36:39]
	v_mfma_f32_16x16x32_f16 v[32:35], v[218:221], v[158:161], v[32:35]
	v_mfma_f32_16x16x32_f16 v[28:31], v[218:221], v[186:189], v[28:31]
	v_mfma_f32_16x16x32_f16 v[56:59], v[198:201], v[162:165], v[56:59]
	v_mfma_f32_16x16x32_f16 v[52:55], v[198:201], v[190:193], v[52:55]
	v_mfma_f32_16x16x32_f16 v[48:51], v[206:209], v[162:165], v[48:51]
	v_mfma_f32_16x16x32_f16 v[44:47], v[206:209], v[190:193], v[44:47]
	v_mfma_f32_16x16x32_f16 v[40:43], v[214:217], v[162:165], v[40:43]
	v_mfma_f32_16x16x32_f16 v[36:39], v[214:217], v[190:193], v[36:39]
	v_mfma_f32_16x16x32_f16 v[32:35], v[222:225], v[162:165], v[32:35]
	v_mfma_f32_16x16x32_f16 v[28:31], v[222:225], v[190:193], v[28:31]
	s_barrier
;   #define STAGE(P,BASE,LD,br,kt) do{ const HALF* _u=(BASE)+(long)(br)*(((&(LD))==&lda)?lda_u:(LD))+(long)(kt)*G_BK; \
;     for(int _i=0;_i<2;++_i){ \
;       __builtin_amdgcn_global_load_lds((const unsigned*)(_u+(long)_i*(((&(LD))==&lda)?stepa:stepb)+((&(LD))==&lda?oa0:ob0)), \
;         (unsigned*)((char*)(P)+t5*16+_i*8192),16,0,0);}}while(0)
;   #define LDA(dst,b,h) for(int m=0;m<4;++m)for(int k=0;k<2;++k) \
;     dst[m][k]=*reinterpret_cast<const h8*>(la+(((b)*2+(h))*16384+m*2048+k*1024))
;   #define LDB(dst,b,h) for(int n=0;n<2;++n)for(int k=0;k<2;++k) \
;     dst[n][k]=*reinterpret_cast<const h8*>(lb+(((b)*2+(h))*16384+n*2048+k*1024))
;   #define MMA(ai,bj,At,Bt_) do{__builtin_amdgcn_s_setprio(1); \
;     for(int m=0;m<4;++m)for(int n=0;n<2;++n)for(int k=0;k<2;++k) \
;       acc[ai][bj][m][n]=__builtin_amdgcn_mfma_f32_16x16x32_f16(At[m][k],Bt_[n][k],acc[ai][bj][m][n],0,0,0); \
;     __builtin_amdgcn_s_setprio(0);}while(0)
;   #define WAIT_V(n) asm volatile("s_waitcnt vmcnt(" #n ")":::"memory")
;   #define WAIT_L(n) asm volatile("s_waitcnt lgkmcnt(" #n ")":::"memory")
;   #define BAR __builtin_amdgcn_s_barrier()
;   #define SCHED __builtin_amdgcn_sched_barrier(0)
;     ...
;     STAGE(SB(0,1),Bt,ldb,G_HALF,t+2);
;     WAIT_V(6); BAR; MMA(1,1,At,B1); BAR;
;     LDB(B0,1,0); SCHED; LDA(At,1,0); STAGE(SA(0,1),A,lda,G_HALF,t+2);
;     WAIT_L(8); BAR; WAIT_L(0); MMA(0,0,At,B0); BAR; SCHED;
;     LDB(B1,1,1); STAGE(SB(1,0),Bt,ldb,0,t+3);
;     BAR; WAIT_L(0); MMA(0,1,At,B1); BAR;
;     LDA(At,1,1); STAGE(SA(1,0),A,lda,0,t+3);
	s_mov_b64 s[12:13], 0x2240100
	v_readfirstlane_b32 s1, v140
	v_lshl_add_u64 v[158:159], v[168:169], 0, s[12:13]
	s_mov_b32 m0, s1
	s_mov_b64 s[12:13], 0x2260100
	v_readfirstlane_b32 s1, v141
	global_load_lds_dwordx4 v[158:159], off
	v_lshl_add_u64 v[158:159], v[168:169], 0, s[12:13]
	s_mov_b32 m0, s1
	s_nop 0
	global_load_lds_dwordx4 v[158:159], off
	s_waitcnt vmcnt(6)
	s_barrier
	v_mfma_f32_16x16x32_f16 v[24:27], v[194:197], v[226:229], v[24:27]
	v_mfma_f32_16x16x32_f16 v[20:23], v[194:197], v[234:237], v[20:23]
	v_mfma_f32_16x16x32_f16 v[16:19], v[202:205], v[226:229], v[16:19]
	v_mfma_f32_16x16x32_f16 v[12:15], v[202:205], v[234:237], v[12:15]
	v_mfma_f32_16x16x32_f16 v[8:11], v[210:213], v[226:229], v[8:11]
	v_mfma_f32_16x16x32_f16 v[4:7], v[210:213], v[234:237], v[4:7]
	v_mfma_f32_16x16x32_f16 v[0:3], v[218:221], v[226:229], v[0:3]
	v_mfma_f32_16x16x32_f16 v[72:75], v[218:221], v[234:237], v[72:75]
	v_mfma_f32_16x16x32_f16 v[24:27], v[198:201], v[230:233], v[24:27]
	v_mfma_f32_16x16x32_f16 v[20:23], v[198:201], v[238:241], v[20:23]
	v_mfma_f32_16x16x32_f16 v[16:19], v[206:209], v[230:233], v[16:19]
	v_mfma_f32_16x16x32_f16 v[12:15], v[206:209], v[238:241], v[12:15]
	v_mfma_f32_16x16x32_f16 v[8:11], v[214:217], v[230:233], v[8:11]
	v_mfma_f32_16x16x32_f16 v[4:7], v[214:217], v[238:241], v[4:7]
	v_mfma_f32_16x16x32_f16 v[0:3], v[222:225], v[230:233], v[0:3]
	v_mfma_f32_16x16x32_f16 v[72:75], v[222:225], v[238:241], v[72:75]
	s_barrier
	ds_read_b128 v[158:161], v135 offset:32768
	ds_read_b128 v[162:165], v135 offset:33792
	ds_read_b128 v[186:189], v135 offset:34816
	ds_read_b128 v[190:193], v135 offset:35840
	s_mov_b64 s[12:13], 0x31ef0100
	v_readfirstlane_b32 s1, v142
	v_lshl_add_u64 v[170:171], v[166:167], 0, s[12:13]
	s_mov_b32 m0, s1
	s_mov_b64 s[12:13], 0x31f10100
	v_readfirstlane_b32 s1, v143
	ds_read_b128 v[194:197], v134 offset:32768
	ds_read_b128 v[198:201], v134 offset:33792
	ds_read_b128 v[202:205], v134 offset:34816
	ds_read_b128 v[206:209], v134 offset:35840
	ds_read_b128 v[210:213], v134 offset:36864
	ds_read_b128 v[214:217], v134 offset:37888
	ds_read_b128 v[218:221], v134 offset:38912
	ds_read_b128 v[222:225], v134 offset:39936
	global_load_lds_dwordx4 v[170:171], off
	v_lshl_add_u64 v[170:171], v[166:167], 0, s[12:13]
	s_mov_b32 m0, s1
	s_nop 0
	global_load_lds_dwordx4 v[170:171], off
	s_waitcnt lgkmcnt(8)
	s_barrier
	s_waitcnt lgkmcnt(0)
	s_waitcnt lgkmcnt(0)
	v_mfma_f32_16x16x32_f16 v[124:127], v[194:197], v[158:161], v[124:127]
	v_mfma_f32_16x16x32_f16 v[120:123], v[194:197], v[186:189], v[120:123]
	v_mfma_f32_16x16x32_f16 v[116:119], v[202:205], v[158:161], v[116:119]
	v_mfma_f32_16x16x32_f16 v[112:115], v[202:205], v[186:189], v[112:115]
	v_mfma_f32_16x16x32_f16 v[108:111], v[210:213], v[158:161], v[108:111]
	v_mfma_f32_16x16x32_f16 v[104:107], v[210:213], v[186:189], v[104:107]
	v_mfma_f32_16x16x32_f16 v[100:103], v[218:221], v[158:161], v[100:103]
	v_mfma_f32_16x16x32_f16 v[96:99], v[218:221], v[186:189], v[96:99]
	v_mfma_f32_16x16x32_f16 v[124:127], v[198:201], v[162:165], v[124:127]
	v_mfma_f32_16x16x32_f16 v[120:123], v[198:201], v[190:193], v[120:123]
	v_mfma_f32_16x16x32_f16 v[116:119], v[206:209], v[162:165], v[116:119]
	v_mfma_f32_16x16x32_f16 v[112:115], v[206:209], v[190:193], v[112:115]
	v_mfma_f32_16x16x32_f16 v[108:111], v[214:217], v[162:165], v[108:111]
	v_mfma_f32_16x16x32_f16 v[104:107], v[214:217], v[190:193], v[104:107]
	v_mfma_f32_16x16x32_f16 v[100:103], v[222:225], v[162:165], v[100:103]
	v_mfma_f32_16x16x32_f16 v[96:99], v[222:225], v[190:193], v[96:99]
	s_barrier
	s_mov_b64 s[12:13], 0x2200180
	v_readfirstlane_b32 s1, v144
	v_lshl_add_u64 v[170:171], v[168:169], 0, s[12:13]
	s_mov_b32 m0, s1
	s_mov_b64 s[12:13], 0x2220180
	v_readfirstlane_b32 s1, v145
	ds_read_b128 v[226:229], v135 offset:49152
	ds_read_b128 v[230:233], v135 offset:50176
	ds_read_b128 v[234:237], v135 offset:51200
	ds_read_b128 v[238:241], v135 offset:52224
	global_load_lds_dwordx4 v[170:171], off
	v_lshl_add_u64 v[170:171], v[168:169], 0, s[12:13]
	s_mov_b32 m0, s1
	s_nop 0
	global_load_lds_dwordx4 v[170:171], off
	s_barrier
	s_waitcnt lgkmcnt(0)
	s_waitcnt lgkmcnt(0)
	v_mfma_f32_16x16x32_f16 v[92:95], v[194:197], v[226:229], v[92:95]
	v_mfma_f32_16x16x32_f16 v[88:91], v[194:197], v[234:237], v[88:91]
	v_mfma_f32_16x16x32_f16 v[84:87], v[202:205], v[226:229], v[84:87]
	v_mfma_f32_16x16x32_f16 v[80:83], v[202:205], v[234:237], v[80:83]
	v_mfma_f32_16x16x32_f16 v[76:79], v[210:213], v[226:229], v[76:79]
	v_mfma_f32_16x16x32_f16 v[68:71], v[210:213], v[234:237], v[68:71]
	v_mfma_f32_16x16x32_f16 v[64:67], v[218:221], v[226:229], v[64:67]
	v_mfma_f32_16x16x32_f16 v[60:63], v[218:221], v[234:237], v[60:63]
	v_mfma_f32_16x16x32_f16 v[92:95], v[198:201], v[230:233], v[92:95]
	v_mfma_f32_16x16x32_f16 v[88:91], v[198:201], v[238:241], v[88:91]
	v_mfma_f32_16x16x32_f16 v[84:87], v[206:209], v[230:233], v[84:87]
	v_mfma_f32_16x16x32_f16 v[80:83], v[206:209], v[238:241], v[80:83]
	v_mfma_f32_16x16x32_f16 v[76:79], v[214:217], v[230:233], v[76:79]
	v_mfma_f32_16x16x32_f16 v[68:71], v[214:217], v[238:241], v[68:71]
	v_mfma_f32_16x16x32_f16 v[64:67], v[222:225], v[230:233], v[64:67]
	v_mfma_f32_16x16x32_f16 v[60:63], v[222:225], v[238:241], v[60:63]
	s_mov_b64 s[12:13], 0x31eb0180
	v_readfirstlane_b32 s1, v146
	v_lshl_add_u64 v[170:171], v[166:167], 0, s[12:13]
	s_mov_b32 m0, s1
	s_mov_b64 s[12:13], 0x31ed0180
	v_readfirstlane_b32 s1, v147
	s_barrier
;   #define STAGE(P,BASE,LD,br,kt) do{ const HALF* _u=(BASE)+(long)(br)*(((&(LD))==&lda)?lda_u:(LD))+(long)(kt)*G_BK; \
;     for(int _i=0;_i<2;++_i){ \
;       __builtin_amdgcn_global_load_lds((const unsigned*)(_u+(long)_i*(((&(LD))==&lda)?stepa:stepb)+((&(LD))==&lda?oa0:ob0)), \
;         (unsigned*)((char*)(P)+t5*16+_i*8192),16,0,0);}}while(0)
;   #define LDA(dst,b,h) for(int m=0;m<4;++m)for(int k=0;k<2;++k) \
;     dst[m][k]=*reinterpret_cast<const h8*>(la+(((b)*2+(h))*16384+m*2048+k*1024))
;   #define LDB(dst,b,h) for(int n=0;n<2;++n)for(int k=0;k<2;++k) \
;     dst[n][k]=*reinterpret_cast<const h8*>(lb+(((b)*2+(h))*16384+n*2048+k*1024))
;   #define MMA(ai,bj,At,Bt_) do{__builtin_amdgcn_s_setprio(1); \
;     for(int m=0;m<4;++m)for(int n=0;n<2;++n)for(int k=0;k<2;++k) \
;       acc[ai][bj][m][n]=__builtin_amdgcn_mfma_f32_16x16x32_f16(At[m][k],Bt_[n][k],acc[ai][bj][m][n],0,0,0); \
;     __builtin_amdgcn_s_setprio(0);}while(0)
;   #define WAIT_V(n) asm volatile("s_waitcnt vmcnt(" #n ")":::"memory")
;   #define WAIT_L(n) asm volatile("s_waitcnt lgkmcnt(" #n ")":::"memory")
;   #define BAR __builtin_amdgcn_s_barrier()
;   #define SCHED __builtin_amdgcn_sched_barrier(0)
;     ...
;     LDA(At,1,1); STAGE(SA(1,0),A,lda,0,t+3);
;     BAR; WAIT_L(0); MMA(1,0,At,B0); BAR; SCHED;
;     STAGE(SB(1,1),Bt,ldb,G_HALF,t+3);
;     WAIT_V(6); BAR; MMA(1,1,At,B1); BAR;
;   }
;   { LDB(B0,0,0); LDA(At,0,0); STAGE(SA(1,1),A,lda,G_HALF,nt-1);
;     BAR; WAIT_L(0); MMA(0,0,At,B0); BAR;
;     LDB(B1,0,1); BAR; WAIT_L(0); MMA(0,1,At,B1); BAR;
	ds_read_b128 v[194:197], v134 offset:49152
	ds_read_b128 v[198:201], v134 offset:50176
	ds_read_b128 v[202:205], v134 offset:51200
	ds_read_b128 v[206:209], v134 offset:52224
	ds_read_b128 v[210:213], v134 offset:53248
	ds_read_b128 v[214:217], v134 offset:54272
	ds_read_b128 v[218:221], v134 offset:55296
	ds_read_b128 v[222:225], v134 offset:56320
	global_load_lds_dwordx4 v[170:171], off
	v_lshl_add_u64 v[166:167], v[166:167], 0, s[12:13]
	s_mov_b32 m0, s1
	s_nop 0
	global_load_lds_dwordx4 v[166:167], off
	s_barrier
	s_waitcnt lgkmcnt(0)
	s_waitcnt lgkmcnt(0)
	v_mfma_f32_16x16x32_f16 v[56:59], v[194:197], v[158:161], v[56:59]
	v_mfma_f32_16x16x32_f16 v[52:55], v[194:197], v[186:189], v[52:55]
	v_mfma_f32_16x16x32_f16 v[48:51], v[202:205], v[158:161], v[48:51]
	v_mfma_f32_16x16x32_f16 v[44:47], v[202:205], v[186:189], v[44:47]
	v_mfma_f32_16x16x32_f16 v[40:43], v[210:213], v[158:161], v[40:43]
	v_mfma_f32_16x16x32_f16 v[36:39], v[210:213], v[186:189], v[36:39]
	v_mfma_f32_16x16x32_f16 v[32:35], v[218:221], v[158:161], v[32:35]
	v_mfma_f32_16x16x32_f16 v[28:31], v[218:221], v[186:189], v[28:31]
	v_mfma_f32_16x16x32_f16 v[56:59], v[198:201], v[162:165], v[56:59]
	v_mfma_f32_16x16x32_f16 v[52:55], v[198:201], v[190:193], v[52:55]
	v_mfma_f32_16x16x32_f16 v[48:51], v[206:209], v[162:165], v[48:51]
	v_mfma_f32_16x16x32_f16 v[44:47], v[206:209], v[190:193], v[44:47]
	v_mfma_f32_16x16x32_f16 v[40:43], v[214:217], v[162:165], v[40:43]
	v_mfma_f32_16x16x32_f16 v[36:39], v[214:217], v[190:193], v[36:39]
	v_mfma_f32_16x16x32_f16 v[32:35], v[222:225], v[162:165], v[32:35]
	v_mfma_f32_16x16x32_f16 v[28:31], v[222:225], v[190:193], v[28:31]
	s_barrier
	s_mov_b64 s[12:13], 0x2240180
	v_readfirstlane_b32 s1, v148
	v_lshl_add_u64 v[158:159], v[168:169], 0, s[12:13]
	s_mov_b32 m0, s1
	s_mov_b64 s[12:13], 0x2260180
	v_readfirstlane_b32 s1, v149
	global_load_lds_dwordx4 v[158:159], off
	v_lshl_add_u64 v[158:159], v[168:169], 0, s[12:13]
	s_mov_b32 m0, s1
	s_nop 0
	global_load_lds_dwordx4 v[158:159], off
	s_waitcnt vmcnt(6)
	s_barrier
	v_mfma_f32_16x16x32_f16 v[24:27], v[194:197], v[226:229], v[24:27]
	v_mfma_f32_16x16x32_f16 v[20:23], v[194:197], v[234:237], v[20:23]
	v_mfma_f32_16x16x32_f16 v[16:19], v[202:205], v[226:229], v[16:19]
	v_mfma_f32_16x16x32_f16 v[12:15], v[202:205], v[234:237], v[12:15]
	v_mfma_f32_16x16x32_f16 v[8:11], v[210:213], v[226:229], v[8:11]
	v_mfma_f32_16x16x32_f16 v[4:7], v[210:213], v[234:237], v[4:7]
	v_mfma_f32_16x16x32_f16 v[0:3], v[218:221], v[226:229], v[0:3]
	v_mfma_f32_16x16x32_f16 v[72:75], v[218:221], v[234:237], v[72:75]
	v_mfma_f32_16x16x32_f16 v[24:27], v[198:201], v[230:233], v[24:27]
	v_mfma_f32_16x16x32_f16 v[20:23], v[198:201], v[238:241], v[20:23]
	v_mfma_f32_16x16x32_f16 v[16:19], v[206:209], v[230:233], v[16:19]
	v_mfma_f32_16x16x32_f16 v[12:15], v[206:209], v[238:241], v[12:15]
	v_mfma_f32_16x16x32_f16 v[8:11], v[214:217], v[230:233], v[8:11]
	v_mfma_f32_16x16x32_f16 v[4:7], v[214:217], v[238:241], v[4:7]
	v_mfma_f32_16x16x32_f16 v[0:3], v[222:225], v[230:233], v[0:3]
	v_mfma_f32_16x16x32_f16 v[72:75], v[222:225], v[238:241], v[72:75]
	s_add_i32 s0, s0, 2
	s_add_u32 s8, s8, 0x100
	s_addc_u32 s9, s9, 0
	s_add_u32 s10, s10, 0x100
	s_addc_u32 s11, s11, 0
	s_cmp_lt_u32 s0, 12
	s_barrier
	s_cbranch_scc1 .LBB0_151
	v_lshl_add_u64 v[128:129], v[152:153], 1, s[58:59]
	s_mov_b64 s[0:1], 0x40780
	v_lshl_add_u64 v[148:149], v[128:129], 0, s[0:1]
	v_readfirstlane_b32 s0, v150
	s_mov_b32 m0, s0
	s_mov_b64 s[0:1], 0x60780
	v_lshl_add_u64 v[128:129], v[128:129], 0, s[0:1]
	v_readfirstlane_b32 s0, v151
	ds_read_b128 v[136:139], v135
	ds_read_b128 v[140:143], v135 offset:1024
	ds_read_b128 v[144:147], v135 offset:2048
	ds_read_b128 v[158:161], v135 offset:3072
	ds_read_b128 v[162:165], v134
	ds_read_b128 v[186:189], v134 offset:1024
	ds_read_b128 v[190:193], v134 offset:2048
	ds_read_b128 v[194:197], v134 offset:3072
	ds_read_b128 v[198:201], v134 offset:4096
	ds_read_b128 v[202:205], v134 offset:5120
	ds_read_b128 v[206:209], v134 offset:6144
	ds_read_b128 v[210:213], v134 offset:7168
	global_load_lds_dwordx4 v[148:149], off
	s_mov_b32 m0, s0
	s_nop 0
	global_load_lds_dwordx4 v[128:129], off
	s_barrier
	s_waitcnt lgkmcnt(0)
	s_waitcnt lgkmcnt(0)
	v_mfma_f32_16x16x32_f16 v[124:127], v[162:165], v[136:139], v[124:127]
	v_mfma_f32_16x16x32_f16 v[120:123], v[162:165], v[144:147], v[120:123]
	v_mfma_f32_16x16x32_f16 v[116:119], v[190:193], v[136:139], v[116:119]
	v_mfma_f32_16x16x32_f16 v[112:115], v[190:193], v[144:147], v[112:115]
	v_mfma_f32_16x16x32_f16 v[108:111], v[198:201], v[136:139], v[108:111]
	v_mfma_f32_16x16x32_f16 v[104:107], v[198:201], v[144:147], v[104:107]
	v_mfma_f32_16x16x32_f16 v[100:103], v[206:209], v[136:139], v[100:103]
	v_mfma_f32_16x16x32_f16 v[96:99], v[206:209], v[144:147], v[96:99]
	v_mfma_f32_16x16x32_f16 v[124:127], v[186:189], v[140:143], v[124:127]
	v_mfma_f32_16x16x32_f16 v[120:123], v[186:189], v[158:161], v[120:123]
	v_mfma_f32_16x16x32_f16 v[116:119], v[194:197], v[140:143], v[116:119]
	v_mfma_f32_16x16x32_f16 v[112:115], v[194:197], v[158:161], v[112:115]
	v_mfma_f32_16x16x32_f16 v[108:111], v[202:205], v[140:143], v[108:111]
	v_mfma_f32_16x16x32_f16 v[104:107], v[202:205], v[158:161], v[104:107]
	v_mfma_f32_16x16x32_f16 v[100:103], v[210:213], v[140:143], v[100:103]
	v_mfma_f32_16x16x32_f16 v[96:99], v[210:213], v[158:161], v[96:99]
	s_barrier
	ds_read_b128 v[148:151], v135 offset:16384
	ds_read_b128 v[214:217], v135 offset:17408
	ds_read_b128 v[218:221], v135 offset:18432
	ds_read_b128 v[222:225], v135 offset:19456
	s_barrier
;   #define LDA(dst,b,h) for(int m=0;m<4;++m)for(int k=0;k<2;++k) \
;     dst[m][k]=*reinterpret_cast<const h8*>(la+(((b)*2+(h))*16384+m*2048+k*1024))
;   #define LDB(dst,b,h) for(int n=0;n<2;++n)for(int k=0;k<2;++k) \
;     dst[n][k]=*reinterpret_cast<const h8*>(lb+(((b)*2+(h))*16384+n*2048+k*1024))
;   #define MMA(ai,bj,At,Bt_) do{__builtin_amdgcn_s_setprio(1); \
;     for(int m=0;m<4;++m)for(int n=0;n<2;++n)for(int k=0;k<2;++k) \
;       acc[ai][bj][m][n]=__builtin_amdgcn_mfma_f32_16x16x32_f16(At[m][k],Bt_[n][k],acc[ai][bj][m][n],0,0,0); \
;     __builtin_amdgcn_s_setprio(0);}while(0)
;   #define WAIT_V(n) asm volatile("s_waitcnt vmcnt(" #n ")":::"memory")
;   #define WAIT_L(n) asm volatile("s_waitcnt lgkmcnt(" #n ")":::"memory")
;   #define BAR __builtin_amdgcn_s_barrier()
;     ...
;     LDB(B1,0,1); BAR; WAIT_L(0); MMA(0,1,At,B1); BAR;
;     LDA(At,0,1); WAIT_V(4); BAR; WAIT_L(0); MMA(1,0,At,B0); MMA(1,1,At,B1); BAR; }
;   { LDB(B0,1,0); LDA(At,1,0); WAIT_V(2); BAR; WAIT_L(0); MMA(0,0,At,B0); BAR;
	s_waitcnt lgkmcnt(0)
	s_waitcnt lgkmcnt(0)
	v_mfma_f32_16x16x32_f16 v[92:95], v[162:165], v[148:151], v[92:95]
	v_mfma_f32_16x16x32_f16 v[88:91], v[162:165], v[218:221], v[88:91]
	v_mfma_f32_16x16x32_f16 v[84:87], v[190:193], v[148:151], v[84:87]
	v_mfma_f32_16x16x32_f16 v[80:83], v[190:193], v[218:221], v[80:83]
	v_mfma_f32_16x16x32_f16 v[76:79], v[198:201], v[148:151], v[76:79]
	v_mfma_f32_16x16x32_f16 v[68:71], v[198:201], v[218:221], v[68:71]
	v_mfma_f32_16x16x32_f16 v[64:67], v[206:209], v[148:151], v[64:67]
	v_mfma_f32_16x16x32_f16 v[60:63], v[206:209], v[218:221], v[60:63]
	v_mfma_f32_16x16x32_f16 v[92:95], v[186:189], v[214:217], v[92:95]
	v_mfma_f32_16x16x32_f16 v[88:91], v[186:189], v[222:225], v[88:91]
	v_mfma_f32_16x16x32_f16 v[84:87], v[194:197], v[214:217], v[84:87]
	v_mfma_f32_16x16x32_f16 v[80:83], v[194:197], v[222:225], v[80:83]
	v_mfma_f32_16x16x32_f16 v[76:79], v[202:205], v[214:217], v[76:79]
	v_mfma_f32_16x16x32_f16 v[68:71], v[202:205], v[222:225], v[68:71]
	v_mfma_f32_16x16x32_f16 v[64:67], v[210:213], v[214:217], v[64:67]
	v_mfma_f32_16x16x32_f16 v[60:63], v[210:213], v[222:225], v[60:63]
	s_barrier
	ds_read_b128 v[162:165], v134 offset:16384
	ds_read_b128 v[186:189], v134 offset:17408
	ds_read_b128 v[190:193], v134 offset:18432
	ds_read_b128 v[194:197], v134 offset:19456
	ds_read_b128 v[198:201], v134 offset:20480
	ds_read_b128 v[202:205], v134 offset:21504
	ds_read_b128 v[206:209], v134 offset:22528
	ds_read_b128 v[210:213], v134 offset:23552
	s_waitcnt vmcnt(4)
	s_barrier
	s_waitcnt lgkmcnt(0)
	s_waitcnt lgkmcnt(0)
	v_mfma_f32_16x16x32_f16 v[56:59], v[162:165], v[136:139], v[56:59]
	v_mfma_f32_16x16x32_f16 v[52:55], v[162:165], v[144:147], v[52:55]
	v_mfma_f32_16x16x32_f16 v[48:51], v[190:193], v[136:139], v[48:51]
	v_mfma_f32_16x16x32_f16 v[44:47], v[190:193], v[144:147], v[44:47]
	v_mfma_f32_16x16x32_f16 v[40:43], v[198:201], v[136:139], v[40:43]
	v_mfma_f32_16x16x32_f16 v[36:39], v[198:201], v[144:147], v[36:39]
	v_mfma_f32_16x16x32_f16 v[32:35], v[206:209], v[136:139], v[32:35]
	v_mfma_f32_16x16x32_f16 v[28:31], v[206:209], v[144:147], v[28:31]
	v_mfma_f32_16x16x32_f16 v[56:59], v[186:189], v[140:143], v[56:59]
	v_mfma_f32_16x16x32_f16 v[52:55], v[186:189], v[158:161], v[52:55]
	v_mfma_f32_16x16x32_f16 v[48:51], v[194:197], v[140:143], v[48:51]
	v_mfma_f32_16x16x32_f16 v[44:47], v[194:197], v[158:161], v[44:47]
	v_mfma_f32_16x16x32_f16 v[40:43], v[202:205], v[140:143], v[40:43]
	v_mfma_f32_16x16x32_f16 v[36:39], v[202:205], v[158:161], v[36:39]
	v_mfma_f32_16x16x32_f16 v[32:35], v[210:213], v[140:143], v[32:35]
	v_mfma_f32_16x16x32_f16 v[28:31], v[210:213], v[158:161], v[28:31]
	v_mfma_f32_16x16x32_f16 v[24:27], v[162:165], v[148:151], v[24:27]
	v_mfma_f32_16x16x32_f16 v[20:23], v[162:165], v[218:221], v[20:23]
	v_mfma_f32_16x16x32_f16 v[16:19], v[190:193], v[148:151], v[16:19]
	v_mfma_f32_16x16x32_f16 v[12:15], v[190:193], v[218:221], v[12:15]
	v_mfma_f32_16x16x32_f16 v[8:11], v[198:201], v[148:151], v[8:11]
	v_mfma_f32_16x16x32_f16 v[4:7], v[198:201], v[218:221], v[4:7]
	v_mfma_f32_16x16x32_f16 v[0:3], v[206:209], v[148:151], v[0:3]
	v_mfma_f32_16x16x32_f16 v[24:27], v[186:189], v[214:217], v[24:27]
	v_mfma_f32_16x16x32_f16 v[20:23], v[186:189], v[222:225], v[20:23]
	v_mfma_f32_16x16x32_f16 v[16:19], v[194:197], v[214:217], v[16:19]
	v_mfma_f32_16x16x32_f16 v[12:15], v[194:197], v[222:225], v[12:15]
	v_mfma_f32_16x16x32_f16 v[8:11], v[202:205], v[214:217], v[8:11]
	v_mfma_f32_16x16x32_f16 v[4:7], v[202:205], v[222:225], v[4:7]
	v_mfma_f32_16x16x32_f16 v[0:3], v[210:213], v[214:217], v[0:3]
	v_mfma_f32_16x16x32_f16 v[72:75], v[206:209], v[218:221], v[72:75]
	v_mfma_f32_16x16x32_f16 v[136:139], v[210:213], v[222:225], v[72:75]
	s_barrier
	ds_read_b128 v[140:143], v135 offset:32768
	ds_read_b128 v[144:147], v135 offset:33792
	ds_read_b128 v[148:151], v135 offset:34816
	ds_read_b128 v[158:161], v135 offset:35840
	s_nop 0
	ds_read_b128 v[72:75], v134 offset:32768
	ds_read_b128 v[162:165], v134 offset:33792
	ds_read_b128 v[186:189], v134 offset:34816
	ds_read_b128 v[190:193], v134 offset:35840
	ds_read_b128 v[194:197], v134 offset:36864
	ds_read_b128 v[198:201], v134 offset:37888
	ds_read_b128 v[202:205], v134 offset:38912
	ds_read_b128 v[206:209], v134 offset:39936
	s_waitcnt vmcnt(2)
	s_barrier
;   #define LDA(dst,b,h) for(int m=0;m<4;++m)for(int k=0;k<2;++k) \
;     dst[m][k]=*reinterpret_cast<const h8*>(la+(((b)*2+(h))*16384+m*2048+k*1024))
;   #define LDB(dst,b,h) for(int n=0;n<2;++n)for(int k=0;k<2;++k) \
;     dst[n][k]=*reinterpret_cast<const h8*>(lb+(((b)*2+(h))*16384+n*2048+k*1024))
;   #define MMA(ai,bj,At,Bt_) do{__builtin_amdgcn_s_setprio(1); \
;     for(int m=0;m<4;++m)for(int n=0;n<2;++n)for(int k=0;k<2;++k) \
;       acc[ai][bj][m][n]=__builtin_amdgcn_mfma_f32_16x16x32_f16(At[m][k],Bt_[n][k],acc[ai][bj][m][n],0,0,0); \
;     __builtin_amdgcn_s_setprio(0);}while(0)
;   #define WAIT_V(n) asm volatile("s_waitcnt vmcnt(" #n ")":::"memory")
;   #define WAIT_L(n) asm volatile("s_waitcnt lgkmcnt(" #n ")":::"memory")
;   #define BAR __builtin_amdgcn_s_barrier()
;     ...
;   { LDB(B0,1,0); LDA(At,1,0); WAIT_V(2); BAR; WAIT_L(0); MMA(0,0,At,B0); BAR;
;     LDB(B1,1,1); WAIT_V(0); BAR; WAIT_L(0); MMA(0,1,At,B1); BAR;
;     LDA(At,1,1); BAR; WAIT_L(0); MMA(1,0,At,B0); MMA(1,1,At,B1); BAR; }
;   if(wr==0)BAR;
	s_waitcnt lgkmcnt(0)
	s_waitcnt lgkmcnt(0)
	v_mfma_f32_16x16x32_f16 v[124:127], v[72:75], v[140:143], v[124:127]
	v_mfma_f32_16x16x32_f16 v[120:123], v[72:75], v[148:151], v[120:123]
	v_mfma_f32_16x16x32_f16 v[116:119], v[186:189], v[140:143], v[116:119]
	v_mfma_f32_16x16x32_f16 v[112:115], v[186:189], v[148:151], v[112:115]
	v_mfma_f32_16x16x32_f16 v[108:111], v[194:197], v[140:143], v[108:111]
	v_mfma_f32_16x16x32_f16 v[104:107], v[194:197], v[148:151], v[104:107]
	v_mfma_f32_16x16x32_f16 v[100:103], v[202:205], v[140:143], v[100:103]
	v_mfma_f32_16x16x32_f16 v[96:99], v[202:205], v[148:151], v[96:99]
	v_mfma_f32_16x16x32_f16 v[124:127], v[162:165], v[144:147], v[124:127]
	v_mfma_f32_16x16x32_f16 v[120:123], v[162:165], v[158:161], v[120:123]
	v_mfma_f32_16x16x32_f16 v[116:119], v[190:193], v[144:147], v[116:119]
	v_mfma_f32_16x16x32_f16 v[112:115], v[190:193], v[158:161], v[112:115]
	v_mfma_f32_16x16x32_f16 v[108:111], v[198:201], v[144:147], v[108:111]
	v_mfma_f32_16x16x32_f16 v[104:107], v[198:201], v[158:161], v[104:107]
	v_mfma_f32_16x16x32_f16 v[100:103], v[206:209], v[144:147], v[100:103]
	v_mfma_f32_16x16x32_f16 v[96:99], v[206:209], v[158:161], v[96:99]
	s_barrier
	ds_read_b128 v[210:213], v135 offset:49152
	ds_read_b128 v[214:217], v135 offset:50176
	ds_read_b128 v[218:221], v135 offset:51200
	ds_read_b128 v[222:225], v135 offset:52224
	s_waitcnt vmcnt(0)
	s_barrier
	s_waitcnt lgkmcnt(0)
	s_waitcnt lgkmcnt(0)
	v_mfma_f32_16x16x32_f16 v[92:95], v[72:75], v[210:213], v[92:95]
	v_mfma_f32_16x16x32_f16 v[72:75], v[72:75], v[218:221], v[88:91]
	v_mfma_f32_16x16x32_f16 v[88:91], v[162:165], v[222:225], v[72:75]
	v_mfma_f32_16x16x32_f16 v[72:75], v[186:189], v[210:213], v[84:87]
	v_mfma_f32_16x16x32_f16 v[84:87], v[190:193], v[214:217], v[72:75]
	v_mfma_f32_16x16x32_f16 v[72:75], v[186:189], v[218:221], v[80:83]
	v_mfma_f32_16x16x32_f16 v[80:83], v[190:193], v[222:225], v[72:75]
	v_mfma_f32_16x16x32_f16 v[72:75], v[194:197], v[210:213], v[76:79]
	v_mfma_f32_16x16x32_f16 v[68:71], v[194:197], v[218:221], v[68:71]
	v_mfma_f32_16x16x32_f16 v[64:67], v[202:205], v[210:213], v[64:67]
	v_mfma_f32_16x16x32_f16 v[60:63], v[202:205], v[218:221], v[60:63]
	v_mfma_f32_16x16x32_f16 v[92:95], v[162:165], v[214:217], v[92:95]
	v_mfma_f32_16x16x32_f16 v[76:79], v[198:201], v[214:217], v[72:75]
	v_mfma_f32_16x16x32_f16 v[72:75], v[198:201], v[222:225], v[68:71]
	v_mfma_f32_16x16x32_f16 v[68:71], v[206:209], v[214:217], v[64:67]
	v_mfma_f32_16x16x32_f16 v[64:67], v[206:209], v[222:225], v[60:63]
	s_barrier
	ds_read_b128 v[162:165], v134 offset:49152
	ds_read_b128 v[186:189], v134 offset:50176
	ds_read_b128 v[190:193], v134 offset:51200
	ds_read_b128 v[194:197], v134 offset:52224
	ds_read_b128 v[198:201], v134 offset:53248
	ds_read_b128 v[202:205], v134 offset:54272
	ds_read_b128 v[206:209], v134 offset:55296
	ds_read_b128 v[226:229], v134 offset:56320
	s_barrier
	s_waitcnt lgkmcnt(0)
	s_waitcnt lgkmcnt(0)
	v_mfma_f32_16x16x32_f16 v[56:59], v[162:165], v[140:143], v[56:59]
	v_mfma_f32_16x16x32_f16 v[52:55], v[162:165], v[148:151], v[52:55]
	v_mfma_f32_16x16x32_f16 v[48:51], v[190:193], v[140:143], v[48:51]
	v_mfma_f32_16x16x32_f16 v[44:47], v[190:193], v[148:151], v[44:47]
	v_mfma_f32_16x16x32_f16 v[40:43], v[198:201], v[140:143], v[40:43]
	v_mfma_f32_16x16x32_f16 v[36:39], v[198:201], v[148:151], v[36:39]
	v_mfma_f32_16x16x32_f16 v[32:35], v[206:209], v[140:143], v[32:35]
	v_mfma_f32_16x16x32_f16 v[28:31], v[206:209], v[148:151], v[28:31]
	v_mfma_f32_16x16x32_f16 v[60:63], v[186:189], v[144:147], v[56:59]
	v_mfma_f32_16x16x32_f16 v[56:59], v[186:189], v[158:161], v[52:55]
	v_mfma_f32_16x16x32_f16 v[52:55], v[194:197], v[144:147], v[48:51]
	v_mfma_f32_16x16x32_f16 v[48:51], v[194:197], v[158:161], v[44:47]
	v_mfma_f32_16x16x32_f16 v[44:47], v[202:205], v[144:147], v[40:43]
	v_mfma_f32_16x16x32_f16 v[40:43], v[202:205], v[158:161], v[36:39]
	v_mfma_f32_16x16x32_f16 v[36:39], v[226:229], v[144:147], v[32:35]
	v_mfma_f32_16x16x32_f16 v[32:35], v[226:229], v[158:161], v[28:31]
	v_mfma_f32_16x16x32_f16 v[24:27], v[162:165], v[210:213], v[24:27]
	v_mfma_f32_16x16x32_f16 v[20:23], v[162:165], v[218:221], v[20:23]
	v_mfma_f32_16x16x32_f16 v[16:19], v[190:193], v[210:213], v[16:19]
	v_mfma_f32_16x16x32_f16 v[12:15], v[190:193], v[218:221], v[12:15]
	v_mfma_f32_16x16x32_f16 v[8:11], v[198:201], v[210:213], v[8:11]
	v_mfma_f32_16x16x32_f16 v[4:7], v[198:201], v[218:221], v[4:7]
	v_mfma_f32_16x16x32_f16 v[0:3], v[206:209], v[210:213], v[0:3]
	v_mfma_f32_16x16x32_f16 v[28:31], v[186:189], v[214:217], v[24:27]
	v_mfma_f32_16x16x32_f16 v[24:27], v[186:189], v[222:225], v[20:23]
	v_mfma_f32_16x16x32_f16 v[20:23], v[194:197], v[214:217], v[16:19]
	v_mfma_f32_16x16x32_f16 v[16:19], v[194:197], v[222:225], v[12:15]
	v_mfma_f32_16x16x32_f16 v[12:15], v[202:205], v[214:217], v[8:11]
	v_mfma_f32_16x16x32_f16 v[8:11], v[202:205], v[222:225], v[4:7]
	v_mfma_f32_16x16x32_f16 v[4:7], v[226:229], v[214:217], v[0:3]
	v_mfma_f32_16x16x32_f16 v[0:3], v[206:209], v[218:221], v[136:139]
	v_mfma_f32_16x16x32_f16 v[0:3], v[226:229], v[222:225], v[0:3]
	s_movk_i32 s0, 0x100
	v_cmp_gt_u32_e32 vcc, s0, v133
	s_barrier
	s_and_saveexec_b64 s[0:1], vcc
	s_cbranch_execz .LBB0_154
	s_barrier

;   #define STAGE(P,BASE,LD,br,kt) do{ const HALF* _u=(BASE)+(long)(br)*(((&(LD))==&lda)?lda_u:(LD))+(long)(kt)*G_BK; \
;     for(int _i=0;_i<2;++_i){ \
;       __builtin_amdgcn_global_load_lds((const unsigned*)(_u+(long)_i*(((&(LD))==&lda)?stepa:stepb)+((&(LD))==&lda?oa0:ob0)), \
;         (unsigned*)((char*)(P)+t5*16+_i*8192),16,0,0);}}while(0)
;   #define LDA(dst,b,h) for(int m=0;m<4;++m)for(int k=0;k<2;++k) \
;     dst[m][k]=*reinterpret_cast<const h8*>(la+(((b)*2+(h))*16384+m*2048+k*1024))
;   #define LDB(dst,b,h) for(int n=0;n<2;++n)for(int k=0;k<2;++k) \
;     dst[n][k]=*reinterpret_cast<const h8*>(lb+(((b)*2+(h))*16384+n*2048+k*1024))
;   #define MMA(ai,bj,At,Bt_) do{__builtin_amdgcn_s_setprio(1); \
;     for(int m=0;m<4;++m)for(int n=0;n<2;++n)for(int k=0;k<2;++k) \
;       acc[ai][bj][m][n]=__builtin_amdgcn_mfma_f32_16x16x32_f16(At[m][k],Bt_[n][k],acc[ai][bj][m][n],0,0,0); \
;     __builtin_amdgcn_s_setprio(0);}while(0)
;   #define WAIT_L(n) asm volatile("s_waitcnt lgkmcnt(" #n ")":::"memory")
;   #define BAR __builtin_amdgcn_s_barrier()
;   #define SCHED __builtin_amdgcn_sched_barrier(0)
;     ...
;   for(int t=0;t<nt-2;t+=2){
;     LDB(B0,0,0); SCHED; LDA(At,0,0); STAGE(SA(1,1),A,lda,G_HALF,t+1);
;     WAIT_L(8); BAR; WAIT_L(0); MMA(0,0,At,B0); BAR; SCHED;
;     LDB(B1,0,1); STAGE(SB(0,0),Bt,ldb,0,t+2);
;     BAR; WAIT_L(0); MMA(0,1,At,B1); BAR;
;     LDA(At,0,1); STAGE(SA(0,0),A,lda,0,t+2);
;     BAR; WAIT_L(0); MMA(1,0,At,B0); BAR; SCHED;
.LBB0_177:
	ds_read_b128 v[158:161], v137
	ds_read_b128 v[162:165], v137 offset:1024
	ds_read_b128 v[186:189], v137 offset:2048
	ds_read_b128 v[190:193], v137 offset:3072
	v_lshl_add_u64 v[166:167], s[6:7], 0, v[132:133]
	s_mov_b64 s[12:13], 0x3eb1080
	v_add_u32_e32 v152, 0xc000, v140
	v_lshl_add_u64 v[168:169], v[166:167], 0, s[12:13]
	v_readfirstlane_b32 s12, v152
	s_mov_b32 m0, s12
	s_mov_b64 s[12:13], 0x3eb1880
	v_add_u32_e32 v157, 0xe000, v140
	ds_read_b128 v[194:197], v136
	ds_read_b128 v[198:201], v136 offset:1024
	ds_read_b128 v[202:205], v136 offset:2048
	ds_read_b128 v[206:209], v136 offset:3072
	ds_read_b128 v[210:213], v136 offset:4096
	ds_read_b128 v[214:217], v136 offset:5120
	ds_read_b128 v[218:221], v136 offset:6144
	ds_read_b128 v[222:225], v136 offset:7168
	global_load_lds_dwordx4 v[168:169], off
	v_lshl_add_u64 v[168:169], v[166:167], 0, s[12:13]
	v_readfirstlane_b32 s12, v157
	s_mov_b32 m0, s12
	s_nop 0
	global_load_lds_dwordx4 v[168:169], off
	s_waitcnt lgkmcnt(8)
	s_barrier
	s_waitcnt lgkmcnt(0)
	s_waitcnt lgkmcnt(0)
	v_mfma_f32_16x16x32_f16 v[124:127], v[194:197], v[158:161], v[124:127]
	v_mfma_f32_16x16x32_f16 v[120:123], v[194:197], v[186:189], v[120:123]
	v_mfma_f32_16x16x32_f16 v[116:119], v[202:205], v[158:161], v[116:119]
	v_mfma_f32_16x16x32_f16 v[112:115], v[202:205], v[186:189], v[112:115]
	v_mfma_f32_16x16x32_f16 v[108:111], v[210:213], v[158:161], v[108:111]
	v_mfma_f32_16x16x32_f16 v[104:107], v[210:213], v[186:189], v[104:107]
	v_mfma_f32_16x16x32_f16 v[100:103], v[218:221], v[158:161], v[100:103]
	v_mfma_f32_16x16x32_f16 v[96:99], v[218:221], v[186:189], v[96:99]
	v_mfma_f32_16x16x32_f16 v[124:127], v[198:201], v[162:165], v[124:127]
	v_mfma_f32_16x16x32_f16 v[120:123], v[198:201], v[190:193], v[120:123]
	v_mfma_f32_16x16x32_f16 v[116:119], v[206:209], v[162:165], v[116:119]
	v_mfma_f32_16x16x32_f16 v[112:115], v[206:209], v[190:193], v[112:115]
	v_mfma_f32_16x16x32_f16 v[108:111], v[214:217], v[162:165], v[108:111]
	v_mfma_f32_16x16x32_f16 v[104:107], v[214:217], v[190:193], v[104:107]
	v_mfma_f32_16x16x32_f16 v[100:103], v[222:225], v[162:165], v[100:103]
	v_mfma_f32_16x16x32_f16 v[96:99], v[222:225], v[190:193], v[96:99]
	s_barrier
	v_lshl_add_u64 v[168:169], s[6:7], 0, v[130:131]
	v_readfirstlane_b32 s12, v138
	v_lshl_add_u64 v[170:171], v[168:169], 0, s[92:93]
	s_mov_b32 m0, s12
	v_readfirstlane_b32 s12, v139
	ds_read_b128 v[226:229], v137 offset:16384
	ds_read_b128 v[230:233], v137 offset:17408
	ds_read_b128 v[234:237], v137 offset:18432
	ds_read_b128 v[238:241], v137 offset:19456
	global_load_lds_dwordx4 v[170:171], off
	v_lshl_add_u64 v[170:171], v[168:169], 0, s[66:67]
	s_mov_b32 m0, s12
	s_nop 0
	global_load_lds_dwordx4 v[170:171], off
	s_barrier
	s_waitcnt lgkmcnt(0)
	s_waitcnt lgkmcnt(0)
	v_mfma_f32_16x16x32_f16 v[92:95], v[194:197], v[226:229], v[92:95]
	v_mfma_f32_16x16x32_f16 v[88:91], v[194:197], v[234:237], v[88:91]
	v_mfma_f32_16x16x32_f16 v[84:87], v[202:205], v[226:229], v[84:87]
	v_mfma_f32_16x16x32_f16 v[80:83], v[202:205], v[234:237], v[80:83]
	v_mfma_f32_16x16x32_f16 v[76:79], v[210:213], v[226:229], v[76:79]
	v_mfma_f32_16x16x32_f16 v[72:75], v[210:213], v[234:237], v[72:75]
	v_mfma_f32_16x16x32_f16 v[68:71], v[218:221], v[226:229], v[68:71]
	v_mfma_f32_16x16x32_f16 v[64:67], v[218:221], v[234:237], v[64:67]
	v_mfma_f32_16x16x32_f16 v[92:95], v[198:201], v[230:233], v[92:95]
	v_mfma_f32_16x16x32_f16 v[88:91], v[198:201], v[238:241], v[88:91]
	v_mfma_f32_16x16x32_f16 v[84:87], v[206:209], v[230:233], v[84:87]
	v_mfma_f32_16x16x32_f16 v[80:83], v[206:209], v[238:241], v[80:83]
	v_mfma_f32_16x16x32_f16 v[76:79], v[214:217], v[230:233], v[76:79]
	v_mfma_f32_16x16x32_f16 v[72:75], v[214:217], v[238:241], v[72:75]
	v_mfma_f32_16x16x32_f16 v[68:71], v[222:225], v[230:233], v[68:71]
	v_mfma_f32_16x16x32_f16 v[64:67], v[222:225], v[238:241], v[64:67]
	v_readfirstlane_b32 s12, v140
	v_lshl_add_u64 v[170:171], v[166:167], 0, s[36:37]
	s_mov_b32 m0, s12
	s_mov_b64 s[12:13], 0x3eb0900
	s_barrier
	ds_read_b128 v[194:197], v136 offset:16384
	ds_read_b128 v[198:201], v136 offset:17408
	ds_read_b128 v[202:205], v136 offset:18432
	ds_read_b128 v[206:209], v136 offset:19456
	ds_read_b128 v[210:213], v136 offset:20480
	ds_read_b128 v[214:217], v136 offset:21504
	ds_read_b128 v[218:221], v136 offset:22528
	ds_read_b128 v[222:225], v136 offset:23552
	global_load_lds_dwordx4 v[170:171], off
	v_lshl_add_u64 v[170:171], v[166:167], 0, s[12:13]
	v_readfirstlane_b32 s12, v141
	s_mov_b32 m0, s12
	s_nop 0
	global_load_lds_dwordx4 v[170:171], off
	s_barrier
	s_waitcnt lgkmcnt(0)
	s_waitcnt lgkmcnt(0)
	v_mfma_f32_16x16x32_f16 v[60:63], v[194:197], v[158:161], v[60:63]
	v_mfma_f32_16x16x32_f16 v[56:59], v[194:197], v[186:189], v[56:59]
	v_mfma_f32_16x16x32_f16 v[52:55], v[202:205], v[158:161], v[52:55]
	v_mfma_f32_16x16x32_f16 v[48:51], v[202:205], v[186:189], v[48:51]
	v_mfma_f32_16x16x32_f16 v[44:47], v[210:213], v[158:161], v[44:47]
	v_mfma_f32_16x16x32_f16 v[40:43], v[210:213], v[186:189], v[40:43]
	v_mfma_f32_16x16x32_f16 v[36:39], v[218:221], v[158:161], v[36:39]
	v_mfma_f32_16x16x32_f16 v[32:35], v[218:221], v[186:189], v[32:35]
	v_mfma_f32_16x16x32_f16 v[60:63], v[198:201], v[162:165], v[60:63]
	v_mfma_f32_16x16x32_f16 v[56:59], v[198:201], v[190:193], v[56:59]
	v_mfma_f32_16x16x32_f16 v[52:55], v[206:209], v[162:165], v[52:55]
	v_mfma_f32_16x16x32_f16 v[48:51], v[206:209], v[190:193], v[48:51]
	v_mfma_f32_16x16x32_f16 v[44:47], v[214:217], v[162:165], v[44:47]
	v_mfma_f32_16x16x32_f16 v[40:43], v[214:217], v[190:193], v[40:43]
	v_mfma_f32_16x16x32_f16 v[36:39], v[222:225], v[162:165], v[36:39]
	v_mfma_f32_16x16x32_f16 v[32:35], v[222:225], v[190:193], v[32:35]
	s_barrier
;   #define STAGE(P,BASE,LD,br,kt) do{ const HALF* _u=(BASE)+(long)(br)*(((&(LD))==&lda)?lda_u:(LD))+(long)(kt)*G_BK; \
;     for(int _i=0;_i<2;++_i){ \
;       __builtin_amdgcn_global_load_lds((const unsigned*)(_u+(long)_i*(((&(LD))==&lda)?stepa:stepb)+((&(LD))==&lda?oa0:ob0)), \
;         (unsigned*)((char*)(P)+t5*16+_i*8192),16,0,0);}}while(0)
;   #define LDA(dst,b,h) for(int m=0;m<4;++m)for(int k=0;k<2;++k) \
;     dst[m][k]=*reinterpret_cast<const h8*>(la+(((b)*2+(h))*16384+m*2048+k*1024))
;   #define LDB(dst,b,h) for(int n=0;n<2;++n)for(int k=0;k<2;++k) \
;     dst[n][k]=*reinterpret_cast<const h8*>(lb+(((b)*2+(h))*16384+n*2048+k*1024))
;   #define MMA(ai,bj,At,Bt_) do{__builtin_amdgcn_s_setprio(1); \
;     for(int m=0;m<4;++m)for(int n=0;n<2;++n)for(int k=0;k<2;++k) \
;       acc[ai][bj][m][n]=__builtin_amdgcn_mfma_f32_16x16x32_f16(At[m][k],Bt_[n][k],acc[ai][bj][m][n],0,0,0); \
;     __builtin_amdgcn_s_setprio(0);}while(0)
;   #define WAIT_V(n) asm volatile("s_waitcnt vmcnt(" #n ")":::"memory")
;   #define WAIT_L(n) asm volatile("s_waitcnt lgkmcnt(" #n ")":::"memory")
;   #define BAR __builtin_amdgcn_s_barrier()
;   #define SCHED __builtin_amdgcn_sched_barrier(0)
;     ...
;     STAGE(SB(0,1),Bt,ldb,G_HALF,t+2);
;     WAIT_V(6); BAR; MMA(1,1,At,B1); BAR;
;     LDB(B0,1,0); SCHED; LDA(At,1,0); STAGE(SA(0,1),A,lda,G_HALF,t+2);
;     WAIT_L(8); BAR; WAIT_L(0); MMA(0,0,At,B0); BAR; SCHED;
;     LDB(B1,1,1); STAGE(SB(1,0),Bt,ldb,0,t+3);
;     BAR; WAIT_L(0); MMA(0,1,At,B1); BAR;
;     LDA(At,1,1); STAGE(SA(1,0),A,lda,0,t+3);
	v_readfirstlane_b32 s12, v142
	v_lshl_add_u64 v[158:159], v[168:169], 0, s[38:39]
	s_mov_b32 m0, s12
	v_readfirstlane_b32 s12, v143
	global_load_lds_dwordx4 v[158:159], off
	v_lshl_add_u64 v[158:159], v[168:169], 0, s[40:41]
	s_mov_b32 m0, s12
	s_nop 0
	global_load_lds_dwordx4 v[158:159], off
	s_waitcnt vmcnt(6)
	s_barrier
	v_mfma_f32_16x16x32_f16 v[28:31], v[194:197], v[226:229], v[28:31]
	v_mfma_f32_16x16x32_f16 v[24:27], v[194:197], v[234:237], v[24:27]
	v_mfma_f32_16x16x32_f16 v[20:23], v[202:205], v[226:229], v[20:23]
	v_mfma_f32_16x16x32_f16 v[16:19], v[202:205], v[234:237], v[16:19]
	v_mfma_f32_16x16x32_f16 v[12:15], v[210:213], v[226:229], v[12:15]
	v_mfma_f32_16x16x32_f16 v[8:11], v[210:213], v[234:237], v[8:11]
	v_mfma_f32_16x16x32_f16 v[4:7], v[218:221], v[226:229], v[4:7]
	v_mfma_f32_16x16x32_f16 v[0:3], v[218:221], v[234:237], v[0:3]
	v_mfma_f32_16x16x32_f16 v[28:31], v[198:201], v[230:233], v[28:31]
	v_mfma_f32_16x16x32_f16 v[24:27], v[198:201], v[238:241], v[24:27]
	v_mfma_f32_16x16x32_f16 v[20:23], v[206:209], v[230:233], v[20:23]
	v_mfma_f32_16x16x32_f16 v[16:19], v[206:209], v[238:241], v[16:19]
	v_mfma_f32_16x16x32_f16 v[12:15], v[214:217], v[230:233], v[12:15]
	v_mfma_f32_16x16x32_f16 v[8:11], v[214:217], v[238:241], v[8:11]
	v_mfma_f32_16x16x32_f16 v[4:7], v[222:225], v[230:233], v[4:7]
	v_mfma_f32_16x16x32_f16 v[0:3], v[222:225], v[238:241], v[0:3]
	s_barrier
	ds_read_b128 v[158:161], v137 offset:32768
	ds_read_b128 v[162:165], v137 offset:33792
	ds_read_b128 v[186:189], v137 offset:34816
	ds_read_b128 v[190:193], v137 offset:35840
	s_mov_b64 s[12:13], 0x3eb1100
	v_lshl_add_u64 v[170:171], v[166:167], 0, s[12:13]
	v_readfirstlane_b32 s12, v144
	s_mov_b32 m0, s12
	s_mov_b64 s[12:13], 0x3eb1900
	ds_read_b128 v[194:197], v136 offset:32768
	ds_read_b128 v[198:201], v136 offset:33792
	ds_read_b128 v[202:205], v136 offset:34816
	ds_read_b128 v[206:209], v136 offset:35840
	ds_read_b128 v[210:213], v136 offset:36864
	ds_read_b128 v[214:217], v136 offset:37888
	ds_read_b128 v[218:221], v136 offset:38912
	ds_read_b128 v[222:225], v136 offset:39936
	global_load_lds_dwordx4 v[170:171], off
	v_lshl_add_u64 v[170:171], v[166:167], 0, s[12:13]
	v_readfirstlane_b32 s12, v145
	s_mov_b32 m0, s12
	s_nop 0
	global_load_lds_dwordx4 v[170:171], off
	s_waitcnt lgkmcnt(8)
	s_barrier
	s_waitcnt lgkmcnt(0)
	s_waitcnt lgkmcnt(0)
	v_mfma_f32_16x16x32_f16 v[124:127], v[194:197], v[158:161], v[124:127]
	v_mfma_f32_16x16x32_f16 v[120:123], v[194:197], v[186:189], v[120:123]
	v_mfma_f32_16x16x32_f16 v[116:119], v[202:205], v[158:161], v[116:119]
	v_mfma_f32_16x16x32_f16 v[112:115], v[202:205], v[186:189], v[112:115]
	v_mfma_f32_16x16x32_f16 v[108:111], v[210:213], v[158:161], v[108:111]
	v_mfma_f32_16x16x32_f16 v[104:107], v[210:213], v[186:189], v[104:107]
	v_mfma_f32_16x16x32_f16 v[100:103], v[218:221], v[158:161], v[100:103]
	v_mfma_f32_16x16x32_f16 v[96:99], v[218:221], v[186:189], v[96:99]
	v_mfma_f32_16x16x32_f16 v[124:127], v[198:201], v[162:165], v[124:127]
	v_mfma_f32_16x16x32_f16 v[120:123], v[198:201], v[190:193], v[120:123]
	v_mfma_f32_16x16x32_f16 v[116:119], v[206:209], v[162:165], v[116:119]
	v_mfma_f32_16x16x32_f16 v[112:115], v[206:209], v[190:193], v[112:115]
	v_mfma_f32_16x16x32_f16 v[108:111], v[214:217], v[162:165], v[108:111]
	v_mfma_f32_16x16x32_f16 v[104:107], v[214:217], v[190:193], v[104:107]
	v_mfma_f32_16x16x32_f16 v[100:103], v[222:225], v[162:165], v[100:103]
	v_mfma_f32_16x16x32_f16 v[96:99], v[222:225], v[190:193], v[96:99]
	s_barrier
	v_readfirstlane_b32 s12, v146
	v_lshl_add_u64 v[170:171], v[168:169], 0, s[42:43]
	s_mov_b32 m0, s12
	v_readfirstlane_b32 s12, v147
	ds_read_b128 v[226:229], v137 offset:49152
	ds_read_b128 v[230:233], v137 offset:50176
	ds_read_b128 v[234:237], v137 offset:51200
	ds_read_b128 v[238:241], v137 offset:52224
	global_load_lds_dwordx4 v[170:171], off
	v_lshl_add_u64 v[170:171], v[168:169], 0, s[96:97]
	s_mov_b32 m0, s12
	s_nop 0
	global_load_lds_dwordx4 v[170:171], off
	s_barrier
	s_waitcnt lgkmcnt(0)
	s_waitcnt lgkmcnt(0)
	v_mfma_f32_16x16x32_f16 v[92:95], v[194:197], v[226:229], v[92:95]
	v_mfma_f32_16x16x32_f16 v[88:91], v[194:197], v[234:237], v[88:91]
	v_mfma_f32_16x16x32_f16 v[84:87], v[202:205], v[226:229], v[84:87]
	v_mfma_f32_16x16x32_f16 v[80:83], v[202:205], v[234:237], v[80:83]
	v_mfma_f32_16x16x32_f16 v[76:79], v[210:213], v[226:229], v[76:79]
	v_mfma_f32_16x16x32_f16 v[72:75], v[210:213], v[234:237], v[72:75]
	v_mfma_f32_16x16x32_f16 v[68:71], v[218:221], v[226:229], v[68:71]
	v_mfma_f32_16x16x32_f16 v[64:67], v[218:221], v[234:237], v[64:67]
	v_mfma_f32_16x16x32_f16 v[92:95], v[198:201], v[230:233], v[92:95]
	v_mfma_f32_16x16x32_f16 v[88:91], v[198:201], v[238:241], v[88:91]
	v_mfma_f32_16x16x32_f16 v[84:87], v[206:209], v[230:233], v[84:87]
	v_mfma_f32_16x16x32_f16 v[80:83], v[206:209], v[238:241], v[80:83]
	v_mfma_f32_16x16x32_f16 v[76:79], v[214:217], v[230:233], v[76:79]
	v_mfma_f32_16x16x32_f16 v[72:75], v[214:217], v[238:241], v[72:75]
	v_mfma_f32_16x16x32_f16 v[68:71], v[222:225], v[230:233], v[68:71]
	v_mfma_f32_16x16x32_f16 v[64:67], v[222:225], v[238:241], v[64:67]
	v_readfirstlane_b32 s12, v148
	s_mov_b32 m0, s12
	s_mov_b64 s[12:13], 0x3eb0980
	v_lshl_add_u64 v[170:171], v[166:167], 0, s[60:61]
	v_lshl_add_u64 v[166:167], v[166:167], 0, s[12:13]
	v_readfirstlane_b32 s12, v149
	s_barrier
	ds_read_b128 v[194:197], v136 offset:49152
	ds_read_b128 v[198:201], v136 offset:50176
	ds_read_b128 v[202:205], v136 offset:51200
	ds_read_b128 v[206:209], v136 offset:52224
	ds_read_b128 v[210:213], v136 offset:53248
	ds_read_b128 v[214:217], v136 offset:54272
	ds_read_b128 v[218:221], v136 offset:55296
	ds_read_b128 v[222:225], v136 offset:56320
	global_load_lds_dwordx4 v[170:171], off
	s_mov_b32 m0, s12
	s_nop 0
	global_load_lds_dwordx4 v[166:167], off
	s_barrier
;   #define STAGE(P,BASE,LD,br,kt) do{ const HALF* _u=(BASE)+(long)(br)*(((&(LD))==&lda)?lda_u:(LD))+(long)(kt)*G_BK; \
;     for(int _i=0;_i<2;++_i){ \
;       __builtin_amdgcn_global_load_lds((const unsigned*)(_u+(long)_i*(((&(LD))==&lda)?stepa:stepb)+((&(LD))==&lda?oa0:ob0)), \
;         (unsigned*)((char*)(P)+t5*16+_i*8192),16,0,0);}}while(0)
;   #define LDA(dst,b,h) for(int m=0;m<4;++m)for(int k=0;k<2;++k) \
;     dst[m][k]=*reinterpret_cast<const h8*>(la+(((b)*2+(h))*16384+m*2048+k*1024))
;   #define LDB(dst,b,h) for(int n=0;n<2;++n)for(int k=0;k<2;++k) \
;     dst[n][k]=*reinterpret_cast<const h8*>(lb+(((b)*2+(h))*16384+n*2048+k*1024))
;   #define MMA(ai,bj,At,Bt_) do{__builtin_amdgcn_s_setprio(1); \
;     for(int m=0;m<4;++m)for(int n=0;n<2;++n)for(int k=0;k<2;++k) \
;       acc[ai][bj][m][n]=__builtin_amdgcn_mfma_f32_16x16x32_f16(At[m][k],Bt_[n][k],acc[ai][bj][m][n],0,0,0); \
;     __builtin_amdgcn_s_setprio(0);}while(0)
;   #define WAIT_V(n) asm volatile("s_waitcnt vmcnt(" #n ")":::"memory")
;   #define WAIT_L(n) asm volatile("s_waitcnt lgkmcnt(" #n ")":::"memory")
;   #define BAR __builtin_amdgcn_s_barrier()
;   #define SCHED __builtin_amdgcn_sched_barrier(0)
;     ...
;     LDA(At,1,1); STAGE(SA(1,0),A,lda,0,t+3);
;     BAR; WAIT_L(0); MMA(1,0,At,B0); BAR; SCHED;
;     STAGE(SB(1,1),Bt,ldb,G_HALF,t+3);
;     WAIT_V(6); BAR; MMA(1,1,At,B1); BAR;
;   }
;   { LDB(B0,0,0); LDA(At,0,0); STAGE(SA(1,1),A,lda,G_HALF,nt-1);
;     BAR; WAIT_L(0); MMA(0,0,At,B0); BAR;
;     LDB(B1,0,1); BAR; WAIT_L(0); MMA(0,1,At,B1); BAR;
	s_waitcnt lgkmcnt(0)
	s_waitcnt lgkmcnt(0)
	v_mfma_f32_16x16x32_f16 v[60:63], v[194:197], v[158:161], v[60:63]
	v_mfma_f32_16x16x32_f16 v[56:59], v[194:197], v[186:189], v[56:59]
	v_mfma_f32_16x16x32_f16 v[52:55], v[202:205], v[158:161], v[52:55]
	v_mfma_f32_16x16x32_f16 v[48:51], v[202:205], v[186:189], v[48:51]
	v_mfma_f32_16x16x32_f16 v[44:47], v[210:213], v[158:161], v[44:47]
	v_mfma_f32_16x16x32_f16 v[40:43], v[210:213], v[186:189], v[40:43]
	v_mfma_f32_16x16x32_f16 v[36:39], v[218:221], v[158:161], v[36:39]
	v_mfma_f32_16x16x32_f16 v[32:35], v[218:221], v[186:189], v[32:35]
	v_mfma_f32_16x16x32_f16 v[60:63], v[198:201], v[162:165], v[60:63]
	v_mfma_f32_16x16x32_f16 v[56:59], v[198:201], v[190:193], v[56:59]
	v_mfma_f32_16x16x32_f16 v[52:55], v[206:209], v[162:165], v[52:55]
	v_mfma_f32_16x16x32_f16 v[48:51], v[206:209], v[190:193], v[48:51]
	v_mfma_f32_16x16x32_f16 v[44:47], v[214:217], v[162:165], v[44:47]
	v_mfma_f32_16x16x32_f16 v[40:43], v[214:217], v[190:193], v[40:43]
	v_mfma_f32_16x16x32_f16 v[36:39], v[222:225], v[162:165], v[36:39]
	v_mfma_f32_16x16x32_f16 v[32:35], v[222:225], v[190:193], v[32:35]
	s_barrier
	v_readfirstlane_b32 s12, v150
	v_lshl_add_u64 v[158:159], v[168:169], 0, s[14:15]
	s_mov_b32 m0, s12
	v_readfirstlane_b32 s12, v151
	global_load_lds_dwordx4 v[158:159], off
	v_lshl_add_u64 v[158:159], v[168:169], 0, s[58:59]
	s_mov_b32 m0, s12
	s_nop 0
	global_load_lds_dwordx4 v[158:159], off
	s_waitcnt vmcnt(6)
	s_barrier
	v_mfma_f32_16x16x32_f16 v[28:31], v[194:197], v[226:229], v[28:31]
	v_mfma_f32_16x16x32_f16 v[24:27], v[194:197], v[234:237], v[24:27]
	v_mfma_f32_16x16x32_f16 v[20:23], v[202:205], v[226:229], v[20:23]
	v_mfma_f32_16x16x32_f16 v[16:19], v[202:205], v[234:237], v[16:19]
	v_mfma_f32_16x16x32_f16 v[12:15], v[210:213], v[226:229], v[12:15]
	v_mfma_f32_16x16x32_f16 v[8:11], v[210:213], v[234:237], v[8:11]
	v_mfma_f32_16x16x32_f16 v[4:7], v[218:221], v[226:229], v[4:7]
	v_mfma_f32_16x16x32_f16 v[0:3], v[218:221], v[234:237], v[0:3]
	v_mfma_f32_16x16x32_f16 v[28:31], v[198:201], v[230:233], v[28:31]
	v_mfma_f32_16x16x32_f16 v[24:27], v[198:201], v[238:241], v[24:27]
	v_mfma_f32_16x16x32_f16 v[20:23], v[206:209], v[230:233], v[20:23]
	v_mfma_f32_16x16x32_f16 v[16:19], v[206:209], v[238:241], v[16:19]
	v_mfma_f32_16x16x32_f16 v[12:15], v[214:217], v[230:233], v[12:15]
	v_mfma_f32_16x16x32_f16 v[8:11], v[214:217], v[238:241], v[8:11]
	v_mfma_f32_16x16x32_f16 v[4:7], v[222:225], v[230:233], v[4:7]
	v_mfma_f32_16x16x32_f16 v[0:3], v[222:225], v[238:241], v[0:3]
	s_add_i32 s1, s1, 2
	s_add_u32 s6, s6, 0x100
	s_addc_u32 s7, s7, 0
	s_cmp_lt_u32 s1, 12
	s_barrier
	s_cbranch_scc1 .LBB0_177
	s_mov_b64 s[6:7], 0x1780
	v_readfirstlane_b32 s1, v152
	v_lshl_add_u64 v[150:151], v[128:129], 0, s[6:7]
	s_mov_b32 m0, s1
	s_mov_b64 s[6:7], 0x1f80
	v_readfirstlane_b32 s1, v157
	ds_read_b128 v[130:133], v137
	ds_read_b128 v[138:141], v137 offset:1024
	ds_read_b128 v[142:145], v137 offset:2048
	ds_read_b128 v[146:149], v137 offset:3072
	ds_read_b128 v[158:161], v136
	ds_read_b128 v[162:165], v136 offset:1024
	ds_read_b128 v[186:189], v136 offset:2048
	ds_read_b128 v[190:193], v136 offset:3072
	ds_read_b128 v[194:197], v136 offset:4096
	ds_read_b128 v[198:201], v136 offset:5120
	ds_read_b128 v[202:205], v136 offset:6144
	ds_read_b128 v[206:209], v136 offset:7168
	global_load_lds_dwordx4 v[150:151], off
	v_lshl_add_u64 v[128:129], v[128:129], 0, s[6:7]
	s_mov_b32 m0, s1
	s_nop 0
	global_load_lds_dwordx4 v[128:129], off
	s_barrier
	s_waitcnt lgkmcnt(0)
	s_waitcnt lgkmcnt(0)
	v_mfma_f32_16x16x32_f16 v[124:127], v[158:161], v[130:133], v[124:127]
	v_mfma_f32_16x16x32_f16 v[120:123], v[158:161], v[142:145], v[120:123]
	v_mfma_f32_16x16x32_f16 v[116:119], v[186:189], v[130:133], v[116:119]
	v_mfma_f32_16x16x32_f16 v[112:115], v[186:189], v[142:145], v[112:115]
	v_mfma_f32_16x16x32_f16 v[108:111], v[194:197], v[130:133], v[108:111]
	v_mfma_f32_16x16x32_f16 v[104:107], v[194:197], v[142:145], v[104:107]
	v_mfma_f32_16x16x32_f16 v[124:127], v[162:165], v[138:141], v[124:127]
	v_mfma_f32_16x16x32_f16 v[120:123], v[162:165], v[146:149], v[120:123]
	v_mfma_f32_16x16x32_f16 v[116:119], v[190:193], v[138:141], v[116:119]
	v_mfma_f32_16x16x32_f16 v[112:115], v[190:193], v[146:149], v[112:115]
	v_mfma_f32_16x16x32_f16 v[108:111], v[198:201], v[138:141], v[108:111]
	v_mfma_f32_16x16x32_f16 v[104:107], v[198:201], v[146:149], v[104:107]
	v_mfma_f32_16x16x32_f16 v[100:103], v[202:205], v[130:133], v[100:103]
	v_mfma_f32_16x16x32_f16 v[96:99], v[202:205], v[142:145], v[96:99]
	v_mfma_f32_16x16x32_f16 v[210:213], v[206:209], v[138:141], v[100:103]
	v_mfma_f32_16x16x32_f16 v[214:217], v[206:209], v[146:149], v[96:99]
	s_barrier
	s_nop 3
	ds_read_b128 v[96:99], v137 offset:16384
	ds_read_b128 v[100:103], v137 offset:17408
	ds_read_b128 v[218:221], v137 offset:18432
	ds_read_b128 v[222:225], v137 offset:19456
	s_barrier
	s_waitcnt lgkmcnt(0)
	s_waitcnt lgkmcnt(0)
	v_mfma_f32_16x16x32_f16 v[92:95], v[158:161], v[96:99], v[92:95]
	v_mfma_f32_16x16x32_f16 v[84:87], v[186:189], v[96:99], v[84:87]
	v_mfma_f32_16x16x32_f16 v[80:83], v[186:189], v[218:221], v[80:83]
	v_mfma_f32_16x16x32_f16 v[76:79], v[194:197], v[96:99], v[76:79]
	v_mfma_f32_16x16x32_f16 v[72:75], v[194:197], v[218:221], v[72:75]
	v_mfma_f32_16x16x32_f16 v[64:67], v[202:205], v[218:221], v[64:67]
	v_mfma_f32_16x16x32_f16 v[92:95], v[162:165], v[100:103], v[92:95]
	v_mfma_f32_16x16x32_f16 v[88:91], v[158:161], v[218:221], v[88:91]
	v_mfma_f32_16x16x32_f16 v[84:87], v[190:193], v[100:103], v[84:87]
	v_mfma_f32_16x16x32_f16 v[80:83], v[190:193], v[222:225], v[80:83]
	v_mfma_f32_16x16x32_f16 v[76:79], v[198:201], v[100:103], v[76:79]
	v_mfma_f32_16x16x32_f16 v[72:75], v[198:201], v[222:225], v[72:75]
	v_mfma_f32_16x16x32_f16 v[68:71], v[202:205], v[96:99], v[68:71]
	v_mfma_f32_16x16x32_f16 v[64:67], v[206:209], v[222:225], v[64:67]
	v_mfma_f32_16x16x32_f16 v[158:161], v[162:165], v[222:225], v[88:91]
	v_mfma_f32_16x16x32_f16 v[162:165], v[206:209], v[100:103], v[68:71]
	s_barrier
;   #define LDA(dst,b,h) for(int m=0;m<4;++m)for(int k=0;k<2;++k) \
;     dst[m][k]=*reinterpret_cast<const h8*>(la+(((b)*2+(h))*16384+m*2048+k*1024))
;   #define LDB(dst,b,h) for(int n=0;n<2;++n)for(int k=0;k<2;++k) \
;     dst[n][k]=*reinterpret_cast<const h8*>(lb+(((b)*2+(h))*16384+n*2048+k*1024))
;   #define MMA(ai,bj,At,Bt_) do{__builtin_amdgcn_s_setprio(1); \
;     for(int m=0;m<4;++m)for(int n=0;n<2;++n)for(int k=0;k<2;++k) \
;       acc[ai][bj][m][n]=__builtin_amdgcn_mfma_f32_16x16x32_f16(At[m][k],Bt_[n][k],acc[ai][bj][m][n],0,0,0); \
;     __builtin_amdgcn_s_setprio(0);}while(0)
;   #define WAIT_V(n) asm volatile("s_waitcnt vmcnt(" #n ")":::"memory")
;   #define WAIT_L(n) asm volatile("s_waitcnt lgkmcnt(" #n ")":::"memory")
;   #define BAR __builtin_amdgcn_s_barrier()
;     ...
;     LDB(B1,0,1); BAR; WAIT_L(0); MMA(0,1,At,B1); BAR;
;     LDA(At,0,1); WAIT_V(4); BAR; WAIT_L(0); MMA(1,0,At,B0); MMA(1,1,At,B1); BAR; }
;   { LDB(B0,1,0); LDA(At,1,0); WAIT_V(2); BAR; WAIT_L(0); MMA(0,0,At,B0); BAR;
	s_nop 2
	ds_read_b128 v[68:71], v136 offset:16384
	ds_read_b128 v[88:91], v136 offset:17408
	ds_read_b128 v[186:189], v136 offset:18432
	ds_read_b128 v[190:193], v136 offset:19456
	ds_read_b128 v[194:197], v136 offset:20480
	ds_read_b128 v[198:201], v136 offset:21504
	ds_read_b128 v[202:205], v136 offset:22528
	ds_read_b128 v[206:209], v136 offset:23552
	s_waitcnt vmcnt(4)
	s_barrier
	s_waitcnt lgkmcnt(0)
	s_waitcnt lgkmcnt(0)
	v_mfma_f32_16x16x32_f16 v[56:59], v[68:71], v[142:145], v[56:59]
	v_mfma_f32_16x16x32_f16 v[52:55], v[186:189], v[130:133], v[52:55]
	v_mfma_f32_16x16x32_f16 v[44:47], v[194:197], v[130:133], v[44:47]
	v_mfma_f32_16x16x32_f16 v[40:43], v[194:197], v[142:145], v[40:43]
	v_mfma_f32_16x16x32_f16 v[36:39], v[202:205], v[130:133], v[36:39]
	v_mfma_f32_16x16x32_f16 v[32:35], v[202:205], v[142:145], v[32:35]
	v_mfma_f32_16x16x32_f16 v[60:63], v[68:71], v[130:133], v[60:63]
	v_mfma_f32_16x16x32_f16 v[56:59], v[88:91], v[146:149], v[56:59]
	v_mfma_f32_16x16x32_f16 v[52:55], v[190:193], v[138:141], v[52:55]
	v_mfma_f32_16x16x32_f16 v[48:51], v[186:189], v[142:145], v[48:51]
	v_mfma_f32_16x16x32_f16 v[44:47], v[198:201], v[138:141], v[44:47]
	v_mfma_f32_16x16x32_f16 v[40:43], v[198:201], v[146:149], v[40:43]
	v_mfma_f32_16x16x32_f16 v[36:39], v[206:209], v[138:141], v[36:39]
	v_mfma_f32_16x16x32_f16 v[32:35], v[206:209], v[146:149], v[32:35]
	v_mfma_f32_16x16x32_f16 v[226:229], v[88:91], v[138:141], v[60:63]
	v_mfma_f32_16x16x32_f16 v[230:233], v[190:193], v[146:149], v[48:51]
	v_mfma_f32_16x16x32_f16 v[28:31], v[68:71], v[96:99], v[28:31]
	v_mfma_f32_16x16x32_f16 v[24:27], v[68:71], v[218:221], v[24:27]
	v_mfma_f32_16x16x32_f16 v[20:23], v[186:189], v[96:99], v[20:23]
	v_mfma_f32_16x16x32_f16 v[16:19], v[186:189], v[218:221], v[16:19]
	v_mfma_f32_16x16x32_f16 v[12:15], v[194:197], v[96:99], v[12:15]
	v_mfma_f32_16x16x32_f16 v[8:11], v[194:197], v[218:221], v[8:11]
	v_mfma_f32_16x16x32_f16 v[4:7], v[202:205], v[96:99], v[4:7]
	v_mfma_f32_16x16x32_f16 v[0:3], v[202:205], v[218:221], v[0:3]
	v_mfma_f32_16x16x32_f16 v[28:31], v[88:91], v[100:103], v[28:31]
	v_mfma_f32_16x16x32_f16 v[24:27], v[88:91], v[222:225], v[24:27]
	v_mfma_f32_16x16x32_f16 v[20:23], v[190:193], v[100:103], v[20:23]
	v_mfma_f32_16x16x32_f16 v[16:19], v[190:193], v[222:225], v[16:19]
	v_mfma_f32_16x16x32_f16 v[12:15], v[198:201], v[100:103], v[12:15]
	v_mfma_f32_16x16x32_f16 v[8:11], v[198:201], v[222:225], v[8:11]
	v_mfma_f32_16x16x32_f16 v[4:7], v[206:209], v[100:103], v[4:7]
	v_mfma_f32_16x16x32_f16 v[0:3], v[206:209], v[222:225], v[0:3]
	s_barrier
	ds_read_b128 v[128:131], v137 offset:32768
	ds_read_b128 v[138:141], v137 offset:33792
	ds_read_b128 v[142:145], v137 offset:34816
	ds_read_b128 v[146:149], v137 offset:35840
	ds_read_b128 v[48:51], v136 offset:32768
	ds_read_b128 v[60:63], v136 offset:33792
	ds_read_b128 v[68:71], v136 offset:34816
	ds_read_b128 v[186:189], v136 offset:35840
	ds_read_b128 v[190:193], v136 offset:36864
	ds_read_b128 v[194:197], v136 offset:37888
	ds_read_b128 v[198:201], v136 offset:38912
	ds_read_b128 v[202:205], v136 offset:39936
	s_waitcnt vmcnt(2)
	s_barrier
	s_waitcnt lgkmcnt(0)
	s_waitcnt lgkmcnt(0)
	v_mfma_f32_16x16x32_f16 v[88:91], v[48:51], v[128:131], v[124:127]
	v_mfma_f32_16x16x32_f16 v[124:127], v[60:63], v[138:141], v[88:91]
	v_mfma_f32_16x16x32_f16 v[88:91], v[48:51], v[142:145], v[120:123]
	v_mfma_f32_16x16x32_f16 v[120:123], v[60:63], v[146:149], v[88:91]
	v_mfma_f32_16x16x32_f16 v[88:91], v[68:71], v[128:131], v[116:119]
	v_mfma_f32_16x16x32_f16 v[116:119], v[186:189], v[138:141], v[88:91]
	v_mfma_f32_16x16x32_f16 v[88:91], v[68:71], v[142:145], v[112:115]
	v_mfma_f32_16x16x32_f16 v[112:115], v[186:189], v[146:149], v[88:91]
	v_mfma_f32_16x16x32_f16 v[88:91], v[190:193], v[128:131], v[108:111]
	v_mfma_f32_16x16x32_f16 v[108:111], v[194:197], v[138:141], v[88:91]
	v_mfma_f32_16x16x32_f16 v[88:91], v[190:193], v[142:145], v[104:107]
	v_mfma_f32_16x16x32_f16 v[100:103], v[194:197], v[146:149], v[88:91]
	v_mfma_f32_16x16x32_f16 v[88:91], v[198:201], v[128:131], v[210:213]
	v_mfma_f32_16x16x32_f16 v[96:99], v[202:205], v[138:141], v[88:91]
	v_mfma_f32_16x16x32_f16 v[88:91], v[198:201], v[142:145], v[214:217]
	v_mfma_f32_16x16x32_f16 v[88:91], v[202:205], v[146:149], v[88:91]
	s_barrier
;   #define LDA(dst,b,h) for(int m=0;m<4;++m)for(int k=0;k<2;++k) \
;     dst[m][k]=*reinterpret_cast<const h8*>(la+(((b)*2+(h))*16384+m*2048+k*1024))
;   #define LDB(dst,b,h) for(int n=0;n<2;++n)for(int k=0;k<2;++k) \
;     dst[n][k]=*reinterpret_cast<const h8*>(lb+(((b)*2+(h))*16384+n*2048+k*1024))
;   #define MMA(ai,bj,At,Bt_) do{__builtin_amdgcn_s_setprio(1); \
;     for(int m=0;m<4;++m)for(int n=0;n<2;++n)for(int k=0;k<2;++k) \
;       acc[ai][bj][m][n]=__builtin_amdgcn_mfma_f32_16x16x32_f16(At[m][k],Bt_[n][k],acc[ai][bj][m][n],0,0,0); \
;     __builtin_amdgcn_s_setprio(0);}while(0)
;   #define WAIT_V(n) asm volatile("s_waitcnt vmcnt(" #n ")":::"memory")
;   #define WAIT_L(n) asm volatile("s_waitcnt lgkmcnt(" #n ")":::"memory")
;   #define BAR __builtin_amdgcn_s_barrier()
;     ...
;   { LDB(B0,1,0); LDA(At,1,0); WAIT_V(2); BAR; WAIT_L(0); MMA(0,0,At,B0); BAR;
;     LDB(B1,1,1); WAIT_V(0); BAR; WAIT_L(0); MMA(0,1,At,B1); BAR;
;     LDA(At,1,1); BAR; WAIT_L(0); MMA(1,0,At,B0); MMA(1,1,At,B1); BAR; }
;   if(wr==0)BAR;
	ds_read_b128 v[206:209], v137 offset:49152
	ds_read_b128 v[210:213], v137 offset:50176
	ds_read_b128 v[214:217], v137 offset:51200
	ds_read_b128 v[218:221], v137 offset:52224
	s_waitcnt vmcnt(0)
	s_barrier
	s_waitcnt lgkmcnt(0)
	s_waitcnt lgkmcnt(0)
	v_mfma_f32_16x16x32_f16 v[92:95], v[48:51], v[206:209], v[92:95]
	v_mfma_f32_16x16x32_f16 v[48:51], v[48:51], v[214:217], v[158:161]
	v_mfma_f32_16x16x32_f16 v[104:107], v[60:63], v[210:213], v[92:95]
	v_mfma_f32_16x16x32_f16 v[92:95], v[60:63], v[218:221], v[48:51]
	v_mfma_f32_16x16x32_f16 v[48:51], v[68:71], v[206:209], v[84:87]
	v_mfma_f32_16x16x32_f16 v[84:87], v[186:189], v[210:213], v[48:51]
	v_mfma_f32_16x16x32_f16 v[48:51], v[68:71], v[214:217], v[80:83]
	v_mfma_f32_16x16x32_f16 v[80:83], v[186:189], v[218:221], v[48:51]
	v_mfma_f32_16x16x32_f16 v[48:51], v[190:193], v[206:209], v[76:79]
	v_mfma_f32_16x16x32_f16 v[76:79], v[194:197], v[210:213], v[48:51]
	v_mfma_f32_16x16x32_f16 v[48:51], v[190:193], v[214:217], v[72:75]
	v_mfma_f32_16x16x32_f16 v[68:71], v[194:197], v[218:221], v[48:51]
	v_mfma_f32_16x16x32_f16 v[48:51], v[198:201], v[206:209], v[162:165]
	v_mfma_f32_16x16x32_f16 v[60:63], v[202:205], v[210:213], v[48:51]
	v_mfma_f32_16x16x32_f16 v[48:51], v[198:201], v[214:217], v[64:67]
	v_mfma_f32_16x16x32_f16 v[48:51], v[202:205], v[218:221], v[48:51]
	s_barrier
	ds_read_b128 v[158:161], v136 offset:49152
	ds_read_b128 v[162:165], v136 offset:50176
	ds_read_b128 v[186:189], v136 offset:51200
	ds_read_b128 v[190:193], v136 offset:52224
	ds_read_b128 v[194:197], v136 offset:53248
	ds_read_b128 v[198:201], v136 offset:54272
	ds_read_b128 v[202:205], v136 offset:55296
	ds_read_b128 v[222:225], v136 offset:56320
	s_barrier
	s_waitcnt lgkmcnt(0)
	s_waitcnt lgkmcnt(0)
	v_mfma_f32_16x16x32_f16 v[64:67], v[158:161], v[128:131], v[226:229]
	v_mfma_f32_16x16x32_f16 v[56:59], v[158:161], v[142:145], v[56:59]
	v_mfma_f32_16x16x32_f16 v[52:55], v[186:189], v[128:131], v[52:55]
	v_mfma_f32_16x16x32_f16 v[72:75], v[162:165], v[138:141], v[64:67]
	v_mfma_f32_16x16x32_f16 v[64:67], v[162:165], v[146:149], v[56:59]
	v_mfma_f32_16x16x32_f16 v[56:59], v[190:193], v[138:141], v[52:55]
	v_mfma_f32_16x16x32_f16 v[52:55], v[186:189], v[142:145], v[230:233]
	v_mfma_f32_16x16x32_f16 v[44:47], v[194:197], v[128:131], v[44:47]
	v_mfma_f32_16x16x32_f16 v[40:43], v[194:197], v[142:145], v[40:43]
	v_mfma_f32_16x16x32_f16 v[36:39], v[202:205], v[128:131], v[36:39]
	v_mfma_f32_16x16x32_f16 v[32:35], v[202:205], v[142:145], v[32:35]
	v_mfma_f32_16x16x32_f16 v[52:55], v[190:193], v[146:149], v[52:55]
	v_mfma_f32_16x16x32_f16 v[44:47], v[198:201], v[138:141], v[44:47]
	v_mfma_f32_16x16x32_f16 v[40:43], v[198:201], v[146:149], v[40:43]
	v_mfma_f32_16x16x32_f16 v[36:39], v[222:225], v[138:141], v[36:39]
	v_mfma_f32_16x16x32_f16 v[32:35], v[222:225], v[146:149], v[32:35]
	v_mfma_f32_16x16x32_f16 v[28:31], v[158:161], v[206:209], v[28:31]
	v_mfma_f32_16x16x32_f16 v[24:27], v[158:161], v[214:217], v[24:27]
	v_mfma_f32_16x16x32_f16 v[20:23], v[186:189], v[206:209], v[20:23]
	v_mfma_f32_16x16x32_f16 v[16:19], v[186:189], v[214:217], v[16:19]
	v_mfma_f32_16x16x32_f16 v[12:15], v[194:197], v[206:209], v[12:15]
	v_mfma_f32_16x16x32_f16 v[8:11], v[194:197], v[214:217], v[8:11]
	v_mfma_f32_16x16x32_f16 v[4:7], v[202:205], v[206:209], v[4:7]
	v_mfma_f32_16x16x32_f16 v[0:3], v[202:205], v[214:217], v[0:3]
	v_mfma_f32_16x16x32_f16 v[28:31], v[162:165], v[210:213], v[28:31]
	v_mfma_f32_16x16x32_f16 v[24:27], v[162:165], v[218:221], v[24:27]
	v_mfma_f32_16x16x32_f16 v[20:23], v[190:193], v[210:213], v[20:23]
	v_mfma_f32_16x16x32_f16 v[16:19], v[190:193], v[218:221], v[16:19]
	v_mfma_f32_16x16x32_f16 v[12:15], v[198:201], v[210:213], v[12:15]
	v_mfma_f32_16x16x32_f16 v[8:11], v[198:201], v[218:221], v[8:11]
	v_mfma_f32_16x16x32_f16 v[4:7], v[222:225], v[210:213], v[4:7]
	v_mfma_f32_16x16x32_f16 v[0:3], v[222:225], v[218:221], v[0:3]
	s_movk_i32 s1, 0x100
	v_cmp_gt_u32_e32 vcc, s1, v135
	s_barrier
	s_and_saveexec_b64 s[6:7], vcc
	s_cbranch_execz .LBB0_180
	s_barrier

;   #define STAGE(P,BASE,LD,br,kt) do{ const HALF* _u=(BASE)+(long)(br)*(((&(LD))==&lda)?lda_u:(LD))+(long)(kt)*G_BK; \
;     for(int _i=0;_i<2;++_i){ \
;       __builtin_amdgcn_global_load_lds((const unsigned*)(_u+(long)_i*(((&(LD))==&lda)?stepa:stepb)+((&(LD))==&lda?oa0:ob0)), \
;         (unsigned*)((char*)(P)+t5*16+_i*8192),16,0,0);}}while(0)
;   #define LDA(dst,b,h) for(int m=0;m<4;++m)for(int k=0;k<2;++k) \
;     dst[m][k]=*reinterpret_cast<const h8*>(la+(((b)*2+(h))*16384+m*2048+k*1024))
;   #define LDB(dst,b,h) for(int n=0;n<2;++n)for(int k=0;k<2;++k) \
;     dst[n][k]=*reinterpret_cast<const h8*>(lb+(((b)*2+(h))*16384+n*2048+k*1024))
;   #define MMA(ai,bj,At,Bt_) do{__builtin_amdgcn_s_setprio(1); \
;     for(int m=0;m<4;++m)for(int n=0;n<2;++n)for(int k=0;k<2;++k) \
;       acc[ai][bj][m][n]=__builtin_amdgcn_mfma_f32_16x16x32_f16(At[m][k],Bt_[n][k],acc[ai][bj][m][n],0,0,0); \
;     __builtin_amdgcn_s_setprio(0);}while(0)
;   #define WAIT_L(n) asm volatile("s_waitcnt lgkmcnt(" #n ")":::"memory")
;   #define BAR __builtin_amdgcn_s_barrier()
;   #define SCHED __builtin_amdgcn_sched_barrier(0)
;     ...
;   for(int t=0;t<nt-2;t+=2){
;     LDB(B0,0,0); SCHED; LDA(At,0,0); STAGE(SA(1,1),A,lda,G_HALF,t+1);
;     WAIT_L(8); BAR; WAIT_L(0); MMA(0,0,At,B0); BAR; SCHED;
;     LDB(B1,0,1); STAGE(SB(0,0),Bt,ldb,0,t+2);
;     BAR; WAIT_L(0); MMA(0,1,At,B1); BAR;
;     LDA(At,0,1); STAGE(SA(0,0),A,lda,0,t+2);
;     BAR; WAIT_L(0); MMA(1,0,At,B0); BAR; SCHED;
.LBB0_193:
	ds_read_b128 v[158:161], v133
	ds_read_b128 v[162:165], v133 offset:1024
	ds_read_b128 v[186:189], v133 offset:2048
	ds_read_b128 v[190:193], v133 offset:3072
	v_add_u32_e32 v148, 0xc000, v136
	v_lshl_add_u64 v[150:151], v[128:129], 0, s[10:11]
	v_readfirstlane_b32 s13, v148
	v_add_u32_e32 v149, 0xe000, v136
	v_lshl_add_u64 v[166:167], v[150:151], 0, s[68:69]
	s_mov_b32 m0, s13
	v_readfirstlane_b32 s13, v149
	ds_read_b128 v[194:197], v132
	ds_read_b128 v[198:201], v132 offset:1024
	ds_read_b128 v[202:205], v132 offset:2048
	ds_read_b128 v[206:209], v132 offset:3072
	ds_read_b128 v[210:213], v132 offset:4096
	ds_read_b128 v[214:217], v132 offset:5120
	ds_read_b128 v[218:221], v132 offset:6144
	ds_read_b128 v[222:225], v132 offset:7168
	global_load_lds_dwordx4 v[166:167], off
	v_lshl_add_u64 v[166:167], v[150:151], 0, s[70:71]
	s_mov_b32 m0, s13
	s_nop 0
	global_load_lds_dwordx4 v[166:167], off
	s_waitcnt lgkmcnt(8)
	s_barrier
	s_waitcnt lgkmcnt(0)
	s_waitcnt lgkmcnt(0)
	v_mfma_f32_16x16x32_f16 v[124:127], v[194:197], v[158:161], v[124:127]
	v_mfma_f32_16x16x32_f16 v[120:123], v[194:197], v[186:189], v[120:123]
	v_mfma_f32_16x16x32_f16 v[116:119], v[202:205], v[158:161], v[116:119]
	v_mfma_f32_16x16x32_f16 v[112:115], v[202:205], v[186:189], v[112:115]
	v_mfma_f32_16x16x32_f16 v[108:111], v[210:213], v[158:161], v[108:111]
	v_mfma_f32_16x16x32_f16 v[104:107], v[210:213], v[186:189], v[104:107]
	v_mfma_f32_16x16x32_f16 v[100:103], v[218:221], v[158:161], v[100:103]
	v_mfma_f32_16x16x32_f16 v[96:99], v[218:221], v[186:189], v[96:99]
	v_mfma_f32_16x16x32_f16 v[124:127], v[198:201], v[162:165], v[124:127]
	v_mfma_f32_16x16x32_f16 v[120:123], v[198:201], v[190:193], v[120:123]
	v_mfma_f32_16x16x32_f16 v[116:119], v[206:209], v[162:165], v[116:119]
	v_mfma_f32_16x16x32_f16 v[112:115], v[206:209], v[190:193], v[112:115]
	v_mfma_f32_16x16x32_f16 v[108:111], v[214:217], v[162:165], v[108:111]
	v_mfma_f32_16x16x32_f16 v[104:107], v[214:217], v[190:193], v[104:107]
	v_mfma_f32_16x16x32_f16 v[100:103], v[222:225], v[162:165], v[100:103]
	v_mfma_f32_16x16x32_f16 v[96:99], v[222:225], v[190:193], v[96:99]
	s_barrier
	v_lshl_add_u64 v[166:167], v[128:129], 0, s[6:7]
	v_readfirstlane_b32 s13, v134
	v_lshl_add_u64 v[168:169], v[166:167], 0, s[92:93]
	s_mov_b32 m0, s13
	v_readfirstlane_b32 s13, v135
	ds_read_b128 v[226:229], v133 offset:16384
	ds_read_b128 v[230:233], v133 offset:17408
	ds_read_b128 v[234:237], v133 offset:18432
	ds_read_b128 v[238:241], v133 offset:19456
	global_load_lds_dwordx4 v[168:169], off
	v_lshl_add_u64 v[168:169], v[166:167], 0, s[66:67]
	s_mov_b32 m0, s13
	s_nop 0
	global_load_lds_dwordx4 v[168:169], off
	s_barrier
	s_waitcnt lgkmcnt(0)
	s_waitcnt lgkmcnt(0)
	v_mfma_f32_16x16x32_f16 v[92:95], v[194:197], v[226:229], v[92:95]
	v_mfma_f32_16x16x32_f16 v[88:91], v[194:197], v[234:237], v[88:91]
	v_mfma_f32_16x16x32_f16 v[84:87], v[202:205], v[226:229], v[84:87]
	v_mfma_f32_16x16x32_f16 v[80:83], v[202:205], v[234:237], v[80:83]
	v_mfma_f32_16x16x32_f16 v[76:79], v[210:213], v[226:229], v[76:79]
	v_mfma_f32_16x16x32_f16 v[72:75], v[210:213], v[234:237], v[72:75]
	v_mfma_f32_16x16x32_f16 v[68:71], v[218:221], v[226:229], v[68:71]
	v_mfma_f32_16x16x32_f16 v[64:67], v[218:221], v[234:237], v[64:67]
	v_mfma_f32_16x16x32_f16 v[92:95], v[198:201], v[230:233], v[92:95]
	v_mfma_f32_16x16x32_f16 v[88:91], v[198:201], v[238:241], v[88:91]
	v_mfma_f32_16x16x32_f16 v[84:87], v[206:209], v[230:233], v[84:87]
	v_mfma_f32_16x16x32_f16 v[80:83], v[206:209], v[238:241], v[80:83]
	v_mfma_f32_16x16x32_f16 v[76:79], v[214:217], v[230:233], v[76:79]
	v_mfma_f32_16x16x32_f16 v[72:75], v[214:217], v[238:241], v[72:75]
	v_mfma_f32_16x16x32_f16 v[68:71], v[222:225], v[230:233], v[68:71]
	v_mfma_f32_16x16x32_f16 v[64:67], v[222:225], v[238:241], v[64:67]
	v_readfirstlane_b32 s13, v136
	v_lshl_add_u64 v[168:169], v[150:151], 0, s[36:37]
	s_mov_b32 m0, s13
	v_readfirstlane_b32 s13, v137
	s_barrier
	ds_read_b128 v[194:197], v132 offset:16384
	ds_read_b128 v[198:201], v132 offset:17408
	ds_read_b128 v[202:205], v132 offset:18432
	ds_read_b128 v[206:209], v132 offset:19456
	ds_read_b128 v[210:213], v132 offset:20480
	ds_read_b128 v[214:217], v132 offset:21504
	ds_read_b128 v[218:221], v132 offset:22528
	ds_read_b128 v[222:225], v132 offset:23552
	global_load_lds_dwordx4 v[168:169], off
	v_lshl_add_u64 v[168:169], v[150:151], 0, s[54:55]
	s_mov_b32 m0, s13
	s_nop 0
	global_load_lds_dwordx4 v[168:169], off
	s_barrier
	s_waitcnt lgkmcnt(0)
	s_waitcnt lgkmcnt(0)
	v_mfma_f32_16x16x32_f16 v[60:63], v[194:197], v[158:161], v[60:63]
	v_mfma_f32_16x16x32_f16 v[56:59], v[194:197], v[186:189], v[56:59]
	v_mfma_f32_16x16x32_f16 v[52:55], v[202:205], v[158:161], v[52:55]
	v_mfma_f32_16x16x32_f16 v[48:51], v[202:205], v[186:189], v[48:51]
	v_mfma_f32_16x16x32_f16 v[44:47], v[210:213], v[158:161], v[44:47]
	v_mfma_f32_16x16x32_f16 v[40:43], v[210:213], v[186:189], v[40:43]
	v_mfma_f32_16x16x32_f16 v[36:39], v[218:221], v[158:161], v[36:39]
	v_mfma_f32_16x16x32_f16 v[32:35], v[218:221], v[186:189], v[32:35]
	v_mfma_f32_16x16x32_f16 v[60:63], v[198:201], v[162:165], v[60:63]
	v_mfma_f32_16x16x32_f16 v[56:59], v[198:201], v[190:193], v[56:59]
	v_mfma_f32_16x16x32_f16 v[52:55], v[206:209], v[162:165], v[52:55]
	v_mfma_f32_16x16x32_f16 v[48:51], v[206:209], v[190:193], v[48:51]
	v_mfma_f32_16x16x32_f16 v[44:47], v[214:217], v[162:165], v[44:47]
	v_mfma_f32_16x16x32_f16 v[40:43], v[214:217], v[190:193], v[40:43]
	v_mfma_f32_16x16x32_f16 v[36:39], v[222:225], v[162:165], v[36:39]
	v_mfma_f32_16x16x32_f16 v[32:35], v[222:225], v[190:193], v[32:35]
	s_barrier
;   #define STAGE(P,BASE,LD,br,kt) do{ const HALF* _u=(BASE)+(long)(br)*(((&(LD))==&lda)?lda_u:(LD))+(long)(kt)*G_BK; \
;     for(int _i=0;_i<2;++_i){ \
;       __builtin_amdgcn_global_load_lds((const unsigned*)(_u+(long)_i*(((&(LD))==&lda)?stepa:stepb)+((&(LD))==&lda?oa0:ob0)), \
;         (unsigned*)((char*)(P)+t5*16+_i*8192),16,0,0);}}while(0)
;   #define LDA(dst,b,h) for(int m=0;m<4;++m)for(int k=0;k<2;++k) \
;     dst[m][k]=*reinterpret_cast<const h8*>(la+(((b)*2+(h))*16384+m*2048+k*1024))
;   #define LDB(dst,b,h) for(int n=0;n<2;++n)for(int k=0;k<2;++k) \
;     dst[n][k]=*reinterpret_cast<const h8*>(lb+(((b)*2+(h))*16384+n*2048+k*1024))
;   #define MMA(ai,bj,At,Bt_) do{__builtin_amdgcn_s_setprio(1); \
;     for(int m=0;m<4;++m)for(int n=0;n<2;++n)for(int k=0;k<2;++k) \
;       acc[ai][bj][m][n]=__builtin_amdgcn_mfma_f32_16x16x32_f16(At[m][k],Bt_[n][k],acc[ai][bj][m][n],0,0,0); \
;     __builtin_amdgcn_s_setprio(0);}while(0)
;   #define WAIT_V(n) asm volatile("s_waitcnt vmcnt(" #n ")":::"memory")
;   #define WAIT_L(n) asm volatile("s_waitcnt lgkmcnt(" #n ")":::"memory")
;   #define BAR __builtin_amdgcn_s_barrier()
;   #define SCHED __builtin_amdgcn_sched_barrier(0)
;     ...
;     STAGE(SB(0,1),Bt,ldb,G_HALF,t+2);
;     WAIT_V(6); BAR; MMA(1,1,At,B1); BAR;
;     LDB(B0,1,0); SCHED; LDA(At,1,0); STAGE(SA(0,1),A,lda,G_HALF,t+2);
;     WAIT_L(8); BAR; WAIT_L(0); MMA(0,0,At,B0); BAR; SCHED;
;     LDB(B1,1,1); STAGE(SB(1,0),Bt,ldb,0,t+3);
;     BAR; WAIT_L(0); MMA(0,1,At,B1); BAR;
;     LDA(At,1,1); STAGE(SA(1,0),A,lda,0,t+3);
	v_readfirstlane_b32 s13, v138
	v_lshl_add_u64 v[158:159], v[166:167], 0, s[38:39]
	s_mov_b32 m0, s13
	v_readfirstlane_b32 s13, v139
	global_load_lds_dwordx4 v[158:159], off
	v_lshl_add_u64 v[158:159], v[166:167], 0, s[40:41]
	s_mov_b32 m0, s13
	s_nop 0
	global_load_lds_dwordx4 v[158:159], off
	s_waitcnt vmcnt(6)
	s_barrier
	v_mfma_f32_16x16x32_f16 v[28:31], v[194:197], v[226:229], v[28:31]
	v_mfma_f32_16x16x32_f16 v[24:27], v[194:197], v[234:237], v[24:27]
	v_mfma_f32_16x16x32_f16 v[20:23], v[202:205], v[226:229], v[20:23]
	v_mfma_f32_16x16x32_f16 v[16:19], v[202:205], v[234:237], v[16:19]
	v_mfma_f32_16x16x32_f16 v[12:15], v[210:213], v[226:229], v[12:15]
	v_mfma_f32_16x16x32_f16 v[8:11], v[210:213], v[234:237], v[8:11]
	v_mfma_f32_16x16x32_f16 v[4:7], v[218:221], v[226:229], v[4:7]
	v_mfma_f32_16x16x32_f16 v[0:3], v[218:221], v[234:237], v[0:3]
	v_mfma_f32_16x16x32_f16 v[28:31], v[198:201], v[230:233], v[28:31]
	v_mfma_f32_16x16x32_f16 v[24:27], v[198:201], v[238:241], v[24:27]
	v_mfma_f32_16x16x32_f16 v[20:23], v[206:209], v[230:233], v[20:23]
	v_mfma_f32_16x16x32_f16 v[16:19], v[206:209], v[238:241], v[16:19]
	v_mfma_f32_16x16x32_f16 v[12:15], v[214:217], v[230:233], v[12:15]
	v_mfma_f32_16x16x32_f16 v[8:11], v[214:217], v[238:241], v[8:11]
	v_mfma_f32_16x16x32_f16 v[4:7], v[222:225], v[230:233], v[4:7]
	v_mfma_f32_16x16x32_f16 v[0:3], v[222:225], v[238:241], v[0:3]
	s_barrier
	ds_read_b128 v[158:161], v133 offset:32768
	ds_read_b128 v[162:165], v133 offset:33792
	ds_read_b128 v[186:189], v133 offset:34816
	ds_read_b128 v[190:193], v133 offset:35840
	v_readfirstlane_b32 s13, v140
	v_lshl_add_u64 v[168:169], v[150:151], 0, s[24:25]
	s_mov_b32 m0, s13
	v_readfirstlane_b32 s13, v141
	ds_read_b128 v[194:197], v132 offset:32768
	ds_read_b128 v[198:201], v132 offset:33792
	ds_read_b128 v[202:205], v132 offset:34816
	ds_read_b128 v[206:209], v132 offset:35840
	ds_read_b128 v[210:213], v132 offset:36864
	ds_read_b128 v[214:217], v132 offset:37888
	ds_read_b128 v[218:221], v132 offset:38912
	ds_read_b128 v[222:225], v132 offset:39936
	global_load_lds_dwordx4 v[168:169], off
	v_lshl_add_u64 v[168:169], v[150:151], 0, s[48:49]
	s_mov_b32 m0, s13
	s_nop 0
	global_load_lds_dwordx4 v[168:169], off
	s_waitcnt lgkmcnt(8)
	s_barrier
	s_waitcnt lgkmcnt(0)
	s_waitcnt lgkmcnt(0)
	v_mfma_f32_16x16x32_f16 v[124:127], v[194:197], v[158:161], v[124:127]
	v_mfma_f32_16x16x32_f16 v[120:123], v[194:197], v[186:189], v[120:123]
	v_mfma_f32_16x16x32_f16 v[116:119], v[202:205], v[158:161], v[116:119]
	v_mfma_f32_16x16x32_f16 v[112:115], v[202:205], v[186:189], v[112:115]
	v_mfma_f32_16x16x32_f16 v[108:111], v[210:213], v[158:161], v[108:111]
	v_mfma_f32_16x16x32_f16 v[104:107], v[210:213], v[186:189], v[104:107]
	v_mfma_f32_16x16x32_f16 v[100:103], v[218:221], v[158:161], v[100:103]
	v_mfma_f32_16x16x32_f16 v[96:99], v[218:221], v[186:189], v[96:99]
	v_mfma_f32_16x16x32_f16 v[124:127], v[198:201], v[162:165], v[124:127]
	v_mfma_f32_16x16x32_f16 v[120:123], v[198:201], v[190:193], v[120:123]
	v_mfma_f32_16x16x32_f16 v[116:119], v[206:209], v[162:165], v[116:119]
	v_mfma_f32_16x16x32_f16 v[112:115], v[206:209], v[190:193], v[112:115]
	v_mfma_f32_16x16x32_f16 v[108:111], v[214:217], v[162:165], v[108:111]
	v_mfma_f32_16x16x32_f16 v[104:107], v[214:217], v[190:193], v[104:107]
	v_mfma_f32_16x16x32_f16 v[100:103], v[222:225], v[162:165], v[100:103]
	v_mfma_f32_16x16x32_f16 v[96:99], v[222:225], v[190:193], v[96:99]
	s_barrier
	v_readfirstlane_b32 s13, v142
	v_lshl_add_u64 v[168:169], v[166:167], 0, s[42:43]
	s_mov_b32 m0, s13
	v_readfirstlane_b32 s13, v143
	ds_read_b128 v[226:229], v133 offset:49152
	ds_read_b128 v[230:233], v133 offset:50176
	ds_read_b128 v[234:237], v133 offset:51200
	ds_read_b128 v[238:241], v133 offset:52224
	global_load_lds_dwordx4 v[168:169], off
	v_lshl_add_u64 v[168:169], v[166:167], 0, s[96:97]
	s_mov_b32 m0, s13
	s_nop 0
	global_load_lds_dwordx4 v[168:169], off
	s_barrier
	s_waitcnt lgkmcnt(0)
	s_waitcnt lgkmcnt(0)
	v_mfma_f32_16x16x32_f16 v[92:95], v[194:197], v[226:229], v[92:95]
	v_mfma_f32_16x16x32_f16 v[88:91], v[194:197], v[234:237], v[88:91]
	v_mfma_f32_16x16x32_f16 v[84:87], v[202:205], v[226:229], v[84:87]
	v_mfma_f32_16x16x32_f16 v[80:83], v[202:205], v[234:237], v[80:83]
	v_mfma_f32_16x16x32_f16 v[76:79], v[210:213], v[226:229], v[76:79]
	v_mfma_f32_16x16x32_f16 v[72:75], v[210:213], v[234:237], v[72:75]
	v_mfma_f32_16x16x32_f16 v[68:71], v[218:221], v[226:229], v[68:71]
	v_mfma_f32_16x16x32_f16 v[64:67], v[218:221], v[234:237], v[64:67]
	v_mfma_f32_16x16x32_f16 v[92:95], v[198:201], v[230:233], v[92:95]
	v_mfma_f32_16x16x32_f16 v[88:91], v[198:201], v[238:241], v[88:91]
	v_mfma_f32_16x16x32_f16 v[84:87], v[206:209], v[230:233], v[84:87]
	v_mfma_f32_16x16x32_f16 v[80:83], v[206:209], v[238:241], v[80:83]
	v_mfma_f32_16x16x32_f16 v[76:79], v[214:217], v[230:233], v[76:79]
	v_mfma_f32_16x16x32_f16 v[72:75], v[214:217], v[238:241], v[72:75]
	v_mfma_f32_16x16x32_f16 v[68:71], v[222:225], v[230:233], v[68:71]
	v_mfma_f32_16x16x32_f16 v[64:67], v[222:225], v[238:241], v[64:67]
	v_readfirstlane_b32 s13, v144
	v_lshl_add_u64 v[168:169], v[150:151], 0, s[60:61]
	s_mov_b32 m0, s13
	v_readfirstlane_b32 s13, v145
	s_barrier
	ds_read_b128 v[194:197], v132 offset:49152
	ds_read_b128 v[198:201], v132 offset:50176
	ds_read_b128 v[202:205], v132 offset:51200
	ds_read_b128 v[206:209], v132 offset:52224
	ds_read_b128 v[210:213], v132 offset:53248
	ds_read_b128 v[214:217], v132 offset:54272
	ds_read_b128 v[218:221], v132 offset:55296
	ds_read_b128 v[222:225], v132 offset:56320
	global_load_lds_dwordx4 v[168:169], off
	v_lshl_add_u64 v[150:151], v[150:151], 0, s[26:27]
	s_mov_b32 m0, s13
	s_nop 0
	global_load_lds_dwordx4 v[150:151], off
	s_barrier
;   #define STAGE(P,BASE,LD,br,kt) do{ const HALF* _u=(BASE)+(long)(br)*(((&(LD))==&lda)?lda_u:(LD))+(long)(kt)*G_BK; \
;     for(int _i=0;_i<2;++_i){ \
;       __builtin_amdgcn_global_load_lds((const unsigned*)(_u+(long)_i*(((&(LD))==&lda)?stepa:stepb)+((&(LD))==&lda?oa0:ob0)), \
;         (unsigned*)((char*)(P)+t5*16+_i*8192),16,0,0);}}while(0)
;   #define LDA(dst,b,h) for(int m=0;m<4;++m)for(int k=0;k<2;++k) \
;     dst[m][k]=*reinterpret_cast<const h8*>(la+(((b)*2+(h))*16384+m*2048+k*1024))
;   #define LDB(dst,b,h) for(int n=0;n<2;++n)for(int k=0;k<2;++k) \
;     dst[n][k]=*reinterpret_cast<const h8*>(lb+(((b)*2+(h))*16384+n*2048+k*1024))
;   #define MMA(ai,bj,At,Bt_) do{__builtin_amdgcn_s_setprio(1); \
;     for(int m=0;m<4;++m)for(int n=0;n<2;++n)for(int k=0;k<2;++k) \
;       acc[ai][bj][m][n]=__builtin_amdgcn_mfma_f32_16x16x32_f16(At[m][k],Bt_[n][k],acc[ai][bj][m][n],0,0,0); \
;     __builtin_amdgcn_s_setprio(0);}while(0)
;   #define WAIT_V(n) asm volatile("s_waitcnt vmcnt(" #n ")":::"memory")
;   #define WAIT_L(n) asm volatile("s_waitcnt lgkmcnt(" #n ")":::"memory")
;   #define BAR __builtin_amdgcn_s_barrier()
;   #define SCHED __builtin_amdgcn_sched_barrier(0)
;     ...
;     LDA(At,1,1); STAGE(SA(1,0),A,lda,0,t+3);
;     BAR; WAIT_L(0); MMA(1,0,At,B0); BAR; SCHED;
;     STAGE(SB(1,1),Bt,ldb,G_HALF,t+3);
;     WAIT_V(6); BAR; MMA(1,1,At,B1); BAR;
;   }
;   { LDB(B0,0,0); LDA(At,0,0); STAGE(SA(1,1),A,lda,G_HALF,nt-1);
;     BAR; WAIT_L(0); MMA(0,0,At,B0); BAR;
;     LDB(B1,0,1); BAR; WAIT_L(0); MMA(0,1,At,B1); BAR;
	s_waitcnt lgkmcnt(0)
	s_waitcnt lgkmcnt(0)
	v_mfma_f32_16x16x32_f16 v[60:63], v[194:197], v[158:161], v[60:63]
	v_mfma_f32_16x16x32_f16 v[56:59], v[194:197], v[186:189], v[56:59]
	v_mfma_f32_16x16x32_f16 v[52:55], v[202:205], v[158:161], v[52:55]
	v_mfma_f32_16x16x32_f16 v[48:51], v[202:205], v[186:189], v[48:51]
	v_mfma_f32_16x16x32_f16 v[44:47], v[210:213], v[158:161], v[44:47]
	v_mfma_f32_16x16x32_f16 v[40:43], v[210:213], v[186:189], v[40:43]
	v_mfma_f32_16x16x32_f16 v[36:39], v[218:221], v[158:161], v[36:39]
	v_mfma_f32_16x16x32_f16 v[32:35], v[218:221], v[186:189], v[32:35]
	v_mfma_f32_16x16x32_f16 v[60:63], v[198:201], v[162:165], v[60:63]
	v_mfma_f32_16x16x32_f16 v[56:59], v[198:201], v[190:193], v[56:59]
	v_mfma_f32_16x16x32_f16 v[52:55], v[206:209], v[162:165], v[52:55]
	v_mfma_f32_16x16x32_f16 v[48:51], v[206:209], v[190:193], v[48:51]
	v_mfma_f32_16x16x32_f16 v[44:47], v[214:217], v[162:165], v[44:47]
	v_mfma_f32_16x16x32_f16 v[40:43], v[214:217], v[190:193], v[40:43]
	v_mfma_f32_16x16x32_f16 v[36:39], v[222:225], v[162:165], v[36:39]
	v_mfma_f32_16x16x32_f16 v[32:35], v[222:225], v[190:193], v[32:35]
	s_barrier
	v_readfirstlane_b32 s13, v146
	v_lshl_add_u64 v[150:151], v[166:167], 0, s[14:15]
	s_mov_b32 m0, s13
	v_readfirstlane_b32 s13, v147
	global_load_lds_dwordx4 v[150:151], off
	v_lshl_add_u64 v[150:151], v[166:167], 0, s[58:59]
	s_mov_b32 m0, s13
	s_nop 0
	global_load_lds_dwordx4 v[150:151], off
	s_waitcnt vmcnt(6)
	s_barrier
	v_mfma_f32_16x16x32_f16 v[28:31], v[194:197], v[226:229], v[28:31]
	v_mfma_f32_16x16x32_f16 v[24:27], v[194:197], v[234:237], v[24:27]
	v_mfma_f32_16x16x32_f16 v[20:23], v[202:205], v[226:229], v[20:23]
	v_mfma_f32_16x16x32_f16 v[16:19], v[202:205], v[234:237], v[16:19]
	v_mfma_f32_16x16x32_f16 v[12:15], v[210:213], v[226:229], v[12:15]
	v_mfma_f32_16x16x32_f16 v[8:11], v[210:213], v[234:237], v[8:11]
	v_mfma_f32_16x16x32_f16 v[4:7], v[218:221], v[226:229], v[4:7]
	v_mfma_f32_16x16x32_f16 v[0:3], v[218:221], v[234:237], v[0:3]
	v_mfma_f32_16x16x32_f16 v[28:31], v[198:201], v[230:233], v[28:31]
	v_mfma_f32_16x16x32_f16 v[24:27], v[198:201], v[238:241], v[24:27]
	v_mfma_f32_16x16x32_f16 v[20:23], v[206:209], v[230:233], v[20:23]
	v_mfma_f32_16x16x32_f16 v[16:19], v[206:209], v[238:241], v[16:19]
	v_mfma_f32_16x16x32_f16 v[12:15], v[214:217], v[230:233], v[12:15]
	v_mfma_f32_16x16x32_f16 v[8:11], v[214:217], v[238:241], v[8:11]
	v_mfma_f32_16x16x32_f16 v[4:7], v[222:225], v[230:233], v[4:7]
	v_mfma_f32_16x16x32_f16 v[0:3], v[222:225], v[238:241], v[0:3]
	s_add_i32 s12, s12, 2
	s_cmp_lt_u32 s12, 12
	v_lshl_add_u64 v[128:129], v[128:129], 0, s[92:93]
	s_barrier
	s_cbranch_scc1 .LBB0_193
	v_lshl_add_u64 v[128:129], v[152:153], 1, s[2:3]
	s_mov_b64 s[2:3], 0x40780
	v_lshl_add_u64 v[146:147], v[128:129], 0, s[2:3]
	v_readfirstlane_b32 s2, v148
	s_mov_b32 m0, s2
	s_mov_b64 s[2:3], 0x60780
	v_lshl_add_u64 v[128:129], v[128:129], 0, s[2:3]
	v_readfirstlane_b32 s2, v149
	ds_read_b128 v[134:137], v133
	ds_read_b128 v[138:141], v133 offset:1024
	ds_read_b128 v[142:145], v133 offset:2048
	ds_read_b128 v[158:161], v133 offset:3072
	ds_read_b128 v[162:165], v132
	ds_read_b128 v[186:189], v132 offset:1024
	ds_read_b128 v[190:193], v132 offset:2048
	ds_read_b128 v[194:197], v132 offset:3072
	ds_read_b128 v[198:201], v132 offset:4096
	ds_read_b128 v[202:205], v132 offset:5120
	ds_read_b128 v[206:209], v132 offset:6144
	ds_read_b128 v[210:213], v132 offset:7168
	global_load_lds_dwordx4 v[146:147], off
	s_mov_b32 m0, s2
	s_nop 0
	global_load_lds_dwordx4 v[128:129], off
	s_barrier
	s_waitcnt lgkmcnt(0)
	s_waitcnt lgkmcnt(0)
	v_mfma_f32_16x16x32_f16 v[124:127], v[162:165], v[134:137], v[124:127]
	v_mfma_f32_16x16x32_f16 v[116:119], v[190:193], v[134:137], v[116:119]
	v_mfma_f32_16x16x32_f16 v[108:111], v[198:201], v[134:137], v[108:111]
	v_mfma_f32_16x16x32_f16 v[100:103], v[206:209], v[134:137], v[100:103]
	v_mfma_f32_16x16x32_f16 v[124:127], v[186:189], v[138:141], v[124:127]
	v_mfma_f32_16x16x32_f16 v[120:123], v[162:165], v[142:145], v[120:123]
	v_mfma_f32_16x16x32_f16 v[116:119], v[194:197], v[138:141], v[116:119]
	v_mfma_f32_16x16x32_f16 v[112:115], v[190:193], v[142:145], v[112:115]
	v_mfma_f32_16x16x32_f16 v[108:111], v[202:205], v[138:141], v[108:111]
	v_mfma_f32_16x16x32_f16 v[104:107], v[198:201], v[142:145], v[104:107]
	v_mfma_f32_16x16x32_f16 v[100:103], v[210:213], v[138:141], v[100:103]
	v_mfma_f32_16x16x32_f16 v[96:99], v[206:209], v[142:145], v[96:99]
	v_mfma_f32_16x16x32_f16 v[146:149], v[186:189], v[158:161], v[120:123]
	v_mfma_f32_16x16x32_f16 v[214:217], v[194:197], v[158:161], v[112:115]
	v_mfma_f32_16x16x32_f16 v[218:221], v[202:205], v[158:161], v[104:107]
	v_mfma_f32_16x16x32_f16 v[222:225], v[210:213], v[158:161], v[96:99]
	s_barrier
	s_nop 1
	ds_read_b128 v[96:99], v133 offset:16384
	ds_read_b128 v[104:107], v133 offset:17408
	ds_read_b128 v[112:115], v133 offset:18432
	ds_read_b128 v[120:123], v133 offset:19456
	s_barrier
	s_waitcnt lgkmcnt(0)
	s_waitcnt lgkmcnt(0)
	v_mfma_f32_16x16x32_f16 v[92:95], v[162:165], v[96:99], v[92:95]
	v_mfma_f32_16x16x32_f16 v[84:87], v[190:193], v[96:99], v[84:87]
	v_mfma_f32_16x16x32_f16 v[76:79], v[198:201], v[96:99], v[76:79]
	v_mfma_f32_16x16x32_f16 v[68:71], v[206:209], v[96:99], v[68:71]
	v_mfma_f32_16x16x32_f16 v[92:95], v[186:189], v[104:107], v[92:95]
	v_mfma_f32_16x16x32_f16 v[88:91], v[162:165], v[112:115], v[88:91]
	v_mfma_f32_16x16x32_f16 v[84:87], v[194:197], v[104:107], v[84:87]
	v_mfma_f32_16x16x32_f16 v[80:83], v[190:193], v[112:115], v[80:83]
	v_mfma_f32_16x16x32_f16 v[76:79], v[202:205], v[104:107], v[76:79]
	v_mfma_f32_16x16x32_f16 v[72:75], v[198:201], v[112:115], v[72:75]
	v_mfma_f32_16x16x32_f16 v[68:71], v[210:213], v[104:107], v[68:71]
	v_mfma_f32_16x16x32_f16 v[64:67], v[206:209], v[112:115], v[64:67]
	v_mfma_f32_16x16x32_f16 v[162:165], v[186:189], v[120:123], v[88:91]
	v_mfma_f32_16x16x32_f16 v[186:189], v[194:197], v[120:123], v[80:83]
	v_mfma_f32_16x16x32_f16 v[190:193], v[202:205], v[120:123], v[72:75]
	v_mfma_f32_16x16x32_f16 v[194:197], v[210:213], v[120:123], v[64:67]
	s_barrier
;   #define LDA(dst,b,h) for(int m=0;m<4;++m)for(int k=0;k<2;++k) \
;     dst[m][k]=*reinterpret_cast<const h8*>(la+(((b)*2+(h))*16384+m*2048+k*1024))
;   #define LDB(dst,b,h) for(int n=0;n<2;++n)for(int k=0;k<2;++k) \
;     dst[n][k]=*reinterpret_cast<const h8*>(lb+(((b)*2+(h))*16384+n*2048+k*1024))
;   #define MMA(ai,bj,At,Bt_) do{__builtin_amdgcn_s_setprio(1); \
;     for(int m=0;m<4;++m)for(int n=0;n<2;++n)for(int k=0;k<2;++k) \
;       acc[ai][bj][m][n]=__builtin_amdgcn_mfma_f32_16x16x32_f16(At[m][k],Bt_[n][k],acc[ai][bj][m][n],0,0,0); \
;     __builtin_amdgcn_s_setprio(0);}while(0)
;   #define WAIT_V(n) asm volatile("s_waitcnt vmcnt(" #n ")":::"memory")
;   #define WAIT_L(n) asm volatile("s_waitcnt lgkmcnt(" #n ")":::"memory")
;   #define BAR __builtin_amdgcn_s_barrier()
;     ...
;     LDB(B1,0,1); BAR; WAIT_L(0); MMA(0,1,At,B1); BAR;
;     LDA(At,0,1); WAIT_V(4); BAR; WAIT_L(0); MMA(1,0,At,B0); MMA(1,1,At,B1); BAR; }
;   { LDB(B0,1,0); LDA(At,1,0); WAIT_V(2); BAR; WAIT_L(0); MMA(0,0,At,B0); BAR;
	s_nop 1
	ds_read_b128 v[64:67], v132 offset:16384
	ds_read_b128 v[72:75], v132 offset:17408
	ds_read_b128 v[80:83], v132 offset:18432
	ds_read_b128 v[88:91], v132 offset:19456
	ds_read_b128 v[198:201], v132 offset:20480
	ds_read_b128 v[202:205], v132 offset:21504
	ds_read_b128 v[206:209], v132 offset:22528
	ds_read_b128 v[210:213], v132 offset:23552
	s_waitcnt vmcnt(4)
	s_barrier
	s_waitcnt lgkmcnt(0)
	s_waitcnt lgkmcnt(0)
	v_mfma_f32_16x16x32_f16 v[60:63], v[64:67], v[134:137], v[60:63]
	v_mfma_f32_16x16x32_f16 v[52:55], v[80:83], v[134:137], v[52:55]
	v_mfma_f32_16x16x32_f16 v[44:47], v[198:201], v[134:137], v[44:47]
	v_mfma_f32_16x16x32_f16 v[36:39], v[206:209], v[134:137], v[36:39]
	v_mfma_f32_16x16x32_f16 v[60:63], v[72:75], v[138:141], v[60:63]
	v_mfma_f32_16x16x32_f16 v[56:59], v[64:67], v[142:145], v[56:59]
	v_mfma_f32_16x16x32_f16 v[52:55], v[88:91], v[138:141], v[52:55]
	v_mfma_f32_16x16x32_f16 v[48:51], v[80:83], v[142:145], v[48:51]
	v_mfma_f32_16x16x32_f16 v[44:47], v[202:205], v[138:141], v[44:47]
	v_mfma_f32_16x16x32_f16 v[40:43], v[198:201], v[142:145], v[40:43]
	v_mfma_f32_16x16x32_f16 v[36:39], v[210:213], v[138:141], v[36:39]
	v_mfma_f32_16x16x32_f16 v[32:35], v[206:209], v[142:145], v[32:35]
	v_mfma_f32_16x16x32_f16 v[226:229], v[72:75], v[158:161], v[56:59]
	v_mfma_f32_16x16x32_f16 v[230:233], v[88:91], v[158:161], v[48:51]
	v_mfma_f32_16x16x32_f16 v[234:237], v[202:205], v[158:161], v[40:43]
	v_mfma_f32_16x16x32_f16 v[134:137], v[210:213], v[158:161], v[32:35]
	v_mfma_f32_16x16x32_f16 v[28:31], v[64:67], v[96:99], v[28:31]
	v_mfma_f32_16x16x32_f16 v[20:23], v[80:83], v[96:99], v[20:23]
	v_mfma_f32_16x16x32_f16 v[12:15], v[198:201], v[96:99], v[12:15]
	v_mfma_f32_16x16x32_f16 v[8:11], v[198:201], v[112:115], v[8:11]
	v_mfma_f32_16x16x32_f16 v[4:7], v[206:209], v[96:99], v[4:7]
	v_mfma_f32_16x16x32_f16 v[0:3], v[206:209], v[112:115], v[0:3]
	v_mfma_f32_16x16x32_f16 v[28:31], v[72:75], v[104:107], v[28:31]
	v_mfma_f32_16x16x32_f16 v[24:27], v[64:67], v[112:115], v[24:27]
	v_mfma_f32_16x16x32_f16 v[20:23], v[88:91], v[104:107], v[20:23]
	v_mfma_f32_16x16x32_f16 v[16:19], v[80:83], v[112:115], v[16:19]
	v_mfma_f32_16x16x32_f16 v[12:15], v[202:205], v[104:107], v[12:15]
	v_mfma_f32_16x16x32_f16 v[8:11], v[202:205], v[120:123], v[8:11]
	v_mfma_f32_16x16x32_f16 v[4:7], v[210:213], v[104:107], v[4:7]
	v_mfma_f32_16x16x32_f16 v[0:3], v[210:213], v[120:123], v[0:3]
	v_mfma_f32_16x16x32_f16 v[138:141], v[72:75], v[120:123], v[24:27]
	v_mfma_f32_16x16x32_f16 v[142:145], v[88:91], v[120:123], v[16:19]
	s_barrier
	s_nop 0
	ds_read_b128 v[16:19], v133 offset:32768
	ds_read_b128 v[24:27], v133 offset:33792
	ds_read_b128 v[158:161], v133 offset:34816
	ds_read_b128 v[198:201], v133 offset:35840
	ds_read_b128 v[32:35], v132 offset:32768
	ds_read_b128 v[40:43], v132 offset:33792
	ds_read_b128 v[48:51], v132 offset:34816
	ds_read_b128 v[56:59], v132 offset:35840
	ds_read_b128 v[64:67], v132 offset:36864
	ds_read_b128 v[202:205], v132 offset:37888
	ds_read_b128 v[206:209], v132 offset:38912
	ds_read_b128 v[210:213], v132 offset:39936
	s_waitcnt vmcnt(2)
	s_barrier
	s_waitcnt lgkmcnt(0)
	s_waitcnt lgkmcnt(0)
	v_mfma_f32_16x16x32_f16 v[72:75], v[32:35], v[16:19], v[124:127]
	v_mfma_f32_16x16x32_f16 v[120:123], v[40:43], v[24:27], v[72:75]
	v_mfma_f32_16x16x32_f16 v[72:75], v[32:35], v[158:161], v[146:149]
	v_mfma_f32_16x16x32_f16 v[124:127], v[40:43], v[198:201], v[72:75]
	v_mfma_f32_16x16x32_f16 v[72:75], v[48:51], v[16:19], v[116:119]
	v_mfma_f32_16x16x32_f16 v[112:115], v[56:59], v[24:27], v[72:75]
	v_mfma_f32_16x16x32_f16 v[72:75], v[48:51], v[158:161], v[214:217]
	v_mfma_f32_16x16x32_f16 v[116:119], v[56:59], v[198:201], v[72:75]
	v_mfma_f32_16x16x32_f16 v[72:75], v[64:67], v[16:19], v[108:111]
	v_mfma_f32_16x16x32_f16 v[104:107], v[202:205], v[24:27], v[72:75]
	v_mfma_f32_16x16x32_f16 v[72:75], v[64:67], v[158:161], v[218:221]
	v_mfma_f32_16x16x32_f16 v[108:111], v[202:205], v[198:201], v[72:75]
	v_mfma_f32_16x16x32_f16 v[72:75], v[206:209], v[16:19], v[100:103]
	v_mfma_f32_16x16x32_f16 v[96:99], v[210:213], v[24:27], v[72:75]
	v_mfma_f32_16x16x32_f16 v[72:75], v[206:209], v[158:161], v[222:225]
	v_mfma_f32_16x16x32_f16 v[100:103], v[210:213], v[198:201], v[72:75]
	s_barrier
;   #define LDA(dst,b,h) for(int m=0;m<4;++m)for(int k=0;k<2;++k) \
;     dst[m][k]=*reinterpret_cast<const h8*>(la+(((b)*2+(h))*16384+m*2048+k*1024))
;   #define LDB(dst,b,h) for(int n=0;n<2;++n)for(int k=0;k<2;++k) \
;     dst[n][k]=*reinterpret_cast<const h8*>(lb+(((b)*2+(h))*16384+n*2048+k*1024))
;   #define MMA(ai,bj,At,Bt_) do{__builtin_amdgcn_s_setprio(1); \
;     for(int m=0;m<4;++m)for(int n=0;n<2;++n)for(int k=0;k<2;++k) \
;       acc[ai][bj][m][n]=__builtin_amdgcn_mfma_f32_16x16x32_f16(At[m][k],Bt_[n][k],acc[ai][bj][m][n],0,0,0); \
;     __builtin_amdgcn_s_setprio(0);}while(0)
;   #define WAIT_V(n) asm volatile("s_waitcnt vmcnt(" #n ")":::"memory")
;   #define WAIT_L(n) asm volatile("s_waitcnt lgkmcnt(" #n ")":::"memory")
;   #define BAR __builtin_amdgcn_s_barrier()
;     ...
;   { LDB(B0,1,0); LDA(At,1,0); WAIT_V(2); BAR; WAIT_L(0); MMA(0,0,At,B0); BAR;
;     LDB(B1,1,1); WAIT_V(0); BAR; WAIT_L(0); MMA(0,1,At,B1); BAR;
;     LDA(At,1,1); BAR; WAIT_L(0); MMA(1,0,At,B0); MMA(1,1,At,B1); BAR; }
;   if(wr==0)BAR;
	ds_read_b128 v[146:149], v133 offset:49152
	ds_read_b128 v[214:217], v133 offset:50176
	ds_read_b128 v[218:221], v133 offset:51200
	ds_read_b128 v[222:225], v133 offset:52224
	s_waitcnt vmcnt(0)
	s_barrier
	s_waitcnt lgkmcnt(0)
	s_waitcnt lgkmcnt(0)
	v_mfma_f32_16x16x32_f16 v[72:75], v[32:35], v[146:149], v[92:95]
	v_mfma_f32_16x16x32_f16 v[32:35], v[32:35], v[218:221], v[162:165]
	v_mfma_f32_16x16x32_f16 v[92:95], v[40:43], v[222:225], v[32:35]
	v_mfma_f32_16x16x32_f16 v[32:35], v[48:51], v[146:149], v[84:87]
	v_mfma_f32_16x16x32_f16 v[80:83], v[56:59], v[214:217], v[32:35]
	v_mfma_f32_16x16x32_f16 v[32:35], v[48:51], v[218:221], v[186:189]
	v_mfma_f32_16x16x32_f16 v[84:87], v[56:59], v[222:225], v[32:35]
	v_mfma_f32_16x16x32_f16 v[32:35], v[64:67], v[146:149], v[76:79]
	v_mfma_f32_16x16x32_f16 v[88:91], v[40:43], v[214:217], v[72:75]
	v_mfma_f32_16x16x32_f16 v[72:75], v[202:205], v[214:217], v[32:35]
	v_mfma_f32_16x16x32_f16 v[32:35], v[64:67], v[218:221], v[190:193]
	v_mfma_f32_16x16x32_f16 v[76:79], v[202:205], v[222:225], v[32:35]
	v_mfma_f32_16x16x32_f16 v[32:35], v[206:209], v[146:149], v[68:71]
	v_mfma_f32_16x16x32_f16 v[64:67], v[210:213], v[214:217], v[32:35]
	v_mfma_f32_16x16x32_f16 v[32:35], v[206:209], v[218:221], v[194:197]
	v_mfma_f32_16x16x32_f16 v[68:71], v[210:213], v[222:225], v[32:35]
	s_barrier
	ds_read_b128 v[162:165], v132 offset:49152
	ds_read_b128 v[186:189], v132 offset:50176
	ds_read_b128 v[190:193], v132 offset:51200
	ds_read_b128 v[194:197], v132 offset:52224
	ds_read_b128 v[202:205], v132 offset:53248
	ds_read_b128 v[206:209], v132 offset:54272
	ds_read_b128 v[210:213], v132 offset:55296
	ds_read_b128 v[238:241], v132 offset:56320
	s_barrier
	s_waitcnt lgkmcnt(0)
	s_waitcnt lgkmcnt(0)
	v_mfma_f32_16x16x32_f16 v[32:35], v[162:165], v[16:19], v[60:63]
	v_mfma_f32_16x16x32_f16 v[56:59], v[186:189], v[24:27], v[32:35]
	v_mfma_f32_16x16x32_f16 v[32:35], v[162:165], v[158:161], v[226:229]
	v_mfma_f32_16x16x32_f16 v[60:63], v[186:189], v[198:201], v[32:35]
	v_mfma_f32_16x16x32_f16 v[32:35], v[190:193], v[16:19], v[52:55]
	v_mfma_f32_16x16x32_f16 v[48:51], v[194:197], v[24:27], v[32:35]
	v_mfma_f32_16x16x32_f16 v[32:35], v[190:193], v[158:161], v[230:233]
	v_mfma_f32_16x16x32_f16 v[52:55], v[194:197], v[198:201], v[32:35]
	v_mfma_f32_16x16x32_f16 v[32:35], v[202:205], v[16:19], v[44:47]
	v_mfma_f32_16x16x32_f16 v[40:43], v[206:209], v[24:27], v[32:35]
	v_mfma_f32_16x16x32_f16 v[32:35], v[202:205], v[158:161], v[234:237]
	v_mfma_f32_16x16x32_f16 v[16:19], v[210:213], v[16:19], v[36:39]
	v_mfma_f32_16x16x32_f16 v[44:47], v[206:209], v[198:201], v[32:35]
	v_mfma_f32_16x16x32_f16 v[32:35], v[238:241], v[24:27], v[16:19]
	v_mfma_f32_16x16x32_f16 v[16:19], v[210:213], v[158:161], v[134:137]
	v_mfma_f32_16x16x32_f16 v[36:39], v[238:241], v[198:201], v[16:19]
	v_mfma_f32_16x16x32_f16 v[16:19], v[162:165], v[146:149], v[28:31]
	v_mfma_f32_16x16x32_f16 v[24:27], v[186:189], v[214:217], v[16:19]
	v_mfma_f32_16x16x32_f16 v[16:19], v[162:165], v[218:221], v[138:141]
	v_mfma_f32_16x16x32_f16 v[28:31], v[186:189], v[222:225], v[16:19]
	v_mfma_f32_16x16x32_f16 v[16:19], v[190:193], v[146:149], v[20:23]
	v_mfma_f32_16x16x32_f16 v[20:23], v[190:193], v[218:221], v[142:145]
	v_mfma_f32_16x16x32_f16 v[12:15], v[202:205], v[146:149], v[12:15]
	v_mfma_f32_16x16x32_f16 v[8:11], v[202:205], v[218:221], v[8:11]
	v_mfma_f32_16x16x32_f16 v[4:7], v[210:213], v[146:149], v[4:7]
	v_mfma_f32_16x16x32_f16 v[0:3], v[210:213], v[218:221], v[0:3]
	v_mfma_f32_16x16x32_f16 v[16:19], v[194:197], v[214:217], v[16:19]
	v_mfma_f32_16x16x32_f16 v[20:23], v[194:197], v[222:225], v[20:23]
	v_mfma_f32_16x16x32_f16 v[12:15], v[206:209], v[214:217], v[12:15]
	v_mfma_f32_16x16x32_f16 v[8:11], v[206:209], v[222:225], v[8:11]
	v_mfma_f32_16x16x32_f16 v[4:7], v[238:241], v[214:217], v[4:7]
	v_mfma_f32_16x16x32_f16 v[0:3], v[238:241], v[222:225], v[0:3]
	s_movk_i32 s2, 0x100
	v_cmp_gt_u32_e32 vcc, s2, v131
	s_barrier
	s_and_saveexec_b64 s[2:3], vcc
	s_cbranch_execz .LBB0_196
	s_barrier

;   #define STAGE(P,BASE,LD,br,kt) do{ const HALF* _u=(BASE)+(long)(br)*(((&(LD))==&lda)?lda_u:(LD))+(long)(kt)*G_BK; \
;     for(int _i=0;_i<2;++_i){ \
;       __builtin_amdgcn_global_load_lds((const unsigned*)(_u+(long)_i*(((&(LD))==&lda)?stepa:stepb)+((&(LD))==&lda?oa0:ob0)), \
;         (unsigned*)((char*)(P)+t5*16+_i*8192),16,0,0);}}while(0)
;   #define LDA(dst,b,h) for(int m=0;m<4;++m)for(int k=0;k<2;++k) \
;     dst[m][k]=*reinterpret_cast<const h8*>(la+(((b)*2+(h))*16384+m*2048+k*1024))
;   #define LDB(dst,b,h) for(int n=0;n<2;++n)for(int k=0;k<2;++k) \
;     dst[n][k]=*reinterpret_cast<const h8*>(lb+(((b)*2+(h))*16384+n*2048+k*1024))
;   #define MMA(ai,bj,At,Bt_) do{__builtin_amdgcn_s_setprio(1); \
;     for(int m=0;m<4;++m)for(int n=0;n<2;++n)for(int k=0;k<2;++k) \
;       acc[ai][bj][m][n]=__builtin_amdgcn_mfma_f32_16x16x32_f16(At[m][k],Bt_[n][k],acc[ai][bj][m][n],0,0,0); \
;     __builtin_amdgcn_s_setprio(0);}while(0)
;   #define WAIT_L(n) asm volatile("s_waitcnt lgkmcnt(" #n ")":::"memory")
;   #define BAR __builtin_amdgcn_s_barrier()
;   #define SCHED __builtin_amdgcn_sched_barrier(0)
;     ...
;   for(int t=0;t<nt-2;t+=2){
;     LDB(B0,0,0); SCHED; LDA(At,0,0); STAGE(SA(1,1),A,lda,G_HALF,t+1);
;     WAIT_L(8); BAR; WAIT_L(0); MMA(0,0,At,B0); BAR; SCHED;
;     LDB(B1,0,1); STAGE(SB(0,0),Bt,ldb,0,t+2);
;     BAR; WAIT_L(0); MMA(0,1,At,B1); BAR;
;     LDA(At,0,1); STAGE(SA(0,0),A,lda,0,t+2);
;     BAR; WAIT_L(0); MMA(1,0,At,B0); BAR; SCHED;
.LBB0_209:
	ds_read_b128 v[158:161], v133
	ds_read_b128 v[162:165], v133 offset:1024
	ds_read_b128 v[186:189], v133 offset:2048
	ds_read_b128 v[190:193], v133 offset:3072
	v_add_u32_e32 v148, 0xc000, v136
	v_lshl_add_u64 v[150:151], v[128:129], 0, s[10:11]
	v_readfirstlane_b32 s13, v148
	v_add_u32_e32 v149, 0xe000, v136
	v_lshl_add_u64 v[166:167], v[150:151], 0, s[68:69]
	s_mov_b32 m0, s13
	v_readfirstlane_b32 s13, v149
	ds_read_b128 v[194:197], v132
	ds_read_b128 v[198:201], v132 offset:1024
	ds_read_b128 v[202:205], v132 offset:2048
	ds_read_b128 v[206:209], v132 offset:3072
	ds_read_b128 v[210:213], v132 offset:4096
	ds_read_b128 v[214:217], v132 offset:5120
	ds_read_b128 v[218:221], v132 offset:6144
	ds_read_b128 v[222:225], v132 offset:7168
	global_load_lds_dwordx4 v[166:167], off
	v_lshl_add_u64 v[166:167], v[150:151], 0, s[70:71]
	s_mov_b32 m0, s13
	s_nop 0
	global_load_lds_dwordx4 v[166:167], off
	s_waitcnt lgkmcnt(8)
	s_barrier
	s_waitcnt lgkmcnt(0)
	s_waitcnt lgkmcnt(0)
	v_mfma_f32_16x16x32_f16 v[124:127], v[194:197], v[158:161], v[124:127]
	v_mfma_f32_16x16x32_f16 v[120:123], v[194:197], v[186:189], v[120:123]
	v_mfma_f32_16x16x32_f16 v[116:119], v[202:205], v[158:161], v[116:119]
	v_mfma_f32_16x16x32_f16 v[112:115], v[202:205], v[186:189], v[112:115]
	v_mfma_f32_16x16x32_f16 v[108:111], v[210:213], v[158:161], v[108:111]
	v_mfma_f32_16x16x32_f16 v[104:107], v[210:213], v[186:189], v[104:107]
	v_mfma_f32_16x16x32_f16 v[100:103], v[218:221], v[158:161], v[100:103]
	v_mfma_f32_16x16x32_f16 v[96:99], v[218:221], v[186:189], v[96:99]
	v_mfma_f32_16x16x32_f16 v[124:127], v[198:201], v[162:165], v[124:127]
	v_mfma_f32_16x16x32_f16 v[120:123], v[198:201], v[190:193], v[120:123]
	v_mfma_f32_16x16x32_f16 v[116:119], v[206:209], v[162:165], v[116:119]
	v_mfma_f32_16x16x32_f16 v[112:115], v[206:209], v[190:193], v[112:115]
	v_mfma_f32_16x16x32_f16 v[108:111], v[214:217], v[162:165], v[108:111]
	v_mfma_f32_16x16x32_f16 v[104:107], v[214:217], v[190:193], v[104:107]
	v_mfma_f32_16x16x32_f16 v[100:103], v[222:225], v[162:165], v[100:103]
	v_mfma_f32_16x16x32_f16 v[96:99], v[222:225], v[190:193], v[96:99]
	s_barrier
	v_lshl_add_u64 v[166:167], v[128:129], 0, s[6:7]
	v_readfirstlane_b32 s13, v134
	v_lshl_add_u64 v[168:169], v[166:167], 0, s[92:93]
	s_mov_b32 m0, s13
	v_readfirstlane_b32 s13, v135
	ds_read_b128 v[226:229], v133 offset:16384
	ds_read_b128 v[230:233], v133 offset:17408
	ds_read_b128 v[234:237], v133 offset:18432
	ds_read_b128 v[238:241], v133 offset:19456
	global_load_lds_dwordx4 v[168:169], off
	v_lshl_add_u64 v[168:169], v[166:167], 0, s[66:67]
	s_mov_b32 m0, s13
	s_nop 0
	global_load_lds_dwordx4 v[168:169], off
	s_barrier
	s_waitcnt lgkmcnt(0)
	s_waitcnt lgkmcnt(0)
	v_mfma_f32_16x16x32_f16 v[92:95], v[194:197], v[226:229], v[92:95]
	v_mfma_f32_16x16x32_f16 v[88:91], v[194:197], v[234:237], v[88:91]
	v_mfma_f32_16x16x32_f16 v[84:87], v[202:205], v[226:229], v[84:87]
	v_mfma_f32_16x16x32_f16 v[80:83], v[202:205], v[234:237], v[80:83]
	v_mfma_f32_16x16x32_f16 v[76:79], v[210:213], v[226:229], v[76:79]
	v_mfma_f32_16x16x32_f16 v[72:75], v[210:213], v[234:237], v[72:75]
	v_mfma_f32_16x16x32_f16 v[68:71], v[218:221], v[226:229], v[68:71]
	v_mfma_f32_16x16x32_f16 v[64:67], v[218:221], v[234:237], v[64:67]
	v_mfma_f32_16x16x32_f16 v[92:95], v[198:201], v[230:233], v[92:95]
	v_mfma_f32_16x16x32_f16 v[88:91], v[198:201], v[238:241], v[88:91]
	v_mfma_f32_16x16x32_f16 v[84:87], v[206:209], v[230:233], v[84:87]
	v_mfma_f32_16x16x32_f16 v[80:83], v[206:209], v[238:241], v[80:83]
	v_mfma_f32_16x16x32_f16 v[76:79], v[214:217], v[230:233], v[76:79]
	v_mfma_f32_16x16x32_f16 v[72:75], v[214:217], v[238:241], v[72:75]
	v_mfma_f32_16x16x32_f16 v[68:71], v[222:225], v[230:233], v[68:71]
	v_mfma_f32_16x16x32_f16 v[64:67], v[222:225], v[238:241], v[64:67]
	v_readfirstlane_b32 s13, v136
	v_lshl_add_u64 v[168:169], v[150:151], 0, s[36:37]
	s_mov_b32 m0, s13
	v_readfirstlane_b32 s13, v137
	s_barrier
	ds_read_b128 v[194:197], v132 offset:16384
	ds_read_b128 v[198:201], v132 offset:17408
	ds_read_b128 v[202:205], v132 offset:18432
	ds_read_b128 v[206:209], v132 offset:19456
	ds_read_b128 v[210:213], v132 offset:20480
	ds_read_b128 v[214:217], v132 offset:21504
	ds_read_b128 v[218:221], v132 offset:22528
	ds_read_b128 v[222:225], v132 offset:23552
	global_load_lds_dwordx4 v[168:169], off
	v_lshl_add_u64 v[168:169], v[150:151], 0, s[54:55]
	s_mov_b32 m0, s13
	s_nop 0
	global_load_lds_dwordx4 v[168:169], off
	s_barrier
	s_waitcnt lgkmcnt(0)
	s_waitcnt lgkmcnt(0)
	v_mfma_f32_16x16x32_f16 v[60:63], v[194:197], v[158:161], v[60:63]
	v_mfma_f32_16x16x32_f16 v[56:59], v[194:197], v[186:189], v[56:59]
	v_mfma_f32_16x16x32_f16 v[52:55], v[202:205], v[158:161], v[52:55]
	v_mfma_f32_16x16x32_f16 v[48:51], v[202:205], v[186:189], v[48:51]
	v_mfma_f32_16x16x32_f16 v[44:47], v[210:213], v[158:161], v[44:47]
	v_mfma_f32_16x16x32_f16 v[40:43], v[210:213], v[186:189], v[40:43]
	v_mfma_f32_16x16x32_f16 v[36:39], v[218:221], v[158:161], v[36:39]
	v_mfma_f32_16x16x32_f16 v[32:35], v[218:221], v[186:189], v[32:35]
	v_mfma_f32_16x16x32_f16 v[60:63], v[198:201], v[162:165], v[60:63]
	v_mfma_f32_16x16x32_f16 v[56:59], v[198:201], v[190:193], v[56:59]
	v_mfma_f32_16x16x32_f16 v[52:55], v[206:209], v[162:165], v[52:55]
	v_mfma_f32_16x16x32_f16 v[48:51], v[206:209], v[190:193], v[48:51]
	v_mfma_f32_16x16x32_f16 v[44:47], v[214:217], v[162:165], v[44:47]
	v_mfma_f32_16x16x32_f16 v[40:43], v[214:217], v[190:193], v[40:43]
	v_mfma_f32_16x16x32_f16 v[36:39], v[222:225], v[162:165], v[36:39]
	v_mfma_f32_16x16x32_f16 v[32:35], v[222:225], v[190:193], v[32:35]
	s_barrier
;   #define STAGE(P,BASE,LD,br,kt) do{ const HALF* _u=(BASE)+(long)(br)*(((&(LD))==&lda)?lda_u:(LD))+(long)(kt)*G_BK; \
;     for(int _i=0;_i<2;++_i){ \
;       __builtin_amdgcn_global_load_lds((const unsigned*)(_u+(long)_i*(((&(LD))==&lda)?stepa:stepb)+((&(LD))==&lda?oa0:ob0)), \
;         (unsigned*)((char*)(P)+t5*16+_i*8192),16,0,0);}}while(0)
;   #define LDA(dst,b,h) for(int m=0;m<4;++m)for(int k=0;k<2;++k) \
;     dst[m][k]=*reinterpret_cast<const h8*>(la+(((b)*2+(h))*16384+m*2048+k*1024))
;   #define LDB(dst,b,h) for(int n=0;n<2;++n)for(int k=0;k<2;++k) \
;     dst[n][k]=*reinterpret_cast<const h8*>(lb+(((b)*2+(h))*16384+n*2048+k*1024))
;   #define MMA(ai,bj,At,Bt_) do{__builtin_amdgcn_s_setprio(1); \
;     for(int m=0;m<4;++m)for(int n=0;n<2;++n)for(int k=0;k<2;++k) \
;       acc[ai][bj][m][n]=__builtin_amdgcn_mfma_f32_16x16x32_f16(At[m][k],Bt_[n][k],acc[ai][bj][m][n],0,0,0); \
;     __builtin_amdgcn_s_setprio(0);}while(0)
;   #define WAIT_V(n) asm volatile("s_waitcnt vmcnt(" #n ")":::"memory")
;   #define WAIT_L(n) asm volatile("s_waitcnt lgkmcnt(" #n ")":::"memory")
;   #define BAR __builtin_amdgcn_s_barrier()
;   #define SCHED __builtin_amdgcn_sched_barrier(0)
;     ...
;     STAGE(SB(0,1),Bt,ldb,G_HALF,t+2);
;     WAIT_V(6); BAR; MMA(1,1,At,B1); BAR;
;     LDB(B0,1,0); SCHED; LDA(At,1,0); STAGE(SA(0,1),A,lda,G_HALF,t+2);
;     WAIT_L(8); BAR; WAIT_L(0); MMA(0,0,At,B0); BAR; SCHED;
;     LDB(B1,1,1); STAGE(SB(1,0),Bt,ldb,0,t+3);
;     BAR; WAIT_L(0); MMA(0,1,At,B1); BAR;
;     LDA(At,1,1); STAGE(SA(1,0),A,lda,0,t+3);
	v_readfirstlane_b32 s13, v138
	v_lshl_add_u64 v[158:159], v[166:167], 0, s[38:39]
	s_mov_b32 m0, s13
	v_readfirstlane_b32 s13, v139
	global_load_lds_dwordx4 v[158:159], off
	v_lshl_add_u64 v[158:159], v[166:167], 0, s[40:41]
	s_mov_b32 m0, s13
	s_nop 0
	global_load_lds_dwordx4 v[158:159], off
	s_waitcnt vmcnt(6)
	s_barrier
	v_mfma_f32_16x16x32_f16 v[28:31], v[194:197], v[226:229], v[28:31]
	v_mfma_f32_16x16x32_f16 v[24:27], v[194:197], v[234:237], v[24:27]
	v_mfma_f32_16x16x32_f16 v[20:23], v[202:205], v[226:229], v[20:23]
	v_mfma_f32_16x16x32_f16 v[16:19], v[202:205], v[234:237], v[16:19]
	v_mfma_f32_16x16x32_f16 v[12:15], v[210:213], v[226:229], v[12:15]
	v_mfma_f32_16x16x32_f16 v[8:11], v[210:213], v[234:237], v[8:11]
	v_mfma_f32_16x16x32_f16 v[4:7], v[218:221], v[226:229], v[4:7]
	v_mfma_f32_16x16x32_f16 v[0:3], v[218:221], v[234:237], v[0:3]
	v_mfma_f32_16x16x32_f16 v[28:31], v[198:201], v[230:233], v[28:31]
	v_mfma_f32_16x16x32_f16 v[24:27], v[198:201], v[238:241], v[24:27]
	v_mfma_f32_16x16x32_f16 v[20:23], v[206:209], v[230:233], v[20:23]
	v_mfma_f32_16x16x32_f16 v[16:19], v[206:209], v[238:241], v[16:19]
	v_mfma_f32_16x16x32_f16 v[12:15], v[214:217], v[230:233], v[12:15]
	v_mfma_f32_16x16x32_f16 v[8:11], v[214:217], v[238:241], v[8:11]
	v_mfma_f32_16x16x32_f16 v[4:7], v[222:225], v[230:233], v[4:7]
	v_mfma_f32_16x16x32_f16 v[0:3], v[222:225], v[238:241], v[0:3]
	s_barrier
	ds_read_b128 v[158:161], v133 offset:32768
	ds_read_b128 v[162:165], v133 offset:33792
	ds_read_b128 v[186:189], v133 offset:34816
	ds_read_b128 v[190:193], v133 offset:35840
	v_readfirstlane_b32 s13, v140
	v_lshl_add_u64 v[168:169], v[150:151], 0, s[24:25]
	s_mov_b32 m0, s13
	v_readfirstlane_b32 s13, v141
	ds_read_b128 v[194:197], v132 offset:32768
	ds_read_b128 v[198:201], v132 offset:33792
	ds_read_b128 v[202:205], v132 offset:34816
	ds_read_b128 v[206:209], v132 offset:35840
	ds_read_b128 v[210:213], v132 offset:36864
	ds_read_b128 v[214:217], v132 offset:37888
	ds_read_b128 v[218:221], v132 offset:38912
	ds_read_b128 v[222:225], v132 offset:39936
	global_load_lds_dwordx4 v[168:169], off
	v_lshl_add_u64 v[168:169], v[150:151], 0, s[48:49]
	s_mov_b32 m0, s13
	s_nop 0
	global_load_lds_dwordx4 v[168:169], off
	s_waitcnt lgkmcnt(8)
	s_barrier
	s_waitcnt lgkmcnt(0)
	s_waitcnt lgkmcnt(0)
	v_mfma_f32_16x16x32_f16 v[124:127], v[194:197], v[158:161], v[124:127]
	v_mfma_f32_16x16x32_f16 v[120:123], v[194:197], v[186:189], v[120:123]
	v_mfma_f32_16x16x32_f16 v[116:119], v[202:205], v[158:161], v[116:119]
	v_mfma_f32_16x16x32_f16 v[112:115], v[202:205], v[186:189], v[112:115]
	v_mfma_f32_16x16x32_f16 v[108:111], v[210:213], v[158:161], v[108:111]
	v_mfma_f32_16x16x32_f16 v[104:107], v[210:213], v[186:189], v[104:107]
	v_mfma_f32_16x16x32_f16 v[100:103], v[218:221], v[158:161], v[100:103]
	v_mfma_f32_16x16x32_f16 v[96:99], v[218:221], v[186:189], v[96:99]
	v_mfma_f32_16x16x32_f16 v[124:127], v[198:201], v[162:165], v[124:127]
	v_mfma_f32_16x16x32_f16 v[120:123], v[198:201], v[190:193], v[120:123]
	v_mfma_f32_16x16x32_f16 v[116:119], v[206:209], v[162:165], v[116:119]
	v_mfma_f32_16x16x32_f16 v[112:115], v[206:209], v[190:193], v[112:115]
	v_mfma_f32_16x16x32_f16 v[108:111], v[214:217], v[162:165], v[108:111]
	v_mfma_f32_16x16x32_f16 v[104:107], v[214:217], v[190:193], v[104:107]
	v_mfma_f32_16x16x32_f16 v[100:103], v[222:225], v[162:165], v[100:103]
	v_mfma_f32_16x16x32_f16 v[96:99], v[222:225], v[190:193], v[96:99]
	s_barrier
	v_readfirstlane_b32 s13, v142
	v_lshl_add_u64 v[168:169], v[166:167], 0, s[42:43]
	s_mov_b32 m0, s13
	v_readfirstlane_b32 s13, v143
	ds_read_b128 v[226:229], v133 offset:49152
	ds_read_b128 v[230:233], v133 offset:50176
	ds_read_b128 v[234:237], v133 offset:51200
	ds_read_b128 v[238:241], v133 offset:52224
	global_load_lds_dwordx4 v[168:169], off
	v_lshl_add_u64 v[168:169], v[166:167], 0, s[96:97]
	s_mov_b32 m0, s13
	s_nop 0
	global_load_lds_dwordx4 v[168:169], off
	s_barrier
	s_waitcnt lgkmcnt(0)
	s_waitcnt lgkmcnt(0)
	v_mfma_f32_16x16x32_f16 v[92:95], v[194:197], v[226:229], v[92:95]
	v_mfma_f32_16x16x32_f16 v[88:91], v[194:197], v[234:237], v[88:91]
	v_mfma_f32_16x16x32_f16 v[84:87], v[202:205], v[226:229], v[84:87]
	v_mfma_f32_16x16x32_f16 v[80:83], v[202:205], v[234:237], v[80:83]
	v_mfma_f32_16x16x32_f16 v[76:79], v[210:213], v[226:229], v[76:79]
	v_mfma_f32_16x16x32_f16 v[72:75], v[210:213], v[234:237], v[72:75]
	v_mfma_f32_16x16x32_f16 v[68:71], v[218:221], v[226:229], v[68:71]
	v_mfma_f32_16x16x32_f16 v[64:67], v[218:221], v[234:237], v[64:67]
	v_mfma_f32_16x16x32_f16 v[92:95], v[198:201], v[230:233], v[92:95]
	v_mfma_f32_16x16x32_f16 v[88:91], v[198:201], v[238:241], v[88:91]
	v_mfma_f32_16x16x32_f16 v[84:87], v[206:209], v[230:233], v[84:87]
	v_mfma_f32_16x16x32_f16 v[80:83], v[206:209], v[238:241], v[80:83]
	v_mfma_f32_16x16x32_f16 v[76:79], v[214:217], v[230:233], v[76:79]
	v_mfma_f32_16x16x32_f16 v[72:75], v[214:217], v[238:241], v[72:75]
	v_mfma_f32_16x16x32_f16 v[68:71], v[222:225], v[230:233], v[68:71]
	v_mfma_f32_16x16x32_f16 v[64:67], v[222:225], v[238:241], v[64:67]
	v_readfirstlane_b32 s13, v144
	v_lshl_add_u64 v[168:169], v[150:151], 0, s[60:61]
	s_mov_b32 m0, s13
	v_readfirstlane_b32 s13, v145
	s_barrier
	ds_read_b128 v[194:197], v132 offset:49152
	ds_read_b128 v[198:201], v132 offset:50176
	ds_read_b128 v[202:205], v132 offset:51200
	ds_read_b128 v[206:209], v132 offset:52224
	ds_read_b128 v[210:213], v132 offset:53248
	ds_read_b128 v[214:217], v132 offset:54272
	ds_read_b128 v[218:221], v132 offset:55296
	ds_read_b128 v[222:225], v132 offset:56320
	global_load_lds_dwordx4 v[168:169], off
	v_lshl_add_u64 v[150:151], v[150:151], 0, s[26:27]
	s_mov_b32 m0, s13
	s_nop 0
	global_load_lds_dwordx4 v[150:151], off
	s_barrier
;   #define STAGE(P,BASE,LD,br,kt) do{ const HALF* _u=(BASE)+(long)(br)*(((&(LD))==&lda)?lda_u:(LD))+(long)(kt)*G_BK; \
;     for(int _i=0;_i<2;++_i){ \
;       __builtin_amdgcn_global_load_lds((const unsigned*)(_u+(long)_i*(((&(LD))==&lda)?stepa:stepb)+((&(LD))==&lda?oa0:ob0)), \
;         (unsigned*)((char*)(P)+t5*16+_i*8192),16,0,0);}}while(0)
;   #define LDA(dst,b,h) for(int m=0;m<4;++m)for(int k=0;k<2;++k) \
;     dst[m][k]=*reinterpret_cast<const h8*>(la+(((b)*2+(h))*16384+m*2048+k*1024))
;   #define LDB(dst,b,h) for(int n=0;n<2;++n)for(int k=0;k<2;++k) \
;     dst[n][k]=*reinterpret_cast<const h8*>(lb+(((b)*2+(h))*16384+n*2048+k*1024))
;   #define MMA(ai,bj,At,Bt_) do{__builtin_amdgcn_s_setprio(1); \
;     for(int m=0;m<4;++m)for(int n=0;n<2;++n)for(int k=0;k<2;++k) \
;       acc[ai][bj][m][n]=__builtin_amdgcn_mfma_f32_16x16x32_f16(At[m][k],Bt_[n][k],acc[ai][bj][m][n],0,0,0); \
;     __builtin_amdgcn_s_setprio(0);}while(0)
;   #define WAIT_V(n) asm volatile("s_waitcnt vmcnt(" #n ")":::"memory")
;   #define WAIT_L(n) asm volatile("s_waitcnt lgkmcnt(" #n ")":::"memory")
;   #define BAR __builtin_amdgcn_s_barrier()
;   #define SCHED __builtin_amdgcn_sched_barrier(0)
;     ...
;     LDA(At,1,1); STAGE(SA(1,0),A,lda,0,t+3);
;     BAR; WAIT_L(0); MMA(1,0,At,B0); BAR; SCHED;
;     STAGE(SB(1,1),Bt,ldb,G_HALF,t+3);
;     WAIT_V(6); BAR; MMA(1,1,At,B1); BAR;
;   }
;   { LDB(B0,0,0); LDA(At,0,0); STAGE(SA(1,1),A,lda,G_HALF,nt-1);
;     BAR; WAIT_L(0); MMA(0,0,At,B0); BAR;
;     LDB(B1,0,1); BAR; WAIT_L(0); MMA(0,1,At,B1); BAR;
	s_waitcnt lgkmcnt(0)
	s_waitcnt lgkmcnt(0)
	v_mfma_f32_16x16x32_f16 v[60:63], v[194:197], v[158:161], v[60:63]
	v_mfma_f32_16x16x32_f16 v[56:59], v[194:197], v[186:189], v[56:59]
	v_mfma_f32_16x16x32_f16 v[52:55], v[202:205], v[158:161], v[52:55]
	v_mfma_f32_16x16x32_f16 v[48:51], v[202:205], v[186:189], v[48:51]
	v_mfma_f32_16x16x32_f16 v[44:47], v[210:213], v[158:161], v[44:47]
	v_mfma_f32_16x16x32_f16 v[40:43], v[210:213], v[186:189], v[40:43]
	v_mfma_f32_16x16x32_f16 v[36:39], v[218:221], v[158:161], v[36:39]
	v_mfma_f32_16x16x32_f16 v[32:35], v[218:221], v[186:189], v[32:35]
	v_mfma_f32_16x16x32_f16 v[60:63], v[198:201], v[162:165], v[60:63]
	v_mfma_f32_16x16x32_f16 v[56:59], v[198:201], v[190:193], v[56:59]
	v_mfma_f32_16x16x32_f16 v[52:55], v[206:209], v[162:165], v[52:55]
	v_mfma_f32_16x16x32_f16 v[48:51], v[206:209], v[190:193], v[48:51]
	v_mfma_f32_16x16x32_f16 v[44:47], v[214:217], v[162:165], v[44:47]
	v_mfma_f32_16x16x32_f16 v[40:43], v[214:217], v[190:193], v[40:43]
	v_mfma_f32_16x16x32_f16 v[36:39], v[222:225], v[162:165], v[36:39]
	v_mfma_f32_16x16x32_f16 v[32:35], v[222:225], v[190:193], v[32:35]
	s_barrier
	v_readfirstlane_b32 s13, v146
	v_lshl_add_u64 v[150:151], v[166:167], 0, s[14:15]
	s_mov_b32 m0, s13
	v_readfirstlane_b32 s13, v147
	global_load_lds_dwordx4 v[150:151], off
	v_lshl_add_u64 v[150:151], v[166:167], 0, s[58:59]
	s_mov_b32 m0, s13
	s_nop 0
	global_load_lds_dwordx4 v[150:151], off
	s_waitcnt vmcnt(6)
	s_barrier
	v_mfma_f32_16x16x32_f16 v[28:31], v[194:197], v[226:229], v[28:31]
	v_mfma_f32_16x16x32_f16 v[24:27], v[194:197], v[234:237], v[24:27]
	v_mfma_f32_16x16x32_f16 v[20:23], v[202:205], v[226:229], v[20:23]
	v_mfma_f32_16x16x32_f16 v[16:19], v[202:205], v[234:237], v[16:19]
	v_mfma_f32_16x16x32_f16 v[12:15], v[210:213], v[226:229], v[12:15]
	v_mfma_f32_16x16x32_f16 v[8:11], v[210:213], v[234:237], v[8:11]
	v_mfma_f32_16x16x32_f16 v[4:7], v[218:221], v[226:229], v[4:7]
	v_mfma_f32_16x16x32_f16 v[0:3], v[218:221], v[234:237], v[0:3]
	v_mfma_f32_16x16x32_f16 v[28:31], v[198:201], v[230:233], v[28:31]
	v_mfma_f32_16x16x32_f16 v[24:27], v[198:201], v[238:241], v[24:27]
	v_mfma_f32_16x16x32_f16 v[20:23], v[206:209], v[230:233], v[20:23]
	v_mfma_f32_16x16x32_f16 v[16:19], v[206:209], v[238:241], v[16:19]
	v_mfma_f32_16x16x32_f16 v[12:15], v[214:217], v[230:233], v[12:15]
	v_mfma_f32_16x16x32_f16 v[8:11], v[214:217], v[238:241], v[8:11]
	v_mfma_f32_16x16x32_f16 v[4:7], v[222:225], v[230:233], v[4:7]
	v_mfma_f32_16x16x32_f16 v[0:3], v[222:225], v[238:241], v[0:3]
	s_add_i32 s12, s12, 2
	s_cmp_lt_u32 s12, 12
	v_lshl_add_u64 v[128:129], v[128:129], 0, s[92:93]
	s_barrier
	s_cbranch_scc1 .LBB0_209
	v_lshl_add_u64 v[128:129], v[152:153], 1, s[2:3]
	s_mov_b64 s[2:3], 0x40780
	v_lshl_add_u64 v[146:147], v[128:129], 0, s[2:3]
	v_readfirstlane_b32 s2, v148
	s_mov_b32 m0, s2
	s_mov_b64 s[2:3], 0x60780
	v_lshl_add_u64 v[128:129], v[128:129], 0, s[2:3]
	v_readfirstlane_b32 s2, v149
	ds_read_b128 v[134:137], v133
	ds_read_b128 v[138:141], v133 offset:1024
	ds_read_b128 v[142:145], v133 offset:2048
	ds_read_b128 v[158:161], v133 offset:3072
	ds_read_b128 v[162:165], v132
	ds_read_b128 v[186:189], v132 offset:1024
	ds_read_b128 v[190:193], v132 offset:2048
	ds_read_b128 v[194:197], v132 offset:3072
	ds_read_b128 v[198:201], v132 offset:4096
	ds_read_b128 v[202:205], v132 offset:5120
	ds_read_b128 v[206:209], v132 offset:6144
	ds_read_b128 v[210:213], v132 offset:7168
	global_load_lds_dwordx4 v[146:147], off
	s_mov_b32 m0, s2
	s_nop 0
	global_load_lds_dwordx4 v[128:129], off
	s_barrier
	s_waitcnt lgkmcnt(0)
	s_waitcnt lgkmcnt(0)
	v_mfma_f32_16x16x32_f16 v[124:127], v[162:165], v[134:137], v[124:127]
	v_mfma_f32_16x16x32_f16 v[116:119], v[190:193], v[134:137], v[116:119]
	v_mfma_f32_16x16x32_f16 v[108:111], v[198:201], v[134:137], v[108:111]
	v_mfma_f32_16x16x32_f16 v[100:103], v[206:209], v[134:137], v[100:103]
	v_mfma_f32_16x16x32_f16 v[124:127], v[186:189], v[138:141], v[124:127]
	v_mfma_f32_16x16x32_f16 v[120:123], v[162:165], v[142:145], v[120:123]
	v_mfma_f32_16x16x32_f16 v[116:119], v[194:197], v[138:141], v[116:119]
	v_mfma_f32_16x16x32_f16 v[112:115], v[190:193], v[142:145], v[112:115]
	v_mfma_f32_16x16x32_f16 v[108:111], v[202:205], v[138:141], v[108:111]
	v_mfma_f32_16x16x32_f16 v[104:107], v[198:201], v[142:145], v[104:107]
	v_mfma_f32_16x16x32_f16 v[100:103], v[210:213], v[138:141], v[100:103]
	v_mfma_f32_16x16x32_f16 v[96:99], v[206:209], v[142:145], v[96:99]
	v_mfma_f32_16x16x32_f16 v[146:149], v[186:189], v[158:161], v[120:123]
	v_mfma_f32_16x16x32_f16 v[214:217], v[194:197], v[158:161], v[112:115]
	v_mfma_f32_16x16x32_f16 v[218:221], v[202:205], v[158:161], v[104:107]
	v_mfma_f32_16x16x32_f16 v[222:225], v[210:213], v[158:161], v[96:99]
	s_barrier
	s_nop 1
	ds_read_b128 v[96:99], v133 offset:16384
	ds_read_b128 v[104:107], v133 offset:17408
	ds_read_b128 v[112:115], v133 offset:18432
	ds_read_b128 v[120:123], v133 offset:19456
	s_barrier
	s_waitcnt lgkmcnt(0)
	s_waitcnt lgkmcnt(0)
	v_mfma_f32_16x16x32_f16 v[92:95], v[162:165], v[96:99], v[92:95]
	v_mfma_f32_16x16x32_f16 v[84:87], v[190:193], v[96:99], v[84:87]
	v_mfma_f32_16x16x32_f16 v[76:79], v[198:201], v[96:99], v[76:79]
	v_mfma_f32_16x16x32_f16 v[68:71], v[206:209], v[96:99], v[68:71]
	v_mfma_f32_16x16x32_f16 v[92:95], v[186:189], v[104:107], v[92:95]
	v_mfma_f32_16x16x32_f16 v[88:91], v[162:165], v[112:115], v[88:91]
	v_mfma_f32_16x16x32_f16 v[84:87], v[194:197], v[104:107], v[84:87]
	v_mfma_f32_16x16x32_f16 v[80:83], v[190:193], v[112:115], v[80:83]
	v_mfma_f32_16x16x32_f16 v[76:79], v[202:205], v[104:107], v[76:79]
	v_mfma_f32_16x16x32_f16 v[72:75], v[198:201], v[112:115], v[72:75]
	v_mfma_f32_16x16x32_f16 v[68:71], v[210:213], v[104:107], v[68:71]
	v_mfma_f32_16x16x32_f16 v[64:67], v[206:209], v[112:115], v[64:67]
	v_mfma_f32_16x16x32_f16 v[162:165], v[186:189], v[120:123], v[88:91]
	v_mfma_f32_16x16x32_f16 v[186:189], v[194:197], v[120:123], v[80:83]
	v_mfma_f32_16x16x32_f16 v[190:193], v[202:205], v[120:123], v[72:75]
	v_mfma_f32_16x16x32_f16 v[194:197], v[210:213], v[120:123], v[64:67]
	s_barrier
;   #define LDA(dst,b,h) for(int m=0;m<4;++m)for(int k=0;k<2;++k) \
;     dst[m][k]=*reinterpret_cast<const h8*>(la+(((b)*2+(h))*16384+m*2048+k*1024))
;   #define LDB(dst,b,h) for(int n=0;n<2;++n)for(int k=0;k<2;++k) \
;     dst[n][k]=*reinterpret_cast<const h8*>(lb+(((b)*2+(h))*16384+n*2048+k*1024))
;   #define MMA(ai,bj,At,Bt_) do{__builtin_amdgcn_s_setprio(1); \
;     for(int m=0;m<4;++m)for(int n=0;n<2;++n)for(int k=0;k<2;++k) \
;       acc[ai][bj][m][n]=__builtin_amdgcn_mfma_f32_16x16x32_f16(At[m][k],Bt_[n][k],acc[ai][bj][m][n],0,0,0); \
;     __builtin_amdgcn_s_setprio(0);}while(0)
;   #define WAIT_V(n) asm volatile("s_waitcnt vmcnt(" #n ")":::"memory")
;   #define WAIT_L(n) asm volatile("s_waitcnt lgkmcnt(" #n ")":::"memory")
;   #define BAR __builtin_amdgcn_s_barrier()
;     ...
;     LDB(B1,0,1); BAR; WAIT_L(0); MMA(0,1,At,B1); BAR;
;     LDA(At,0,1); WAIT_V(4); BAR; WAIT_L(0); MMA(1,0,At,B0); MMA(1,1,At,B1); BAR; }
;   { LDB(B0,1,0); LDA(At,1,0); WAIT_V(2); BAR; WAIT_L(0); MMA(0,0,At,B0); BAR;
	s_nop 1
	ds_read_b128 v[64:67], v132 offset:16384
	ds_read_b128 v[72:75], v132 offset:17408
	ds_read_b128 v[80:83], v132 offset:18432
	ds_read_b128 v[88:91], v132 offset:19456
	ds_read_b128 v[198:201], v132 offset:20480
	ds_read_b128 v[202:205], v132 offset:21504
	ds_read_b128 v[206:209], v132 offset:22528
	ds_read_b128 v[210:213], v132 offset:23552
	s_waitcnt vmcnt(4)
	s_barrier
	s_waitcnt lgkmcnt(0)
	s_waitcnt lgkmcnt(0)
	v_mfma_f32_16x16x32_f16 v[60:63], v[64:67], v[134:137], v[60:63]
	v_mfma_f32_16x16x32_f16 v[52:55], v[80:83], v[134:137], v[52:55]
	v_mfma_f32_16x16x32_f16 v[44:47], v[198:201], v[134:137], v[44:47]
	v_mfma_f32_16x16x32_f16 v[36:39], v[206:209], v[134:137], v[36:39]
	v_mfma_f32_16x16x32_f16 v[60:63], v[72:75], v[138:141], v[60:63]
	v_mfma_f32_16x16x32_f16 v[56:59], v[64:67], v[142:145], v[56:59]
	v_mfma_f32_16x16x32_f16 v[52:55], v[88:91], v[138:141], v[52:55]
	v_mfma_f32_16x16x32_f16 v[48:51], v[80:83], v[142:145], v[48:51]
	v_mfma_f32_16x16x32_f16 v[44:47], v[202:205], v[138:141], v[44:47]
	v_mfma_f32_16x16x32_f16 v[40:43], v[198:201], v[142:145], v[40:43]
	v_mfma_f32_16x16x32_f16 v[36:39], v[210:213], v[138:141], v[36:39]
	v_mfma_f32_16x16x32_f16 v[32:35], v[206:209], v[142:145], v[32:35]
	v_mfma_f32_16x16x32_f16 v[226:229], v[72:75], v[158:161], v[56:59]
	v_mfma_f32_16x16x32_f16 v[230:233], v[88:91], v[158:161], v[48:51]
	v_mfma_f32_16x16x32_f16 v[234:237], v[202:205], v[158:161], v[40:43]
	v_mfma_f32_16x16x32_f16 v[134:137], v[210:213], v[158:161], v[32:35]
	v_mfma_f32_16x16x32_f16 v[28:31], v[64:67], v[96:99], v[28:31]
	v_mfma_f32_16x16x32_f16 v[20:23], v[80:83], v[96:99], v[20:23]
	v_mfma_f32_16x16x32_f16 v[12:15], v[198:201], v[96:99], v[12:15]
	v_mfma_f32_16x16x32_f16 v[4:7], v[206:209], v[96:99], v[4:7]
	v_mfma_f32_16x16x32_f16 v[28:31], v[72:75], v[104:107], v[28:31]
	v_mfma_f32_16x16x32_f16 v[24:27], v[64:67], v[112:115], v[24:27]
	v_mfma_f32_16x16x32_f16 v[20:23], v[88:91], v[104:107], v[20:23]
	v_mfma_f32_16x16x32_f16 v[16:19], v[80:83], v[112:115], v[16:19]
	v_mfma_f32_16x16x32_f16 v[12:15], v[202:205], v[104:107], v[12:15]
	v_mfma_f32_16x16x32_f16 v[8:11], v[198:201], v[112:115], v[8:11]
	v_mfma_f32_16x16x32_f16 v[4:7], v[210:213], v[104:107], v[4:7]
	v_mfma_f32_16x16x32_f16 v[0:3], v[206:209], v[112:115], v[0:3]
	v_mfma_f32_16x16x32_f16 v[138:141], v[72:75], v[120:123], v[24:27]
	v_mfma_f32_16x16x32_f16 v[142:145], v[88:91], v[120:123], v[16:19]
	v_mfma_f32_16x16x32_f16 v[158:161], v[202:205], v[120:123], v[8:11]
	v_mfma_f32_16x16x32_f16 v[198:201], v[210:213], v[120:123], v[0:3]
	s_barrier
	s_nop 1
	ds_read_b128 v[0:3], v133 offset:32768
	ds_read_b128 v[8:11], v133 offset:33792
	ds_read_b128 v[16:19], v133 offset:34816
	ds_read_b128 v[24:27], v133 offset:35840
	ds_read_b128 v[32:35], v132 offset:32768
	ds_read_b128 v[40:43], v132 offset:33792
	ds_read_b128 v[48:51], v132 offset:34816
	ds_read_b128 v[56:59], v132 offset:35840
	ds_read_b128 v[64:67], v132 offset:36864
	ds_read_b128 v[202:205], v132 offset:37888
	ds_read_b128 v[206:209], v132 offset:38912
	ds_read_b128 v[210:213], v132 offset:39936
	s_waitcnt vmcnt(2)
	s_barrier
	s_waitcnt lgkmcnt(0)
	s_waitcnt lgkmcnt(0)
	v_mfma_f32_16x16x32_f16 v[72:75], v[32:35], v[0:3], v[124:127]
	v_mfma_f32_16x16x32_f16 v[120:123], v[40:43], v[8:11], v[72:75]
	v_mfma_f32_16x16x32_f16 v[72:75], v[32:35], v[16:19], v[146:149]
	v_mfma_f32_16x16x32_f16 v[124:127], v[40:43], v[24:27], v[72:75]
	v_mfma_f32_16x16x32_f16 v[72:75], v[48:51], v[0:3], v[116:119]
	v_mfma_f32_16x16x32_f16 v[112:115], v[56:59], v[8:11], v[72:75]
	v_mfma_f32_16x16x32_f16 v[72:75], v[48:51], v[16:19], v[214:217]
	v_mfma_f32_16x16x32_f16 v[116:119], v[56:59], v[24:27], v[72:75]
	v_mfma_f32_16x16x32_f16 v[72:75], v[64:67], v[0:3], v[108:111]
	v_mfma_f32_16x16x32_f16 v[104:107], v[202:205], v[8:11], v[72:75]
	v_mfma_f32_16x16x32_f16 v[72:75], v[64:67], v[16:19], v[218:221]
	v_mfma_f32_16x16x32_f16 v[108:111], v[202:205], v[24:27], v[72:75]
	v_mfma_f32_16x16x32_f16 v[72:75], v[206:209], v[0:3], v[100:103]
	v_mfma_f32_16x16x32_f16 v[96:99], v[210:213], v[8:11], v[72:75]
	v_mfma_f32_16x16x32_f16 v[72:75], v[206:209], v[16:19], v[222:225]
	v_mfma_f32_16x16x32_f16 v[100:103], v[210:213], v[24:27], v[72:75]
	s_barrier
;   #define LDA(dst,b,h) for(int m=0;m<4;++m)for(int k=0;k<2;++k) \
;     dst[m][k]=*reinterpret_cast<const h8*>(la+(((b)*2+(h))*16384+m*2048+k*1024))
;   #define LDB(dst,b,h) for(int n=0;n<2;++n)for(int k=0;k<2;++k) \
;     dst[n][k]=*reinterpret_cast<const h8*>(lb+(((b)*2+(h))*16384+n*2048+k*1024))
;   #define MMA(ai,bj,At,Bt_) do{__builtin_amdgcn_s_setprio(1); \
;     for(int m=0;m<4;++m)for(int n=0;n<2;++n)for(int k=0;k<2;++k) \
;       acc[ai][bj][m][n]=__builtin_amdgcn_mfma_f32_16x16x32_f16(At[m][k],Bt_[n][k],acc[ai][bj][m][n],0,0,0); \
;     __builtin_amdgcn_s_setprio(0);}while(0)
;   #define WAIT_V(n) asm volatile("s_waitcnt vmcnt(" #n ")":::"memory")
;   #define WAIT_L(n) asm volatile("s_waitcnt lgkmcnt(" #n ")":::"memory")
;   #define BAR __builtin_amdgcn_s_barrier()
;     ...
;   { LDB(B0,1,0); LDA(At,1,0); WAIT_V(2); BAR; WAIT_L(0); MMA(0,0,At,B0); BAR;
;     LDB(B1,1,1); WAIT_V(0); BAR; WAIT_L(0); MMA(0,1,At,B1); BAR;
;     LDA(At,1,1); BAR; WAIT_L(0); MMA(1,0,At,B0); MMA(1,1,At,B1); BAR; }
;   if(wr==0)BAR;
	ds_read_b128 v[146:149], v133 offset:49152
	ds_read_b128 v[214:217], v133 offset:50176
	ds_read_b128 v[218:221], v133 offset:51200
	ds_read_b128 v[222:225], v133 offset:52224
	s_waitcnt vmcnt(0)
	s_barrier
	s_waitcnt lgkmcnt(0)
	s_waitcnt lgkmcnt(0)
	v_mfma_f32_16x16x32_f16 v[72:75], v[32:35], v[146:149], v[92:95]
	v_mfma_f32_16x16x32_f16 v[32:35], v[32:35], v[218:221], v[162:165]
	v_mfma_f32_16x16x32_f16 v[92:95], v[40:43], v[222:225], v[32:35]
	v_mfma_f32_16x16x32_f16 v[32:35], v[48:51], v[146:149], v[84:87]
	v_mfma_f32_16x16x32_f16 v[80:83], v[56:59], v[214:217], v[32:35]
	v_mfma_f32_16x16x32_f16 v[32:35], v[48:51], v[218:221], v[186:189]
	v_mfma_f32_16x16x32_f16 v[84:87], v[56:59], v[222:225], v[32:35]
	v_mfma_f32_16x16x32_f16 v[32:35], v[64:67], v[146:149], v[76:79]
	v_mfma_f32_16x16x32_f16 v[88:91], v[40:43], v[214:217], v[72:75]
	v_mfma_f32_16x16x32_f16 v[72:75], v[202:205], v[214:217], v[32:35]
	v_mfma_f32_16x16x32_f16 v[32:35], v[64:67], v[218:221], v[190:193]
	v_mfma_f32_16x16x32_f16 v[76:79], v[202:205], v[222:225], v[32:35]
	v_mfma_f32_16x16x32_f16 v[32:35], v[206:209], v[146:149], v[68:71]
	v_mfma_f32_16x16x32_f16 v[64:67], v[210:213], v[214:217], v[32:35]
	v_mfma_f32_16x16x32_f16 v[32:35], v[206:209], v[218:221], v[194:197]
	v_mfma_f32_16x16x32_f16 v[68:71], v[210:213], v[222:225], v[32:35]
	s_barrier
	ds_read_b128 v[162:165], v132 offset:49152
	ds_read_b128 v[186:189], v132 offset:50176
	ds_read_b128 v[190:193], v132 offset:51200
	ds_read_b128 v[194:197], v132 offset:52224
	ds_read_b128 v[202:205], v132 offset:53248
	ds_read_b128 v[206:209], v132 offset:54272
	ds_read_b128 v[210:213], v132 offset:55296
	ds_read_b128 v[238:241], v132 offset:56320
	s_barrier
	s_waitcnt lgkmcnt(0)
	s_waitcnt lgkmcnt(0)
	v_mfma_f32_16x16x32_f16 v[32:35], v[162:165], v[0:3], v[60:63]
	v_mfma_f32_16x16x32_f16 v[56:59], v[186:189], v[8:11], v[32:35]
	v_mfma_f32_16x16x32_f16 v[32:35], v[162:165], v[16:19], v[226:229]
	v_mfma_f32_16x16x32_f16 v[60:63], v[186:189], v[24:27], v[32:35]
	v_mfma_f32_16x16x32_f16 v[32:35], v[190:193], v[0:3], v[52:55]
	v_mfma_f32_16x16x32_f16 v[48:51], v[194:197], v[8:11], v[32:35]
	v_mfma_f32_16x16x32_f16 v[32:35], v[190:193], v[16:19], v[230:233]
	v_mfma_f32_16x16x32_f16 v[52:55], v[194:197], v[24:27], v[32:35]
	v_mfma_f32_16x16x32_f16 v[32:35], v[202:205], v[0:3], v[44:47]
	v_mfma_f32_16x16x32_f16 v[40:43], v[206:209], v[8:11], v[32:35]
	v_mfma_f32_16x16x32_f16 v[32:35], v[202:205], v[16:19], v[234:237]
	v_mfma_f32_16x16x32_f16 v[0:3], v[210:213], v[0:3], v[36:39]
	v_mfma_f32_16x16x32_f16 v[44:47], v[206:209], v[24:27], v[32:35]
	v_mfma_f32_16x16x32_f16 v[32:35], v[238:241], v[8:11], v[0:3]
	v_mfma_f32_16x16x32_f16 v[0:3], v[210:213], v[16:19], v[134:137]
	v_mfma_f32_16x16x32_f16 v[36:39], v[238:241], v[24:27], v[0:3]
	v_mfma_f32_16x16x32_f16 v[0:3], v[162:165], v[146:149], v[28:31]
	v_mfma_f32_16x16x32_f16 v[24:27], v[186:189], v[214:217], v[0:3]
	v_mfma_f32_16x16x32_f16 v[0:3], v[162:165], v[218:221], v[138:141]
	v_mfma_f32_16x16x32_f16 v[28:31], v[186:189], v[222:225], v[0:3]
	v_mfma_f32_16x16x32_f16 v[0:3], v[190:193], v[146:149], v[20:23]
	v_mfma_f32_16x16x32_f16 v[16:19], v[194:197], v[214:217], v[0:3]
	v_mfma_f32_16x16x32_f16 v[0:3], v[190:193], v[218:221], v[142:145]
	v_mfma_f32_16x16x32_f16 v[20:23], v[194:197], v[222:225], v[0:3]
	v_mfma_f32_16x16x32_f16 v[0:3], v[202:205], v[146:149], v[12:15]
	v_mfma_f32_16x16x32_f16 v[8:11], v[206:209], v[214:217], v[0:3]
	v_mfma_f32_16x16x32_f16 v[0:3], v[202:205], v[218:221], v[158:161]
	v_mfma_f32_16x16x32_f16 v[12:15], v[206:209], v[222:225], v[0:3]
	v_mfma_f32_16x16x32_f16 v[0:3], v[210:213], v[146:149], v[4:7]
	v_mfma_f32_16x16x32_f16 v[4:7], v[210:213], v[218:221], v[198:201]
	v_mfma_f32_16x16x32_f16 v[0:3], v[238:241], v[214:217], v[0:3]
	v_mfma_f32_16x16x32_f16 v[4:7], v[238:241], v[222:225], v[4:7]
	s_movk_i32 s2, 0x100
	v_cmp_gt_u32_e32 vcc, s2, v131
	s_barrier
	s_and_saveexec_b64 s[2:3], vcc
	s_cbranch_execz .LBB0_212
	s_barrier

;   #define STAGE(P,BASE,LD,br,kt) do{ const HALF* _u=(BASE)+(long)(br)*(((&(LD))==&lda)?lda_u:(LD))+(long)(kt)*G_BK; \
;     for(int _i=0;_i<2;++_i){ \
;       __builtin_amdgcn_global_load_lds((const unsigned*)(_u+(long)_i*(((&(LD))==&lda)?stepa:stepb)+((&(LD))==&lda?oa0:ob0)), \
;         (unsigned*)((char*)(P)+t5*16+_i*8192),16,0,0);}}while(0)
;   #define LDA(dst,b,h) for(int m=0;m<4;++m)for(int k=0;k<2;++k) \
;     dst[m][k]=*reinterpret_cast<const h8*>(la+(((b)*2+(h))*16384+m*2048+k*1024))
;   #define LDB(dst,b,h) for(int n=0;n<2;++n)for(int k=0;k<2;++k) \
;     dst[n][k]=*reinterpret_cast<const h8*>(lb+(((b)*2+(h))*16384+n*2048+k*1024))
;   #define MMA(ai,bj,At,Bt_) do{__builtin_amdgcn_s_setprio(1); \
;     for(int m=0;m<4;++m)for(int n=0;n<2;++n)for(int k=0;k<2;++k) \
;       acc[ai][bj][m][n]=__builtin_amdgcn_mfma_f32_16x16x32_f16(At[m][k],Bt_[n][k],acc[ai][bj][m][n],0,0,0); \
;     __builtin_amdgcn_s_setprio(0);}while(0)
;   #define WAIT_L(n) asm volatile("s_waitcnt lgkmcnt(" #n ")":::"memory")
;   #define BAR __builtin_amdgcn_s_barrier()
;   #define SCHED __builtin_amdgcn_sched_barrier(0)
;     ...
;   for(int t=0;t<nt-2;t+=2){
;     LDB(B0,0,0); SCHED; LDA(At,0,0); STAGE(SA(1,1),A,lda,G_HALF,t+1);
;     WAIT_L(8); BAR; WAIT_L(0); MMA(0,0,At,B0); BAR; SCHED;
;     LDB(B1,0,1); STAGE(SB(0,0),Bt,ldb,0,t+2);
;     BAR; WAIT_L(0); MMA(0,1,At,B1); BAR;
;     LDA(At,0,1); STAGE(SA(0,0),A,lda,0,t+2);
;     BAR; WAIT_L(0); MMA(1,0,At,B0); BAR; SCHED;
.LBB0_245:
	ds_read_b128 v[158:161], v133
	ds_read_b128 v[162:165], v133 offset:1024
	ds_read_b128 v[186:189], v133 offset:2048
	ds_read_b128 v[190:193], v133 offset:3072
	v_add_u32_e32 v148, 0xc000, v136
	v_lshl_add_u64 v[150:151], v[128:129], 0, s[10:11]
	v_readfirstlane_b32 s7, v148
	v_add_u32_e32 v149, 0xe000, v136
	v_lshl_add_u64 v[166:167], v[150:151], 0, s[58:59]
	s_mov_b32 m0, s7
	v_readfirstlane_b32 s7, v149
	ds_read_b128 v[194:197], v132
	ds_read_b128 v[198:201], v132 offset:1024
	ds_read_b128 v[202:205], v132 offset:2048
	ds_read_b128 v[206:209], v132 offset:3072
	ds_read_b128 v[210:213], v132 offset:4096
	ds_read_b128 v[214:217], v132 offset:5120
	ds_read_b128 v[218:221], v132 offset:6144
	ds_read_b128 v[222:225], v132 offset:7168
	global_load_lds_dwordx4 v[166:167], off
	v_lshl_add_u64 v[166:167], v[150:151], 0, s[68:69]
	s_mov_b32 m0, s7
	s_nop 0
	global_load_lds_dwordx4 v[166:167], off
	s_waitcnt lgkmcnt(8)
	s_barrier
	s_waitcnt lgkmcnt(0)
	s_waitcnt lgkmcnt(0)
	v_mfma_f32_16x16x32_f16 v[124:127], v[194:197], v[158:161], v[124:127]
	v_mfma_f32_16x16x32_f16 v[120:123], v[194:197], v[186:189], v[120:123]
	v_mfma_f32_16x16x32_f16 v[116:119], v[202:205], v[158:161], v[116:119]
	v_mfma_f32_16x16x32_f16 v[112:115], v[202:205], v[186:189], v[112:115]
	v_mfma_f32_16x16x32_f16 v[108:111], v[210:213], v[158:161], v[108:111]
	v_mfma_f32_16x16x32_f16 v[104:107], v[210:213], v[186:189], v[104:107]
	v_mfma_f32_16x16x32_f16 v[100:103], v[218:221], v[158:161], v[100:103]
	v_mfma_f32_16x16x32_f16 v[96:99], v[218:221], v[186:189], v[96:99]
	v_mfma_f32_16x16x32_f16 v[124:127], v[198:201], v[162:165], v[124:127]
	v_mfma_f32_16x16x32_f16 v[120:123], v[198:201], v[190:193], v[120:123]
	v_mfma_f32_16x16x32_f16 v[116:119], v[206:209], v[162:165], v[116:119]
	v_mfma_f32_16x16x32_f16 v[112:115], v[206:209], v[190:193], v[112:115]
	v_mfma_f32_16x16x32_f16 v[108:111], v[214:217], v[162:165], v[108:111]
	v_mfma_f32_16x16x32_f16 v[104:107], v[214:217], v[190:193], v[104:107]
	v_mfma_f32_16x16x32_f16 v[100:103], v[222:225], v[162:165], v[100:103]
	v_mfma_f32_16x16x32_f16 v[96:99], v[222:225], v[190:193], v[96:99]
	s_barrier
	v_lshl_add_u64 v[166:167], v[128:129], 0, s[2:3]
	v_readfirstlane_b32 s7, v134
	v_lshl_add_u64 v[168:169], v[166:167], 0, s[92:93]
	s_mov_b32 m0, s7
	v_readfirstlane_b32 s7, v135
	ds_read_b128 v[226:229], v133 offset:16384
	ds_read_b128 v[230:233], v133 offset:17408
	ds_read_b128 v[234:237], v133 offset:18432
	ds_read_b128 v[238:241], v133 offset:19456
	global_load_lds_dwordx4 v[168:169], off
	v_lshl_add_u64 v[168:169], v[166:167], 0, s[66:67]
	s_mov_b32 m0, s7
	s_nop 0
	global_load_lds_dwordx4 v[168:169], off
	s_barrier
	s_waitcnt lgkmcnt(0)
	s_waitcnt lgkmcnt(0)
	v_mfma_f32_16x16x32_f16 v[92:95], v[194:197], v[226:229], v[92:95]
	v_mfma_f32_16x16x32_f16 v[88:91], v[194:197], v[234:237], v[88:91]
	v_mfma_f32_16x16x32_f16 v[84:87], v[202:205], v[226:229], v[84:87]
	v_mfma_f32_16x16x32_f16 v[80:83], v[202:205], v[234:237], v[80:83]
	v_mfma_f32_16x16x32_f16 v[76:79], v[210:213], v[226:229], v[76:79]
	v_mfma_f32_16x16x32_f16 v[72:75], v[210:213], v[234:237], v[72:75]
	v_mfma_f32_16x16x32_f16 v[68:71], v[218:221], v[226:229], v[68:71]
	v_mfma_f32_16x16x32_f16 v[64:67], v[218:221], v[234:237], v[64:67]
	v_mfma_f32_16x16x32_f16 v[92:95], v[198:201], v[230:233], v[92:95]
	v_mfma_f32_16x16x32_f16 v[88:91], v[198:201], v[238:241], v[88:91]
	v_mfma_f32_16x16x32_f16 v[84:87], v[206:209], v[230:233], v[84:87]
	v_mfma_f32_16x16x32_f16 v[80:83], v[206:209], v[238:241], v[80:83]
	v_mfma_f32_16x16x32_f16 v[76:79], v[214:217], v[230:233], v[76:79]
	v_mfma_f32_16x16x32_f16 v[72:75], v[214:217], v[238:241], v[72:75]
	v_mfma_f32_16x16x32_f16 v[68:71], v[222:225], v[230:233], v[68:71]
	v_mfma_f32_16x16x32_f16 v[64:67], v[222:225], v[238:241], v[64:67]
	v_readfirstlane_b32 s7, v136
	v_lshl_add_u64 v[168:169], v[150:151], 0, s[36:37]
	s_mov_b32 m0, s7
	v_readfirstlane_b32 s7, v137
	s_barrier
	ds_read_b128 v[194:197], v132 offset:16384
	ds_read_b128 v[198:201], v132 offset:17408
	ds_read_b128 v[202:205], v132 offset:18432
	ds_read_b128 v[206:209], v132 offset:19456
	ds_read_b128 v[210:213], v132 offset:20480
	ds_read_b128 v[214:217], v132 offset:21504
	ds_read_b128 v[218:221], v132 offset:22528
	ds_read_b128 v[222:225], v132 offset:23552
	global_load_lds_dwordx4 v[168:169], off
	v_lshl_add_u64 v[168:169], v[150:151], 0, s[54:55]
	s_mov_b32 m0, s7
	s_nop 0
	global_load_lds_dwordx4 v[168:169], off
	s_barrier
	s_waitcnt lgkmcnt(0)
	s_waitcnt lgkmcnt(0)
	v_mfma_f32_16x16x32_f16 v[60:63], v[194:197], v[158:161], v[60:63]
	v_mfma_f32_16x16x32_f16 v[56:59], v[194:197], v[186:189], v[56:59]
	v_mfma_f32_16x16x32_f16 v[52:55], v[202:205], v[158:161], v[52:55]
	v_mfma_f32_16x16x32_f16 v[48:51], v[202:205], v[186:189], v[48:51]
	v_mfma_f32_16x16x32_f16 v[44:47], v[210:213], v[158:161], v[44:47]
	v_mfma_f32_16x16x32_f16 v[40:43], v[210:213], v[186:189], v[40:43]
	v_mfma_f32_16x16x32_f16 v[36:39], v[218:221], v[158:161], v[36:39]
	v_mfma_f32_16x16x32_f16 v[32:35], v[218:221], v[186:189], v[32:35]
	v_mfma_f32_16x16x32_f16 v[60:63], v[198:201], v[162:165], v[60:63]
	v_mfma_f32_16x16x32_f16 v[56:59], v[198:201], v[190:193], v[56:59]
	v_mfma_f32_16x16x32_f16 v[52:55], v[206:209], v[162:165], v[52:55]
	v_mfma_f32_16x16x32_f16 v[48:51], v[206:209], v[190:193], v[48:51]
	v_mfma_f32_16x16x32_f16 v[44:47], v[214:217], v[162:165], v[44:47]
	v_mfma_f32_16x16x32_f16 v[40:43], v[214:217], v[190:193], v[40:43]
	v_mfma_f32_16x16x32_f16 v[36:39], v[222:225], v[162:165], v[36:39]
	v_mfma_f32_16x16x32_f16 v[32:35], v[222:225], v[190:193], v[32:35]
	s_barrier
;   #define STAGE(P,BASE,LD,br,kt) do{ const HALF* _u=(BASE)+(long)(br)*(((&(LD))==&lda)?lda_u:(LD))+(long)(kt)*G_BK; \
;     for(int _i=0;_i<2;++_i){ \
;       __builtin_amdgcn_global_load_lds((const unsigned*)(_u+(long)_i*(((&(LD))==&lda)?stepa:stepb)+((&(LD))==&lda?oa0:ob0)), \
;         (unsigned*)((char*)(P)+t5*16+_i*8192),16,0,0);}}while(0)
;   #define LDA(dst,b,h) for(int m=0;m<4;++m)for(int k=0;k<2;++k) \
;     dst[m][k]=*reinterpret_cast<const h8*>(la+(((b)*2+(h))*16384+m*2048+k*1024))
;   #define LDB(dst,b,h) for(int n=0;n<2;++n)for(int k=0;k<2;++k) \
;     dst[n][k]=*reinterpret_cast<const h8*>(lb+(((b)*2+(h))*16384+n*2048+k*1024))
;   #define MMA(ai,bj,At,Bt_) do{__builtin_amdgcn_s_setprio(1); \
;     for(int m=0;m<4;++m)for(int n=0;n<2;++n)for(int k=0;k<2;++k) \
;       acc[ai][bj][m][n]=__builtin_amdgcn_mfma_f32_16x16x32_f16(At[m][k],Bt_[n][k],acc[ai][bj][m][n],0,0,0); \
;     __builtin_amdgcn_s_setprio(0);}while(0)
;   #define WAIT_V(n) asm volatile("s_waitcnt vmcnt(" #n ")":::"memory")
;   #define WAIT_L(n) asm volatile("s_waitcnt lgkmcnt(" #n ")":::"memory")
;   #define BAR __builtin_amdgcn_s_barrier()
;   #define SCHED __builtin_amdgcn_sched_barrier(0)
;     ...
;     STAGE(SB(0,1),Bt,ldb,G_HALF,t+2);
;     WAIT_V(6); BAR; MMA(1,1,At,B1); BAR;
;     LDB(B0,1,0); SCHED; LDA(At,1,0); STAGE(SA(0,1),A,lda,G_HALF,t+2);
;     WAIT_L(8); BAR; WAIT_L(0); MMA(0,0,At,B0); BAR; SCHED;
;     LDB(B1,1,1); STAGE(SB(1,0),Bt,ldb,0,t+3);
;     BAR; WAIT_L(0); MMA(0,1,At,B1); BAR;
;     LDA(At,1,1); STAGE(SA(1,0),A,lda,0,t+3);
	v_readfirstlane_b32 s7, v138
	v_lshl_add_u64 v[158:159], v[166:167], 0, s[38:39]
	s_mov_b32 m0, s7
	v_readfirstlane_b32 s7, v139
	global_load_lds_dwordx4 v[158:159], off
	v_lshl_add_u64 v[158:159], v[166:167], 0, s[40:41]
	s_mov_b32 m0, s7
	s_nop 0
	global_load_lds_dwordx4 v[158:159], off
	s_waitcnt vmcnt(6)
	s_barrier
	v_mfma_f32_16x16x32_f16 v[28:31], v[194:197], v[226:229], v[28:31]
	v_mfma_f32_16x16x32_f16 v[24:27], v[194:197], v[234:237], v[24:27]
	v_mfma_f32_16x16x32_f16 v[20:23], v[202:205], v[226:229], v[20:23]
	v_mfma_f32_16x16x32_f16 v[16:19], v[202:205], v[234:237], v[16:19]
	v_mfma_f32_16x16x32_f16 v[12:15], v[210:213], v[226:229], v[12:15]
	v_mfma_f32_16x16x32_f16 v[8:11], v[210:213], v[234:237], v[8:11]
	v_mfma_f32_16x16x32_f16 v[4:7], v[218:221], v[226:229], v[4:7]
	v_mfma_f32_16x16x32_f16 v[0:3], v[218:221], v[234:237], v[0:3]
	v_mfma_f32_16x16x32_f16 v[28:31], v[198:201], v[230:233], v[28:31]
	v_mfma_f32_16x16x32_f16 v[24:27], v[198:201], v[238:241], v[24:27]
	v_mfma_f32_16x16x32_f16 v[20:23], v[206:209], v[230:233], v[20:23]
	v_mfma_f32_16x16x32_f16 v[16:19], v[206:209], v[238:241], v[16:19]
	v_mfma_f32_16x16x32_f16 v[12:15], v[214:217], v[230:233], v[12:15]
	v_mfma_f32_16x16x32_f16 v[8:11], v[214:217], v[238:241], v[8:11]
	v_mfma_f32_16x16x32_f16 v[4:7], v[222:225], v[230:233], v[4:7]
	v_mfma_f32_16x16x32_f16 v[0:3], v[222:225], v[238:241], v[0:3]
	s_barrier
	ds_read_b128 v[158:161], v133 offset:32768
	ds_read_b128 v[162:165], v133 offset:33792
	ds_read_b128 v[186:189], v133 offset:34816
	ds_read_b128 v[190:193], v133 offset:35840
	v_readfirstlane_b32 s7, v140
	v_lshl_add_u64 v[168:169], v[150:151], 0, s[24:25]
	s_mov_b32 m0, s7
	v_readfirstlane_b32 s7, v141
	ds_read_b128 v[194:197], v132 offset:32768
	ds_read_b128 v[198:201], v132 offset:33792
	ds_read_b128 v[202:205], v132 offset:34816
	ds_read_b128 v[206:209], v132 offset:35840
	ds_read_b128 v[210:213], v132 offset:36864
	ds_read_b128 v[214:217], v132 offset:37888
	ds_read_b128 v[218:221], v132 offset:38912
	ds_read_b128 v[222:225], v132 offset:39936
	global_load_lds_dwordx4 v[168:169], off
	v_lshl_add_u64 v[168:169], v[150:151], 0, s[48:49]
	s_mov_b32 m0, s7
	s_nop 0
	global_load_lds_dwordx4 v[168:169], off
	s_waitcnt lgkmcnt(8)
	s_barrier
	s_waitcnt lgkmcnt(0)
	s_waitcnt lgkmcnt(0)
	v_mfma_f32_16x16x32_f16 v[124:127], v[194:197], v[158:161], v[124:127]
	v_mfma_f32_16x16x32_f16 v[120:123], v[194:197], v[186:189], v[120:123]
	v_mfma_f32_16x16x32_f16 v[116:119], v[202:205], v[158:161], v[116:119]
	v_mfma_f32_16x16x32_f16 v[112:115], v[202:205], v[186:189], v[112:115]
	v_mfma_f32_16x16x32_f16 v[108:111], v[210:213], v[158:161], v[108:111]
	v_mfma_f32_16x16x32_f16 v[104:107], v[210:213], v[186:189], v[104:107]
	v_mfma_f32_16x16x32_f16 v[100:103], v[218:221], v[158:161], v[100:103]
	v_mfma_f32_16x16x32_f16 v[96:99], v[218:221], v[186:189], v[96:99]
	v_mfma_f32_16x16x32_f16 v[124:127], v[198:201], v[162:165], v[124:127]
	v_mfma_f32_16x16x32_f16 v[120:123], v[198:201], v[190:193], v[120:123]
	v_mfma_f32_16x16x32_f16 v[116:119], v[206:209], v[162:165], v[116:119]
	v_mfma_f32_16x16x32_f16 v[112:115], v[206:209], v[190:193], v[112:115]
	v_mfma_f32_16x16x32_f16 v[108:111], v[214:217], v[162:165], v[108:111]
	v_mfma_f32_16x16x32_f16 v[104:107], v[214:217], v[190:193], v[104:107]
	v_mfma_f32_16x16x32_f16 v[100:103], v[222:225], v[162:165], v[100:103]
	v_mfma_f32_16x16x32_f16 v[96:99], v[222:225], v[190:193], v[96:99]
	s_barrier
	v_readfirstlane_b32 s7, v142
	v_lshl_add_u64 v[168:169], v[166:167], 0, s[42:43]
	s_mov_b32 m0, s7
	v_readfirstlane_b32 s7, v143
	ds_read_b128 v[226:229], v133 offset:49152
	ds_read_b128 v[230:233], v133 offset:50176
	ds_read_b128 v[234:237], v133 offset:51200
	ds_read_b128 v[238:241], v133 offset:52224
	global_load_lds_dwordx4 v[168:169], off
	v_lshl_add_u64 v[168:169], v[166:167], 0, s[96:97]
	s_mov_b32 m0, s7
	s_nop 0
	global_load_lds_dwordx4 v[168:169], off
	s_barrier
	s_waitcnt lgkmcnt(0)
	s_waitcnt lgkmcnt(0)
	v_mfma_f32_16x16x32_f16 v[92:95], v[194:197], v[226:229], v[92:95]
	v_mfma_f32_16x16x32_f16 v[88:91], v[194:197], v[234:237], v[88:91]
	v_mfma_f32_16x16x32_f16 v[84:87], v[202:205], v[226:229], v[84:87]
	v_mfma_f32_16x16x32_f16 v[80:83], v[202:205], v[234:237], v[80:83]
	v_mfma_f32_16x16x32_f16 v[76:79], v[210:213], v[226:229], v[76:79]
	v_mfma_f32_16x16x32_f16 v[72:75], v[210:213], v[234:237], v[72:75]
	v_mfma_f32_16x16x32_f16 v[68:71], v[218:221], v[226:229], v[68:71]
	v_mfma_f32_16x16x32_f16 v[64:67], v[218:221], v[234:237], v[64:67]
	v_mfma_f32_16x16x32_f16 v[92:95], v[198:201], v[230:233], v[92:95]
	v_mfma_f32_16x16x32_f16 v[88:91], v[198:201], v[238:241], v[88:91]
	v_mfma_f32_16x16x32_f16 v[84:87], v[206:209], v[230:233], v[84:87]
	v_mfma_f32_16x16x32_f16 v[80:83], v[206:209], v[238:241], v[80:83]
	v_mfma_f32_16x16x32_f16 v[76:79], v[214:217], v[230:233], v[76:79]
	v_mfma_f32_16x16x32_f16 v[72:75], v[214:217], v[238:241], v[72:75]
	v_mfma_f32_16x16x32_f16 v[68:71], v[222:225], v[230:233], v[68:71]
	v_mfma_f32_16x16x32_f16 v[64:67], v[222:225], v[238:241], v[64:67]
	v_readfirstlane_b32 s7, v144
	v_lshl_add_u64 v[168:169], v[150:151], 0, s[60:61]
	s_mov_b32 m0, s7
	v_readfirstlane_b32 s7, v145
	s_barrier
	ds_read_b128 v[194:197], v132 offset:49152
	ds_read_b128 v[198:201], v132 offset:50176
	ds_read_b128 v[202:205], v132 offset:51200
	ds_read_b128 v[206:209], v132 offset:52224
	ds_read_b128 v[210:213], v132 offset:53248
	ds_read_b128 v[214:217], v132 offset:54272
	ds_read_b128 v[218:221], v132 offset:55296
	ds_read_b128 v[222:225], v132 offset:56320
	global_load_lds_dwordx4 v[168:169], off
	v_lshl_add_u64 v[150:151], v[150:151], 0, s[26:27]
	s_mov_b32 m0, s7
	s_nop 0
	global_load_lds_dwordx4 v[150:151], off
	s_barrier
;   #define STAGE(P,BASE,LD,br,kt) do{ const HALF* _u=(BASE)+(long)(br)*(((&(LD))==&lda)?lda_u:(LD))+(long)(kt)*G_BK; \
;     for(int _i=0;_i<2;++_i){ \
;       __builtin_amdgcn_global_load_lds((const unsigned*)(_u+(long)_i*(((&(LD))==&lda)?stepa:stepb)+((&(LD))==&lda?oa0:ob0)), \
;         (unsigned*)((char*)(P)+t5*16+_i*8192),16,0,0);}}while(0)
;   #define LDA(dst,b,h) for(int m=0;m<4;++m)for(int k=0;k<2;++k) \
;     dst[m][k]=*reinterpret_cast<const h8*>(la+(((b)*2+(h))*16384+m*2048+k*1024))
;   #define LDB(dst,b,h) for(int n=0;n<2;++n)for(int k=0;k<2;++k) \
;     dst[n][k]=*reinterpret_cast<const h8*>(lb+(((b)*2+(h))*16384+n*2048+k*1024))
;   #define MMA(ai,bj,At,Bt_) do{__builtin_amdgcn_s_setprio(1); \
;     for(int m=0;m<4;++m)for(int n=0;n<2;++n)for(int k=0;k<2;++k) \
;       acc[ai][bj][m][n]=__builtin_amdgcn_mfma_f32_16x16x32_f16(At[m][k],Bt_[n][k],acc[ai][bj][m][n],0,0,0); \
;     __builtin_amdgcn_s_setprio(0);}while(0)
;   #define WAIT_V(n) asm volatile("s_waitcnt vmcnt(" #n ")":::"memory")
;   #define WAIT_L(n) asm volatile("s_waitcnt lgkmcnt(" #n ")":::"memory")
;   #define BAR __builtin_amdgcn_s_barrier()
;   #define SCHED __builtin_amdgcn_sched_barrier(0)
;     ...
;     LDA(At,1,1); STAGE(SA(1,0),A,lda,0,t+3);
;     BAR; WAIT_L(0); MMA(1,0,At,B0); BAR; SCHED;
;     STAGE(SB(1,1),Bt,ldb,G_HALF,t+3);
;     WAIT_V(6); BAR; MMA(1,1,At,B1); BAR;
;   }
;   { LDB(B0,0,0); LDA(At,0,0); STAGE(SA(1,1),A,lda,G_HALF,nt-1);
;     BAR; WAIT_L(0); MMA(0,0,At,B0); BAR;
;     LDB(B1,0,1); BAR; WAIT_L(0); MMA(0,1,At,B1); BAR;
	s_waitcnt lgkmcnt(0)
	s_waitcnt lgkmcnt(0)
	v_mfma_f32_16x16x32_f16 v[60:63], v[194:197], v[158:161], v[60:63]
	v_mfma_f32_16x16x32_f16 v[56:59], v[194:197], v[186:189], v[56:59]
	v_mfma_f32_16x16x32_f16 v[52:55], v[202:205], v[158:161], v[52:55]
	v_mfma_f32_16x16x32_f16 v[48:51], v[202:205], v[186:189], v[48:51]
	v_mfma_f32_16x16x32_f16 v[44:47], v[210:213], v[158:161], v[44:47]
	v_mfma_f32_16x16x32_f16 v[40:43], v[210:213], v[186:189], v[40:43]
	v_mfma_f32_16x16x32_f16 v[36:39], v[218:221], v[158:161], v[36:39]
	v_mfma_f32_16x16x32_f16 v[32:35], v[218:221], v[186:189], v[32:35]
	v_mfma_f32_16x16x32_f16 v[60:63], v[198:201], v[162:165], v[60:63]
	v_mfma_f32_16x16x32_f16 v[56:59], v[198:201], v[190:193], v[56:59]
	v_mfma_f32_16x16x32_f16 v[52:55], v[206:209], v[162:165], v[52:55]
	v_mfma_f32_16x16x32_f16 v[48:51], v[206:209], v[190:193], v[48:51]
	v_mfma_f32_16x16x32_f16 v[44:47], v[214:217], v[162:165], v[44:47]
	v_mfma_f32_16x16x32_f16 v[40:43], v[214:217], v[190:193], v[40:43]
	v_mfma_f32_16x16x32_f16 v[36:39], v[222:225], v[162:165], v[36:39]
	v_mfma_f32_16x16x32_f16 v[32:35], v[222:225], v[190:193], v[32:35]
	s_barrier
	v_readfirstlane_b32 s7, v146
	v_lshl_add_u64 v[150:151], v[166:167], 0, s[12:13]
	s_mov_b32 m0, s7
	v_readfirstlane_b32 s7, v147
	global_load_lds_dwordx4 v[150:151], off
	v_lshl_add_u64 v[150:151], v[166:167], 0, s[14:15]
	s_mov_b32 m0, s7
	s_nop 0
	global_load_lds_dwordx4 v[150:151], off
	s_waitcnt vmcnt(6)
	s_barrier
	v_mfma_f32_16x16x32_f16 v[28:31], v[194:197], v[226:229], v[28:31]
	v_mfma_f32_16x16x32_f16 v[24:27], v[194:197], v[234:237], v[24:27]
	v_mfma_f32_16x16x32_f16 v[20:23], v[202:205], v[226:229], v[20:23]
	v_mfma_f32_16x16x32_f16 v[16:19], v[202:205], v[234:237], v[16:19]
	v_mfma_f32_16x16x32_f16 v[12:15], v[210:213], v[226:229], v[12:15]
	v_mfma_f32_16x16x32_f16 v[8:11], v[210:213], v[234:237], v[8:11]
	v_mfma_f32_16x16x32_f16 v[4:7], v[218:221], v[226:229], v[4:7]
	v_mfma_f32_16x16x32_f16 v[0:3], v[218:221], v[234:237], v[0:3]
	v_mfma_f32_16x16x32_f16 v[28:31], v[198:201], v[230:233], v[28:31]
	v_mfma_f32_16x16x32_f16 v[24:27], v[198:201], v[238:241], v[24:27]
	v_mfma_f32_16x16x32_f16 v[20:23], v[206:209], v[230:233], v[20:23]
	v_mfma_f32_16x16x32_f16 v[16:19], v[206:209], v[238:241], v[16:19]
	v_mfma_f32_16x16x32_f16 v[12:15], v[214:217], v[230:233], v[12:15]
	v_mfma_f32_16x16x32_f16 v[8:11], v[214:217], v[238:241], v[8:11]
	v_mfma_f32_16x16x32_f16 v[4:7], v[222:225], v[230:233], v[4:7]
	v_mfma_f32_16x16x32_f16 v[0:3], v[222:225], v[238:241], v[0:3]
	s_add_i32 s6, s6, 2
	s_cmp_lt_u32 s6, 12
	v_lshl_add_u64 v[128:129], v[128:129], 0, s[92:93]
	s_barrier
	s_cbranch_scc1 .LBB0_245
	v_lshl_add_u64 v[128:129], v[152:153], 1, s[0:1]
	s_mov_b64 s[0:1], 0x40780
	v_lshl_add_u64 v[146:147], v[128:129], 0, s[0:1]
	v_readfirstlane_b32 s0, v148
	s_mov_b32 m0, s0
	s_mov_b64 s[0:1], 0x60780
	v_lshl_add_u64 v[128:129], v[128:129], 0, s[0:1]
	v_readfirstlane_b32 s0, v149
	ds_read_b128 v[134:137], v133
	ds_read_b128 v[138:141], v133 offset:1024
	ds_read_b128 v[142:145], v133 offset:2048
	ds_read_b128 v[158:161], v133 offset:3072
	ds_read_b128 v[162:165], v132
	ds_read_b128 v[186:189], v132 offset:1024
	ds_read_b128 v[190:193], v132 offset:2048
	ds_read_b128 v[194:197], v132 offset:3072
	ds_read_b128 v[198:201], v132 offset:4096
	ds_read_b128 v[202:205], v132 offset:5120
	ds_read_b128 v[206:209], v132 offset:6144
	ds_read_b128 v[210:213], v132 offset:7168
	global_load_lds_dwordx4 v[146:147], off
	s_mov_b32 m0, s0
	s_nop 0
	global_load_lds_dwordx4 v[128:129], off
	s_barrier
	s_waitcnt lgkmcnt(0)
	s_waitcnt lgkmcnt(0)
	v_mfma_f32_16x16x32_f16 v[124:127], v[162:165], v[134:137], v[124:127]
	v_mfma_f32_16x16x32_f16 v[120:123], v[162:165], v[142:145], v[120:123]
	v_mfma_f32_16x16x32_f16 v[116:119], v[190:193], v[134:137], v[116:119]
	v_mfma_f32_16x16x32_f16 v[112:115], v[190:193], v[142:145], v[112:115]
	v_mfma_f32_16x16x32_f16 v[108:111], v[198:201], v[134:137], v[108:111]
	v_mfma_f32_16x16x32_f16 v[104:107], v[198:201], v[142:145], v[104:107]
	v_mfma_f32_16x16x32_f16 v[124:127], v[186:189], v[138:141], v[124:127]
	v_mfma_f32_16x16x32_f16 v[120:123], v[186:189], v[158:161], v[120:123]
	v_mfma_f32_16x16x32_f16 v[116:119], v[194:197], v[138:141], v[116:119]
	v_mfma_f32_16x16x32_f16 v[112:115], v[194:197], v[158:161], v[112:115]
	v_mfma_f32_16x16x32_f16 v[108:111], v[202:205], v[138:141], v[108:111]
	v_mfma_f32_16x16x32_f16 v[104:107], v[202:205], v[158:161], v[104:107]
	v_mfma_f32_16x16x32_f16 v[100:103], v[206:209], v[134:137], v[100:103]
	v_mfma_f32_16x16x32_f16 v[96:99], v[206:209], v[142:145], v[96:99]
	v_mfma_f32_16x16x32_f16 v[146:149], v[210:213], v[138:141], v[100:103]
	v_mfma_f32_16x16x32_f16 v[214:217], v[210:213], v[158:161], v[96:99]
	s_barrier
	s_nop 3
	ds_read_b128 v[96:99], v133 offset:16384
	ds_read_b128 v[100:103], v133 offset:17408
	ds_read_b128 v[218:221], v133 offset:18432
	ds_read_b128 v[222:225], v133 offset:19456
	s_barrier
	s_waitcnt lgkmcnt(0)
	s_waitcnt lgkmcnt(0)
	v_mfma_f32_16x16x32_f16 v[92:95], v[162:165], v[96:99], v[92:95]
	v_mfma_f32_16x16x32_f16 v[84:87], v[190:193], v[96:99], v[84:87]
	v_mfma_f32_16x16x32_f16 v[80:83], v[190:193], v[218:221], v[80:83]
	v_mfma_f32_16x16x32_f16 v[76:79], v[198:201], v[96:99], v[76:79]
	v_mfma_f32_16x16x32_f16 v[72:75], v[198:201], v[218:221], v[72:75]
	v_mfma_f32_16x16x32_f16 v[68:71], v[206:209], v[96:99], v[68:71]
	v_mfma_f32_16x16x32_f16 v[64:67], v[206:209], v[218:221], v[64:67]
	v_mfma_f32_16x16x32_f16 v[92:95], v[186:189], v[100:103], v[92:95]
	v_mfma_f32_16x16x32_f16 v[88:91], v[162:165], v[218:221], v[88:91]
	v_mfma_f32_16x16x32_f16 v[84:87], v[194:197], v[100:103], v[84:87]
	v_mfma_f32_16x16x32_f16 v[80:83], v[194:197], v[222:225], v[80:83]
	v_mfma_f32_16x16x32_f16 v[76:79], v[202:205], v[100:103], v[76:79]
	v_mfma_f32_16x16x32_f16 v[72:75], v[202:205], v[222:225], v[72:75]
	v_mfma_f32_16x16x32_f16 v[68:71], v[210:213], v[100:103], v[68:71]
	v_mfma_f32_16x16x32_f16 v[64:67], v[210:213], v[222:225], v[64:67]
	v_mfma_f32_16x16x32_f16 v[162:165], v[186:189], v[222:225], v[88:91]
	s_barrier
;   #define LDA(dst,b,h) for(int m=0;m<4;++m)for(int k=0;k<2;++k) \
;     dst[m][k]=*reinterpret_cast<const h8*>(la+(((b)*2+(h))*16384+m*2048+k*1024))
;   #define LDB(dst,b,h) for(int n=0;n<2;++n)for(int k=0;k<2;++k) \
;     dst[n][k]=*reinterpret_cast<const h8*>(lb+(((b)*2+(h))*16384+n*2048+k*1024))
;   #define MMA(ai,bj,At,Bt_) do{__builtin_amdgcn_s_setprio(1); \
;     for(int m=0;m<4;++m)for(int n=0;n<2;++n)for(int k=0;k<2;++k) \
;       acc[ai][bj][m][n]=__builtin_amdgcn_mfma_f32_16x16x32_f16(At[m][k],Bt_[n][k],acc[ai][bj][m][n],0,0,0); \
;     __builtin_amdgcn_s_setprio(0);}while(0)
;   #define WAIT_V(n) asm volatile("s_waitcnt vmcnt(" #n ")":::"memory")
;   #define WAIT_L(n) asm volatile("s_waitcnt lgkmcnt(" #n ")":::"memory")
;   #define BAR __builtin_amdgcn_s_barrier()
;     ...
;     LDA(At,0,1); WAIT_V(4); BAR; WAIT_L(0); MMA(1,0,At,B0); MMA(1,1,At,B1); BAR; }
;   { LDB(B0,1,0); LDA(At,1,0); WAIT_V(2); BAR; WAIT_L(0); MMA(0,0,At,B0); BAR;
	s_nop 0
	ds_read_b128 v[88:91], v132 offset:16384
	ds_read_b128 v[186:189], v132 offset:17408
	ds_read_b128 v[190:193], v132 offset:18432
	ds_read_b128 v[194:197], v132 offset:19456
	ds_read_b128 v[198:201], v132 offset:20480
	ds_read_b128 v[202:205], v132 offset:21504
	ds_read_b128 v[206:209], v132 offset:22528
	ds_read_b128 v[210:213], v132 offset:23552
	s_waitcnt vmcnt(4)
	s_barrier
	s_waitcnt lgkmcnt(0)
	s_waitcnt lgkmcnt(0)
	v_mfma_f32_16x16x32_f16 v[56:59], v[88:91], v[142:145], v[56:59]
	v_mfma_f32_16x16x32_f16 v[48:51], v[190:193], v[142:145], v[48:51]
	v_mfma_f32_16x16x32_f16 v[44:47], v[198:201], v[134:137], v[44:47]
	v_mfma_f32_16x16x32_f16 v[40:43], v[198:201], v[142:145], v[40:43]
	v_mfma_f32_16x16x32_f16 v[36:39], v[206:209], v[134:137], v[36:39]
	v_mfma_f32_16x16x32_f16 v[32:35], v[206:209], v[142:145], v[32:35]
	v_mfma_f32_16x16x32_f16 v[60:63], v[88:91], v[134:137], v[60:63]
	v_mfma_f32_16x16x32_f16 v[56:59], v[186:189], v[158:161], v[56:59]
	v_mfma_f32_16x16x32_f16 v[52:55], v[190:193], v[134:137], v[52:55]
	v_mfma_f32_16x16x32_f16 v[48:51], v[194:197], v[158:161], v[48:51]
	v_mfma_f32_16x16x32_f16 v[44:47], v[202:205], v[138:141], v[44:47]
	v_mfma_f32_16x16x32_f16 v[40:43], v[202:205], v[158:161], v[40:43]
	v_mfma_f32_16x16x32_f16 v[36:39], v[210:213], v[138:141], v[36:39]
	v_mfma_f32_16x16x32_f16 v[32:35], v[210:213], v[158:161], v[32:35]
	v_mfma_f32_16x16x32_f16 v[226:229], v[186:189], v[138:141], v[60:63]
	v_mfma_f32_16x16x32_f16 v[230:233], v[194:197], v[138:141], v[52:55]
	v_mfma_f32_16x16x32_f16 v[28:31], v[88:91], v[96:99], v[28:31]
	v_mfma_f32_16x16x32_f16 v[24:27], v[88:91], v[218:221], v[24:27]
	v_mfma_f32_16x16x32_f16 v[20:23], v[190:193], v[96:99], v[20:23]
	v_mfma_f32_16x16x32_f16 v[16:19], v[190:193], v[218:221], v[16:19]
	v_mfma_f32_16x16x32_f16 v[12:15], v[198:201], v[96:99], v[12:15]
	v_mfma_f32_16x16x32_f16 v[8:11], v[198:201], v[218:221], v[8:11]
	v_mfma_f32_16x16x32_f16 v[4:7], v[206:209], v[96:99], v[4:7]
	v_mfma_f32_16x16x32_f16 v[0:3], v[206:209], v[218:221], v[0:3]
	v_mfma_f32_16x16x32_f16 v[28:31], v[186:189], v[100:103], v[28:31]
	v_mfma_f32_16x16x32_f16 v[24:27], v[186:189], v[222:225], v[24:27]
	v_mfma_f32_16x16x32_f16 v[20:23], v[194:197], v[100:103], v[20:23]
	v_mfma_f32_16x16x32_f16 v[16:19], v[194:197], v[222:225], v[16:19]
	v_mfma_f32_16x16x32_f16 v[12:15], v[202:205], v[100:103], v[12:15]
	v_mfma_f32_16x16x32_f16 v[8:11], v[202:205], v[222:225], v[8:11]
	v_mfma_f32_16x16x32_f16 v[4:7], v[210:213], v[100:103], v[4:7]
	v_mfma_f32_16x16x32_f16 v[0:3], v[210:213], v[222:225], v[0:3]
	s_barrier
	ds_read_b128 v[134:137], v133 offset:32768
	ds_read_b128 v[138:141], v133 offset:33792
	ds_read_b128 v[142:145], v133 offset:34816
	ds_read_b128 v[158:161], v133 offset:35840
	ds_read_b128 v[52:55], v132 offset:32768
	ds_read_b128 v[60:63], v132 offset:33792
	ds_read_b128 v[186:189], v132 offset:34816
	ds_read_b128 v[190:193], v132 offset:35840
	ds_read_b128 v[194:197], v132 offset:36864
	ds_read_b128 v[198:201], v132 offset:37888
	ds_read_b128 v[202:205], v132 offset:38912
	ds_read_b128 v[206:209], v132 offset:39936
	s_waitcnt vmcnt(2)
	s_barrier
	s_waitcnt lgkmcnt(0)
	s_waitcnt lgkmcnt(0)
	v_mfma_f32_16x16x32_f16 v[88:91], v[52:55], v[134:137], v[124:127]
	v_mfma_f32_16x16x32_f16 v[124:127], v[60:63], v[138:141], v[88:91]
	v_mfma_f32_16x16x32_f16 v[88:91], v[52:55], v[142:145], v[120:123]
	v_mfma_f32_16x16x32_f16 v[120:123], v[60:63], v[158:161], v[88:91]
	v_mfma_f32_16x16x32_f16 v[88:91], v[186:189], v[134:137], v[116:119]
	v_mfma_f32_16x16x32_f16 v[116:119], v[190:193], v[138:141], v[88:91]
	v_mfma_f32_16x16x32_f16 v[88:91], v[186:189], v[142:145], v[112:115]
	v_mfma_f32_16x16x32_f16 v[112:115], v[190:193], v[158:161], v[88:91]
	v_mfma_f32_16x16x32_f16 v[88:91], v[194:197], v[134:137], v[108:111]
	v_mfma_f32_16x16x32_f16 v[108:111], v[198:201], v[138:141], v[88:91]
	v_mfma_f32_16x16x32_f16 v[88:91], v[194:197], v[142:145], v[104:107]
	v_mfma_f32_16x16x32_f16 v[100:103], v[198:201], v[158:161], v[88:91]
	v_mfma_f32_16x16x32_f16 v[88:91], v[202:205], v[134:137], v[146:149]
	v_mfma_f32_16x16x32_f16 v[96:99], v[206:209], v[138:141], v[88:91]
	v_mfma_f32_16x16x32_f16 v[88:91], v[202:205], v[142:145], v[214:217]
	v_mfma_f32_16x16x32_f16 v[88:91], v[206:209], v[158:161], v[88:91]
	s_barrier
;   #define LDA(dst,b,h) for(int m=0;m<4;++m)for(int k=0;k<2;++k) \
;     dst[m][k]=*reinterpret_cast<const h8*>(la+(((b)*2+(h))*16384+m*2048+k*1024))
;   #define LDB(dst,b,h) for(int n=0;n<2;++n)for(int k=0;k<2;++k) \
;     dst[n][k]=*reinterpret_cast<const h8*>(lb+(((b)*2+(h))*16384+n*2048+k*1024))
;   #define MMA(ai,bj,At,Bt_) do{__builtin_amdgcn_s_setprio(1); \
;     for(int m=0;m<4;++m)for(int n=0;n<2;++n)for(int k=0;k<2;++k) \
;       acc[ai][bj][m][n]=__builtin_amdgcn_mfma_f32_16x16x32_f16(At[m][k],Bt_[n][k],acc[ai][bj][m][n],0,0,0); \
;     __builtin_amdgcn_s_setprio(0);}while(0)
;   #define WAIT_V(n) asm volatile("s_waitcnt vmcnt(" #n ")":::"memory")
;   #define WAIT_L(n) asm volatile("s_waitcnt lgkmcnt(" #n ")":::"memory")
;   #define BAR __builtin_amdgcn_s_barrier()
;     ...
;     LDB(B1,1,1); WAIT_V(0); BAR; WAIT_L(0); MMA(0,1,At,B1); BAR;
;     LDA(At,1,1); BAR; WAIT_L(0); MMA(1,0,At,B0); MMA(1,1,At,B1); BAR; }
;   if(wr==0)BAR;
	ds_read_b128 v[146:149], v133 offset:49152
	ds_read_b128 v[210:213], v133 offset:50176
	ds_read_b128 v[214:217], v133 offset:51200
	ds_read_b128 v[218:221], v133 offset:52224
	s_waitcnt vmcnt(0)
	s_barrier
	s_waitcnt lgkmcnt(0)
	s_waitcnt lgkmcnt(0)
	v_mfma_f32_16x16x32_f16 v[92:95], v[52:55], v[146:149], v[92:95]
	v_mfma_f32_16x16x32_f16 v[52:55], v[52:55], v[214:217], v[162:165]
	v_mfma_f32_16x16x32_f16 v[104:107], v[60:63], v[210:213], v[92:95]
	v_mfma_f32_16x16x32_f16 v[92:95], v[60:63], v[218:221], v[52:55]
	v_mfma_f32_16x16x32_f16 v[52:55], v[186:189], v[146:149], v[84:87]
	v_mfma_f32_16x16x32_f16 v[84:87], v[190:193], v[210:213], v[52:55]
	v_mfma_f32_16x16x32_f16 v[52:55], v[186:189], v[214:217], v[80:83]
	v_mfma_f32_16x16x32_f16 v[80:83], v[190:193], v[218:221], v[52:55]
	v_mfma_f32_16x16x32_f16 v[52:55], v[194:197], v[146:149], v[76:79]
	v_mfma_f32_16x16x32_f16 v[76:79], v[198:201], v[210:213], v[52:55]
	v_mfma_f32_16x16x32_f16 v[52:55], v[194:197], v[214:217], v[72:75]
	v_mfma_f32_16x16x32_f16 v[72:75], v[198:201], v[218:221], v[52:55]
	v_mfma_f32_16x16x32_f16 v[52:55], v[202:205], v[146:149], v[68:71]
	v_mfma_f32_16x16x32_f16 v[60:63], v[206:209], v[210:213], v[52:55]
	v_mfma_f32_16x16x32_f16 v[52:55], v[202:205], v[214:217], v[64:67]
	v_mfma_f32_16x16x32_f16 v[52:55], v[206:209], v[218:221], v[52:55]
	s_barrier
	ds_read_b128 v[162:165], v132 offset:49152
	ds_read_b128 v[186:189], v132 offset:50176
	ds_read_b128 v[190:193], v132 offset:51200
	ds_read_b128 v[194:197], v132 offset:52224
	ds_read_b128 v[198:201], v132 offset:53248
	ds_read_b128 v[202:205], v132 offset:54272
	ds_read_b128 v[206:209], v132 offset:55296
	ds_read_b128 v[222:225], v132 offset:56320
	s_barrier
	s_waitcnt lgkmcnt(0)
	s_waitcnt lgkmcnt(0)
	v_mfma_f32_16x16x32_f16 v[64:67], v[162:165], v[134:137], v[226:229]
	v_mfma_f32_16x16x32_f16 v[56:59], v[162:165], v[142:145], v[56:59]
	v_mfma_f32_16x16x32_f16 v[68:71], v[186:189], v[138:141], v[64:67]
	v_mfma_f32_16x16x32_f16 v[64:67], v[186:189], v[158:161], v[56:59]
	v_mfma_f32_16x16x32_f16 v[56:59], v[190:193], v[134:137], v[230:233]
	v_mfma_f32_16x16x32_f16 v[48:51], v[190:193], v[142:145], v[48:51]
	v_mfma_f32_16x16x32_f16 v[44:47], v[198:201], v[134:137], v[44:47]
	v_mfma_f32_16x16x32_f16 v[40:43], v[198:201], v[142:145], v[40:43]
	v_mfma_f32_16x16x32_f16 v[36:39], v[206:209], v[134:137], v[36:39]
	v_mfma_f32_16x16x32_f16 v[32:35], v[206:209], v[142:145], v[32:35]
	v_mfma_f32_16x16x32_f16 v[56:59], v[194:197], v[138:141], v[56:59]
	v_mfma_f32_16x16x32_f16 v[48:51], v[194:197], v[158:161], v[48:51]
	v_mfma_f32_16x16x32_f16 v[44:47], v[202:205], v[138:141], v[44:47]
	v_mfma_f32_16x16x32_f16 v[40:43], v[202:205], v[158:161], v[40:43]
	v_mfma_f32_16x16x32_f16 v[36:39], v[222:225], v[138:141], v[36:39]
	v_mfma_f32_16x16x32_f16 v[32:35], v[222:225], v[158:161], v[32:35]
	v_mfma_f32_16x16x32_f16 v[28:31], v[162:165], v[146:149], v[28:31]
	v_mfma_f32_16x16x32_f16 v[24:27], v[162:165], v[214:217], v[24:27]
	v_mfma_f32_16x16x32_f16 v[20:23], v[190:193], v[146:149], v[20:23]
	v_mfma_f32_16x16x32_f16 v[16:19], v[190:193], v[214:217], v[16:19]
	v_mfma_f32_16x16x32_f16 v[12:15], v[198:201], v[146:149], v[12:15]
	v_mfma_f32_16x16x32_f16 v[8:11], v[198:201], v[214:217], v[8:11]
	v_mfma_f32_16x16x32_f16 v[4:7], v[206:209], v[146:149], v[4:7]
	v_mfma_f32_16x16x32_f16 v[0:3], v[206:209], v[214:217], v[0:3]
	v_mfma_f32_16x16x32_f16 v[28:31], v[186:189], v[210:213], v[28:31]
	v_mfma_f32_16x16x32_f16 v[24:27], v[186:189], v[218:221], v[24:27]
	v_mfma_f32_16x16x32_f16 v[20:23], v[194:197], v[210:213], v[20:23]
	v_mfma_f32_16x16x32_f16 v[16:19], v[194:197], v[218:221], v[16:19]
	v_mfma_f32_16x16x32_f16 v[12:15], v[202:205], v[210:213], v[12:15]
	v_mfma_f32_16x16x32_f16 v[8:11], v[202:205], v[218:221], v[8:11]
	v_mfma_f32_16x16x32_f16 v[4:7], v[222:225], v[210:213], v[4:7]
	v_mfma_f32_16x16x32_f16 v[0:3], v[222:225], v[218:221], v[0:3]
	s_movk_i32 s0, 0x100
	v_cmp_gt_u32_e32 vcc, s0, v131
	s_barrier
	s_and_saveexec_b64 s[0:1], vcc
	s_cbranch_execz .LBB0_248
	s_barrier

;   #define STAGE(P,BASE,LD,br,kt) do{ const HALF* _u=(BASE)+(long)(br)*(((&(LD))==&lda)?lda_u:(LD))+(long)(kt)*G_BK; \
;     for(int _i=0;_i<2;++_i){ \
;       __builtin_amdgcn_global_load_lds((const unsigned*)(_u+(long)_i*(((&(LD))==&lda)?stepa:stepb)+((&(LD))==&lda?oa0:ob0)), \
;         (unsigned*)((char*)(P)+t5*16+_i*8192),16,0,0);}}while(0)
;   #define LDA(dst,b,h) for(int m=0;m<4;++m)for(int k=0;k<2;++k) \
;     dst[m][k]=*reinterpret_cast<const h8*>(la+(((b)*2+(h))*16384+m*2048+k*1024))
;   #define LDB(dst,b,h) for(int n=0;n<2;++n)for(int k=0;k<2;++k) \
;     dst[n][k]=*reinterpret_cast<const h8*>(lb+(((b)*2+(h))*16384+n*2048+k*1024))
;   #define MMA(ai,bj,At,Bt_) do{__builtin_amdgcn_s_setprio(1); \
;     for(int m=0;m<4;++m)for(int n=0;n<2;++n)for(int k=0;k<2;++k) \
;       acc[ai][bj][m][n]=__builtin_amdgcn_mfma_f32_16x16x32_f16(At[m][k],Bt_[n][k],acc[ai][bj][m][n],0,0,0); \
;     __builtin_amdgcn_s_setprio(0);}while(0)
;   #define WAIT_L(n) asm volatile("s_waitcnt lgkmcnt(" #n ")":::"memory")
;   #define BAR __builtin_amdgcn_s_barrier()
;   #define SCHED __builtin_amdgcn_sched_barrier(0)
;     ...
;     LDB(B0,0,0); SCHED; LDA(At,0,0); STAGE(SA(1,1),A,lda,G_HALF,t+1);
;     WAIT_L(8); BAR; WAIT_L(0); MMA(0,0,At,B0); BAR; SCHED;
;     LDB(B1,0,1); STAGE(SB(0,0),Bt,ldb,0,t+2);
;     BAR; WAIT_L(0); MMA(0,1,At,B1); BAR;
;     LDA(At,0,1); STAGE(SA(0,0),A,lda,0,t+2);
;     BAR; WAIT_L(0); MMA(1,0,At,B0); BAR; SCHED;
.LBB0_262:
	ds_read_b128 v[158:161], v133
	ds_read_b128 v[162:165], v133 offset:1024
	ds_read_b128 v[186:189], v133 offset:2048
	ds_read_b128 v[190:193], v133 offset:3072
	v_add_u32_e32 v148, 0xc000, v136
	v_lshl_add_u64 v[150:151], s[6:7], 0, v[128:129]
	v_readfirstlane_b32 s13, v148
	v_add_u32_e32 v149, 0xe000, v136
	v_lshl_add_u64 v[166:167], v[150:151], 0, s[88:89]
	s_mov_b32 m0, s13
	v_readfirstlane_b32 s13, v149
	ds_read_b128 v[194:197], v132
	ds_read_b128 v[198:201], v132 offset:1024
	ds_read_b128 v[202:205], v132 offset:2048
	ds_read_b128 v[206:209], v132 offset:3072
	ds_read_b128 v[210:213], v132 offset:4096
	ds_read_b128 v[214:217], v132 offset:5120
	ds_read_b128 v[218:221], v132 offset:6144
	ds_read_b128 v[222:225], v132 offset:7168
	global_load_lds_dwordx4 v[166:167], off
	v_lshl_add_u64 v[166:167], v[150:151], 0, s[90:91]
	s_mov_b32 m0, s13
	s_nop 0
	global_load_lds_dwordx4 v[166:167], off
	s_waitcnt lgkmcnt(8)
	s_barrier
	s_waitcnt lgkmcnt(0)
	s_waitcnt lgkmcnt(0)
	v_mfma_f32_16x16x32_f16 v[124:127], v[194:197], v[158:161], v[124:127]
	v_mfma_f32_16x16x32_f16 v[120:123], v[194:197], v[186:189], v[120:123]
	v_mfma_f32_16x16x32_f16 v[116:119], v[202:205], v[158:161], v[116:119]
	v_mfma_f32_16x16x32_f16 v[112:115], v[202:205], v[186:189], v[112:115]
	v_mfma_f32_16x16x32_f16 v[108:111], v[210:213], v[158:161], v[108:111]
	v_mfma_f32_16x16x32_f16 v[104:107], v[210:213], v[186:189], v[104:107]
	v_mfma_f32_16x16x32_f16 v[100:103], v[218:221], v[158:161], v[100:103]
	v_mfma_f32_16x16x32_f16 v[96:99], v[218:221], v[186:189], v[96:99]
	v_mfma_f32_16x16x32_f16 v[124:127], v[198:201], v[162:165], v[124:127]
	v_mfma_f32_16x16x32_f16 v[120:123], v[198:201], v[190:193], v[120:123]
	v_mfma_f32_16x16x32_f16 v[116:119], v[206:209], v[162:165], v[116:119]
	v_mfma_f32_16x16x32_f16 v[112:115], v[206:209], v[190:193], v[112:115]
	v_mfma_f32_16x16x32_f16 v[108:111], v[214:217], v[162:165], v[108:111]
	v_mfma_f32_16x16x32_f16 v[104:107], v[214:217], v[190:193], v[104:107]
	v_mfma_f32_16x16x32_f16 v[100:103], v[222:225], v[162:165], v[100:103]
	v_mfma_f32_16x16x32_f16 v[96:99], v[222:225], v[190:193], v[96:99]
	s_barrier
	v_lshl_add_u64 v[166:167], s[2:3], 0, v[128:129]
	v_readfirstlane_b32 s13, v134
	v_lshl_add_u64 v[168:169], v[166:167], 0, s[36:37]
	s_mov_b32 m0, s13
	v_readfirstlane_b32 s13, v135
	ds_read_b128 v[226:229], v133 offset:16384
	ds_read_b128 v[230:233], v133 offset:17408
	ds_read_b128 v[234:237], v133 offset:18432
	ds_read_b128 v[238:241], v133 offset:19456
	global_load_lds_dwordx4 v[168:169], off
	v_lshl_add_u64 v[168:169], v[166:167], 0, s[54:55]
	s_mov_b32 m0, s13
	s_nop 0
	global_load_lds_dwordx4 v[168:169], off
	s_barrier
	s_waitcnt lgkmcnt(0)
	s_waitcnt lgkmcnt(0)
	v_mfma_f32_16x16x32_f16 v[92:95], v[194:197], v[226:229], v[92:95]
	v_mfma_f32_16x16x32_f16 v[88:91], v[194:197], v[234:237], v[88:91]
	v_mfma_f32_16x16x32_f16 v[84:87], v[202:205], v[226:229], v[84:87]
	v_mfma_f32_16x16x32_f16 v[80:83], v[202:205], v[234:237], v[80:83]
	v_mfma_f32_16x16x32_f16 v[76:79], v[210:213], v[226:229], v[76:79]
	v_mfma_f32_16x16x32_f16 v[72:75], v[210:213], v[234:237], v[72:75]
	v_mfma_f32_16x16x32_f16 v[68:71], v[218:221], v[226:229], v[68:71]
	v_mfma_f32_16x16x32_f16 v[64:67], v[218:221], v[234:237], v[64:67]
	v_mfma_f32_16x16x32_f16 v[92:95], v[198:201], v[230:233], v[92:95]
	v_mfma_f32_16x16x32_f16 v[88:91], v[198:201], v[238:241], v[88:91]
	v_mfma_f32_16x16x32_f16 v[84:87], v[206:209], v[230:233], v[84:87]
	v_mfma_f32_16x16x32_f16 v[80:83], v[206:209], v[238:241], v[80:83]
	v_mfma_f32_16x16x32_f16 v[76:79], v[214:217], v[230:233], v[76:79]
	v_mfma_f32_16x16x32_f16 v[72:75], v[214:217], v[238:241], v[72:75]
	v_mfma_f32_16x16x32_f16 v[68:71], v[222:225], v[230:233], v[68:71]
	v_mfma_f32_16x16x32_f16 v[64:67], v[222:225], v[238:241], v[64:67]
	v_readfirstlane_b32 s13, v136
	v_lshl_add_u64 v[168:169], v[150:151], 0, s[92:93]
	s_mov_b32 m0, s13
	v_readfirstlane_b32 s13, v137
	s_barrier
	ds_read_b128 v[194:197], v132 offset:16384
	ds_read_b128 v[198:201], v132 offset:17408
	ds_read_b128 v[202:205], v132 offset:18432
	ds_read_b128 v[206:209], v132 offset:19456
	ds_read_b128 v[210:213], v132 offset:20480
	ds_read_b128 v[214:217], v132 offset:21504
	ds_read_b128 v[218:221], v132 offset:22528
	ds_read_b128 v[222:225], v132 offset:23552
	global_load_lds_dwordx4 v[168:169], off
	v_lshl_add_u64 v[168:169], v[150:151], 0, s[66:67]
	s_mov_b32 m0, s13
	s_nop 0
	global_load_lds_dwordx4 v[168:169], off
	s_barrier
	s_waitcnt lgkmcnt(0)
	s_waitcnt lgkmcnt(0)
	v_mfma_f32_16x16x32_f16 v[60:63], v[194:197], v[158:161], v[60:63]
	v_mfma_f32_16x16x32_f16 v[56:59], v[194:197], v[186:189], v[56:59]
	v_mfma_f32_16x16x32_f16 v[52:55], v[202:205], v[158:161], v[52:55]
	v_mfma_f32_16x16x32_f16 v[48:51], v[202:205], v[186:189], v[48:51]
	v_mfma_f32_16x16x32_f16 v[44:47], v[210:213], v[158:161], v[44:47]
	v_mfma_f32_16x16x32_f16 v[40:43], v[210:213], v[186:189], v[40:43]
	v_mfma_f32_16x16x32_f16 v[36:39], v[218:221], v[158:161], v[36:39]
	v_mfma_f32_16x16x32_f16 v[32:35], v[218:221], v[186:189], v[32:35]
	v_mfma_f32_16x16x32_f16 v[60:63], v[198:201], v[162:165], v[60:63]
	v_mfma_f32_16x16x32_f16 v[56:59], v[198:201], v[190:193], v[56:59]
	v_mfma_f32_16x16x32_f16 v[52:55], v[206:209], v[162:165], v[52:55]
	v_mfma_f32_16x16x32_f16 v[48:51], v[206:209], v[190:193], v[48:51]
	v_mfma_f32_16x16x32_f16 v[44:47], v[214:217], v[162:165], v[44:47]
	v_mfma_f32_16x16x32_f16 v[40:43], v[214:217], v[190:193], v[40:43]
	v_mfma_f32_16x16x32_f16 v[36:39], v[222:225], v[162:165], v[36:39]
	v_mfma_f32_16x16x32_f16 v[32:35], v[222:225], v[190:193], v[32:35]
	s_barrier
;   #define STAGE(P,BASE,LD,br,kt) do{ const HALF* _u=(BASE)+(long)(br)*(((&(LD))==&lda)?lda_u:(LD))+(long)(kt)*G_BK; \
;     for(int _i=0;_i<2;++_i){ \
;       __builtin_amdgcn_global_load_lds((const unsigned*)(_u+(long)_i*(((&(LD))==&lda)?stepa:stepb)+((&(LD))==&lda?oa0:ob0)), \
;         (unsigned*)((char*)(P)+t5*16+_i*8192),16,0,0);}}while(0)
;   #define LDA(dst,b,h) for(int m=0;m<4;++m)for(int k=0;k<2;++k) \
;     dst[m][k]=*reinterpret_cast<const h8*>(la+(((b)*2+(h))*16384+m*2048+k*1024))
;   #define LDB(dst,b,h) for(int n=0;n<2;++n)for(int k=0;k<2;++k) \
;     dst[n][k]=*reinterpret_cast<const h8*>(lb+(((b)*2+(h))*16384+n*2048+k*1024))
;   #define MMA(ai,bj,At,Bt_) do{__builtin_amdgcn_s_setprio(1); \
;     for(int m=0;m<4;++m)for(int n=0;n<2;++n)for(int k=0;k<2;++k) \
;       acc[ai][bj][m][n]=__builtin_amdgcn_mfma_f32_16x16x32_f16(At[m][k],Bt_[n][k],acc[ai][bj][m][n],0,0,0); \
;     __builtin_amdgcn_s_setprio(0);}while(0)
;   #define WAIT_V(n) asm volatile("s_waitcnt vmcnt(" #n ")":::"memory")
;   #define WAIT_L(n) asm volatile("s_waitcnt lgkmcnt(" #n ")":::"memory")
;   #define BAR __builtin_amdgcn_s_barrier()
;   #define SCHED __builtin_amdgcn_sched_barrier(0)
;     ...
;     STAGE(SB(0,1),Bt,ldb,G_HALF,t+2);
;     WAIT_V(6); BAR; MMA(1,1,At,B1); BAR;
;     LDB(B0,1,0); SCHED; LDA(At,1,0); STAGE(SA(0,1),A,lda,G_HALF,t+2);
;     WAIT_L(8); BAR; WAIT_L(0); MMA(0,0,At,B0); BAR; SCHED;
;     LDB(B1,1,1); STAGE(SB(1,0),Bt,ldb,0,t+3);
;     BAR; WAIT_L(0); MMA(0,1,At,B1); BAR;
;     LDA(At,1,1); STAGE(SA(1,0),A,lda,0,t+3);
	v_readfirstlane_b32 s13, v138
	v_lshl_add_u64 v[158:159], v[166:167], 0, s[24:25]
	s_mov_b32 m0, s13
	v_readfirstlane_b32 s13, v139
	global_load_lds_dwordx4 v[158:159], off
	v_lshl_add_u64 v[158:159], v[166:167], 0, s[48:49]
	s_mov_b32 m0, s13
	s_nop 0
	global_load_lds_dwordx4 v[158:159], off
	s_waitcnt vmcnt(6)
	s_barrier
	v_mfma_f32_16x16x32_f16 v[28:31], v[194:197], v[226:229], v[28:31]
	v_mfma_f32_16x16x32_f16 v[24:27], v[194:197], v[234:237], v[24:27]
	v_mfma_f32_16x16x32_f16 v[20:23], v[202:205], v[226:229], v[20:23]
	v_mfma_f32_16x16x32_f16 v[16:19], v[202:205], v[234:237], v[16:19]
	v_mfma_f32_16x16x32_f16 v[12:15], v[210:213], v[226:229], v[12:15]
	v_mfma_f32_16x16x32_f16 v[8:11], v[210:213], v[234:237], v[8:11]
	v_mfma_f32_16x16x32_f16 v[4:7], v[218:221], v[226:229], v[4:7]
	v_mfma_f32_16x16x32_f16 v[0:3], v[218:221], v[234:237], v[0:3]
	v_mfma_f32_16x16x32_f16 v[28:31], v[198:201], v[230:233], v[28:31]
	v_mfma_f32_16x16x32_f16 v[24:27], v[198:201], v[238:241], v[24:27]
	v_mfma_f32_16x16x32_f16 v[20:23], v[206:209], v[230:233], v[20:23]
	v_mfma_f32_16x16x32_f16 v[16:19], v[206:209], v[238:241], v[16:19]
	v_mfma_f32_16x16x32_f16 v[12:15], v[214:217], v[230:233], v[12:15]
	v_mfma_f32_16x16x32_f16 v[8:11], v[214:217], v[238:241], v[8:11]
	v_mfma_f32_16x16x32_f16 v[4:7], v[222:225], v[230:233], v[4:7]
	v_mfma_f32_16x16x32_f16 v[0:3], v[222:225], v[238:241], v[0:3]
	s_barrier
	ds_read_b128 v[158:161], v133 offset:32768
	ds_read_b128 v[162:165], v133 offset:33792
	ds_read_b128 v[186:189], v133 offset:34816
	ds_read_b128 v[190:193], v133 offset:35840
	v_readfirstlane_b32 s13, v140
	v_lshl_add_u64 v[168:169], v[150:151], 0, s[38:39]
	s_mov_b32 m0, s13
	v_readfirstlane_b32 s13, v141
	ds_read_b128 v[194:197], v132 offset:32768
	ds_read_b128 v[198:201], v132 offset:33792
	ds_read_b128 v[202:205], v132 offset:34816
	ds_read_b128 v[206:209], v132 offset:35840
	ds_read_b128 v[210:213], v132 offset:36864
	ds_read_b128 v[214:217], v132 offset:37888
	ds_read_b128 v[218:221], v132 offset:38912
	ds_read_b128 v[222:225], v132 offset:39936
	global_load_lds_dwordx4 v[168:169], off
	v_lshl_add_u64 v[168:169], v[150:151], 0, s[40:41]
	s_mov_b32 m0, s13
	s_nop 0
	global_load_lds_dwordx4 v[168:169], off
	s_waitcnt lgkmcnt(8)
	s_barrier
	s_waitcnt lgkmcnt(0)
	s_waitcnt lgkmcnt(0)
	v_mfma_f32_16x16x32_f16 v[124:127], v[194:197], v[158:161], v[124:127]
	v_mfma_f32_16x16x32_f16 v[120:123], v[194:197], v[186:189], v[120:123]
	v_mfma_f32_16x16x32_f16 v[116:119], v[202:205], v[158:161], v[116:119]
	v_mfma_f32_16x16x32_f16 v[112:115], v[202:205], v[186:189], v[112:115]
	v_mfma_f32_16x16x32_f16 v[108:111], v[210:213], v[158:161], v[108:111]
	v_mfma_f32_16x16x32_f16 v[104:107], v[210:213], v[186:189], v[104:107]
	v_mfma_f32_16x16x32_f16 v[100:103], v[218:221], v[158:161], v[100:103]
	v_mfma_f32_16x16x32_f16 v[96:99], v[218:221], v[186:189], v[96:99]
	v_mfma_f32_16x16x32_f16 v[124:127], v[198:201], v[162:165], v[124:127]
	v_mfma_f32_16x16x32_f16 v[120:123], v[198:201], v[190:193], v[120:123]
	v_mfma_f32_16x16x32_f16 v[116:119], v[206:209], v[162:165], v[116:119]
	v_mfma_f32_16x16x32_f16 v[112:115], v[206:209], v[190:193], v[112:115]
	v_mfma_f32_16x16x32_f16 v[108:111], v[214:217], v[162:165], v[108:111]
	v_mfma_f32_16x16x32_f16 v[104:107], v[214:217], v[190:193], v[104:107]
	v_mfma_f32_16x16x32_f16 v[100:103], v[222:225], v[162:165], v[100:103]
	v_mfma_f32_16x16x32_f16 v[96:99], v[222:225], v[190:193], v[96:99]
	s_barrier
	v_readfirstlane_b32 s13, v142
	v_lshl_add_u64 v[168:169], v[166:167], 0, s[60:61]
	s_mov_b32 m0, s13
	v_readfirstlane_b32 s13, v143
	ds_read_b128 v[226:229], v133 offset:49152
	ds_read_b128 v[230:233], v133 offset:50176
	ds_read_b128 v[234:237], v133 offset:51200
	ds_read_b128 v[238:241], v133 offset:52224
	global_load_lds_dwordx4 v[168:169], off
	v_lshl_add_u64 v[168:169], v[166:167], 0, s[26:27]
	s_mov_b32 m0, s13
	s_nop 0
	global_load_lds_dwordx4 v[168:169], off
	s_barrier
	s_waitcnt lgkmcnt(0)
	s_waitcnt lgkmcnt(0)
	v_mfma_f32_16x16x32_f16 v[92:95], v[194:197], v[226:229], v[92:95]
	v_mfma_f32_16x16x32_f16 v[88:91], v[194:197], v[234:237], v[88:91]
	v_mfma_f32_16x16x32_f16 v[84:87], v[202:205], v[226:229], v[84:87]
	v_mfma_f32_16x16x32_f16 v[80:83], v[202:205], v[234:237], v[80:83]
	v_mfma_f32_16x16x32_f16 v[76:79], v[210:213], v[226:229], v[76:79]
	v_mfma_f32_16x16x32_f16 v[72:75], v[210:213], v[234:237], v[72:75]
	v_mfma_f32_16x16x32_f16 v[68:71], v[218:221], v[226:229], v[68:71]
	v_mfma_f32_16x16x32_f16 v[64:67], v[218:221], v[234:237], v[64:67]
	v_mfma_f32_16x16x32_f16 v[92:95], v[198:201], v[230:233], v[92:95]
	v_mfma_f32_16x16x32_f16 v[88:91], v[198:201], v[238:241], v[88:91]
	v_mfma_f32_16x16x32_f16 v[84:87], v[206:209], v[230:233], v[84:87]
	v_mfma_f32_16x16x32_f16 v[80:83], v[206:209], v[238:241], v[80:83]
	v_mfma_f32_16x16x32_f16 v[76:79], v[214:217], v[230:233], v[76:79]
	v_mfma_f32_16x16x32_f16 v[72:75], v[214:217], v[238:241], v[72:75]
	v_mfma_f32_16x16x32_f16 v[68:71], v[222:225], v[230:233], v[68:71]
	v_mfma_f32_16x16x32_f16 v[64:67], v[222:225], v[238:241], v[64:67]
	v_readfirstlane_b32 s13, v144
	v_lshl_add_u64 v[168:169], v[150:151], 0, s[42:43]
	s_mov_b32 m0, s13
	v_readfirstlane_b32 s13, v145
	s_barrier
	ds_read_b128 v[194:197], v132 offset:49152
	ds_read_b128 v[198:201], v132 offset:50176
	ds_read_b128 v[202:205], v132 offset:51200
	ds_read_b128 v[206:209], v132 offset:52224
	ds_read_b128 v[210:213], v132 offset:53248
	ds_read_b128 v[214:217], v132 offset:54272
	ds_read_b128 v[218:221], v132 offset:55296
	ds_read_b128 v[222:225], v132 offset:56320
	global_load_lds_dwordx4 v[168:169], off
	v_lshl_add_u64 v[150:151], v[150:151], 0, s[96:97]
	s_mov_b32 m0, s13
	s_nop 0
	global_load_lds_dwordx4 v[150:151], off
	s_barrier
;   #define STAGE(P,BASE,LD,br,kt) do{ const HALF* _u=(BASE)+(long)(br)*(((&(LD))==&lda)?lda_u:(LD))+(long)(kt)*G_BK; \
;     for(int _i=0;_i<2;++_i){ \
;       __builtin_amdgcn_global_load_lds((const unsigned*)(_u+(long)_i*(((&(LD))==&lda)?stepa:stepb)+((&(LD))==&lda?oa0:ob0)), \
;         (unsigned*)((char*)(P)+t5*16+_i*8192),16,0,0);}}while(0)
;   #define LDA(dst,b,h) for(int m=0;m<4;++m)for(int k=0;k<2;++k) \
;     dst[m][k]=*reinterpret_cast<const h8*>(la+(((b)*2+(h))*16384+m*2048+k*1024))
;   #define LDB(dst,b,h) for(int n=0;n<2;++n)for(int k=0;k<2;++k) \
;     dst[n][k]=*reinterpret_cast<const h8*>(lb+(((b)*2+(h))*16384+n*2048+k*1024))
;   #define MMA(ai,bj,At,Bt_) do{__builtin_amdgcn_s_setprio(1); \
;     for(int m=0;m<4;++m)for(int n=0;n<2;++n)for(int k=0;k<2;++k) \
;       acc[ai][bj][m][n]=__builtin_amdgcn_mfma_f32_16x16x32_f16(At[m][k],Bt_[n][k],acc[ai][bj][m][n],0,0,0); \
;     __builtin_amdgcn_s_setprio(0);}while(0)
;   #define WAIT_V(n) asm volatile("s_waitcnt vmcnt(" #n ")":::"memory")
;   #define WAIT_L(n) asm volatile("s_waitcnt lgkmcnt(" #n ")":::"memory")
;   #define BAR __builtin_amdgcn_s_barrier()
;   #define SCHED __builtin_amdgcn_sched_barrier(0)
;     ...
;     BAR; WAIT_L(0); MMA(1,0,At,B0); BAR; SCHED;
;     STAGE(SB(1,1),Bt,ldb,G_HALF,t+3);
;     WAIT_V(6); BAR; MMA(1,1,At,B1); BAR;
;   }
;   { LDB(B0,0,0); LDA(At,0,0); STAGE(SA(1,1),A,lda,G_HALF,nt-1);
;     BAR; WAIT_L(0); MMA(0,0,At,B0); BAR;
;     LDB(B1,0,1); BAR; WAIT_L(0); MMA(0,1,At,B1); BAR;
	s_waitcnt lgkmcnt(0)
	s_waitcnt lgkmcnt(0)
	v_mfma_f32_16x16x32_f16 v[60:63], v[194:197], v[158:161], v[60:63]
	v_mfma_f32_16x16x32_f16 v[56:59], v[194:197], v[186:189], v[56:59]
	v_mfma_f32_16x16x32_f16 v[52:55], v[202:205], v[158:161], v[52:55]
	v_mfma_f32_16x16x32_f16 v[48:51], v[202:205], v[186:189], v[48:51]
	v_mfma_f32_16x16x32_f16 v[44:47], v[210:213], v[158:161], v[44:47]
	v_mfma_f32_16x16x32_f16 v[40:43], v[210:213], v[186:189], v[40:43]
	v_mfma_f32_16x16x32_f16 v[36:39], v[218:221], v[158:161], v[36:39]
	v_mfma_f32_16x16x32_f16 v[32:35], v[218:221], v[186:189], v[32:35]
	v_mfma_f32_16x16x32_f16 v[60:63], v[198:201], v[162:165], v[60:63]
	v_mfma_f32_16x16x32_f16 v[56:59], v[198:201], v[190:193], v[56:59]
	v_mfma_f32_16x16x32_f16 v[52:55], v[206:209], v[162:165], v[52:55]
	v_mfma_f32_16x16x32_f16 v[48:51], v[206:209], v[190:193], v[48:51]
	v_mfma_f32_16x16x32_f16 v[44:47], v[214:217], v[162:165], v[44:47]
	v_mfma_f32_16x16x32_f16 v[40:43], v[214:217], v[190:193], v[40:43]
	v_mfma_f32_16x16x32_f16 v[36:39], v[222:225], v[162:165], v[36:39]
	v_mfma_f32_16x16x32_f16 v[32:35], v[222:225], v[190:193], v[32:35]
	s_barrier
	v_readfirstlane_b32 s13, v146
	v_lshl_add_u64 v[150:151], v[166:167], 0, s[56:57]
	s_mov_b32 m0, s13
	v_readfirstlane_b32 s13, v147
	global_load_lds_dwordx4 v[150:151], off
	v_lshl_add_u64 v[150:151], v[166:167], 0, s[52:53]
	s_mov_b32 m0, s13
	s_nop 0
	global_load_lds_dwordx4 v[150:151], off
	s_waitcnt vmcnt(6)
	s_barrier
	v_mfma_f32_16x16x32_f16 v[28:31], v[194:197], v[226:229], v[28:31]
	v_mfma_f32_16x16x32_f16 v[24:27], v[194:197], v[234:237], v[24:27]
	v_mfma_f32_16x16x32_f16 v[20:23], v[202:205], v[226:229], v[20:23]
	v_mfma_f32_16x16x32_f16 v[16:19], v[202:205], v[234:237], v[16:19]
	v_mfma_f32_16x16x32_f16 v[12:15], v[210:213], v[226:229], v[12:15]
	v_mfma_f32_16x16x32_f16 v[8:11], v[210:213], v[234:237], v[8:11]
	v_mfma_f32_16x16x32_f16 v[4:7], v[218:221], v[226:229], v[4:7]
	v_mfma_f32_16x16x32_f16 v[0:3], v[218:221], v[234:237], v[0:3]
	v_mfma_f32_16x16x32_f16 v[28:31], v[198:201], v[230:233], v[28:31]
	v_mfma_f32_16x16x32_f16 v[24:27], v[198:201], v[238:241], v[24:27]
	v_mfma_f32_16x16x32_f16 v[20:23], v[206:209], v[230:233], v[20:23]
	v_mfma_f32_16x16x32_f16 v[16:19], v[206:209], v[238:241], v[16:19]
	v_mfma_f32_16x16x32_f16 v[12:15], v[214:217], v[230:233], v[12:15]
	v_mfma_f32_16x16x32_f16 v[8:11], v[214:217], v[238:241], v[8:11]
	v_mfma_f32_16x16x32_f16 v[4:7], v[222:225], v[230:233], v[4:7]
	v_mfma_f32_16x16x32_f16 v[0:3], v[222:225], v[238:241], v[0:3]
	s_add_i32 s12, s12, 2
	s_add_u32 s2, s2, 0x100
	s_addc_u32 s3, s3, 0
	s_add_u32 s6, s6, 0x100
	s_addc_u32 s7, s7, 0
	s_cmp_lt_u32 s12, 12
	s_barrier
	s_cbranch_scc1 .LBB0_262
	v_lshl_add_u64 v[128:129], v[152:153], 1, s[0:1]
	s_mov_b64 s[0:1], 0x40780
	v_lshl_add_u64 v[146:147], v[128:129], 0, s[0:1]
	v_readfirstlane_b32 s0, v148
	s_mov_b32 m0, s0
	s_mov_b64 s[0:1], 0x60780
	v_lshl_add_u64 v[128:129], v[128:129], 0, s[0:1]
	v_readfirstlane_b32 s0, v149
	ds_read_b128 v[134:137], v133
	ds_read_b128 v[138:141], v133 offset:1024
	ds_read_b128 v[142:145], v133 offset:2048
	ds_read_b128 v[158:161], v133 offset:3072
	ds_read_b128 v[162:165], v132
	ds_read_b128 v[186:189], v132 offset:1024
	ds_read_b128 v[190:193], v132 offset:2048
	ds_read_b128 v[194:197], v132 offset:3072
	ds_read_b128 v[198:201], v132 offset:4096
	ds_read_b128 v[202:205], v132 offset:5120
	ds_read_b128 v[206:209], v132 offset:6144
	ds_read_b128 v[210:213], v132 offset:7168
	global_load_lds_dwordx4 v[146:147], off
	s_mov_b32 m0, s0
	s_nop 0
	global_load_lds_dwordx4 v[128:129], off
	s_barrier
	s_waitcnt lgkmcnt(0)
	s_waitcnt lgkmcnt(0)
	v_mfma_f32_16x16x32_f16 v[124:127], v[162:165], v[134:137], v[124:127]
	v_mfma_f32_16x16x32_f16 v[120:123], v[162:165], v[142:145], v[120:123]
	v_mfma_f32_16x16x32_f16 v[116:119], v[190:193], v[134:137], v[116:119]
	v_mfma_f32_16x16x32_f16 v[112:115], v[190:193], v[142:145], v[112:115]
	v_mfma_f32_16x16x32_f16 v[108:111], v[198:201], v[134:137], v[108:111]
	v_mfma_f32_16x16x32_f16 v[104:107], v[198:201], v[142:145], v[104:107]
	v_mfma_f32_16x16x32_f16 v[100:103], v[206:209], v[134:137], v[100:103]
	v_mfma_f32_16x16x32_f16 v[96:99], v[206:209], v[142:145], v[96:99]
	v_mfma_f32_16x16x32_f16 v[124:127], v[186:189], v[138:141], v[124:127]
	v_mfma_f32_16x16x32_f16 v[120:123], v[186:189], v[158:161], v[120:123]
	v_mfma_f32_16x16x32_f16 v[116:119], v[194:197], v[138:141], v[116:119]
	v_mfma_f32_16x16x32_f16 v[112:115], v[194:197], v[158:161], v[112:115]
	v_mfma_f32_16x16x32_f16 v[108:111], v[202:205], v[138:141], v[108:111]
	v_mfma_f32_16x16x32_f16 v[104:107], v[202:205], v[158:161], v[104:107]
	v_mfma_f32_16x16x32_f16 v[100:103], v[210:213], v[138:141], v[100:103]
	v_mfma_f32_16x16x32_f16 v[96:99], v[210:213], v[158:161], v[96:99]
	s_barrier
	ds_read_b128 v[146:149], v133 offset:16384
	ds_read_b128 v[214:217], v133 offset:17408
	ds_read_b128 v[218:221], v133 offset:18432
	ds_read_b128 v[222:225], v133 offset:19456
	s_barrier
	s_waitcnt lgkmcnt(0)
	s_waitcnt lgkmcnt(0)
	v_mfma_f32_16x16x32_f16 v[92:95], v[162:165], v[146:149], v[92:95]
	v_mfma_f32_16x16x32_f16 v[88:91], v[162:165], v[218:221], v[88:91]
	v_mfma_f32_16x16x32_f16 v[84:87], v[190:193], v[146:149], v[84:87]
	v_mfma_f32_16x16x32_f16 v[80:83], v[190:193], v[218:221], v[80:83]
	v_mfma_f32_16x16x32_f16 v[76:79], v[198:201], v[146:149], v[76:79]
	v_mfma_f32_16x16x32_f16 v[72:75], v[198:201], v[218:221], v[72:75]
	v_mfma_f32_16x16x32_f16 v[68:71], v[206:209], v[146:149], v[68:71]
	v_mfma_f32_16x16x32_f16 v[64:67], v[206:209], v[218:221], v[64:67]
	v_mfma_f32_16x16x32_f16 v[92:95], v[186:189], v[214:217], v[92:95]
	v_mfma_f32_16x16x32_f16 v[88:91], v[186:189], v[222:225], v[88:91]
	v_mfma_f32_16x16x32_f16 v[84:87], v[194:197], v[214:217], v[84:87]
	v_mfma_f32_16x16x32_f16 v[80:83], v[194:197], v[222:225], v[80:83]
	v_mfma_f32_16x16x32_f16 v[76:79], v[202:205], v[214:217], v[76:79]
	v_mfma_f32_16x16x32_f16 v[72:75], v[202:205], v[222:225], v[72:75]
	v_mfma_f32_16x16x32_f16 v[68:71], v[210:213], v[214:217], v[68:71]
	v_mfma_f32_16x16x32_f16 v[64:67], v[210:213], v[222:225], v[64:67]
	s_barrier
;   #define LDA(dst,b,h) for(int m=0;m<4;++m)for(int k=0;k<2;++k) \
;     dst[m][k]=*reinterpret_cast<const h8*>(la+(((b)*2+(h))*16384+m*2048+k*1024))
;   #define LDB(dst,b,h) for(int n=0;n<2;++n)for(int k=0;k<2;++k) \
;     dst[n][k]=*reinterpret_cast<const h8*>(lb+(((b)*2+(h))*16384+n*2048+k*1024))
;   #define MMA(ai,bj,At,Bt_) do{__builtin_amdgcn_s_setprio(1); \
;     for(int m=0;m<4;++m)for(int n=0;n<2;++n)for(int k=0;k<2;++k) \
;       acc[ai][bj][m][n]=__builtin_amdgcn_mfma_f32_16x16x32_f16(At[m][k],Bt_[n][k],acc[ai][bj][m][n],0,0,0); \
;     __builtin_amdgcn_s_setprio(0);}while(0)
;   #define WAIT_V(n) asm volatile("s_waitcnt vmcnt(" #n ")":::"memory")
;   #define WAIT_L(n) asm volatile("s_waitcnt lgkmcnt(" #n ")":::"memory")
;   #define BAR __builtin_amdgcn_s_barrier()
;     ...
;     LDA(At,0,1); WAIT_V(4); BAR; WAIT_L(0); MMA(1,0,At,B0); MMA(1,1,At,B1); BAR; }
;   { LDB(B0,1,0); LDA(At,1,0); WAIT_V(2); BAR; WAIT_L(0); MMA(0,0,At,B0); BAR;
	ds_read_b128 v[162:165], v132 offset:16384
	ds_read_b128 v[186:189], v132 offset:17408
	ds_read_b128 v[190:193], v132 offset:18432
	ds_read_b128 v[194:197], v132 offset:19456
	ds_read_b128 v[198:201], v132 offset:20480
	ds_read_b128 v[202:205], v132 offset:21504
	ds_read_b128 v[206:209], v132 offset:22528
	ds_read_b128 v[210:213], v132 offset:23552
	s_waitcnt vmcnt(4)
	s_barrier
	s_waitcnt lgkmcnt(0)
	s_waitcnt lgkmcnt(0)
	v_mfma_f32_16x16x32_f16 v[60:63], v[162:165], v[134:137], v[60:63]
	v_mfma_f32_16x16x32_f16 v[56:59], v[162:165], v[142:145], v[56:59]
	v_mfma_f32_16x16x32_f16 v[52:55], v[190:193], v[134:137], v[52:55]
	v_mfma_f32_16x16x32_f16 v[48:51], v[190:193], v[142:145], v[48:51]
	v_mfma_f32_16x16x32_f16 v[44:47], v[198:201], v[134:137], v[44:47]
	v_mfma_f32_16x16x32_f16 v[40:43], v[198:201], v[142:145], v[40:43]
	v_mfma_f32_16x16x32_f16 v[36:39], v[206:209], v[134:137], v[36:39]
	v_mfma_f32_16x16x32_f16 v[32:35], v[206:209], v[142:145], v[32:35]
	v_mfma_f32_16x16x32_f16 v[60:63], v[186:189], v[138:141], v[60:63]
	v_mfma_f32_16x16x32_f16 v[56:59], v[186:189], v[158:161], v[56:59]
	v_mfma_f32_16x16x32_f16 v[52:55], v[194:197], v[138:141], v[52:55]
	v_mfma_f32_16x16x32_f16 v[48:51], v[194:197], v[158:161], v[48:51]
	v_mfma_f32_16x16x32_f16 v[44:47], v[202:205], v[138:141], v[44:47]
	v_mfma_f32_16x16x32_f16 v[40:43], v[202:205], v[158:161], v[40:43]
	v_mfma_f32_16x16x32_f16 v[36:39], v[210:213], v[138:141], v[36:39]
	v_mfma_f32_16x16x32_f16 v[32:35], v[210:213], v[158:161], v[32:35]
	v_mfma_f32_16x16x32_f16 v[28:31], v[162:165], v[146:149], v[28:31]
	v_mfma_f32_16x16x32_f16 v[24:27], v[162:165], v[218:221], v[24:27]
	v_mfma_f32_16x16x32_f16 v[20:23], v[190:193], v[146:149], v[20:23]
	v_mfma_f32_16x16x32_f16 v[16:19], v[190:193], v[218:221], v[16:19]
	v_mfma_f32_16x16x32_f16 v[12:15], v[198:201], v[146:149], v[12:15]
	v_mfma_f32_16x16x32_f16 v[8:11], v[198:201], v[218:221], v[8:11]
	v_mfma_f32_16x16x32_f16 v[4:7], v[206:209], v[146:149], v[4:7]
	v_mfma_f32_16x16x32_f16 v[0:3], v[206:209], v[218:221], v[0:3]
	v_mfma_f32_16x16x32_f16 v[28:31], v[186:189], v[214:217], v[28:31]
	v_mfma_f32_16x16x32_f16 v[24:27], v[186:189], v[222:225], v[24:27]
	v_mfma_f32_16x16x32_f16 v[20:23], v[194:197], v[214:217], v[20:23]
	v_mfma_f32_16x16x32_f16 v[16:19], v[194:197], v[222:225], v[16:19]
	v_mfma_f32_16x16x32_f16 v[12:15], v[202:205], v[214:217], v[12:15]
	v_mfma_f32_16x16x32_f16 v[8:11], v[202:205], v[222:225], v[8:11]
	v_mfma_f32_16x16x32_f16 v[4:7], v[210:213], v[214:217], v[4:7]
	v_mfma_f32_16x16x32_f16 v[0:3], v[210:213], v[222:225], v[0:3]
	s_barrier
	ds_read_b128 v[134:137], v133 offset:32768
	ds_read_b128 v[138:141], v133 offset:33792
	ds_read_b128 v[142:145], v133 offset:34816
	ds_read_b128 v[146:149], v133 offset:35840
	ds_read_b128 v[158:161], v132 offset:32768
	ds_read_b128 v[162:165], v132 offset:33792
	ds_read_b128 v[186:189], v132 offset:34816
	ds_read_b128 v[190:193], v132 offset:35840
	ds_read_b128 v[194:197], v132 offset:36864
	ds_read_b128 v[198:201], v132 offset:37888
	ds_read_b128 v[202:205], v132 offset:38912
	ds_read_b128 v[206:209], v132 offset:39936
	s_waitcnt vmcnt(2)
	s_barrier
	s_waitcnt lgkmcnt(0)
	s_waitcnt lgkmcnt(0)
	v_mfma_f32_16x16x32_f16 v[124:127], v[158:161], v[134:137], v[124:127]
	v_mfma_f32_16x16x32_f16 v[120:123], v[158:161], v[142:145], v[120:123]
	v_mfma_f32_16x16x32_f16 v[116:119], v[186:189], v[134:137], v[116:119]
	v_mfma_f32_16x16x32_f16 v[112:115], v[186:189], v[142:145], v[112:115]
	v_mfma_f32_16x16x32_f16 v[108:111], v[194:197], v[134:137], v[108:111]
	v_mfma_f32_16x16x32_f16 v[104:107], v[194:197], v[142:145], v[104:107]
	v_mfma_f32_16x16x32_f16 v[100:103], v[202:205], v[134:137], v[100:103]
	v_mfma_f32_16x16x32_f16 v[96:99], v[202:205], v[142:145], v[96:99]
	v_mfma_f32_16x16x32_f16 v[124:127], v[162:165], v[138:141], v[124:127]
	v_mfma_f32_16x16x32_f16 v[120:123], v[162:165], v[146:149], v[120:123]
	v_mfma_f32_16x16x32_f16 v[116:119], v[190:193], v[138:141], v[116:119]
	v_mfma_f32_16x16x32_f16 v[112:115], v[190:193], v[146:149], v[112:115]
	v_mfma_f32_16x16x32_f16 v[108:111], v[198:201], v[138:141], v[108:111]
	v_mfma_f32_16x16x32_f16 v[104:107], v[198:201], v[146:149], v[104:107]
	v_mfma_f32_16x16x32_f16 v[100:103], v[206:209], v[138:141], v[100:103]
	v_mfma_f32_16x16x32_f16 v[96:99], v[206:209], v[146:149], v[96:99]
	s_barrier
;   #define LDA(dst,b,h) for(int m=0;m<4;++m)for(int k=0;k<2;++k) \
;     dst[m][k]=*reinterpret_cast<const h8*>(la+(((b)*2+(h))*16384+m*2048+k*1024))
;   #define LDB(dst,b,h) for(int n=0;n<2;++n)for(int k=0;k<2;++k) \
;     dst[n][k]=*reinterpret_cast<const h8*>(lb+(((b)*2+(h))*16384+n*2048+k*1024))
;   #define MMA(ai,bj,At,Bt_) do{__builtin_amdgcn_s_setprio(1); \
;     for(int m=0;m<4;++m)for(int n=0;n<2;++n)for(int k=0;k<2;++k) \
;       acc[ai][bj][m][n]=__builtin_amdgcn_mfma_f32_16x16x32_f16(At[m][k],Bt_[n][k],acc[ai][bj][m][n],0,0,0); \
;     __builtin_amdgcn_s_setprio(0);}while(0)
;   #define WAIT_V(n) asm volatile("s_waitcnt vmcnt(" #n ")":::"memory")
;   #define WAIT_L(n) asm volatile("s_waitcnt lgkmcnt(" #n ")":::"memory")
;   #define BAR __builtin_amdgcn_s_barrier()
;     ...
;     LDB(B1,1,1); WAIT_V(0); BAR; WAIT_L(0); MMA(0,1,At,B1); BAR;
;     LDA(At,1,1); BAR; WAIT_L(0); MMA(1,0,At,B0); MMA(1,1,At,B1); BAR; }
;   if(wr==0)BAR;
	ds_read_b128 v[210:213], v133 offset:49152
	ds_read_b128 v[214:217], v133 offset:50176
	ds_read_b128 v[218:221], v133 offset:51200
	ds_read_b128 v[222:225], v133 offset:52224
	s_waitcnt vmcnt(0)
	s_barrier
	s_waitcnt lgkmcnt(0)
	s_waitcnt lgkmcnt(0)
	v_mfma_f32_16x16x32_f16 v[92:95], v[158:161], v[210:213], v[92:95]
	v_mfma_f32_16x16x32_f16 v[88:91], v[158:161], v[218:221], v[88:91]
	v_mfma_f32_16x16x32_f16 v[84:87], v[186:189], v[210:213], v[84:87]
	v_mfma_f32_16x16x32_f16 v[80:83], v[186:189], v[218:221], v[80:83]
	v_mfma_f32_16x16x32_f16 v[76:79], v[194:197], v[210:213], v[76:79]
	v_mfma_f32_16x16x32_f16 v[72:75], v[194:197], v[218:221], v[72:75]
	v_mfma_f32_16x16x32_f16 v[68:71], v[202:205], v[210:213], v[68:71]
	v_mfma_f32_16x16x32_f16 v[64:67], v[202:205], v[218:221], v[64:67]
	v_mfma_f32_16x16x32_f16 v[92:95], v[162:165], v[214:217], v[92:95]
	v_mfma_f32_16x16x32_f16 v[88:91], v[162:165], v[222:225], v[88:91]
	v_mfma_f32_16x16x32_f16 v[84:87], v[190:193], v[214:217], v[84:87]
	v_mfma_f32_16x16x32_f16 v[80:83], v[190:193], v[222:225], v[80:83]
	v_mfma_f32_16x16x32_f16 v[76:79], v[198:201], v[214:217], v[76:79]
	v_mfma_f32_16x16x32_f16 v[72:75], v[198:201], v[222:225], v[72:75]
	v_mfma_f32_16x16x32_f16 v[68:71], v[206:209], v[214:217], v[68:71]
	v_mfma_f32_16x16x32_f16 v[64:67], v[206:209], v[222:225], v[64:67]
	s_barrier
	ds_read_b128 v[158:161], v132 offset:49152
	ds_read_b128 v[162:165], v132 offset:50176
	ds_read_b128 v[186:189], v132 offset:51200
	ds_read_b128 v[190:193], v132 offset:52224
	ds_read_b128 v[194:197], v132 offset:53248
	ds_read_b128 v[198:201], v132 offset:54272
	ds_read_b128 v[202:205], v132 offset:55296
	ds_read_b128 v[206:209], v132 offset:56320
	s_barrier
	s_waitcnt lgkmcnt(0)
	s_waitcnt lgkmcnt(0)
	v_mfma_f32_16x16x32_f16 v[60:63], v[158:161], v[134:137], v[60:63]
	v_mfma_f32_16x16x32_f16 v[56:59], v[158:161], v[142:145], v[56:59]
	v_mfma_f32_16x16x32_f16 v[52:55], v[186:189], v[134:137], v[52:55]
	v_mfma_f32_16x16x32_f16 v[48:51], v[186:189], v[142:145], v[48:51]
	v_mfma_f32_16x16x32_f16 v[44:47], v[194:197], v[134:137], v[44:47]
	v_mfma_f32_16x16x32_f16 v[40:43], v[194:197], v[142:145], v[40:43]
	v_mfma_f32_16x16x32_f16 v[36:39], v[202:205], v[134:137], v[36:39]
	v_mfma_f32_16x16x32_f16 v[32:35], v[202:205], v[142:145], v[32:35]
	v_mfma_f32_16x16x32_f16 v[60:63], v[162:165], v[138:141], v[60:63]
	v_mfma_f32_16x16x32_f16 v[56:59], v[162:165], v[146:149], v[56:59]
	v_mfma_f32_16x16x32_f16 v[52:55], v[190:193], v[138:141], v[52:55]
	v_mfma_f32_16x16x32_f16 v[48:51], v[190:193], v[146:149], v[48:51]
	v_mfma_f32_16x16x32_f16 v[44:47], v[198:201], v[138:141], v[44:47]
	v_mfma_f32_16x16x32_f16 v[40:43], v[198:201], v[146:149], v[40:43]
	v_mfma_f32_16x16x32_f16 v[36:39], v[206:209], v[138:141], v[36:39]
	v_mfma_f32_16x16x32_f16 v[32:35], v[206:209], v[146:149], v[32:35]
	v_mfma_f32_16x16x32_f16 v[28:31], v[158:161], v[210:213], v[28:31]
	v_mfma_f32_16x16x32_f16 v[24:27], v[158:161], v[218:221], v[24:27]
	v_mfma_f32_16x16x32_f16 v[20:23], v[186:189], v[210:213], v[20:23]
	v_mfma_f32_16x16x32_f16 v[16:19], v[186:189], v[218:221], v[16:19]
	v_mfma_f32_16x16x32_f16 v[12:15], v[194:197], v[210:213], v[12:15]
	v_mfma_f32_16x16x32_f16 v[8:11], v[194:197], v[218:221], v[8:11]
	v_mfma_f32_16x16x32_f16 v[4:7], v[202:205], v[210:213], v[4:7]
	v_mfma_f32_16x16x32_f16 v[0:3], v[202:205], v[218:221], v[0:3]
	v_mfma_f32_16x16x32_f16 v[28:31], v[162:165], v[214:217], v[28:31]
	v_mfma_f32_16x16x32_f16 v[24:27], v[162:165], v[222:225], v[24:27]
	v_mfma_f32_16x16x32_f16 v[20:23], v[190:193], v[214:217], v[20:23]
	v_mfma_f32_16x16x32_f16 v[16:19], v[190:193], v[222:225], v[16:19]
	v_mfma_f32_16x16x32_f16 v[12:15], v[198:201], v[214:217], v[12:15]
	v_mfma_f32_16x16x32_f16 v[8:11], v[198:201], v[222:225], v[8:11]
	v_mfma_f32_16x16x32_f16 v[4:7], v[206:209], v[214:217], v[4:7]
	v_mfma_f32_16x16x32_f16 v[0:3], v[206:209], v[222:225], v[0:3]
	s_movk_i32 s0, 0x100
	v_cmp_gt_u32_e32 vcc, s0, v131
	s_barrier
	s_and_saveexec_b64 s[0:1], vcc
	s_cbranch_execz .LBB0_265
	s_barrier

;   #define STAGE(P,BASE,LD,br,kt) do{ const HALF* _u=(BASE)+(long)(br)*(((&(LD))==&lda)?lda_u:(LD))+(long)(kt)*G_BK; \
;     for(int _i=0;_i<2;++_i){ \
;       __builtin_amdgcn_global_load_lds((const unsigned*)(_u+(long)_i*(((&(LD))==&lda)?stepa:stepb)+((&(LD))==&lda?oa0:ob0)), \
;         (unsigned*)((char*)(P)+t5*16+_i*8192),16,0,0);}}while(0)
;   #define LDA(dst,b,h) for(int m=0;m<4;++m)for(int k=0;k<2;++k) \
;     dst[m][k]=*reinterpret_cast<const h8*>(la+(((b)*2+(h))*16384+m*2048+k*1024))
;   #define LDB(dst,b,h) for(int n=0;n<2;++n)for(int k=0;k<2;++k) \
;     dst[n][k]=*reinterpret_cast<const h8*>(lb+(((b)*2+(h))*16384+n*2048+k*1024))
;   #define MMA(ai,bj,At,Bt_) do{__builtin_amdgcn_s_setprio(1); \
;     for(int m=0;m<4;++m)for(int n=0;n<2;++n)for(int k=0;k<2;++k) \
;       acc[ai][bj][m][n]=__builtin_amdgcn_mfma_f32_16x16x32_f16(At[m][k],Bt_[n][k],acc[ai][bj][m][n],0,0,0); \
;     __builtin_amdgcn_s_setprio(0);}while(0)
;   #define WAIT_L(n) asm volatile("s_waitcnt lgkmcnt(" #n ")":::"memory")
;   #define BAR __builtin_amdgcn_s_barrier()
;   #define SCHED __builtin_amdgcn_sched_barrier(0)
;     ...
;     LDB(B0,0,0); SCHED; LDA(At,0,0); STAGE(SA(1,1),A,lda,G_HALF,t+1);
;     WAIT_L(8); BAR; WAIT_L(0); MMA(0,0,At,B0); BAR; SCHED;
;     LDB(B1,0,1); STAGE(SB(0,0),Bt,ldb,0,t+2);
;     BAR; WAIT_L(0); MMA(0,1,At,B1); BAR;
;     LDA(At,0,1); STAGE(SA(0,0),A,lda,0,t+2);
;     BAR; WAIT_L(0); MMA(1,0,At,B0); BAR; SCHED;
.LBB0_279:
	ds_read_b128 v[158:161], v133
	ds_read_b128 v[162:165], v133 offset:1024
	ds_read_b128 v[186:189], v133 offset:2048
	ds_read_b128 v[190:193], v133 offset:3072
	v_add_u32_e32 v148, 0xc000, v136
	v_lshl_add_u64 v[150:151], s[6:7], 0, v[128:129]
	v_readfirstlane_b32 s13, v148
	v_add_u32_e32 v149, 0xe000, v136
	v_lshl_add_u64 v[166:167], v[150:151], 0, s[88:89]
	s_mov_b32 m0, s13
	v_readfirstlane_b32 s13, v149
	ds_read_b128 v[194:197], v132
	ds_read_b128 v[198:201], v132 offset:1024
	ds_read_b128 v[202:205], v132 offset:2048
	ds_read_b128 v[206:209], v132 offset:3072
	ds_read_b128 v[210:213], v132 offset:4096
	ds_read_b128 v[214:217], v132 offset:5120
	ds_read_b128 v[218:221], v132 offset:6144
	ds_read_b128 v[222:225], v132 offset:7168
	global_load_lds_dwordx4 v[166:167], off
	v_lshl_add_u64 v[166:167], v[150:151], 0, s[90:91]
	s_mov_b32 m0, s13
	s_nop 0
	global_load_lds_dwordx4 v[166:167], off
	s_waitcnt lgkmcnt(8)
	s_barrier
	s_waitcnt lgkmcnt(0)
	s_waitcnt lgkmcnt(0)
	v_mfma_f32_16x16x32_f16 v[124:127], v[194:197], v[158:161], v[124:127]
	v_mfma_f32_16x16x32_f16 v[120:123], v[194:197], v[186:189], v[120:123]
	v_mfma_f32_16x16x32_f16 v[116:119], v[202:205], v[158:161], v[116:119]
	v_mfma_f32_16x16x32_f16 v[112:115], v[202:205], v[186:189], v[112:115]
	v_mfma_f32_16x16x32_f16 v[108:111], v[210:213], v[158:161], v[108:111]
	v_mfma_f32_16x16x32_f16 v[104:107], v[210:213], v[186:189], v[104:107]
	v_mfma_f32_16x16x32_f16 v[100:103], v[218:221], v[158:161], v[100:103]
	v_mfma_f32_16x16x32_f16 v[96:99], v[218:221], v[186:189], v[96:99]
	v_mfma_f32_16x16x32_f16 v[124:127], v[198:201], v[162:165], v[124:127]
	v_mfma_f32_16x16x32_f16 v[120:123], v[198:201], v[190:193], v[120:123]
	v_mfma_f32_16x16x32_f16 v[116:119], v[206:209], v[162:165], v[116:119]
	v_mfma_f32_16x16x32_f16 v[112:115], v[206:209], v[190:193], v[112:115]
	v_mfma_f32_16x16x32_f16 v[108:111], v[214:217], v[162:165], v[108:111]
	v_mfma_f32_16x16x32_f16 v[104:107], v[214:217], v[190:193], v[104:107]
	v_mfma_f32_16x16x32_f16 v[100:103], v[222:225], v[162:165], v[100:103]
	v_mfma_f32_16x16x32_f16 v[96:99], v[222:225], v[190:193], v[96:99]
	s_barrier
	v_lshl_add_u64 v[166:167], s[2:3], 0, v[128:129]
	v_readfirstlane_b32 s13, v134
	v_lshl_add_u64 v[168:169], v[166:167], 0, s[36:37]
	s_mov_b32 m0, s13
	v_readfirstlane_b32 s13, v135
	ds_read_b128 v[226:229], v133 offset:16384
	ds_read_b128 v[230:233], v133 offset:17408
	ds_read_b128 v[234:237], v133 offset:18432
	ds_read_b128 v[238:241], v133 offset:19456
	global_load_lds_dwordx4 v[168:169], off
	v_lshl_add_u64 v[168:169], v[166:167], 0, s[54:55]
	s_mov_b32 m0, s13
	s_nop 0
	global_load_lds_dwordx4 v[168:169], off
	s_barrier
	s_waitcnt lgkmcnt(0)
	s_waitcnt lgkmcnt(0)
	v_mfma_f32_16x16x32_f16 v[92:95], v[194:197], v[226:229], v[92:95]
	v_mfma_f32_16x16x32_f16 v[88:91], v[194:197], v[234:237], v[88:91]
	v_mfma_f32_16x16x32_f16 v[84:87], v[202:205], v[226:229], v[84:87]
	v_mfma_f32_16x16x32_f16 v[80:83], v[202:205], v[234:237], v[80:83]
	v_mfma_f32_16x16x32_f16 v[76:79], v[210:213], v[226:229], v[76:79]
	v_mfma_f32_16x16x32_f16 v[72:75], v[210:213], v[234:237], v[72:75]
	v_mfma_f32_16x16x32_f16 v[68:71], v[218:221], v[226:229], v[68:71]
	v_mfma_f32_16x16x32_f16 v[64:67], v[218:221], v[234:237], v[64:67]
	v_mfma_f32_16x16x32_f16 v[92:95], v[198:201], v[230:233], v[92:95]
	v_mfma_f32_16x16x32_f16 v[88:91], v[198:201], v[238:241], v[88:91]
	v_mfma_f32_16x16x32_f16 v[84:87], v[206:209], v[230:233], v[84:87]
	v_mfma_f32_16x16x32_f16 v[80:83], v[206:209], v[238:241], v[80:83]
	v_mfma_f32_16x16x32_f16 v[76:79], v[214:217], v[230:233], v[76:79]
	v_mfma_f32_16x16x32_f16 v[72:75], v[214:217], v[238:241], v[72:75]
	v_mfma_f32_16x16x32_f16 v[68:71], v[222:225], v[230:233], v[68:71]
	v_mfma_f32_16x16x32_f16 v[64:67], v[222:225], v[238:241], v[64:67]
	v_readfirstlane_b32 s13, v136
	v_lshl_add_u64 v[168:169], v[150:151], 0, s[92:93]
	s_mov_b32 m0, s13
	v_readfirstlane_b32 s13, v137
	s_barrier
	ds_read_b128 v[194:197], v132 offset:16384
	ds_read_b128 v[198:201], v132 offset:17408
	ds_read_b128 v[202:205], v132 offset:18432
	ds_read_b128 v[206:209], v132 offset:19456
	ds_read_b128 v[210:213], v132 offset:20480
	ds_read_b128 v[214:217], v132 offset:21504
	ds_read_b128 v[218:221], v132 offset:22528
	ds_read_b128 v[222:225], v132 offset:23552
	global_load_lds_dwordx4 v[168:169], off
	v_lshl_add_u64 v[168:169], v[150:151], 0, s[66:67]
	s_mov_b32 m0, s13
	s_nop 0
	global_load_lds_dwordx4 v[168:169], off
	s_barrier
	s_waitcnt lgkmcnt(0)
	s_waitcnt lgkmcnt(0)
	v_mfma_f32_16x16x32_f16 v[60:63], v[194:197], v[158:161], v[60:63]
	v_mfma_f32_16x16x32_f16 v[56:59], v[194:197], v[186:189], v[56:59]
	v_mfma_f32_16x16x32_f16 v[52:55], v[202:205], v[158:161], v[52:55]
	v_mfma_f32_16x16x32_f16 v[48:51], v[202:205], v[186:189], v[48:51]
	v_mfma_f32_16x16x32_f16 v[44:47], v[210:213], v[158:161], v[44:47]
	v_mfma_f32_16x16x32_f16 v[40:43], v[210:213], v[186:189], v[40:43]
	v_mfma_f32_16x16x32_f16 v[36:39], v[218:221], v[158:161], v[36:39]
	v_mfma_f32_16x16x32_f16 v[32:35], v[218:221], v[186:189], v[32:35]
	v_mfma_f32_16x16x32_f16 v[60:63], v[198:201], v[162:165], v[60:63]
	v_mfma_f32_16x16x32_f16 v[56:59], v[198:201], v[190:193], v[56:59]
	v_mfma_f32_16x16x32_f16 v[52:55], v[206:209], v[162:165], v[52:55]
	v_mfma_f32_16x16x32_f16 v[48:51], v[206:209], v[190:193], v[48:51]
	v_mfma_f32_16x16x32_f16 v[44:47], v[214:217], v[162:165], v[44:47]
	v_mfma_f32_16x16x32_f16 v[40:43], v[214:217], v[190:193], v[40:43]
	v_mfma_f32_16x16x32_f16 v[36:39], v[222:225], v[162:165], v[36:39]
	v_mfma_f32_16x16x32_f16 v[32:35], v[222:225], v[190:193], v[32:35]
	s_barrier
;   #define STAGE(P,BASE,LD,br,kt) do{ const HALF* _u=(BASE)+(long)(br)*(((&(LD))==&lda)?lda_u:(LD))+(long)(kt)*G_BK; \
;     for(int _i=0;_i<2;++_i){ \
;       __builtin_amdgcn_global_load_lds((const unsigned*)(_u+(long)_i*(((&(LD))==&lda)?stepa:stepb)+((&(LD))==&lda?oa0:ob0)), \
;         (unsigned*)((char*)(P)+t5*16+_i*8192),16,0,0);}}while(0)
;   #define LDA(dst,b,h) for(int m=0;m<4;++m)for(int k=0;k<2;++k) \
;     dst[m][k]=*reinterpret_cast<const h8*>(la+(((b)*2+(h))*16384+m*2048+k*1024))
;   #define LDB(dst,b,h) for(int n=0;n<2;++n)for(int k=0;k<2;++k) \
;     dst[n][k]=*reinterpret_cast<const h8*>(lb+(((b)*2+(h))*16384+n*2048+k*1024))
;   #define MMA(ai,bj,At,Bt_) do{__builtin_amdgcn_s_setprio(1); \
;     for(int m=0;m<4;++m)for(int n=0;n<2;++n)for(int k=0;k<2;++k) \
;       acc[ai][bj][m][n]=__builtin_amdgcn_mfma_f32_16x16x32_f16(At[m][k],Bt_[n][k],acc[ai][bj][m][n],0,0,0); \
;     __builtin_amdgcn_s_setprio(0);}while(0)
;   #define WAIT_V(n) asm volatile("s_waitcnt vmcnt(" #n ")":::"memory")
;   #define WAIT_L(n) asm volatile("s_waitcnt lgkmcnt(" #n ")":::"memory")
;   #define BAR __builtin_amdgcn_s_barrier()
;   #define SCHED __builtin_amdgcn_sched_barrier(0)
;     ...
;     STAGE(SB(0,1),Bt,ldb,G_HALF,t+2);
;     WAIT_V(6); BAR; MMA(1,1,At,B1); BAR;
;     LDB(B0,1,0); SCHED; LDA(At,1,0); STAGE(SA(0,1),A,lda,G_HALF,t+2);
;     WAIT_L(8); BAR; WAIT_L(0); MMA(0,0,At,B0); BAR; SCHED;
;     LDB(B1,1,1); STAGE(SB(1,0),Bt,ldb,0,t+3);
;     BAR; WAIT_L(0); MMA(0,1,At,B1); BAR;
;     LDA(At,1,1); STAGE(SA(1,0),A,lda,0,t+3);
	v_readfirstlane_b32 s13, v138
	v_lshl_add_u64 v[158:159], v[166:167], 0, s[24:25]
	s_mov_b32 m0, s13
	v_readfirstlane_b32 s13, v139
	global_load_lds_dwordx4 v[158:159], off
	v_lshl_add_u64 v[158:159], v[166:167], 0, s[48:49]
	s_mov_b32 m0, s13
	s_nop 0
	global_load_lds_dwordx4 v[158:159], off
	s_waitcnt vmcnt(6)
	s_barrier
	v_mfma_f32_16x16x32_f16 v[28:31], v[194:197], v[226:229], v[28:31]
	v_mfma_f32_16x16x32_f16 v[24:27], v[194:197], v[234:237], v[24:27]
	v_mfma_f32_16x16x32_f16 v[20:23], v[202:205], v[226:229], v[20:23]
	v_mfma_f32_16x16x32_f16 v[16:19], v[202:205], v[234:237], v[16:19]
	v_mfma_f32_16x16x32_f16 v[12:15], v[210:213], v[226:229], v[12:15]
	v_mfma_f32_16x16x32_f16 v[8:11], v[210:213], v[234:237], v[8:11]
	v_mfma_f32_16x16x32_f16 v[4:7], v[218:221], v[226:229], v[4:7]
	v_mfma_f32_16x16x32_f16 v[0:3], v[218:221], v[234:237], v[0:3]
	v_mfma_f32_16x16x32_f16 v[28:31], v[198:201], v[230:233], v[28:31]
	v_mfma_f32_16x16x32_f16 v[24:27], v[198:201], v[238:241], v[24:27]
	v_mfma_f32_16x16x32_f16 v[20:23], v[206:209], v[230:233], v[20:23]
	v_mfma_f32_16x16x32_f16 v[16:19], v[206:209], v[238:241], v[16:19]
	v_mfma_f32_16x16x32_f16 v[12:15], v[214:217], v[230:233], v[12:15]
	v_mfma_f32_16x16x32_f16 v[8:11], v[214:217], v[238:241], v[8:11]
	v_mfma_f32_16x16x32_f16 v[4:7], v[222:225], v[230:233], v[4:7]
	v_mfma_f32_16x16x32_f16 v[0:3], v[222:225], v[238:241], v[0:3]
	s_barrier
	ds_read_b128 v[158:161], v133 offset:32768
	ds_read_b128 v[162:165], v133 offset:33792
	ds_read_b128 v[186:189], v133 offset:34816
	ds_read_b128 v[190:193], v133 offset:35840
	v_readfirstlane_b32 s13, v140
	v_lshl_add_u64 v[168:169], v[150:151], 0, s[38:39]
	s_mov_b32 m0, s13
	v_readfirstlane_b32 s13, v141
	ds_read_b128 v[194:197], v132 offset:32768
	ds_read_b128 v[198:201], v132 offset:33792
	ds_read_b128 v[202:205], v132 offset:34816
	ds_read_b128 v[206:209], v132 offset:35840
	ds_read_b128 v[210:213], v132 offset:36864
	ds_read_b128 v[214:217], v132 offset:37888
	ds_read_b128 v[218:221], v132 offset:38912
	ds_read_b128 v[222:225], v132 offset:39936
	global_load_lds_dwordx4 v[168:169], off
	v_lshl_add_u64 v[168:169], v[150:151], 0, s[40:41]
	s_mov_b32 m0, s13
	s_nop 0
	global_load_lds_dwordx4 v[168:169], off
	s_waitcnt lgkmcnt(8)
	s_barrier
	s_waitcnt lgkmcnt(0)
	s_waitcnt lgkmcnt(0)
	v_mfma_f32_16x16x32_f16 v[124:127], v[194:197], v[158:161], v[124:127]
	v_mfma_f32_16x16x32_f16 v[120:123], v[194:197], v[186:189], v[120:123]
	v_mfma_f32_16x16x32_f16 v[116:119], v[202:205], v[158:161], v[116:119]
	v_mfma_f32_16x16x32_f16 v[112:115], v[202:205], v[186:189], v[112:115]
	v_mfma_f32_16x16x32_f16 v[108:111], v[210:213], v[158:161], v[108:111]
	v_mfma_f32_16x16x32_f16 v[104:107], v[210:213], v[186:189], v[104:107]
	v_mfma_f32_16x16x32_f16 v[100:103], v[218:221], v[158:161], v[100:103]
	v_mfma_f32_16x16x32_f16 v[96:99], v[218:221], v[186:189], v[96:99]
	v_mfma_f32_16x16x32_f16 v[124:127], v[198:201], v[162:165], v[124:127]
	v_mfma_f32_16x16x32_f16 v[120:123], v[198:201], v[190:193], v[120:123]
	v_mfma_f32_16x16x32_f16 v[116:119], v[206:209], v[162:165], v[116:119]
	v_mfma_f32_16x16x32_f16 v[112:115], v[206:209], v[190:193], v[112:115]
	v_mfma_f32_16x16x32_f16 v[108:111], v[214:217], v[162:165], v[108:111]
	v_mfma_f32_16x16x32_f16 v[104:107], v[214:217], v[190:193], v[104:107]
	v_mfma_f32_16x16x32_f16 v[100:103], v[222:225], v[162:165], v[100:103]
	v_mfma_f32_16x16x32_f16 v[96:99], v[222:225], v[190:193], v[96:99]
	s_barrier
	v_readfirstlane_b32 s13, v142
	v_lshl_add_u64 v[168:169], v[166:167], 0, s[60:61]
	s_mov_b32 m0, s13
	v_readfirstlane_b32 s13, v143
	ds_read_b128 v[226:229], v133 offset:49152
	ds_read_b128 v[230:233], v133 offset:50176
	ds_read_b128 v[234:237], v133 offset:51200
	ds_read_b128 v[238:241], v133 offset:52224
	global_load_lds_dwordx4 v[168:169], off
	v_lshl_add_u64 v[168:169], v[166:167], 0, s[26:27]
	s_mov_b32 m0, s13
	s_nop 0
	global_load_lds_dwordx4 v[168:169], off
	s_barrier
	s_waitcnt lgkmcnt(0)
	s_waitcnt lgkmcnt(0)
	v_mfma_f32_16x16x32_f16 v[92:95], v[194:197], v[226:229], v[92:95]
	v_mfma_f32_16x16x32_f16 v[88:91], v[194:197], v[234:237], v[88:91]
	v_mfma_f32_16x16x32_f16 v[84:87], v[202:205], v[226:229], v[84:87]
	v_mfma_f32_16x16x32_f16 v[80:83], v[202:205], v[234:237], v[80:83]
	v_mfma_f32_16x16x32_f16 v[76:79], v[210:213], v[226:229], v[76:79]
	v_mfma_f32_16x16x32_f16 v[72:75], v[210:213], v[234:237], v[72:75]
	v_mfma_f32_16x16x32_f16 v[68:71], v[218:221], v[226:229], v[68:71]
	v_mfma_f32_16x16x32_f16 v[64:67], v[218:221], v[234:237], v[64:67]
	v_mfma_f32_16x16x32_f16 v[92:95], v[198:201], v[230:233], v[92:95]
	v_mfma_f32_16x16x32_f16 v[88:91], v[198:201], v[238:241], v[88:91]
	v_mfma_f32_16x16x32_f16 v[84:87], v[206:209], v[230:233], v[84:87]
	v_mfma_f32_16x16x32_f16 v[80:83], v[206:209], v[238:241], v[80:83]
	v_mfma_f32_16x16x32_f16 v[76:79], v[214:217], v[230:233], v[76:79]
	v_mfma_f32_16x16x32_f16 v[72:75], v[214:217], v[238:241], v[72:75]
	v_mfma_f32_16x16x32_f16 v[68:71], v[222:225], v[230:233], v[68:71]
	v_mfma_f32_16x16x32_f16 v[64:67], v[222:225], v[238:241], v[64:67]
	v_readfirstlane_b32 s13, v144
	v_lshl_add_u64 v[168:169], v[150:151], 0, s[42:43]
	s_mov_b32 m0, s13
	v_readfirstlane_b32 s13, v145
	s_barrier
	ds_read_b128 v[194:197], v132 offset:49152
	ds_read_b128 v[198:201], v132 offset:50176
	ds_read_b128 v[202:205], v132 offset:51200
	ds_read_b128 v[206:209], v132 offset:52224
	ds_read_b128 v[210:213], v132 offset:53248
	ds_read_b128 v[214:217], v132 offset:54272
	ds_read_b128 v[218:221], v132 offset:55296
	ds_read_b128 v[222:225], v132 offset:56320
	global_load_lds_dwordx4 v[168:169], off
	v_lshl_add_u64 v[150:151], v[150:151], 0, s[96:97]
	s_mov_b32 m0, s13
	s_nop 0
	global_load_lds_dwordx4 v[150:151], off
	s_barrier
;   #define STAGE(P,BASE,LD,br,kt) do{ const HALF* _u=(BASE)+(long)(br)*(((&(LD))==&lda)?lda_u:(LD))+(long)(kt)*G_BK; \
;     for(int _i=0;_i<2;++_i){ \
;       __builtin_amdgcn_global_load_lds((const unsigned*)(_u+(long)_i*(((&(LD))==&lda)?stepa:stepb)+((&(LD))==&lda?oa0:ob0)), \
;         (unsigned*)((char*)(P)+t5*16+_i*8192),16,0,0);}}while(0)
;   #define LDA(dst,b,h) for(int m=0;m<4;++m)for(int k=0;k<2;++k) \
;     dst[m][k]=*reinterpret_cast<const h8*>(la+(((b)*2+(h))*16384+m*2048+k*1024))
;   #define LDB(dst,b,h) for(int n=0;n<2;++n)for(int k=0;k<2;++k) \
;     dst[n][k]=*reinterpret_cast<const h8*>(lb+(((b)*2+(h))*16384+n*2048+k*1024))
;   #define MMA(ai,bj,At,Bt_) do{__builtin_amdgcn_s_setprio(1); \
;     for(int m=0;m<4;++m)for(int n=0;n<2;++n)for(int k=0;k<2;++k) \
;       acc[ai][bj][m][n]=__builtin_amdgcn_mfma_f32_16x16x32_f16(At[m][k],Bt_[n][k],acc[ai][bj][m][n],0,0,0); \
;     __builtin_amdgcn_s_setprio(0);}while(0)
;   #define WAIT_V(n) asm volatile("s_waitcnt vmcnt(" #n ")":::"memory")
;   #define WAIT_L(n) asm volatile("s_waitcnt lgkmcnt(" #n ")":::"memory")
;   #define BAR __builtin_amdgcn_s_barrier()
;   #define SCHED __builtin_amdgcn_sched_barrier(0)
;     ...
;     BAR; WAIT_L(0); MMA(1,0,At,B0); BAR; SCHED;
;     STAGE(SB(1,1),Bt,ldb,G_HALF,t+3);
;     WAIT_V(6); BAR; MMA(1,1,At,B1); BAR;
;   }
;   { LDB(B0,0,0); LDA(At,0,0); STAGE(SA(1,1),A,lda,G_HALF,nt-1);
;     BAR; WAIT_L(0); MMA(0,0,At,B0); BAR;
;     LDB(B1,0,1); BAR; WAIT_L(0); MMA(0,1,At,B1); BAR;
	s_waitcnt lgkmcnt(0)
	s_waitcnt lgkmcnt(0)
	v_mfma_f32_16x16x32_f16 v[60:63], v[194:197], v[158:161], v[60:63]
	v_mfma_f32_16x16x32_f16 v[56:59], v[194:197], v[186:189], v[56:59]
	v_mfma_f32_16x16x32_f16 v[52:55], v[202:205], v[158:161], v[52:55]
	v_mfma_f32_16x16x32_f16 v[48:51], v[202:205], v[186:189], v[48:51]
	v_mfma_f32_16x16x32_f16 v[44:47], v[210:213], v[158:161], v[44:47]
	v_mfma_f32_16x16x32_f16 v[40:43], v[210:213], v[186:189], v[40:43]
	v_mfma_f32_16x16x32_f16 v[36:39], v[218:221], v[158:161], v[36:39]
	v_mfma_f32_16x16x32_f16 v[32:35], v[218:221], v[186:189], v[32:35]
	v_mfma_f32_16x16x32_f16 v[60:63], v[198:201], v[162:165], v[60:63]
	v_mfma_f32_16x16x32_f16 v[56:59], v[198:201], v[190:193], v[56:59]
	v_mfma_f32_16x16x32_f16 v[52:55], v[206:209], v[162:165], v[52:55]
	v_mfma_f32_16x16x32_f16 v[48:51], v[206:209], v[190:193], v[48:51]
	v_mfma_f32_16x16x32_f16 v[44:47], v[214:217], v[162:165], v[44:47]
	v_mfma_f32_16x16x32_f16 v[40:43], v[214:217], v[190:193], v[40:43]
	v_mfma_f32_16x16x32_f16 v[36:39], v[222:225], v[162:165], v[36:39]
	v_mfma_f32_16x16x32_f16 v[32:35], v[222:225], v[190:193], v[32:35]
	s_barrier
	v_readfirstlane_b32 s13, v146
	v_lshl_add_u64 v[150:151], v[166:167], 0, s[56:57]
	s_mov_b32 m0, s13
	v_readfirstlane_b32 s13, v147
	global_load_lds_dwordx4 v[150:151], off
	v_lshl_add_u64 v[150:151], v[166:167], 0, s[52:53]
	s_mov_b32 m0, s13
	s_nop 0
	global_load_lds_dwordx4 v[150:151], off
	s_waitcnt vmcnt(6)
	s_barrier
	v_mfma_f32_16x16x32_f16 v[28:31], v[194:197], v[226:229], v[28:31]
	v_mfma_f32_16x16x32_f16 v[24:27], v[194:197], v[234:237], v[24:27]
	v_mfma_f32_16x16x32_f16 v[20:23], v[202:205], v[226:229], v[20:23]
	v_mfma_f32_16x16x32_f16 v[16:19], v[202:205], v[234:237], v[16:19]
	v_mfma_f32_16x16x32_f16 v[12:15], v[210:213], v[226:229], v[12:15]
	v_mfma_f32_16x16x32_f16 v[8:11], v[210:213], v[234:237], v[8:11]
	v_mfma_f32_16x16x32_f16 v[4:7], v[218:221], v[226:229], v[4:7]
	v_mfma_f32_16x16x32_f16 v[0:3], v[218:221], v[234:237], v[0:3]
	v_mfma_f32_16x16x32_f16 v[28:31], v[198:201], v[230:233], v[28:31]
	v_mfma_f32_16x16x32_f16 v[24:27], v[198:201], v[238:241], v[24:27]
	v_mfma_f32_16x16x32_f16 v[20:23], v[206:209], v[230:233], v[20:23]
	v_mfma_f32_16x16x32_f16 v[16:19], v[206:209], v[238:241], v[16:19]
	v_mfma_f32_16x16x32_f16 v[12:15], v[214:217], v[230:233], v[12:15]
	v_mfma_f32_16x16x32_f16 v[8:11], v[214:217], v[238:241], v[8:11]
	v_mfma_f32_16x16x32_f16 v[4:7], v[222:225], v[230:233], v[4:7]
	v_mfma_f32_16x16x32_f16 v[0:3], v[222:225], v[238:241], v[0:3]
	s_add_i32 s12, s12, 2
	s_add_u32 s2, s2, 0x100
	s_addc_u32 s3, s3, 0
	s_add_u32 s6, s6, 0x100
	s_addc_u32 s7, s7, 0
	s_cmp_lt_u32 s12, 12
	s_barrier
	s_cbranch_scc1 .LBB0_279
	v_lshl_add_u64 v[128:129], v[152:153], 1, s[0:1]
	s_mov_b64 s[0:1], 0x40780
	v_lshl_add_u64 v[146:147], v[128:129], 0, s[0:1]
	v_readfirstlane_b32 s0, v148
	s_mov_b32 m0, s0
	s_mov_b64 s[0:1], 0x60780
	v_lshl_add_u64 v[128:129], v[128:129], 0, s[0:1]
	v_readfirstlane_b32 s0, v149
	ds_read_b128 v[134:137], v133
	ds_read_b128 v[138:141], v133 offset:1024
	ds_read_b128 v[142:145], v133 offset:2048
	ds_read_b128 v[158:161], v133 offset:3072
	ds_read_b128 v[162:165], v132
	ds_read_b128 v[186:189], v132 offset:1024
	ds_read_b128 v[190:193], v132 offset:2048
	ds_read_b128 v[194:197], v132 offset:3072
	ds_read_b128 v[198:201], v132 offset:4096
	ds_read_b128 v[202:205], v132 offset:5120
	ds_read_b128 v[206:209], v132 offset:6144
	ds_read_b128 v[210:213], v132 offset:7168
	global_load_lds_dwordx4 v[146:147], off
	s_mov_b32 m0, s0
	s_nop 0
	global_load_lds_dwordx4 v[128:129], off
	s_barrier
	s_waitcnt lgkmcnt(0)
	s_waitcnt lgkmcnt(0)
	v_mfma_f32_16x16x32_f16 v[124:127], v[162:165], v[134:137], v[124:127]
	v_mfma_f32_16x16x32_f16 v[120:123], v[162:165], v[142:145], v[120:123]
	v_mfma_f32_16x16x32_f16 v[116:119], v[190:193], v[134:137], v[116:119]
	v_mfma_f32_16x16x32_f16 v[112:115], v[190:193], v[142:145], v[112:115]
	v_mfma_f32_16x16x32_f16 v[108:111], v[198:201], v[134:137], v[108:111]
	v_mfma_f32_16x16x32_f16 v[104:107], v[198:201], v[142:145], v[104:107]
	v_mfma_f32_16x16x32_f16 v[124:127], v[186:189], v[138:141], v[124:127]
	v_mfma_f32_16x16x32_f16 v[120:123], v[186:189], v[158:161], v[120:123]
	v_mfma_f32_16x16x32_f16 v[116:119], v[194:197], v[138:141], v[116:119]
	v_mfma_f32_16x16x32_f16 v[112:115], v[194:197], v[158:161], v[112:115]
	v_mfma_f32_16x16x32_f16 v[108:111], v[202:205], v[138:141], v[108:111]
	v_mfma_f32_16x16x32_f16 v[104:107], v[202:205], v[158:161], v[104:107]
	v_mfma_f32_16x16x32_f16 v[100:103], v[206:209], v[134:137], v[100:103]
	v_mfma_f32_16x16x32_f16 v[96:99], v[206:209], v[142:145], v[96:99]
	v_mfma_f32_16x16x32_f16 v[146:149], v[210:213], v[138:141], v[100:103]
	v_mfma_f32_16x16x32_f16 v[214:217], v[210:213], v[158:161], v[96:99]
	s_barrier
	s_nop 3
	ds_read_b128 v[96:99], v133 offset:16384
	ds_read_b128 v[100:103], v133 offset:17408
	ds_read_b128 v[218:221], v133 offset:18432
	ds_read_b128 v[222:225], v133 offset:19456
	s_barrier
	s_waitcnt lgkmcnt(0)
	s_waitcnt lgkmcnt(0)
	v_mfma_f32_16x16x32_f16 v[92:95], v[162:165], v[96:99], v[92:95]
	v_mfma_f32_16x16x32_f16 v[84:87], v[190:193], v[96:99], v[84:87]
	v_mfma_f32_16x16x32_f16 v[80:83], v[190:193], v[218:221], v[80:83]
	v_mfma_f32_16x16x32_f16 v[76:79], v[198:201], v[96:99], v[76:79]
	v_mfma_f32_16x16x32_f16 v[72:75], v[198:201], v[218:221], v[72:75]
	v_mfma_f32_16x16x32_f16 v[68:71], v[206:209], v[96:99], v[68:71]
	v_mfma_f32_16x16x32_f16 v[64:67], v[206:209], v[218:221], v[64:67]
	v_mfma_f32_16x16x32_f16 v[92:95], v[186:189], v[100:103], v[92:95]
	v_mfma_f32_16x16x32_f16 v[88:91], v[162:165], v[218:221], v[88:91]
	v_mfma_f32_16x16x32_f16 v[84:87], v[194:197], v[100:103], v[84:87]
	v_mfma_f32_16x16x32_f16 v[80:83], v[194:197], v[222:225], v[80:83]
	v_mfma_f32_16x16x32_f16 v[76:79], v[202:205], v[100:103], v[76:79]
	v_mfma_f32_16x16x32_f16 v[72:75], v[202:205], v[222:225], v[72:75]
	v_mfma_f32_16x16x32_f16 v[68:71], v[210:213], v[100:103], v[68:71]
	v_mfma_f32_16x16x32_f16 v[64:67], v[210:213], v[222:225], v[64:67]
	v_mfma_f32_16x16x32_f16 v[162:165], v[186:189], v[222:225], v[88:91]
	s_barrier
;   #define LDA(dst,b,h) for(int m=0;m<4;++m)for(int k=0;k<2;++k) \
;     dst[m][k]=*reinterpret_cast<const h8*>(la+(((b)*2+(h))*16384+m*2048+k*1024))
;   #define LDB(dst,b,h) for(int n=0;n<2;++n)for(int k=0;k<2;++k) \
;     dst[n][k]=*reinterpret_cast<const h8*>(lb+(((b)*2+(h))*16384+n*2048+k*1024))
;   #define MMA(ai,bj,At,Bt_) do{__builtin_amdgcn_s_setprio(1); \
;     for(int m=0;m<4;++m)for(int n=0;n<2;++n)for(int k=0;k<2;++k) \
;       acc[ai][bj][m][n]=__builtin_amdgcn_mfma_f32_16x16x32_f16(At[m][k],Bt_[n][k],acc[ai][bj][m][n],0,0,0); \
;     __builtin_amdgcn_s_setprio(0);}while(0)
;   #define WAIT_V(n) asm volatile("s_waitcnt vmcnt(" #n ")":::"memory")
;   #define WAIT_L(n) asm volatile("s_waitcnt lgkmcnt(" #n ")":::"memory")
;   #define BAR __builtin_amdgcn_s_barrier()
;     ...
;     LDA(At,0,1); WAIT_V(4); BAR; WAIT_L(0); MMA(1,0,At,B0); MMA(1,1,At,B1); BAR; }
;   { LDB(B0,1,0); LDA(At,1,0); WAIT_V(2); BAR; WAIT_L(0); MMA(0,0,At,B0); BAR;
	s_nop 0
	ds_read_b128 v[88:91], v132 offset:16384
	ds_read_b128 v[186:189], v132 offset:17408
	ds_read_b128 v[190:193], v132 offset:18432
	ds_read_b128 v[194:197], v132 offset:19456
	ds_read_b128 v[198:201], v132 offset:20480
	ds_read_b128 v[202:205], v132 offset:21504
	ds_read_b128 v[206:209], v132 offset:22528
	ds_read_b128 v[210:213], v132 offset:23552
	s_waitcnt vmcnt(4)
	s_barrier
	s_waitcnt lgkmcnt(0)
	s_waitcnt lgkmcnt(0)
	v_mfma_f32_16x16x32_f16 v[56:59], v[88:91], v[142:145], v[56:59]
	v_mfma_f32_16x16x32_f16 v[48:51], v[190:193], v[142:145], v[48:51]
	v_mfma_f32_16x16x32_f16 v[44:47], v[198:201], v[134:137], v[44:47]
	v_mfma_f32_16x16x32_f16 v[40:43], v[198:201], v[142:145], v[40:43]
	v_mfma_f32_16x16x32_f16 v[36:39], v[206:209], v[134:137], v[36:39]
	v_mfma_f32_16x16x32_f16 v[32:35], v[206:209], v[142:145], v[32:35]
	v_mfma_f32_16x16x32_f16 v[60:63], v[88:91], v[134:137], v[60:63]
	v_mfma_f32_16x16x32_f16 v[56:59], v[186:189], v[158:161], v[56:59]
	v_mfma_f32_16x16x32_f16 v[52:55], v[190:193], v[134:137], v[52:55]
	v_mfma_f32_16x16x32_f16 v[48:51], v[194:197], v[158:161], v[48:51]
	v_mfma_f32_16x16x32_f16 v[44:47], v[202:205], v[138:141], v[44:47]
	v_mfma_f32_16x16x32_f16 v[40:43], v[202:205], v[158:161], v[40:43]
	v_mfma_f32_16x16x32_f16 v[36:39], v[210:213], v[138:141], v[36:39]
	v_mfma_f32_16x16x32_f16 v[32:35], v[210:213], v[158:161], v[32:35]
	v_mfma_f32_16x16x32_f16 v[226:229], v[186:189], v[138:141], v[60:63]
	v_mfma_f32_16x16x32_f16 v[230:233], v[194:197], v[138:141], v[52:55]
	v_mfma_f32_16x16x32_f16 v[28:31], v[88:91], v[96:99], v[28:31]
	v_mfma_f32_16x16x32_f16 v[24:27], v[88:91], v[218:221], v[24:27]
	v_mfma_f32_16x16x32_f16 v[20:23], v[190:193], v[96:99], v[20:23]
	v_mfma_f32_16x16x32_f16 v[16:19], v[190:193], v[218:221], v[16:19]
	v_mfma_f32_16x16x32_f16 v[12:15], v[198:201], v[96:99], v[12:15]
	v_mfma_f32_16x16x32_f16 v[8:11], v[198:201], v[218:221], v[8:11]
	v_mfma_f32_16x16x32_f16 v[4:7], v[206:209], v[96:99], v[4:7]
	v_mfma_f32_16x16x32_f16 v[0:3], v[206:209], v[218:221], v[0:3]
	v_mfma_f32_16x16x32_f16 v[28:31], v[186:189], v[100:103], v[28:31]
	v_mfma_f32_16x16x32_f16 v[24:27], v[186:189], v[222:225], v[24:27]
	v_mfma_f32_16x16x32_f16 v[20:23], v[194:197], v[100:103], v[20:23]
	v_mfma_f32_16x16x32_f16 v[16:19], v[194:197], v[222:225], v[16:19]
	v_mfma_f32_16x16x32_f16 v[12:15], v[202:205], v[100:103], v[12:15]
	v_mfma_f32_16x16x32_f16 v[8:11], v[202:205], v[222:225], v[8:11]
	v_mfma_f32_16x16x32_f16 v[4:7], v[210:213], v[100:103], v[4:7]
	v_mfma_f32_16x16x32_f16 v[0:3], v[210:213], v[222:225], v[0:3]
	s_barrier
	ds_read_b128 v[134:137], v133 offset:32768
	ds_read_b128 v[138:141], v133 offset:33792
	ds_read_b128 v[142:145], v133 offset:34816
	ds_read_b128 v[158:161], v133 offset:35840
	ds_read_b128 v[52:55], v132 offset:32768
	ds_read_b128 v[60:63], v132 offset:33792
	ds_read_b128 v[186:189], v132 offset:34816
	ds_read_b128 v[190:193], v132 offset:35840
	ds_read_b128 v[194:197], v132 offset:36864
	ds_read_b128 v[198:201], v132 offset:37888
	ds_read_b128 v[202:205], v132 offset:38912
	ds_read_b128 v[206:209], v132 offset:39936
	s_waitcnt vmcnt(2)
	s_barrier
	s_waitcnt lgkmcnt(0)
	s_waitcnt lgkmcnt(0)
	v_mfma_f32_16x16x32_f16 v[88:91], v[52:55], v[134:137], v[124:127]
	v_mfma_f32_16x16x32_f16 v[124:127], v[60:63], v[138:141], v[88:91]
	v_mfma_f32_16x16x32_f16 v[88:91], v[52:55], v[142:145], v[120:123]
	v_mfma_f32_16x16x32_f16 v[120:123], v[60:63], v[158:161], v[88:91]
	v_mfma_f32_16x16x32_f16 v[88:91], v[186:189], v[134:137], v[116:119]
	v_mfma_f32_16x16x32_f16 v[116:119], v[190:193], v[138:141], v[88:91]
	v_mfma_f32_16x16x32_f16 v[88:91], v[186:189], v[142:145], v[112:115]
	v_mfma_f32_16x16x32_f16 v[112:115], v[190:193], v[158:161], v[88:91]
	v_mfma_f32_16x16x32_f16 v[88:91], v[194:197], v[134:137], v[108:111]
	v_mfma_f32_16x16x32_f16 v[108:111], v[198:201], v[138:141], v[88:91]
	v_mfma_f32_16x16x32_f16 v[88:91], v[194:197], v[142:145], v[104:107]
	v_mfma_f32_16x16x32_f16 v[100:103], v[198:201], v[158:161], v[88:91]
	v_mfma_f32_16x16x32_f16 v[88:91], v[202:205], v[134:137], v[146:149]
	v_mfma_f32_16x16x32_f16 v[96:99], v[206:209], v[138:141], v[88:91]
	v_mfma_f32_16x16x32_f16 v[88:91], v[202:205], v[142:145], v[214:217]
	v_mfma_f32_16x16x32_f16 v[88:91], v[206:209], v[158:161], v[88:91]
	s_barrier
;   #define LDA(dst,b,h) for(int m=0;m<4;++m)for(int k=0;k<2;++k) \
;     dst[m][k]=*reinterpret_cast<const h8*>(la+(((b)*2+(h))*16384+m*2048+k*1024))
;   #define LDB(dst,b,h) for(int n=0;n<2;++n)for(int k=0;k<2;++k) \
;     dst[n][k]=*reinterpret_cast<const h8*>(lb+(((b)*2+(h))*16384+n*2048+k*1024))
;   #define MMA(ai,bj,At,Bt_) do{__builtin_amdgcn_s_setprio(1); \
;     for(int m=0;m<4;++m)for(int n=0;n<2;++n)for(int k=0;k<2;++k) \
;       acc[ai][bj][m][n]=__builtin_amdgcn_mfma_f32_16x16x32_f16(At[m][k],Bt_[n][k],acc[ai][bj][m][n],0,0,0); \
;     __builtin_amdgcn_s_setprio(0);}while(0)
;   #define WAIT_V(n) asm volatile("s_waitcnt vmcnt(" #n ")":::"memory")
;   #define WAIT_L(n) asm volatile("s_waitcnt lgkmcnt(" #n ")":::"memory")
;   #define BAR __builtin_amdgcn_s_barrier()
;     ...
;     LDB(B1,1,1); WAIT_V(0); BAR; WAIT_L(0); MMA(0,1,At,B1); BAR;
;     LDA(At,1,1); BAR; WAIT_L(0); MMA(1,0,At,B0); MMA(1,1,At,B1); BAR; }
;   if(wr==0)BAR;
	ds_read_b128 v[146:149], v133 offset:49152
	ds_read_b128 v[210:213], v133 offset:50176
	ds_read_b128 v[214:217], v133 offset:51200
	ds_read_b128 v[218:221], v133 offset:52224
	s_waitcnt vmcnt(0)
	s_barrier
	s_waitcnt lgkmcnt(0)
	s_waitcnt lgkmcnt(0)
	v_mfma_f32_16x16x32_f16 v[92:95], v[52:55], v[146:149], v[92:95]
	v_mfma_f32_16x16x32_f16 v[52:55], v[52:55], v[214:217], v[162:165]
	v_mfma_f32_16x16x32_f16 v[104:107], v[60:63], v[210:213], v[92:95]
	v_mfma_f32_16x16x32_f16 v[92:95], v[60:63], v[218:221], v[52:55]
	v_mfma_f32_16x16x32_f16 v[52:55], v[186:189], v[146:149], v[84:87]
	v_mfma_f32_16x16x32_f16 v[84:87], v[190:193], v[210:213], v[52:55]
	v_mfma_f32_16x16x32_f16 v[52:55], v[186:189], v[214:217], v[80:83]
	v_mfma_f32_16x16x32_f16 v[80:83], v[190:193], v[218:221], v[52:55]
	v_mfma_f32_16x16x32_f16 v[52:55], v[194:197], v[146:149], v[76:79]
	v_mfma_f32_16x16x32_f16 v[76:79], v[198:201], v[210:213], v[52:55]
	v_mfma_f32_16x16x32_f16 v[52:55], v[194:197], v[214:217], v[72:75]
	v_mfma_f32_16x16x32_f16 v[72:75], v[198:201], v[218:221], v[52:55]
	v_mfma_f32_16x16x32_f16 v[52:55], v[202:205], v[146:149], v[68:71]
	v_mfma_f32_16x16x32_f16 v[60:63], v[206:209], v[210:213], v[52:55]
	v_mfma_f32_16x16x32_f16 v[52:55], v[202:205], v[214:217], v[64:67]
	v_mfma_f32_16x16x32_f16 v[52:55], v[206:209], v[218:221], v[52:55]
	s_barrier
	ds_read_b128 v[162:165], v132 offset:49152
	ds_read_b128 v[186:189], v132 offset:50176
	ds_read_b128 v[190:193], v132 offset:51200
	ds_read_b128 v[194:197], v132 offset:52224
	ds_read_b128 v[198:201], v132 offset:53248
	ds_read_b128 v[202:205], v132 offset:54272
	ds_read_b128 v[206:209], v132 offset:55296
	ds_read_b128 v[222:225], v132 offset:56320
	s_barrier
	s_waitcnt lgkmcnt(0)
	s_waitcnt lgkmcnt(0)
	v_mfma_f32_16x16x32_f16 v[64:67], v[162:165], v[134:137], v[226:229]
	v_mfma_f32_16x16x32_f16 v[56:59], v[162:165], v[142:145], v[56:59]
	v_mfma_f32_16x16x32_f16 v[68:71], v[186:189], v[138:141], v[64:67]
	v_mfma_f32_16x16x32_f16 v[64:67], v[186:189], v[158:161], v[56:59]
	v_mfma_f32_16x16x32_f16 v[56:59], v[190:193], v[134:137], v[230:233]
	v_mfma_f32_16x16x32_f16 v[48:51], v[190:193], v[142:145], v[48:51]
	v_mfma_f32_16x16x32_f16 v[44:47], v[198:201], v[134:137], v[44:47]
	v_mfma_f32_16x16x32_f16 v[40:43], v[198:201], v[142:145], v[40:43]
	v_mfma_f32_16x16x32_f16 v[36:39], v[206:209], v[134:137], v[36:39]
	v_mfma_f32_16x16x32_f16 v[32:35], v[206:209], v[142:145], v[32:35]
	v_mfma_f32_16x16x32_f16 v[56:59], v[194:197], v[138:141], v[56:59]
	v_mfma_f32_16x16x32_f16 v[48:51], v[194:197], v[158:161], v[48:51]
	v_mfma_f32_16x16x32_f16 v[44:47], v[202:205], v[138:141], v[44:47]
	v_mfma_f32_16x16x32_f16 v[40:43], v[202:205], v[158:161], v[40:43]
	v_mfma_f32_16x16x32_f16 v[36:39], v[222:225], v[138:141], v[36:39]
	v_mfma_f32_16x16x32_f16 v[32:35], v[222:225], v[158:161], v[32:35]
	v_mfma_f32_16x16x32_f16 v[28:31], v[162:165], v[146:149], v[28:31]
	v_mfma_f32_16x16x32_f16 v[24:27], v[162:165], v[214:217], v[24:27]
	v_mfma_f32_16x16x32_f16 v[20:23], v[190:193], v[146:149], v[20:23]
	v_mfma_f32_16x16x32_f16 v[16:19], v[190:193], v[214:217], v[16:19]
	v_mfma_f32_16x16x32_f16 v[12:15], v[198:201], v[146:149], v[12:15]
	v_mfma_f32_16x16x32_f16 v[8:11], v[198:201], v[214:217], v[8:11]
	v_mfma_f32_16x16x32_f16 v[4:7], v[206:209], v[146:149], v[4:7]
	v_mfma_f32_16x16x32_f16 v[0:3], v[206:209], v[214:217], v[0:3]
	v_mfma_f32_16x16x32_f16 v[28:31], v[186:189], v[210:213], v[28:31]
	v_mfma_f32_16x16x32_f16 v[24:27], v[186:189], v[218:221], v[24:27]
	v_mfma_f32_16x16x32_f16 v[20:23], v[194:197], v[210:213], v[20:23]
	v_mfma_f32_16x16x32_f16 v[16:19], v[194:197], v[218:221], v[16:19]
	v_mfma_f32_16x16x32_f16 v[12:15], v[202:205], v[210:213], v[12:15]
	v_mfma_f32_16x16x32_f16 v[8:11], v[202:205], v[218:221], v[8:11]
	v_mfma_f32_16x16x32_f16 v[4:7], v[222:225], v[210:213], v[4:7]
	v_mfma_f32_16x16x32_f16 v[0:3], v[222:225], v[218:221], v[0:3]
	s_movk_i32 s0, 0x100
	v_cmp_gt_u32_e32 vcc, s0, v131
	s_barrier
	s_and_saveexec_b64 s[0:1], vcc
	s_cbranch_execz .LBB0_282
	s_barrier

;   #define STAGE(P,BASE,LD,br,kt) do{ const HALF* _u=(BASE)+(long)(br)*(((&(LD))==&lda)?lda_u:(LD))+(long)(kt)*G_BK; \
;     for(int _i=0;_i<2;++_i){ \
;       __builtin_amdgcn_global_load_lds((const unsigned*)(_u+(long)_i*(((&(LD))==&lda)?stepa:stepb)+((&(LD))==&lda?oa0:ob0)), \
;         (unsigned*)((char*)(P)+t5*16+_i*8192),16,0,0);}}while(0)
;   #define LDA(dst,b,h) for(int m=0;m<4;++m)for(int k=0;k<2;++k) \
;     dst[m][k]=*reinterpret_cast<const h8*>(la+(((b)*2+(h))*16384+m*2048+k*1024))
;   #define LDB(dst,b,h) for(int n=0;n<2;++n)for(int k=0;k<2;++k) \
;     dst[n][k]=*reinterpret_cast<const h8*>(lb+(((b)*2+(h))*16384+n*2048+k*1024))
;   #define MMA(ai,bj,At,Bt_) do{__builtin_amdgcn_s_setprio(1); \
;     for(int m=0;m<4;++m)for(int n=0;n<2;++n)for(int k=0;k<2;++k) \
;       acc[ai][bj][m][n]=__builtin_amdgcn_mfma_f32_16x16x32_f16(At[m][k],Bt_[n][k],acc[ai][bj][m][n],0,0,0); \
;     __builtin_amdgcn_s_setprio(0);}while(0)
;   #define WAIT_L(n) asm volatile("s_waitcnt lgkmcnt(" #n ")":::"memory")
;   #define BAR __builtin_amdgcn_s_barrier()
;   #define SCHED __builtin_amdgcn_sched_barrier(0)
;     ...
;     LDB(B0,0,0); SCHED; LDA(At,0,0); STAGE(SA(1,1),A,lda,G_HALF,t+1);
;     WAIT_L(8); BAR; WAIT_L(0); MMA(0,0,At,B0); BAR; SCHED;
;     LDB(B1,0,1); STAGE(SB(0,0),Bt,ldb,0,t+2);
;     BAR; WAIT_L(0); MMA(0,1,At,B1); BAR;
;     LDA(At,0,1); STAGE(SA(0,0),A,lda,0,t+2);
;     BAR; WAIT_L(0); MMA(1,0,At,B0); BAR; SCHED;
.LBB0_295:
	ds_read_b128 v[158:161], v133
	ds_read_b128 v[162:165], v133 offset:1024
	ds_read_b128 v[186:189], v133 offset:2048
	ds_read_b128 v[190:193], v133 offset:3072
	v_add_u32_e32 v148, 0xc000, v136
	v_lshl_add_u64 v[150:151], s[6:7], 0, v[128:129]
	v_readfirstlane_b32 s10, v148
	v_add_u32_e32 v149, 0xe000, v136
	v_lshl_add_u64 v[166:167], v[150:151], 0, s[88:89]
	s_mov_b32 m0, s10
	v_readfirstlane_b32 s10, v149
	ds_read_b128 v[194:197], v132
	ds_read_b128 v[198:201], v132 offset:1024
	ds_read_b128 v[202:205], v132 offset:2048
	ds_read_b128 v[206:209], v132 offset:3072
	ds_read_b128 v[210:213], v132 offset:4096
	ds_read_b128 v[214:217], v132 offset:5120
	ds_read_b128 v[218:221], v132 offset:6144
	ds_read_b128 v[222:225], v132 offset:7168
	global_load_lds_dwordx4 v[166:167], off
	v_lshl_add_u64 v[166:167], v[150:151], 0, s[90:91]
	s_mov_b32 m0, s10
	s_nop 0
	global_load_lds_dwordx4 v[166:167], off
	s_waitcnt lgkmcnt(8)
	s_barrier
	s_waitcnt lgkmcnt(0)
	s_waitcnt lgkmcnt(0)
	v_mfma_f32_16x16x32_f16 v[124:127], v[194:197], v[158:161], v[124:127]
	v_mfma_f32_16x16x32_f16 v[120:123], v[194:197], v[186:189], v[120:123]
	v_mfma_f32_16x16x32_f16 v[116:119], v[202:205], v[158:161], v[116:119]
	v_mfma_f32_16x16x32_f16 v[112:115], v[202:205], v[186:189], v[112:115]
	v_mfma_f32_16x16x32_f16 v[108:111], v[210:213], v[158:161], v[108:111]
	v_mfma_f32_16x16x32_f16 v[104:107], v[210:213], v[186:189], v[104:107]
	v_mfma_f32_16x16x32_f16 v[100:103], v[218:221], v[158:161], v[100:103]
	v_mfma_f32_16x16x32_f16 v[96:99], v[218:221], v[186:189], v[96:99]
	v_mfma_f32_16x16x32_f16 v[124:127], v[198:201], v[162:165], v[124:127]
	v_mfma_f32_16x16x32_f16 v[120:123], v[198:201], v[190:193], v[120:123]
	v_mfma_f32_16x16x32_f16 v[116:119], v[206:209], v[162:165], v[116:119]
	v_mfma_f32_16x16x32_f16 v[112:115], v[206:209], v[190:193], v[112:115]
	v_mfma_f32_16x16x32_f16 v[108:111], v[214:217], v[162:165], v[108:111]
	v_mfma_f32_16x16x32_f16 v[104:107], v[214:217], v[190:193], v[104:107]
	v_mfma_f32_16x16x32_f16 v[100:103], v[222:225], v[162:165], v[100:103]
	v_mfma_f32_16x16x32_f16 v[96:99], v[222:225], v[190:193], v[96:99]
	s_barrier
	v_lshl_add_u64 v[166:167], s[2:3], 0, v[128:129]
	v_readfirstlane_b32 s10, v134
	v_lshl_add_u64 v[168:169], v[166:167], 0, s[36:37]
	s_mov_b32 m0, s10
	v_readfirstlane_b32 s10, v135
	ds_read_b128 v[226:229], v133 offset:16384
	ds_read_b128 v[230:233], v133 offset:17408
	ds_read_b128 v[234:237], v133 offset:18432
	ds_read_b128 v[238:241], v133 offset:19456
	global_load_lds_dwordx4 v[168:169], off
	v_lshl_add_u64 v[168:169], v[166:167], 0, s[54:55]
	s_mov_b32 m0, s10
	s_nop 0
	global_load_lds_dwordx4 v[168:169], off
	s_barrier
	s_waitcnt lgkmcnt(0)
	s_waitcnt lgkmcnt(0)
	v_mfma_f32_16x16x32_f16 v[92:95], v[194:197], v[226:229], v[92:95]
	v_mfma_f32_16x16x32_f16 v[88:91], v[194:197], v[234:237], v[88:91]
	v_mfma_f32_16x16x32_f16 v[84:87], v[202:205], v[226:229], v[84:87]
	v_mfma_f32_16x16x32_f16 v[80:83], v[202:205], v[234:237], v[80:83]
	v_mfma_f32_16x16x32_f16 v[76:79], v[210:213], v[226:229], v[76:79]
	v_mfma_f32_16x16x32_f16 v[72:75], v[210:213], v[234:237], v[72:75]
	v_mfma_f32_16x16x32_f16 v[68:71], v[218:221], v[226:229], v[68:71]
	v_mfma_f32_16x16x32_f16 v[64:67], v[218:221], v[234:237], v[64:67]
	v_mfma_f32_16x16x32_f16 v[92:95], v[198:201], v[230:233], v[92:95]
	v_mfma_f32_16x16x32_f16 v[88:91], v[198:201], v[238:241], v[88:91]
	v_mfma_f32_16x16x32_f16 v[84:87], v[206:209], v[230:233], v[84:87]
	v_mfma_f32_16x16x32_f16 v[80:83], v[206:209], v[238:241], v[80:83]
	v_mfma_f32_16x16x32_f16 v[76:79], v[214:217], v[230:233], v[76:79]
	v_mfma_f32_16x16x32_f16 v[72:75], v[214:217], v[238:241], v[72:75]
	v_mfma_f32_16x16x32_f16 v[68:71], v[222:225], v[230:233], v[68:71]
	v_mfma_f32_16x16x32_f16 v[64:67], v[222:225], v[238:241], v[64:67]
	v_readfirstlane_b32 s10, v136
	v_lshl_add_u64 v[168:169], v[150:151], 0, s[92:93]
	s_mov_b32 m0, s10
	v_readfirstlane_b32 s10, v137
	s_barrier
	ds_read_b128 v[194:197], v132 offset:16384
	ds_read_b128 v[198:201], v132 offset:17408
	ds_read_b128 v[202:205], v132 offset:18432
	ds_read_b128 v[206:209], v132 offset:19456
	ds_read_b128 v[210:213], v132 offset:20480
	ds_read_b128 v[214:217], v132 offset:21504
	ds_read_b128 v[218:221], v132 offset:22528
	ds_read_b128 v[222:225], v132 offset:23552
	global_load_lds_dwordx4 v[168:169], off
	v_lshl_add_u64 v[168:169], v[150:151], 0, s[66:67]
	s_mov_b32 m0, s10
	s_nop 0
	global_load_lds_dwordx4 v[168:169], off
	s_barrier
	s_waitcnt lgkmcnt(0)
	s_waitcnt lgkmcnt(0)
	v_mfma_f32_16x16x32_f16 v[60:63], v[194:197], v[158:161], v[60:63]
	v_mfma_f32_16x16x32_f16 v[56:59], v[194:197], v[186:189], v[56:59]
	v_mfma_f32_16x16x32_f16 v[52:55], v[202:205], v[158:161], v[52:55]
	v_mfma_f32_16x16x32_f16 v[48:51], v[202:205], v[186:189], v[48:51]
	v_mfma_f32_16x16x32_f16 v[44:47], v[210:213], v[158:161], v[44:47]
	v_mfma_f32_16x16x32_f16 v[40:43], v[210:213], v[186:189], v[40:43]
	v_mfma_f32_16x16x32_f16 v[36:39], v[218:221], v[158:161], v[36:39]
	v_mfma_f32_16x16x32_f16 v[32:35], v[218:221], v[186:189], v[32:35]
	v_mfma_f32_16x16x32_f16 v[60:63], v[198:201], v[162:165], v[60:63]
	v_mfma_f32_16x16x32_f16 v[56:59], v[198:201], v[190:193], v[56:59]
	v_mfma_f32_16x16x32_f16 v[52:55], v[206:209], v[162:165], v[52:55]
	v_mfma_f32_16x16x32_f16 v[48:51], v[206:209], v[190:193], v[48:51]
	v_mfma_f32_16x16x32_f16 v[44:47], v[214:217], v[162:165], v[44:47]
	v_mfma_f32_16x16x32_f16 v[40:43], v[214:217], v[190:193], v[40:43]
	v_mfma_f32_16x16x32_f16 v[36:39], v[222:225], v[162:165], v[36:39]
	v_mfma_f32_16x16x32_f16 v[32:35], v[222:225], v[190:193], v[32:35]
	s_barrier
;   #define STAGE(P,BASE,LD,br,kt) do{ const HALF* _u=(BASE)+(long)(br)*(((&(LD))==&lda)?lda_u:(LD))+(long)(kt)*G_BK; \
;     for(int _i=0;_i<2;++_i){ \
;       __builtin_amdgcn_global_load_lds((const unsigned*)(_u+(long)_i*(((&(LD))==&lda)?stepa:stepb)+((&(LD))==&lda?oa0:ob0)), \
;         (unsigned*)((char*)(P)+t5*16+_i*8192),16,0,0);}}while(0)
;   #define LDA(dst,b,h) for(int m=0;m<4;++m)for(int k=0;k<2;++k) \
;     dst[m][k]=*reinterpret_cast<const h8*>(la+(((b)*2+(h))*16384+m*2048+k*1024))
;   #define LDB(dst,b,h) for(int n=0;n<2;++n)for(int k=0;k<2;++k) \
;     dst[n][k]=*reinterpret_cast<const h8*>(lb+(((b)*2+(h))*16384+n*2048+k*1024))
;   #define MMA(ai,bj,At,Bt_) do{__builtin_amdgcn_s_setprio(1); \
;     for(int m=0;m<4;++m)for(int n=0;n<2;++n)for(int k=0;k<2;++k) \
;       acc[ai][bj][m][n]=__builtin_amdgcn_mfma_f32_16x16x32_f16(At[m][k],Bt_[n][k],acc[ai][bj][m][n],0,0,0); \
;     __builtin_amdgcn_s_setprio(0);}while(0)
;   #define WAIT_V(n) asm volatile("s_waitcnt vmcnt(" #n ")":::"memory")
;   #define WAIT_L(n) asm volatile("s_waitcnt lgkmcnt(" #n ")":::"memory")
;   #define BAR __builtin_amdgcn_s_barrier()
;   #define SCHED __builtin_amdgcn_sched_barrier(0)
;     ...
;     STAGE(SB(0,1),Bt,ldb,G_HALF,t+2);
;     WAIT_V(6); BAR; MMA(1,1,At,B1); BAR;
;     LDB(B0,1,0); SCHED; LDA(At,1,0); STAGE(SA(0,1),A,lda,G_HALF,t+2);
;     WAIT_L(8); BAR; WAIT_L(0); MMA(0,0,At,B0); BAR; SCHED;
;     LDB(B1,1,1); STAGE(SB(1,0),Bt,ldb,0,t+3);
;     BAR; WAIT_L(0); MMA(0,1,At,B1); BAR;
;     LDA(At,1,1); STAGE(SA(1,0),A,lda,0,t+3);
	v_readfirstlane_b32 s10, v138
	v_lshl_add_u64 v[158:159], v[166:167], 0, s[24:25]
	s_mov_b32 m0, s10
	v_readfirstlane_b32 s10, v139
	global_load_lds_dwordx4 v[158:159], off
	v_lshl_add_u64 v[158:159], v[166:167], 0, s[48:49]
	s_mov_b32 m0, s10
	s_nop 0
	global_load_lds_dwordx4 v[158:159], off
	s_waitcnt vmcnt(6)
	s_barrier
	v_mfma_f32_16x16x32_f16 v[28:31], v[194:197], v[226:229], v[28:31]
	v_mfma_f32_16x16x32_f16 v[24:27], v[194:197], v[234:237], v[24:27]
	v_mfma_f32_16x16x32_f16 v[20:23], v[202:205], v[226:229], v[20:23]
	v_mfma_f32_16x16x32_f16 v[16:19], v[202:205], v[234:237], v[16:19]
	v_mfma_f32_16x16x32_f16 v[12:15], v[210:213], v[226:229], v[12:15]
	v_mfma_f32_16x16x32_f16 v[8:11], v[210:213], v[234:237], v[8:11]
	v_mfma_f32_16x16x32_f16 v[4:7], v[218:221], v[226:229], v[4:7]
	v_mfma_f32_16x16x32_f16 v[0:3], v[218:221], v[234:237], v[0:3]
	v_mfma_f32_16x16x32_f16 v[28:31], v[198:201], v[230:233], v[28:31]
	v_mfma_f32_16x16x32_f16 v[24:27], v[198:201], v[238:241], v[24:27]
	v_mfma_f32_16x16x32_f16 v[20:23], v[206:209], v[230:233], v[20:23]
	v_mfma_f32_16x16x32_f16 v[16:19], v[206:209], v[238:241], v[16:19]
	v_mfma_f32_16x16x32_f16 v[12:15], v[214:217], v[230:233], v[12:15]
	v_mfma_f32_16x16x32_f16 v[8:11], v[214:217], v[238:241], v[8:11]
	v_mfma_f32_16x16x32_f16 v[4:7], v[222:225], v[230:233], v[4:7]
	v_mfma_f32_16x16x32_f16 v[0:3], v[222:225], v[238:241], v[0:3]
	s_barrier
	ds_read_b128 v[158:161], v133 offset:32768
	ds_read_b128 v[162:165], v133 offset:33792
	ds_read_b128 v[186:189], v133 offset:34816
	ds_read_b128 v[190:193], v133 offset:35840
	v_readfirstlane_b32 s10, v140
	v_lshl_add_u64 v[168:169], v[150:151], 0, s[38:39]
	s_mov_b32 m0, s10
	v_readfirstlane_b32 s10, v141
	ds_read_b128 v[194:197], v132 offset:32768
	ds_read_b128 v[198:201], v132 offset:33792
	ds_read_b128 v[202:205], v132 offset:34816
	ds_read_b128 v[206:209], v132 offset:35840
	ds_read_b128 v[210:213], v132 offset:36864
	ds_read_b128 v[214:217], v132 offset:37888
	ds_read_b128 v[218:221], v132 offset:38912
	ds_read_b128 v[222:225], v132 offset:39936
	global_load_lds_dwordx4 v[168:169], off
	v_lshl_add_u64 v[168:169], v[150:151], 0, s[40:41]
	s_mov_b32 m0, s10
	s_nop 0
	global_load_lds_dwordx4 v[168:169], off
	s_waitcnt lgkmcnt(8)
	s_barrier
	s_waitcnt lgkmcnt(0)
	s_waitcnt lgkmcnt(0)
	v_mfma_f32_16x16x32_f16 v[124:127], v[194:197], v[158:161], v[124:127]
	v_mfma_f32_16x16x32_f16 v[120:123], v[194:197], v[186:189], v[120:123]
	v_mfma_f32_16x16x32_f16 v[116:119], v[202:205], v[158:161], v[116:119]
	v_mfma_f32_16x16x32_f16 v[112:115], v[202:205], v[186:189], v[112:115]
	v_mfma_f32_16x16x32_f16 v[108:111], v[210:213], v[158:161], v[108:111]
	v_mfma_f32_16x16x32_f16 v[104:107], v[210:213], v[186:189], v[104:107]
	v_mfma_f32_16x16x32_f16 v[100:103], v[218:221], v[158:161], v[100:103]
	v_mfma_f32_16x16x32_f16 v[96:99], v[218:221], v[186:189], v[96:99]
	v_mfma_f32_16x16x32_f16 v[124:127], v[198:201], v[162:165], v[124:127]
	v_mfma_f32_16x16x32_f16 v[120:123], v[198:201], v[190:193], v[120:123]
	v_mfma_f32_16x16x32_f16 v[116:119], v[206:209], v[162:165], v[116:119]
	v_mfma_f32_16x16x32_f16 v[112:115], v[206:209], v[190:193], v[112:115]
	v_mfma_f32_16x16x32_f16 v[108:111], v[214:217], v[162:165], v[108:111]
	v_mfma_f32_16x16x32_f16 v[104:107], v[214:217], v[190:193], v[104:107]
	v_mfma_f32_16x16x32_f16 v[100:103], v[222:225], v[162:165], v[100:103]
	v_mfma_f32_16x16x32_f16 v[96:99], v[222:225], v[190:193], v[96:99]
	s_barrier
	v_readfirstlane_b32 s10, v142
	v_lshl_add_u64 v[168:169], v[166:167], 0, s[60:61]
	s_mov_b32 m0, s10
	v_readfirstlane_b32 s10, v143
	ds_read_b128 v[226:229], v133 offset:49152
	ds_read_b128 v[230:233], v133 offset:50176
	ds_read_b128 v[234:237], v133 offset:51200
	ds_read_b128 v[238:241], v133 offset:52224
	global_load_lds_dwordx4 v[168:169], off
	v_lshl_add_u64 v[168:169], v[166:167], 0, s[26:27]
	s_mov_b32 m0, s10
	s_nop 0
	global_load_lds_dwordx4 v[168:169], off
	s_barrier
	s_waitcnt lgkmcnt(0)
	s_waitcnt lgkmcnt(0)
	v_mfma_f32_16x16x32_f16 v[92:95], v[194:197], v[226:229], v[92:95]
	v_mfma_f32_16x16x32_f16 v[88:91], v[194:197], v[234:237], v[88:91]
	v_mfma_f32_16x16x32_f16 v[84:87], v[202:205], v[226:229], v[84:87]
	v_mfma_f32_16x16x32_f16 v[80:83], v[202:205], v[234:237], v[80:83]
	v_mfma_f32_16x16x32_f16 v[76:79], v[210:213], v[226:229], v[76:79]
	v_mfma_f32_16x16x32_f16 v[72:75], v[210:213], v[234:237], v[72:75]
	v_mfma_f32_16x16x32_f16 v[68:71], v[218:221], v[226:229], v[68:71]
	v_mfma_f32_16x16x32_f16 v[64:67], v[218:221], v[234:237], v[64:67]
	v_mfma_f32_16x16x32_f16 v[92:95], v[198:201], v[230:233], v[92:95]
	v_mfma_f32_16x16x32_f16 v[88:91], v[198:201], v[238:241], v[88:91]
	v_mfma_f32_16x16x32_f16 v[84:87], v[206:209], v[230:233], v[84:87]
	v_mfma_f32_16x16x32_f16 v[80:83], v[206:209], v[238:241], v[80:83]
	v_mfma_f32_16x16x32_f16 v[76:79], v[214:217], v[230:233], v[76:79]
	v_mfma_f32_16x16x32_f16 v[72:75], v[214:217], v[238:241], v[72:75]
	v_mfma_f32_16x16x32_f16 v[68:71], v[222:225], v[230:233], v[68:71]
	v_mfma_f32_16x16x32_f16 v[64:67], v[222:225], v[238:241], v[64:67]
	v_readfirstlane_b32 s10, v144
	v_lshl_add_u64 v[168:169], v[150:151], 0, s[42:43]
	s_mov_b32 m0, s10
	v_readfirstlane_b32 s10, v145
	s_barrier
	ds_read_b128 v[194:197], v132 offset:49152
	ds_read_b128 v[198:201], v132 offset:50176
	ds_read_b128 v[202:205], v132 offset:51200
	ds_read_b128 v[206:209], v132 offset:52224
	ds_read_b128 v[210:213], v132 offset:53248
	ds_read_b128 v[214:217], v132 offset:54272
	ds_read_b128 v[218:221], v132 offset:55296
	ds_read_b128 v[222:225], v132 offset:56320
	global_load_lds_dwordx4 v[168:169], off
	v_lshl_add_u64 v[150:151], v[150:151], 0, s[96:97]
	s_mov_b32 m0, s10
	s_nop 0
	global_load_lds_dwordx4 v[150:151], off
	s_barrier
;   #define STAGE(P,BASE,LD,br,kt) do{ const HALF* _u=(BASE)+(long)(br)*(((&(LD))==&lda)?lda_u:(LD))+(long)(kt)*G_BK; \
;     for(int _i=0;_i<2;++_i){ \
;       __builtin_amdgcn_global_load_lds((const unsigned*)(_u+(long)_i*(((&(LD))==&lda)?stepa:stepb)+((&(LD))==&lda?oa0:ob0)), \
;         (unsigned*)((char*)(P)+t5*16+_i*8192),16,0,0);}}while(0)
;   #define LDA(dst,b,h) for(int m=0;m<4;++m)for(int k=0;k<2;++k) \
;     dst[m][k]=*reinterpret_cast<const h8*>(la+(((b)*2+(h))*16384+m*2048+k*1024))
;   #define LDB(dst,b,h) for(int n=0;n<2;++n)for(int k=0;k<2;++k) \
;     dst[n][k]=*reinterpret_cast<const h8*>(lb+(((b)*2+(h))*16384+n*2048+k*1024))
;   #define MMA(ai,bj,At,Bt_) do{__builtin_amdgcn_s_setprio(1); \
;     for(int m=0;m<4;++m)for(int n=0;n<2;++n)for(int k=0;k<2;++k) \
;       acc[ai][bj][m][n]=__builtin_amdgcn_mfma_f32_16x16x32_f16(At[m][k],Bt_[n][k],acc[ai][bj][m][n],0,0,0); \
;     __builtin_amdgcn_s_setprio(0);}while(0)
;   #define WAIT_V(n) asm volatile("s_waitcnt vmcnt(" #n ")":::"memory")
;   #define WAIT_L(n) asm volatile("s_waitcnt lgkmcnt(" #n ")":::"memory")
;   #define BAR __builtin_amdgcn_s_barrier()
;   #define SCHED __builtin_amdgcn_sched_barrier(0)
;     ...
;     BAR; WAIT_L(0); MMA(1,0,At,B0); BAR; SCHED;
;     STAGE(SB(1,1),Bt,ldb,G_HALF,t+3);
;     WAIT_V(6); BAR; MMA(1,1,At,B1); BAR;
;   }
;   { LDB(B0,0,0); LDA(At,0,0); STAGE(SA(1,1),A,lda,G_HALF,nt-1);
;     BAR; WAIT_L(0); MMA(0,0,At,B0); BAR;
;     LDB(B1,0,1); BAR; WAIT_L(0); MMA(0,1,At,B1); BAR;
	s_waitcnt lgkmcnt(0)
	s_waitcnt lgkmcnt(0)
	v_mfma_f32_16x16x32_f16 v[60:63], v[194:197], v[158:161], v[60:63]
	v_mfma_f32_16x16x32_f16 v[56:59], v[194:197], v[186:189], v[56:59]
	v_mfma_f32_16x16x32_f16 v[52:55], v[202:205], v[158:161], v[52:55]
	v_mfma_f32_16x16x32_f16 v[48:51], v[202:205], v[186:189], v[48:51]
	v_mfma_f32_16x16x32_f16 v[44:47], v[210:213], v[158:161], v[44:47]
	v_mfma_f32_16x16x32_f16 v[40:43], v[210:213], v[186:189], v[40:43]
	v_mfma_f32_16x16x32_f16 v[36:39], v[218:221], v[158:161], v[36:39]
	v_mfma_f32_16x16x32_f16 v[32:35], v[218:221], v[186:189], v[32:35]
	v_mfma_f32_16x16x32_f16 v[60:63], v[198:201], v[162:165], v[60:63]
	v_mfma_f32_16x16x32_f16 v[56:59], v[198:201], v[190:193], v[56:59]
	v_mfma_f32_16x16x32_f16 v[52:55], v[206:209], v[162:165], v[52:55]
	v_mfma_f32_16x16x32_f16 v[48:51], v[206:209], v[190:193], v[48:51]
	v_mfma_f32_16x16x32_f16 v[44:47], v[214:217], v[162:165], v[44:47]
	v_mfma_f32_16x16x32_f16 v[40:43], v[214:217], v[190:193], v[40:43]
	v_mfma_f32_16x16x32_f16 v[36:39], v[222:225], v[162:165], v[36:39]
	v_mfma_f32_16x16x32_f16 v[32:35], v[222:225], v[190:193], v[32:35]
	s_barrier
	v_readfirstlane_b32 s10, v146
	v_lshl_add_u64 v[150:151], v[166:167], 0, s[56:57]
	s_mov_b32 m0, s10
	v_readfirstlane_b32 s10, v147
	global_load_lds_dwordx4 v[150:151], off
	v_lshl_add_u64 v[150:151], v[166:167], 0, s[52:53]
	s_mov_b32 m0, s10
	s_nop 0
	global_load_lds_dwordx4 v[150:151], off
	s_waitcnt vmcnt(6)
	s_barrier
	v_mfma_f32_16x16x32_f16 v[28:31], v[194:197], v[226:229], v[28:31]
	v_mfma_f32_16x16x32_f16 v[24:27], v[194:197], v[234:237], v[24:27]
	v_mfma_f32_16x16x32_f16 v[20:23], v[202:205], v[226:229], v[20:23]
	v_mfma_f32_16x16x32_f16 v[16:19], v[202:205], v[234:237], v[16:19]
	v_mfma_f32_16x16x32_f16 v[12:15], v[210:213], v[226:229], v[12:15]
	v_mfma_f32_16x16x32_f16 v[8:11], v[210:213], v[234:237], v[8:11]
	v_mfma_f32_16x16x32_f16 v[4:7], v[218:221], v[226:229], v[4:7]
	v_mfma_f32_16x16x32_f16 v[0:3], v[218:221], v[234:237], v[0:3]
	v_mfma_f32_16x16x32_f16 v[28:31], v[198:201], v[230:233], v[28:31]
	v_mfma_f32_16x16x32_f16 v[24:27], v[198:201], v[238:241], v[24:27]
	v_mfma_f32_16x16x32_f16 v[20:23], v[206:209], v[230:233], v[20:23]
	v_mfma_f32_16x16x32_f16 v[16:19], v[206:209], v[238:241], v[16:19]
	v_mfma_f32_16x16x32_f16 v[12:15], v[214:217], v[230:233], v[12:15]
	v_mfma_f32_16x16x32_f16 v[8:11], v[214:217], v[238:241], v[8:11]
	v_mfma_f32_16x16x32_f16 v[4:7], v[222:225], v[230:233], v[4:7]
	v_mfma_f32_16x16x32_f16 v[0:3], v[222:225], v[238:241], v[0:3]
	s_add_i32 s8, s8, 2
	s_add_u32 s2, s2, 0x100
	s_addc_u32 s3, s3, 0
	s_add_u32 s6, s6, 0x100
	s_addc_u32 s7, s7, 0
	s_cmp_lt_u32 s8, 12
	s_barrier
	s_cbranch_scc1 .LBB0_295
	v_lshl_add_u64 v[128:129], v[152:153], 1, s[0:1]
	s_mov_b64 s[0:1], 0x40780
	v_lshl_add_u64 v[146:147], v[128:129], 0, s[0:1]
	v_readfirstlane_b32 s0, v148
	s_mov_b32 m0, s0
	s_mov_b64 s[0:1], 0x60780
	v_lshl_add_u64 v[128:129], v[128:129], 0, s[0:1]
	v_readfirstlane_b32 s0, v149
	ds_read_b128 v[134:137], v133
	ds_read_b128 v[138:141], v133 offset:1024
	ds_read_b128 v[142:145], v133 offset:2048
	ds_read_b128 v[158:161], v133 offset:3072
	ds_read_b128 v[162:165], v132
	ds_read_b128 v[186:189], v132 offset:1024
	ds_read_b128 v[190:193], v132 offset:2048
	ds_read_b128 v[194:197], v132 offset:3072
	ds_read_b128 v[198:201], v132 offset:4096
	ds_read_b128 v[202:205], v132 offset:5120
	ds_read_b128 v[206:209], v132 offset:6144
	ds_read_b128 v[210:213], v132 offset:7168
	global_load_lds_dwordx4 v[146:147], off
	s_mov_b32 m0, s0
	s_nop 0
	global_load_lds_dwordx4 v[128:129], off
	s_barrier
	s_waitcnt lgkmcnt(0)
	s_waitcnt lgkmcnt(0)
	v_mfma_f32_16x16x32_f16 v[124:127], v[162:165], v[134:137], v[124:127]
	v_mfma_f32_16x16x32_f16 v[120:123], v[162:165], v[142:145], v[120:123]
	v_mfma_f32_16x16x32_f16 v[116:119], v[190:193], v[134:137], v[116:119]
	v_mfma_f32_16x16x32_f16 v[112:115], v[190:193], v[142:145], v[112:115]
	v_mfma_f32_16x16x32_f16 v[108:111], v[198:201], v[134:137], v[108:111]
	v_mfma_f32_16x16x32_f16 v[104:107], v[198:201], v[142:145], v[104:107]
	v_mfma_f32_16x16x32_f16 v[100:103], v[206:209], v[134:137], v[100:103]
	v_mfma_f32_16x16x32_f16 v[96:99], v[206:209], v[142:145], v[96:99]
	v_mfma_f32_16x16x32_f16 v[124:127], v[186:189], v[138:141], v[124:127]
	v_mfma_f32_16x16x32_f16 v[120:123], v[186:189], v[158:161], v[120:123]
	v_mfma_f32_16x16x32_f16 v[116:119], v[194:197], v[138:141], v[116:119]
	v_mfma_f32_16x16x32_f16 v[112:115], v[194:197], v[158:161], v[112:115]
	v_mfma_f32_16x16x32_f16 v[108:111], v[202:205], v[138:141], v[108:111]
	v_mfma_f32_16x16x32_f16 v[104:107], v[202:205], v[158:161], v[104:107]
	v_mfma_f32_16x16x32_f16 v[100:103], v[210:213], v[138:141], v[100:103]
	v_mfma_f32_16x16x32_f16 v[96:99], v[210:213], v[158:161], v[96:99]
	s_barrier
	ds_read_b128 v[146:149], v133 offset:16384
	ds_read_b128 v[214:217], v133 offset:17408
	ds_read_b128 v[218:221], v133 offset:18432
	ds_read_b128 v[222:225], v133 offset:19456
	s_barrier
	s_waitcnt lgkmcnt(0)
	s_waitcnt lgkmcnt(0)
	v_mfma_f32_16x16x32_f16 v[92:95], v[162:165], v[146:149], v[92:95]
	v_mfma_f32_16x16x32_f16 v[88:91], v[162:165], v[218:221], v[88:91]
	v_mfma_f32_16x16x32_f16 v[84:87], v[190:193], v[146:149], v[84:87]
	v_mfma_f32_16x16x32_f16 v[80:83], v[190:193], v[218:221], v[80:83]
	v_mfma_f32_16x16x32_f16 v[76:79], v[198:201], v[146:149], v[76:79]
	v_mfma_f32_16x16x32_f16 v[72:75], v[198:201], v[218:221], v[72:75]
	v_mfma_f32_16x16x32_f16 v[68:71], v[206:209], v[146:149], v[68:71]
	v_mfma_f32_16x16x32_f16 v[64:67], v[206:209], v[218:221], v[64:67]
	v_mfma_f32_16x16x32_f16 v[92:95], v[186:189], v[214:217], v[92:95]
	v_mfma_f32_16x16x32_f16 v[88:91], v[186:189], v[222:225], v[88:91]
	v_mfma_f32_16x16x32_f16 v[84:87], v[194:197], v[214:217], v[84:87]
	v_mfma_f32_16x16x32_f16 v[80:83], v[194:197], v[222:225], v[80:83]
	v_mfma_f32_16x16x32_f16 v[76:79], v[202:205], v[214:217], v[76:79]
	v_mfma_f32_16x16x32_f16 v[72:75], v[202:205], v[222:225], v[72:75]
	v_mfma_f32_16x16x32_f16 v[68:71], v[210:213], v[214:217], v[68:71]
	v_mfma_f32_16x16x32_f16 v[64:67], v[210:213], v[222:225], v[64:67]
	s_barrier
;   #define LDA(dst,b,h) for(int m=0;m<4;++m)for(int k=0;k<2;++k) \
;     dst[m][k]=*reinterpret_cast<const h8*>(la+(((b)*2+(h))*16384+m*2048+k*1024))
;   #define LDB(dst,b,h) for(int n=0;n<2;++n)for(int k=0;k<2;++k) \
;     dst[n][k]=*reinterpret_cast<const h8*>(lb+(((b)*2+(h))*16384+n*2048+k*1024))
;   #define MMA(ai,bj,At,Bt_) do{__builtin_amdgcn_s_setprio(1); \
;     for(int m=0;m<4;++m)for(int n=0;n<2;++n)for(int k=0;k<2;++k) \
;       acc[ai][bj][m][n]=__builtin_amdgcn_mfma_f32_16x16x32_f16(At[m][k],Bt_[n][k],acc[ai][bj][m][n],0,0,0); \
;     __builtin_amdgcn_s_setprio(0);}while(0)
;   #define WAIT_V(n) asm volatile("s_waitcnt vmcnt(" #n ")":::"memory")
;   #define WAIT_L(n) asm volatile("s_waitcnt lgkmcnt(" #n ")":::"memory")
;   #define BAR __builtin_amdgcn_s_barrier()
;     ...
;     LDA(At,0,1); WAIT_V(4); BAR; WAIT_L(0); MMA(1,0,At,B0); MMA(1,1,At,B1); BAR; }
;   { LDB(B0,1,0); LDA(At,1,0); WAIT_V(2); BAR; WAIT_L(0); MMA(0,0,At,B0); BAR;
	ds_read_b128 v[162:165], v132 offset:16384
	ds_read_b128 v[186:189], v132 offset:17408
	ds_read_b128 v[190:193], v132 offset:18432
	ds_read_b128 v[194:197], v132 offset:19456
	ds_read_b128 v[198:201], v132 offset:20480
	ds_read_b128 v[202:205], v132 offset:21504
	ds_read_b128 v[206:209], v132 offset:22528
	ds_read_b128 v[210:213], v132 offset:23552
	s_waitcnt vmcnt(4)
	s_barrier
	s_waitcnt lgkmcnt(0)
	s_waitcnt lgkmcnt(0)
	v_mfma_f32_16x16x32_f16 v[60:63], v[162:165], v[134:137], v[60:63]
	v_mfma_f32_16x16x32_f16 v[56:59], v[162:165], v[142:145], v[56:59]
	v_mfma_f32_16x16x32_f16 v[52:55], v[190:193], v[134:137], v[52:55]
	v_mfma_f32_16x16x32_f16 v[48:51], v[190:193], v[142:145], v[48:51]
	v_mfma_f32_16x16x32_f16 v[44:47], v[198:201], v[134:137], v[44:47]
	v_mfma_f32_16x16x32_f16 v[40:43], v[198:201], v[142:145], v[40:43]
	v_mfma_f32_16x16x32_f16 v[36:39], v[206:209], v[134:137], v[36:39]
	v_mfma_f32_16x16x32_f16 v[32:35], v[206:209], v[142:145], v[32:35]
	v_mfma_f32_16x16x32_f16 v[60:63], v[186:189], v[138:141], v[60:63]
	v_mfma_f32_16x16x32_f16 v[56:59], v[186:189], v[158:161], v[56:59]
	v_mfma_f32_16x16x32_f16 v[52:55], v[194:197], v[138:141], v[52:55]
	v_mfma_f32_16x16x32_f16 v[48:51], v[194:197], v[158:161], v[48:51]
	v_mfma_f32_16x16x32_f16 v[44:47], v[202:205], v[138:141], v[44:47]
	v_mfma_f32_16x16x32_f16 v[40:43], v[202:205], v[158:161], v[40:43]
	v_mfma_f32_16x16x32_f16 v[36:39], v[210:213], v[138:141], v[36:39]
	v_mfma_f32_16x16x32_f16 v[32:35], v[210:213], v[158:161], v[32:35]
	v_mfma_f32_16x16x32_f16 v[28:31], v[162:165], v[146:149], v[28:31]
	v_mfma_f32_16x16x32_f16 v[24:27], v[162:165], v[218:221], v[24:27]
	v_mfma_f32_16x16x32_f16 v[20:23], v[190:193], v[146:149], v[20:23]
	v_mfma_f32_16x16x32_f16 v[16:19], v[190:193], v[218:221], v[16:19]
	v_mfma_f32_16x16x32_f16 v[12:15], v[198:201], v[146:149], v[12:15]
	v_mfma_f32_16x16x32_f16 v[8:11], v[198:201], v[218:221], v[8:11]
	v_mfma_f32_16x16x32_f16 v[4:7], v[206:209], v[146:149], v[4:7]
	v_mfma_f32_16x16x32_f16 v[0:3], v[206:209], v[218:221], v[0:3]
	v_mfma_f32_16x16x32_f16 v[28:31], v[186:189], v[214:217], v[28:31]
	v_mfma_f32_16x16x32_f16 v[24:27], v[186:189], v[222:225], v[24:27]
	v_mfma_f32_16x16x32_f16 v[20:23], v[194:197], v[214:217], v[20:23]
	v_mfma_f32_16x16x32_f16 v[16:19], v[194:197], v[222:225], v[16:19]
	v_mfma_f32_16x16x32_f16 v[12:15], v[202:205], v[214:217], v[12:15]
	v_mfma_f32_16x16x32_f16 v[8:11], v[202:205], v[222:225], v[8:11]
	v_mfma_f32_16x16x32_f16 v[4:7], v[210:213], v[214:217], v[4:7]
	v_mfma_f32_16x16x32_f16 v[0:3], v[210:213], v[222:225], v[0:3]
	s_barrier
	ds_read_b128 v[134:137], v133 offset:32768
	ds_read_b128 v[138:141], v133 offset:33792
	ds_read_b128 v[142:145], v133 offset:34816
	ds_read_b128 v[146:149], v133 offset:35840
	ds_read_b128 v[158:161], v132 offset:32768
	ds_read_b128 v[162:165], v132 offset:33792
	ds_read_b128 v[186:189], v132 offset:34816
	ds_read_b128 v[190:193], v132 offset:35840
	ds_read_b128 v[194:197], v132 offset:36864
	ds_read_b128 v[198:201], v132 offset:37888
	ds_read_b128 v[202:205], v132 offset:38912
	ds_read_b128 v[206:209], v132 offset:39936
	s_waitcnt vmcnt(2)
	s_barrier
	s_waitcnt lgkmcnt(0)
	s_waitcnt lgkmcnt(0)
	v_mfma_f32_16x16x32_f16 v[124:127], v[158:161], v[134:137], v[124:127]
	v_mfma_f32_16x16x32_f16 v[120:123], v[158:161], v[142:145], v[120:123]
	v_mfma_f32_16x16x32_f16 v[116:119], v[186:189], v[134:137], v[116:119]
	v_mfma_f32_16x16x32_f16 v[112:115], v[186:189], v[142:145], v[112:115]
	v_mfma_f32_16x16x32_f16 v[108:111], v[194:197], v[134:137], v[108:111]
	v_mfma_f32_16x16x32_f16 v[104:107], v[194:197], v[142:145], v[104:107]
	v_mfma_f32_16x16x32_f16 v[100:103], v[202:205], v[134:137], v[100:103]
	v_mfma_f32_16x16x32_f16 v[96:99], v[202:205], v[142:145], v[96:99]
	v_mfma_f32_16x16x32_f16 v[124:127], v[162:165], v[138:141], v[124:127]
	v_mfma_f32_16x16x32_f16 v[120:123], v[162:165], v[146:149], v[120:123]
	v_mfma_f32_16x16x32_f16 v[116:119], v[190:193], v[138:141], v[116:119]
	v_mfma_f32_16x16x32_f16 v[112:115], v[190:193], v[146:149], v[112:115]
	v_mfma_f32_16x16x32_f16 v[108:111], v[198:201], v[138:141], v[108:111]
	v_mfma_f32_16x16x32_f16 v[104:107], v[198:201], v[146:149], v[104:107]
	v_mfma_f32_16x16x32_f16 v[100:103], v[206:209], v[138:141], v[100:103]
	v_mfma_f32_16x16x32_f16 v[96:99], v[206:209], v[146:149], v[96:99]
	s_barrier
;   #define LDA(dst,b,h) for(int m=0;m<4;++m)for(int k=0;k<2;++k) \
;     dst[m][k]=*reinterpret_cast<const h8*>(la+(((b)*2+(h))*16384+m*2048+k*1024))
;   #define LDB(dst,b,h) for(int n=0;n<2;++n)for(int k=0;k<2;++k) \
;     dst[n][k]=*reinterpret_cast<const h8*>(lb+(((b)*2+(h))*16384+n*2048+k*1024))
;   #define MMA(ai,bj,At,Bt_) do{__builtin_amdgcn_s_setprio(1); \
;     for(int m=0;m<4;++m)for(int n=0;n<2;++n)for(int k=0;k<2;++k) \
;       acc[ai][bj][m][n]=__builtin_amdgcn_mfma_f32_16x16x32_f16(At[m][k],Bt_[n][k],acc[ai][bj][m][n],0,0,0); \
;     __builtin_amdgcn_s_setprio(0);}while(0)
;   #define WAIT_V(n) asm volatile("s_waitcnt vmcnt(" #n ")":::"memory")
;   #define WAIT_L(n) asm volatile("s_waitcnt lgkmcnt(" #n ")":::"memory")
;   #define BAR __builtin_amdgcn_s_barrier()
;     ...
;     LDB(B1,1,1); WAIT_V(0); BAR; WAIT_L(0); MMA(0,1,At,B1); BAR;
;     LDA(At,1,1); BAR; WAIT_L(0); MMA(1,0,At,B0); MMA(1,1,At,B1); BAR; }
;   if(wr==0)BAR;
	ds_read_b128 v[210:213], v133 offset:49152
	ds_read_b128 v[214:217], v133 offset:50176
	ds_read_b128 v[218:221], v133 offset:51200
	ds_read_b128 v[222:225], v133 offset:52224
	s_waitcnt vmcnt(0)
	s_barrier
	s_waitcnt lgkmcnt(0)
	s_waitcnt lgkmcnt(0)
	v_mfma_f32_16x16x32_f16 v[92:95], v[158:161], v[210:213], v[92:95]
	v_mfma_f32_16x16x32_f16 v[88:91], v[158:161], v[218:221], v[88:91]
	v_mfma_f32_16x16x32_f16 v[84:87], v[186:189], v[210:213], v[84:87]
	v_mfma_f32_16x16x32_f16 v[80:83], v[186:189], v[218:221], v[80:83]
	v_mfma_f32_16x16x32_f16 v[76:79], v[194:197], v[210:213], v[76:79]
	v_mfma_f32_16x16x32_f16 v[72:75], v[194:197], v[218:221], v[72:75]
	v_mfma_f32_16x16x32_f16 v[68:71], v[202:205], v[210:213], v[68:71]
	v_mfma_f32_16x16x32_f16 v[64:67], v[202:205], v[218:221], v[64:67]
	v_mfma_f32_16x16x32_f16 v[92:95], v[162:165], v[214:217], v[92:95]
	v_mfma_f32_16x16x32_f16 v[88:91], v[162:165], v[222:225], v[88:91]
	v_mfma_f32_16x16x32_f16 v[84:87], v[190:193], v[214:217], v[84:87]
	v_mfma_f32_16x16x32_f16 v[80:83], v[190:193], v[222:225], v[80:83]
	v_mfma_f32_16x16x32_f16 v[76:79], v[198:201], v[214:217], v[76:79]
	v_mfma_f32_16x16x32_f16 v[72:75], v[198:201], v[222:225], v[72:75]
	v_mfma_f32_16x16x32_f16 v[68:71], v[206:209], v[214:217], v[68:71]
	v_mfma_f32_16x16x32_f16 v[64:67], v[206:209], v[222:225], v[64:67]
	s_barrier
	ds_read_b128 v[158:161], v132 offset:49152
	ds_read_b128 v[162:165], v132 offset:50176
	ds_read_b128 v[186:189], v132 offset:51200
	ds_read_b128 v[190:193], v132 offset:52224
	ds_read_b128 v[194:197], v132 offset:53248
	ds_read_b128 v[198:201], v132 offset:54272
	ds_read_b128 v[202:205], v132 offset:55296
	ds_read_b128 v[206:209], v132 offset:56320
	s_barrier
	s_waitcnt lgkmcnt(0)
	s_waitcnt lgkmcnt(0)
	v_mfma_f32_16x16x32_f16 v[60:63], v[158:161], v[134:137], v[60:63]
	v_mfma_f32_16x16x32_f16 v[56:59], v[158:161], v[142:145], v[56:59]
	v_mfma_f32_16x16x32_f16 v[52:55], v[186:189], v[134:137], v[52:55]
	v_mfma_f32_16x16x32_f16 v[48:51], v[186:189], v[142:145], v[48:51]
	v_mfma_f32_16x16x32_f16 v[44:47], v[194:197], v[134:137], v[44:47]
	v_mfma_f32_16x16x32_f16 v[40:43], v[194:197], v[142:145], v[40:43]
	v_mfma_f32_16x16x32_f16 v[36:39], v[202:205], v[134:137], v[36:39]
	v_mfma_f32_16x16x32_f16 v[32:35], v[202:205], v[142:145], v[32:35]
	v_mfma_f32_16x16x32_f16 v[60:63], v[162:165], v[138:141], v[60:63]
	v_mfma_f32_16x16x32_f16 v[56:59], v[162:165], v[146:149], v[56:59]
	v_mfma_f32_16x16x32_f16 v[52:55], v[190:193], v[138:141], v[52:55]
	v_mfma_f32_16x16x32_f16 v[48:51], v[190:193], v[146:149], v[48:51]
	v_mfma_f32_16x16x32_f16 v[44:47], v[198:201], v[138:141], v[44:47]
	v_mfma_f32_16x16x32_f16 v[40:43], v[198:201], v[146:149], v[40:43]
	v_mfma_f32_16x16x32_f16 v[36:39], v[206:209], v[138:141], v[36:39]
	v_mfma_f32_16x16x32_f16 v[32:35], v[206:209], v[146:149], v[32:35]
	v_mfma_f32_16x16x32_f16 v[28:31], v[158:161], v[210:213], v[28:31]
	v_mfma_f32_16x16x32_f16 v[24:27], v[158:161], v[218:221], v[24:27]
	v_mfma_f32_16x16x32_f16 v[20:23], v[186:189], v[210:213], v[20:23]
	v_mfma_f32_16x16x32_f16 v[16:19], v[186:189], v[218:221], v[16:19]
	v_mfma_f32_16x16x32_f16 v[12:15], v[194:197], v[210:213], v[12:15]
	v_mfma_f32_16x16x32_f16 v[8:11], v[194:197], v[218:221], v[8:11]
	v_mfma_f32_16x16x32_f16 v[4:7], v[202:205], v[210:213], v[4:7]
	v_mfma_f32_16x16x32_f16 v[0:3], v[202:205], v[218:221], v[0:3]
	v_mfma_f32_16x16x32_f16 v[28:31], v[162:165], v[214:217], v[28:31]
	v_mfma_f32_16x16x32_f16 v[24:27], v[162:165], v[222:225], v[24:27]
	v_mfma_f32_16x16x32_f16 v[20:23], v[190:193], v[214:217], v[20:23]
	v_mfma_f32_16x16x32_f16 v[16:19], v[190:193], v[222:225], v[16:19]
	v_mfma_f32_16x16x32_f16 v[12:15], v[198:201], v[214:217], v[12:15]
	v_mfma_f32_16x16x32_f16 v[8:11], v[198:201], v[222:225], v[8:11]
	v_mfma_f32_16x16x32_f16 v[4:7], v[206:209], v[214:217], v[4:7]
	v_mfma_f32_16x16x32_f16 v[0:3], v[206:209], v[222:225], v[0:3]
	s_movk_i32 s0, 0x100
	v_cmp_gt_u32_e32 vcc, s0, v131
	s_barrier
	s_and_saveexec_b64 s[0:1], vcc
	s_cbranch_execz .LBB0_298
	s_barrier

;   #define STAGE(P,BASE,LD,br,kt) do{ const HALF* _u=(BASE)+(long)(br)*(((&(LD))==&lda)?lda_u:(LD))+(long)(kt)*G_BK; \
;     for(int _i=0;_i<2;++_i){ \
;       __builtin_amdgcn_global_load_lds((const unsigned*)(_u+(long)_i*(((&(LD))==&lda)?stepa:stepb)+((&(LD))==&lda?oa0:ob0)), \
;         (unsigned*)((char*)(P)+t5*16+_i*8192),16,0,0);}}while(0)
;   #define LDA(dst,b,h) for(int m=0;m<4;++m)for(int k=0;k<2;++k) \
;     dst[m][k]=*reinterpret_cast<const h8*>(la+(((b)*2+(h))*16384+m*2048+k*1024))
;   #define LDB(dst,b,h) for(int n=0;n<2;++n)for(int k=0;k<2;++k) \
;     dst[n][k]=*reinterpret_cast<const h8*>(lb+(((b)*2+(h))*16384+n*2048+k*1024))
;   #define MMA(ai,bj,At,Bt_) do{__builtin_amdgcn_s_setprio(1); \
;     for(int m=0;m<4;++m)for(int n=0;n<2;++n)for(int k=0;k<2;++k) \
;       acc[ai][bj][m][n]=__builtin_amdgcn_mfma_f32_16x16x32_f16(At[m][k],Bt_[n][k],acc[ai][bj][m][n],0,0,0); \
;     __builtin_amdgcn_s_setprio(0);}while(0)
;   #define WAIT_L(n) asm volatile("s_waitcnt lgkmcnt(" #n ")":::"memory")
;   #define BAR __builtin_amdgcn_s_barrier()
;   #define SCHED __builtin_amdgcn_sched_barrier(0)
;     ...
;     LDB(B0,0,0); SCHED; LDA(At,0,0); STAGE(SA(1,1),A,lda,G_HALF,t+1);
;     WAIT_L(8); BAR; WAIT_L(0); MMA(0,0,At,B0); BAR; SCHED;
;     LDB(B1,0,1); STAGE(SB(0,0),Bt,ldb,0,t+2);
;     BAR; WAIT_L(0); MMA(0,1,At,B1); BAR;
;     LDA(At,0,1); STAGE(SA(0,0),A,lda,0,t+2);
;     BAR; WAIT_L(0); MMA(1,0,At,B0); BAR; SCHED;
; __global__ void __launch_bounds__(512, 2) mega(P p) {
;     ...
;           job_resid_g<1024>(p, (const HALF*)(ws + OFF_MRG), (const HALF*)(ws + OFF_WO), rj0 + rstride * k, sm);
.LBB0_323:
	ds_read_b128 v[158:161], v133
	ds_read_b128 v[162:165], v133 offset:1024
	ds_read_b128 v[186:189], v133 offset:2048
	ds_read_b128 v[190:193], v133 offset:3072
	v_add_u32_e32 v148, 0xc000, v136
	v_lshl_add_u64 v[150:151], s[70:71], 0, v[128:129]
	s_mov_b64 s[14:15], 0xdef0080
	v_readfirstlane_b32 s13, v148
	v_add_u32_e32 v149, 0xe000, v136
	v_lshl_add_u64 v[166:167], v[150:151], 0, s[14:15]
	s_mov_b32 m0, s13
	s_mov_b64 s[14:15], 0xdf10080
	v_readfirstlane_b32 s13, v149
	ds_read_b128 v[194:197], v132
	ds_read_b128 v[198:201], v132 offset:1024
	ds_read_b128 v[202:205], v132 offset:2048
	ds_read_b128 v[206:209], v132 offset:3072
	ds_read_b128 v[210:213], v132 offset:4096
	ds_read_b128 v[214:217], v132 offset:5120
	ds_read_b128 v[218:221], v132 offset:6144
	ds_read_b128 v[222:225], v132 offset:7168
	global_load_lds_dwordx4 v[166:167], off
	v_lshl_add_u64 v[166:167], v[150:151], 0, s[14:15]
	s_mov_b32 m0, s13
	s_nop 0
	global_load_lds_dwordx4 v[166:167], off
	s_waitcnt lgkmcnt(8)
	s_barrier
	s_waitcnt lgkmcnt(0)
	s_waitcnt lgkmcnt(0)
	v_mfma_f32_16x16x32_f16 v[124:127], v[194:197], v[158:161], v[124:127]
	v_mfma_f32_16x16x32_f16 v[120:123], v[194:197], v[186:189], v[120:123]
	v_mfma_f32_16x16x32_f16 v[116:119], v[202:205], v[158:161], v[116:119]
	v_mfma_f32_16x16x32_f16 v[112:115], v[202:205], v[186:189], v[112:115]
	v_mfma_f32_16x16x32_f16 v[108:111], v[210:213], v[158:161], v[108:111]
	v_mfma_f32_16x16x32_f16 v[104:107], v[210:213], v[186:189], v[104:107]
	v_mfma_f32_16x16x32_f16 v[100:103], v[218:221], v[158:161], v[100:103]
	v_mfma_f32_16x16x32_f16 v[96:99], v[218:221], v[186:189], v[96:99]
	v_mfma_f32_16x16x32_f16 v[124:127], v[198:201], v[162:165], v[124:127]
	v_mfma_f32_16x16x32_f16 v[120:123], v[198:201], v[190:193], v[120:123]
	v_mfma_f32_16x16x32_f16 v[116:119], v[206:209], v[162:165], v[116:119]
	v_mfma_f32_16x16x32_f16 v[112:115], v[206:209], v[190:193], v[112:115]
	v_mfma_f32_16x16x32_f16 v[108:111], v[214:217], v[162:165], v[108:111]
	v_mfma_f32_16x16x32_f16 v[104:107], v[214:217], v[190:193], v[104:107]
	v_mfma_f32_16x16x32_f16 v[100:103], v[222:225], v[162:165], v[100:103]
	v_mfma_f32_16x16x32_f16 v[96:99], v[222:225], v[190:193], v[96:99]
	s_barrier
	v_lshl_add_u64 v[166:167], s[58:59], 0, v[128:129]
	s_mov_b64 s[14:15], 0x2400100
	v_readfirstlane_b32 s13, v134
	v_lshl_add_u64 v[168:169], v[166:167], 0, s[14:15]
	s_mov_b32 m0, s13
	s_mov_b64 s[14:15], 0x2420100
	v_readfirstlane_b32 s13, v135
	ds_read_b128 v[226:229], v133 offset:16384
	ds_read_b128 v[230:233], v133 offset:17408
	ds_read_b128 v[234:237], v133 offset:18432
	ds_read_b128 v[238:241], v133 offset:19456
	global_load_lds_dwordx4 v[168:169], off
	v_lshl_add_u64 v[168:169], v[166:167], 0, s[14:15]
	s_mov_b32 m0, s13
	s_nop 0
	global_load_lds_dwordx4 v[168:169], off
	s_barrier
	s_waitcnt lgkmcnt(0)
	s_waitcnt lgkmcnt(0)
	v_mfma_f32_16x16x32_f16 v[92:95], v[194:197], v[226:229], v[92:95]
	v_mfma_f32_16x16x32_f16 v[88:91], v[194:197], v[234:237], v[88:91]
	v_mfma_f32_16x16x32_f16 v[84:87], v[202:205], v[226:229], v[84:87]
	v_mfma_f32_16x16x32_f16 v[80:83], v[202:205], v[234:237], v[80:83]
	v_mfma_f32_16x16x32_f16 v[76:79], v[210:213], v[226:229], v[76:79]
	v_mfma_f32_16x16x32_f16 v[72:75], v[210:213], v[234:237], v[72:75]
	v_mfma_f32_16x16x32_f16 v[68:71], v[218:221], v[226:229], v[68:71]
	v_mfma_f32_16x16x32_f16 v[64:67], v[218:221], v[234:237], v[64:67]
	v_mfma_f32_16x16x32_f16 v[92:95], v[198:201], v[230:233], v[92:95]
	v_mfma_f32_16x16x32_f16 v[88:91], v[198:201], v[238:241], v[88:91]
	v_mfma_f32_16x16x32_f16 v[84:87], v[206:209], v[230:233], v[84:87]
	v_mfma_f32_16x16x32_f16 v[80:83], v[206:209], v[238:241], v[80:83]
	v_mfma_f32_16x16x32_f16 v[76:79], v[214:217], v[230:233], v[76:79]
	v_mfma_f32_16x16x32_f16 v[72:75], v[214:217], v[238:241], v[72:75]
	v_mfma_f32_16x16x32_f16 v[68:71], v[222:225], v[230:233], v[68:71]
	v_mfma_f32_16x16x32_f16 v[64:67], v[222:225], v[238:241], v[64:67]
	v_readfirstlane_b32 s13, v136
	v_lshl_add_u64 v[168:169], v[150:151], 0, s[50:51]
	s_mov_b32 m0, s13
	s_mov_b64 s[14:15], 0xded0100
	v_readfirstlane_b32 s13, v137
	s_barrier
	ds_read_b128 v[194:197], v132 offset:16384
	ds_read_b128 v[198:201], v132 offset:17408
	ds_read_b128 v[202:205], v132 offset:18432
	ds_read_b128 v[206:209], v132 offset:19456
	ds_read_b128 v[210:213], v132 offset:20480
	ds_read_b128 v[214:217], v132 offset:21504
	ds_read_b128 v[218:221], v132 offset:22528
	ds_read_b128 v[222:225], v132 offset:23552
	global_load_lds_dwordx4 v[168:169], off
	v_lshl_add_u64 v[168:169], v[150:151], 0, s[14:15]
	s_mov_b32 m0, s13
	s_nop 0
	global_load_lds_dwordx4 v[168:169], off
	s_barrier
	s_waitcnt lgkmcnt(0)
	s_waitcnt lgkmcnt(0)
	v_mfma_f32_16x16x32_f16 v[60:63], v[194:197], v[158:161], v[60:63]
	v_mfma_f32_16x16x32_f16 v[56:59], v[194:197], v[186:189], v[56:59]
	v_mfma_f32_16x16x32_f16 v[52:55], v[202:205], v[158:161], v[52:55]
	v_mfma_f32_16x16x32_f16 v[48:51], v[202:205], v[186:189], v[48:51]
	v_mfma_f32_16x16x32_f16 v[44:47], v[210:213], v[158:161], v[44:47]
	v_mfma_f32_16x16x32_f16 v[40:43], v[210:213], v[186:189], v[40:43]
	v_mfma_f32_16x16x32_f16 v[36:39], v[218:221], v[158:161], v[36:39]
	v_mfma_f32_16x16x32_f16 v[32:35], v[218:221], v[186:189], v[32:35]
	v_mfma_f32_16x16x32_f16 v[60:63], v[198:201], v[162:165], v[60:63]
	v_mfma_f32_16x16x32_f16 v[56:59], v[198:201], v[190:193], v[56:59]
	v_mfma_f32_16x16x32_f16 v[52:55], v[206:209], v[162:165], v[52:55]
	v_mfma_f32_16x16x32_f16 v[48:51], v[206:209], v[190:193], v[48:51]
	v_mfma_f32_16x16x32_f16 v[44:47], v[214:217], v[162:165], v[44:47]
	v_mfma_f32_16x16x32_f16 v[40:43], v[214:217], v[190:193], v[40:43]
	v_mfma_f32_16x16x32_f16 v[36:39], v[222:225], v[162:165], v[36:39]
	v_mfma_f32_16x16x32_f16 v[32:35], v[222:225], v[190:193], v[32:35]
	s_barrier
;   #define STAGE(P,BASE,LD,br,kt) do{ const HALF* _u=(BASE)+(long)(br)*(((&(LD))==&lda)?lda_u:(LD))+(long)(kt)*G_BK; \
;     for(int _i=0;_i<2;++_i){ \
;       __builtin_amdgcn_global_load_lds((const unsigned*)(_u+(long)_i*(((&(LD))==&lda)?stepa:stepb)+((&(LD))==&lda?oa0:ob0)), \
;         (unsigned*)((char*)(P)+t5*16+_i*8192),16,0,0);}}while(0)
;   #define LDA(dst,b,h) for(int m=0;m<4;++m)for(int k=0;k<2;++k) \
;     dst[m][k]=*reinterpret_cast<const h8*>(la+(((b)*2+(h))*16384+m*2048+k*1024))
;   #define LDB(dst,b,h) for(int n=0;n<2;++n)for(int k=0;k<2;++k) \
;     dst[n][k]=*reinterpret_cast<const h8*>(lb+(((b)*2+(h))*16384+n*2048+k*1024))
;   #define MMA(ai,bj,At,Bt_) do{__builtin_amdgcn_s_setprio(1); \
;     for(int m=0;m<4;++m)for(int n=0;n<2;++n)for(int k=0;k<2;++k) \
;       acc[ai][bj][m][n]=__builtin_amdgcn_mfma_f32_16x16x32_f16(At[m][k],Bt_[n][k],acc[ai][bj][m][n],0,0,0); \
;     __builtin_amdgcn_s_setprio(0);}while(0)
;   #define WAIT_V(n) asm volatile("s_waitcnt vmcnt(" #n ")":::"memory")
;   #define WAIT_L(n) asm volatile("s_waitcnt lgkmcnt(" #n ")":::"memory")
;   #define BAR __builtin_amdgcn_s_barrier()
;   #define SCHED __builtin_amdgcn_sched_barrier(0)
;     ...
;     STAGE(SB(0,1),Bt,ldb,G_HALF,t+2);
;     WAIT_V(6); BAR; MMA(1,1,At,B1); BAR;
;     LDB(B0,1,0); SCHED; LDA(At,1,0); STAGE(SA(0,1),A,lda,G_HALF,t+2);
;     WAIT_L(8); BAR; WAIT_L(0); MMA(0,0,At,B0); BAR; SCHED;
;     LDB(B1,1,1); STAGE(SB(1,0),Bt,ldb,0,t+3);
;     BAR; WAIT_L(0); MMA(0,1,At,B1); BAR;
	s_mov_b64 s[14:15], 0x2440100
	v_readfirstlane_b32 s13, v138
	v_lshl_add_u64 v[158:159], v[166:167], 0, s[14:15]
	s_mov_b32 m0, s13
	s_mov_b64 s[14:15], 0x2460100
	v_readfirstlane_b32 s13, v139
	global_load_lds_dwordx4 v[158:159], off
	v_lshl_add_u64 v[158:159], v[166:167], 0, s[14:15]
	s_mov_b32 m0, s13
	s_nop 0
	global_load_lds_dwordx4 v[158:159], off
	s_waitcnt vmcnt(6)
	s_barrier
	v_mfma_f32_16x16x32_f16 v[28:31], v[194:197], v[226:229], v[28:31]
	v_mfma_f32_16x16x32_f16 v[24:27], v[194:197], v[234:237], v[24:27]
	v_mfma_f32_16x16x32_f16 v[20:23], v[202:205], v[226:229], v[20:23]
	v_mfma_f32_16x16x32_f16 v[16:19], v[202:205], v[234:237], v[16:19]
	v_mfma_f32_16x16x32_f16 v[12:15], v[210:213], v[226:229], v[12:15]
	v_mfma_f32_16x16x32_f16 v[8:11], v[210:213], v[234:237], v[8:11]
	v_mfma_f32_16x16x32_f16 v[4:7], v[218:221], v[226:229], v[4:7]
	v_mfma_f32_16x16x32_f16 v[0:3], v[218:221], v[234:237], v[0:3]
	v_mfma_f32_16x16x32_f16 v[28:31], v[198:201], v[230:233], v[28:31]
	v_mfma_f32_16x16x32_f16 v[24:27], v[198:201], v[238:241], v[24:27]
	v_mfma_f32_16x16x32_f16 v[20:23], v[206:209], v[230:233], v[20:23]
	v_mfma_f32_16x16x32_f16 v[16:19], v[206:209], v[238:241], v[16:19]
	v_mfma_f32_16x16x32_f16 v[12:15], v[214:217], v[230:233], v[12:15]
	v_mfma_f32_16x16x32_f16 v[8:11], v[214:217], v[238:241], v[8:11]
	v_mfma_f32_16x16x32_f16 v[4:7], v[222:225], v[230:233], v[4:7]
	v_mfma_f32_16x16x32_f16 v[0:3], v[222:225], v[238:241], v[0:3]
	s_barrier
	ds_read_b128 v[158:161], v133 offset:32768
	ds_read_b128 v[162:165], v133 offset:33792
	ds_read_b128 v[186:189], v133 offset:34816
	ds_read_b128 v[190:193], v133 offset:35840
	s_mov_b64 s[14:15], 0xdef0100
	v_readfirstlane_b32 s13, v140
	v_lshl_add_u64 v[168:169], v[150:151], 0, s[14:15]
	s_mov_b32 m0, s13
	s_mov_b64 s[14:15], 0xdf10100
	v_readfirstlane_b32 s13, v141
	ds_read_b128 v[194:197], v132 offset:32768
	ds_read_b128 v[198:201], v132 offset:33792
	ds_read_b128 v[202:205], v132 offset:34816
	ds_read_b128 v[206:209], v132 offset:35840
	ds_read_b128 v[210:213], v132 offset:36864
	ds_read_b128 v[214:217], v132 offset:37888
	ds_read_b128 v[218:221], v132 offset:38912
	ds_read_b128 v[222:225], v132 offset:39936
	global_load_lds_dwordx4 v[168:169], off
	v_lshl_add_u64 v[168:169], v[150:151], 0, s[14:15]
	s_mov_b32 m0, s13
	s_nop 0
	global_load_lds_dwordx4 v[168:169], off
	s_waitcnt lgkmcnt(8)
	s_barrier
	s_waitcnt lgkmcnt(0)
	s_waitcnt lgkmcnt(0)
	v_mfma_f32_16x16x32_f16 v[124:127], v[194:197], v[158:161], v[124:127]
	v_mfma_f32_16x16x32_f16 v[120:123], v[194:197], v[186:189], v[120:123]
	v_mfma_f32_16x16x32_f16 v[116:119], v[202:205], v[158:161], v[116:119]
	v_mfma_f32_16x16x32_f16 v[112:115], v[202:205], v[186:189], v[112:115]
	v_mfma_f32_16x16x32_f16 v[108:111], v[210:213], v[158:161], v[108:111]
	v_mfma_f32_16x16x32_f16 v[104:107], v[210:213], v[186:189], v[104:107]
	v_mfma_f32_16x16x32_f16 v[100:103], v[218:221], v[158:161], v[100:103]
	v_mfma_f32_16x16x32_f16 v[96:99], v[218:221], v[186:189], v[96:99]
	v_mfma_f32_16x16x32_f16 v[124:127], v[198:201], v[162:165], v[124:127]
	v_mfma_f32_16x16x32_f16 v[120:123], v[198:201], v[190:193], v[120:123]
	v_mfma_f32_16x16x32_f16 v[116:119], v[206:209], v[162:165], v[116:119]
	v_mfma_f32_16x16x32_f16 v[112:115], v[206:209], v[190:193], v[112:115]
	v_mfma_f32_16x16x32_f16 v[108:111], v[214:217], v[162:165], v[108:111]
	v_mfma_f32_16x16x32_f16 v[104:107], v[214:217], v[190:193], v[104:107]
	v_mfma_f32_16x16x32_f16 v[100:103], v[222:225], v[162:165], v[100:103]
	v_mfma_f32_16x16x32_f16 v[96:99], v[222:225], v[190:193], v[96:99]
	s_barrier
	s_mov_b64 s[14:15], 0x2400180
	v_readfirstlane_b32 s13, v142
	v_lshl_add_u64 v[168:169], v[166:167], 0, s[14:15]
	s_mov_b32 m0, s13
	s_mov_b64 s[14:15], 0x2420180
	v_readfirstlane_b32 s13, v143
	ds_read_b128 v[226:229], v133 offset:49152
	ds_read_b128 v[230:233], v133 offset:50176
	ds_read_b128 v[234:237], v133 offset:51200
	ds_read_b128 v[238:241], v133 offset:52224
	global_load_lds_dwordx4 v[168:169], off
	v_lshl_add_u64 v[168:169], v[166:167], 0, s[14:15]
	s_mov_b32 m0, s13
	s_nop 0
	global_load_lds_dwordx4 v[168:169], off
	s_barrier
	s_waitcnt lgkmcnt(0)
	s_waitcnt lgkmcnt(0)
	v_mfma_f32_16x16x32_f16 v[92:95], v[194:197], v[226:229], v[92:95]
	v_mfma_f32_16x16x32_f16 v[88:91], v[194:197], v[234:237], v[88:91]
	v_mfma_f32_16x16x32_f16 v[84:87], v[202:205], v[226:229], v[84:87]
	v_mfma_f32_16x16x32_f16 v[80:83], v[202:205], v[234:237], v[80:83]
	v_mfma_f32_16x16x32_f16 v[76:79], v[210:213], v[226:229], v[76:79]
	v_mfma_f32_16x16x32_f16 v[72:75], v[210:213], v[234:237], v[72:75]
	v_mfma_f32_16x16x32_f16 v[68:71], v[218:221], v[226:229], v[68:71]
	v_mfma_f32_16x16x32_f16 v[64:67], v[218:221], v[234:237], v[64:67]
	v_mfma_f32_16x16x32_f16 v[92:95], v[198:201], v[230:233], v[92:95]
	v_mfma_f32_16x16x32_f16 v[88:91], v[198:201], v[238:241], v[88:91]
	v_mfma_f32_16x16x32_f16 v[84:87], v[206:209], v[230:233], v[84:87]
	v_mfma_f32_16x16x32_f16 v[80:83], v[206:209], v[238:241], v[80:83]
	v_mfma_f32_16x16x32_f16 v[76:79], v[214:217], v[230:233], v[76:79]
	v_mfma_f32_16x16x32_f16 v[72:75], v[214:217], v[238:241], v[72:75]
	v_mfma_f32_16x16x32_f16 v[68:71], v[222:225], v[230:233], v[68:71]
	v_mfma_f32_16x16x32_f16 v[64:67], v[222:225], v[238:241], v[64:67]
	v_readfirstlane_b32 s13, v144
	v_lshl_add_u64 v[168:169], v[150:151], 0, s[46:47]
	s_mov_b32 m0, s13
	s_mov_b64 s[14:15], 0xded0180
	v_readfirstlane_b32 s13, v145
	s_barrier
;   #define STAGE(P,BASE,LD,br,kt) do{ const HALF* _u=(BASE)+(long)(br)*(((&(LD))==&lda)?lda_u:(LD))+(long)(kt)*G_BK; \
;     for(int _i=0;_i<2;++_i){ \
;       __builtin_amdgcn_global_load_lds((const unsigned*)(_u+(long)_i*(((&(LD))==&lda)?stepa:stepb)+((&(LD))==&lda?oa0:ob0)), \
;         (unsigned*)((char*)(P)+t5*16+_i*8192),16,0,0);}}while(0)
;   #define LDA(dst,b,h) for(int m=0;m<4;++m)for(int k=0;k<2;++k) \
;     dst[m][k]=*reinterpret_cast<const h8*>(la+(((b)*2+(h))*16384+m*2048+k*1024))
;   #define LDB(dst,b,h) for(int n=0;n<2;++n)for(int k=0;k<2;++k) \
;     dst[n][k]=*reinterpret_cast<const h8*>(lb+(((b)*2+(h))*16384+n*2048+k*1024))
;   #define MMA(ai,bj,At,Bt_) do{__builtin_amdgcn_s_setprio(1); \
;     for(int m=0;m<4;++m)for(int n=0;n<2;++n)for(int k=0;k<2;++k) \
;       acc[ai][bj][m][n]=__builtin_amdgcn_mfma_f32_16x16x32_f16(At[m][k],Bt_[n][k],acc[ai][bj][m][n],0,0,0); \
;     __builtin_amdgcn_s_setprio(0);}while(0)
;   #define WAIT_V(n) asm volatile("s_waitcnt vmcnt(" #n ")":::"memory")
;   #define WAIT_L(n) asm volatile("s_waitcnt lgkmcnt(" #n ")":::"memory")
;   #define BAR __builtin_amdgcn_s_barrier()
;   #define SCHED __builtin_amdgcn_sched_barrier(0)
;     ...
;     LDA(At,1,1); STAGE(SA(1,0),A,lda,0,t+3);
;     BAR; WAIT_L(0); MMA(1,0,At,B0); BAR; SCHED;
;     STAGE(SB(1,1),Bt,ldb,G_HALF,t+3);
;     WAIT_V(6); BAR; MMA(1,1,At,B1); BAR;
;   }
;   { LDB(B0,0,0); LDA(At,0,0); STAGE(SA(1,1),A,lda,G_HALF,nt-1);
;     BAR; WAIT_L(0); MMA(0,0,At,B0); BAR;
;     LDB(B1,0,1); BAR; WAIT_L(0); MMA(0,1,At,B1); BAR;
	ds_read_b128 v[194:197], v132 offset:49152
	ds_read_b128 v[198:201], v132 offset:50176
	ds_read_b128 v[202:205], v132 offset:51200
	ds_read_b128 v[206:209], v132 offset:52224
	ds_read_b128 v[210:213], v132 offset:53248
	ds_read_b128 v[214:217], v132 offset:54272
	ds_read_b128 v[218:221], v132 offset:55296
	ds_read_b128 v[222:225], v132 offset:56320
	global_load_lds_dwordx4 v[168:169], off
	v_lshl_add_u64 v[150:151], v[150:151], 0, s[14:15]
	s_mov_b32 m0, s13
	s_nop 0
	global_load_lds_dwordx4 v[150:151], off
	s_barrier
	s_waitcnt lgkmcnt(0)
	s_waitcnt lgkmcnt(0)
	v_mfma_f32_16x16x32_f16 v[60:63], v[194:197], v[158:161], v[60:63]
	v_mfma_f32_16x16x32_f16 v[56:59], v[194:197], v[186:189], v[56:59]
	v_mfma_f32_16x16x32_f16 v[52:55], v[202:205], v[158:161], v[52:55]
	v_mfma_f32_16x16x32_f16 v[48:51], v[202:205], v[186:189], v[48:51]
	v_mfma_f32_16x16x32_f16 v[44:47], v[210:213], v[158:161], v[44:47]
	v_mfma_f32_16x16x32_f16 v[40:43], v[210:213], v[186:189], v[40:43]
	v_mfma_f32_16x16x32_f16 v[36:39], v[218:221], v[158:161], v[36:39]
	v_mfma_f32_16x16x32_f16 v[32:35], v[218:221], v[186:189], v[32:35]
	v_mfma_f32_16x16x32_f16 v[60:63], v[198:201], v[162:165], v[60:63]
	v_mfma_f32_16x16x32_f16 v[56:59], v[198:201], v[190:193], v[56:59]
	v_mfma_f32_16x16x32_f16 v[52:55], v[206:209], v[162:165], v[52:55]
	v_mfma_f32_16x16x32_f16 v[48:51], v[206:209], v[190:193], v[48:51]
	v_mfma_f32_16x16x32_f16 v[44:47], v[214:217], v[162:165], v[44:47]
	v_mfma_f32_16x16x32_f16 v[40:43], v[214:217], v[190:193], v[40:43]
	v_mfma_f32_16x16x32_f16 v[36:39], v[222:225], v[162:165], v[36:39]
	v_mfma_f32_16x16x32_f16 v[32:35], v[222:225], v[190:193], v[32:35]
	s_barrier
	s_mov_b64 s[14:15], 0x2440180
	v_readfirstlane_b32 s13, v146
	v_lshl_add_u64 v[150:151], v[166:167], 0, s[14:15]
	s_mov_b32 m0, s13
	s_mov_b64 s[14:15], 0x2460180
	v_readfirstlane_b32 s13, v147
	global_load_lds_dwordx4 v[150:151], off
	v_lshl_add_u64 v[150:151], v[166:167], 0, s[14:15]
	s_mov_b32 m0, s13
	s_nop 0
	global_load_lds_dwordx4 v[150:151], off
	s_waitcnt vmcnt(6)
	s_barrier
	v_mfma_f32_16x16x32_f16 v[28:31], v[194:197], v[226:229], v[28:31]
	v_mfma_f32_16x16x32_f16 v[24:27], v[194:197], v[234:237], v[24:27]
	v_mfma_f32_16x16x32_f16 v[20:23], v[202:205], v[226:229], v[20:23]
	v_mfma_f32_16x16x32_f16 v[16:19], v[202:205], v[234:237], v[16:19]
	v_mfma_f32_16x16x32_f16 v[12:15], v[210:213], v[226:229], v[12:15]
	v_mfma_f32_16x16x32_f16 v[8:11], v[210:213], v[234:237], v[8:11]
	v_mfma_f32_16x16x32_f16 v[4:7], v[218:221], v[226:229], v[4:7]
	v_mfma_f32_16x16x32_f16 v[0:3], v[218:221], v[234:237], v[0:3]
	v_mfma_f32_16x16x32_f16 v[28:31], v[198:201], v[230:233], v[28:31]
	v_mfma_f32_16x16x32_f16 v[24:27], v[198:201], v[238:241], v[24:27]
	v_mfma_f32_16x16x32_f16 v[20:23], v[206:209], v[230:233], v[20:23]
	v_mfma_f32_16x16x32_f16 v[16:19], v[206:209], v[238:241], v[16:19]
	v_mfma_f32_16x16x32_f16 v[12:15], v[214:217], v[230:233], v[12:15]
	v_mfma_f32_16x16x32_f16 v[8:11], v[214:217], v[238:241], v[8:11]
	v_mfma_f32_16x16x32_f16 v[4:7], v[222:225], v[230:233], v[4:7]
	v_mfma_f32_16x16x32_f16 v[0:3], v[222:225], v[238:241], v[0:3]
	s_add_i32 s12, s12, 2
	s_add_u32 s58, s58, 0x100
	s_addc_u32 s59, s59, 0
	s_add_u32 s70, s70, 0x100
	s_addc_u32 s71, s71, 0
	s_cmp_lt_u32 s12, 12
	s_barrier
	s_cbranch_scc1 .LBB0_323
	v_lshl_add_u64 v[128:129], v[152:153], 1, s[10:11]
	s_mov_b64 s[10:11], 0x40780
	v_lshl_add_u64 v[146:147], v[128:129], 0, s[10:11]
	v_readfirstlane_b32 s10, v148
	s_mov_b32 m0, s10
	s_mov_b64 s[10:11], 0x60780
	v_lshl_add_u64 v[128:129], v[128:129], 0, s[10:11]
	v_readfirstlane_b32 s10, v149
	ds_read_b128 v[134:137], v133
	ds_read_b128 v[138:141], v133 offset:1024
	ds_read_b128 v[142:145], v133 offset:2048
	ds_read_b128 v[158:161], v133 offset:3072
	ds_read_b128 v[162:165], v132
	ds_read_b128 v[186:189], v132 offset:1024
	ds_read_b128 v[190:193], v132 offset:2048
	ds_read_b128 v[194:197], v132 offset:3072
	ds_read_b128 v[198:201], v132 offset:4096
	ds_read_b128 v[202:205], v132 offset:5120
	ds_read_b128 v[206:209], v132 offset:6144
	ds_read_b128 v[210:213], v132 offset:7168
	global_load_lds_dwordx4 v[146:147], off
	s_mov_b32 m0, s10
	s_nop 0
	global_load_lds_dwordx4 v[128:129], off
	s_barrier
	s_waitcnt lgkmcnt(0)
	s_waitcnt lgkmcnt(0)
	v_mfma_f32_16x16x32_f16 v[124:127], v[162:165], v[134:137], v[124:127]
	v_mfma_f32_16x16x32_f16 v[120:123], v[162:165], v[142:145], v[120:123]
	v_mfma_f32_16x16x32_f16 v[116:119], v[190:193], v[134:137], v[116:119]
	v_mfma_f32_16x16x32_f16 v[112:115], v[190:193], v[142:145], v[112:115]
	v_mfma_f32_16x16x32_f16 v[108:111], v[198:201], v[134:137], v[108:111]
	v_mfma_f32_16x16x32_f16 v[104:107], v[198:201], v[142:145], v[104:107]
	v_mfma_f32_16x16x32_f16 v[100:103], v[206:209], v[134:137], v[100:103]
	v_mfma_f32_16x16x32_f16 v[96:99], v[206:209], v[142:145], v[96:99]
	v_mfma_f32_16x16x32_f16 v[124:127], v[186:189], v[138:141], v[124:127]
	v_mfma_f32_16x16x32_f16 v[120:123], v[186:189], v[158:161], v[120:123]
	v_mfma_f32_16x16x32_f16 v[116:119], v[194:197], v[138:141], v[116:119]
	v_mfma_f32_16x16x32_f16 v[112:115], v[194:197], v[158:161], v[112:115]
	v_mfma_f32_16x16x32_f16 v[108:111], v[202:205], v[138:141], v[108:111]
	v_mfma_f32_16x16x32_f16 v[104:107], v[202:205], v[158:161], v[104:107]
	v_mfma_f32_16x16x32_f16 v[100:103], v[210:213], v[138:141], v[100:103]
	v_mfma_f32_16x16x32_f16 v[96:99], v[210:213], v[158:161], v[96:99]
	s_barrier
	ds_read_b128 v[146:149], v133 offset:16384
	ds_read_b128 v[214:217], v133 offset:17408
	ds_read_b128 v[218:221], v133 offset:18432
	ds_read_b128 v[222:225], v133 offset:19456
	s_barrier
;   #define LDA(dst,b,h) for(int m=0;m<4;++m)for(int k=0;k<2;++k) \
;     dst[m][k]=*reinterpret_cast<const h8*>(la+(((b)*2+(h))*16384+m*2048+k*1024))
;   #define LDB(dst,b,h) for(int n=0;n<2;++n)for(int k=0;k<2;++k) \
;     dst[n][k]=*reinterpret_cast<const h8*>(lb+(((b)*2+(h))*16384+n*2048+k*1024))
;   #define MMA(ai,bj,At,Bt_) do{__builtin_amdgcn_s_setprio(1); \
;     for(int m=0;m<4;++m)for(int n=0;n<2;++n)for(int k=0;k<2;++k) \
;       acc[ai][bj][m][n]=__builtin_amdgcn_mfma_f32_16x16x32_f16(At[m][k],Bt_[n][k],acc[ai][bj][m][n],0,0,0); \
;     __builtin_amdgcn_s_setprio(0);}while(0)
;   #define WAIT_V(n) asm volatile("s_waitcnt vmcnt(" #n ")":::"memory")
;   #define WAIT_L(n) asm volatile("s_waitcnt lgkmcnt(" #n ")":::"memory")
;   #define BAR __builtin_amdgcn_s_barrier()
;     ...
;     LDB(B1,0,1); BAR; WAIT_L(0); MMA(0,1,At,B1); BAR;
;     LDA(At,0,1); WAIT_V(4); BAR; WAIT_L(0); MMA(1,0,At,B0); MMA(1,1,At,B1); BAR; }
;   { LDB(B0,1,0); LDA(At,1,0); WAIT_V(2); BAR; WAIT_L(0); MMA(0,0,At,B0); BAR;
	s_waitcnt lgkmcnt(0)
	s_waitcnt lgkmcnt(0)
	v_mfma_f32_16x16x32_f16 v[92:95], v[162:165], v[146:149], v[92:95]
	v_mfma_f32_16x16x32_f16 v[88:91], v[162:165], v[218:221], v[88:91]
	v_mfma_f32_16x16x32_f16 v[84:87], v[190:193], v[146:149], v[84:87]
	v_mfma_f32_16x16x32_f16 v[80:83], v[190:193], v[218:221], v[80:83]
	v_mfma_f32_16x16x32_f16 v[76:79], v[198:201], v[146:149], v[76:79]
	v_mfma_f32_16x16x32_f16 v[72:75], v[198:201], v[218:221], v[72:75]
	v_mfma_f32_16x16x32_f16 v[68:71], v[206:209], v[146:149], v[68:71]
	v_mfma_f32_16x16x32_f16 v[64:67], v[206:209], v[218:221], v[64:67]
	v_mfma_f32_16x16x32_f16 v[92:95], v[186:189], v[214:217], v[92:95]
	v_mfma_f32_16x16x32_f16 v[88:91], v[186:189], v[222:225], v[88:91]
	v_mfma_f32_16x16x32_f16 v[84:87], v[194:197], v[214:217], v[84:87]
	v_mfma_f32_16x16x32_f16 v[80:83], v[194:197], v[222:225], v[80:83]
	v_mfma_f32_16x16x32_f16 v[76:79], v[202:205], v[214:217], v[76:79]
	v_mfma_f32_16x16x32_f16 v[72:75], v[202:205], v[222:225], v[72:75]
	v_mfma_f32_16x16x32_f16 v[68:71], v[210:213], v[214:217], v[68:71]
	v_mfma_f32_16x16x32_f16 v[64:67], v[210:213], v[222:225], v[64:67]
	s_barrier
	ds_read_b128 v[162:165], v132 offset:16384
	ds_read_b128 v[186:189], v132 offset:17408
	ds_read_b128 v[190:193], v132 offset:18432
	ds_read_b128 v[194:197], v132 offset:19456
	ds_read_b128 v[198:201], v132 offset:20480
	ds_read_b128 v[202:205], v132 offset:21504
	ds_read_b128 v[206:209], v132 offset:22528
	ds_read_b128 v[210:213], v132 offset:23552
	s_waitcnt vmcnt(4)
	s_barrier
	s_waitcnt lgkmcnt(0)
	s_waitcnt lgkmcnt(0)
	v_mfma_f32_16x16x32_f16 v[60:63], v[162:165], v[134:137], v[60:63]
	v_mfma_f32_16x16x32_f16 v[56:59], v[162:165], v[142:145], v[56:59]
	v_mfma_f32_16x16x32_f16 v[52:55], v[190:193], v[134:137], v[52:55]
	v_mfma_f32_16x16x32_f16 v[48:51], v[190:193], v[142:145], v[48:51]
	v_mfma_f32_16x16x32_f16 v[44:47], v[198:201], v[134:137], v[44:47]
	v_mfma_f32_16x16x32_f16 v[40:43], v[198:201], v[142:145], v[40:43]
	v_mfma_f32_16x16x32_f16 v[36:39], v[206:209], v[134:137], v[36:39]
	v_mfma_f32_16x16x32_f16 v[32:35], v[206:209], v[142:145], v[32:35]
	v_mfma_f32_16x16x32_f16 v[60:63], v[186:189], v[138:141], v[60:63]
	v_mfma_f32_16x16x32_f16 v[56:59], v[186:189], v[158:161], v[56:59]
	v_mfma_f32_16x16x32_f16 v[52:55], v[194:197], v[138:141], v[52:55]
	v_mfma_f32_16x16x32_f16 v[48:51], v[194:197], v[158:161], v[48:51]
	v_mfma_f32_16x16x32_f16 v[44:47], v[202:205], v[138:141], v[44:47]
	v_mfma_f32_16x16x32_f16 v[40:43], v[202:205], v[158:161], v[40:43]
	v_mfma_f32_16x16x32_f16 v[36:39], v[210:213], v[138:141], v[36:39]
	v_mfma_f32_16x16x32_f16 v[32:35], v[210:213], v[158:161], v[32:35]
	v_mfma_f32_16x16x32_f16 v[28:31], v[162:165], v[146:149], v[28:31]
	v_mfma_f32_16x16x32_f16 v[24:27], v[162:165], v[218:221], v[24:27]
	v_mfma_f32_16x16x32_f16 v[20:23], v[190:193], v[146:149], v[20:23]
	v_mfma_f32_16x16x32_f16 v[16:19], v[190:193], v[218:221], v[16:19]
	v_mfma_f32_16x16x32_f16 v[12:15], v[198:201], v[146:149], v[12:15]
	v_mfma_f32_16x16x32_f16 v[8:11], v[198:201], v[218:221], v[8:11]
	v_mfma_f32_16x16x32_f16 v[4:7], v[206:209], v[146:149], v[4:7]
	v_mfma_f32_16x16x32_f16 v[0:3], v[206:209], v[218:221], v[0:3]
	v_mfma_f32_16x16x32_f16 v[28:31], v[186:189], v[214:217], v[28:31]
	v_mfma_f32_16x16x32_f16 v[24:27], v[186:189], v[222:225], v[24:27]
	v_mfma_f32_16x16x32_f16 v[20:23], v[194:197], v[214:217], v[20:23]
	v_mfma_f32_16x16x32_f16 v[16:19], v[194:197], v[222:225], v[16:19]
	v_mfma_f32_16x16x32_f16 v[12:15], v[202:205], v[214:217], v[12:15]
	v_mfma_f32_16x16x32_f16 v[8:11], v[202:205], v[222:225], v[8:11]
	v_mfma_f32_16x16x32_f16 v[4:7], v[210:213], v[214:217], v[4:7]
	v_mfma_f32_16x16x32_f16 v[0:3], v[210:213], v[222:225], v[0:3]
	s_barrier
	ds_read_b128 v[134:137], v133 offset:32768
	ds_read_b128 v[138:141], v133 offset:33792
	ds_read_b128 v[142:145], v133 offset:34816
	ds_read_b128 v[146:149], v133 offset:35840
	ds_read_b128 v[158:161], v132 offset:32768
	ds_read_b128 v[162:165], v132 offset:33792
	ds_read_b128 v[186:189], v132 offset:34816
	ds_read_b128 v[190:193], v132 offset:35840
	ds_read_b128 v[194:197], v132 offset:36864
	ds_read_b128 v[198:201], v132 offset:37888
	ds_read_b128 v[202:205], v132 offset:38912
	ds_read_b128 v[206:209], v132 offset:39936
	s_waitcnt vmcnt(2)
	s_barrier
;   #define LDA(dst,b,h) for(int m=0;m<4;++m)for(int k=0;k<2;++k) \
;     dst[m][k]=*reinterpret_cast<const h8*>(la+(((b)*2+(h))*16384+m*2048+k*1024))
;   #define LDB(dst,b,h) for(int n=0;n<2;++n)for(int k=0;k<2;++k) \
;     dst[n][k]=*reinterpret_cast<const h8*>(lb+(((b)*2+(h))*16384+n*2048+k*1024))
;   #define MMA(ai,bj,At,Bt_) do{__builtin_amdgcn_s_setprio(1); \
;     for(int m=0;m<4;++m)for(int n=0;n<2;++n)for(int k=0;k<2;++k) \
;       acc[ai][bj][m][n]=__builtin_amdgcn_mfma_f32_16x16x32_f16(At[m][k],Bt_[n][k],acc[ai][bj][m][n],0,0,0); \
;     __builtin_amdgcn_s_setprio(0);}while(0)
;   #define WAIT_V(n) asm volatile("s_waitcnt vmcnt(" #n ")":::"memory")
;   #define WAIT_L(n) asm volatile("s_waitcnt lgkmcnt(" #n ")":::"memory")
;   #define BAR __builtin_amdgcn_s_barrier()
;     ...
;   { LDB(B0,1,0); LDA(At,1,0); WAIT_V(2); BAR; WAIT_L(0); MMA(0,0,At,B0); BAR;
;     LDB(B1,1,1); WAIT_V(0); BAR; WAIT_L(0); MMA(0,1,At,B1); BAR;
;     LDA(At,1,1); BAR; WAIT_L(0); MMA(1,0,At,B0); MMA(1,1,At,B1); BAR; }
;   if(wr==0)BAR;
	s_waitcnt lgkmcnt(0)
	s_waitcnt lgkmcnt(0)
	v_mfma_f32_16x16x32_f16 v[124:127], v[158:161], v[134:137], v[124:127]
	v_mfma_f32_16x16x32_f16 v[120:123], v[158:161], v[142:145], v[120:123]
	v_mfma_f32_16x16x32_f16 v[116:119], v[186:189], v[134:137], v[116:119]
	v_mfma_f32_16x16x32_f16 v[112:115], v[186:189], v[142:145], v[112:115]
	v_mfma_f32_16x16x32_f16 v[108:111], v[194:197], v[134:137], v[108:111]
	v_mfma_f32_16x16x32_f16 v[104:107], v[194:197], v[142:145], v[104:107]
	v_mfma_f32_16x16x32_f16 v[100:103], v[202:205], v[134:137], v[100:103]
	v_mfma_f32_16x16x32_f16 v[96:99], v[202:205], v[142:145], v[96:99]
	v_mfma_f32_16x16x32_f16 v[124:127], v[162:165], v[138:141], v[124:127]
	v_mfma_f32_16x16x32_f16 v[120:123], v[162:165], v[146:149], v[120:123]
	v_mfma_f32_16x16x32_f16 v[116:119], v[190:193], v[138:141], v[116:119]
	v_mfma_f32_16x16x32_f16 v[112:115], v[190:193], v[146:149], v[112:115]
	v_mfma_f32_16x16x32_f16 v[108:111], v[198:201], v[138:141], v[108:111]
	v_mfma_f32_16x16x32_f16 v[104:107], v[198:201], v[146:149], v[104:107]
	v_mfma_f32_16x16x32_f16 v[100:103], v[206:209], v[138:141], v[100:103]
	v_mfma_f32_16x16x32_f16 v[96:99], v[206:209], v[146:149], v[96:99]
	s_barrier
	ds_read_b128 v[210:213], v133 offset:49152
	ds_read_b128 v[214:217], v133 offset:50176
	ds_read_b128 v[218:221], v133 offset:51200
	ds_read_b128 v[222:225], v133 offset:52224
	s_waitcnt vmcnt(0)
	s_barrier
	s_waitcnt lgkmcnt(0)
	s_waitcnt lgkmcnt(0)
	v_mfma_f32_16x16x32_f16 v[92:95], v[158:161], v[210:213], v[92:95]
	v_mfma_f32_16x16x32_f16 v[88:91], v[158:161], v[218:221], v[88:91]
	v_mfma_f32_16x16x32_f16 v[84:87], v[186:189], v[210:213], v[84:87]
	v_mfma_f32_16x16x32_f16 v[80:83], v[186:189], v[218:221], v[80:83]
	v_mfma_f32_16x16x32_f16 v[76:79], v[194:197], v[210:213], v[76:79]
	v_mfma_f32_16x16x32_f16 v[72:75], v[194:197], v[218:221], v[72:75]
	v_mfma_f32_16x16x32_f16 v[68:71], v[202:205], v[210:213], v[68:71]
	v_mfma_f32_16x16x32_f16 v[64:67], v[202:205], v[218:221], v[64:67]
	v_mfma_f32_16x16x32_f16 v[92:95], v[162:165], v[214:217], v[92:95]
	v_mfma_f32_16x16x32_f16 v[88:91], v[162:165], v[222:225], v[88:91]
	v_mfma_f32_16x16x32_f16 v[84:87], v[190:193], v[214:217], v[84:87]
	v_mfma_f32_16x16x32_f16 v[80:83], v[190:193], v[222:225], v[80:83]
	v_mfma_f32_16x16x32_f16 v[76:79], v[198:201], v[214:217], v[76:79]
	v_mfma_f32_16x16x32_f16 v[72:75], v[198:201], v[222:225], v[72:75]
	v_mfma_f32_16x16x32_f16 v[68:71], v[206:209], v[214:217], v[68:71]
	v_mfma_f32_16x16x32_f16 v[64:67], v[206:209], v[222:225], v[64:67]
	s_barrier
	ds_read_b128 v[158:161], v132 offset:49152
	ds_read_b128 v[162:165], v132 offset:50176
	ds_read_b128 v[186:189], v132 offset:51200
	ds_read_b128 v[190:193], v132 offset:52224
	ds_read_b128 v[194:197], v132 offset:53248
	ds_read_b128 v[198:201], v132 offset:54272
	ds_read_b128 v[202:205], v132 offset:55296
	ds_read_b128 v[206:209], v132 offset:56320
	s_barrier
	s_waitcnt lgkmcnt(0)
	s_waitcnt lgkmcnt(0)
	v_mfma_f32_16x16x32_f16 v[60:63], v[158:161], v[134:137], v[60:63]
	v_mfma_f32_16x16x32_f16 v[56:59], v[158:161], v[142:145], v[56:59]
	v_mfma_f32_16x16x32_f16 v[52:55], v[186:189], v[134:137], v[52:55]
	v_mfma_f32_16x16x32_f16 v[48:51], v[186:189], v[142:145], v[48:51]
	v_mfma_f32_16x16x32_f16 v[44:47], v[194:197], v[134:137], v[44:47]
	v_mfma_f32_16x16x32_f16 v[40:43], v[194:197], v[142:145], v[40:43]
	v_mfma_f32_16x16x32_f16 v[36:39], v[202:205], v[134:137], v[36:39]
	v_mfma_f32_16x16x32_f16 v[32:35], v[202:205], v[142:145], v[32:35]
	v_mfma_f32_16x16x32_f16 v[60:63], v[162:165], v[138:141], v[60:63]
	v_mfma_f32_16x16x32_f16 v[56:59], v[162:165], v[146:149], v[56:59]
	v_mfma_f32_16x16x32_f16 v[52:55], v[190:193], v[138:141], v[52:55]
	v_mfma_f32_16x16x32_f16 v[48:51], v[190:193], v[146:149], v[48:51]
	v_mfma_f32_16x16x32_f16 v[44:47], v[198:201], v[138:141], v[44:47]
	v_mfma_f32_16x16x32_f16 v[40:43], v[198:201], v[146:149], v[40:43]
	v_mfma_f32_16x16x32_f16 v[36:39], v[206:209], v[138:141], v[36:39]
	v_mfma_f32_16x16x32_f16 v[32:35], v[206:209], v[146:149], v[32:35]
	v_mfma_f32_16x16x32_f16 v[28:31], v[158:161], v[210:213], v[28:31]
	v_mfma_f32_16x16x32_f16 v[24:27], v[158:161], v[218:221], v[24:27]
	v_mfma_f32_16x16x32_f16 v[20:23], v[186:189], v[210:213], v[20:23]
	v_mfma_f32_16x16x32_f16 v[16:19], v[186:189], v[218:221], v[16:19]
	v_mfma_f32_16x16x32_f16 v[12:15], v[194:197], v[210:213], v[12:15]
	v_mfma_f32_16x16x32_f16 v[8:11], v[194:197], v[218:221], v[8:11]
	v_mfma_f32_16x16x32_f16 v[4:7], v[202:205], v[210:213], v[4:7]
	v_mfma_f32_16x16x32_f16 v[0:3], v[202:205], v[218:221], v[0:3]
	v_mfma_f32_16x16x32_f16 v[28:31], v[162:165], v[214:217], v[28:31]
	v_mfma_f32_16x16x32_f16 v[24:27], v[162:165], v[222:225], v[24:27]
	v_mfma_f32_16x16x32_f16 v[20:23], v[190:193], v[214:217], v[20:23]
	v_mfma_f32_16x16x32_f16 v[16:19], v[190:193], v[222:225], v[16:19]
	v_mfma_f32_16x16x32_f16 v[12:15], v[198:201], v[214:217], v[12:15]
	v_mfma_f32_16x16x32_f16 v[8:11], v[198:201], v[222:225], v[8:11]
	v_mfma_f32_16x16x32_f16 v[4:7], v[206:209], v[214:217], v[4:7]
	v_mfma_f32_16x16x32_f16 v[0:3], v[206:209], v[222:225], v[0:3]
	s_movk_i32 s10, 0x100
	v_cmp_gt_u32_e32 vcc, s10, v131
	s_barrier
	s_and_saveexec_b64 s[10:11], vcc
	s_cbranch_execz .LBB0_326
	s_barrier

;   #define STAGE(P,BASE,LD,br,kt) do{ const HALF* _u=(BASE)+(long)(br)*(((&(LD))==&lda)?lda_u:(LD))+(long)(kt)*G_BK; \
;     for(int _i=0;_i<2;++_i){ \
;       __builtin_amdgcn_global_load_lds((const unsigned*)(_u+(long)_i*(((&(LD))==&lda)?stepa:stepb)+((&(LD))==&lda?oa0:ob0)), \
;         (unsigned*)((char*)(P)+t5*16+_i*8192),16,0,0);}}while(0)
;   #define LDA(dst,b,h) for(int m=0;m<4;++m)for(int k=0;k<2;++k) \
;     dst[m][k]=*reinterpret_cast<const h8*>(la+(((b)*2+(h))*16384+m*2048+k*1024))
;   #define LDB(dst,b,h) for(int n=0;n<2;++n)for(int k=0;k<2;++k) \
;     dst[n][k]=*reinterpret_cast<const h8*>(lb+(((b)*2+(h))*16384+n*2048+k*1024))
;   #define MMA(ai,bj,At,Bt_) do{__builtin_amdgcn_s_setprio(1); \
;     for(int m=0;m<4;++m)for(int n=0;n<2;++n)for(int k=0;k<2;++k) \
;       acc[ai][bj][m][n]=__builtin_amdgcn_mfma_f32_16x16x32_f16(At[m][k],Bt_[n][k],acc[ai][bj][m][n],0,0,0); \
;     __builtin_amdgcn_s_setprio(0);}while(0)
;   #define WAIT_V(n) asm volatile("s_waitcnt vmcnt(" #n ")":::"memory")
;   #define WAIT_L(n) asm volatile("s_waitcnt lgkmcnt(" #n ")":::"memory")
;   #define BAR __builtin_amdgcn_s_barrier()
;   #define SCHED __builtin_amdgcn_sched_barrier(0)
;     ...
;   {int _b=t5*16;int _r,_c;g_stage_rc(_b,_r,_c);
;     oa0=n2 ? (unsigned)((n2*(_r&63)+(_r>>6))*1024+_c) : (unsigned)(_r*lda+_c); ob0=(unsigned)(_r*ldb+_c);}
;   STAGE(SB(0,0),Bt,ldb,0,0); STAGE(SA(0,0),A,lda,0,0);
;   STAGE(SB(0,1),Bt,ldb,G_HALF,0); STAGE(SA(0,1),A,lda,G_HALF,0);
;   if(wr==1)BAR;
;   WAIT_V(4); BAR;
;   STAGE(SB(1,0),Bt,ldb,0,1); STAGE(SA(1,0),A,lda,0,1); STAGE(SB(1,1),Bt,ldb,G_HALF,1);
;   WAIT_V(6); BAR;
;   for(int t=0;t<nt-2;t+=2){
;     LDB(B0,0,0); SCHED; LDA(At,0,0); STAGE(SA(1,1),A,lda,G_HALF,t+1);
;     WAIT_L(8); BAR; WAIT_L(0); MMA(0,0,At,B0); BAR; SCHED;
;     LDB(B1,0,1); STAGE(SB(0,0),Bt,ldb,0,t+2);
;     BAR; WAIT_L(0); MMA(0,1,At,B1); BAR;
;     LDA(At,0,1); STAGE(SA(0,0),A,lda,0,t+2);
.LBB0_380:
	s_or_b64 exec, exec, s[0:1]
	v_lshlrev_b32_e32 v19, 6, v128
	v_lshlrev_b32_e32 v21, 2, v128
	v_and_b32_e32 v18, 48, v128
	v_and_b32_e32 v20, 0x3c0, v19
	v_and_b32_e32 v21, 32, v21
	v_bitop3_b32 v20, v20, v21, v18 bitop3:0x36
	v_lshlrev_b32_e32 v21, 13, v17
	v_add_u32_e32 v17, s29, v16
	v_and_b32_e32 v22, 0x3000, v19
	v_readfirstlane_b32 s15, v17
	v_add_u32_e32 v17, 0x2000, v17
	v_lshl_add_u64 v[18:19], v[4:5], 0, s[84:85]
	s_mov_b32 m0, s15
	s_mov_b64 s[16:17], 0x20080
	v_readfirstlane_b32 s14, v17
	v_add_u32_e32 v17, 0x8000, v12
	s_waitcnt vmcnt(4)
	s_barrier
	global_load_lds_dwordx4 v[18:19], off
	v_lshl_add_u64 v[18:19], v[4:5], 0, s[16:17]
	s_mov_b32 m0, s14
	v_readfirstlane_b32 s12, v17
	v_add_u32_e32 v17, 0xa000, v12
	global_load_lds_dwordx4 v[18:19], off
	v_lshl_add_u64 v[18:19], v[0:1], 0, s[84:85]
	s_mov_b32 m0, s12
	v_readfirstlane_b32 s7, v17
	v_add_u32_e32 v23, s62, v16
	global_load_lds_dwordx4 v[18:19], off
	v_lshl_add_u64 v[18:19], v[0:1], 0, s[16:17]
	s_mov_b32 m0, s7
	v_readfirstlane_b32 s1, v23
	global_load_lds_dwordx4 v[18:19], off
	v_lshl_add_u64 v[18:19], v[4:5], 0, s[88:89]
	s_mov_b32 m0, s1
	v_lshl_add_u64 v[16:17], v[4:5], 0, s[90:91]
	global_load_lds_dwordx4 v[18:19], off
	v_add_u32_e32 v18, 0x2000, v23
	v_add3_u32 v129, s95, v22, v20
	v_readfirstlane_b32 s0, v18
	s_mov_b32 m0, s0
	v_add3_u32 v131, 0, v21, v20
	global_load_lds_dwordx4 v[16:17], off
	s_waitcnt vmcnt(6)
	s_barrier
	ds_read_b128 v[16:19], v129
	ds_read_b128 v[20:23], v129 offset:1024
	ds_read_b128 v[24:27], v129 offset:2048
	ds_read_b128 v[28:31], v129 offset:3072
	v_add_u32_e32 v66, 0xc000, v12
	v_lshl_add_u64 v[64:65], v[6:7], 0, s[84:85]
	v_readfirstlane_b32 s13, v66
	v_add_u32_e32 v66, 0xe000, v12
	s_mov_b32 m0, s13
	v_readfirstlane_b32 s11, v66
	ds_read_b128 v[32:35], v131
	ds_read_b128 v[36:39], v131 offset:1024
	ds_read_b128 v[40:43], v131 offset:2048
	ds_read_b128 v[44:47], v131 offset:3072
	ds_read_b128 v[48:51], v131 offset:4096
	ds_read_b128 v[52:55], v131 offset:5120
	ds_read_b128 v[56:59], v131 offset:6144
	ds_read_b128 v[60:63], v131 offset:7168
	global_load_lds_dwordx4 v[64:65], off
	v_lshl_add_u64 v[64:65], v[6:7], 0, s[16:17]
	s_mov_b32 m0, s11
	s_nop 0
	global_load_lds_dwordx4 v[64:65], off
	s_waitcnt lgkmcnt(8)
	s_barrier
	s_waitcnt lgkmcnt(0)
	s_waitcnt lgkmcnt(0)
	v_mfma_f32_16x16x32_f16 v[64:67], v[32:35], v[16:19], 0
	v_mfma_f32_16x16x32_f16 v[68:71], v[32:35], v[24:27], 0
	v_mfma_f32_16x16x32_f16 v[72:75], v[40:43], v[16:19], 0
	v_mfma_f32_16x16x32_f16 v[76:79], v[40:43], v[24:27], 0
	v_mfma_f32_16x16x32_f16 v[80:83], v[48:51], v[16:19], 0
	v_mfma_f32_16x16x32_f16 v[84:87], v[48:51], v[24:27], 0
	v_mfma_f32_16x16x32_f16 v[88:91], v[56:59], v[16:19], 0
	v_mfma_f32_16x16x32_f16 v[92:95], v[56:59], v[24:27], 0
	v_mfma_f32_16x16x32_f16 v[64:67], v[36:39], v[20:23], v[64:67]
	v_mfma_f32_16x16x32_f16 v[68:71], v[36:39], v[28:31], v[68:71]
	v_mfma_f32_16x16x32_f16 v[72:75], v[44:47], v[20:23], v[72:75]
	v_mfma_f32_16x16x32_f16 v[76:79], v[44:47], v[28:31], v[76:79]
	v_mfma_f32_16x16x32_f16 v[80:83], v[52:55], v[20:23], v[80:83]
	v_mfma_f32_16x16x32_f16 v[84:87], v[52:55], v[28:31], v[84:87]
	v_mfma_f32_16x16x32_f16 v[88:91], v[60:63], v[20:23], v[88:91]
	v_mfma_f32_16x16x32_f16 v[92:95], v[60:63], v[28:31], v[92:95]
	s_barrier
	v_readfirstlane_b32 s16, v14
	v_lshl_add_u64 v[112:113], v[4:5], 0, s[92:93]
	s_mov_b32 m0, s16
	v_readfirstlane_b32 s16, v15
	ds_read_b128 v[96:99], v129 offset:16384
	ds_read_b128 v[100:103], v129 offset:17408
	ds_read_b128 v[104:107], v129 offset:18432
	ds_read_b128 v[108:111], v129 offset:19456
	global_load_lds_dwordx4 v[112:113], off
	v_lshl_add_u64 v[112:113], v[4:5], 0, s[66:67]
	s_mov_b32 m0, s16
	s_nop 0
	global_load_lds_dwordx4 v[112:113], off
	s_barrier
	s_waitcnt lgkmcnt(0)
	s_waitcnt lgkmcnt(0)
	v_mfma_f32_16x16x32_f16 v[112:115], v[32:35], v[96:99], 0
	v_mfma_f32_16x16x32_f16 v[32:35], v[32:35], v[104:107], 0
	v_mfma_f32_16x16x32_f16 v[112:115], v[36:39], v[100:103], v[112:115]
	v_mfma_f32_16x16x32_f16 v[32:35], v[36:39], v[108:111], v[32:35]
	v_mfma_f32_16x16x32_f16 v[36:39], v[40:43], v[96:99], 0
	v_mfma_f32_16x16x32_f16 v[40:43], v[40:43], v[104:107], 0
	v_mfma_f32_16x16x32_f16 v[36:39], v[44:47], v[100:103], v[36:39]
	v_mfma_f32_16x16x32_f16 v[40:43], v[44:47], v[108:111], v[40:43]
	v_mfma_f32_16x16x32_f16 v[44:47], v[48:51], v[96:99], 0
	v_mfma_f32_16x16x32_f16 v[48:51], v[48:51], v[104:107], 0
	v_mfma_f32_16x16x32_f16 v[44:47], v[52:55], v[100:103], v[44:47]
	v_mfma_f32_16x16x32_f16 v[48:51], v[52:55], v[108:111], v[48:51]
	v_mfma_f32_16x16x32_f16 v[52:55], v[56:59], v[96:99], 0
	v_mfma_f32_16x16x32_f16 v[56:59], v[56:59], v[104:107], 0
	v_mfma_f32_16x16x32_f16 v[52:55], v[60:63], v[100:103], v[52:55]
	v_mfma_f32_16x16x32_f16 v[56:59], v[60:63], v[108:111], v[56:59]
	v_readfirstlane_b32 s16, v12
	v_lshl_add_u64 v[14:15], v[0:1], 0, s[92:93]
	s_mov_b32 m0, s16
	v_readfirstlane_b32 s16, v13
	s_barrier
	ds_read_b128 v[60:63], v131 offset:16384
	ds_read_b128 v[116:119], v131 offset:17408
	ds_read_b128 v[120:123], v131 offset:18432
	ds_read_b128 v[124:127], v131 offset:19456
	ds_read_b128 v[132:135], v131 offset:20480
	ds_read_b128 v[136:139], v131 offset:21504
	ds_read_b128 v[140:143], v131 offset:22528
	ds_read_b128 v[144:147], v131 offset:23552
	global_load_lds_dwordx4 v[14:15], off
	v_lshl_add_u64 v[14:15], v[0:1], 0, s[66:67]
	s_mov_b32 m0, s16
	s_nop 0
	global_load_lds_dwordx4 v[14:15], off
	s_barrier
;   #define STAGE(P,BASE,LD,br,kt) do{ const HALF* _u=(BASE)+(long)(br)*(((&(LD))==&lda)?lda_u:(LD))+(long)(kt)*G_BK; \
;     for(int _i=0;_i<2;++_i){ \
;       __builtin_amdgcn_global_load_lds((const unsigned*)(_u+(long)_i*(((&(LD))==&lda)?stepa:stepb)+((&(LD))==&lda?oa0:ob0)), \
;         (unsigned*)((char*)(P)+t5*16+_i*8192),16,0,0);}}while(0)
;   #define LDA(dst,b,h) for(int m=0;m<4;++m)for(int k=0;k<2;++k) \
;     dst[m][k]=*reinterpret_cast<const h8*>(la+(((b)*2+(h))*16384+m*2048+k*1024))
;   #define LDB(dst,b,h) for(int n=0;n<2;++n)for(int k=0;k<2;++k) \
;     dst[n][k]=*reinterpret_cast<const h8*>(lb+(((b)*2+(h))*16384+n*2048+k*1024))
;   #define MMA(ai,bj,At,Bt_) do{__builtin_amdgcn_s_setprio(1); \
;     for(int m=0;m<4;++m)for(int n=0;n<2;++n)for(int k=0;k<2;++k) \
;       acc[ai][bj][m][n]=__builtin_amdgcn_mfma_f32_16x16x32_f16(At[m][k],Bt_[n][k],acc[ai][bj][m][n],0,0,0); \
;     __builtin_amdgcn_s_setprio(0);}while(0)
;   #define WAIT_V(n) asm volatile("s_waitcnt vmcnt(" #n ")":::"memory")
;   #define WAIT_L(n) asm volatile("s_waitcnt lgkmcnt(" #n ")":::"memory")
;   #define BAR __builtin_amdgcn_s_barrier()
;   #define SCHED __builtin_amdgcn_sched_barrier(0)
;     ...
;     BAR; WAIT_L(0); MMA(1,0,At,B0); BAR; SCHED;
;     STAGE(SB(0,1),Bt,ldb,G_HALF,t+2);
;     WAIT_V(6); BAR; MMA(1,1,At,B1); BAR;
;     LDB(B0,1,0); SCHED; LDA(At,1,0); STAGE(SA(0,1),A,lda,G_HALF,t+2);
;     WAIT_L(8); BAR; WAIT_L(0); MMA(0,0,At,B0); BAR; SCHED;
;     LDB(B1,1,1); STAGE(SB(1,0),Bt,ldb,0,t+3);
;     BAR; WAIT_L(0); MMA(0,1,At,B1); BAR;
	s_waitcnt lgkmcnt(0)
	s_waitcnt lgkmcnt(0)
	v_mfma_f32_16x16x32_f16 v[12:15], v[60:63], v[16:19], 0
	v_mfma_f32_16x16x32_f16 v[158:161], v[120:123], v[16:19], 0
	v_mfma_f32_16x16x32_f16 v[170:173], v[132:135], v[16:19], 0
	v_mfma_f32_16x16x32_f16 v[16:19], v[140:143], v[16:19], 0
	v_mfma_f32_16x16x32_f16 v[12:15], v[116:119], v[20:23], v[12:15]
	v_mfma_f32_16x16x32_f16 v[158:161], v[124:127], v[20:23], v[158:161]
	v_mfma_f32_16x16x32_f16 v[170:173], v[136:139], v[20:23], v[170:173]
	v_mfma_f32_16x16x32_f16 v[16:19], v[144:147], v[20:23], v[16:19]
	v_mfma_f32_16x16x32_f16 v[20:23], v[140:143], v[24:27], 0
	v_mfma_f32_16x16x32_f16 v[148:151], v[60:63], v[24:27], 0
	v_mfma_f32_16x16x32_f16 v[162:165], v[120:123], v[24:27], 0
	v_mfma_f32_16x16x32_f16 v[186:189], v[132:135], v[24:27], 0
	v_mfma_f32_16x16x32_f16 v[20:23], v[144:147], v[28:31], v[20:23]
	v_mfma_f32_16x16x32_f16 v[148:151], v[116:119], v[28:31], v[148:151]
	v_mfma_f32_16x16x32_f16 v[162:165], v[124:127], v[28:31], v[162:165]
	v_mfma_f32_16x16x32_f16 v[186:189], v[136:139], v[28:31], v[186:189]
	s_barrier
	v_readfirstlane_b32 s16, v10
	v_lshl_add_u64 v[24:25], v[2:3], 0, s[92:93]
	s_mov_b32 m0, s16
	v_readfirstlane_b32 s16, v11
	global_load_lds_dwordx4 v[24:25], off
	v_lshl_add_u64 v[24:25], v[2:3], 0, s[66:67]
	s_mov_b32 m0, s16
	s_nop 0
	global_load_lds_dwordx4 v[24:25], off
	s_waitcnt vmcnt(6)
	s_barrier
	v_mfma_f32_16x16x32_f16 v[24:27], v[60:63], v[96:99], 0
	v_mfma_f32_16x16x32_f16 v[28:31], v[60:63], v[104:107], 0
	v_mfma_f32_16x16x32_f16 v[24:27], v[116:119], v[100:103], v[24:27]
	v_mfma_f32_16x16x32_f16 v[28:31], v[116:119], v[108:111], v[28:31]
	v_mfma_f32_16x16x32_f16 v[60:63], v[120:123], v[96:99], 0
	v_mfma_f32_16x16x32_f16 v[116:119], v[120:123], v[104:107], 0
	v_mfma_f32_16x16x32_f16 v[120:123], v[132:135], v[96:99], 0
	v_mfma_f32_16x16x32_f16 v[96:99], v[140:143], v[96:99], 0
	v_mfma_f32_16x16x32_f16 v[60:63], v[124:127], v[100:103], v[60:63]
	v_mfma_f32_16x16x32_f16 v[116:119], v[124:127], v[108:111], v[116:119]
	v_mfma_f32_16x16x32_f16 v[120:123], v[136:139], v[100:103], v[120:123]
	v_mfma_f32_16x16x32_f16 v[124:127], v[132:135], v[104:107], 0
	v_mfma_f32_16x16x32_f16 v[96:99], v[144:147], v[100:103], v[96:99]
	v_mfma_f32_16x16x32_f16 v[100:103], v[140:143], v[104:107], 0
	v_mfma_f32_16x16x32_f16 v[124:127], v[136:139], v[108:111], v[124:127]
	v_mfma_f32_16x16x32_f16 v[100:103], v[144:147], v[108:111], v[100:103]
	s_barrier
	ds_read_b128 v[104:107], v129 offset:32768
	ds_read_b128 v[108:111], v129 offset:33792
	ds_read_b128 v[132:135], v129 offset:34816
	ds_read_b128 v[136:139], v129 offset:35840
	v_readfirstlane_b32 s16, v8
	v_lshl_add_u64 v[10:11], v[6:7], 0, s[92:93]
	s_mov_b32 m0, s16
	v_readfirstlane_b32 s16, v9
	ds_read_b128 v[140:143], v131 offset:32768
	ds_read_b128 v[144:147], v131 offset:33792
	ds_read_b128 v[190:193], v131 offset:34816
	ds_read_b128 v[194:197], v131 offset:35840
	ds_read_b128 v[198:201], v131 offset:36864
	ds_read_b128 v[202:205], v131 offset:37888
	ds_read_b128 v[206:209], v131 offset:38912
	ds_read_b128 v[210:213], v131 offset:39936
	global_load_lds_dwordx4 v[10:11], off
	v_lshl_add_u64 v[6:7], v[6:7], 0, s[66:67]
	s_mov_b32 m0, s16
	s_nop 0
	global_load_lds_dwordx4 v[6:7], off
	s_waitcnt lgkmcnt(8)
	s_barrier
	s_waitcnt lgkmcnt(0)
	s_waitcnt lgkmcnt(0)
	v_mfma_f32_16x16x32_f16 v[6:9], v[140:143], v[104:107], v[64:67]
	v_mfma_f32_16x16x32_f16 v[64:67], v[140:143], v[132:135], v[68:71]
	v_mfma_f32_16x16x32_f16 v[68:71], v[190:193], v[104:107], v[72:75]
	v_mfma_f32_16x16x32_f16 v[72:75], v[190:193], v[132:135], v[76:79]
	v_mfma_f32_16x16x32_f16 v[76:79], v[198:201], v[104:107], v[80:83]
	v_mfma_f32_16x16x32_f16 v[80:83], v[198:201], v[132:135], v[84:87]
	v_mfma_f32_16x16x32_f16 v[84:87], v[206:209], v[104:107], v[88:91]
	v_mfma_f32_16x16x32_f16 v[88:91], v[206:209], v[132:135], v[92:95]
	v_mfma_f32_16x16x32_f16 v[6:9], v[144:147], v[108:111], v[6:9]
	v_mfma_f32_16x16x32_f16 v[64:67], v[144:147], v[136:139], v[64:67]
	v_mfma_f32_16x16x32_f16 v[68:71], v[194:197], v[108:111], v[68:71]
	v_mfma_f32_16x16x32_f16 v[72:75], v[194:197], v[136:139], v[72:75]
	v_mfma_f32_16x16x32_f16 v[76:79], v[202:205], v[108:111], v[76:79]
	v_mfma_f32_16x16x32_f16 v[80:83], v[202:205], v[136:139], v[80:83]
	v_mfma_f32_16x16x32_f16 v[84:87], v[210:213], v[108:111], v[84:87]
	v_mfma_f32_16x16x32_f16 v[88:91], v[210:213], v[136:139], v[88:91]
	s_barrier
	s_mov_b32 m0, s15
	v_lshl_add_u64 v[10:11], v[4:5], 0, s[42:43]
	ds_read_b128 v[92:95], v129 offset:49152
	ds_read_b128 v[214:217], v129 offset:50176
	ds_read_b128 v[218:221], v129 offset:51200
	ds_read_b128 v[222:225], v129 offset:52224
	global_load_lds_dwordx4 v[10:11], off
	v_lshl_add_u64 v[4:5], v[4:5], 0, s[96:97]
	s_mov_b32 m0, s14
	s_nop 0
	global_load_lds_dwordx4 v[4:5], off
	s_barrier
	s_waitcnt lgkmcnt(0)
	s_waitcnt lgkmcnt(0)
	v_mfma_f32_16x16x32_f16 v[112:115], v[140:143], v[92:95], v[112:115]
	v_mfma_f32_16x16x32_f16 v[32:35], v[140:143], v[218:221], v[32:35]
	v_mfma_f32_16x16x32_f16 v[36:39], v[190:193], v[92:95], v[36:39]
	v_mfma_f32_16x16x32_f16 v[40:43], v[190:193], v[218:221], v[40:43]
	v_mfma_f32_16x16x32_f16 v[44:47], v[198:201], v[92:95], v[44:47]
	v_mfma_f32_16x16x32_f16 v[48:51], v[198:201], v[218:221], v[48:51]
	v_mfma_f32_16x16x32_f16 v[52:55], v[206:209], v[92:95], v[52:55]
	v_mfma_f32_16x16x32_f16 v[56:59], v[206:209], v[218:221], v[56:59]
	v_mfma_f32_16x16x32_f16 v[112:115], v[144:147], v[214:217], v[112:115]
	v_mfma_f32_16x16x32_f16 v[32:35], v[144:147], v[222:225], v[32:35]
	v_mfma_f32_16x16x32_f16 v[36:39], v[194:197], v[214:217], v[36:39]
	v_mfma_f32_16x16x32_f16 v[40:43], v[194:197], v[222:225], v[40:43]
	v_mfma_f32_16x16x32_f16 v[44:47], v[202:205], v[214:217], v[44:47]
	v_mfma_f32_16x16x32_f16 v[48:51], v[202:205], v[222:225], v[48:51]
	v_mfma_f32_16x16x32_f16 v[52:55], v[210:213], v[214:217], v[52:55]
	v_mfma_f32_16x16x32_f16 v[56:59], v[210:213], v[222:225], v[56:59]
	s_mov_b32 m0, s12
	v_lshl_add_u64 v[4:5], v[0:1], 0, s[42:43]
	s_barrier
;   #define STAGE(P,BASE,LD,br,kt) do{ const HALF* _u=(BASE)+(long)(br)*(((&(LD))==&lda)?lda_u:(LD))+(long)(kt)*G_BK; \
;     for(int _i=0;_i<2;++_i){ \
;       __builtin_amdgcn_global_load_lds((const unsigned*)(_u+(long)_i*(((&(LD))==&lda)?stepa:stepb)+((&(LD))==&lda?oa0:ob0)), \
;         (unsigned*)((char*)(P)+t5*16+_i*8192),16,0,0);}}while(0)
;   #define LDA(dst,b,h) for(int m=0;m<4;++m)for(int k=0;k<2;++k) \
;     dst[m][k]=*reinterpret_cast<const h8*>(la+(((b)*2+(h))*16384+m*2048+k*1024))
;   #define LDB(dst,b,h) for(int n=0;n<2;++n)for(int k=0;k<2;++k) \
;     dst[n][k]=*reinterpret_cast<const h8*>(lb+(((b)*2+(h))*16384+n*2048+k*1024))
;   #define MMA(ai,bj,At,Bt_) do{__builtin_amdgcn_s_setprio(1); \
;     for(int m=0;m<4;++m)for(int n=0;n<2;++n)for(int k=0;k<2;++k) \
;       acc[ai][bj][m][n]=__builtin_amdgcn_mfma_f32_16x16x32_f16(At[m][k],Bt_[n][k],acc[ai][bj][m][n],0,0,0); \
;     __builtin_amdgcn_s_setprio(0);}while(0)
;   #define WAIT_V(n) asm volatile("s_waitcnt vmcnt(" #n ")":::"memory")
;   #define WAIT_L(n) asm volatile("s_waitcnt lgkmcnt(" #n ")":::"memory")
;   #define BAR __builtin_amdgcn_s_barrier()
;   #define SCHED __builtin_amdgcn_sched_barrier(0)
;     ...
;     LDA(At,1,1); STAGE(SA(1,0),A,lda,0,t+3);
;     BAR; WAIT_L(0); MMA(1,0,At,B0); BAR; SCHED;
;     STAGE(SB(1,1),Bt,ldb,G_HALF,t+3);
;     WAIT_V(6); BAR; MMA(1,1,At,B1); BAR;
;   }
;   { LDB(B0,0,0); LDA(At,0,0); STAGE(SA(1,1),A,lda,G_HALF,nt-1);
;     BAR; WAIT_L(0); MMA(0,0,At,B0); BAR;
;     LDB(B1,0,1); BAR; WAIT_L(0); MMA(0,1,At,B1); BAR;
	ds_read_b128 v[140:143], v131 offset:49152
	ds_read_b128 v[144:147], v131 offset:50176
	ds_read_b128 v[190:193], v131 offset:51200
	ds_read_b128 v[194:197], v131 offset:52224
	ds_read_b128 v[198:201], v131 offset:53248
	ds_read_b128 v[202:205], v131 offset:54272
	ds_read_b128 v[206:209], v131 offset:55296
	ds_read_b128 v[210:213], v131 offset:56320
	global_load_lds_dwordx4 v[4:5], off
	v_lshl_add_u64 v[4:5], v[0:1], 0, s[96:97]
	s_mov_b32 m0, s7
	s_nop 0
	global_load_lds_dwordx4 v[4:5], off
	s_barrier
	s_waitcnt lgkmcnt(0)
	s_waitcnt lgkmcnt(0)
	v_mfma_f32_16x16x32_f16 v[10:13], v[140:143], v[104:107], v[12:15]
	v_mfma_f32_16x16x32_f16 v[14:17], v[206:209], v[104:107], v[16:19]
	v_mfma_f32_16x16x32_f16 v[18:21], v[206:209], v[132:135], v[20:23]
	v_mfma_f32_16x16x32_f16 v[10:13], v[144:147], v[108:111], v[10:13]
	v_mfma_f32_16x16x32_f16 v[148:151], v[140:143], v[132:135], v[148:151]
	v_mfma_f32_16x16x32_f16 v[158:161], v[190:193], v[104:107], v[158:161]
	v_mfma_f32_16x16x32_f16 v[162:165], v[190:193], v[132:135], v[162:165]
	v_mfma_f32_16x16x32_f16 v[170:173], v[198:201], v[104:107], v[170:173]
	v_mfma_f32_16x16x32_f16 v[186:189], v[198:201], v[132:135], v[186:189]
	v_mfma_f32_16x16x32_f16 v[14:17], v[210:213], v[108:111], v[14:17]
	v_mfma_f32_16x16x32_f16 v[18:21], v[210:213], v[136:139], v[18:21]
	v_mfma_f32_16x16x32_f16 v[148:151], v[144:147], v[136:139], v[148:151]
	v_mfma_f32_16x16x32_f16 v[158:161], v[194:197], v[108:111], v[158:161]
	v_mfma_f32_16x16x32_f16 v[162:165], v[194:197], v[136:139], v[162:165]
	v_mfma_f32_16x16x32_f16 v[170:173], v[202:205], v[108:111], v[170:173]
	v_mfma_f32_16x16x32_f16 v[186:189], v[202:205], v[136:139], v[186:189]
	s_barrier
	s_mov_b32 m0, s1
	v_lshl_add_u64 v[4:5], v[2:3], 0, s[42:43]
	global_load_lds_dwordx4 v[4:5], off
	v_lshl_add_u64 v[2:3], v[2:3], 0, s[96:97]
	s_mov_b32 m0, s0
	s_nop 0
	global_load_lds_dwordx4 v[2:3], off
	s_waitcnt vmcnt(6)
	s_barrier
	v_mfma_f32_16x16x32_f16 v[2:5], v[140:143], v[92:95], v[24:27]
	v_mfma_f32_16x16x32_f16 v[22:25], v[140:143], v[218:221], v[28:31]
	v_mfma_f32_16x16x32_f16 v[26:29], v[190:193], v[92:95], v[60:63]
	v_mfma_f32_16x16x32_f16 v[60:63], v[190:193], v[218:221], v[116:119]
	v_mfma_f32_16x16x32_f16 v[104:107], v[198:201], v[92:95], v[120:123]
	v_mfma_f32_16x16x32_f16 v[108:111], v[198:201], v[218:221], v[124:127]
	v_mfma_f32_16x16x32_f16 v[92:95], v[206:209], v[92:95], v[96:99]
	v_mfma_f32_16x16x32_f16 v[96:99], v[206:209], v[218:221], v[100:103]
	v_mfma_f32_16x16x32_f16 v[2:5], v[144:147], v[214:217], v[2:5]
	v_mfma_f32_16x16x32_f16 v[22:25], v[144:147], v[222:225], v[22:25]
	v_mfma_f32_16x16x32_f16 v[26:29], v[194:197], v[214:217], v[26:29]
	v_mfma_f32_16x16x32_f16 v[60:63], v[194:197], v[222:225], v[60:63]
	v_mfma_f32_16x16x32_f16 v[104:107], v[202:205], v[214:217], v[104:107]
	v_mfma_f32_16x16x32_f16 v[108:111], v[202:205], v[222:225], v[108:111]
	v_mfma_f32_16x16x32_f16 v[92:95], v[210:213], v[214:217], v[92:95]
	v_mfma_f32_16x16x32_f16 v[96:99], v[210:213], v[222:225], v[96:99]
	s_mov_b64 s[0:1], 0x40180
	s_mov_b32 m0, s13
	v_lshl_add_u64 v[30:31], v[0:1], 0, s[0:1]
	s_mov_b64 s[0:1], 0x60180
	s_barrier
	ds_read_b128 v[100:103], v129
	ds_read_b128 v[116:119], v129 offset:1024
	ds_read_b128 v[120:123], v129 offset:2048
	ds_read_b128 v[124:127], v129 offset:3072
	ds_read_b128 v[132:135], v131
	ds_read_b128 v[136:139], v131 offset:1024
	ds_read_b128 v[140:143], v131 offset:2048
	ds_read_b128 v[144:147], v131 offset:3072
	ds_read_b128 v[190:193], v131 offset:4096
	ds_read_b128 v[194:197], v131 offset:5120
	ds_read_b128 v[198:201], v131 offset:6144
	ds_read_b128 v[202:205], v131 offset:7168
	global_load_lds_dwordx4 v[30:31], off
	v_lshl_add_u64 v[0:1], v[0:1], 0, s[0:1]
	s_mov_b32 m0, s11
	s_nop 0
	global_load_lds_dwordx4 v[0:1], off
	s_barrier
	s_waitcnt lgkmcnt(0)
	s_waitcnt lgkmcnt(0)
	v_mfma_f32_16x16x32_f16 v[6:9], v[132:135], v[100:103], v[6:9]
	v_mfma_f32_16x16x32_f16 v[64:67], v[132:135], v[120:123], v[64:67]
	v_mfma_f32_16x16x32_f16 v[68:71], v[140:143], v[100:103], v[68:71]
	v_mfma_f32_16x16x32_f16 v[72:75], v[140:143], v[120:123], v[72:75]
	v_mfma_f32_16x16x32_f16 v[76:79], v[190:193], v[100:103], v[76:79]
	v_mfma_f32_16x16x32_f16 v[80:83], v[190:193], v[120:123], v[80:83]
	v_mfma_f32_16x16x32_f16 v[84:87], v[198:201], v[100:103], v[84:87]
	v_mfma_f32_16x16x32_f16 v[88:91], v[198:201], v[120:123], v[88:91]
	v_mfma_f32_16x16x32_f16 v[6:9], v[136:139], v[116:119], v[6:9]
	v_mfma_f32_16x16x32_f16 v[64:67], v[136:139], v[124:127], v[64:67]
	v_mfma_f32_16x16x32_f16 v[68:71], v[144:147], v[116:119], v[68:71]
	v_mfma_f32_16x16x32_f16 v[72:75], v[144:147], v[124:127], v[72:75]
	v_mfma_f32_16x16x32_f16 v[76:79], v[194:197], v[116:119], v[76:79]
	v_mfma_f32_16x16x32_f16 v[80:83], v[194:197], v[124:127], v[80:83]
	v_mfma_f32_16x16x32_f16 v[84:87], v[202:205], v[116:119], v[84:87]
	v_mfma_f32_16x16x32_f16 v[88:91], v[202:205], v[124:127], v[88:91]
	s_barrier
	ds_read_b128 v[206:209], v129 offset:16384
	ds_read_b128 v[210:213], v129 offset:17408
	ds_read_b128 v[214:217], v129 offset:18432
	ds_read_b128 v[218:221], v129 offset:19456
	s_barrier
;   #define LDA(dst,b,h) for(int m=0;m<4;++m)for(int k=0;k<2;++k) \
;     dst[m][k]=*reinterpret_cast<const h8*>(la+(((b)*2+(h))*16384+m*2048+k*1024))
;   #define LDB(dst,b,h) for(int n=0;n<2;++n)for(int k=0;k<2;++k) \
;     dst[n][k]=*reinterpret_cast<const h8*>(lb+(((b)*2+(h))*16384+n*2048+k*1024))
;   #define MMA(ai,bj,At,Bt_) do{__builtin_amdgcn_s_setprio(1); \
;     for(int m=0;m<4;++m)for(int n=0;n<2;++n)for(int k=0;k<2;++k) \
;       acc[ai][bj][m][n]=__builtin_amdgcn_mfma_f32_16x16x32_f16(At[m][k],Bt_[n][k],acc[ai][bj][m][n],0,0,0); \
;     __builtin_amdgcn_s_setprio(0);}while(0)
;   #define WAIT_V(n) asm volatile("s_waitcnt vmcnt(" #n ")":::"memory")
;   #define WAIT_L(n) asm volatile("s_waitcnt lgkmcnt(" #n ")":::"memory")
;   #define BAR __builtin_amdgcn_s_barrier()
;     ...
;     LDB(B1,0,1); BAR; WAIT_L(0); MMA(0,1,At,B1); BAR;
;     LDA(At,0,1); WAIT_V(4); BAR; WAIT_L(0); MMA(1,0,At,B0); MMA(1,1,At,B1); BAR; }
;   { LDB(B0,1,0); LDA(At,1,0); WAIT_V(2); BAR; WAIT_L(0); MMA(0,0,At,B0); BAR;
	s_waitcnt lgkmcnt(0)
	s_waitcnt lgkmcnt(0)
	v_mfma_f32_16x16x32_f16 v[30:33], v[132:135], v[214:217], v[32:35]
	v_mfma_f32_16x16x32_f16 v[34:37], v[140:143], v[206:209], v[36:39]
	v_mfma_f32_16x16x32_f16 v[38:41], v[140:143], v[214:217], v[40:43]
	v_mfma_f32_16x16x32_f16 v[42:45], v[190:193], v[206:209], v[44:47]
	v_mfma_f32_16x16x32_f16 v[46:49], v[190:193], v[214:217], v[48:51]
	v_mfma_f32_16x16x32_f16 v[50:53], v[198:201], v[206:209], v[52:55]
	v_mfma_f32_16x16x32_f16 v[54:57], v[198:201], v[214:217], v[56:59]
	v_mfma_f32_16x16x32_f16 v[112:115], v[132:135], v[206:209], v[112:115]
	v_mfma_f32_16x16x32_f16 v[30:33], v[136:139], v[218:221], v[30:33]
	v_mfma_f32_16x16x32_f16 v[34:37], v[144:147], v[210:213], v[34:37]
	v_mfma_f32_16x16x32_f16 v[38:41], v[144:147], v[218:221], v[38:41]
	v_mfma_f32_16x16x32_f16 v[42:45], v[194:197], v[210:213], v[42:45]
	v_mfma_f32_16x16x32_f16 v[46:49], v[194:197], v[218:221], v[46:49]
	v_mfma_f32_16x16x32_f16 v[50:53], v[202:205], v[210:213], v[50:53]
	v_mfma_f32_16x16x32_f16 v[54:57], v[202:205], v[218:221], v[54:57]
	v_mfma_f32_16x16x32_f16 v[222:225], v[136:139], v[210:213], v[112:115]
	s_barrier
	s_nop 0
	ds_read_b128 v[112:115], v131 offset:16384
	ds_read_b128 v[132:135], v131 offset:17408
	ds_read_b128 v[136:139], v131 offset:18432
	ds_read_b128 v[140:143], v131 offset:19456
	ds_read_b128 v[144:147], v131 offset:20480
	ds_read_b128 v[190:193], v131 offset:21504
	ds_read_b128 v[194:197], v131 offset:22528
	ds_read_b128 v[198:201], v131 offset:23552
	s_waitcnt vmcnt(4)
	s_barrier
	s_waitcnt lgkmcnt(0)
	s_waitcnt lgkmcnt(0)
	v_mfma_f32_16x16x32_f16 v[10:13], v[112:115], v[100:103], v[10:13]
	v_mfma_f32_16x16x32_f16 v[14:17], v[194:197], v[100:103], v[14:17]
	v_mfma_f32_16x16x32_f16 v[18:21], v[194:197], v[120:123], v[18:21]
	v_mfma_f32_16x16x32_f16 v[10:13], v[132:135], v[116:119], v[10:13]
	v_mfma_f32_16x16x32_f16 v[148:151], v[112:115], v[120:123], v[148:151]
	v_mfma_f32_16x16x32_f16 v[158:161], v[136:139], v[100:103], v[158:161]
	v_mfma_f32_16x16x32_f16 v[162:165], v[136:139], v[120:123], v[162:165]
	v_mfma_f32_16x16x32_f16 v[170:173], v[144:147], v[100:103], v[170:173]
	v_mfma_f32_16x16x32_f16 v[186:189], v[144:147], v[120:123], v[186:189]
	v_mfma_f32_16x16x32_f16 v[14:17], v[198:201], v[116:119], v[14:17]
	v_mfma_f32_16x16x32_f16 v[18:21], v[198:201], v[124:127], v[18:21]
	v_mfma_f32_16x16x32_f16 v[148:151], v[132:135], v[124:127], v[148:151]
	v_mfma_f32_16x16x32_f16 v[158:161], v[140:143], v[116:119], v[158:161]
	v_mfma_f32_16x16x32_f16 v[162:165], v[140:143], v[124:127], v[162:165]
	v_mfma_f32_16x16x32_f16 v[170:173], v[190:193], v[116:119], v[170:173]
	v_mfma_f32_16x16x32_f16 v[186:189], v[190:193], v[124:127], v[186:189]
	v_mfma_f32_16x16x32_f16 v[0:3], v[112:115], v[206:209], v[2:5]
	v_mfma_f32_16x16x32_f16 v[22:25], v[112:115], v[214:217], v[22:25]
	v_mfma_f32_16x16x32_f16 v[26:29], v[136:139], v[206:209], v[26:29]
	v_mfma_f32_16x16x32_f16 v[0:3], v[132:135], v[210:213], v[0:3]
	v_mfma_f32_16x16x32_f16 v[22:25], v[132:135], v[218:221], v[22:25]
	v_mfma_f32_16x16x32_f16 v[132:135], v[140:143], v[210:213], v[26:29]
	v_mfma_f32_16x16x32_f16 v[26:29], v[136:139], v[214:217], v[60:63]
	v_mfma_f32_16x16x32_f16 v[136:139], v[140:143], v[218:221], v[26:29]
	v_mfma_f32_16x16x32_f16 v[26:29], v[144:147], v[206:209], v[104:107]
	v_mfma_f32_16x16x32_f16 v[140:143], v[190:193], v[210:213], v[26:29]
	v_mfma_f32_16x16x32_f16 v[26:29], v[144:147], v[214:217], v[108:111]
	v_mfma_f32_16x16x32_f16 v[144:147], v[190:193], v[218:221], v[26:29]
	v_mfma_f32_16x16x32_f16 v[26:29], v[194:197], v[206:209], v[92:95]
	v_mfma_f32_16x16x32_f16 v[190:193], v[198:201], v[210:213], v[26:29]
	v_mfma_f32_16x16x32_f16 v[26:29], v[194:197], v[214:217], v[96:99]
	v_mfma_f32_16x16x32_f16 v[194:197], v[198:201], v[218:221], v[26:29]
	s_barrier
	s_nop 4
	ds_read_b128 v[26:29], v129 offset:32768
	ds_read_b128 v[198:201], v129 offset:33792
	ds_read_b128 v[202:205], v129 offset:34816
	ds_read_b128 v[206:209], v129 offset:35840
	ds_read_b128 v[58:61], v131 offset:32768
	ds_read_b128 v[210:213], v131 offset:33792
	ds_read_b128 v[214:217], v131 offset:34816
	ds_read_b128 v[218:221], v131 offset:35840
	ds_read_b128 v[226:229], v131 offset:36864
	ds_read_b128 v[230:233], v131 offset:37888
	ds_read_b128 v[234:237], v131 offset:38912
	ds_read_b128 v[238:241], v131 offset:39936
	s_waitcnt vmcnt(2)
	s_barrier
;   #define LDA(dst,b,h) for(int m=0;m<4;++m)for(int k=0;k<2;++k) \
;     dst[m][k]=*reinterpret_cast<const h8*>(la+(((b)*2+(h))*16384+m*2048+k*1024))
;   #define LDB(dst,b,h) for(int n=0;n<2;++n)for(int k=0;k<2;++k) \
;     dst[n][k]=*reinterpret_cast<const h8*>(lb+(((b)*2+(h))*16384+n*2048+k*1024))
;   #define MMA(ai,bj,At,Bt_) do{__builtin_amdgcn_s_setprio(1); \
;     for(int m=0;m<4;++m)for(int n=0;n<2;++n)for(int k=0;k<2;++k) \
;       acc[ai][bj][m][n]=__builtin_amdgcn_mfma_f32_16x16x32_f16(At[m][k],Bt_[n][k],acc[ai][bj][m][n],0,0,0); \
;     __builtin_amdgcn_s_setprio(0);}while(0)
;   #define WAIT_V(n) asm volatile("s_waitcnt vmcnt(" #n ")":::"memory")
;   #define WAIT_L(n) asm volatile("s_waitcnt lgkmcnt(" #n ")":::"memory")
;   #define BAR __builtin_amdgcn_s_barrier()
;     ...
;   { LDB(B0,1,0); LDA(At,1,0); WAIT_V(2); BAR; WAIT_L(0); MMA(0,0,At,B0); BAR;
;     LDB(B1,1,1); WAIT_V(0); BAR; WAIT_L(0); MMA(0,1,At,B1); BAR;
;     LDA(At,1,1); BAR; WAIT_L(0); MMA(1,0,At,B0); MMA(1,1,At,B1); BAR; }
;   if(wr==0)BAR;
	s_waitcnt lgkmcnt(0)
	s_waitcnt lgkmcnt(0)
	v_mfma_f32_16x16x32_f16 v[4:7], v[58:61], v[26:29], v[6:9]
	v_mfma_f32_16x16x32_f16 v[124:127], v[210:213], v[198:201], v[4:7]
	v_mfma_f32_16x16x32_f16 v[4:7], v[58:61], v[202:205], v[64:67]
	v_mfma_f32_16x16x32_f16 v[120:123], v[210:213], v[206:209], v[4:7]
	v_mfma_f32_16x16x32_f16 v[4:7], v[214:217], v[26:29], v[68:71]
	v_mfma_f32_16x16x32_f16 v[116:119], v[218:221], v[198:201], v[4:7]
	v_mfma_f32_16x16x32_f16 v[4:7], v[214:217], v[202:205], v[72:75]
	v_mfma_f32_16x16x32_f16 v[112:115], v[218:221], v[206:209], v[4:7]
	v_mfma_f32_16x16x32_f16 v[4:7], v[226:229], v[26:29], v[76:79]
	v_mfma_f32_16x16x32_f16 v[108:111], v[230:233], v[198:201], v[4:7]
	v_mfma_f32_16x16x32_f16 v[4:7], v[226:229], v[202:205], v[80:83]
	v_mfma_f32_16x16x32_f16 v[104:107], v[230:233], v[206:209], v[4:7]
	v_mfma_f32_16x16x32_f16 v[4:7], v[234:237], v[26:29], v[84:87]
	v_mfma_f32_16x16x32_f16 v[100:103], v[238:241], v[198:201], v[4:7]
	v_mfma_f32_16x16x32_f16 v[4:7], v[234:237], v[202:205], v[88:91]
	v_mfma_f32_16x16x32_f16 v[96:99], v[238:241], v[206:209], v[4:7]
	s_barrier
	s_nop 4
	ds_read_b128 v[4:7], v129 offset:49152
	ds_read_b128 v[242:245], v129 offset:50176
	ds_read_b128 v[246:249], v129 offset:51200
	ds_read_b128 v[250:253], v129 offset:52224
	s_waitcnt vmcnt(0)
	s_barrier
	s_waitcnt lgkmcnt(0)
	s_waitcnt lgkmcnt(0)
	v_mfma_f32_16x16x32_f16 v[30:33], v[58:61], v[246:249], v[30:33]
	v_mfma_f32_16x16x32_f16 v[88:91], v[210:213], v[250:253], v[30:33]
	v_mfma_f32_16x16x32_f16 v[30:33], v[214:217], v[4:7], v[34:37]
	v_mfma_f32_16x16x32_f16 v[84:87], v[218:221], v[242:245], v[30:33]
	v_mfma_f32_16x16x32_f16 v[30:33], v[214:217], v[246:249], v[38:41]
	v_mfma_f32_16x16x32_f16 v[80:83], v[218:221], v[250:253], v[30:33]
	v_mfma_f32_16x16x32_f16 v[30:33], v[226:229], v[4:7], v[42:45]
	v_mfma_f32_16x16x32_f16 v[76:79], v[230:233], v[242:245], v[30:33]
	v_mfma_f32_16x16x32_f16 v[30:33], v[226:229], v[246:249], v[46:49]
	v_mfma_f32_16x16x32_f16 v[72:75], v[230:233], v[250:253], v[30:33]
	v_mfma_f32_16x16x32_f16 v[30:33], v[234:237], v[4:7], v[50:53]
	v_mfma_f32_16x16x32_f16 v[62:65], v[58:61], v[4:7], v[222:225]
	v_mfma_f32_16x16x32_f16 v[68:71], v[238:241], v[242:245], v[30:33]
	v_mfma_f32_16x16x32_f16 v[30:33], v[234:237], v[246:249], v[54:57]
	v_mfma_f32_16x16x32_f16 v[92:95], v[210:213], v[242:245], v[62:65]
	v_mfma_f32_16x16x32_f16 v[64:67], v[238:241], v[250:253], v[30:33]
	s_barrier
	ds_read_b128 v[210:213], v131 offset:49152
	ds_read_b128 v[214:217], v131 offset:50176
	ds_read_b128 v[218:221], v131 offset:51200
	ds_read_b128 v[222:225], v131 offset:52224
	ds_read_b128 v[226:229], v131 offset:53248
	ds_read_b128 v[230:233], v131 offset:54272
	ds_read_b128 v[234:237], v131 offset:55296
	ds_read_b128 v[238:241], v131 offset:56320
	s_barrier
	s_waitcnt lgkmcnt(0)
	s_waitcnt lgkmcnt(0)
	v_mfma_f32_16x16x32_f16 v[8:11], v[210:213], v[26:29], v[10:13]
	v_mfma_f32_16x16x32_f16 v[60:63], v[214:217], v[198:201], v[8:11]
	v_mfma_f32_16x16x32_f16 v[8:11], v[210:213], v[202:205], v[148:151]
	v_mfma_f32_16x16x32_f16 v[56:59], v[214:217], v[206:209], v[8:11]
	v_mfma_f32_16x16x32_f16 v[8:11], v[218:221], v[26:29], v[158:161]
	v_mfma_f32_16x16x32_f16 v[52:55], v[222:225], v[198:201], v[8:11]
	v_mfma_f32_16x16x32_f16 v[8:11], v[218:221], v[202:205], v[162:165]
	v_mfma_f32_16x16x32_f16 v[48:51], v[222:225], v[206:209], v[8:11]
	v_mfma_f32_16x16x32_f16 v[8:11], v[226:229], v[26:29], v[170:173]
	v_mfma_f32_16x16x32_f16 v[44:47], v[230:233], v[198:201], v[8:11]
	v_mfma_f32_16x16x32_f16 v[8:11], v[226:229], v[202:205], v[186:189]
	v_mfma_f32_16x16x32_f16 v[40:43], v[230:233], v[206:209], v[8:11]
	v_mfma_f32_16x16x32_f16 v[8:11], v[234:237], v[26:29], v[14:17]
	v_mfma_f32_16x16x32_f16 v[36:39], v[238:241], v[198:201], v[8:11]
	v_mfma_f32_16x16x32_f16 v[8:11], v[234:237], v[202:205], v[18:21]
	v_mfma_f32_16x16x32_f16 v[32:35], v[238:241], v[206:209], v[8:11]
	v_mfma_f32_16x16x32_f16 v[0:3], v[210:213], v[4:7], v[0:3]
	v_mfma_f32_16x16x32_f16 v[28:31], v[214:217], v[242:245], v[0:3]
	v_mfma_f32_16x16x32_f16 v[0:3], v[210:213], v[246:249], v[22:25]
	v_mfma_f32_16x16x32_f16 v[24:27], v[214:217], v[250:253], v[0:3]
	v_mfma_f32_16x16x32_f16 v[0:3], v[218:221], v[4:7], v[132:135]
	v_mfma_f32_16x16x32_f16 v[20:23], v[222:225], v[242:245], v[0:3]
	v_mfma_f32_16x16x32_f16 v[0:3], v[218:221], v[246:249], v[136:139]
	v_mfma_f32_16x16x32_f16 v[16:19], v[222:225], v[250:253], v[0:3]
	v_mfma_f32_16x16x32_f16 v[0:3], v[226:229], v[4:7], v[140:143]
	v_mfma_f32_16x16x32_f16 v[12:15], v[230:233], v[242:245], v[0:3]
	v_mfma_f32_16x16x32_f16 v[0:3], v[226:229], v[246:249], v[144:147]
	v_mfma_f32_16x16x32_f16 v[8:11], v[230:233], v[250:253], v[0:3]
	v_mfma_f32_16x16x32_f16 v[0:3], v[234:237], v[4:7], v[190:193]
	v_mfma_f32_16x16x32_f16 v[4:7], v[238:241], v[242:245], v[0:3]
	v_mfma_f32_16x16x32_f16 v[0:3], v[234:237], v[246:249], v[194:197]
	v_mfma_f32_16x16x32_f16 v[0:3], v[238:241], v[250:253], v[0:3]
	s_movk_i32 s0, 0x100
	v_cmp_gt_u32_e32 vcc, s0, v128
	s_barrier
	s_and_saveexec_b64 s[0:1], vcc
	s_cbranch_execz .LBB0_382
	s_barrier

;   #define STAGE(P,BASE,LD,br,kt) do{ const HALF* _u=(BASE)+(long)(br)*(((&(LD))==&lda)?lda_u:(LD))+(long)(kt)*G_BK; \
;     for(int _i=0;_i<2;++_i){ \
;       __builtin_amdgcn_global_load_lds((const unsigned*)(_u+(long)_i*(((&(LD))==&lda)?stepa:stepb)+((&(LD))==&lda?oa0:ob0)), \
;         (unsigned*)((char*)(P)+t5*16+_i*8192),16,0,0);}}while(0)
;   #define LDA(dst,b,h) for(int m=0;m<4;++m)for(int k=0;k<2;++k) \
;     dst[m][k]=*reinterpret_cast<const h8*>(la+(((b)*2+(h))*16384+m*2048+k*1024))
;   #define LDB(dst,b,h) for(int n=0;n<2;++n)for(int k=0;k<2;++k) \
;     dst[n][k]=*reinterpret_cast<const h8*>(lb+(((b)*2+(h))*16384+n*2048+k*1024))
;   #define MMA(ai,bj,At,Bt_) do{__builtin_amdgcn_s_setprio(1); \
;     for(int m=0;m<4;++m)for(int n=0;n<2;++n)for(int k=0;k<2;++k) \
;       acc[ai][bj][m][n]=__builtin_amdgcn_mfma_f32_16x16x32_f16(At[m][k],Bt_[n][k],acc[ai][bj][m][n],0,0,0); \
;     __builtin_amdgcn_s_setprio(0);}while(0)
;   #define WAIT_V(n) asm volatile("s_waitcnt vmcnt(" #n ")":::"memory")
;   #define WAIT_L(n) asm volatile("s_waitcnt lgkmcnt(" #n ")":::"memory")
;   #define BAR __builtin_amdgcn_s_barrier()
;   #define SCHED __builtin_amdgcn_sched_barrier(0)
;     ...
;   const int _ob=fr*64+fq*16, _sw=_ob^(((_ob>>9)&1)<<5);
;   const char* la=(const char*)shm+wr*8192+_sw;
;   const char* lb=(const char*)shm+65536+wc*4096+_sw;
;   unsigned oa0, ob0;
;   const int stepa = n2 ? 1024 : 64 * lda, stepb = 64 * ldb;
;   const int lda_u = n2 ? 16 : lda;
;   {int _b=t5*16;int _r,_c;g_stage_rc(_b,_r,_c);
;     oa0=n2 ? (unsigned)((n2*(_r&63)+(_r>>6))*1024+_c) : (unsigned)(_r*lda+_c); ob0=(unsigned)(_r*ldb+_c);}
;   STAGE(SB(0,0),Bt,ldb,0,0); STAGE(SA(0,0),A,lda,0,0);
;   STAGE(SB(0,1),Bt,ldb,G_HALF,0); STAGE(SA(0,1),A,lda,G_HALF,0);
;   if(wr==1)BAR;
;   WAIT_V(4); BAR;
;   STAGE(SB(1,0),Bt,ldb,0,1); STAGE(SA(1,0),A,lda,0,1); STAGE(SB(1,1),Bt,ldb,G_HALF,1);
;   WAIT_V(6); BAR;
;   for(int t=0;t<nt-2;t+=2){
;     LDB(B0,0,0); SCHED; LDA(At,0,0); STAGE(SA(1,1),A,lda,G_HALF,t+1);
;     WAIT_L(8); BAR; WAIT_L(0); MMA(0,0,At,B0); BAR; SCHED;
;     LDB(B1,0,1); STAGE(SB(0,0),Bt,ldb,0,t+2);
;     BAR; WAIT_L(0); MMA(0,1,At,B1); BAR;
;     LDA(At,0,1); STAGE(SA(0,0),A,lda,0,t+2);
.LBB0_394:
	s_or_b64 exec, exec, s[2:3]
	v_lshlrev_b32_e32 v19, 6, v129
	v_lshlrev_b32_e32 v21, 2, v129
	v_and_b32_e32 v18, 48, v129
	v_and_b32_e32 v20, 0x3c0, v19
	v_and_b32_e32 v21, 32, v21
	v_bitop3_b32 v20, v20, v21, v18 bitop3:0x36
	v_lshlrev_b32_e32 v21, 13, v17
	v_add_u32_e32 v17, s29, v16
	v_and_b32_e32 v22, 0x3000, v19
	v_readfirstlane_b32 s16, v17
	v_add_u32_e32 v17, 0x2000, v17
	v_lshl_add_u64 v[18:19], v[4:5], 0, s[84:85]
	s_mov_b32 m0, s16
	s_mov_b64 s[20:21], 0x100080
	v_readfirstlane_b32 s15, v17
	v_add_u32_e32 v17, 0x8000, v12
	s_waitcnt vmcnt(4)
	s_barrier
	global_load_lds_dwordx4 v[18:19], off
	v_lshl_add_u64 v[18:19], v[4:5], 0, s[20:21]
	s_mov_b32 m0, s15
	v_readfirstlane_b32 s12, v17
	v_add_u32_e32 v17, 0xa000, v12
	global_load_lds_dwordx4 v[18:19], off
	v_lshl_add_u64 v[18:19], v[0:1], 0, s[84:85]
	s_mov_b32 m0, s12
	v_readfirstlane_b32 s11, v17
	global_load_lds_dwordx4 v[18:19], off
	v_lshl_add_u64 v[18:19], v[0:1], 0, s[20:21]
	s_mov_b32 m0, s11
	s_mov_b64 s[2:3], 0x200080
	v_add_u32_e32 v23, s62, v16
	global_load_lds_dwordx4 v[18:19], off
	v_lshl_add_u64 v[18:19], v[4:5], 0, s[2:3]
	v_readfirstlane_b32 s2, v23
	s_mov_b32 m0, s2
	s_mov_b64 s[18:19], 0x300080
	global_load_lds_dwordx4 v[18:19], off
	v_add_u32_e32 v18, 0x2000, v23
	v_lshl_add_u64 v[16:17], v[4:5], 0, s[18:19]
	v_readfirstlane_b32 s3, v18
	s_mov_b32 m0, s3
	v_add3_u32 v150, s95, v22, v20
	global_load_lds_dwordx4 v[16:17], off
	s_waitcnt vmcnt(6)
	s_barrier
	v_add3_u32 v151, 0, v21, v20
	ds_read_b128 v[16:19], v150
	ds_read_b128 v[20:23], v150 offset:1024
	ds_read_b128 v[24:27], v150 offset:2048
	ds_read_b128 v[28:31], v150 offset:3072
	v_add_u32_e32 v66, 0xc000, v12
	v_lshl_add_u64 v[64:65], v[6:7], 0, s[84:85]
	v_readfirstlane_b32 s14, v66
	v_add_u32_e32 v66, 0xe000, v12
	s_mov_b32 m0, s14
	v_readfirstlane_b32 s13, v66
	ds_read_b128 v[32:35], v151
	ds_read_b128 v[36:39], v151 offset:1024
	ds_read_b128 v[40:43], v151 offset:2048
	ds_read_b128 v[44:47], v151 offset:3072
	ds_read_b128 v[48:51], v151 offset:4096
	ds_read_b128 v[52:55], v151 offset:5120
	ds_read_b128 v[56:59], v151 offset:6144
	ds_read_b128 v[60:63], v151 offset:7168
	global_load_lds_dwordx4 v[64:65], off
	v_lshl_add_u64 v[64:65], v[6:7], 0, s[20:21]
	s_mov_b32 m0, s13
	s_nop 0
	global_load_lds_dwordx4 v[64:65], off
	s_waitcnt lgkmcnt(8)
	s_barrier
	s_waitcnt lgkmcnt(0)
	s_waitcnt lgkmcnt(0)
	v_mfma_f32_16x16x32_f16 v[64:67], v[32:35], v[16:19], 0
	v_mfma_f32_16x16x32_f16 v[68:71], v[32:35], v[24:27], 0
	v_mfma_f32_16x16x32_f16 v[72:75], v[40:43], v[16:19], 0
	v_mfma_f32_16x16x32_f16 v[76:79], v[40:43], v[24:27], 0
	v_mfma_f32_16x16x32_f16 v[80:83], v[48:51], v[16:19], 0
	v_mfma_f32_16x16x32_f16 v[84:87], v[48:51], v[24:27], 0
	v_mfma_f32_16x16x32_f16 v[88:91], v[56:59], v[16:19], 0
	v_mfma_f32_16x16x32_f16 v[92:95], v[56:59], v[24:27], 0
	v_mfma_f32_16x16x32_f16 v[64:67], v[36:39], v[20:23], v[64:67]
	v_mfma_f32_16x16x32_f16 v[68:71], v[36:39], v[28:31], v[68:71]
	v_mfma_f32_16x16x32_f16 v[72:75], v[44:47], v[20:23], v[72:75]
	v_mfma_f32_16x16x32_f16 v[76:79], v[44:47], v[28:31], v[76:79]
	v_mfma_f32_16x16x32_f16 v[80:83], v[52:55], v[20:23], v[80:83]
	v_mfma_f32_16x16x32_f16 v[84:87], v[52:55], v[28:31], v[84:87]
	v_mfma_f32_16x16x32_f16 v[88:91], v[60:63], v[20:23], v[88:91]
	v_mfma_f32_16x16x32_f16 v[92:95], v[60:63], v[28:31], v[92:95]
	s_barrier
	v_readfirstlane_b32 s17, v14
	v_lshl_add_u64 v[112:113], v[4:5], 0, s[92:93]
	s_mov_b32 m0, s17
	s_mov_b64 s[18:19], 0x100100
	v_readfirstlane_b32 s17, v15
	ds_read_b128 v[96:99], v150 offset:16384
	ds_read_b128 v[100:103], v150 offset:17408
	ds_read_b128 v[104:107], v150 offset:18432
	ds_read_b128 v[108:111], v150 offset:19456
	global_load_lds_dwordx4 v[112:113], off
	v_lshl_add_u64 v[112:113], v[4:5], 0, s[18:19]
	s_mov_b32 m0, s17
	s_nop 0
	global_load_lds_dwordx4 v[112:113], off
	s_barrier
	s_waitcnt lgkmcnt(0)
	s_waitcnt lgkmcnt(0)
	v_mfma_f32_16x16x32_f16 v[112:115], v[32:35], v[96:99], 0
	v_mfma_f32_16x16x32_f16 v[32:35], v[32:35], v[104:107], 0
	v_mfma_f32_16x16x32_f16 v[112:115], v[36:39], v[100:103], v[112:115]
	v_mfma_f32_16x16x32_f16 v[32:35], v[36:39], v[108:111], v[32:35]
	v_mfma_f32_16x16x32_f16 v[36:39], v[40:43], v[96:99], 0
	v_mfma_f32_16x16x32_f16 v[40:43], v[40:43], v[104:107], 0
	v_mfma_f32_16x16x32_f16 v[36:39], v[44:47], v[100:103], v[36:39]
	v_mfma_f32_16x16x32_f16 v[40:43], v[44:47], v[108:111], v[40:43]
	v_mfma_f32_16x16x32_f16 v[44:47], v[48:51], v[96:99], 0
	v_mfma_f32_16x16x32_f16 v[48:51], v[48:51], v[104:107], 0
	v_mfma_f32_16x16x32_f16 v[44:47], v[52:55], v[100:103], v[44:47]
	v_mfma_f32_16x16x32_f16 v[48:51], v[52:55], v[108:111], v[48:51]
	v_mfma_f32_16x16x32_f16 v[52:55], v[56:59], v[96:99], 0
	v_mfma_f32_16x16x32_f16 v[56:59], v[56:59], v[104:107], 0
	v_mfma_f32_16x16x32_f16 v[52:55], v[60:63], v[100:103], v[52:55]
	v_mfma_f32_16x16x32_f16 v[56:59], v[60:63], v[108:111], v[56:59]
	v_readfirstlane_b32 s17, v12
	v_lshl_add_u64 v[14:15], v[0:1], 0, s[92:93]
	s_mov_b32 m0, s17
	v_readfirstlane_b32 s17, v13
	s_barrier
	ds_read_b128 v[60:63], v151 offset:16384
	ds_read_b128 v[116:119], v151 offset:17408
	ds_read_b128 v[120:123], v151 offset:18432
	ds_read_b128 v[124:127], v151 offset:19456
	ds_read_b128 v[130:133], v151 offset:20480
	ds_read_b128 v[134:137], v151 offset:21504
	ds_read_b128 v[138:141], v151 offset:22528
	ds_read_b128 v[142:145], v151 offset:23552
	global_load_lds_dwordx4 v[14:15], off
	v_lshl_add_u64 v[14:15], v[0:1], 0, s[18:19]
	s_mov_b32 m0, s17
	s_nop 0
	global_load_lds_dwordx4 v[14:15], off
	s_barrier
;   #define STAGE(P,BASE,LD,br,kt) do{ const HALF* _u=(BASE)+(long)(br)*(((&(LD))==&lda)?lda_u:(LD))+(long)(kt)*G_BK; \
;     for(int _i=0;_i<2;++_i){ \
;       __builtin_amdgcn_global_load_lds((const unsigned*)(_u+(long)_i*(((&(LD))==&lda)?stepa:stepb)+((&(LD))==&lda?oa0:ob0)), \
;         (unsigned*)((char*)(P)+t5*16+_i*8192),16,0,0);}}while(0)
;   #define LDA(dst,b,h) for(int m=0;m<4;++m)for(int k=0;k<2;++k) \
;     dst[m][k]=*reinterpret_cast<const h8*>(la+(((b)*2+(h))*16384+m*2048+k*1024))
;   #define LDB(dst,b,h) for(int n=0;n<2;++n)for(int k=0;k<2;++k) \
;     dst[n][k]=*reinterpret_cast<const h8*>(lb+(((b)*2+(h))*16384+n*2048+k*1024))
;   #define MMA(ai,bj,At,Bt_) do{__builtin_amdgcn_s_setprio(1); \
;     for(int m=0;m<4;++m)for(int n=0;n<2;++n)for(int k=0;k<2;++k) \
;       acc[ai][bj][m][n]=__builtin_amdgcn_mfma_f32_16x16x32_f16(At[m][k],Bt_[n][k],acc[ai][bj][m][n],0,0,0); \
;     __builtin_amdgcn_s_setprio(0);}while(0)
;   #define WAIT_V(n) asm volatile("s_waitcnt vmcnt(" #n ")":::"memory")
;   #define WAIT_L(n) asm volatile("s_waitcnt lgkmcnt(" #n ")":::"memory")
;   #define BAR __builtin_amdgcn_s_barrier()
;   #define SCHED __builtin_amdgcn_sched_barrier(0)
;     ...
;     BAR; WAIT_L(0); MMA(1,0,At,B0); BAR; SCHED;
;     STAGE(SB(0,1),Bt,ldb,G_HALF,t+2);
;     WAIT_V(6); BAR; MMA(1,1,At,B1); BAR;
;     LDB(B0,1,0); SCHED; LDA(At,1,0); STAGE(SA(0,1),A,lda,G_HALF,t+2);
;     WAIT_L(8); BAR; WAIT_L(0); MMA(0,0,At,B0); BAR; SCHED;
;     LDB(B1,1,1); STAGE(SB(1,0),Bt,ldb,0,t+3);
;     BAR; WAIT_L(0); MMA(0,1,At,B1); BAR;
	s_waitcnt lgkmcnt(0)
	s_waitcnt lgkmcnt(0)
	v_mfma_f32_16x16x32_f16 v[12:15], v[60:63], v[16:19], 0
	v_mfma_f32_16x16x32_f16 v[158:161], v[120:123], v[16:19], 0
	v_mfma_f32_16x16x32_f16 v[186:189], v[130:133], v[16:19], 0
	v_mfma_f32_16x16x32_f16 v[16:19], v[138:141], v[16:19], 0
	v_mfma_f32_16x16x32_f16 v[12:15], v[116:119], v[20:23], v[12:15]
	v_mfma_f32_16x16x32_f16 v[158:161], v[124:127], v[20:23], v[158:161]
	v_mfma_f32_16x16x32_f16 v[186:189], v[134:137], v[20:23], v[186:189]
	v_mfma_f32_16x16x32_f16 v[16:19], v[142:145], v[20:23], v[16:19]
	v_mfma_f32_16x16x32_f16 v[20:23], v[138:141], v[24:27], 0
	v_mfma_f32_16x16x32_f16 v[146:149], v[60:63], v[24:27], 0
	v_mfma_f32_16x16x32_f16 v[162:165], v[120:123], v[24:27], 0
	v_mfma_f32_16x16x32_f16 v[190:193], v[130:133], v[24:27], 0
	v_mfma_f32_16x16x32_f16 v[20:23], v[142:145], v[28:31], v[20:23]
	v_mfma_f32_16x16x32_f16 v[146:149], v[116:119], v[28:31], v[146:149]
	v_mfma_f32_16x16x32_f16 v[162:165], v[124:127], v[28:31], v[162:165]
	v_mfma_f32_16x16x32_f16 v[190:193], v[134:137], v[28:31], v[190:193]
	s_barrier
	v_readfirstlane_b32 s17, v10
	v_lshl_add_u64 v[24:25], v[2:3], 0, s[92:93]
	s_mov_b32 m0, s17
	v_readfirstlane_b32 s17, v11
	global_load_lds_dwordx4 v[24:25], off
	v_lshl_add_u64 v[24:25], v[2:3], 0, s[18:19]
	s_mov_b32 m0, s17
	s_nop 0
	global_load_lds_dwordx4 v[24:25], off
	s_waitcnt vmcnt(6)
	s_barrier
	v_mfma_f32_16x16x32_f16 v[24:27], v[60:63], v[96:99], 0
	v_mfma_f32_16x16x32_f16 v[28:31], v[60:63], v[104:107], 0
	v_mfma_f32_16x16x32_f16 v[24:27], v[116:119], v[100:103], v[24:27]
	v_mfma_f32_16x16x32_f16 v[28:31], v[116:119], v[108:111], v[28:31]
	v_mfma_f32_16x16x32_f16 v[60:63], v[120:123], v[96:99], 0
	v_mfma_f32_16x16x32_f16 v[116:119], v[120:123], v[104:107], 0
	v_mfma_f32_16x16x32_f16 v[120:123], v[130:133], v[96:99], 0
	v_mfma_f32_16x16x32_f16 v[96:99], v[138:141], v[96:99], 0
	v_mfma_f32_16x16x32_f16 v[60:63], v[124:127], v[100:103], v[60:63]
	v_mfma_f32_16x16x32_f16 v[116:119], v[124:127], v[108:111], v[116:119]
	v_mfma_f32_16x16x32_f16 v[120:123], v[134:137], v[100:103], v[120:123]
	v_mfma_f32_16x16x32_f16 v[124:127], v[130:133], v[104:107], 0
	v_mfma_f32_16x16x32_f16 v[96:99], v[142:145], v[100:103], v[96:99]
	v_mfma_f32_16x16x32_f16 v[100:103], v[138:141], v[104:107], 0
	v_mfma_f32_16x16x32_f16 v[124:127], v[134:137], v[108:111], v[124:127]
	v_mfma_f32_16x16x32_f16 v[100:103], v[142:145], v[108:111], v[100:103]
	s_barrier
	ds_read_b128 v[104:107], v150 offset:32768
	ds_read_b128 v[108:111], v150 offset:33792
	ds_read_b128 v[130:133], v150 offset:34816
	ds_read_b128 v[134:137], v150 offset:35840
	v_readfirstlane_b32 s17, v8
	v_lshl_add_u64 v[10:11], v[6:7], 0, s[92:93]
	s_mov_b32 m0, s17
	v_readfirstlane_b32 s17, v9
	ds_read_b128 v[138:141], v151 offset:32768
	ds_read_b128 v[142:145], v151 offset:33792
	ds_read_b128 v[194:197], v151 offset:34816
	ds_read_b128 v[198:201], v151 offset:35840
	ds_read_b128 v[202:205], v151 offset:36864
	ds_read_b128 v[206:209], v151 offset:37888
	ds_read_b128 v[210:213], v151 offset:38912
	ds_read_b128 v[214:217], v151 offset:39936
	global_load_lds_dwordx4 v[10:11], off
	v_lshl_add_u64 v[6:7], v[6:7], 0, s[18:19]
	s_mov_b32 m0, s17
	s_nop 0
	global_load_lds_dwordx4 v[6:7], off
	s_waitcnt lgkmcnt(8)
	s_barrier
	s_waitcnt lgkmcnt(0)
	s_waitcnt lgkmcnt(0)
	v_mfma_f32_16x16x32_f16 v[6:9], v[138:141], v[104:107], v[64:67]
	v_mfma_f32_16x16x32_f16 v[64:67], v[138:141], v[130:133], v[68:71]
	v_mfma_f32_16x16x32_f16 v[68:71], v[194:197], v[104:107], v[72:75]
	v_mfma_f32_16x16x32_f16 v[72:75], v[194:197], v[130:133], v[76:79]
	v_mfma_f32_16x16x32_f16 v[76:79], v[202:205], v[104:107], v[80:83]
	v_mfma_f32_16x16x32_f16 v[80:83], v[202:205], v[130:133], v[84:87]
	v_mfma_f32_16x16x32_f16 v[84:87], v[210:213], v[104:107], v[88:91]
	v_mfma_f32_16x16x32_f16 v[88:91], v[210:213], v[130:133], v[92:95]
	v_mfma_f32_16x16x32_f16 v[6:9], v[142:145], v[108:111], v[6:9]
	v_mfma_f32_16x16x32_f16 v[64:67], v[142:145], v[134:137], v[64:67]
	v_mfma_f32_16x16x32_f16 v[68:71], v[198:201], v[108:111], v[68:71]
	v_mfma_f32_16x16x32_f16 v[72:75], v[198:201], v[134:137], v[72:75]
	v_mfma_f32_16x16x32_f16 v[76:79], v[206:209], v[108:111], v[76:79]
	v_mfma_f32_16x16x32_f16 v[80:83], v[206:209], v[134:137], v[80:83]
	v_mfma_f32_16x16x32_f16 v[84:87], v[214:217], v[108:111], v[84:87]
	v_mfma_f32_16x16x32_f16 v[88:91], v[214:217], v[134:137], v[88:91]
	s_barrier
	s_mov_b32 m0, s16
	v_lshl_add_u64 v[10:11], v[4:5], 0, s[42:43]
	s_mov_b64 s[16:17], 0x100180
	ds_read_b128 v[92:95], v150 offset:49152
	ds_read_b128 v[218:221], v150 offset:50176
	ds_read_b128 v[222:225], v150 offset:51200
	ds_read_b128 v[226:229], v150 offset:52224
	global_load_lds_dwordx4 v[10:11], off
	v_lshl_add_u64 v[4:5], v[4:5], 0, s[16:17]
	s_mov_b32 m0, s15
	s_nop 0
	global_load_lds_dwordx4 v[4:5], off
	s_barrier
	s_waitcnt lgkmcnt(0)
	s_waitcnt lgkmcnt(0)
	v_mfma_f32_16x16x32_f16 v[112:115], v[138:141], v[92:95], v[112:115]
	v_mfma_f32_16x16x32_f16 v[32:35], v[138:141], v[222:225], v[32:35]
	v_mfma_f32_16x16x32_f16 v[36:39], v[194:197], v[92:95], v[36:39]
	v_mfma_f32_16x16x32_f16 v[40:43], v[194:197], v[222:225], v[40:43]
	v_mfma_f32_16x16x32_f16 v[44:47], v[202:205], v[92:95], v[44:47]
	v_mfma_f32_16x16x32_f16 v[48:51], v[202:205], v[222:225], v[48:51]
	v_mfma_f32_16x16x32_f16 v[52:55], v[210:213], v[92:95], v[52:55]
	v_mfma_f32_16x16x32_f16 v[56:59], v[210:213], v[222:225], v[56:59]
	v_mfma_f32_16x16x32_f16 v[112:115], v[142:145], v[218:221], v[112:115]
	v_mfma_f32_16x16x32_f16 v[32:35], v[142:145], v[226:229], v[32:35]
	v_mfma_f32_16x16x32_f16 v[36:39], v[198:201], v[218:221], v[36:39]
	v_mfma_f32_16x16x32_f16 v[40:43], v[198:201], v[226:229], v[40:43]
	v_mfma_f32_16x16x32_f16 v[44:47], v[206:209], v[218:221], v[44:47]
	v_mfma_f32_16x16x32_f16 v[48:51], v[206:209], v[226:229], v[48:51]
	v_mfma_f32_16x16x32_f16 v[52:55], v[214:217], v[218:221], v[52:55]
	v_mfma_f32_16x16x32_f16 v[56:59], v[214:217], v[226:229], v[56:59]
	s_mov_b32 m0, s12
	v_lshl_add_u64 v[4:5], v[0:1], 0, s[42:43]
	s_barrier
;   #define STAGE(P,BASE,LD,br,kt) do{ const HALF* _u=(BASE)+(long)(br)*(((&(LD))==&lda)?lda_u:(LD))+(long)(kt)*G_BK; \
;     for(int _i=0;_i<2;++_i){ \
;       __builtin_amdgcn_global_load_lds((const unsigned*)(_u+(long)_i*(((&(LD))==&lda)?stepa:stepb)+((&(LD))==&lda?oa0:ob0)), \
;         (unsigned*)((char*)(P)+t5*16+_i*8192),16,0,0);}}while(0)
;   #define LDA(dst,b,h) for(int m=0;m<4;++m)for(int k=0;k<2;++k) \
;     dst[m][k]=*reinterpret_cast<const h8*>(la+(((b)*2+(h))*16384+m*2048+k*1024))
;   #define LDB(dst,b,h) for(int n=0;n<2;++n)for(int k=0;k<2;++k) \
;     dst[n][k]=*reinterpret_cast<const h8*>(lb+(((b)*2+(h))*16384+n*2048+k*1024))
;   #define MMA(ai,bj,At,Bt_) do{__builtin_amdgcn_s_setprio(1); \
;     for(int m=0;m<4;++m)for(int n=0;n<2;++n)for(int k=0;k<2;++k) \
;       acc[ai][bj][m][n]=__builtin_amdgcn_mfma_f32_16x16x32_f16(At[m][k],Bt_[n][k],acc[ai][bj][m][n],0,0,0); \
;     __builtin_amdgcn_s_setprio(0);}while(0)
;   #define WAIT_V(n) asm volatile("s_waitcnt vmcnt(" #n ")":::"memory")
;   #define WAIT_L(n) asm volatile("s_waitcnt lgkmcnt(" #n ")":::"memory")
;   #define BAR __builtin_amdgcn_s_barrier()
;   #define SCHED __builtin_amdgcn_sched_barrier(0)
;     ...
;     LDA(At,1,1); STAGE(SA(1,0),A,lda,0,t+3);
;     BAR; WAIT_L(0); MMA(1,0,At,B0); BAR; SCHED;
;     STAGE(SB(1,1),Bt,ldb,G_HALF,t+3);
;     WAIT_V(6); BAR; MMA(1,1,At,B1); BAR;
;   }
;   { LDB(B0,0,0); LDA(At,0,0); STAGE(SA(1,1),A,lda,G_HALF,nt-1);
;     BAR; WAIT_L(0); MMA(0,0,At,B0); BAR;
;     LDB(B1,0,1); BAR; WAIT_L(0); MMA(0,1,At,B1); BAR;
	ds_read_b128 v[138:141], v151 offset:49152
	ds_read_b128 v[142:145], v151 offset:50176
	ds_read_b128 v[194:197], v151 offset:51200
	ds_read_b128 v[198:201], v151 offset:52224
	ds_read_b128 v[202:205], v151 offset:53248
	ds_read_b128 v[206:209], v151 offset:54272
	ds_read_b128 v[210:213], v151 offset:55296
	ds_read_b128 v[214:217], v151 offset:56320
	global_load_lds_dwordx4 v[4:5], off
	v_lshl_add_u64 v[4:5], v[0:1], 0, s[16:17]
	s_mov_b32 m0, s11
	s_nop 0
	global_load_lds_dwordx4 v[4:5], off
	s_barrier
	s_waitcnt lgkmcnt(0)
	s_waitcnt lgkmcnt(0)
	v_mfma_f32_16x16x32_f16 v[10:13], v[138:141], v[104:107], v[12:15]
	v_mfma_f32_16x16x32_f16 v[14:17], v[210:213], v[104:107], v[16:19]
	v_mfma_f32_16x16x32_f16 v[18:21], v[210:213], v[130:133], v[20:23]
	v_mfma_f32_16x16x32_f16 v[10:13], v[142:145], v[108:111], v[10:13]
	v_mfma_f32_16x16x32_f16 v[146:149], v[138:141], v[130:133], v[146:149]
	v_mfma_f32_16x16x32_f16 v[158:161], v[194:197], v[104:107], v[158:161]
	v_mfma_f32_16x16x32_f16 v[162:165], v[194:197], v[130:133], v[162:165]
	v_mfma_f32_16x16x32_f16 v[186:189], v[202:205], v[104:107], v[186:189]
	v_mfma_f32_16x16x32_f16 v[190:193], v[202:205], v[130:133], v[190:193]
	v_mfma_f32_16x16x32_f16 v[14:17], v[214:217], v[108:111], v[14:17]
	v_mfma_f32_16x16x32_f16 v[18:21], v[214:217], v[134:137], v[18:21]
	v_mfma_f32_16x16x32_f16 v[146:149], v[142:145], v[134:137], v[146:149]
	v_mfma_f32_16x16x32_f16 v[158:161], v[198:201], v[108:111], v[158:161]
	v_mfma_f32_16x16x32_f16 v[162:165], v[198:201], v[134:137], v[162:165]
	v_mfma_f32_16x16x32_f16 v[186:189], v[206:209], v[108:111], v[186:189]
	v_mfma_f32_16x16x32_f16 v[190:193], v[206:209], v[134:137], v[190:193]
	s_barrier
	s_mov_b32 m0, s2
	v_lshl_add_u64 v[4:5], v[2:3], 0, s[42:43]
	global_load_lds_dwordx4 v[4:5], off
	v_lshl_add_u64 v[2:3], v[2:3], 0, s[16:17]
	s_mov_b32 m0, s3
	s_nop 0
	global_load_lds_dwordx4 v[2:3], off
	s_waitcnt vmcnt(6)
	s_barrier
	v_mfma_f32_16x16x32_f16 v[2:5], v[138:141], v[92:95], v[24:27]
	v_mfma_f32_16x16x32_f16 v[22:25], v[138:141], v[222:225], v[28:31]
	v_mfma_f32_16x16x32_f16 v[26:29], v[194:197], v[92:95], v[60:63]
	v_mfma_f32_16x16x32_f16 v[60:63], v[194:197], v[222:225], v[116:119]
	v_mfma_f32_16x16x32_f16 v[104:107], v[202:205], v[92:95], v[120:123]
	v_mfma_f32_16x16x32_f16 v[108:111], v[202:205], v[222:225], v[124:127]
	v_mfma_f32_16x16x32_f16 v[92:95], v[210:213], v[92:95], v[96:99]
	v_mfma_f32_16x16x32_f16 v[96:99], v[210:213], v[222:225], v[100:103]
	v_mfma_f32_16x16x32_f16 v[2:5], v[142:145], v[218:221], v[2:5]
	v_mfma_f32_16x16x32_f16 v[22:25], v[142:145], v[226:229], v[22:25]
	v_mfma_f32_16x16x32_f16 v[26:29], v[198:201], v[218:221], v[26:29]
	v_mfma_f32_16x16x32_f16 v[60:63], v[198:201], v[226:229], v[60:63]
	v_mfma_f32_16x16x32_f16 v[104:107], v[206:209], v[218:221], v[104:107]
	v_mfma_f32_16x16x32_f16 v[108:111], v[206:209], v[226:229], v[108:111]
	v_mfma_f32_16x16x32_f16 v[92:95], v[214:217], v[218:221], v[92:95]
	v_mfma_f32_16x16x32_f16 v[96:99], v[214:217], v[226:229], v[96:99]
	s_mov_b64 s[2:3], 0x200180
	s_mov_b32 m0, s14
	v_lshl_add_u64 v[30:31], v[0:1], 0, s[2:3]
	s_mov_b64 s[2:3], 0x300180
	s_barrier
	ds_read_b128 v[100:103], v150
	ds_read_b128 v[116:119], v150 offset:1024
	ds_read_b128 v[120:123], v150 offset:2048
	ds_read_b128 v[124:127], v150 offset:3072
	ds_read_b128 v[130:133], v151
	ds_read_b128 v[134:137], v151 offset:1024
	ds_read_b128 v[138:141], v151 offset:2048
	ds_read_b128 v[142:145], v151 offset:3072
	ds_read_b128 v[194:197], v151 offset:4096
	ds_read_b128 v[198:201], v151 offset:5120
	ds_read_b128 v[202:205], v151 offset:6144
	ds_read_b128 v[206:209], v151 offset:7168
	global_load_lds_dwordx4 v[30:31], off
	v_lshl_add_u64 v[0:1], v[0:1], 0, s[2:3]
	s_mov_b32 m0, s13
	s_nop 0
	global_load_lds_dwordx4 v[0:1], off
	s_barrier
	s_waitcnt lgkmcnt(0)
	s_waitcnt lgkmcnt(0)
	v_mfma_f32_16x16x32_f16 v[6:9], v[130:133], v[100:103], v[6:9]
	v_mfma_f32_16x16x32_f16 v[64:67], v[130:133], v[120:123], v[64:67]
	v_mfma_f32_16x16x32_f16 v[68:71], v[138:141], v[100:103], v[68:71]
	v_mfma_f32_16x16x32_f16 v[72:75], v[138:141], v[120:123], v[72:75]
	v_mfma_f32_16x16x32_f16 v[76:79], v[194:197], v[100:103], v[76:79]
	v_mfma_f32_16x16x32_f16 v[80:83], v[194:197], v[120:123], v[80:83]
	v_mfma_f32_16x16x32_f16 v[84:87], v[202:205], v[100:103], v[84:87]
	v_mfma_f32_16x16x32_f16 v[88:91], v[202:205], v[120:123], v[88:91]
	v_mfma_f32_16x16x32_f16 v[6:9], v[134:137], v[116:119], v[6:9]
	v_mfma_f32_16x16x32_f16 v[64:67], v[134:137], v[124:127], v[64:67]
	v_mfma_f32_16x16x32_f16 v[68:71], v[142:145], v[116:119], v[68:71]
	v_mfma_f32_16x16x32_f16 v[72:75], v[142:145], v[124:127], v[72:75]
	v_mfma_f32_16x16x32_f16 v[76:79], v[198:201], v[116:119], v[76:79]
	v_mfma_f32_16x16x32_f16 v[80:83], v[198:201], v[124:127], v[80:83]
	v_mfma_f32_16x16x32_f16 v[84:87], v[206:209], v[116:119], v[84:87]
	v_mfma_f32_16x16x32_f16 v[88:91], v[206:209], v[124:127], v[88:91]
	s_barrier
	ds_read_b128 v[210:213], v150 offset:16384
	ds_read_b128 v[214:217], v150 offset:17408
	ds_read_b128 v[218:221], v150 offset:18432
	ds_read_b128 v[222:225], v150 offset:19456
	s_barrier
;   #define LDA(dst,b,h) for(int m=0;m<4;++m)for(int k=0;k<2;++k) \
;     dst[m][k]=*reinterpret_cast<const h8*>(la+(((b)*2+(h))*16384+m*2048+k*1024))
;   #define LDB(dst,b,h) for(int n=0;n<2;++n)for(int k=0;k<2;++k) \
;     dst[n][k]=*reinterpret_cast<const h8*>(lb+(((b)*2+(h))*16384+n*2048+k*1024))
;   #define MMA(ai,bj,At,Bt_) do{__builtin_amdgcn_s_setprio(1); \
;     for(int m=0;m<4;++m)for(int n=0;n<2;++n)for(int k=0;k<2;++k) \
;       acc[ai][bj][m][n]=__builtin_amdgcn_mfma_f32_16x16x32_f16(At[m][k],Bt_[n][k],acc[ai][bj][m][n],0,0,0); \
;     __builtin_amdgcn_s_setprio(0);}while(0)
;   #define WAIT_V(n) asm volatile("s_waitcnt vmcnt(" #n ")":::"memory")
;   #define WAIT_L(n) asm volatile("s_waitcnt lgkmcnt(" #n ")":::"memory")
;   #define BAR __builtin_amdgcn_s_barrier()
;     ...
;     LDB(B1,0,1); BAR; WAIT_L(0); MMA(0,1,At,B1); BAR;
;     LDA(At,0,1); WAIT_V(4); BAR; WAIT_L(0); MMA(1,0,At,B0); MMA(1,1,At,B1); BAR; }
;   { LDB(B0,1,0); LDA(At,1,0); WAIT_V(2); BAR; WAIT_L(0); MMA(0,0,At,B0); BAR;
	s_waitcnt lgkmcnt(0)
	s_waitcnt lgkmcnt(0)
	v_mfma_f32_16x16x32_f16 v[30:33], v[130:133], v[218:221], v[32:35]
	v_mfma_f32_16x16x32_f16 v[34:37], v[138:141], v[210:213], v[36:39]
	v_mfma_f32_16x16x32_f16 v[38:41], v[138:141], v[218:221], v[40:43]
	v_mfma_f32_16x16x32_f16 v[42:45], v[194:197], v[210:213], v[44:47]
	v_mfma_f32_16x16x32_f16 v[46:49], v[194:197], v[218:221], v[48:51]
	v_mfma_f32_16x16x32_f16 v[50:53], v[202:205], v[210:213], v[52:55]
	v_mfma_f32_16x16x32_f16 v[54:57], v[202:205], v[218:221], v[56:59]
	v_mfma_f32_16x16x32_f16 v[112:115], v[130:133], v[210:213], v[112:115]
	v_mfma_f32_16x16x32_f16 v[30:33], v[134:137], v[222:225], v[30:33]
	v_mfma_f32_16x16x32_f16 v[34:37], v[142:145], v[214:217], v[34:37]
	v_mfma_f32_16x16x32_f16 v[38:41], v[142:145], v[222:225], v[38:41]
	v_mfma_f32_16x16x32_f16 v[42:45], v[198:201], v[214:217], v[42:45]
	v_mfma_f32_16x16x32_f16 v[46:49], v[198:201], v[222:225], v[46:49]
	v_mfma_f32_16x16x32_f16 v[50:53], v[206:209], v[214:217], v[50:53]
	v_mfma_f32_16x16x32_f16 v[54:57], v[206:209], v[222:225], v[54:57]
	v_mfma_f32_16x16x32_f16 v[226:229], v[134:137], v[214:217], v[112:115]
	s_barrier
	s_nop 0
	ds_read_b128 v[112:115], v151 offset:16384
	ds_read_b128 v[130:133], v151 offset:17408
	ds_read_b128 v[134:137], v151 offset:18432
	ds_read_b128 v[138:141], v151 offset:19456
	ds_read_b128 v[142:145], v151 offset:20480
	ds_read_b128 v[194:197], v151 offset:21504
	ds_read_b128 v[198:201], v151 offset:22528
	ds_read_b128 v[202:205], v151 offset:23552
	s_waitcnt vmcnt(4)
	s_barrier
	s_waitcnt lgkmcnt(0)
	s_waitcnt lgkmcnt(0)
	v_mfma_f32_16x16x32_f16 v[10:13], v[112:115], v[100:103], v[10:13]
	v_mfma_f32_16x16x32_f16 v[14:17], v[198:201], v[100:103], v[14:17]
	v_mfma_f32_16x16x32_f16 v[18:21], v[198:201], v[120:123], v[18:21]
	v_mfma_f32_16x16x32_f16 v[10:13], v[130:133], v[116:119], v[10:13]
	v_mfma_f32_16x16x32_f16 v[146:149], v[112:115], v[120:123], v[146:149]
	v_mfma_f32_16x16x32_f16 v[158:161], v[134:137], v[100:103], v[158:161]
	v_mfma_f32_16x16x32_f16 v[162:165], v[134:137], v[120:123], v[162:165]
	v_mfma_f32_16x16x32_f16 v[186:189], v[142:145], v[100:103], v[186:189]
	v_mfma_f32_16x16x32_f16 v[190:193], v[142:145], v[120:123], v[190:193]
	v_mfma_f32_16x16x32_f16 v[14:17], v[202:205], v[116:119], v[14:17]
	v_mfma_f32_16x16x32_f16 v[18:21], v[202:205], v[124:127], v[18:21]
	v_mfma_f32_16x16x32_f16 v[146:149], v[130:133], v[124:127], v[146:149]
	v_mfma_f32_16x16x32_f16 v[158:161], v[138:141], v[116:119], v[158:161]
	v_mfma_f32_16x16x32_f16 v[162:165], v[138:141], v[124:127], v[162:165]
	v_mfma_f32_16x16x32_f16 v[186:189], v[194:197], v[116:119], v[186:189]
	v_mfma_f32_16x16x32_f16 v[190:193], v[194:197], v[124:127], v[190:193]
	v_mfma_f32_16x16x32_f16 v[0:3], v[112:115], v[210:213], v[2:5]
	v_mfma_f32_16x16x32_f16 v[22:25], v[112:115], v[218:221], v[22:25]
	v_mfma_f32_16x16x32_f16 v[26:29], v[134:137], v[210:213], v[26:29]
	v_mfma_f32_16x16x32_f16 v[0:3], v[130:133], v[214:217], v[0:3]
	v_mfma_f32_16x16x32_f16 v[22:25], v[130:133], v[222:225], v[22:25]
	v_mfma_f32_16x16x32_f16 v[130:133], v[138:141], v[214:217], v[26:29]
	v_mfma_f32_16x16x32_f16 v[26:29], v[134:137], v[218:221], v[60:63]
	v_mfma_f32_16x16x32_f16 v[134:137], v[138:141], v[222:225], v[26:29]
	v_mfma_f32_16x16x32_f16 v[26:29], v[142:145], v[210:213], v[104:107]
	v_mfma_f32_16x16x32_f16 v[138:141], v[194:197], v[214:217], v[26:29]
	v_mfma_f32_16x16x32_f16 v[26:29], v[142:145], v[218:221], v[108:111]
	v_mfma_f32_16x16x32_f16 v[142:145], v[194:197], v[222:225], v[26:29]
	v_mfma_f32_16x16x32_f16 v[26:29], v[198:201], v[210:213], v[92:95]
	v_mfma_f32_16x16x32_f16 v[194:197], v[202:205], v[214:217], v[26:29]
	v_mfma_f32_16x16x32_f16 v[26:29], v[198:201], v[218:221], v[96:99]
	v_mfma_f32_16x16x32_f16 v[198:201], v[202:205], v[222:225], v[26:29]
	s_barrier
	s_nop 4
	ds_read_b128 v[26:29], v150 offset:32768
	ds_read_b128 v[202:205], v150 offset:33792
	ds_read_b128 v[206:209], v150 offset:34816
	ds_read_b128 v[210:213], v150 offset:35840
	ds_read_b128 v[58:61], v151 offset:32768
	ds_read_b128 v[92:95], v151 offset:33792
	ds_read_b128 v[214:217], v151 offset:34816
	ds_read_b128 v[218:221], v151 offset:35840
	ds_read_b128 v[222:225], v151 offset:36864
	ds_read_b128 v[230:233], v151 offset:37888
	ds_read_b128 v[234:237], v151 offset:38912
	ds_read_b128 v[238:241], v151 offset:39936
	s_waitcnt vmcnt(2)
	s_barrier
;   #define LDA(dst,b,h) for(int m=0;m<4;++m)for(int k=0;k<2;++k) \
;     dst[m][k]=*reinterpret_cast<const h8*>(la+(((b)*2+(h))*16384+m*2048+k*1024))
;   #define LDB(dst,b,h) for(int n=0;n<2;++n)for(int k=0;k<2;++k) \
;     dst[n][k]=*reinterpret_cast<const h8*>(lb+(((b)*2+(h))*16384+n*2048+k*1024))
;   #define MMA(ai,bj,At,Bt_) do{__builtin_amdgcn_s_setprio(1); \
;     for(int m=0;m<4;++m)for(int n=0;n<2;++n)for(int k=0;k<2;++k) \
;       acc[ai][bj][m][n]=__builtin_amdgcn_mfma_f32_16x16x32_f16(At[m][k],Bt_[n][k],acc[ai][bj][m][n],0,0,0); \
;     __builtin_amdgcn_s_setprio(0);}while(0)
;   #define WAIT_V(n) asm volatile("s_waitcnt vmcnt(" #n ")":::"memory")
;   #define WAIT_L(n) asm volatile("s_waitcnt lgkmcnt(" #n ")":::"memory")
;   #define BAR __builtin_amdgcn_s_barrier()
;     ...
;   { LDB(B0,1,0); LDA(At,1,0); WAIT_V(2); BAR; WAIT_L(0); MMA(0,0,At,B0); BAR;
;     LDB(B1,1,1); WAIT_V(0); BAR; WAIT_L(0); MMA(0,1,At,B1); BAR;
;     LDA(At,1,1); BAR; WAIT_L(0); MMA(1,0,At,B0); MMA(1,1,At,B1); BAR; }
;   if(wr==0)BAR;
	s_waitcnt lgkmcnt(0)
	s_waitcnt lgkmcnt(0)
	v_mfma_f32_16x16x32_f16 v[4:7], v[58:61], v[26:29], v[6:9]
	v_mfma_f32_16x16x32_f16 v[124:127], v[92:95], v[202:205], v[4:7]
	v_mfma_f32_16x16x32_f16 v[4:7], v[58:61], v[206:209], v[64:67]
	v_mfma_f32_16x16x32_f16 v[120:123], v[92:95], v[210:213], v[4:7]
	v_mfma_f32_16x16x32_f16 v[4:7], v[214:217], v[26:29], v[68:71]
	v_mfma_f32_16x16x32_f16 v[116:119], v[218:221], v[202:205], v[4:7]
	v_mfma_f32_16x16x32_f16 v[4:7], v[214:217], v[206:209], v[72:75]
	v_mfma_f32_16x16x32_f16 v[112:115], v[218:221], v[210:213], v[4:7]
	v_mfma_f32_16x16x32_f16 v[4:7], v[222:225], v[26:29], v[76:79]
	v_mfma_f32_16x16x32_f16 v[108:111], v[230:233], v[202:205], v[4:7]
	v_mfma_f32_16x16x32_f16 v[4:7], v[222:225], v[206:209], v[80:83]
	v_mfma_f32_16x16x32_f16 v[100:103], v[230:233], v[210:213], v[4:7]
	v_mfma_f32_16x16x32_f16 v[4:7], v[234:237], v[26:29], v[84:87]
	v_mfma_f32_16x16x32_f16 v[96:99], v[238:241], v[202:205], v[4:7]
	v_mfma_f32_16x16x32_f16 v[4:7], v[234:237], v[206:209], v[88:91]
	v_mfma_f32_16x16x32_f16 v[88:91], v[238:241], v[210:213], v[4:7]
	s_barrier
	s_nop 4
	ds_read_b128 v[4:7], v150 offset:49152
	ds_read_b128 v[242:245], v150 offset:50176
	ds_read_b128 v[246:249], v150 offset:51200
	ds_read_b128 v[250:253], v150 offset:52224
	s_waitcnt vmcnt(0)
	s_barrier
	s_waitcnt lgkmcnt(0)
	s_waitcnt lgkmcnt(0)
	v_mfma_f32_16x16x32_f16 v[62:65], v[58:61], v[4:7], v[226:229]
	v_mfma_f32_16x16x32_f16 v[30:33], v[58:61], v[246:249], v[30:33]
	v_mfma_f32_16x16x32_f16 v[104:107], v[92:95], v[242:245], v[62:65]
	v_mfma_f32_16x16x32_f16 v[92:95], v[92:95], v[250:253], v[30:33]
	v_mfma_f32_16x16x32_f16 v[30:33], v[214:217], v[4:7], v[34:37]
	v_mfma_f32_16x16x32_f16 v[84:87], v[218:221], v[242:245], v[30:33]
	v_mfma_f32_16x16x32_f16 v[30:33], v[214:217], v[246:249], v[38:41]
	v_mfma_f32_16x16x32_f16 v[80:83], v[218:221], v[250:253], v[30:33]
	v_mfma_f32_16x16x32_f16 v[30:33], v[222:225], v[4:7], v[42:45]
	v_mfma_f32_16x16x32_f16 v[76:79], v[230:233], v[242:245], v[30:33]
	v_mfma_f32_16x16x32_f16 v[30:33], v[222:225], v[246:249], v[46:49]
	v_mfma_f32_16x16x32_f16 v[68:71], v[230:233], v[250:253], v[30:33]
	v_mfma_f32_16x16x32_f16 v[30:33], v[234:237], v[4:7], v[50:53]
	v_mfma_f32_16x16x32_f16 v[60:63], v[238:241], v[242:245], v[30:33]
	v_mfma_f32_16x16x32_f16 v[30:33], v[234:237], v[246:249], v[54:57]
	v_mfma_f32_16x16x32_f16 v[48:51], v[238:241], v[250:253], v[30:33]
	s_barrier
	ds_read_b128 v[214:217], v151 offset:49152
	ds_read_b128 v[218:221], v151 offset:50176
	ds_read_b128 v[222:225], v151 offset:51200
	ds_read_b128 v[226:229], v151 offset:52224
	ds_read_b128 v[230:233], v151 offset:53248
	ds_read_b128 v[234:237], v151 offset:54272
	ds_read_b128 v[238:241], v151 offset:55296
	ds_read_b128 v[170:173], v151 offset:56320
	s_barrier
	s_waitcnt lgkmcnt(0)
	s_waitcnt lgkmcnt(0)
	v_mfma_f32_16x16x32_f16 v[8:11], v[214:217], v[26:29], v[10:13]
	v_mfma_f32_16x16x32_f16 v[72:75], v[218:221], v[202:205], v[8:11]
	v_mfma_f32_16x16x32_f16 v[8:11], v[214:217], v[206:209], v[146:149]
	v_mfma_f32_16x16x32_f16 v[64:67], v[218:221], v[210:213], v[8:11]
	v_mfma_f32_16x16x32_f16 v[8:11], v[222:225], v[26:29], v[158:161]
	v_mfma_f32_16x16x32_f16 v[56:59], v[226:229], v[202:205], v[8:11]
	v_mfma_f32_16x16x32_f16 v[8:11], v[222:225], v[206:209], v[162:165]
	v_mfma_f32_16x16x32_f16 v[52:55], v[226:229], v[210:213], v[8:11]
	v_mfma_f32_16x16x32_f16 v[8:11], v[230:233], v[26:29], v[186:189]
	v_mfma_f32_16x16x32_f16 v[44:47], v[234:237], v[202:205], v[8:11]
	v_mfma_f32_16x16x32_f16 v[8:11], v[230:233], v[206:209], v[190:193]
	v_mfma_f32_16x16x32_f16 v[40:43], v[234:237], v[210:213], v[8:11]
	v_mfma_f32_16x16x32_f16 v[8:11], v[238:241], v[26:29], v[14:17]
	v_mfma_f32_16x16x32_f16 v[36:39], v[170:173], v[202:205], v[8:11]
	v_mfma_f32_16x16x32_f16 v[8:11], v[238:241], v[206:209], v[18:21]
	v_mfma_f32_16x16x32_f16 v[32:35], v[170:173], v[210:213], v[8:11]
	v_mfma_f32_16x16x32_f16 v[0:3], v[214:217], v[4:7], v[0:3]
	v_mfma_f32_16x16x32_f16 v[28:31], v[218:221], v[242:245], v[0:3]
	v_mfma_f32_16x16x32_f16 v[0:3], v[214:217], v[246:249], v[22:25]
	v_mfma_f32_16x16x32_f16 v[24:27], v[218:221], v[250:253], v[0:3]
	v_mfma_f32_16x16x32_f16 v[0:3], v[222:225], v[4:7], v[130:133]
	v_mfma_f32_16x16x32_f16 v[20:23], v[226:229], v[242:245], v[0:3]
	v_mfma_f32_16x16x32_f16 v[0:3], v[222:225], v[246:249], v[134:137]
	v_mfma_f32_16x16x32_f16 v[16:19], v[226:229], v[250:253], v[0:3]
	v_mfma_f32_16x16x32_f16 v[0:3], v[230:233], v[4:7], v[138:141]
	v_mfma_f32_16x16x32_f16 v[12:15], v[234:237], v[242:245], v[0:3]
	v_mfma_f32_16x16x32_f16 v[0:3], v[230:233], v[246:249], v[142:145]
	v_mfma_f32_16x16x32_f16 v[8:11], v[234:237], v[250:253], v[0:3]
	v_mfma_f32_16x16x32_f16 v[0:3], v[238:241], v[4:7], v[194:197]
	v_mfma_f32_16x16x32_f16 v[4:7], v[170:173], v[242:245], v[0:3]
	v_mfma_f32_16x16x32_f16 v[0:3], v[238:241], v[246:249], v[198:201]
	v_mfma_f32_16x16x32_f16 v[0:3], v[170:173], v[250:253], v[0:3]
	s_movk_i32 s2, 0x100
	v_cmp_gt_u32_e32 vcc, s2, v129
	s_barrier
	s_and_saveexec_b64 s[2:3], vcc
	s_cbranch_execz .LBB0_396
	s_barrier

; DEV float logsig(float x) { return -log1pf(expf(-x)); }
;   #define STAGE(P,BASE,LD,br,kt) do{ const HALF* _u=(BASE)+(long)(br)*(((&(LD))==&lda)?lda_u:(LD))+(long)(kt)*G_BK; \
;     for(int _i=0;_i<2;++_i){ \
;       __builtin_amdgcn_global_load_lds((const unsigned*)(_u+(long)_i*(((&(LD))==&lda)?stepa:stepb)+((&(LD))==&lda?oa0:ob0)), \
;         (unsigned*)((char*)(P)+t5*16+_i*8192),16,0,0);}}while(0)
;   #define LDA(dst,b,h) for(int m=0;m<4;++m)for(int k=0;k<2;++k) \
;     dst[m][k]=*reinterpret_cast<const h8*>(la+(((b)*2+(h))*16384+m*2048+k*1024))
;   #define LDB(dst,b,h) for(int n=0;n<2;++n)for(int k=0;k<2;++k) \
;     dst[n][k]=*reinterpret_cast<const h8*>(lb+(((b)*2+(h))*16384+n*2048+k*1024))
;   #define MMA(ai,bj,At,Bt_) do{__builtin_amdgcn_s_setprio(1); \
;     for(int m=0;m<4;++m)for(int n=0;n<2;++n)for(int k=0;k<2;++k) \
;       acc[ai][bj][m][n]=__builtin_amdgcn_mfma_f32_16x16x32_f16(At[m][k],Bt_[n][k],acc[ai][bj][m][n],0,0,0); \
;     __builtin_amdgcn_s_setprio(0);}while(0)
;   #define WAIT_V(n) asm volatile("s_waitcnt vmcnt(" #n ")":::"memory")
;   #define WAIT_L(n) asm volatile("s_waitcnt lgkmcnt(" #n ")":::"memory")
;   #define BAR __builtin_amdgcn_s_barrier()
;     ...
;   const int _ob=fr*64+fq*16, _sw=_ob^(((_ob>>9)&1)<<5);
;   const char* la=(const char*)shm+wr*8192+_sw;
;   const char* lb=(const char*)shm+65536+wc*4096+_sw;
;   unsigned oa0, ob0;
;   const int stepa = n2 ? 1024 : 64 * lda, stepb = 64 * ldb;
;   const int lda_u = n2 ? 16 : lda;
;   {int _b=t5*16;int _r,_c;g_stage_rc(_b,_r,_c);
;     oa0=n2 ? (unsigned)((n2*(_r&63)+(_r>>6))*1024+_c) : (unsigned)(_r*lda+_c); ob0=(unsigned)(_r*ldb+_c);}
;   STAGE(SB(0,0),Bt,ldb,0,0); STAGE(SA(0,0),A,lda,0,0);
;   STAGE(SB(0,1),Bt,ldb,G_HALF,0); STAGE(SA(0,1),A,lda,G_HALF,0);
;   if(wr==1)BAR;
;   WAIT_V(4); BAR;
;   STAGE(SB(1,0),Bt,ldb,0,1); STAGE(SA(1,0),A,lda,0,1); STAGE(SB(1,1),Bt,ldb,G_HALF,1);
;   WAIT_V(6); BAR;
;   for(int t=0;t<nt-2;t+=2){
;     LDB(B0,0,0); SCHED; LDA(At,0,0); STAGE(SA(1,1),A,lda,G_HALF,t+1);
;     WAIT_L(8); BAR; WAIT_L(0); MMA(0,0,At,B0); BAR; SCHED;
;     LDB(B1,0,1); STAGE(SB(0,0),Bt,ldb,0,t+2);
;     BAR; WAIT_L(0); MMA(0,1,At,B1); BAR;
;     LDA(At,0,1); STAGE(SA(0,0),A,lda,0,t+2);
; __device__ void job_retout_g(const P& p, int l, int job, HALF* sm) {
;     ...
;   const float lgf = logsig(p.decay[l * 8 + h]);
;   const float lgb = logsig(p.decay[l * 8 + 4 + h]);
.LBB0_479:
	s_or_b64 exec, exec, s[6:7]
	s_mov_b32 s6, 0x3f2aaada
	v_pk_fma_f32 v[94:95], v[88:89], v[0:1], s[6:7] op_sel_hi:[1,1,0]
	s_mov_b32 s6, 0xb102e308
	v_pk_fma_f32 v[92:93], v[80:81], s[6:7], v[2:3] op_sel_hi:[1,0,1]
	v_lshlrev_b32_e32 v1, 6, v122
	v_lshlrev_b32_e32 v3, 2, v122
	v_add_u32_e32 v22, s29, v12
	v_and_b32_e32 v0, 48, v122
	v_and_b32_e32 v2, 0x3c0, v1
	v_and_b32_e32 v3, 32, v3
	v_readfirstlane_b32 s77, v22
	v_add_u32_e32 v22, 0x2000, v22
	v_bitop3_b32 v2, v2, v3, v0 bitop3:0x36
	v_lshlrev_b32_e32 v3, 13, v14
	v_and_b32_e32 v14, 0x3000, v1
	v_lshl_add_u64 v[0:1], v[4:5], 0, s[84:85]
	s_mov_b32 m0, s77
	s_mov_b64 s[6:7], 0x20080
	v_readfirstlane_b32 s76, v22
	v_add_u32_e32 v22, 0x8000, v20
	s_waitcnt vmcnt(4)
	s_barrier
	global_load_lds_dwordx4 v[0:1], off
	v_lshl_add_u64 v[0:1], v[4:5], 0, s[6:7]
	s_mov_b32 m0, s76
	v_readfirstlane_b32 s44, v22
	v_add_u32_e32 v22, 0xa000, v20
	global_load_lds_dwordx4 v[0:1], off
	v_lshl_add_u64 v[0:1], v[6:7], 0, s[84:85]
	s_mov_b32 m0, s44
	s_mov_b64 s[70:71], 0x8080
	v_readfirstlane_b32 s22, v22
	s_add_u32 s6, s10, 0x40080
	v_add_u32_e32 v12, s62, v12
	global_load_lds_dwordx4 v[0:1], off
	v_lshl_add_u64 v[0:1], v[6:7], 0, s[70:71]
	s_mov_b32 m0, s22
	s_addc_u32 s7, s11, 0
	v_readfirstlane_b32 s13, v12
	v_add_u32_e32 v12, 0x2000, v12
	global_load_lds_dwordx4 v[0:1], off
	v_lshl_add_u64 v[0:1], v[152:153], 1, s[6:7]
	s_mov_b32 m0, s13
	v_readfirstlane_b32 s12, v12
	global_load_lds_dwordx4 v[0:1], off
	v_lshl_add_u64 v[0:1], v[0:1], 0, s[68:69]
	s_mov_b32 m0, s12
	v_add3_u32 v81, s95, v14, v2
	global_load_lds_dwordx4 v[0:1], off
	s_waitcnt vmcnt(6)
	s_barrier
	v_add3_u32 v123, 0, v3, v2
	ds_read_b128 v[0:3], v81
	ds_read_b128 v[22:25], v81 offset:1024
	ds_read_b128 v[26:29], v81 offset:2048
	ds_read_b128 v[30:33], v81 offset:3072
	v_add_u32_e32 v12, 0xc000, v20
	v_lshl_add_u64 v[66:67], v[10:11], 0, s[84:85]
	v_readfirstlane_b32 s80, v12
	s_mov_b32 m0, s80
	v_add_u32_e32 v12, 0xe000, v20
	ds_read_b128 v[34:37], v123
	ds_read_b128 v[38:41], v123 offset:1024
	ds_read_b128 v[42:45], v123 offset:2048
	ds_read_b128 v[46:49], v123 offset:3072
	ds_read_b128 v[50:53], v123 offset:4096
	ds_read_b128 v[54:57], v123 offset:5120
	ds_read_b128 v[58:61], v123 offset:6144
	ds_read_b128 v[62:65], v123 offset:7168
	global_load_lds_dwordx4 v[66:67], off
	v_lshl_add_u64 v[66:67], v[10:11], 0, s[70:71]
	v_readfirstlane_b32 s71, v12
	s_mov_b32 m0, s71
	s_nop 0
	global_load_lds_dwordx4 v[66:67], off
	s_waitcnt lgkmcnt(8)
	s_barrier
	s_waitcnt lgkmcnt(0)
	s_waitcnt lgkmcnt(0)
	v_mfma_f32_16x16x32_f16 v[66:69], v[34:37], v[0:3], 0
	v_mfma_f32_16x16x32_f16 v[76:79], v[34:37], v[26:29], 0
	v_mfma_f32_16x16x32_f16 v[84:87], v[42:45], v[0:3], 0
	v_mfma_f32_16x16x32_f16 v[96:99], v[42:45], v[26:29], 0
	v_mfma_f32_16x16x32_f16 v[100:103], v[50:53], v[0:3], 0
	v_mfma_f32_16x16x32_f16 v[104:107], v[50:53], v[26:29], 0
	v_mfma_f32_16x16x32_f16 v[108:111], v[58:61], v[0:3], 0
	v_mfma_f32_16x16x32_f16 v[112:115], v[58:61], v[26:29], 0
	v_mfma_f32_16x16x32_f16 v[66:69], v[38:41], v[22:25], v[66:69]
	v_mfma_f32_16x16x32_f16 v[76:79], v[38:41], v[30:33], v[76:79]
	v_mfma_f32_16x16x32_f16 v[84:87], v[46:49], v[22:25], v[84:87]
	v_mfma_f32_16x16x32_f16 v[96:99], v[46:49], v[30:33], v[96:99]
	v_mfma_f32_16x16x32_f16 v[100:103], v[54:57], v[22:25], v[100:103]
	v_mfma_f32_16x16x32_f16 v[104:107], v[54:57], v[30:33], v[104:107]
	v_mfma_f32_16x16x32_f16 v[108:111], v[62:65], v[22:25], v[108:111]
	v_mfma_f32_16x16x32_f16 v[112:115], v[62:65], v[30:33], v[112:115]
	s_barrier
	v_readfirstlane_b32 s81, v13
	v_lshl_add_u64 v[70:71], v[4:5], 0, s[92:93]
	s_mov_b32 m0, s81
	v_readfirstlane_b32 s81, v15
	ds_read_b128 v[116:119], v81 offset:16384
	ds_read_b128 v[124:127], v81 offset:17408
	ds_read_b128 v[128:131], v81 offset:18432
	ds_read_b128 v[132:135], v81 offset:19456
	global_load_lds_dwordx4 v[70:71], off
	v_lshl_add_u64 v[12:13], v[4:5], 0, s[66:67]
	s_mov_b32 m0, s81
	s_nop 0
	global_load_lds_dwordx4 v[12:13], off
	s_barrier
	s_waitcnt lgkmcnt(0)
	s_waitcnt lgkmcnt(0)
	v_mfma_f32_16x16x32_f16 v[12:15], v[34:37], v[116:119], 0
	v_mfma_f32_16x16x32_f16 v[34:37], v[34:37], v[128:131], 0
	v_mfma_f32_16x16x32_f16 v[12:15], v[38:41], v[124:127], v[12:15]
	v_mfma_f32_16x16x32_f16 v[34:37], v[38:41], v[132:135], v[34:37]
	v_mfma_f32_16x16x32_f16 v[38:41], v[42:45], v[116:119], 0
	v_mfma_f32_16x16x32_f16 v[42:45], v[42:45], v[128:131], 0
	v_mfma_f32_16x16x32_f16 v[38:41], v[46:49], v[124:127], v[38:41]
	v_mfma_f32_16x16x32_f16 v[42:45], v[46:49], v[132:135], v[42:45]
	v_mfma_f32_16x16x32_f16 v[46:49], v[50:53], v[116:119], 0
	v_mfma_f32_16x16x32_f16 v[50:53], v[50:53], v[128:131], 0
	v_mfma_f32_16x16x32_f16 v[46:49], v[54:57], v[124:127], v[46:49]
	v_mfma_f32_16x16x32_f16 v[50:53], v[54:57], v[132:135], v[50:53]
	v_mfma_f32_16x16x32_f16 v[54:57], v[58:61], v[116:119], 0
	v_mfma_f32_16x16x32_f16 v[58:61], v[58:61], v[128:131], 0
	v_mfma_f32_16x16x32_f16 v[54:57], v[62:65], v[124:127], v[54:57]
	v_mfma_f32_16x16x32_f16 v[58:61], v[62:65], v[132:135], v[58:61]
	v_readfirstlane_b32 s81, v20
	v_lshl_add_u64 v[70:71], v[6:7], 0, s[92:93]
	s_mov_b32 m0, s81
	s_mov_b64 s[68:69], 0x8100
	v_readfirstlane_b32 s81, v21
	s_barrier
	ds_read_b128 v[62:65], v123 offset:16384
	ds_read_b128 v[136:139], v123 offset:17408
	ds_read_b128 v[140:143], v123 offset:18432
	ds_read_b128 v[144:147], v123 offset:19456
	ds_read_b128 v[148:151], v123 offset:20480
	ds_read_b128 v[158:161], v123 offset:21504
	ds_read_b128 v[162:165], v123 offset:22528
	ds_read_b128 v[170:173], v123 offset:23552
	global_load_lds_dwordx4 v[70:71], off
	v_lshl_add_u64 v[70:71], v[6:7], 0, s[68:69]
	s_mov_b32 m0, s81
	s_nop 0
	global_load_lds_dwordx4 v[70:71], off
	s_barrier
;   #define STAGE(P,BASE,LD,br,kt) do{ const HALF* _u=(BASE)+(long)(br)*(((&(LD))==&lda)?lda_u:(LD))+(long)(kt)*G_BK; \
;     for(int _i=0;_i<2;++_i){ \
;       __builtin_amdgcn_global_load_lds((const unsigned*)(_u+(long)_i*(((&(LD))==&lda)?stepa:stepb)+((&(LD))==&lda?oa0:ob0)), \
;         (unsigned*)((char*)(P)+t5*16+_i*8192),16,0,0);}}while(0)
;   #define LDA(dst,b,h) for(int m=0;m<4;++m)for(int k=0;k<2;++k) \
;     dst[m][k]=*reinterpret_cast<const h8*>(la+(((b)*2+(h))*16384+m*2048+k*1024))
;   #define LDB(dst,b,h) for(int n=0;n<2;++n)for(int k=0;k<2;++k) \
;     dst[n][k]=*reinterpret_cast<const h8*>(lb+(((b)*2+(h))*16384+n*2048+k*1024))
;   #define MMA(ai,bj,At,Bt_) do{__builtin_amdgcn_s_setprio(1); \
;     for(int m=0;m<4;++m)for(int n=0;n<2;++n)for(int k=0;k<2;++k) \
;       acc[ai][bj][m][n]=__builtin_amdgcn_mfma_f32_16x16x32_f16(At[m][k],Bt_[n][k],acc[ai][bj][m][n],0,0,0); \
;     __builtin_amdgcn_s_setprio(0);}while(0)
;   #define WAIT_V(n) asm volatile("s_waitcnt vmcnt(" #n ")":::"memory")
;   #define WAIT_L(n) asm volatile("s_waitcnt lgkmcnt(" #n ")":::"memory")
;   #define BAR __builtin_amdgcn_s_barrier()
;   #define SCHED __builtin_amdgcn_sched_barrier(0)
;     ...
;     BAR; WAIT_L(0); MMA(1,0,At,B0); BAR; SCHED;
;     STAGE(SB(0,1),Bt,ldb,G_HALF,t+2);
;     WAIT_V(6); BAR; MMA(1,1,At,B1); BAR;
;     LDB(B0,1,0); SCHED; LDA(At,1,0); STAGE(SA(0,1),A,lda,G_HALF,t+2);
;     WAIT_L(8); BAR; WAIT_L(0); MMA(0,0,At,B0); BAR; SCHED;
;     LDB(B1,1,1); STAGE(SB(1,0),Bt,ldb,0,t+3);
;     BAR; WAIT_L(0); MMA(0,1,At,B1); BAR;
	s_waitcnt lgkmcnt(0)
	s_waitcnt lgkmcnt(0)
	v_mfma_f32_16x16x32_f16 v[186:189], v[62:65], v[0:3], 0
	v_mfma_f32_16x16x32_f16 v[194:197], v[140:143], v[0:3], 0
	v_mfma_f32_16x16x32_f16 v[202:205], v[148:151], v[0:3], 0
	v_mfma_f32_16x16x32_f16 v[0:3], v[162:165], v[0:3], 0
	v_mfma_f32_16x16x32_f16 v[186:189], v[136:139], v[22:25], v[186:189]
	v_mfma_f32_16x16x32_f16 v[194:197], v[144:147], v[22:25], v[194:197]
	v_mfma_f32_16x16x32_f16 v[202:205], v[158:161], v[22:25], v[202:205]
	v_mfma_f32_16x16x32_f16 v[0:3], v[170:173], v[22:25], v[0:3]
	v_mfma_f32_16x16x32_f16 v[20:23], v[162:165], v[26:29], 0
	v_mfma_f32_16x16x32_f16 v[190:193], v[62:65], v[26:29], 0
	v_mfma_f32_16x16x32_f16 v[198:201], v[140:143], v[26:29], 0
	v_mfma_f32_16x16x32_f16 v[206:209], v[148:151], v[26:29], 0
	v_mfma_f32_16x16x32_f16 v[20:23], v[170:173], v[30:33], v[20:23]
	v_mfma_f32_16x16x32_f16 v[190:193], v[136:139], v[30:33], v[190:193]
	v_mfma_f32_16x16x32_f16 v[198:201], v[144:147], v[30:33], v[198:201]
	v_mfma_f32_16x16x32_f16 v[206:209], v[158:161], v[30:33], v[206:209]
	s_barrier
	v_readfirstlane_b32 s81, v18
	v_lshl_add_u64 v[24:25], v[8:9], 0, s[92:93]
	s_mov_b32 m0, s81
	v_readfirstlane_b32 s81, v19
	global_load_lds_dwordx4 v[24:25], off
	v_lshl_add_u64 v[24:25], v[8:9], 0, s[66:67]
	s_mov_b32 m0, s81
	s_nop 0
	global_load_lds_dwordx4 v[24:25], off
	s_waitcnt vmcnt(6)
	s_barrier
	v_mfma_f32_16x16x32_f16 v[24:27], v[62:65], v[116:119], 0
	v_mfma_f32_16x16x32_f16 v[28:31], v[62:65], v[128:131], 0
	v_mfma_f32_16x16x32_f16 v[24:27], v[136:139], v[124:127], v[24:27]
	v_mfma_f32_16x16x32_f16 v[28:31], v[136:139], v[132:135], v[28:31]
	v_mfma_f32_16x16x32_f16 v[62:65], v[140:143], v[116:119], 0
	v_mfma_f32_16x16x32_f16 v[136:139], v[140:143], v[128:131], 0
	v_mfma_f32_16x16x32_f16 v[62:65], v[144:147], v[124:127], v[62:65]
	v_mfma_f32_16x16x32_f16 v[136:139], v[144:147], v[132:135], v[136:139]
	v_mfma_f32_16x16x32_f16 v[140:143], v[148:151], v[116:119], 0
	v_mfma_f32_16x16x32_f16 v[144:147], v[148:151], v[128:131], 0
	v_mfma_f32_16x16x32_f16 v[116:119], v[162:165], v[116:119], 0
	v_mfma_f32_16x16x32_f16 v[140:143], v[158:161], v[124:127], v[140:143]
	v_mfma_f32_16x16x32_f16 v[144:147], v[158:161], v[132:135], v[144:147]
	v_mfma_f32_16x16x32_f16 v[116:119], v[170:173], v[124:127], v[116:119]
	v_mfma_f32_16x16x32_f16 v[124:127], v[162:165], v[128:131], 0
	v_mfma_f32_16x16x32_f16 v[124:127], v[170:173], v[132:135], v[124:127]
	s_barrier
	ds_read_b128 v[128:131], v81 offset:32768
	ds_read_b128 v[132:135], v81 offset:33792
	ds_read_b128 v[148:151], v81 offset:34816
	ds_read_b128 v[158:161], v81 offset:35840
	v_readfirstlane_b32 s81, v16
	v_lshl_add_u64 v[18:19], v[10:11], 0, s[92:93]
	s_mov_b32 m0, s81
	v_readfirstlane_b32 s81, v17
	ds_read_b128 v[162:165], v123 offset:32768
	ds_read_b128 v[170:173], v123 offset:33792
	ds_read_b128 v[210:213], v123 offset:34816
	ds_read_b128 v[214:217], v123 offset:35840
	ds_read_b128 v[218:221], v123 offset:36864
	ds_read_b128 v[222:225], v123 offset:37888
	ds_read_b128 v[226:229], v123 offset:38912
	ds_read_b128 v[230:233], v123 offset:39936
	global_load_lds_dwordx4 v[18:19], off
	v_lshl_add_u64 v[10:11], v[10:11], 0, s[68:69]
	s_mov_b32 m0, s81
	s_nop 0
	global_load_lds_dwordx4 v[10:11], off
	s_waitcnt lgkmcnt(8)
	s_barrier
	s_waitcnt lgkmcnt(0)
	s_waitcnt lgkmcnt(0)
	v_mfma_f32_16x16x32_f16 v[16:19], v[162:165], v[128:131], v[66:69]
	v_mfma_f32_16x16x32_f16 v[66:69], v[162:165], v[148:151], v[76:79]
	v_mfma_f32_16x16x32_f16 v[76:79], v[210:213], v[128:131], v[84:87]
	v_mfma_f32_16x16x32_f16 v[84:87], v[210:213], v[148:151], v[96:99]
	v_mfma_f32_16x16x32_f16 v[96:99], v[218:221], v[128:131], v[100:103]
	v_mfma_f32_16x16x32_f16 v[100:103], v[218:221], v[148:151], v[104:107]
	v_mfma_f32_16x16x32_f16 v[104:107], v[226:229], v[128:131], v[108:111]
	v_mfma_f32_16x16x32_f16 v[108:111], v[226:229], v[148:151], v[112:115]
	v_mfma_f32_16x16x32_f16 v[16:19], v[170:173], v[132:135], v[16:19]
	v_mfma_f32_16x16x32_f16 v[66:69], v[170:173], v[158:161], v[66:69]
	v_mfma_f32_16x16x32_f16 v[76:79], v[214:217], v[132:135], v[76:79]
	v_mfma_f32_16x16x32_f16 v[84:87], v[214:217], v[158:161], v[84:87]
	v_mfma_f32_16x16x32_f16 v[96:99], v[222:225], v[132:135], v[96:99]
	v_mfma_f32_16x16x32_f16 v[100:103], v[222:225], v[158:161], v[100:103]
	v_mfma_f32_16x16x32_f16 v[104:107], v[230:233], v[132:135], v[104:107]
	v_mfma_f32_16x16x32_f16 v[108:111], v[230:233], v[158:161], v[108:111]
	s_barrier
	s_mov_b32 m0, s77
	v_lshl_add_u64 v[10:11], v[4:5], 0, s[42:43]
	ds_read_b128 v[112:115], v81 offset:49152
	ds_read_b128 v[234:237], v81 offset:50176
	ds_read_b128 v[238:241], v81 offset:51200
	ds_read_b128 v[242:245], v81 offset:52224
	global_load_lds_dwordx4 v[10:11], off
	v_lshl_add_u64 v[4:5], v[4:5], 0, s[96:97]
	s_mov_b32 m0, s76
	s_nop 0
	global_load_lds_dwordx4 v[4:5], off
	s_barrier
	s_waitcnt lgkmcnt(0)
	s_waitcnt lgkmcnt(0)
	v_mfma_f32_16x16x32_f16 v[10:13], v[162:165], v[112:115], v[12:15]
	v_mfma_f32_16x16x32_f16 v[32:35], v[162:165], v[238:241], v[34:37]
	v_mfma_f32_16x16x32_f16 v[36:39], v[210:213], v[112:115], v[38:41]
	v_mfma_f32_16x16x32_f16 v[40:43], v[210:213], v[238:241], v[42:45]
	v_mfma_f32_16x16x32_f16 v[44:47], v[218:221], v[112:115], v[46:49]
	v_mfma_f32_16x16x32_f16 v[48:51], v[218:221], v[238:241], v[50:53]
	v_mfma_f32_16x16x32_f16 v[52:55], v[226:229], v[112:115], v[54:57]
	v_mfma_f32_16x16x32_f16 v[56:59], v[226:229], v[238:241], v[58:61]
	v_mfma_f32_16x16x32_f16 v[10:13], v[170:173], v[234:237], v[10:13]
	v_mfma_f32_16x16x32_f16 v[32:35], v[170:173], v[242:245], v[32:35]
	v_mfma_f32_16x16x32_f16 v[36:39], v[214:217], v[234:237], v[36:39]
	v_mfma_f32_16x16x32_f16 v[40:43], v[214:217], v[242:245], v[40:43]
	v_mfma_f32_16x16x32_f16 v[44:47], v[222:225], v[234:237], v[44:47]
	v_mfma_f32_16x16x32_f16 v[48:51], v[222:225], v[242:245], v[48:51]
	v_mfma_f32_16x16x32_f16 v[52:55], v[230:233], v[234:237], v[52:55]
	v_mfma_f32_16x16x32_f16 v[56:59], v[230:233], v[242:245], v[56:59]
	s_mov_b32 m0, s44
	v_lshl_add_u64 v[4:5], v[6:7], 0, s[42:43]
	s_mov_b64 s[68:69], 0x8180
	s_barrier
;   #define STAGE(P,BASE,LD,br,kt) do{ const HALF* _u=(BASE)+(long)(br)*(((&(LD))==&lda)?lda_u:(LD))+(long)(kt)*G_BK; \
;     for(int _i=0;_i<2;++_i){ \
;       __builtin_amdgcn_global_load_lds((const unsigned*)(_u+(long)_i*(((&(LD))==&lda)?stepa:stepb)+((&(LD))==&lda?oa0:ob0)), \
;         (unsigned*)((char*)(P)+t5*16+_i*8192),16,0,0);}}while(0)
;   #define LDA(dst,b,h) for(int m=0;m<4;++m)for(int k=0;k<2;++k) \
;     dst[m][k]=*reinterpret_cast<const h8*>(la+(((b)*2+(h))*16384+m*2048+k*1024))
;   #define LDB(dst,b,h) for(int n=0;n<2;++n)for(int k=0;k<2;++k) \
;     dst[n][k]=*reinterpret_cast<const h8*>(lb+(((b)*2+(h))*16384+n*2048+k*1024))
;   #define MMA(ai,bj,At,Bt_) do{__builtin_amdgcn_s_setprio(1); \
;     for(int m=0;m<4;++m)for(int n=0;n<2;++n)for(int k=0;k<2;++k) \
;       acc[ai][bj][m][n]=__builtin_amdgcn_mfma_f32_16x16x32_f16(At[m][k],Bt_[n][k],acc[ai][bj][m][n],0,0,0); \
;     __builtin_amdgcn_s_setprio(0);}while(0)
;   #define WAIT_V(n) asm volatile("s_waitcnt vmcnt(" #n ")":::"memory")
;   #define WAIT_L(n) asm volatile("s_waitcnt lgkmcnt(" #n ")":::"memory")
;   #define BAR __builtin_amdgcn_s_barrier()
;   #define SCHED __builtin_amdgcn_sched_barrier(0)
;     ...
;     LDA(At,1,1); STAGE(SA(1,0),A,lda,0,t+3);
;     BAR; WAIT_L(0); MMA(1,0,At,B0); BAR; SCHED;
;     STAGE(SB(1,1),Bt,ldb,G_HALF,t+3);
;     WAIT_V(6); BAR; MMA(1,1,At,B1); BAR;
;   }
;   { LDB(B0,0,0); LDA(At,0,0); STAGE(SA(1,1),A,lda,G_HALF,nt-1);
;     BAR; WAIT_L(0); MMA(0,0,At,B0); BAR;
;     LDB(B1,0,1); BAR; WAIT_L(0); MMA(0,1,At,B1); BAR;
	ds_read_b128 v[162:165], v123 offset:49152
	ds_read_b128 v[170:173], v123 offset:50176
	ds_read_b128 v[210:213], v123 offset:51200
	ds_read_b128 v[214:217], v123 offset:52224
	ds_read_b128 v[218:221], v123 offset:53248
	ds_read_b128 v[222:225], v123 offset:54272
	ds_read_b128 v[226:229], v123 offset:55296
	ds_read_b128 v[230:233], v123 offset:56320
	global_load_lds_dwordx4 v[4:5], off
	v_lshl_add_u64 v[4:5], v[6:7], 0, s[68:69]
	s_mov_b32 m0, s22
	s_nop 0
	global_load_lds_dwordx4 v[4:5], off
	s_barrier
	s_waitcnt lgkmcnt(0)
	s_waitcnt lgkmcnt(0)
	v_mfma_f32_16x16x32_f16 v[0:3], v[226:229], v[128:131], v[0:3]
	v_mfma_f32_16x16x32_f16 v[20:23], v[226:229], v[148:151], v[20:23]
	v_mfma_f32_16x16x32_f16 v[186:189], v[162:165], v[128:131], v[186:189]
	v_mfma_f32_16x16x32_f16 v[190:193], v[162:165], v[148:151], v[190:193]
	v_mfma_f32_16x16x32_f16 v[194:197], v[210:213], v[128:131], v[194:197]
	v_mfma_f32_16x16x32_f16 v[198:201], v[210:213], v[148:151], v[198:201]
	v_mfma_f32_16x16x32_f16 v[202:205], v[218:221], v[128:131], v[202:205]
	v_mfma_f32_16x16x32_f16 v[206:209], v[218:221], v[148:151], v[206:209]
	v_mfma_f32_16x16x32_f16 v[0:3], v[230:233], v[132:135], v[0:3]
	v_mfma_f32_16x16x32_f16 v[20:23], v[230:233], v[158:161], v[20:23]
	v_mfma_f32_16x16x32_f16 v[186:189], v[170:173], v[132:135], v[186:189]
	v_mfma_f32_16x16x32_f16 v[190:193], v[170:173], v[158:161], v[190:193]
	v_mfma_f32_16x16x32_f16 v[194:197], v[214:217], v[132:135], v[194:197]
	v_mfma_f32_16x16x32_f16 v[198:201], v[214:217], v[158:161], v[198:201]
	v_mfma_f32_16x16x32_f16 v[202:205], v[222:225], v[132:135], v[202:205]
	v_mfma_f32_16x16x32_f16 v[206:209], v[222:225], v[158:161], v[206:209]
	s_barrier
	s_mov_b32 m0, s13
	v_lshl_add_u64 v[4:5], v[8:9], 0, s[42:43]
	global_load_lds_dwordx4 v[4:5], off
	v_lshl_add_u64 v[4:5], v[8:9], 0, s[96:97]
	s_mov_b32 m0, s12
	s_nop 0
	global_load_lds_dwordx4 v[4:5], off
	s_waitcnt vmcnt(6)
	s_barrier
	v_mfma_f32_16x16x32_f16 v[24:27], v[162:165], v[112:115], v[24:27]
	v_mfma_f32_16x16x32_f16 v[28:31], v[162:165], v[238:241], v[28:31]
	v_mfma_f32_16x16x32_f16 v[60:63], v[210:213], v[112:115], v[62:65]
	v_mfma_f32_16x16x32_f16 v[128:131], v[210:213], v[238:241], v[136:139]
	v_mfma_f32_16x16x32_f16 v[132:135], v[218:221], v[112:115], v[140:143]
	v_mfma_f32_16x16x32_f16 v[136:139], v[218:221], v[238:241], v[144:147]
	v_mfma_f32_16x16x32_f16 v[112:115], v[226:229], v[112:115], v[116:119]
	v_mfma_f32_16x16x32_f16 v[116:119], v[226:229], v[238:241], v[124:127]
	v_mfma_f32_16x16x32_f16 v[24:27], v[170:173], v[234:237], v[24:27]
	v_mfma_f32_16x16x32_f16 v[28:31], v[170:173], v[242:245], v[28:31]
	v_mfma_f32_16x16x32_f16 v[60:63], v[214:217], v[234:237], v[60:63]
	v_mfma_f32_16x16x32_f16 v[128:131], v[214:217], v[242:245], v[128:131]
	v_mfma_f32_16x16x32_f16 v[132:135], v[222:225], v[234:237], v[132:135]
	v_mfma_f32_16x16x32_f16 v[136:139], v[222:225], v[242:245], v[136:139]
	v_mfma_f32_16x16x32_f16 v[112:115], v[230:233], v[234:237], v[112:115]
	v_mfma_f32_16x16x32_f16 v[116:119], v[230:233], v[242:245], v[116:119]
	s_mov_b64 s[12:13], 0x10180
	s_mov_b32 m0, s80
	v_lshl_add_u64 v[4:5], v[6:7], 0, s[12:13]
	s_mov_b64 s[12:13], 0x18180
	s_barrier
	ds_read_b128 v[124:127], v81
	ds_read_b128 v[140:143], v81 offset:1024
	ds_read_b128 v[144:147], v81 offset:2048
	ds_read_b128 v[148:151], v81 offset:3072
	ds_read_b128 v[158:161], v123
	ds_read_b128 v[162:165], v123 offset:1024
	ds_read_b128 v[170:173], v123 offset:2048
	ds_read_b128 v[210:213], v123 offset:3072
	ds_read_b128 v[214:217], v123 offset:4096
	ds_read_b128 v[218:221], v123 offset:5120
	ds_read_b128 v[222:225], v123 offset:6144
	ds_read_b128 v[226:229], v123 offset:7168
	global_load_lds_dwordx4 v[4:5], off
	v_lshl_add_u64 v[4:5], v[6:7], 0, s[12:13]
	s_mov_b32 m0, s71
	s_nop 0
	global_load_lds_dwordx4 v[4:5], off
	s_barrier
	s_waitcnt lgkmcnt(0)
	s_waitcnt lgkmcnt(0)
	v_mfma_f32_16x16x32_f16 v[4:7], v[158:161], v[124:127], v[16:19]
	v_mfma_f32_16x16x32_f16 v[14:17], v[158:161], v[144:147], v[66:69]
	v_mfma_f32_16x16x32_f16 v[64:67], v[170:173], v[124:127], v[76:79]
	v_mfma_f32_16x16x32_f16 v[68:71], v[170:173], v[144:147], v[84:87]
	v_mfma_f32_16x16x32_f16 v[76:79], v[214:217], v[124:127], v[96:99]
	v_mfma_f32_16x16x32_f16 v[84:87], v[214:217], v[144:147], v[100:103]
	v_mfma_f32_16x16x32_f16 v[96:99], v[222:225], v[124:127], v[104:107]
	v_mfma_f32_16x16x32_f16 v[100:103], v[222:225], v[144:147], v[108:111]
	v_mfma_f32_16x16x32_f16 v[4:7], v[162:165], v[140:143], v[4:7]
	v_mfma_f32_16x16x32_f16 v[14:17], v[162:165], v[148:151], v[14:17]
	v_mfma_f32_16x16x32_f16 v[64:67], v[210:213], v[140:143], v[64:67]
	v_mfma_f32_16x16x32_f16 v[68:71], v[210:213], v[148:151], v[68:71]
	v_mfma_f32_16x16x32_f16 v[76:79], v[218:221], v[140:143], v[76:79]
	v_mfma_f32_16x16x32_f16 v[84:87], v[218:221], v[148:151], v[84:87]
	v_mfma_f32_16x16x32_f16 v[96:99], v[226:229], v[140:143], v[96:99]
	v_mfma_f32_16x16x32_f16 v[100:103], v[226:229], v[148:151], v[100:103]
	s_barrier
	ds_read_b128 v[104:107], v81 offset:16384
	ds_read_b128 v[108:111], v81 offset:17408
	ds_read_b128 v[230:233], v81 offset:18432
	ds_read_b128 v[234:237], v81 offset:19456
	s_barrier
;   #define LDA(dst,b,h) for(int m=0;m<4;++m)for(int k=0;k<2;++k) \
;     dst[m][k]=*reinterpret_cast<const h8*>(la+(((b)*2+(h))*16384+m*2048+k*1024))
;   #define LDB(dst,b,h) for(int n=0;n<2;++n)for(int k=0;k<2;++k) \
;     dst[n][k]=*reinterpret_cast<const h8*>(lb+(((b)*2+(h))*16384+n*2048+k*1024))
;   #define MMA(ai,bj,At,Bt_) do{__builtin_amdgcn_s_setprio(1); \
;     for(int m=0;m<4;++m)for(int n=0;n<2;++n)for(int k=0;k<2;++k) \
;       acc[ai][bj][m][n]=__builtin_amdgcn_mfma_f32_16x16x32_f16(At[m][k],Bt_[n][k],acc[ai][bj][m][n],0,0,0); \
;     __builtin_amdgcn_s_setprio(0);}while(0)
;   #define WAIT_V(n) asm volatile("s_waitcnt vmcnt(" #n ")":::"memory")
;   #define WAIT_L(n) asm volatile("s_waitcnt lgkmcnt(" #n ")":::"memory")
;   #define BAR __builtin_amdgcn_s_barrier()
;     ...
;     LDB(B1,0,1); BAR; WAIT_L(0); MMA(0,1,At,B1); BAR;
;     LDA(At,0,1); WAIT_V(4); BAR; WAIT_L(0); MMA(1,0,At,B0); MMA(1,1,At,B1); BAR; }
;   { LDB(B0,1,0); LDA(At,1,0); WAIT_V(2); BAR; WAIT_L(0); MMA(0,0,At,B0); BAR;
	s_waitcnt lgkmcnt(0)
	s_waitcnt lgkmcnt(0)
	v_mfma_f32_16x16x32_f16 v[8:11], v[158:161], v[104:107], v[10:13]
	v_mfma_f32_16x16x32_f16 v[238:241], v[162:165], v[108:111], v[8:11]
	v_mfma_f32_16x16x32_f16 v[8:11], v[158:161], v[230:233], v[32:35]
	v_mfma_f32_16x16x32_f16 v[32:35], v[162:165], v[234:237], v[8:11]
	v_mfma_f32_16x16x32_f16 v[8:11], v[170:173], v[104:107], v[36:39]
	v_mfma_f32_16x16x32_f16 v[158:161], v[210:213], v[108:111], v[8:11]
	v_mfma_f32_16x16x32_f16 v[8:11], v[170:173], v[230:233], v[40:43]
	v_mfma_f32_16x16x32_f16 v[40:43], v[210:213], v[234:237], v[8:11]
	v_mfma_f32_16x16x32_f16 v[8:11], v[214:217], v[104:107], v[44:47]
	v_mfma_f32_16x16x32_f16 v[162:165], v[218:221], v[108:111], v[8:11]
	v_mfma_f32_16x16x32_f16 v[8:11], v[214:217], v[230:233], v[48:51]
	v_mfma_f32_16x16x32_f16 v[48:51], v[218:221], v[234:237], v[8:11]
	v_mfma_f32_16x16x32_f16 v[8:11], v[222:225], v[104:107], v[52:55]
	v_mfma_f32_16x16x32_f16 v[170:173], v[226:229], v[108:111], v[8:11]
	v_mfma_f32_16x16x32_f16 v[8:11], v[222:225], v[230:233], v[56:59]
	v_mfma_f32_16x16x32_f16 v[56:59], v[226:229], v[234:237], v[8:11]
	s_barrier
	s_nop 4
	ds_read_b128 v[8:11], v123 offset:16384
	ds_read_b128 v[36:39], v123 offset:17408
	ds_read_b128 v[44:47], v123 offset:18432
	ds_read_b128 v[52:55], v123 offset:19456
	ds_read_b128 v[210:213], v123 offset:20480
	ds_read_b128 v[214:217], v123 offset:21504
	ds_read_b128 v[218:221], v123 offset:22528
	ds_read_b128 v[222:225], v123 offset:23552
	s_waitcnt vmcnt(4)
	s_barrier
	s_waitcnt lgkmcnt(0)
	s_waitcnt lgkmcnt(0)
	v_mfma_f32_16x16x32_f16 v[0:3], v[218:221], v[124:127], v[0:3]
	v_mfma_f32_16x16x32_f16 v[186:189], v[8:11], v[124:127], v[186:189]
	v_mfma_f32_16x16x32_f16 v[194:197], v[44:47], v[124:127], v[194:197]
	v_mfma_f32_16x16x32_f16 v[202:205], v[210:213], v[124:127], v[202:205]
	v_mfma_f32_16x16x32_f16 v[124:127], v[222:225], v[140:143], v[0:3]
	v_mfma_f32_16x16x32_f16 v[0:3], v[218:221], v[144:147], v[20:23]
	v_mfma_f32_16x16x32_f16 v[186:189], v[36:39], v[140:143], v[186:189]
	v_mfma_f32_16x16x32_f16 v[190:193], v[8:11], v[144:147], v[190:193]
	v_mfma_f32_16x16x32_f16 v[194:197], v[52:55], v[140:143], v[194:197]
	v_mfma_f32_16x16x32_f16 v[198:201], v[44:47], v[144:147], v[198:201]
	v_mfma_f32_16x16x32_f16 v[202:205], v[214:217], v[140:143], v[202:205]
	v_mfma_f32_16x16x32_f16 v[206:209], v[210:213], v[144:147], v[206:209]
	v_mfma_f32_16x16x32_f16 v[140:143], v[222:225], v[148:151], v[0:3]
	v_mfma_f32_16x16x32_f16 v[190:193], v[36:39], v[148:151], v[190:193]
	v_mfma_f32_16x16x32_f16 v[198:201], v[52:55], v[148:151], v[198:201]
	v_mfma_f32_16x16x32_f16 v[206:209], v[214:217], v[148:151], v[206:209]
	v_mfma_f32_16x16x32_f16 v[0:3], v[8:11], v[104:107], v[24:27]
	v_mfma_f32_16x16x32_f16 v[144:147], v[36:39], v[108:111], v[0:3]
	v_mfma_f32_16x16x32_f16 v[0:3], v[8:11], v[230:233], v[28:31]
	v_mfma_f32_16x16x32_f16 v[148:151], v[36:39], v[234:237], v[0:3]
	v_mfma_f32_16x16x32_f16 v[0:3], v[44:47], v[104:107], v[60:63]
	v_mfma_f32_16x16x32_f16 v[226:229], v[52:55], v[108:111], v[0:3]
	v_mfma_f32_16x16x32_f16 v[0:3], v[44:47], v[230:233], v[128:131]
	v_mfma_f32_16x16x32_f16 v[242:245], v[52:55], v[234:237], v[0:3]
	v_mfma_f32_16x16x32_f16 v[0:3], v[210:213], v[104:107], v[132:135]
	v_mfma_f32_16x16x32_f16 v[246:249], v[214:217], v[108:111], v[0:3]
	v_mfma_f32_16x16x32_f16 v[0:3], v[210:213], v[230:233], v[136:139]
	v_mfma_f32_16x16x32_f16 v[136:139], v[214:217], v[234:237], v[0:3]
	v_mfma_f32_16x16x32_f16 v[0:3], v[218:221], v[104:107], v[112:115]
	v_mfma_f32_16x16x32_f16 v[210:213], v[222:225], v[108:111], v[0:3]
	v_mfma_f32_16x16x32_f16 v[0:3], v[218:221], v[230:233], v[116:119]
	v_mfma_f32_16x16x32_f16 v[214:217], v[222:225], v[234:237], v[0:3]
	s_barrier
	ds_read_b128 v[108:111], v81 offset:32768
	ds_read_b128 v[112:115], v81 offset:33792
	ds_read_b128 v[116:119], v81 offset:34816
	ds_read_b128 v[128:131], v81 offset:35840
	ds_read_b128 v[36:39], v123 offset:32768
	ds_read_b128 v[44:47], v123 offset:33792
	ds_read_b128 v[52:55], v123 offset:34816
	ds_read_b128 v[60:63], v123 offset:35840
	ds_read_b128 v[104:107], v123 offset:36864
	ds_read_b128 v[132:135], v123 offset:37888
	ds_read_b128 v[218:221], v123 offset:38912
	ds_read_b128 v[222:225], v123 offset:39936
	s_waitcnt vmcnt(2)
	s_barrier
;   #define LDA(dst,b,h) for(int m=0;m<4;++m)for(int k=0;k<2;++k) \
;     dst[m][k]=*reinterpret_cast<const h8*>(la+(((b)*2+(h))*16384+m*2048+k*1024))
;   #define LDB(dst,b,h) for(int n=0;n<2;++n)for(int k=0;k<2;++k) \
;     dst[n][k]=*reinterpret_cast<const h8*>(lb+(((b)*2+(h))*16384+n*2048+k*1024))
;   #define MMA(ai,bj,At,Bt_) do{__builtin_amdgcn_s_setprio(1); \
;     for(int m=0;m<4;++m)for(int n=0;n<2;++n)for(int k=0;k<2;++k) \
;       acc[ai][bj][m][n]=__builtin_amdgcn_mfma_f32_16x16x32_f16(At[m][k],Bt_[n][k],acc[ai][bj][m][n],0,0,0); \
;     __builtin_amdgcn_s_setprio(0);}while(0)
;   #define WAIT_V(n) asm volatile("s_waitcnt vmcnt(" #n ")":::"memory")
;   #define WAIT_L(n) asm volatile("s_waitcnt lgkmcnt(" #n ")":::"memory")
;   #define BAR __builtin_amdgcn_s_barrier()
;     ...
;   { LDB(B0,1,0); LDA(At,1,0); WAIT_V(2); BAR; WAIT_L(0); MMA(0,0,At,B0); BAR;
;     LDB(B1,1,1); WAIT_V(0); BAR; WAIT_L(0); MMA(0,1,At,B1); BAR;
;     LDA(At,1,1); BAR; WAIT_L(0); MMA(1,0,At,B0); MMA(1,1,At,B1); BAR; }
;   if(wr==0)BAR;
	s_waitcnt lgkmcnt(0)
	s_waitcnt lgkmcnt(0)
	v_mfma_f32_16x16x32_f16 v[0:3], v[36:39], v[108:111], v[4:7]
	v_mfma_f32_16x16x32_f16 v[4:7], v[36:39], v[116:119], v[14:17]
	v_mfma_f32_16x16x32_f16 v[8:11], v[52:55], v[108:111], v[64:67]
	v_mfma_f32_16x16x32_f16 v[12:15], v[52:55], v[116:119], v[68:71]
	v_mfma_f32_16x16x32_f16 v[16:19], v[104:107], v[108:111], v[76:79]
	v_mfma_f32_16x16x32_f16 v[20:23], v[104:107], v[116:119], v[84:87]
	v_mfma_f32_16x16x32_f16 v[24:27], v[218:221], v[108:111], v[96:99]
	v_mfma_f32_16x16x32_f16 v[28:31], v[218:221], v[116:119], v[100:103]
	v_mfma_f32_16x16x32_f16 v[0:3], v[44:47], v[112:115], v[0:3]
	v_mfma_f32_16x16x32_f16 v[4:7], v[44:47], v[128:131], v[4:7]
	v_mfma_f32_16x16x32_f16 v[8:11], v[60:63], v[112:115], v[8:11]
	v_mfma_f32_16x16x32_f16 v[12:15], v[60:63], v[128:131], v[12:15]
	v_mfma_f32_16x16x32_f16 v[16:19], v[132:135], v[112:115], v[16:19]
	v_mfma_f32_16x16x32_f16 v[20:23], v[132:135], v[128:131], v[20:23]
	v_mfma_f32_16x16x32_f16 v[24:27], v[222:225], v[112:115], v[24:27]
	v_mfma_f32_16x16x32_f16 v[28:31], v[222:225], v[128:131], v[28:31]
	s_barrier
	ds_read_b128 v[230:233], v81 offset:49152
	ds_read_b128 v[234:237], v81 offset:50176
	ds_read_b128 v[250:253], v81 offset:51200
	ds_read_b128 v[176:179], v81 offset:52224
	s_waitcnt vmcnt(0)
	s_barrier
	s_waitcnt lgkmcnt(0)
	s_waitcnt lgkmcnt(0)
	v_mfma_f32_16x16x32_f16 v[32:35], v[36:39], v[250:253], v[32:35]
	v_mfma_f32_16x16x32_f16 v[64:67], v[36:39], v[230:233], v[238:241]
	v_mfma_f32_16x16x32_f16 v[36:39], v[44:47], v[176:179], v[32:35]
	v_mfma_f32_16x16x32_f16 v[32:35], v[52:55], v[230:233], v[158:161]
	v_mfma_f32_16x16x32_f16 v[68:71], v[60:63], v[234:237], v[32:35]
	v_mfma_f32_16x16x32_f16 v[32:35], v[52:55], v[250:253], v[40:43]
	v_mfma_f32_16x16x32_f16 v[64:67], v[44:47], v[234:237], v[64:67]
	v_mfma_f32_16x16x32_f16 v[44:47], v[60:63], v[176:179], v[32:35]
	v_mfma_f32_16x16x32_f16 v[32:35], v[104:107], v[230:233], v[162:165]
	v_mfma_f32_16x16x32_f16 v[96:99], v[132:135], v[234:237], v[32:35]
	v_mfma_f32_16x16x32_f16 v[32:35], v[104:107], v[250:253], v[48:51]
	v_mfma_f32_16x16x32_f16 v[52:55], v[132:135], v[176:179], v[32:35]
	v_mfma_f32_16x16x32_f16 v[32:35], v[218:221], v[230:233], v[170:173]
	v_mfma_f32_16x16x32_f16 v[100:103], v[222:225], v[234:237], v[32:35]
	v_mfma_f32_16x16x32_f16 v[32:35], v[218:221], v[250:253], v[56:59]
	v_mfma_f32_16x16x32_f16 v[60:63], v[222:225], v[176:179], v[32:35]
	s_barrier
	ds_read_b128 v[132:135], v123 offset:49152
	ds_read_b128 v[158:161], v123 offset:50176
	ds_read_b128 v[162:165], v123 offset:51200
	ds_read_b128 v[170:173], v123 offset:52224
	ds_read_b128 v[218:221], v123 offset:53248
	ds_read_b128 v[222:225], v123 offset:54272
	ds_read_b128 v[238:241], v123 offset:55296
	ds_read_b128 v[166:169], v123 offset:56320
	s_barrier
	s_waitcnt lgkmcnt(0)
	s_waitcnt lgkmcnt(0)
	v_mfma_f32_16x16x32_f16 v[32:35], v[132:135], v[108:111], v[186:189]
	v_mfma_f32_16x16x32_f16 v[40:43], v[162:165], v[108:111], v[194:197]
	v_mfma_f32_16x16x32_f16 v[76:79], v[218:221], v[108:111], v[202:205]
	v_mfma_f32_16x16x32_f16 v[84:87], v[238:241], v[108:111], v[124:127]
	v_mfma_f32_16x16x32_f16 v[48:51], v[158:161], v[112:115], v[32:35]
	v_mfma_f32_16x16x32_f16 v[32:35], v[132:135], v[116:119], v[190:193]
	v_mfma_f32_16x16x32_f16 v[56:59], v[170:173], v[112:115], v[40:43]
	v_mfma_f32_16x16x32_f16 v[40:43], v[162:165], v[116:119], v[198:201]
	v_mfma_f32_16x16x32_f16 v[104:107], v[222:225], v[112:115], v[76:79]
	v_mfma_f32_16x16x32_f16 v[76:79], v[218:221], v[116:119], v[206:209]
	v_mfma_f32_16x16x32_f16 v[112:115], v[166:169], v[112:115], v[84:87]
	v_mfma_f32_16x16x32_f16 v[84:87], v[238:241], v[116:119], v[140:143]
	v_mfma_f32_16x16x32_f16 v[32:35], v[158:161], v[128:131], v[32:35]
	v_mfma_f32_16x16x32_f16 v[40:43], v[170:173], v[128:131], v[40:43]
	v_mfma_f32_16x16x32_f16 v[76:79], v[222:225], v[128:131], v[76:79]
	v_mfma_f32_16x16x32_f16 v[84:87], v[166:169], v[128:131], v[84:87]
	v_mfma_f32_16x16x32_f16 v[124:127], v[162:165], v[250:253], v[242:245]
	v_mfma_f32_16x16x32_f16 v[108:111], v[132:135], v[230:233], v[144:147]
	v_mfma_f32_16x16x32_f16 v[116:119], v[132:135], v[250:253], v[148:151]
	v_mfma_f32_16x16x32_f16 v[132:135], v[170:173], v[176:179], v[124:127]
	v_mfma_f32_16x16x32_f16 v[124:127], v[218:221], v[230:233], v[246:249]
	v_mfma_f32_16x16x32_f16 v[144:147], v[222:225], v[234:237], v[124:127]
	v_mfma_f32_16x16x32_f16 v[124:127], v[218:221], v[250:253], v[136:139]
	v_mfma_f32_16x16x32_f16 v[136:139], v[222:225], v[176:179], v[124:127]
	v_mfma_f32_16x16x32_f16 v[124:127], v[238:241], v[230:233], v[210:213]
	v_mfma_f32_16x16x32_f16 v[128:131], v[158:161], v[176:179], v[116:119]
	v_mfma_f32_16x16x32_f16 v[116:119], v[162:165], v[230:233], v[226:229]
	v_mfma_f32_16x16x32_f16 v[148:151], v[166:169], v[234:237], v[124:127]
	v_mfma_f32_16x16x32_f16 v[124:127], v[238:241], v[250:253], v[214:217]
	v_mfma_f32_16x16x32_f16 v[108:111], v[158:161], v[234:237], v[108:111]
	v_mfma_f32_16x16x32_f16 v[116:119], v[170:173], v[234:237], v[116:119]
	v_mfma_f32_16x16x32_f16 v[140:143], v[166:169], v[176:179], v[124:127]
	s_movk_i32 s12, 0x100
	v_cmp_gt_u32_e32 vcc, s12, v122
	s_barrier
	s_and_saveexec_b64 s[12:13], vcc
	s_cbranch_execz .LBB0_481
	s_barrier

;   #define STAGE(P,BASE,LD,br,kt) do{ const HALF* _u=(BASE)+(long)(br)*(((&(LD))==&lda)?lda_u:(LD))+(long)(kt)*G_BK; \
;     for(int _i=0;_i<2;++_i){ \
;       __builtin_amdgcn_global_load_lds((const unsigned*)(_u+(long)_i*(((&(LD))==&lda)?stepa:stepb)+((&(LD))==&lda?oa0:ob0)), \
;         (unsigned*)((char*)(P)+t5*16+_i*8192),16,0,0);}}while(0)
;   #define WAIT_V(n) asm volatile("s_waitcnt vmcnt(" #n ")":::"memory")
;   #define BAR __builtin_amdgcn_s_barrier()
; #define FOR_AI _Pragma("unroll") for (int ai = 0; ai < 2; ++ai)
; #define FOR_BJ _Pragma("unroll") for (int bj = 0; bj < 2; ++bj)
; #define FOR_M4 _Pragma("unroll") for (int m = 0; m < 4; ++m)
; #define FOR_NN _Pragma("unroll") for (int n = 0; n < 2; ++n)
;     ...
;   const int _ob=fr*64+fq*16, _sw=_ob^(((_ob>>9)&1)<<5);
;   const char* la=(const char*)shm+wr*8192+_sw;
;   const char* lb=(const char*)shm+65536+wc*4096+_sw;
;   unsigned oa0, ob0;
;   const int stepa = n2 ? 1024 : 64 * lda, stepb = 64 * ldb;
;   const int lda_u = n2 ? 16 : lda;
;   {int _b=t5*16;int _r,_c;g_stage_rc(_b,_r,_c);
;     oa0=n2 ? (unsigned)((n2*(_r&63)+(_r>>6))*1024+_c) : (unsigned)(_r*lda+_c); ob0=(unsigned)(_r*ldb+_c);}
;   STAGE(SB(0,0),Bt,ldb,0,0); STAGE(SA(0,0),A,lda,0,0);
;   STAGE(SB(0,1),Bt,ldb,G_HALF,0); STAGE(SA(0,1),A,lda,G_HALF,0);
;   if(wr==1)BAR;
;   WAIT_V(4); BAR;
;   STAGE(SB(1,0),Bt,ldb,0,1); STAGE(SA(1,0),A,lda,0,1); STAGE(SB(1,1),Bt,ldb,G_HALF,1);
;   WAIT_V(6); BAR;
; __device__ void job_retout_g(const P& p, int l, int job, HALF* sm) {
;     ...
;     FOR_BJ FOR_NN {
;       const int i = bj * 128 + wc * 32 + n * 16 + fr;
;       const float sc = expf(lgf * (float)(i + 1) - lgb * (float)(256 - i));
;       FOR_AI FOR_M4 { acc[ai][bj][m][n] *= sc; }
;     }
;   }
;   __syncthreads();
;   {
;     const HALF* Sb = (const HALF*)(ws + G_ST) + ((size_t)((1 * 32 + cgi) * 4 + h) * 512 + nt2 * 256) * 256;
;     gemm256(acc, Sb, 256, Qp, 1024, 256, sm);
.LBB0_483:
	s_or_b64 exec, exec, s[10:11]
	v_pk_mul_f32 v[74:75], v[26:27], v[120:121] op_sel_hi:[1,0]
	v_pk_mul_f32 v[26:27], v[50:51], v[120:121] op_sel_hi:[1,0]
	v_pk_mul_f32 v[50:51], v[42:43], v[170:171] op_sel_hi:[1,0]
	v_pk_mul_f32 v[42:43], v[78:79], v[170:171] op_sel_hi:[1,0]
	v_pk_mul_f32 v[78:79], v[70:71], v[172:173] op_sel_hi:[1,0]
	v_pk_mul_f32 v[70:71], v[98:99], v[172:173] op_sel_hi:[1,0]
	v_pk_mul_f32 v[98:99], v[62:63], v[168:169] op_sel_hi:[1,0]
	v_pk_mul_f32 v[62:63], v[130:131], v[168:169] op_sel_hi:[1,0]
	v_lshlrev_b32_e32 v130, 6, v157
	v_lshlrev_b32_e32 v131, 2, v157
	v_pk_mul_f32 v[72:73], v[24:25], v[120:121] op_sel_hi:[1,0]
	v_pk_mul_f32 v[24:25], v[48:49], v[120:121] op_sel_hi:[1,0]
	v_pk_mul_f32 v[48:49], v[40:41], v[170:171] op_sel_hi:[1,0]
	v_pk_mul_f32 v[40:41], v[76:77], v[170:171] op_sel_hi:[1,0]
	v_pk_mul_f32 v[76:77], v[68:69], v[172:173] op_sel_hi:[1,0]
	v_pk_mul_f32 v[68:69], v[96:97], v[172:173] op_sel_hi:[1,0]
	v_pk_mul_f32 v[96:97], v[60:61], v[168:169] op_sel_hi:[1,0]
	v_pk_mul_f32 v[60:61], v[128:129], v[168:169] op_sel_hi:[1,0]
	v_and_b32_e32 v128, 48, v157
	v_and_b32_e32 v129, 0x3c0, v130
	v_and_b32_e32 v131, 32, v131
	v_bitop3_b32 v128, v129, v131, v128 bitop3:0x36
	v_add_u32_e32 v131, s29, v194
	v_pk_mul_f32 v[80:81], v[16:17], v[120:121] op_sel_hi:[1,0]
	v_readfirstlane_b32 s13, v131
	v_add_u32_e32 v131, 0x2000, v131
	v_pk_mul_f32 v[16:17], v[56:57], v[120:121] op_sel_hi:[1,0]
	v_pk_mul_f32 v[56:57], v[32:33], v[170:171] op_sel_hi:[1,0]
	v_pk_mul_f32 v[32:33], v[84:85], v[170:171] op_sel_hi:[1,0]
	v_pk_mul_f32 v[84:85], v[64:65], v[172:173] op_sel_hi:[1,0]
	v_pk_mul_f32 v[64:65], v[100:101], v[172:173] op_sel_hi:[1,0]
	v_pk_mul_f32 v[100:101], v[52:53], v[168:169] op_sel_hi:[1,0]
	v_pk_mul_f32 v[52:53], v[132:133], v[168:169] op_sel_hi:[1,0]
	v_lshl_add_u64 v[132:133], v[164:165], 0, s[84:85]
	s_mov_b32 m0, s13
	s_mov_b64 s[10:11], 0x20080
	v_readfirstlane_b32 s12, v131
	v_add_u32_e32 v131, 0x8000, v190
	s_waitcnt vmcnt(4)
	s_barrier
	global_load_lds_dwordx4 v[132:133], off
	v_lshl_add_u64 v[132:133], v[164:165], 0, s[10:11]
	s_mov_b32 m0, s12
	v_readfirstlane_b32 s11, v131
	v_add_u32_e32 v131, 0xa000, v190
	global_load_lds_dwordx4 v[132:133], off
	v_lshl_add_u64 v[132:133], v[160:161], 0, s[84:85]
	s_mov_b32 m0, s11
	s_mov_b64 s[20:21], 0x8080
	v_readfirstlane_b32 s10, v131
	global_load_lds_dwordx4 v[132:133], off
	v_lshl_add_u64 v[132:133], v[160:161], 0, s[20:21]
	s_mov_b32 m0, s10
	v_add_u32_e32 v131, s62, v194
	global_load_lds_dwordx4 v[132:133], off
	v_lshl_add_u64 v[132:133], v[152:153], 1, s[6:7]
	v_readfirstlane_b32 s7, v131
	v_add_u32_e32 v131, 0x2000, v131
	s_mov_b32 m0, s7
	v_readfirstlane_b32 s6, v131
	global_load_lds_dwordx4 v[132:133], off
	v_lshl_add_u64 v[132:133], v[132:133], 0, s[18:19]
	s_mov_b32 m0, s6
	v_and_b32_e32 v130, 0x3000, v130
	global_load_lds_dwordx4 v[132:133], off
	v_lshlrev_b32_e32 v129, 13, v159
	v_add3_u32 v152, s95, v130, v128
	v_pk_mul_f32 v[94:95], v[2:3], v[120:121] op_sel_hi:[1,0]
	v_pk_mul_f32 v[92:93], v[0:1], v[120:121] op_sel_hi:[1,0]
	v_pk_mul_f32 v[90:91], v[10:11], v[120:121] op_sel_hi:[1,0]
	v_pk_mul_f32 v[88:89], v[8:9], v[120:121] op_sel_hi:[1,0]
	v_pk_mul_f32 v[82:83], v[18:19], v[120:121] op_sel_hi:[1,0]
	v_pk_mul_f32 v[18:19], v[58:59], v[120:121] op_sel_hi:[1,0]
	v_pk_mul_f32 v[10:11], v[106:107], v[120:121] op_sel_hi:[1,0]
	v_pk_mul_f32 v[8:9], v[104:105], v[120:121] op_sel_hi:[1,0]
	v_pk_mul_f32 v[2:3], v[114:115], v[120:121] op_sel_hi:[1,0]
	v_pk_mul_f32 v[0:1], v[112:113], v[120:121] op_sel_hi:[1,0]
	v_pk_mul_f32 v[114:115], v[22:23], v[170:171] op_sel_hi:[1,0]
	v_pk_mul_f32 v[112:113], v[20:21], v[170:171] op_sel_hi:[1,0]
	v_pk_mul_f32 v[106:107], v[30:31], v[170:171] op_sel_hi:[1,0]
	v_pk_mul_f32 v[104:105], v[28:29], v[170:171] op_sel_hi:[1,0]
	v_pk_mul_f32 v[58:59], v[34:35], v[170:171] op_sel_hi:[1,0]
	v_pk_mul_f32 v[34:35], v[86:87], v[170:171] op_sel_hi:[1,0]
	v_pk_mul_f32 v[86:87], v[66:67], v[172:173] op_sel_hi:[1,0]
	v_pk_mul_f32 v[66:67], v[102:103], v[172:173] op_sel_hi:[1,0]
	v_pk_mul_f32 v[30:31], v[110:111], v[172:173] op_sel_hi:[1,0]
	v_pk_mul_f32 v[28:29], v[108:109], v[172:173] op_sel_hi:[1,0]
	v_pk_mul_f32 v[22:23], v[118:119], v[172:173] op_sel_hi:[1,0]
	v_pk_mul_f32 v[20:21], v[116:117], v[172:173] op_sel_hi:[1,0]
	v_pk_mul_f32 v[118:119], v[38:39], v[168:169] op_sel_hi:[1,0]
	v_pk_mul_f32 v[116:117], v[36:37], v[168:169] op_sel_hi:[1,0]
	v_pk_mul_f32 v[110:111], v[46:47], v[168:169] op_sel_hi:[1,0]
	v_pk_mul_f32 v[108:109], v[44:45], v[168:169] op_sel_hi:[1,0]
	v_pk_mul_f32 v[102:103], v[54:55], v[168:169] op_sel_hi:[1,0]
	v_pk_mul_f32 v[54:55], v[134:135], v[168:169] op_sel_hi:[1,0]
	v_pk_mul_f32 v[46:47], v[138:139], v[168:169] op_sel_hi:[1,0]
	v_pk_mul_f32 v[44:45], v[136:137], v[168:169] op_sel_hi:[1,0]
	v_pk_mul_f32 v[38:39], v[142:143], v[168:169] op_sel_hi:[1,0]
	v_pk_mul_f32 v[36:37], v[140:141], v[168:169] op_sel_hi:[1,0]
	s_waitcnt vmcnt(6)
	s_barrier
;   #define STAGE(P,BASE,LD,br,kt) do{ const HALF* _u=(BASE)+(long)(br)*(((&(LD))==&lda)?lda_u:(LD))+(long)(kt)*G_BK; \
;     for(int _i=0;_i<2;++_i){ \
;       __builtin_amdgcn_global_load_lds((const unsigned*)(_u+(long)_i*(((&(LD))==&lda)?stepa:stepb)+((&(LD))==&lda?oa0:ob0)), \
;         (unsigned*)((char*)(P)+t5*16+_i*8192),16,0,0);}}while(0)
;   #define LDA(dst,b,h) for(int m=0;m<4;++m)for(int k=0;k<2;++k) \
;     dst[m][k]=*reinterpret_cast<const h8*>(la+(((b)*2+(h))*16384+m*2048+k*1024))
;   #define LDB(dst,b,h) for(int n=0;n<2;++n)for(int k=0;k<2;++k) \
;     dst[n][k]=*reinterpret_cast<const h8*>(lb+(((b)*2+(h))*16384+n*2048+k*1024))
;   #define MMA(ai,bj,At,Bt_) do{__builtin_amdgcn_s_setprio(1); \
;     for(int m=0;m<4;++m)for(int n=0;n<2;++n)for(int k=0;k<2;++k) \
;       acc[ai][bj][m][n]=__builtin_amdgcn_mfma_f32_16x16x32_f16(At[m][k],Bt_[n][k],acc[ai][bj][m][n],0,0,0); \
;     __builtin_amdgcn_s_setprio(0);}while(0)
;   #define WAIT_L(n) asm volatile("s_waitcnt lgkmcnt(" #n ")":::"memory")
;   #define BAR __builtin_amdgcn_s_barrier()
;   #define SCHED __builtin_amdgcn_sched_barrier(0)
; #define FOR_AI _Pragma("unroll") for (int ai = 0; ai < 2; ++ai)
; #define FOR_M4 _Pragma("unroll") for (int m = 0; m < 4; ++m)
;     ...
;     LDB(B0,0,0); SCHED; LDA(At,0,0); STAGE(SA(1,1),A,lda,G_HALF,t+1);
;     WAIT_L(8); BAR; WAIT_L(0); MMA(0,0,At,B0); BAR; SCHED;
;     LDB(B1,0,1); STAGE(SB(0,0),Bt,ldb,0,t+2);
;     BAR; WAIT_L(0); MMA(0,1,At,B1); BAR;
;     LDA(At,0,1); STAGE(SA(0,0),A,lda,0,t+2);
;     BAR; WAIT_L(0); MMA(1,0,At,B0); BAR; SCHED;
; __device__ void job_retout_g(const P& p, int l, int job, HALF* sm) {
;     ...
;       FOR_AI FOR_M4 { acc[ai][bj][m][n] *= sc; }
	v_add3_u32 v159, 0, v129, v128
	ds_read_b128 v[128:131], v152
	ds_read_b128 v[132:135], v152 offset:1024
	ds_read_b128 v[136:139], v152 offset:2048
	ds_read_b128 v[140:143], v152 offset:3072
	v_pk_mul_f32 v[126:127], v[6:7], v[170:171] op_sel_hi:[1,0]
	v_pk_mul_f32 v[124:125], v[4:5], v[170:171] op_sel_hi:[1,0]
	v_pk_mul_f32 v[122:123], v[14:15], v[170:171] op_sel_hi:[1,0]
	v_pk_mul_f32 v[120:121], v[12:13], v[170:171] op_sel_hi:[1,0]
	v_pk_mul_f32 v[14:15], v[146:147], v[172:173] op_sel_hi:[1,0]
	v_pk_mul_f32 v[12:13], v[144:145], v[172:173] op_sel_hi:[1,0]
	v_pk_mul_f32 v[6:7], v[150:151], v[172:173] op_sel_hi:[1,0]
	v_pk_mul_f32 v[4:5], v[148:149], v[172:173] op_sel_hi:[1,0]
	v_add_u32_e32 v210, 0xc000, v190
	v_lshl_add_u64 v[172:173], v[166:167], 0, s[84:85]
	v_readfirstlane_b32 s18, v210
	v_add_u32_e32 v210, 0xe000, v190
	s_mov_b32 m0, s18
	v_readfirstlane_b32 s17, v210
	ds_read_b128 v[144:147], v159
	ds_read_b128 v[148:151], v159 offset:1024
	ds_read_b128 v[168:171], v159 offset:2048
	ds_read_b128 v[176:179], v159 offset:3072
	ds_read_b128 v[194:197], v159 offset:4096
	ds_read_b128 v[198:201], v159 offset:5120
	ds_read_b128 v[202:205], v159 offset:6144
	ds_read_b128 v[206:209], v159 offset:7168
	global_load_lds_dwordx4 v[172:173], off
	v_lshl_add_u64 v[172:173], v[166:167], 0, s[20:21]
	s_mov_b32 m0, s17
	s_nop 0
	global_load_lds_dwordx4 v[172:173], off
	s_waitcnt lgkmcnt(8)
	s_barrier
	s_waitcnt lgkmcnt(0)
	s_waitcnt lgkmcnt(0)
	v_mfma_f32_16x16x32_f16 v[112:115], v[194:197], v[136:139], v[112:115]
	v_mfma_f32_16x16x32_f16 v[104:107], v[202:205], v[136:139], v[104:107]
	v_mfma_f32_16x16x32_f16 v[92:95], v[144:147], v[128:131], v[92:95]
	v_mfma_f32_16x16x32_f16 v[124:127], v[144:147], v[136:139], v[124:127]
	v_mfma_f32_16x16x32_f16 v[88:91], v[168:171], v[128:131], v[88:91]
	v_mfma_f32_16x16x32_f16 v[120:123], v[168:171], v[136:139], v[120:123]
	v_mfma_f32_16x16x32_f16 v[80:83], v[194:197], v[128:131], v[80:83]
	v_mfma_f32_16x16x32_f16 v[112:115], v[198:201], v[140:143], v[112:115]
	v_mfma_f32_16x16x32_f16 v[72:75], v[202:205], v[128:131], v[72:75]
	v_mfma_f32_16x16x32_f16 v[104:107], v[206:209], v[140:143], v[104:107]
	v_mfma_f32_16x16x32_f16 v[92:95], v[148:151], v[132:135], v[92:95]
	v_mfma_f32_16x16x32_f16 v[124:127], v[148:151], v[140:143], v[124:127]
	v_mfma_f32_16x16x32_f16 v[88:91], v[176:179], v[132:135], v[88:91]
	v_mfma_f32_16x16x32_f16 v[120:123], v[176:179], v[140:143], v[120:123]
	v_mfma_f32_16x16x32_f16 v[80:83], v[198:201], v[132:135], v[80:83]
	v_mfma_f32_16x16x32_f16 v[72:75], v[206:209], v[132:135], v[72:75]
	s_barrier
	v_readfirstlane_b32 s19, v192
	v_lshl_add_u64 v[172:173], v[164:165], 0, s[92:93]
	s_mov_b32 m0, s19
	v_readfirstlane_b32 s19, v193
	ds_read_b128 v[210:213], v152 offset:16384
	ds_read_b128 v[214:217], v152 offset:17408
	ds_read_b128 v[218:221], v152 offset:18432
	ds_read_b128 v[222:225], v152 offset:19456
	global_load_lds_dwordx4 v[172:173], off
	v_lshl_add_u64 v[172:173], v[164:165], 0, s[66:67]
	s_mov_b32 m0, s19
	s_nop 0
	global_load_lds_dwordx4 v[172:173], off
	s_barrier
	s_waitcnt lgkmcnt(0)
	s_waitcnt lgkmcnt(0)
	v_mfma_f32_16x16x32_f16 v[84:87], v[144:147], v[210:213], v[84:87]
	v_mfma_f32_16x16x32_f16 v[116:119], v[144:147], v[218:221], v[116:119]
	v_mfma_f32_16x16x32_f16 v[76:79], v[168:171], v[210:213], v[76:79]
	v_mfma_f32_16x16x32_f16 v[108:111], v[168:171], v[218:221], v[108:111]
	v_mfma_f32_16x16x32_f16 v[68:71], v[194:197], v[210:213], v[68:71]
	v_mfma_f32_16x16x32_f16 v[100:103], v[194:197], v[218:221], v[100:103]
	v_mfma_f32_16x16x32_f16 v[64:67], v[202:205], v[210:213], v[64:67]
	v_mfma_f32_16x16x32_f16 v[96:99], v[202:205], v[218:221], v[96:99]
	v_mfma_f32_16x16x32_f16 v[84:87], v[148:151], v[214:217], v[84:87]
	v_mfma_f32_16x16x32_f16 v[116:119], v[148:151], v[222:225], v[116:119]
	v_mfma_f32_16x16x32_f16 v[76:79], v[176:179], v[214:217], v[76:79]
	v_mfma_f32_16x16x32_f16 v[108:111], v[176:179], v[222:225], v[108:111]
	v_mfma_f32_16x16x32_f16 v[68:71], v[198:201], v[214:217], v[68:71]
	v_mfma_f32_16x16x32_f16 v[100:103], v[198:201], v[222:225], v[100:103]
	v_mfma_f32_16x16x32_f16 v[64:67], v[206:209], v[214:217], v[64:67]
	v_mfma_f32_16x16x32_f16 v[96:99], v[206:209], v[222:225], v[96:99]
	v_readfirstlane_b32 s19, v190
	v_lshl_add_u64 v[172:173], v[160:161], 0, s[92:93]
	s_mov_b32 m0, s19
	s_mov_b64 s[20:21], 0x8100
	v_readfirstlane_b32 s19, v191
	s_barrier
	ds_read_b128 v[144:147], v159 offset:16384
	ds_read_b128 v[148:151], v159 offset:17408
	ds_read_b128 v[168:171], v159 offset:18432
	ds_read_b128 v[176:179], v159 offset:19456
	ds_read_b128 v[192:195], v159 offset:20480
	ds_read_b128 v[196:199], v159 offset:21504
	ds_read_b128 v[200:203], v159 offset:22528
	ds_read_b128 v[204:207], v159 offset:23552
	global_load_lds_dwordx4 v[172:173], off
	v_lshl_add_u64 v[172:173], v[160:161], 0, s[20:21]
	s_mov_b32 m0, s19
	s_nop 0
	global_load_lds_dwordx4 v[172:173], off
	s_barrier
	s_waitcnt lgkmcnt(0)
	s_waitcnt lgkmcnt(0)
	v_mfma_f32_16x16x32_f16 v[24:27], v[144:147], v[128:131], v[24:27]
	v_mfma_f32_16x16x32_f16 v[56:59], v[144:147], v[136:139], v[56:59]
	v_mfma_f32_16x16x32_f16 v[16:19], v[168:171], v[128:131], v[16:19]
	v_mfma_f32_16x16x32_f16 v[48:51], v[168:171], v[136:139], v[48:51]
	v_mfma_f32_16x16x32_f16 v[8:11], v[192:195], v[128:131], v[8:11]
	v_mfma_f32_16x16x32_f16 v[40:43], v[192:195], v[136:139], v[40:43]
	v_mfma_f32_16x16x32_f16 v[0:3], v[200:203], v[128:131], v[0:3]
	v_mfma_f32_16x16x32_f16 v[32:35], v[200:203], v[136:139], v[32:35]
	v_mfma_f32_16x16x32_f16 v[24:27], v[148:151], v[132:135], v[24:27]
	v_mfma_f32_16x16x32_f16 v[56:59], v[148:151], v[140:143], v[56:59]
	v_mfma_f32_16x16x32_f16 v[16:19], v[176:179], v[132:135], v[16:19]
	v_mfma_f32_16x16x32_f16 v[48:51], v[176:179], v[140:143], v[48:51]
	v_mfma_f32_16x16x32_f16 v[8:11], v[196:199], v[132:135], v[8:11]
	v_mfma_f32_16x16x32_f16 v[40:43], v[196:199], v[140:143], v[40:43]
	v_mfma_f32_16x16x32_f16 v[0:3], v[204:207], v[132:135], v[0:3]
	v_mfma_f32_16x16x32_f16 v[32:35], v[204:207], v[140:143], v[32:35]
	s_barrier
;   #define STAGE(P,BASE,LD,br,kt) do{ const HALF* _u=(BASE)+(long)(br)*(((&(LD))==&lda)?lda_u:(LD))+(long)(kt)*G_BK; \
;     for(int _i=0;_i<2;++_i){ \
;       __builtin_amdgcn_global_load_lds((const unsigned*)(_u+(long)_i*(((&(LD))==&lda)?stepa:stepb)+((&(LD))==&lda?oa0:ob0)), \
;         (unsigned*)((char*)(P)+t5*16+_i*8192),16,0,0);}}while(0)
;   #define LDA(dst,b,h) for(int m=0;m<4;++m)for(int k=0;k<2;++k) \
;     dst[m][k]=*reinterpret_cast<const h8*>(la+(((b)*2+(h))*16384+m*2048+k*1024))
;   #define LDB(dst,b,h) for(int n=0;n<2;++n)for(int k=0;k<2;++k) \
;     dst[n][k]=*reinterpret_cast<const h8*>(lb+(((b)*2+(h))*16384+n*2048+k*1024))
;   #define MMA(ai,bj,At,Bt_) do{__builtin_amdgcn_s_setprio(1); \
;     for(int m=0;m<4;++m)for(int n=0;n<2;++n)for(int k=0;k<2;++k) \
;       acc[ai][bj][m][n]=__builtin_amdgcn_mfma_f32_16x16x32_f16(At[m][k],Bt_[n][k],acc[ai][bj][m][n],0,0,0); \
;     __builtin_amdgcn_s_setprio(0);}while(0)
;   #define WAIT_V(n) asm volatile("s_waitcnt vmcnt(" #n ")":::"memory")
;   #define WAIT_L(n) asm volatile("s_waitcnt lgkmcnt(" #n ")":::"memory")
;   #define BAR __builtin_amdgcn_s_barrier()
;   #define SCHED __builtin_amdgcn_sched_barrier(0)
;     ...
;     STAGE(SB(0,1),Bt,ldb,G_HALF,t+2);
;     WAIT_V(6); BAR; MMA(1,1,At,B1); BAR;
;     LDB(B0,1,0); SCHED; LDA(At,1,0); STAGE(SA(0,1),A,lda,G_HALF,t+2);
;     WAIT_L(8); BAR; WAIT_L(0); MMA(0,0,At,B0); BAR; SCHED;
;     LDB(B1,1,1); STAGE(SB(1,0),Bt,ldb,0,t+3);
;     BAR; WAIT_L(0); MMA(0,1,At,B1); BAR;
;     LDA(At,1,1); STAGE(SA(1,0),A,lda,0,t+3);
	v_readfirstlane_b32 s19, v188
	v_lshl_add_u64 v[128:129], v[162:163], 0, s[92:93]
	s_mov_b32 m0, s19
	v_readfirstlane_b32 s19, v189
	global_load_lds_dwordx4 v[128:129], off
	v_lshl_add_u64 v[128:129], v[162:163], 0, s[66:67]
	s_mov_b32 m0, s19
	s_nop 0
	global_load_lds_dwordx4 v[128:129], off
	s_waitcnt vmcnt(6)
	s_barrier
	v_mfma_f32_16x16x32_f16 v[28:31], v[144:147], v[210:213], v[28:31]
	v_mfma_f32_16x16x32_f16 v[60:63], v[144:147], v[218:221], v[60:63]
	v_mfma_f32_16x16x32_f16 v[20:23], v[168:171], v[210:213], v[20:23]
	v_mfma_f32_16x16x32_f16 v[52:55], v[168:171], v[218:221], v[52:55]
	v_mfma_f32_16x16x32_f16 v[12:15], v[192:195], v[210:213], v[12:15]
	v_mfma_f32_16x16x32_f16 v[44:47], v[192:195], v[218:221], v[44:47]
	v_mfma_f32_16x16x32_f16 v[4:7], v[200:203], v[210:213], v[4:7]
	v_mfma_f32_16x16x32_f16 v[36:39], v[200:203], v[218:221], v[36:39]
	v_mfma_f32_16x16x32_f16 v[28:31], v[148:151], v[214:217], v[28:31]
	v_mfma_f32_16x16x32_f16 v[60:63], v[148:151], v[222:225], v[60:63]
	v_mfma_f32_16x16x32_f16 v[20:23], v[176:179], v[214:217], v[20:23]
	v_mfma_f32_16x16x32_f16 v[52:55], v[176:179], v[222:225], v[52:55]
	v_mfma_f32_16x16x32_f16 v[12:15], v[196:199], v[214:217], v[12:15]
	v_mfma_f32_16x16x32_f16 v[44:47], v[196:199], v[222:225], v[44:47]
	v_mfma_f32_16x16x32_f16 v[4:7], v[204:207], v[214:217], v[4:7]
	v_mfma_f32_16x16x32_f16 v[36:39], v[204:207], v[222:225], v[36:39]
	s_barrier
	ds_read_b128 v[128:131], v152 offset:32768
	ds_read_b128 v[132:135], v152 offset:33792
	ds_read_b128 v[136:139], v152 offset:34816
	ds_read_b128 v[140:143], v152 offset:35840
	v_readfirstlane_b32 s19, v186
	v_lshl_add_u64 v[172:173], v[166:167], 0, s[92:93]
	s_mov_b32 m0, s19
	v_readfirstlane_b32 s19, v187
	ds_read_b128 v[144:147], v159 offset:32768
	ds_read_b128 v[148:151], v159 offset:33792
	ds_read_b128 v[168:171], v159 offset:34816
	ds_read_b128 v[176:179], v159 offset:35840
	ds_read_b128 v[188:191], v159 offset:36864
	ds_read_b128 v[192:195], v159 offset:37888
	ds_read_b128 v[196:199], v159 offset:38912
	ds_read_b128 v[200:203], v159 offset:39936
	global_load_lds_dwordx4 v[172:173], off
	v_lshl_add_u64 v[166:167], v[166:167], 0, s[20:21]
	s_mov_b32 m0, s19
	s_nop 0
	global_load_lds_dwordx4 v[166:167], off
	s_waitcnt lgkmcnt(8)
	s_barrier
	s_waitcnt lgkmcnt(0)
	s_waitcnt lgkmcnt(0)
	v_mfma_f32_16x16x32_f16 v[112:115], v[188:191], v[136:139], v[112:115]
	v_mfma_f32_16x16x32_f16 v[104:107], v[196:199], v[136:139], v[104:107]
	v_mfma_f32_16x16x32_f16 v[92:95], v[144:147], v[128:131], v[92:95]
	v_mfma_f32_16x16x32_f16 v[124:127], v[144:147], v[136:139], v[124:127]
	v_mfma_f32_16x16x32_f16 v[88:91], v[168:171], v[128:131], v[88:91]
	v_mfma_f32_16x16x32_f16 v[120:123], v[168:171], v[136:139], v[120:123]
	v_mfma_f32_16x16x32_f16 v[80:83], v[188:191], v[128:131], v[80:83]
	v_mfma_f32_16x16x32_f16 v[112:115], v[192:195], v[140:143], v[112:115]
	v_mfma_f32_16x16x32_f16 v[72:75], v[196:199], v[128:131], v[72:75]
	v_mfma_f32_16x16x32_f16 v[104:107], v[200:203], v[140:143], v[104:107]
	v_mfma_f32_16x16x32_f16 v[92:95], v[148:151], v[132:135], v[92:95]
	v_mfma_f32_16x16x32_f16 v[124:127], v[148:151], v[140:143], v[124:127]
	v_mfma_f32_16x16x32_f16 v[88:91], v[176:179], v[132:135], v[88:91]
	v_mfma_f32_16x16x32_f16 v[120:123], v[176:179], v[140:143], v[120:123]
	v_mfma_f32_16x16x32_f16 v[80:83], v[192:195], v[132:135], v[80:83]
	v_mfma_f32_16x16x32_f16 v[72:75], v[200:203], v[132:135], v[72:75]
	s_barrier
	s_mov_b32 m0, s13
	v_lshl_add_u64 v[166:167], v[164:165], 0, s[42:43]
	ds_read_b128 v[204:207], v152 offset:49152
	ds_read_b128 v[208:211], v152 offset:50176
	ds_read_b128 v[212:215], v152 offset:51200
	ds_read_b128 v[216:219], v152 offset:52224
	global_load_lds_dwordx4 v[166:167], off
	v_lshl_add_u64 v[164:165], v[164:165], 0, s[96:97]
	s_mov_b32 m0, s12
	s_nop 0
	global_load_lds_dwordx4 v[164:165], off
	s_barrier
	s_waitcnt lgkmcnt(0)
	s_waitcnt lgkmcnt(0)
	v_mfma_f32_16x16x32_f16 v[84:87], v[144:147], v[204:207], v[84:87]
	v_mfma_f32_16x16x32_f16 v[116:119], v[144:147], v[212:215], v[116:119]
	v_mfma_f32_16x16x32_f16 v[76:79], v[168:171], v[204:207], v[76:79]
	v_mfma_f32_16x16x32_f16 v[108:111], v[168:171], v[212:215], v[108:111]
	v_mfma_f32_16x16x32_f16 v[68:71], v[188:191], v[204:207], v[68:71]
	v_mfma_f32_16x16x32_f16 v[100:103], v[188:191], v[212:215], v[100:103]
	v_mfma_f32_16x16x32_f16 v[64:67], v[196:199], v[204:207], v[64:67]
	v_mfma_f32_16x16x32_f16 v[96:99], v[196:199], v[212:215], v[96:99]
	v_mfma_f32_16x16x32_f16 v[84:87], v[148:151], v[208:211], v[84:87]
	v_mfma_f32_16x16x32_f16 v[116:119], v[148:151], v[216:219], v[116:119]
	v_mfma_f32_16x16x32_f16 v[76:79], v[176:179], v[208:211], v[76:79]
	v_mfma_f32_16x16x32_f16 v[108:111], v[176:179], v[216:219], v[108:111]
	v_mfma_f32_16x16x32_f16 v[68:71], v[192:195], v[208:211], v[68:71]
	v_mfma_f32_16x16x32_f16 v[100:103], v[192:195], v[216:219], v[100:103]
	v_mfma_f32_16x16x32_f16 v[64:67], v[200:203], v[208:211], v[64:67]
	v_mfma_f32_16x16x32_f16 v[96:99], v[200:203], v[216:219], v[96:99]
	s_mov_b32 m0, s11
	v_lshl_add_u64 v[172:173], v[160:161], 0, s[42:43]
	s_mov_b64 s[12:13], 0x8180
	s_barrier
	ds_read_b128 v[144:147], v159 offset:49152
	ds_read_b128 v[148:151], v159 offset:50176
	ds_read_b128 v[164:167], v159 offset:51200
	ds_read_b128 v[168:171], v159 offset:52224
	ds_read_b128 v[176:179], v159 offset:53248
	ds_read_b128 v[186:189], v159 offset:54272
	ds_read_b128 v[190:193], v159 offset:55296
	ds_read_b128 v[194:197], v159 offset:56320
	global_load_lds_dwordx4 v[172:173], off
	v_lshl_add_u64 v[172:173], v[160:161], 0, s[12:13]
	s_mov_b32 m0, s10
	s_nop 0
	global_load_lds_dwordx4 v[172:173], off
	s_barrier
;   #define STAGE(P,BASE,LD,br,kt) do{ const HALF* _u=(BASE)+(long)(br)*(((&(LD))==&lda)?lda_u:(LD))+(long)(kt)*G_BK; \
;     for(int _i=0;_i<2;++_i){ \
;       __builtin_amdgcn_global_load_lds((const unsigned*)(_u+(long)_i*(((&(LD))==&lda)?stepa:stepb)+((&(LD))==&lda?oa0:ob0)), \
;         (unsigned*)((char*)(P)+t5*16+_i*8192),16,0,0);}}while(0)
;   #define LDA(dst,b,h) for(int m=0;m<4;++m)for(int k=0;k<2;++k) \
;     dst[m][k]=*reinterpret_cast<const h8*>(la+(((b)*2+(h))*16384+m*2048+k*1024))
;   #define LDB(dst,b,h) for(int n=0;n<2;++n)for(int k=0;k<2;++k) \
;     dst[n][k]=*reinterpret_cast<const h8*>(lb+(((b)*2+(h))*16384+n*2048+k*1024))
;   #define MMA(ai,bj,At,Bt_) do{__builtin_amdgcn_s_setprio(1); \
;     for(int m=0;m<4;++m)for(int n=0;n<2;++n)for(int k=0;k<2;++k) \
;       acc[ai][bj][m][n]=__builtin_amdgcn_mfma_f32_16x16x32_f16(At[m][k],Bt_[n][k],acc[ai][bj][m][n],0,0,0); \
;     __builtin_amdgcn_s_setprio(0);}while(0)
;   #define WAIT_V(n) asm volatile("s_waitcnt vmcnt(" #n ")":::"memory")
;   #define WAIT_L(n) asm volatile("s_waitcnt lgkmcnt(" #n ")":::"memory")
;   #define BAR __builtin_amdgcn_s_barrier()
;   #define SCHED __builtin_amdgcn_sched_barrier(0)
;     ...
;     BAR; WAIT_L(0); MMA(1,0,At,B0); BAR; SCHED;
;     STAGE(SB(1,1),Bt,ldb,G_HALF,t+3);
;     WAIT_V(6); BAR; MMA(1,1,At,B1); BAR;
;   }
;   { LDB(B0,0,0); LDA(At,0,0); STAGE(SA(1,1),A,lda,G_HALF,nt-1);
;     BAR; WAIT_L(0); MMA(0,0,At,B0); BAR;
;     LDB(B1,0,1); BAR; WAIT_L(0); MMA(0,1,At,B1); BAR;
	s_waitcnt lgkmcnt(0)
	s_waitcnt lgkmcnt(0)
	v_mfma_f32_16x16x32_f16 v[24:27], v[144:147], v[128:131], v[24:27]
	v_mfma_f32_16x16x32_f16 v[56:59], v[144:147], v[136:139], v[56:59]
	v_mfma_f32_16x16x32_f16 v[16:19], v[164:167], v[128:131], v[16:19]
	v_mfma_f32_16x16x32_f16 v[48:51], v[164:167], v[136:139], v[48:51]
	v_mfma_f32_16x16x32_f16 v[8:11], v[176:179], v[128:131], v[8:11]
	v_mfma_f32_16x16x32_f16 v[40:43], v[176:179], v[136:139], v[40:43]
	v_mfma_f32_16x16x32_f16 v[0:3], v[190:193], v[128:131], v[0:3]
	v_mfma_f32_16x16x32_f16 v[32:35], v[190:193], v[136:139], v[32:35]
	v_mfma_f32_16x16x32_f16 v[24:27], v[148:151], v[132:135], v[24:27]
	v_mfma_f32_16x16x32_f16 v[56:59], v[148:151], v[140:143], v[56:59]
	v_mfma_f32_16x16x32_f16 v[16:19], v[168:171], v[132:135], v[16:19]
	v_mfma_f32_16x16x32_f16 v[48:51], v[168:171], v[140:143], v[48:51]
	v_mfma_f32_16x16x32_f16 v[8:11], v[186:189], v[132:135], v[8:11]
	v_mfma_f32_16x16x32_f16 v[40:43], v[186:189], v[140:143], v[40:43]
	v_mfma_f32_16x16x32_f16 v[0:3], v[194:197], v[132:135], v[0:3]
	v_mfma_f32_16x16x32_f16 v[32:35], v[194:197], v[140:143], v[32:35]
	s_barrier
	s_mov_b32 m0, s7
	v_lshl_add_u64 v[128:129], v[162:163], 0, s[42:43]
	global_load_lds_dwordx4 v[128:129], off
	v_lshl_add_u64 v[128:129], v[162:163], 0, s[96:97]
	s_mov_b32 m0, s6
	s_nop 0
	global_load_lds_dwordx4 v[128:129], off
	s_waitcnt vmcnt(6)
	s_barrier
	v_mfma_f32_16x16x32_f16 v[28:31], v[144:147], v[204:207], v[28:31]
	v_mfma_f32_16x16x32_f16 v[60:63], v[144:147], v[212:215], v[60:63]
	v_mfma_f32_16x16x32_f16 v[20:23], v[164:167], v[204:207], v[20:23]
	v_mfma_f32_16x16x32_f16 v[52:55], v[164:167], v[212:215], v[52:55]
	v_mfma_f32_16x16x32_f16 v[12:15], v[176:179], v[204:207], v[12:15]
	v_mfma_f32_16x16x32_f16 v[44:47], v[176:179], v[212:215], v[44:47]
	v_mfma_f32_16x16x32_f16 v[4:7], v[190:193], v[204:207], v[4:7]
	v_mfma_f32_16x16x32_f16 v[36:39], v[190:193], v[212:215], v[36:39]
	v_mfma_f32_16x16x32_f16 v[28:31], v[148:151], v[208:211], v[28:31]
	v_mfma_f32_16x16x32_f16 v[60:63], v[148:151], v[216:219], v[60:63]
	v_mfma_f32_16x16x32_f16 v[20:23], v[168:171], v[208:211], v[20:23]
	v_mfma_f32_16x16x32_f16 v[52:55], v[168:171], v[216:219], v[52:55]
	v_mfma_f32_16x16x32_f16 v[12:15], v[186:189], v[208:211], v[12:15]
	v_mfma_f32_16x16x32_f16 v[44:47], v[186:189], v[216:219], v[44:47]
	v_mfma_f32_16x16x32_f16 v[4:7], v[194:197], v[208:211], v[4:7]
	v_mfma_f32_16x16x32_f16 v[36:39], v[194:197], v[216:219], v[36:39]
	s_mov_b64 s[6:7], 0x10180
	s_mov_b32 m0, s18
	v_lshl_add_u64 v[194:195], v[160:161], 0, s[6:7]
	s_mov_b64 s[6:7], 0x18180
	s_barrier
	ds_read_b128 v[128:131], v152
	ds_read_b128 v[132:135], v152 offset:1024
	ds_read_b128 v[136:139], v152 offset:2048
	ds_read_b128 v[140:143], v152 offset:3072
	ds_read_b128 v[144:147], v159
	ds_read_b128 v[148:151], v159 offset:1024
	ds_read_b128 v[162:165], v159 offset:2048
	ds_read_b128 v[166:169], v159 offset:3072
	ds_read_b128 v[170:173], v159 offset:4096
	ds_read_b128 v[176:179], v159 offset:5120
	ds_read_b128 v[186:189], v159 offset:6144
	ds_read_b128 v[190:193], v159 offset:7168
	global_load_lds_dwordx4 v[194:195], off
	v_lshl_add_u64 v[160:161], v[160:161], 0, s[6:7]
	s_mov_b32 m0, s17
	s_nop 0
	global_load_lds_dwordx4 v[160:161], off
	s_barrier
	s_waitcnt lgkmcnt(0)
	s_waitcnt lgkmcnt(0)
	v_mfma_f32_16x16x32_f16 v[112:115], v[170:173], v[136:139], v[112:115]
	v_mfma_f32_16x16x32_f16 v[104:107], v[186:189], v[136:139], v[104:107]
	v_mfma_f32_16x16x32_f16 v[92:95], v[144:147], v[128:131], v[92:95]
	v_mfma_f32_16x16x32_f16 v[124:127], v[144:147], v[136:139], v[124:127]
	v_mfma_f32_16x16x32_f16 v[88:91], v[162:165], v[128:131], v[88:91]
	v_mfma_f32_16x16x32_f16 v[120:123], v[162:165], v[136:139], v[120:123]
	v_mfma_f32_16x16x32_f16 v[80:83], v[170:173], v[128:131], v[80:83]
	v_mfma_f32_16x16x32_f16 v[112:115], v[176:179], v[140:143], v[112:115]
	v_mfma_f32_16x16x32_f16 v[72:75], v[186:189], v[128:131], v[72:75]
	v_mfma_f32_16x16x32_f16 v[104:107], v[190:193], v[140:143], v[104:107]
	v_mfma_f32_16x16x32_f16 v[92:95], v[148:151], v[132:135], v[92:95]
	v_mfma_f32_16x16x32_f16 v[124:127], v[148:151], v[140:143], v[124:127]
	v_mfma_f32_16x16x32_f16 v[88:91], v[166:169], v[132:135], v[88:91]
	v_mfma_f32_16x16x32_f16 v[120:123], v[166:169], v[140:143], v[120:123]
	v_mfma_f32_16x16x32_f16 v[80:83], v[176:179], v[132:135], v[80:83]
	v_mfma_f32_16x16x32_f16 v[72:75], v[190:193], v[132:135], v[72:75]
	s_barrier
	ds_read_b128 v[194:197], v152 offset:16384
	ds_read_b128 v[198:201], v152 offset:17408
	ds_read_b128 v[202:205], v152 offset:18432
	ds_read_b128 v[206:209], v152 offset:19456
	s_barrier
	s_waitcnt lgkmcnt(0)
	s_waitcnt lgkmcnt(0)
	v_mfma_f32_16x16x32_f16 v[68:71], v[170:173], v[194:197], v[68:71]
	v_mfma_f32_16x16x32_f16 v[84:87], v[144:147], v[194:197], v[84:87]
	v_mfma_f32_16x16x32_f16 v[116:119], v[144:147], v[202:205], v[116:119]
	v_mfma_f32_16x16x32_f16 v[76:79], v[162:165], v[194:197], v[76:79]
	v_mfma_f32_16x16x32_f16 v[108:111], v[162:165], v[202:205], v[108:111]
	v_mfma_f32_16x16x32_f16 v[144:147], v[176:179], v[198:201], v[68:71]
	v_mfma_f32_16x16x32_f16 v[68:71], v[170:173], v[202:205], v[100:103]
	v_mfma_f32_16x16x32_f16 v[64:67], v[186:189], v[194:197], v[64:67]
	v_mfma_f32_16x16x32_f16 v[84:87], v[148:151], v[198:201], v[84:87]
	v_mfma_f32_16x16x32_f16 v[116:119], v[148:151], v[206:209], v[116:119]
	v_mfma_f32_16x16x32_f16 v[76:79], v[166:169], v[198:201], v[76:79]
	v_mfma_f32_16x16x32_f16 v[108:111], v[166:169], v[206:209], v[108:111]
	v_mfma_f32_16x16x32_f16 v[100:103], v[176:179], v[206:209], v[68:71]
	v_mfma_f32_16x16x32_f16 v[148:151], v[190:193], v[198:201], v[64:67]
	v_mfma_f32_16x16x32_f16 v[64:67], v[186:189], v[202:205], v[96:99]
	v_mfma_f32_16x16x32_f16 v[160:163], v[190:193], v[206:209], v[64:67]
	s_barrier
;   #define LDA(dst,b,h) for(int m=0;m<4;++m)for(int k=0;k<2;++k) \
;     dst[m][k]=*reinterpret_cast<const h8*>(la+(((b)*2+(h))*16384+m*2048+k*1024))
;   #define LDB(dst,b,h) for(int n=0;n<2;++n)for(int k=0;k<2;++k) \
;     dst[n][k]=*reinterpret_cast<const h8*>(lb+(((b)*2+(h))*16384+n*2048+k*1024))
;   #define MMA(ai,bj,At,Bt_) do{__builtin_amdgcn_s_setprio(1); \
;     for(int m=0;m<4;++m)for(int n=0;n<2;++n)for(int k=0;k<2;++k) \
;       acc[ai][bj][m][n]=__builtin_amdgcn_mfma_f32_16x16x32_f16(At[m][k],Bt_[n][k],acc[ai][bj][m][n],0,0,0); \
;     __builtin_amdgcn_s_setprio(0);}while(0)
;   #define WAIT_V(n) asm volatile("s_waitcnt vmcnt(" #n ")":::"memory")
;   #define WAIT_L(n) asm volatile("s_waitcnt lgkmcnt(" #n ")":::"memory")
;   #define BAR __builtin_amdgcn_s_barrier()
;     ...
;     LDA(At,0,1); WAIT_V(4); BAR; WAIT_L(0); MMA(1,0,At,B0); MMA(1,1,At,B1); BAR; }
;   { LDB(B0,1,0); LDA(At,1,0); WAIT_V(2); BAR; WAIT_L(0); MMA(0,0,At,B0); BAR;
	s_nop 4
	ds_read_b128 v[64:67], v159 offset:16384
	ds_read_b128 v[68:71], v159 offset:17408
	ds_read_b128 v[96:99], v159 offset:18432
	ds_read_b128 v[164:167], v159 offset:19456
	ds_read_b128 v[168:171], v159 offset:20480
	ds_read_b128 v[176:179], v159 offset:21504
	ds_read_b128 v[186:189], v159 offset:22528
	ds_read_b128 v[190:193], v159 offset:23552
	s_waitcnt vmcnt(4)
	s_barrier
	s_waitcnt lgkmcnt(0)
	s_waitcnt lgkmcnt(0)
	v_mfma_f32_16x16x32_f16 v[24:27], v[64:67], v[128:131], v[24:27]
	v_mfma_f32_16x16x32_f16 v[0:3], v[186:189], v[128:131], v[0:3]
	v_mfma_f32_16x16x32_f16 v[210:213], v[68:71], v[132:135], v[24:27]
	v_mfma_f32_16x16x32_f16 v[24:27], v[64:67], v[136:139], v[56:59]
	v_mfma_f32_16x16x32_f16 v[16:19], v[96:99], v[128:131], v[16:19]
	v_mfma_f32_16x16x32_f16 v[8:11], v[168:171], v[128:131], v[8:11]
	v_mfma_f32_16x16x32_f16 v[128:131], v[190:193], v[132:135], v[0:3]
	v_mfma_f32_16x16x32_f16 v[0:3], v[186:189], v[136:139], v[32:35]
	v_mfma_f32_16x16x32_f16 v[56:59], v[68:71], v[140:143], v[24:27]
	v_mfma_f32_16x16x32_f16 v[214:217], v[164:167], v[132:135], v[16:19]
	v_mfma_f32_16x16x32_f16 v[16:19], v[96:99], v[136:139], v[48:51]
	v_mfma_f32_16x16x32_f16 v[222:225], v[176:179], v[132:135], v[8:11]
	v_mfma_f32_16x16x32_f16 v[8:11], v[168:171], v[136:139], v[40:43]
	v_mfma_f32_16x16x32_f16 v[132:135], v[190:193], v[140:143], v[0:3]
	v_mfma_f32_16x16x32_f16 v[218:221], v[164:167], v[140:143], v[16:19]
	v_mfma_f32_16x16x32_f16 v[226:229], v[176:179], v[140:143], v[8:11]
	v_mfma_f32_16x16x32_f16 v[0:3], v[64:67], v[194:197], v[28:31]
	v_mfma_f32_16x16x32_f16 v[136:139], v[68:71], v[198:201], v[0:3]
	v_mfma_f32_16x16x32_f16 v[0:3], v[64:67], v[202:205], v[60:63]
	v_mfma_f32_16x16x32_f16 v[140:143], v[68:71], v[206:209], v[0:3]
	v_mfma_f32_16x16x32_f16 v[0:3], v[96:99], v[194:197], v[20:23]
	v_mfma_f32_16x16x32_f16 v[230:233], v[164:167], v[198:201], v[0:3]
	v_mfma_f32_16x16x32_f16 v[0:3], v[96:99], v[202:205], v[52:55]
	v_mfma_f32_16x16x32_f16 v[164:167], v[164:167], v[206:209], v[0:3]
	v_mfma_f32_16x16x32_f16 v[0:3], v[168:171], v[194:197], v[12:15]
	v_mfma_f32_16x16x32_f16 v[234:237], v[176:179], v[198:201], v[0:3]
	v_mfma_f32_16x16x32_f16 v[0:3], v[168:171], v[202:205], v[44:47]
	v_mfma_f32_16x16x32_f16 v[168:171], v[176:179], v[206:209], v[0:3]
	v_mfma_f32_16x16x32_f16 v[0:3], v[186:189], v[194:197], v[4:7]
	v_mfma_f32_16x16x32_f16 v[176:179], v[190:193], v[198:201], v[0:3]
	v_mfma_f32_16x16x32_f16 v[0:3], v[186:189], v[202:205], v[36:39]
	v_mfma_f32_16x16x32_f16 v[186:189], v[190:193], v[206:209], v[0:3]
	s_barrier
	ds_read_b128 v[190:193], v152 offset:32768
	ds_read_b128 v[194:197], v152 offset:33792
	ds_read_b128 v[198:201], v152 offset:34816
	ds_read_b128 v[202:205], v152 offset:35840
	ds_read_b128 v[32:35], v159 offset:32768
	ds_read_b128 v[36:39], v159 offset:33792
	ds_read_b128 v[40:43], v159 offset:34816
	ds_read_b128 v[44:47], v159 offset:35840
	ds_read_b128 v[48:51], v159 offset:36864
	ds_read_b128 v[52:55], v159 offset:37888
	ds_read_b128 v[60:63], v159 offset:38912
	ds_read_b128 v[206:209], v159 offset:39936
	s_waitcnt vmcnt(2)
	s_barrier
	s_waitcnt lgkmcnt(0)
	s_waitcnt lgkmcnt(0)
	v_mfma_f32_16x16x32_f16 v[0:3], v[32:35], v[190:193], v[92:95]
	v_mfma_f32_16x16x32_f16 v[4:7], v[32:35], v[198:201], v[124:127]
	v_mfma_f32_16x16x32_f16 v[8:11], v[40:43], v[190:193], v[88:91]
	v_mfma_f32_16x16x32_f16 v[12:15], v[40:43], v[198:201], v[120:123]
	v_mfma_f32_16x16x32_f16 v[16:19], v[48:51], v[190:193], v[80:83]
	v_mfma_f32_16x16x32_f16 v[20:23], v[48:51], v[198:201], v[112:115]
	v_mfma_f32_16x16x32_f16 v[24:27], v[60:63], v[190:193], v[72:75]
	v_mfma_f32_16x16x32_f16 v[28:31], v[60:63], v[198:201], v[104:107]
	v_mfma_f32_16x16x32_f16 v[0:3], v[36:39], v[194:197], v[0:3]
	v_mfma_f32_16x16x32_f16 v[4:7], v[36:39], v[202:205], v[4:7]
	v_mfma_f32_16x16x32_f16 v[8:11], v[44:47], v[194:197], v[8:11]
	v_mfma_f32_16x16x32_f16 v[12:15], v[44:47], v[202:205], v[12:15]
	v_mfma_f32_16x16x32_f16 v[16:19], v[52:55], v[194:197], v[16:19]
	v_mfma_f32_16x16x32_f16 v[20:23], v[52:55], v[202:205], v[20:23]
	v_mfma_f32_16x16x32_f16 v[24:27], v[206:209], v[194:197], v[24:27]
	v_mfma_f32_16x16x32_f16 v[28:31], v[206:209], v[202:205], v[28:31]
	s_barrier
;   #define LDA(dst,b,h) for(int m=0;m<4;++m)for(int k=0;k<2;++k) \
;     dst[m][k]=*reinterpret_cast<const h8*>(la+(((b)*2+(h))*16384+m*2048+k*1024))
;   #define LDB(dst,b,h) for(int n=0;n<2;++n)for(int k=0;k<2;++k) \
;     dst[n][k]=*reinterpret_cast<const h8*>(lb+(((b)*2+(h))*16384+n*2048+k*1024))
;   #define MMA(ai,bj,At,Bt_) do{__builtin_amdgcn_s_setprio(1); \
;     for(int m=0;m<4;++m)for(int n=0;n<2;++n)for(int k=0;k<2;++k) \
;       acc[ai][bj][m][n]=__builtin_amdgcn_mfma_f32_16x16x32_f16(At[m][k],Bt_[n][k],acc[ai][bj][m][n],0,0,0); \
;     __builtin_amdgcn_s_setprio(0);}while(0)
;   #define WAIT_V(n) asm volatile("s_waitcnt vmcnt(" #n ")":::"memory")
;   #define WAIT_L(n) asm volatile("s_waitcnt lgkmcnt(" #n ")":::"memory")
;   #define BAR __builtin_amdgcn_s_barrier()
;     ...
;     LDB(B1,1,1); WAIT_V(0); BAR; WAIT_L(0); MMA(0,1,At,B1); BAR;
;     LDA(At,1,1); BAR; WAIT_L(0); MMA(1,0,At,B0); MMA(1,1,At,B1); BAR; }
;   if(wr==0)BAR;
	ds_read_b128 v[72:75], v152 offset:49152
	ds_read_b128 v[80:83], v152 offset:50176
	ds_read_b128 v[88:91], v152 offset:51200
	ds_read_b128 v[92:95], v152 offset:52224
	s_waitcnt vmcnt(0)
	s_barrier
	s_waitcnt lgkmcnt(0)
	s_waitcnt lgkmcnt(0)
	v_mfma_f32_16x16x32_f16 v[64:67], v[32:35], v[72:75], v[84:87]
	v_mfma_f32_16x16x32_f16 v[32:35], v[32:35], v[88:91], v[116:119]
	v_mfma_f32_16x16x32_f16 v[64:67], v[36:39], v[80:83], v[64:67]
	v_mfma_f32_16x16x32_f16 v[36:39], v[36:39], v[92:95], v[32:35]
	v_mfma_f32_16x16x32_f16 v[32:35], v[40:43], v[72:75], v[76:79]
	v_mfma_f32_16x16x32_f16 v[68:71], v[44:47], v[80:83], v[32:35]
	v_mfma_f32_16x16x32_f16 v[32:35], v[40:43], v[88:91], v[108:111]
	v_mfma_f32_16x16x32_f16 v[44:47], v[44:47], v[92:95], v[32:35]
	v_mfma_f32_16x16x32_f16 v[32:35], v[48:51], v[72:75], v[144:147]
	v_mfma_f32_16x16x32_f16 v[96:99], v[52:55], v[80:83], v[32:35]
	v_mfma_f32_16x16x32_f16 v[32:35], v[48:51], v[88:91], v[100:103]
	v_mfma_f32_16x16x32_f16 v[52:55], v[52:55], v[92:95], v[32:35]
	v_mfma_f32_16x16x32_f16 v[32:35], v[60:63], v[72:75], v[148:151]
	v_mfma_f32_16x16x32_f16 v[100:103], v[206:209], v[80:83], v[32:35]
	v_mfma_f32_16x16x32_f16 v[32:35], v[60:63], v[88:91], v[160:163]
	v_mfma_f32_16x16x32_f16 v[60:63], v[206:209], v[92:95], v[32:35]
	s_barrier
	ds_read_b128 v[116:119], v159 offset:49152
	ds_read_b128 v[120:123], v159 offset:50176
	ds_read_b128 v[124:127], v159 offset:51200
	ds_read_b128 v[144:147], v159 offset:52224
	ds_read_b128 v[148:151], v159 offset:53248
	ds_read_b128 v[160:163], v159 offset:54272
	ds_read_b128 v[206:209], v159 offset:55296
	ds_read_b128 v[238:241], v159 offset:56320
	s_barrier
	s_waitcnt lgkmcnt(0)
	s_waitcnt lgkmcnt(0)
	v_mfma_f32_16x16x32_f16 v[32:35], v[116:119], v[190:193], v[210:213]
	v_mfma_f32_16x16x32_f16 v[40:43], v[124:127], v[190:193], v[214:217]
	v_mfma_f32_16x16x32_f16 v[76:79], v[148:151], v[190:193], v[222:225]
	v_mfma_f32_16x16x32_f16 v[84:87], v[206:209], v[190:193], v[128:131]
	v_mfma_f32_16x16x32_f16 v[48:51], v[120:123], v[194:197], v[32:35]
	v_mfma_f32_16x16x32_f16 v[32:35], v[116:119], v[198:201], v[56:59]
	v_mfma_f32_16x16x32_f16 v[56:59], v[144:147], v[194:197], v[40:43]
	v_mfma_f32_16x16x32_f16 v[40:43], v[124:127], v[198:201], v[218:221]
	v_mfma_f32_16x16x32_f16 v[104:107], v[160:163], v[194:197], v[76:79]
	v_mfma_f32_16x16x32_f16 v[76:79], v[148:151], v[198:201], v[226:229]
	v_mfma_f32_16x16x32_f16 v[112:115], v[238:241], v[194:197], v[84:87]
	v_mfma_f32_16x16x32_f16 v[84:87], v[206:209], v[198:201], v[132:135]
	v_mfma_f32_16x16x32_f16 v[32:35], v[120:123], v[202:205], v[32:35]
	v_mfma_f32_16x16x32_f16 v[40:43], v[144:147], v[202:205], v[40:43]
	v_mfma_f32_16x16x32_f16 v[76:79], v[160:163], v[202:205], v[76:79]
	v_mfma_f32_16x16x32_f16 v[84:87], v[238:241], v[202:205], v[84:87]
	v_mfma_f32_16x16x32_f16 v[108:111], v[116:119], v[72:75], v[136:139]
	v_mfma_f32_16x16x32_f16 v[116:119], v[116:119], v[88:91], v[140:143]
	v_mfma_f32_16x16x32_f16 v[108:111], v[120:123], v[80:83], v[108:111]
	v_mfma_f32_16x16x32_f16 v[128:131], v[120:123], v[92:95], v[116:119]
	v_mfma_f32_16x16x32_f16 v[120:123], v[124:127], v[88:91], v[164:167]
	v_mfma_f32_16x16x32_f16 v[116:119], v[124:127], v[72:75], v[230:233]
	v_mfma_f32_16x16x32_f16 v[132:135], v[144:147], v[92:95], v[120:123]
	v_mfma_f32_16x16x32_f16 v[120:123], v[148:151], v[72:75], v[234:237]
	v_mfma_f32_16x16x32_f16 v[72:75], v[206:209], v[72:75], v[176:179]
	v_mfma_f32_16x16x32_f16 v[116:119], v[144:147], v[80:83], v[116:119]
	v_mfma_f32_16x16x32_f16 v[144:147], v[160:163], v[80:83], v[120:123]
	v_mfma_f32_16x16x32_f16 v[120:123], v[148:151], v[88:91], v[168:171]
	v_mfma_f32_16x16x32_f16 v[148:151], v[238:241], v[80:83], v[72:75]
	v_mfma_f32_16x16x32_f16 v[72:75], v[206:209], v[88:91], v[186:189]
	v_mfma_f32_16x16x32_f16 v[136:139], v[160:163], v[92:95], v[120:123]
	v_mfma_f32_16x16x32_f16 v[140:143], v[238:241], v[92:95], v[72:75]
	s_movk_i32 s6, 0x100
	v_cmp_gt_u32_e32 vcc, s6, v157
	s_barrier
	s_and_saveexec_b64 s[6:7], vcc
	s_cbranch_execz .LBB0_485
	s_barrier

;   #define STAGE(P,BASE,LD,br,kt) do{ const HALF* _u=(BASE)+(long)(br)*(((&(LD))==&lda)?lda_u:(LD))+(long)(kt)*G_BK; \
;     for(int _i=0;_i<2;++_i){ \
;       __builtin_amdgcn_global_load_lds((const unsigned*)(_u+(long)_i*(((&(LD))==&lda)?stepa:stepb)+((&(LD))==&lda?oa0:ob0)), \
;         (unsigned*)((char*)(P)+t5*16+_i*8192),16,0,0);}}while(0)
;   #define WAIT_V(n) asm volatile("s_waitcnt vmcnt(" #n ")":::"memory")
;   #define BAR __builtin_amdgcn_s_barrier()
; #define FOR_AI _Pragma("unroll") for (int ai = 0; ai < 2; ++ai)
; #define FOR_BJ _Pragma("unroll") for (int bj = 0; bj < 2; ++bj)
; #define FOR_M4 _Pragma("unroll") for (int m = 0; m < 4; ++m)
; #define FOR_NN _Pragma("unroll") for (int n = 0; n < 2; ++n)
;     ...
;   const int _ob=fr*64+fq*16, _sw=_ob^(((_ob>>9)&1)<<5);
;   const char* la=(const char*)shm+wr*8192+_sw;
;   const char* lb=(const char*)shm+65536+wc*4096+_sw;
;   unsigned oa0, ob0;
;   const int stepa = n2 ? 1024 : 64 * lda, stepb = 64 * ldb;
;   const int lda_u = n2 ? 16 : lda;
;   {int _b=t5*16;int _r,_c;g_stage_rc(_b,_r,_c);
;     oa0=n2 ? (unsigned)((n2*(_r&63)+(_r>>6))*1024+_c) : (unsigned)(_r*lda+_c); ob0=(unsigned)(_r*ldb+_c);}
;   STAGE(SB(0,0),Bt,ldb,0,0); STAGE(SA(0,0),A,lda,0,0);
;   STAGE(SB(0,1),Bt,ldb,G_HALF,0); STAGE(SA(0,1),A,lda,G_HALF,0);
;   if(wr==1)BAR;
;   WAIT_V(4); BAR;
;   STAGE(SB(1,0),Bt,ldb,0,1); STAGE(SA(1,0),A,lda,0,1); STAGE(SB(1,1),Bt,ldb,G_HALF,1);
;   WAIT_V(6); BAR;
; __device__ void job_retout_g(const P& p, int l, int job, HALF* sm) {
;     ...
;     FOR_BJ FOR_NN {
;       const int i = bj * 128 + wc * 32 + n * 16 + fr;
;       const float sc = expf(lgb * (float)(256 - i));
;       FOR_AI FOR_M4 { acc[ai][bj][m][n] *= sc; }
;     }
;   }
;   __syncthreads();
;   {
;     const HALF* Pp = (const HALF*)(ws + G_PP) + ((size_t)(cgi * 256) * 4 + h) * 256;
;     const HALF* VT = (const HALF*)(ws + G_VT) + (size_t)(h * 512 + nt2 * 256) * 8192 + cgi * 256;
;     gemm256(acc, VT, 8192, Pp, 1024, 256, sm);
.LBB0_487:
	s_or_b64 exec, exec, s[6:7]
	v_pk_mul_f32 v[74:75], v[26:27], v[120:121] op_sel_hi:[1,0]
	v_pk_mul_f32 v[26:27], v[50:51], v[120:121] op_sel_hi:[1,0]
	v_pk_mul_f32 v[50:51], v[42:43], v[168:169] op_sel_hi:[1,0]
	v_pk_mul_f32 v[42:43], v[78:79], v[168:169] op_sel_hi:[1,0]
	v_pk_mul_f32 v[78:79], v[70:71], v[158:159] op_sel_hi:[1,0]
	v_pk_mul_f32 v[70:71], v[98:99], v[158:159] op_sel_hi:[1,0]
	v_pk_mul_f32 v[98:99], v[62:63], v[152:153] op_sel_hi:[1,0]
	v_pk_mul_f32 v[62:63], v[130:131], v[152:153] op_sel_hi:[1,0]
	v_lshlrev_b32_e32 v130, 6, v157
	v_lshlrev_b32_e32 v131, 2, v157
	v_pk_mul_f32 v[72:73], v[24:25], v[120:121] op_sel_hi:[1,0]
	v_pk_mul_f32 v[24:25], v[48:49], v[120:121] op_sel_hi:[1,0]
	v_pk_mul_f32 v[48:49], v[40:41], v[168:169] op_sel_hi:[1,0]
	v_pk_mul_f32 v[40:41], v[76:77], v[168:169] op_sel_hi:[1,0]
	v_pk_mul_f32 v[76:77], v[68:69], v[158:159] op_sel_hi:[1,0]
	v_pk_mul_f32 v[68:69], v[96:97], v[158:159] op_sel_hi:[1,0]
	v_pk_mul_f32 v[96:97], v[60:61], v[152:153] op_sel_hi:[1,0]
	v_pk_mul_f32 v[60:61], v[128:129], v[152:153] op_sel_hi:[1,0]
	v_and_b32_e32 v128, 48, v157
	v_and_b32_e32 v129, 0x3c0, v130
	v_and_b32_e32 v131, 32, v131
	v_bitop3_b32 v128, v129, v131, v128 bitop3:0x36
	v_add_u32_e32 v131, s29, v191
	v_pk_mul_f32 v[80:81], v[16:17], v[120:121] op_sel_hi:[1,0]
	v_readfirstlane_b32 s10, v131
	v_add_u32_e32 v131, 0x2000, v131
	v_pk_mul_f32 v[16:17], v[56:57], v[120:121] op_sel_hi:[1,0]
	v_pk_mul_f32 v[56:57], v[32:33], v[168:169] op_sel_hi:[1,0]
	v_pk_mul_f32 v[32:33], v[84:85], v[168:169] op_sel_hi:[1,0]
	v_pk_mul_f32 v[84:85], v[64:65], v[158:159] op_sel_hi:[1,0]
	v_pk_mul_f32 v[64:65], v[100:101], v[158:159] op_sel_hi:[1,0]
	v_pk_mul_f32 v[100:101], v[52:53], v[152:153] op_sel_hi:[1,0]
	v_pk_mul_f32 v[52:53], v[132:133], v[152:153] op_sel_hi:[1,0]
	v_lshl_add_u64 v[132:133], v[164:165], 0, s[84:85]
	s_mov_b32 m0, s10
	s_mov_b64 s[6:7], 0x20080
	v_readfirstlane_b32 s9, v131
	v_add_u32_e32 v131, 0x8000, v187
	s_waitcnt vmcnt(4)
	s_barrier
	global_load_lds_dwordx4 v[132:133], off
	v_lshl_add_u64 v[132:133], v[164:165], 0, s[6:7]
	s_mov_b32 m0, s9
	v_readfirstlane_b32 s8, v131
	v_add_u32_e32 v131, 0xa000, v187
	global_load_lds_dwordx4 v[132:133], off
	v_lshl_add_u64 v[132:133], v[160:161], 0, s[84:85]
	s_mov_b32 m0, s8
	s_mov_b64 s[18:19], 0x100080
	v_readfirstlane_b32 s7, v131
	v_add_u32_e32 v131, s62, v191
	global_load_lds_dwordx4 v[132:133], off
	v_lshl_add_u64 v[132:133], v[160:161], 0, s[18:19]
	s_mov_b32 m0, s7
	v_readfirstlane_b32 s6, v131
	v_add_u32_e32 v131, 0x2000, v131
	global_load_lds_dwordx4 v[132:133], off
	v_lshl_add_u64 v[132:133], v[164:165], 0, s[88:89]
	s_mov_b32 m0, s6
	v_readfirstlane_b32 s1, v131
	global_load_lds_dwordx4 v[132:133], off
	v_lshl_add_u64 v[132:133], v[164:165], 0, s[90:91]
	s_mov_b32 m0, s1
	v_and_b32_e32 v130, 0x3000, v130
	global_load_lds_dwordx4 v[132:133], off
	v_pk_mul_f32 v[94:95], v[2:3], v[120:121] op_sel_hi:[1,0]
	v_pk_mul_f32 v[92:93], v[0:1], v[120:121] op_sel_hi:[1,0]
	v_pk_mul_f32 v[90:91], v[10:11], v[120:121] op_sel_hi:[1,0]
	v_pk_mul_f32 v[88:89], v[8:9], v[120:121] op_sel_hi:[1,0]
	v_pk_mul_f32 v[82:83], v[18:19], v[120:121] op_sel_hi:[1,0]
	v_pk_mul_f32 v[18:19], v[58:59], v[120:121] op_sel_hi:[1,0]
	v_pk_mul_f32 v[10:11], v[106:107], v[120:121] op_sel_hi:[1,0]
	v_pk_mul_f32 v[8:9], v[104:105], v[120:121] op_sel_hi:[1,0]
	v_pk_mul_f32 v[2:3], v[114:115], v[120:121] op_sel_hi:[1,0]
	v_pk_mul_f32 v[0:1], v[112:113], v[120:121] op_sel_hi:[1,0]
	v_pk_mul_f32 v[114:115], v[22:23], v[168:169] op_sel_hi:[1,0]
	v_pk_mul_f32 v[112:113], v[20:21], v[168:169] op_sel_hi:[1,0]
	v_pk_mul_f32 v[106:107], v[30:31], v[168:169] op_sel_hi:[1,0]
	v_pk_mul_f32 v[104:105], v[28:29], v[168:169] op_sel_hi:[1,0]
	v_pk_mul_f32 v[58:59], v[34:35], v[168:169] op_sel_hi:[1,0]
	v_pk_mul_f32 v[34:35], v[86:87], v[168:169] op_sel_hi:[1,0]
	v_pk_mul_f32 v[86:87], v[66:67], v[158:159] op_sel_hi:[1,0]
	v_pk_mul_f32 v[66:67], v[102:103], v[158:159] op_sel_hi:[1,0]
	v_pk_mul_f32 v[30:31], v[110:111], v[158:159] op_sel_hi:[1,0]
	v_pk_mul_f32 v[28:29], v[108:109], v[158:159] op_sel_hi:[1,0]
	v_pk_mul_f32 v[22:23], v[118:119], v[158:159] op_sel_hi:[1,0]
	v_pk_mul_f32 v[20:21], v[116:117], v[158:159] op_sel_hi:[1,0]
	v_pk_mul_f32 v[118:119], v[38:39], v[152:153] op_sel_hi:[1,0]
	v_pk_mul_f32 v[116:117], v[36:37], v[152:153] op_sel_hi:[1,0]
	v_pk_mul_f32 v[110:111], v[46:47], v[152:153] op_sel_hi:[1,0]
	v_pk_mul_f32 v[108:109], v[44:45], v[152:153] op_sel_hi:[1,0]
	v_pk_mul_f32 v[102:103], v[54:55], v[152:153] op_sel_hi:[1,0]
	v_pk_mul_f32 v[54:55], v[134:135], v[152:153] op_sel_hi:[1,0]
	v_pk_mul_f32 v[46:47], v[138:139], v[152:153] op_sel_hi:[1,0]
	v_pk_mul_f32 v[44:45], v[136:137], v[152:153] op_sel_hi:[1,0]
	v_pk_mul_f32 v[38:39], v[142:143], v[152:153] op_sel_hi:[1,0]
	v_pk_mul_f32 v[36:37], v[140:141], v[152:153] op_sel_hi:[1,0]
	v_lshlrev_b32_e32 v129, 13, v192
	v_add3_u32 v152, s95, v130, v128
	s_waitcnt vmcnt(6)
	s_barrier
;   #define STAGE(P,BASE,LD,br,kt) do{ const HALF* _u=(BASE)+(long)(br)*(((&(LD))==&lda)?lda_u:(LD))+(long)(kt)*G_BK; \
;     for(int _i=0;_i<2;++_i){ \
;       __builtin_amdgcn_global_load_lds((const unsigned*)(_u+(long)_i*(((&(LD))==&lda)?stepa:stepb)+((&(LD))==&lda?oa0:ob0)), \
;         (unsigned*)((char*)(P)+t5*16+_i*8192),16,0,0);}}while(0)
;   #define LDA(dst,b,h) for(int m=0;m<4;++m)for(int k=0;k<2;++k) \
;     dst[m][k]=*reinterpret_cast<const h8*>(la+(((b)*2+(h))*16384+m*2048+k*1024))
;   #define LDB(dst,b,h) for(int n=0;n<2;++n)for(int k=0;k<2;++k) \
;     dst[n][k]=*reinterpret_cast<const h8*>(lb+(((b)*2+(h))*16384+n*2048+k*1024))
;   #define MMA(ai,bj,At,Bt_) do{__builtin_amdgcn_s_setprio(1); \
;     for(int m=0;m<4;++m)for(int n=0;n<2;++n)for(int k=0;k<2;++k) \
;       acc[ai][bj][m][n]=__builtin_amdgcn_mfma_f32_16x16x32_f16(At[m][k],Bt_[n][k],acc[ai][bj][m][n],0,0,0); \
;     __builtin_amdgcn_s_setprio(0);}while(0)
;   #define WAIT_L(n) asm volatile("s_waitcnt lgkmcnt(" #n ")":::"memory")
;   #define BAR __builtin_amdgcn_s_barrier()
;   #define SCHED __builtin_amdgcn_sched_barrier(0)
;     ...
;     LDB(B0,0,0); SCHED; LDA(At,0,0); STAGE(SA(1,1),A,lda,G_HALF,t+1);
;     WAIT_L(8); BAR; WAIT_L(0); MMA(0,0,At,B0); BAR; SCHED;
;     LDB(B1,0,1); STAGE(SB(0,0),Bt,ldb,0,t+2);
;     BAR; WAIT_L(0); MMA(0,1,At,B1); BAR;
;     LDA(At,0,1); STAGE(SA(0,0),A,lda,0,t+2);
;     BAR; WAIT_L(0); MMA(1,0,At,B0); BAR; SCHED;
	v_add3_u32 v228, 0, v129, v128
	ds_read_b128 v[128:131], v152
	ds_read_b128 v[132:135], v152 offset:1024
	ds_read_b128 v[136:139], v152 offset:2048
	ds_read_b128 v[140:143], v152 offset:3072
	v_pk_mul_f32 v[126:127], v[6:7], v[168:169] op_sel_hi:[1,0]
	v_pk_mul_f32 v[124:125], v[4:5], v[168:169] op_sel_hi:[1,0]
	v_pk_mul_f32 v[122:123], v[14:15], v[168:169] op_sel_hi:[1,0]
	v_pk_mul_f32 v[120:121], v[12:13], v[168:169] op_sel_hi:[1,0]
	v_pk_mul_f32 v[14:15], v[146:147], v[158:159] op_sel_hi:[1,0]
	v_pk_mul_f32 v[12:13], v[144:145], v[158:159] op_sel_hi:[1,0]
	v_pk_mul_f32 v[6:7], v[150:151], v[158:159] op_sel_hi:[1,0]
	v_pk_mul_f32 v[4:5], v[148:149], v[158:159] op_sel_hi:[1,0]
	v_add_u32_e32 v158, 0xc000, v187
	v_lshl_add_u64 v[168:169], v[166:167], 0, s[84:85]
	v_readfirstlane_b32 s12, v158
	v_add_u32_e32 v158, 0xe000, v187
	s_mov_b32 m0, s12
	v_readfirstlane_b32 s11, v158
	ds_read_b128 v[144:147], v228
	ds_read_b128 v[148:151], v228 offset:1024
	ds_read_b128 v[176:179], v228 offset:2048
	ds_read_b128 v[192:195], v228 offset:3072
	ds_read_b128 v[196:199], v228 offset:4096
	ds_read_b128 v[200:203], v228 offset:5120
	ds_read_b128 v[204:207], v228 offset:6144
	ds_read_b128 v[208:211], v228 offset:7168
	global_load_lds_dwordx4 v[168:169], off
	v_lshl_add_u64 v[168:169], v[166:167], 0, s[18:19]
	s_mov_b32 m0, s11
	s_nop 0
	global_load_lds_dwordx4 v[168:169], off
	s_waitcnt lgkmcnt(8)
	s_barrier
	s_waitcnt lgkmcnt(0)
	s_waitcnt lgkmcnt(0)
	v_mfma_f32_16x16x32_f16 v[92:95], v[144:147], v[128:131], v[92:95]
	v_mfma_f32_16x16x32_f16 v[124:127], v[144:147], v[136:139], v[124:127]
	v_mfma_f32_16x16x32_f16 v[88:91], v[176:179], v[128:131], v[88:91]
	v_mfma_f32_16x16x32_f16 v[120:123], v[176:179], v[136:139], v[120:123]
	v_mfma_f32_16x16x32_f16 v[80:83], v[196:199], v[128:131], v[80:83]
	v_mfma_f32_16x16x32_f16 v[112:115], v[196:199], v[136:139], v[112:115]
	v_mfma_f32_16x16x32_f16 v[72:75], v[204:207], v[128:131], v[72:75]
	v_mfma_f32_16x16x32_f16 v[104:107], v[204:207], v[136:139], v[104:107]
	v_mfma_f32_16x16x32_f16 v[92:95], v[148:151], v[132:135], v[92:95]
	v_mfma_f32_16x16x32_f16 v[124:127], v[148:151], v[140:143], v[124:127]
	v_mfma_f32_16x16x32_f16 v[88:91], v[192:195], v[132:135], v[88:91]
	v_mfma_f32_16x16x32_f16 v[120:123], v[192:195], v[140:143], v[120:123]
	v_mfma_f32_16x16x32_f16 v[80:83], v[200:203], v[132:135], v[80:83]
	v_mfma_f32_16x16x32_f16 v[112:115], v[200:203], v[140:143], v[112:115]
	v_mfma_f32_16x16x32_f16 v[72:75], v[208:211], v[132:135], v[72:75]
	v_mfma_f32_16x16x32_f16 v[104:107], v[208:211], v[140:143], v[104:107]
	s_barrier
	v_readfirstlane_b32 s13, v189
	v_lshl_add_u64 v[168:169], v[164:165], 0, s[92:93]
	s_mov_b32 m0, s13
	v_readfirstlane_b32 s13, v190
	ds_read_b128 v[212:215], v152 offset:16384
	ds_read_b128 v[216:219], v152 offset:17408
	ds_read_b128 v[220:223], v152 offset:18432
	ds_read_b128 v[224:227], v152 offset:19456
	global_load_lds_dwordx4 v[168:169], off
	v_lshl_add_u64 v[168:169], v[164:165], 0, s[66:67]
	s_mov_b32 m0, s13
	s_nop 0
	global_load_lds_dwordx4 v[168:169], off
	s_barrier
	s_waitcnt lgkmcnt(0)
	s_waitcnt lgkmcnt(0)
	v_mfma_f32_16x16x32_f16 v[84:87], v[144:147], v[212:215], v[84:87]
	v_mfma_f32_16x16x32_f16 v[116:119], v[144:147], v[220:223], v[116:119]
	v_mfma_f32_16x16x32_f16 v[76:79], v[176:179], v[212:215], v[76:79]
	v_mfma_f32_16x16x32_f16 v[108:111], v[176:179], v[220:223], v[108:111]
	v_mfma_f32_16x16x32_f16 v[68:71], v[196:199], v[212:215], v[68:71]
	v_mfma_f32_16x16x32_f16 v[100:103], v[196:199], v[220:223], v[100:103]
	v_mfma_f32_16x16x32_f16 v[64:67], v[204:207], v[212:215], v[64:67]
	v_mfma_f32_16x16x32_f16 v[96:99], v[204:207], v[220:223], v[96:99]
	v_mfma_f32_16x16x32_f16 v[84:87], v[148:151], v[216:219], v[84:87]
	v_mfma_f32_16x16x32_f16 v[116:119], v[148:151], v[224:227], v[116:119]
	v_mfma_f32_16x16x32_f16 v[76:79], v[192:195], v[216:219], v[76:79]
	v_mfma_f32_16x16x32_f16 v[108:111], v[192:195], v[224:227], v[108:111]
	v_mfma_f32_16x16x32_f16 v[68:71], v[200:203], v[216:219], v[68:71]
	v_mfma_f32_16x16x32_f16 v[100:103], v[200:203], v[224:227], v[100:103]
	v_mfma_f32_16x16x32_f16 v[64:67], v[208:211], v[216:219], v[64:67]
	v_mfma_f32_16x16x32_f16 v[96:99], v[208:211], v[224:227], v[96:99]
	v_readfirstlane_b32 s13, v187
	v_lshl_add_u64 v[168:169], v[160:161], 0, s[92:93]
	s_mov_b32 m0, s13
	s_mov_b64 s[18:19], 0x100100
	v_readfirstlane_b32 s13, v188
	s_barrier
	ds_read_b128 v[144:147], v228 offset:16384
	ds_read_b128 v[148:151], v228 offset:17408
	ds_read_b128 v[176:179], v228 offset:18432
	ds_read_b128 v[190:193], v228 offset:19456
	ds_read_b128 v[194:197], v228 offset:20480
	ds_read_b128 v[198:201], v228 offset:21504
	ds_read_b128 v[202:205], v228 offset:22528
	ds_read_b128 v[206:209], v228 offset:23552
	global_load_lds_dwordx4 v[168:169], off
	v_lshl_add_u64 v[168:169], v[160:161], 0, s[18:19]
	s_mov_b32 m0, s13
	s_nop 0
	global_load_lds_dwordx4 v[168:169], off
	s_barrier
	s_waitcnt lgkmcnt(0)
	s_waitcnt lgkmcnt(0)
	v_mfma_f32_16x16x32_f16 v[24:27], v[144:147], v[128:131], v[24:27]
	v_mfma_f32_16x16x32_f16 v[56:59], v[144:147], v[136:139], v[56:59]
	v_mfma_f32_16x16x32_f16 v[16:19], v[176:179], v[128:131], v[16:19]
	v_mfma_f32_16x16x32_f16 v[48:51], v[176:179], v[136:139], v[48:51]
	v_mfma_f32_16x16x32_f16 v[8:11], v[194:197], v[128:131], v[8:11]
	v_mfma_f32_16x16x32_f16 v[40:43], v[194:197], v[136:139], v[40:43]
	v_mfma_f32_16x16x32_f16 v[0:3], v[202:205], v[128:131], v[0:3]
	v_mfma_f32_16x16x32_f16 v[32:35], v[202:205], v[136:139], v[32:35]
	v_mfma_f32_16x16x32_f16 v[24:27], v[148:151], v[132:135], v[24:27]
	v_mfma_f32_16x16x32_f16 v[56:59], v[148:151], v[140:143], v[56:59]
	v_mfma_f32_16x16x32_f16 v[16:19], v[190:193], v[132:135], v[16:19]
	v_mfma_f32_16x16x32_f16 v[48:51], v[190:193], v[140:143], v[48:51]
	v_mfma_f32_16x16x32_f16 v[8:11], v[198:201], v[132:135], v[8:11]
	v_mfma_f32_16x16x32_f16 v[40:43], v[198:201], v[140:143], v[40:43]
	v_mfma_f32_16x16x32_f16 v[0:3], v[206:209], v[132:135], v[0:3]
	v_mfma_f32_16x16x32_f16 v[32:35], v[206:209], v[140:143], v[32:35]
	s_barrier
;   #define STAGE(P,BASE,LD,br,kt) do{ const HALF* _u=(BASE)+(long)(br)*(((&(LD))==&lda)?lda_u:(LD))+(long)(kt)*G_BK; \
;     for(int _i=0;_i<2;++_i){ \
;       __builtin_amdgcn_global_load_lds((const unsigned*)(_u+(long)_i*(((&(LD))==&lda)?stepa:stepb)+((&(LD))==&lda?oa0:ob0)), \
;         (unsigned*)((char*)(P)+t5*16+_i*8192),16,0,0);}}while(0)
;   #define LDA(dst,b,h) for(int m=0;m<4;++m)for(int k=0;k<2;++k) \
;     dst[m][k]=*reinterpret_cast<const h8*>(la+(((b)*2+(h))*16384+m*2048+k*1024))
;   #define LDB(dst,b,h) for(int n=0;n<2;++n)for(int k=0;k<2;++k) \
;     dst[n][k]=*reinterpret_cast<const h8*>(lb+(((b)*2+(h))*16384+n*2048+k*1024))
;   #define MMA(ai,bj,At,Bt_) do{__builtin_amdgcn_s_setprio(1); \
;     for(int m=0;m<4;++m)for(int n=0;n<2;++n)for(int k=0;k<2;++k) \
;       acc[ai][bj][m][n]=__builtin_amdgcn_mfma_f32_16x16x32_f16(At[m][k],Bt_[n][k],acc[ai][bj][m][n],0,0,0); \
;     __builtin_amdgcn_s_setprio(0);}while(0)
;   #define WAIT_V(n) asm volatile("s_waitcnt vmcnt(" #n ")":::"memory")
;   #define WAIT_L(n) asm volatile("s_waitcnt lgkmcnt(" #n ")":::"memory")
;   #define BAR __builtin_amdgcn_s_barrier()
;   #define SCHED __builtin_amdgcn_sched_barrier(0)
;     ...
;     STAGE(SB(0,1),Bt,ldb,G_HALF,t+2);
;     WAIT_V(6); BAR; MMA(1,1,At,B1); BAR;
;     LDB(B0,1,0); SCHED; LDA(At,1,0); STAGE(SA(0,1),A,lda,G_HALF,t+2);
;     WAIT_L(8); BAR; WAIT_L(0); MMA(0,0,At,B0); BAR; SCHED;
;     LDB(B1,1,1); STAGE(SB(1,0),Bt,ldb,0,t+3);
;     BAR; WAIT_L(0); MMA(0,1,At,B1); BAR;
;     LDA(At,1,1); STAGE(SA(1,0),A,lda,0,t+3);
	v_readfirstlane_b32 s13, v172
	v_lshl_add_u64 v[128:129], v[162:163], 0, s[92:93]
	s_mov_b32 m0, s13
	v_readfirstlane_b32 s13, v186
	global_load_lds_dwordx4 v[128:129], off
	v_lshl_add_u64 v[128:129], v[162:163], 0, s[66:67]
	s_mov_b32 m0, s13
	s_nop 0
	global_load_lds_dwordx4 v[128:129], off
	s_waitcnt vmcnt(6)
	s_barrier
	v_mfma_f32_16x16x32_f16 v[28:31], v[144:147], v[212:215], v[28:31]
	v_mfma_f32_16x16x32_f16 v[60:63], v[144:147], v[220:223], v[60:63]
	v_mfma_f32_16x16x32_f16 v[20:23], v[176:179], v[212:215], v[20:23]
	v_mfma_f32_16x16x32_f16 v[52:55], v[176:179], v[220:223], v[52:55]
	v_mfma_f32_16x16x32_f16 v[12:15], v[194:197], v[212:215], v[12:15]
	v_mfma_f32_16x16x32_f16 v[44:47], v[194:197], v[220:223], v[44:47]
	v_mfma_f32_16x16x32_f16 v[4:7], v[202:205], v[212:215], v[4:7]
	v_mfma_f32_16x16x32_f16 v[36:39], v[202:205], v[220:223], v[36:39]
	v_mfma_f32_16x16x32_f16 v[28:31], v[148:151], v[216:219], v[28:31]
	v_mfma_f32_16x16x32_f16 v[60:63], v[148:151], v[224:227], v[60:63]
	v_mfma_f32_16x16x32_f16 v[20:23], v[190:193], v[216:219], v[20:23]
	v_mfma_f32_16x16x32_f16 v[52:55], v[190:193], v[224:227], v[52:55]
	v_mfma_f32_16x16x32_f16 v[12:15], v[198:201], v[216:219], v[12:15]
	v_mfma_f32_16x16x32_f16 v[44:47], v[198:201], v[224:227], v[44:47]
	v_mfma_f32_16x16x32_f16 v[4:7], v[206:209], v[216:219], v[4:7]
	v_mfma_f32_16x16x32_f16 v[36:39], v[206:209], v[224:227], v[36:39]
	s_barrier
	ds_read_b128 v[128:131], v152 offset:32768
	ds_read_b128 v[132:135], v152 offset:33792
	ds_read_b128 v[136:139], v152 offset:34816
	ds_read_b128 v[140:143], v152 offset:35840
	v_readfirstlane_b32 s13, v159
	v_lshl_add_u64 v[168:169], v[166:167], 0, s[92:93]
	s_mov_b32 m0, s13
	v_readfirstlane_b32 s13, v170
	ds_read_b128 v[144:147], v228 offset:32768
	ds_read_b128 v[148:151], v228 offset:33792
	ds_read_b128 v[176:179], v228 offset:34816
	ds_read_b128 v[186:189], v228 offset:35840
	ds_read_b128 v[190:193], v228 offset:36864
	ds_read_b128 v[194:197], v228 offset:37888
	ds_read_b128 v[198:201], v228 offset:38912
	ds_read_b128 v[202:205], v228 offset:39936
	global_load_lds_dwordx4 v[168:169], off
	v_lshl_add_u64 v[158:159], v[166:167], 0, s[18:19]
	s_mov_b32 m0, s13
	s_nop 0
	global_load_lds_dwordx4 v[158:159], off
	s_waitcnt lgkmcnt(8)
	s_barrier
	s_waitcnt lgkmcnt(0)
	s_waitcnt lgkmcnt(0)
	v_mfma_f32_16x16x32_f16 v[92:95], v[144:147], v[128:131], v[92:95]
	v_mfma_f32_16x16x32_f16 v[124:127], v[144:147], v[136:139], v[124:127]
	v_mfma_f32_16x16x32_f16 v[88:91], v[176:179], v[128:131], v[88:91]
	v_mfma_f32_16x16x32_f16 v[120:123], v[176:179], v[136:139], v[120:123]
	v_mfma_f32_16x16x32_f16 v[80:83], v[190:193], v[128:131], v[80:83]
	v_mfma_f32_16x16x32_f16 v[112:115], v[190:193], v[136:139], v[112:115]
	v_mfma_f32_16x16x32_f16 v[72:75], v[198:201], v[128:131], v[72:75]
	v_mfma_f32_16x16x32_f16 v[104:107], v[198:201], v[136:139], v[104:107]
	v_mfma_f32_16x16x32_f16 v[92:95], v[148:151], v[132:135], v[92:95]
	v_mfma_f32_16x16x32_f16 v[124:127], v[148:151], v[140:143], v[124:127]
	v_mfma_f32_16x16x32_f16 v[88:91], v[186:189], v[132:135], v[88:91]
	v_mfma_f32_16x16x32_f16 v[120:123], v[186:189], v[140:143], v[120:123]
	v_mfma_f32_16x16x32_f16 v[80:83], v[194:197], v[132:135], v[80:83]
	v_mfma_f32_16x16x32_f16 v[112:115], v[194:197], v[140:143], v[112:115]
	v_mfma_f32_16x16x32_f16 v[72:75], v[202:205], v[132:135], v[72:75]
	v_mfma_f32_16x16x32_f16 v[104:107], v[202:205], v[140:143], v[104:107]
	s_barrier
	s_mov_b32 m0, s10
	v_lshl_add_u64 v[158:159], v[164:165], 0, s[42:43]
	ds_read_b128 v[166:169], v152 offset:49152
	ds_read_b128 v[170:173], v152 offset:50176
	ds_read_b128 v[206:209], v152 offset:51200
	ds_read_b128 v[210:213], v152 offset:52224
	global_load_lds_dwordx4 v[158:159], off
	v_lshl_add_u64 v[158:159], v[164:165], 0, s[96:97]
	s_mov_b32 m0, s9
	s_nop 0
	global_load_lds_dwordx4 v[158:159], off
	s_barrier
	s_waitcnt lgkmcnt(0)
	s_waitcnt lgkmcnt(0)
	v_mfma_f32_16x16x32_f16 v[84:87], v[144:147], v[166:169], v[84:87]
	v_mfma_f32_16x16x32_f16 v[116:119], v[144:147], v[206:209], v[116:119]
	v_mfma_f32_16x16x32_f16 v[76:79], v[176:179], v[166:169], v[76:79]
	v_mfma_f32_16x16x32_f16 v[108:111], v[176:179], v[206:209], v[108:111]
	v_mfma_f32_16x16x32_f16 v[68:71], v[190:193], v[166:169], v[68:71]
	v_mfma_f32_16x16x32_f16 v[100:103], v[190:193], v[206:209], v[100:103]
	v_mfma_f32_16x16x32_f16 v[64:67], v[198:201], v[166:169], v[64:67]
	v_mfma_f32_16x16x32_f16 v[96:99], v[198:201], v[206:209], v[96:99]
	v_mfma_f32_16x16x32_f16 v[84:87], v[148:151], v[170:173], v[84:87]
	v_mfma_f32_16x16x32_f16 v[116:119], v[148:151], v[210:213], v[116:119]
	v_mfma_f32_16x16x32_f16 v[76:79], v[186:189], v[170:173], v[76:79]
	v_mfma_f32_16x16x32_f16 v[108:111], v[186:189], v[210:213], v[108:111]
	v_mfma_f32_16x16x32_f16 v[68:71], v[194:197], v[170:173], v[68:71]
	v_mfma_f32_16x16x32_f16 v[100:103], v[194:197], v[210:213], v[100:103]
	v_mfma_f32_16x16x32_f16 v[64:67], v[202:205], v[170:173], v[64:67]
	v_mfma_f32_16x16x32_f16 v[96:99], v[202:205], v[210:213], v[96:99]
	s_mov_b32 m0, s8
	v_lshl_add_u64 v[158:159], v[160:161], 0, s[42:43]
	s_mov_b64 s[8:9], 0x100180
	s_barrier
	ds_read_b128 v[144:147], v228 offset:49152
	ds_read_b128 v[148:151], v228 offset:50176
	ds_read_b128 v[176:179], v228 offset:51200
	ds_read_b128 v[186:189], v228 offset:52224
	ds_read_b128 v[190:193], v228 offset:53248
	ds_read_b128 v[194:197], v228 offset:54272
	ds_read_b128 v[198:201], v228 offset:55296
	ds_read_b128 v[202:205], v228 offset:56320
	global_load_lds_dwordx4 v[158:159], off
	v_lshl_add_u64 v[158:159], v[160:161], 0, s[8:9]
	s_mov_b32 m0, s7
	s_nop 0
	global_load_lds_dwordx4 v[158:159], off
	s_barrier
;   #define STAGE(P,BASE,LD,br,kt) do{ const HALF* _u=(BASE)+(long)(br)*(((&(LD))==&lda)?lda_u:(LD))+(long)(kt)*G_BK; \
;     for(int _i=0;_i<2;++_i){ \
;       __builtin_amdgcn_global_load_lds((const unsigned*)(_u+(long)_i*(((&(LD))==&lda)?stepa:stepb)+((&(LD))==&lda?oa0:ob0)), \
;         (unsigned*)((char*)(P)+t5*16+_i*8192),16,0,0);}}while(0)
;   #define LDA(dst,b,h) for(int m=0;m<4;++m)for(int k=0;k<2;++k) \
;     dst[m][k]=*reinterpret_cast<const h8*>(la+(((b)*2+(h))*16384+m*2048+k*1024))
;   #define LDB(dst,b,h) for(int n=0;n<2;++n)for(int k=0;k<2;++k) \
;     dst[n][k]=*reinterpret_cast<const h8*>(lb+(((b)*2+(h))*16384+n*2048+k*1024))
;   #define MMA(ai,bj,At,Bt_) do{__builtin_amdgcn_s_setprio(1); \
;     for(int m=0;m<4;++m)for(int n=0;n<2;++n)for(int k=0;k<2;++k) \
;       acc[ai][bj][m][n]=__builtin_amdgcn_mfma_f32_16x16x32_f16(At[m][k],Bt_[n][k],acc[ai][bj][m][n],0,0,0); \
;     __builtin_amdgcn_s_setprio(0);}while(0)
;   #define WAIT_V(n) asm volatile("s_waitcnt vmcnt(" #n ")":::"memory")
;   #define WAIT_L(n) asm volatile("s_waitcnt lgkmcnt(" #n ")":::"memory")
;   #define BAR __builtin_amdgcn_s_barrier()
;   #define SCHED __builtin_amdgcn_sched_barrier(0)
;     ...
;     LDA(At,1,1); STAGE(SA(1,0),A,lda,0,t+3);
;     BAR; WAIT_L(0); MMA(1,0,At,B0); BAR; SCHED;
;     STAGE(SB(1,1),Bt,ldb,G_HALF,t+3);
;     WAIT_V(6); BAR; MMA(1,1,At,B1); BAR;
;   }
;   { LDB(B0,0,0); LDA(At,0,0); STAGE(SA(1,1),A,lda,G_HALF,nt-1);
;     BAR; WAIT_L(0); MMA(0,0,At,B0); BAR;
;     LDB(B1,0,1); BAR; WAIT_L(0); MMA(0,1,At,B1); BAR;
;     LDA(At,0,1); WAIT_V(4); BAR; WAIT_L(0); MMA(1,0,At,B0); MMA(1,1,At,B1); BAR; }
;   { LDB(B0,1,0); LDA(At,1,0); WAIT_V(2); BAR; WAIT_L(0); MMA(0,0,At,B0); BAR;
;     LDB(B1,1,1); WAIT_V(0); BAR; WAIT_L(0); MMA(0,1,At,B1); BAR;
;     LDA(At,1,1); BAR; WAIT_L(0); MMA(1,0,At,B0); MMA(1,1,At,B1); BAR; }
	s_waitcnt lgkmcnt(0)
	s_waitcnt lgkmcnt(0)
	v_mfma_f32_16x16x32_f16 v[24:27], v[144:147], v[128:131], v[24:27]
	v_mfma_f32_16x16x32_f16 v[56:59], v[144:147], v[136:139], v[56:59]
	v_mfma_f32_16x16x32_f16 v[16:19], v[176:179], v[128:131], v[16:19]
	v_mfma_f32_16x16x32_f16 v[48:51], v[176:179], v[136:139], v[48:51]
	v_mfma_f32_16x16x32_f16 v[8:11], v[190:193], v[128:131], v[8:11]
	v_mfma_f32_16x16x32_f16 v[40:43], v[190:193], v[136:139], v[40:43]
	v_mfma_f32_16x16x32_f16 v[0:3], v[198:201], v[128:131], v[0:3]
	v_mfma_f32_16x16x32_f16 v[32:35], v[198:201], v[136:139], v[32:35]
	v_mfma_f32_16x16x32_f16 v[24:27], v[148:151], v[132:135], v[24:27]
	v_mfma_f32_16x16x32_f16 v[56:59], v[148:151], v[140:143], v[56:59]
	v_mfma_f32_16x16x32_f16 v[16:19], v[186:189], v[132:135], v[16:19]
	v_mfma_f32_16x16x32_f16 v[48:51], v[186:189], v[140:143], v[48:51]
	v_mfma_f32_16x16x32_f16 v[8:11], v[194:197], v[132:135], v[8:11]
	v_mfma_f32_16x16x32_f16 v[40:43], v[194:197], v[140:143], v[40:43]
	v_mfma_f32_16x16x32_f16 v[0:3], v[202:205], v[132:135], v[0:3]
	v_mfma_f32_16x16x32_f16 v[32:35], v[202:205], v[140:143], v[32:35]
	s_barrier
	s_mov_b32 m0, s6
	v_lshl_add_u64 v[128:129], v[162:163], 0, s[42:43]
	global_load_lds_dwordx4 v[128:129], off
	v_lshl_add_u64 v[128:129], v[162:163], 0, s[96:97]
	s_mov_b32 m0, s1
	s_nop 0
	global_load_lds_dwordx4 v[128:129], off
	s_waitcnt vmcnt(6)
	s_barrier
	v_mfma_f32_16x16x32_f16 v[28:31], v[144:147], v[166:169], v[28:31]
	v_mfma_f32_16x16x32_f16 v[60:63], v[144:147], v[206:209], v[60:63]
	v_mfma_f32_16x16x32_f16 v[20:23], v[176:179], v[166:169], v[20:23]
	v_mfma_f32_16x16x32_f16 v[52:55], v[176:179], v[206:209], v[52:55]
	v_mfma_f32_16x16x32_f16 v[12:15], v[190:193], v[166:169], v[12:15]
	v_mfma_f32_16x16x32_f16 v[44:47], v[190:193], v[206:209], v[44:47]
	v_mfma_f32_16x16x32_f16 v[4:7], v[198:201], v[166:169], v[4:7]
	v_mfma_f32_16x16x32_f16 v[36:39], v[198:201], v[206:209], v[36:39]
	v_mfma_f32_16x16x32_f16 v[28:31], v[148:151], v[170:173], v[28:31]
	v_mfma_f32_16x16x32_f16 v[60:63], v[148:151], v[210:213], v[60:63]
	v_mfma_f32_16x16x32_f16 v[20:23], v[186:189], v[170:173], v[20:23]
	v_mfma_f32_16x16x32_f16 v[52:55], v[186:189], v[210:213], v[52:55]
	v_mfma_f32_16x16x32_f16 v[12:15], v[194:197], v[170:173], v[12:15]
	v_mfma_f32_16x16x32_f16 v[44:47], v[194:197], v[210:213], v[44:47]
	v_mfma_f32_16x16x32_f16 v[4:7], v[202:205], v[170:173], v[4:7]
	v_mfma_f32_16x16x32_f16 v[36:39], v[202:205], v[210:213], v[36:39]
	s_mov_b64 s[6:7], 0x200180
	s_mov_b32 m0, s12
	v_lshl_add_u64 v[158:159], v[160:161], 0, s[6:7]
	s_mov_b64 s[6:7], 0x300180
	s_barrier
	ds_read_b128 v[128:131], v152
	ds_read_b128 v[132:135], v152 offset:1024
	ds_read_b128 v[136:139], v152 offset:2048
	ds_read_b128 v[140:143], v152 offset:3072
	ds_read_b128 v[144:147], v228
	ds_read_b128 v[148:151], v228 offset:1024
	ds_read_b128 v[162:165], v228 offset:2048
	ds_read_b128 v[166:169], v228 offset:3072
	ds_read_b128 v[170:173], v228 offset:4096
	ds_read_b128 v[176:179], v228 offset:5120
	ds_read_b128 v[186:189], v228 offset:6144
	ds_read_b128 v[190:193], v228 offset:7168
	global_load_lds_dwordx4 v[158:159], off
	v_lshl_add_u64 v[158:159], v[160:161], 0, s[6:7]
	s_mov_b32 m0, s11
	s_nop 0
	global_load_lds_dwordx4 v[158:159], off
	s_barrier
	s_waitcnt lgkmcnt(0)
	s_waitcnt lgkmcnt(0)
	v_mfma_f32_16x16x32_f16 v[92:95], v[144:147], v[128:131], v[92:95]
	v_mfma_f32_16x16x32_f16 v[88:91], v[162:165], v[128:131], v[88:91]
	v_mfma_f32_16x16x32_f16 v[80:83], v[170:173], v[128:131], v[80:83]
	v_mfma_f32_16x16x32_f16 v[72:75], v[186:189], v[128:131], v[72:75]
	v_mfma_f32_16x16x32_f16 v[104:107], v[186:189], v[136:139], v[104:107]
	v_mfma_f32_16x16x32_f16 v[92:95], v[148:151], v[132:135], v[92:95]
	v_mfma_f32_16x16x32_f16 v[124:127], v[144:147], v[136:139], v[124:127]
	v_mfma_f32_16x16x32_f16 v[88:91], v[166:169], v[132:135], v[88:91]
	v_mfma_f32_16x16x32_f16 v[120:123], v[162:165], v[136:139], v[120:123]
	v_mfma_f32_16x16x32_f16 v[80:83], v[176:179], v[132:135], v[80:83]
	v_mfma_f32_16x16x32_f16 v[112:115], v[170:173], v[136:139], v[112:115]
	v_mfma_f32_16x16x32_f16 v[72:75], v[190:193], v[132:135], v[72:75]
	v_mfma_f32_16x16x32_f16 v[104:107], v[190:193], v[140:143], v[104:107]
	v_mfma_f32_16x16x32_f16 v[158:161], v[148:151], v[140:143], v[124:127]
	v_mfma_f32_16x16x32_f16 v[194:197], v[166:169], v[140:143], v[120:123]
	v_mfma_f32_16x16x32_f16 v[198:201], v[176:179], v[140:143], v[112:115]
	s_barrier
	s_nop 0
	ds_read_b128 v[112:115], v152 offset:16384
	ds_read_b128 v[120:123], v152 offset:17408
	ds_read_b128 v[124:127], v152 offset:18432
	ds_read_b128 v[202:205], v152 offset:19456
	s_barrier
	s_waitcnt lgkmcnt(0)
	s_waitcnt lgkmcnt(0)
	v_mfma_f32_16x16x32_f16 v[84:87], v[144:147], v[112:115], v[84:87]
	v_mfma_f32_16x16x32_f16 v[76:79], v[162:165], v[112:115], v[76:79]
	v_mfma_f32_16x16x32_f16 v[68:71], v[170:173], v[112:115], v[68:71]
	v_mfma_f32_16x16x32_f16 v[64:67], v[186:189], v[112:115], v[64:67]
	v_mfma_f32_16x16x32_f16 v[84:87], v[148:151], v[120:123], v[84:87]
	v_mfma_f32_16x16x32_f16 v[116:119], v[144:147], v[124:127], v[116:119]
	v_mfma_f32_16x16x32_f16 v[76:79], v[166:169], v[120:123], v[76:79]
	v_mfma_f32_16x16x32_f16 v[108:111], v[162:165], v[124:127], v[108:111]
	v_mfma_f32_16x16x32_f16 v[68:71], v[176:179], v[120:123], v[68:71]
	v_mfma_f32_16x16x32_f16 v[100:103], v[170:173], v[124:127], v[100:103]
	v_mfma_f32_16x16x32_f16 v[64:67], v[190:193], v[120:123], v[64:67]
	v_mfma_f32_16x16x32_f16 v[96:99], v[186:189], v[124:127], v[96:99]
	v_mfma_f32_16x16x32_f16 v[144:147], v[148:151], v[202:205], v[116:119]
	v_mfma_f32_16x16x32_f16 v[148:151], v[166:169], v[202:205], v[108:111]
	v_mfma_f32_16x16x32_f16 v[162:165], v[176:179], v[202:205], v[100:103]
	v_mfma_f32_16x16x32_f16 v[166:169], v[190:193], v[202:205], v[96:99]
	s_barrier
;   #define LDA(dst,b,h) for(int m=0;m<4;++m)for(int k=0;k<2;++k) \
;     dst[m][k]=*reinterpret_cast<const h8*>(la+(((b)*2+(h))*16384+m*2048+k*1024))
;   #define LDB(dst,b,h) for(int n=0;n<2;++n)for(int k=0;k<2;++k) \
;     dst[n][k]=*reinterpret_cast<const h8*>(lb+(((b)*2+(h))*16384+n*2048+k*1024))
;   #define MMA(ai,bj,At,Bt_) do{__builtin_amdgcn_s_setprio(1); \
;     for(int m=0;m<4;++m)for(int n=0;n<2;++n)for(int k=0;k<2;++k) \
;       acc[ai][bj][m][n]=__builtin_amdgcn_mfma_f32_16x16x32_f16(At[m][k],Bt_[n][k],acc[ai][bj][m][n],0,0,0); \
;     __builtin_amdgcn_s_setprio(0);}while(0)
;   #define WAIT_V(n) asm volatile("s_waitcnt vmcnt(" #n ")":::"memory")
;   #define WAIT_L(n) asm volatile("s_waitcnt lgkmcnt(" #n ")":::"memory")
;   #define BAR __builtin_amdgcn_s_barrier()
;     ...
;     LDB(B1,0,1); BAR; WAIT_L(0); MMA(0,1,At,B1); BAR;
;     LDA(At,0,1); WAIT_V(4); BAR; WAIT_L(0); MMA(1,0,At,B0); MMA(1,1,At,B1); BAR; }
;   { LDB(B0,1,0); LDA(At,1,0); WAIT_V(2); BAR; WAIT_L(0); MMA(0,0,At,B0); BAR;
;     LDB(B1,1,1); WAIT_V(0); BAR; WAIT_L(0); MMA(0,1,At,B1); BAR;
	s_nop 1
	ds_read_b128 v[96:99], v228 offset:16384
	ds_read_b128 v[100:103], v228 offset:17408
	ds_read_b128 v[108:111], v228 offset:18432
	ds_read_b128 v[116:119], v228 offset:19456
	ds_read_b128 v[170:173], v228 offset:20480
	ds_read_b128 v[176:179], v228 offset:21504
	ds_read_b128 v[186:189], v228 offset:22528
	ds_read_b128 v[190:193], v228 offset:23552
	s_waitcnt vmcnt(4)
	s_barrier
	s_waitcnt lgkmcnt(0)
	s_waitcnt lgkmcnt(0)
	v_mfma_f32_16x16x32_f16 v[24:27], v[96:99], v[128:131], v[24:27]
	v_mfma_f32_16x16x32_f16 v[56:59], v[96:99], v[136:139], v[56:59]
	v_mfma_f32_16x16x32_f16 v[16:19], v[108:111], v[128:131], v[16:19]
	v_mfma_f32_16x16x32_f16 v[8:11], v[170:173], v[128:131], v[8:11]
	v_mfma_f32_16x16x32_f16 v[40:43], v[170:173], v[136:139], v[40:43]
	v_mfma_f32_16x16x32_f16 v[0:3], v[186:189], v[128:131], v[0:3]
	v_mfma_f32_16x16x32_f16 v[32:35], v[186:189], v[136:139], v[32:35]
	v_mfma_f32_16x16x32_f16 v[24:27], v[100:103], v[132:135], v[24:27]
	v_mfma_f32_16x16x32_f16 v[56:59], v[100:103], v[140:143], v[56:59]
	v_mfma_f32_16x16x32_f16 v[16:19], v[116:119], v[132:135], v[16:19]
	v_mfma_f32_16x16x32_f16 v[48:51], v[108:111], v[136:139], v[48:51]
	v_mfma_f32_16x16x32_f16 v[8:11], v[176:179], v[132:135], v[8:11]
	v_mfma_f32_16x16x32_f16 v[40:43], v[176:179], v[140:143], v[40:43]
	v_mfma_f32_16x16x32_f16 v[0:3], v[190:193], v[132:135], v[0:3]
	v_mfma_f32_16x16x32_f16 v[32:35], v[190:193], v[140:143], v[32:35]
	v_mfma_f32_16x16x32_f16 v[206:209], v[116:119], v[140:143], v[48:51]
	v_mfma_f32_16x16x32_f16 v[28:31], v[96:99], v[112:115], v[28:31]
	v_mfma_f32_16x16x32_f16 v[48:51], v[96:99], v[124:127], v[60:63]
	v_mfma_f32_16x16x32_f16 v[20:23], v[108:111], v[112:115], v[20:23]
	v_mfma_f32_16x16x32_f16 v[12:15], v[170:173], v[112:115], v[12:15]
	v_mfma_f32_16x16x32_f16 v[4:7], v[186:189], v[112:115], v[4:7]
	v_mfma_f32_16x16x32_f16 v[28:31], v[100:103], v[120:123], v[28:31]
	v_mfma_f32_16x16x32_f16 v[128:131], v[100:103], v[202:205], v[48:51]
	v_mfma_f32_16x16x32_f16 v[20:23], v[116:119], v[120:123], v[20:23]
	v_mfma_f32_16x16x32_f16 v[48:51], v[108:111], v[124:127], v[52:55]
	v_mfma_f32_16x16x32_f16 v[12:15], v[176:179], v[120:123], v[12:15]
	v_mfma_f32_16x16x32_f16 v[44:47], v[170:173], v[124:127], v[44:47]
	v_mfma_f32_16x16x32_f16 v[4:7], v[190:193], v[120:123], v[4:7]
	v_mfma_f32_16x16x32_f16 v[36:39], v[186:189], v[124:127], v[36:39]
	v_mfma_f32_16x16x32_f16 v[132:135], v[116:119], v[202:205], v[48:51]
	v_mfma_f32_16x16x32_f16 v[136:139], v[176:179], v[202:205], v[44:47]
	v_mfma_f32_16x16x32_f16 v[140:143], v[190:193], v[202:205], v[36:39]
	s_barrier
	s_nop 2
	ds_read_b128 v[36:39], v152 offset:32768
	ds_read_b128 v[170:173], v152 offset:33792
	ds_read_b128 v[176:179], v152 offset:34816
	ds_read_b128 v[186:189], v152 offset:35840
	ds_read_b128 v[44:47], v228 offset:32768
	ds_read_b128 v[48:51], v228 offset:33792
	ds_read_b128 v[52:55], v228 offset:34816
	ds_read_b128 v[60:63], v228 offset:35840
	ds_read_b128 v[190:193], v228 offset:36864
	ds_read_b128 v[202:205], v228 offset:37888
	ds_read_b128 v[210:213], v228 offset:38912
	ds_read_b128 v[214:217], v228 offset:39936
	s_waitcnt vmcnt(2)
	s_barrier
	s_waitcnt lgkmcnt(0)
	s_waitcnt lgkmcnt(0)
	v_mfma_f32_16x16x32_f16 v[92:95], v[44:47], v[36:39], v[92:95]
	v_mfma_f32_16x16x32_f16 v[88:91], v[52:55], v[36:39], v[88:91]
	v_mfma_f32_16x16x32_f16 v[80:83], v[190:193], v[36:39], v[80:83]
	v_mfma_f32_16x16x32_f16 v[72:75], v[210:213], v[36:39], v[72:75]
	v_mfma_f32_16x16x32_f16 v[124:127], v[48:51], v[170:173], v[92:95]
	v_mfma_f32_16x16x32_f16 v[92:95], v[44:47], v[176:179], v[158:161]
	v_mfma_f32_16x16x32_f16 v[116:119], v[60:63], v[170:173], v[88:91]
	v_mfma_f32_16x16x32_f16 v[88:91], v[52:55], v[176:179], v[194:197]
	v_mfma_f32_16x16x32_f16 v[108:111], v[202:205], v[170:173], v[80:83]
	v_mfma_f32_16x16x32_f16 v[80:83], v[190:193], v[176:179], v[198:201]
	v_mfma_f32_16x16x32_f16 v[96:99], v[214:217], v[170:173], v[72:75]
	v_mfma_f32_16x16x32_f16 v[72:75], v[210:213], v[176:179], v[104:107]
	v_mfma_f32_16x16x32_f16 v[120:123], v[48:51], v[186:189], v[92:95]
	v_mfma_f32_16x16x32_f16 v[112:115], v[60:63], v[186:189], v[88:91]
	v_mfma_f32_16x16x32_f16 v[100:103], v[202:205], v[186:189], v[80:83]
	v_mfma_f32_16x16x32_f16 v[88:91], v[214:217], v[186:189], v[72:75]
	s_barrier
;   #define LDA(dst,b,h) for(int m=0;m<4;++m)for(int k=0;k<2;++k) \
;     dst[m][k]=*reinterpret_cast<const h8*>(la+(((b)*2+(h))*16384+m*2048+k*1024))
;   #define LDB(dst,b,h) for(int n=0;n<2;++n)for(int k=0;k<2;++k) \
;     dst[n][k]=*reinterpret_cast<const h8*>(lb+(((b)*2+(h))*16384+n*2048+k*1024))
;   #define MMA(ai,bj,At,Bt_) do{__builtin_amdgcn_s_setprio(1); \
;     for(int m=0;m<4;++m)for(int n=0;n<2;++n)for(int k=0;k<2;++k) \
;       acc[ai][bj][m][n]=__builtin_amdgcn_mfma_f32_16x16x32_f16(At[m][k],Bt_[n][k],acc[ai][bj][m][n],0,0,0); \
;     __builtin_amdgcn_s_setprio(0);}while(0)
;   #define WAIT_V(n) asm volatile("s_waitcnt vmcnt(" #n ")":::"memory")
;   #define WAIT_L(n) asm volatile("s_waitcnt lgkmcnt(" #n ")":::"memory")
;   #define BAR __builtin_amdgcn_s_barrier()
;     ...
;   { LDB(B0,1,0); LDA(At,1,0); WAIT_V(2); BAR; WAIT_L(0); MMA(0,0,At,B0); BAR;
;     LDB(B1,1,1); WAIT_V(0); BAR; WAIT_L(0); MMA(0,1,At,B1); BAR;
;     LDA(At,1,1); BAR; WAIT_L(0); MMA(1,0,At,B0); MMA(1,1,At,B1); BAR; }
;   if(wr==0)BAR;
	ds_read_b128 v[158:161], v152 offset:49152
	ds_read_b128 v[194:197], v152 offset:50176
	ds_read_b128 v[198:201], v152 offset:51200
	ds_read_b128 v[218:221], v152 offset:52224
	s_waitcnt vmcnt(0)
	s_barrier
	s_waitcnt lgkmcnt(0)
	s_waitcnt lgkmcnt(0)
	v_mfma_f32_16x16x32_f16 v[72:75], v[44:47], v[158:161], v[84:87]
	v_mfma_f32_16x16x32_f16 v[44:47], v[44:47], v[198:201], v[144:147]
	v_mfma_f32_16x16x32_f16 v[92:95], v[48:51], v[218:221], v[44:47]
	v_mfma_f32_16x16x32_f16 v[44:47], v[52:55], v[158:161], v[76:79]
	v_mfma_f32_16x16x32_f16 v[84:87], v[60:63], v[194:197], v[44:47]
	v_mfma_f32_16x16x32_f16 v[44:47], v[52:55], v[198:201], v[148:151]
	v_mfma_f32_16x16x32_f16 v[80:83], v[60:63], v[218:221], v[44:47]
	v_mfma_f32_16x16x32_f16 v[44:47], v[190:193], v[158:161], v[68:71]
	v_mfma_f32_16x16x32_f16 v[76:79], v[202:205], v[194:197], v[44:47]
	v_mfma_f32_16x16x32_f16 v[44:47], v[190:193], v[198:201], v[162:165]
	v_mfma_f32_16x16x32_f16 v[68:71], v[202:205], v[218:221], v[44:47]
	v_mfma_f32_16x16x32_f16 v[44:47], v[210:213], v[158:161], v[64:67]
	v_mfma_f32_16x16x32_f16 v[60:63], v[214:217], v[194:197], v[44:47]
	v_mfma_f32_16x16x32_f16 v[44:47], v[210:213], v[198:201], v[166:169]
	v_mfma_f32_16x16x32_f16 v[104:107], v[48:51], v[194:197], v[72:75]
	v_mfma_f32_16x16x32_f16 v[48:51], v[214:217], v[218:221], v[44:47]
	s_barrier
	ds_read_b128 v[144:147], v228 offset:49152
	ds_read_b128 v[148:151], v228 offset:50176
	ds_read_b128 v[162:165], v228 offset:51200
	ds_read_b128 v[166:169], v228 offset:52224
	ds_read_b128 v[190:193], v228 offset:53248
	ds_read_b128 v[202:205], v228 offset:54272
	ds_read_b128 v[210:213], v228 offset:55296
	ds_read_b128 v[214:217], v228 offset:56320
	s_barrier
	s_waitcnt lgkmcnt(0)
	s_waitcnt lgkmcnt(0)
	v_mfma_f32_16x16x32_f16 v[24:27], v[144:147], v[36:39], v[24:27]
	v_mfma_f32_16x16x32_f16 v[16:19], v[162:165], v[36:39], v[16:19]
	v_mfma_f32_16x16x32_f16 v[8:11], v[190:193], v[36:39], v[8:11]
	v_mfma_f32_16x16x32_f16 v[0:3], v[210:213], v[36:39], v[0:3]
	v_mfma_f32_16x16x32_f16 v[72:75], v[148:151], v[170:173], v[24:27]
	v_mfma_f32_16x16x32_f16 v[24:27], v[144:147], v[176:179], v[56:59]
	v_mfma_f32_16x16x32_f16 v[56:59], v[166:169], v[170:173], v[16:19]
	v_mfma_f32_16x16x32_f16 v[16:19], v[162:165], v[176:179], v[206:209]
	v_mfma_f32_16x16x32_f16 v[44:47], v[202:205], v[170:173], v[8:11]
	v_mfma_f32_16x16x32_f16 v[8:11], v[190:193], v[176:179], v[40:43]
	v_mfma_f32_16x16x32_f16 v[36:39], v[214:217], v[170:173], v[0:3]
	v_mfma_f32_16x16x32_f16 v[0:3], v[210:213], v[176:179], v[32:35]
	v_mfma_f32_16x16x32_f16 v[64:67], v[148:151], v[186:189], v[24:27]
	v_mfma_f32_16x16x32_f16 v[52:55], v[166:169], v[186:189], v[16:19]
	v_mfma_f32_16x16x32_f16 v[40:43], v[202:205], v[186:189], v[8:11]
	v_mfma_f32_16x16x32_f16 v[32:35], v[214:217], v[186:189], v[0:3]
	v_mfma_f32_16x16x32_f16 v[0:3], v[144:147], v[158:161], v[28:31]
	v_mfma_f32_16x16x32_f16 v[28:31], v[148:151], v[194:197], v[0:3]
	v_mfma_f32_16x16x32_f16 v[0:3], v[144:147], v[198:201], v[128:131]
	v_mfma_f32_16x16x32_f16 v[24:27], v[148:151], v[218:221], v[0:3]
	v_mfma_f32_16x16x32_f16 v[0:3], v[162:165], v[158:161], v[20:23]
	v_mfma_f32_16x16x32_f16 v[20:23], v[166:169], v[194:197], v[0:3]
	v_mfma_f32_16x16x32_f16 v[0:3], v[162:165], v[198:201], v[132:135]
	v_mfma_f32_16x16x32_f16 v[16:19], v[166:169], v[218:221], v[0:3]
	v_mfma_f32_16x16x32_f16 v[0:3], v[190:193], v[158:161], v[12:15]
	v_mfma_f32_16x16x32_f16 v[12:15], v[202:205], v[194:197], v[0:3]
	v_mfma_f32_16x16x32_f16 v[0:3], v[190:193], v[198:201], v[136:139]
	v_mfma_f32_16x16x32_f16 v[8:11], v[202:205], v[218:221], v[0:3]
	v_mfma_f32_16x16x32_f16 v[0:3], v[210:213], v[158:161], v[4:7]
	v_mfma_f32_16x16x32_f16 v[4:7], v[214:217], v[194:197], v[0:3]
	v_mfma_f32_16x16x32_f16 v[0:3], v[210:213], v[198:201], v[140:143]
	v_mfma_f32_16x16x32_f16 v[0:3], v[214:217], v[218:221], v[0:3]
	s_movk_i32 s1, 0x100
	v_cmp_gt_u32_e32 vcc, s1, v157
	s_barrier
	s_and_saveexec_b64 s[6:7], vcc
	s_cbranch_execz .LBB0_489
	s_barrier

;   #define STAGE(P,BASE,LD,br,kt) do{ const HALF* _u=(BASE)+(long)(br)*(((&(LD))==&lda)?lda_u:(LD))+(long)(kt)*G_BK; \
;     for(int _i=0;_i<2;++_i){ \
;       __builtin_amdgcn_global_load_lds((const unsigned*)(_u+(long)_i*(((&(LD))==&lda)?stepa:stepb)+((&(LD))==&lda?oa0:ob0)), \
;         (unsigned*)((char*)(P)+t5*16+_i*8192),16,0,0);}}while(0)
;   #define LDA(dst,b,h) for(int m=0;m<4;++m)for(int k=0;k<2;++k) \
;     dst[m][k]=*reinterpret_cast<const h8*>(la+(((b)*2+(h))*16384+m*2048+k*1024))
;   #define LDB(dst,b,h) for(int n=0;n<2;++n)for(int k=0;k<2;++k) \
;     dst[n][k]=*reinterpret_cast<const h8*>(lb+(((b)*2+(h))*16384+n*2048+k*1024))
;   #define MMA(ai,bj,At,Bt_) do{__builtin_amdgcn_s_setprio(1); \
;     for(int m=0;m<4;++m)for(int n=0;n<2;++n)for(int k=0;k<2;++k) \
;       acc[ai][bj][m][n]=__builtin_amdgcn_mfma_f32_16x16x32_f16(At[m][k],Bt_[n][k],acc[ai][bj][m][n],0,0,0); \
;     __builtin_amdgcn_s_setprio(0);}while(0)
;   #define WAIT_V(n) asm volatile("s_waitcnt vmcnt(" #n ")":::"memory")
;   #define WAIT_L(n) asm volatile("s_waitcnt lgkmcnt(" #n ")":::"memory")
;   #define BAR __builtin_amdgcn_s_barrier()
;   #define SCHED __builtin_amdgcn_sched_barrier(0)
;     ...
;     LDB(B0,0,0); SCHED; LDA(At,0,0); STAGE(SA(1,1),A,lda,G_HALF,t+1);
;     WAIT_L(8); BAR; WAIT_L(0); MMA(0,0,At,B0); BAR; SCHED;
;     LDB(B1,0,1); STAGE(SB(0,0),Bt,ldb,0,t+2);
;     BAR; WAIT_L(0); MMA(0,1,At,B1); BAR;
;     LDA(At,0,1); STAGE(SA(0,0),A,lda,0,t+2);
;     BAR; WAIT_L(0); MMA(1,0,At,B0); BAR; SCHED;
;     STAGE(SB(0,1),Bt,ldb,G_HALF,t+2);
;     WAIT_V(6); BAR; MMA(1,1,At,B1); BAR;
.LBB0_616:
	ds_read_b128 v[158:161], v133
	ds_read_b128 v[162:165], v133 offset:1024
	ds_read_b128 v[166:169], v133 offset:2048
	ds_read_b128 v[170:173], v133 offset:3072
	v_lshl_add_u64 v[150:151], s[10:11], 0, v[128:129]
	s_mov_b64 s[12:13], 0x2640080
	v_add_u32_e32 v148, 0xc000, v136
	v_lshl_add_u64 v[214:215], v[150:151], 0, s[12:13]
	v_readfirstlane_b32 s12, v148
	s_mov_b32 m0, s12
	s_mov_b64 s[12:13], 0x2660080
	v_add_u32_e32 v149, 0xe000, v136
	ds_read_b128 v[176:179], v132
	ds_read_b128 v[186:189], v132 offset:1024
	ds_read_b128 v[190:193], v132 offset:2048
	ds_read_b128 v[194:197], v132 offset:3072
	ds_read_b128 v[198:201], v132 offset:4096
	ds_read_b128 v[202:205], v132 offset:5120
	ds_read_b128 v[206:209], v132 offset:6144
	ds_read_b128 v[210:213], v132 offset:7168
	global_load_lds_dwordx4 v[214:215], off
	v_lshl_add_u64 v[214:215], v[150:151], 0, s[12:13]
	v_readfirstlane_b32 s12, v149
	s_mov_b32 m0, s12
	s_nop 0
	global_load_lds_dwordx4 v[214:215], off
	s_waitcnt lgkmcnt(8)
	s_barrier
	s_waitcnt lgkmcnt(0)
	s_waitcnt lgkmcnt(0)
	v_mfma_f32_16x16x32_f16 v[124:127], v[176:179], v[158:161], v[124:127]
	v_mfma_f32_16x16x32_f16 v[120:123], v[176:179], v[166:169], v[120:123]
	v_mfma_f32_16x16x32_f16 v[116:119], v[190:193], v[158:161], v[116:119]
	v_mfma_f32_16x16x32_f16 v[112:115], v[190:193], v[166:169], v[112:115]
	v_mfma_f32_16x16x32_f16 v[108:111], v[198:201], v[158:161], v[108:111]
	v_mfma_f32_16x16x32_f16 v[104:107], v[198:201], v[166:169], v[104:107]
	v_mfma_f32_16x16x32_f16 v[100:103], v[206:209], v[158:161], v[100:103]
	v_mfma_f32_16x16x32_f16 v[96:99], v[206:209], v[166:169], v[96:99]
	v_mfma_f32_16x16x32_f16 v[124:127], v[186:189], v[162:165], v[124:127]
	v_mfma_f32_16x16x32_f16 v[120:123], v[186:189], v[170:173], v[120:123]
	v_mfma_f32_16x16x32_f16 v[116:119], v[194:197], v[162:165], v[116:119]
	v_mfma_f32_16x16x32_f16 v[112:115], v[194:197], v[170:173], v[112:115]
	v_mfma_f32_16x16x32_f16 v[108:111], v[202:205], v[162:165], v[108:111]
	v_mfma_f32_16x16x32_f16 v[104:107], v[202:205], v[170:173], v[104:107]
	v_mfma_f32_16x16x32_f16 v[100:103], v[210:213], v[162:165], v[100:103]
	v_mfma_f32_16x16x32_f16 v[96:99], v[210:213], v[170:173], v[96:99]
	s_barrier
	v_lshl_add_u64 v[230:231], s[8:9], 0, v[128:129]
	v_readfirstlane_b32 s12, v134
	v_lshl_add_u64 v[232:233], v[230:231], 0, s[36:37]
	s_mov_b32 m0, s12
	v_readfirstlane_b32 s12, v135
	ds_read_b128 v[214:217], v133 offset:16384
	ds_read_b128 v[218:221], v133 offset:17408
	ds_read_b128 v[222:225], v133 offset:18432
	ds_read_b128 v[226:229], v133 offset:19456
	global_load_lds_dwordx4 v[232:233], off
	v_lshl_add_u64 v[232:233], v[230:231], 0, s[54:55]
	s_mov_b32 m0, s12
	s_nop 0
	global_load_lds_dwordx4 v[232:233], off
	s_barrier
	s_waitcnt lgkmcnt(0)
	s_waitcnt lgkmcnt(0)
	v_mfma_f32_16x16x32_f16 v[92:95], v[176:179], v[214:217], v[92:95]
	v_mfma_f32_16x16x32_f16 v[88:91], v[176:179], v[222:225], v[88:91]
	v_mfma_f32_16x16x32_f16 v[84:87], v[190:193], v[214:217], v[84:87]
	v_mfma_f32_16x16x32_f16 v[80:83], v[190:193], v[222:225], v[80:83]
	v_mfma_f32_16x16x32_f16 v[76:79], v[198:201], v[214:217], v[76:79]
	v_mfma_f32_16x16x32_f16 v[72:75], v[198:201], v[222:225], v[72:75]
	v_mfma_f32_16x16x32_f16 v[68:71], v[206:209], v[214:217], v[68:71]
	v_mfma_f32_16x16x32_f16 v[64:67], v[206:209], v[222:225], v[64:67]
	v_mfma_f32_16x16x32_f16 v[92:95], v[186:189], v[218:221], v[92:95]
	v_mfma_f32_16x16x32_f16 v[88:91], v[186:189], v[226:229], v[88:91]
	v_mfma_f32_16x16x32_f16 v[84:87], v[194:197], v[218:221], v[84:87]
	v_mfma_f32_16x16x32_f16 v[80:83], v[194:197], v[226:229], v[80:83]
	v_mfma_f32_16x16x32_f16 v[76:79], v[202:205], v[218:221], v[76:79]
	v_mfma_f32_16x16x32_f16 v[72:75], v[202:205], v[226:229], v[72:75]
	v_mfma_f32_16x16x32_f16 v[68:71], v[210:213], v[218:221], v[68:71]
	v_mfma_f32_16x16x32_f16 v[64:67], v[210:213], v[226:229], v[64:67]
	s_mov_b64 s[12:13], 0x2600100
	v_lshl_add_u64 v[232:233], v[150:151], 0, s[12:13]
	v_readfirstlane_b32 s12, v136
	s_mov_b32 m0, s12
	s_mov_b64 s[12:13], 0x2620100
	s_barrier
	ds_read_b128 v[176:179], v132 offset:16384
	ds_read_b128 v[186:189], v132 offset:17408
	ds_read_b128 v[190:193], v132 offset:18432
	ds_read_b128 v[194:197], v132 offset:19456
	ds_read_b128 v[198:201], v132 offset:20480
	ds_read_b128 v[202:205], v132 offset:21504
	ds_read_b128 v[206:209], v132 offset:22528
	ds_read_b128 v[210:213], v132 offset:23552
	global_load_lds_dwordx4 v[232:233], off
	v_lshl_add_u64 v[232:233], v[150:151], 0, s[12:13]
	v_readfirstlane_b32 s12, v137
	s_mov_b32 m0, s12
	s_nop 0
	global_load_lds_dwordx4 v[232:233], off
	s_barrier
	s_waitcnt lgkmcnt(0)
	s_waitcnt lgkmcnt(0)
	v_mfma_f32_16x16x32_f16 v[60:63], v[176:179], v[158:161], v[60:63]
	v_mfma_f32_16x16x32_f16 v[56:59], v[176:179], v[166:169], v[56:59]
	v_mfma_f32_16x16x32_f16 v[52:55], v[190:193], v[158:161], v[52:55]
	v_mfma_f32_16x16x32_f16 v[48:51], v[190:193], v[166:169], v[48:51]
	v_mfma_f32_16x16x32_f16 v[44:47], v[198:201], v[158:161], v[44:47]
	v_mfma_f32_16x16x32_f16 v[40:43], v[198:201], v[166:169], v[40:43]
	v_mfma_f32_16x16x32_f16 v[36:39], v[206:209], v[158:161], v[36:39]
	v_mfma_f32_16x16x32_f16 v[32:35], v[206:209], v[166:169], v[32:35]
	v_mfma_f32_16x16x32_f16 v[60:63], v[186:189], v[162:165], v[60:63]
	v_mfma_f32_16x16x32_f16 v[56:59], v[186:189], v[170:173], v[56:59]
	v_mfma_f32_16x16x32_f16 v[52:55], v[194:197], v[162:165], v[52:55]
	v_mfma_f32_16x16x32_f16 v[48:51], v[194:197], v[170:173], v[48:51]
	v_mfma_f32_16x16x32_f16 v[44:47], v[202:205], v[162:165], v[44:47]
	v_mfma_f32_16x16x32_f16 v[40:43], v[202:205], v[170:173], v[40:43]
	v_mfma_f32_16x16x32_f16 v[36:39], v[210:213], v[162:165], v[36:39]
	v_mfma_f32_16x16x32_f16 v[32:35], v[210:213], v[170:173], v[32:35]
	s_barrier
;   #define STAGE(P,BASE,LD,br,kt) do{ const HALF* _u=(BASE)+(long)(br)*(((&(LD))==&lda)?lda_u:(LD))+(long)(kt)*G_BK; \
;     for(int _i=0;_i<2;++_i){ \
;       __builtin_amdgcn_global_load_lds((const unsigned*)(_u+(long)_i*(((&(LD))==&lda)?stepa:stepb)+((&(LD))==&lda?oa0:ob0)), \
;         (unsigned*)((char*)(P)+t5*16+_i*8192),16,0,0);}}while(0)
;   #define LDA(dst,b,h) for(int m=0;m<4;++m)for(int k=0;k<2;++k) \
;     dst[m][k]=*reinterpret_cast<const h8*>(la+(((b)*2+(h))*16384+m*2048+k*1024))
;   #define LDB(dst,b,h) for(int n=0;n<2;++n)for(int k=0;k<2;++k) \
;     dst[n][k]=*reinterpret_cast<const h8*>(lb+(((b)*2+(h))*16384+n*2048+k*1024))
;   #define MMA(ai,bj,At,Bt_) do{__builtin_amdgcn_s_setprio(1); \
;     for(int m=0;m<4;++m)for(int n=0;n<2;++n)for(int k=0;k<2;++k) \
;       acc[ai][bj][m][n]=__builtin_amdgcn_mfma_f32_16x16x32_f16(At[m][k],Bt_[n][k],acc[ai][bj][m][n],0,0,0); \
;     __builtin_amdgcn_s_setprio(0);}while(0)
;   #define WAIT_V(n) asm volatile("s_waitcnt vmcnt(" #n ")":::"memory")
;   #define WAIT_L(n) asm volatile("s_waitcnt lgkmcnt(" #n ")":::"memory")
;   #define BAR __builtin_amdgcn_s_barrier()
;   #define SCHED __builtin_amdgcn_sched_barrier(0)
;     ...
;     STAGE(SB(0,1),Bt,ldb,G_HALF,t+2);
;     WAIT_V(6); BAR; MMA(1,1,At,B1); BAR;
;     LDB(B0,1,0); SCHED; LDA(At,1,0); STAGE(SA(0,1),A,lda,G_HALF,t+2);
;     WAIT_L(8); BAR; WAIT_L(0); MMA(0,0,At,B0); BAR; SCHED;
;     LDB(B1,1,1); STAGE(SB(1,0),Bt,ldb,0,t+3);
;     BAR; WAIT_L(0); MMA(0,1,At,B1); BAR;
;     LDA(At,1,1); STAGE(SA(1,0),A,lda,0,t+3);
;     BAR; WAIT_L(0); MMA(1,0,At,B0); BAR; SCHED;
	v_readfirstlane_b32 s12, v138
	v_lshl_add_u64 v[158:159], v[230:231], 0, s[24:25]
	s_mov_b32 m0, s12
	v_readfirstlane_b32 s12, v139
	global_load_lds_dwordx4 v[158:159], off
	v_lshl_add_u64 v[158:159], v[230:231], 0, s[48:49]
	s_mov_b32 m0, s12
	s_nop 0
	global_load_lds_dwordx4 v[158:159], off
	s_waitcnt vmcnt(6)
	s_barrier
	v_mfma_f32_16x16x32_f16 v[28:31], v[176:179], v[214:217], v[28:31]
	v_mfma_f32_16x16x32_f16 v[24:27], v[176:179], v[222:225], v[24:27]
	v_mfma_f32_16x16x32_f16 v[20:23], v[190:193], v[214:217], v[20:23]
	v_mfma_f32_16x16x32_f16 v[16:19], v[190:193], v[222:225], v[16:19]
	v_mfma_f32_16x16x32_f16 v[12:15], v[198:201], v[214:217], v[12:15]
	v_mfma_f32_16x16x32_f16 v[8:11], v[198:201], v[222:225], v[8:11]
	v_mfma_f32_16x16x32_f16 v[4:7], v[206:209], v[214:217], v[4:7]
	v_mfma_f32_16x16x32_f16 v[0:3], v[206:209], v[222:225], v[0:3]
	v_mfma_f32_16x16x32_f16 v[28:31], v[186:189], v[218:221], v[28:31]
	v_mfma_f32_16x16x32_f16 v[24:27], v[186:189], v[226:229], v[24:27]
	v_mfma_f32_16x16x32_f16 v[20:23], v[194:197], v[218:221], v[20:23]
	v_mfma_f32_16x16x32_f16 v[16:19], v[194:197], v[226:229], v[16:19]
	v_mfma_f32_16x16x32_f16 v[12:15], v[202:205], v[218:221], v[12:15]
	v_mfma_f32_16x16x32_f16 v[8:11], v[202:205], v[226:229], v[8:11]
	v_mfma_f32_16x16x32_f16 v[4:7], v[210:213], v[218:221], v[4:7]
	v_mfma_f32_16x16x32_f16 v[0:3], v[210:213], v[226:229], v[0:3]
	s_barrier
	ds_read_b128 v[158:161], v133 offset:32768
	ds_read_b128 v[162:165], v133 offset:33792
	ds_read_b128 v[166:169], v133 offset:34816
	ds_read_b128 v[170:173], v133 offset:35840
	s_mov_b64 s[12:13], 0x2640100
	v_lshl_add_u64 v[214:215], v[150:151], 0, s[12:13]
	v_readfirstlane_b32 s12, v140
	s_mov_b32 m0, s12
	s_mov_b64 s[12:13], 0x2660100
	ds_read_b128 v[176:179], v132 offset:32768
	ds_read_b128 v[186:189], v132 offset:33792
	ds_read_b128 v[190:193], v132 offset:34816
	ds_read_b128 v[194:197], v132 offset:35840
	ds_read_b128 v[198:201], v132 offset:36864
	ds_read_b128 v[202:205], v132 offset:37888
	ds_read_b128 v[206:209], v132 offset:38912
	ds_read_b128 v[210:213], v132 offset:39936
	global_load_lds_dwordx4 v[214:215], off
	v_lshl_add_u64 v[214:215], v[150:151], 0, s[12:13]
	v_readfirstlane_b32 s12, v141
	s_mov_b32 m0, s12
	s_nop 0
	global_load_lds_dwordx4 v[214:215], off
	s_waitcnt lgkmcnt(8)
	s_barrier
	s_waitcnt lgkmcnt(0)
	s_waitcnt lgkmcnt(0)
	v_mfma_f32_16x16x32_f16 v[124:127], v[176:179], v[158:161], v[124:127]
	v_mfma_f32_16x16x32_f16 v[120:123], v[176:179], v[166:169], v[120:123]
	v_mfma_f32_16x16x32_f16 v[116:119], v[190:193], v[158:161], v[116:119]
	v_mfma_f32_16x16x32_f16 v[112:115], v[190:193], v[166:169], v[112:115]
	v_mfma_f32_16x16x32_f16 v[108:111], v[198:201], v[158:161], v[108:111]
	v_mfma_f32_16x16x32_f16 v[104:107], v[198:201], v[166:169], v[104:107]
	v_mfma_f32_16x16x32_f16 v[100:103], v[206:209], v[158:161], v[100:103]
	v_mfma_f32_16x16x32_f16 v[96:99], v[206:209], v[166:169], v[96:99]
	v_mfma_f32_16x16x32_f16 v[124:127], v[186:189], v[162:165], v[124:127]
	v_mfma_f32_16x16x32_f16 v[120:123], v[186:189], v[170:173], v[120:123]
	v_mfma_f32_16x16x32_f16 v[116:119], v[194:197], v[162:165], v[116:119]
	v_mfma_f32_16x16x32_f16 v[112:115], v[194:197], v[170:173], v[112:115]
	v_mfma_f32_16x16x32_f16 v[108:111], v[202:205], v[162:165], v[108:111]
	v_mfma_f32_16x16x32_f16 v[104:107], v[202:205], v[170:173], v[104:107]
	v_mfma_f32_16x16x32_f16 v[100:103], v[210:213], v[162:165], v[100:103]
	v_mfma_f32_16x16x32_f16 v[96:99], v[210:213], v[170:173], v[96:99]
	s_barrier
	v_readfirstlane_b32 s12, v142
	v_lshl_add_u64 v[232:233], v[230:231], 0, s[60:61]
	s_mov_b32 m0, s12
	v_readfirstlane_b32 s12, v143
	ds_read_b128 v[214:217], v133 offset:49152
	ds_read_b128 v[218:221], v133 offset:50176
	ds_read_b128 v[222:225], v133 offset:51200
	ds_read_b128 v[226:229], v133 offset:52224
	global_load_lds_dwordx4 v[232:233], off
	v_lshl_add_u64 v[232:233], v[230:231], 0, s[26:27]
	s_mov_b32 m0, s12
	s_nop 0
	global_load_lds_dwordx4 v[232:233], off
	s_barrier
	s_waitcnt lgkmcnt(0)
	s_waitcnt lgkmcnt(0)
	v_mfma_f32_16x16x32_f16 v[92:95], v[176:179], v[214:217], v[92:95]
	v_mfma_f32_16x16x32_f16 v[88:91], v[176:179], v[222:225], v[88:91]
	v_mfma_f32_16x16x32_f16 v[84:87], v[190:193], v[214:217], v[84:87]
	v_mfma_f32_16x16x32_f16 v[80:83], v[190:193], v[222:225], v[80:83]
	v_mfma_f32_16x16x32_f16 v[76:79], v[198:201], v[214:217], v[76:79]
	v_mfma_f32_16x16x32_f16 v[72:75], v[198:201], v[222:225], v[72:75]
	v_mfma_f32_16x16x32_f16 v[68:71], v[206:209], v[214:217], v[68:71]
	v_mfma_f32_16x16x32_f16 v[64:67], v[206:209], v[222:225], v[64:67]
	v_mfma_f32_16x16x32_f16 v[92:95], v[186:189], v[218:221], v[92:95]
	v_mfma_f32_16x16x32_f16 v[88:91], v[186:189], v[226:229], v[88:91]
	v_mfma_f32_16x16x32_f16 v[84:87], v[194:197], v[218:221], v[84:87]
	v_mfma_f32_16x16x32_f16 v[80:83], v[194:197], v[226:229], v[80:83]
	v_mfma_f32_16x16x32_f16 v[76:79], v[202:205], v[218:221], v[76:79]
	v_mfma_f32_16x16x32_f16 v[72:75], v[202:205], v[226:229], v[72:75]
	v_mfma_f32_16x16x32_f16 v[68:71], v[210:213], v[218:221], v[68:71]
	v_mfma_f32_16x16x32_f16 v[64:67], v[210:213], v[226:229], v[64:67]
	s_mov_b64 s[12:13], 0x2600180
	v_lshl_add_u64 v[232:233], v[150:151], 0, s[12:13]
	v_readfirstlane_b32 s12, v144
	s_mov_b32 m0, s12
	s_mov_b64 s[12:13], 0x2620180
	v_lshl_add_u64 v[150:151], v[150:151], 0, s[12:13]
	v_readfirstlane_b32 s12, v145
	s_barrier
	ds_read_b128 v[176:179], v132 offset:49152
	ds_read_b128 v[186:189], v132 offset:50176
	ds_read_b128 v[190:193], v132 offset:51200
	ds_read_b128 v[194:197], v132 offset:52224
	ds_read_b128 v[198:201], v132 offset:53248
	ds_read_b128 v[202:205], v132 offset:54272
	ds_read_b128 v[206:209], v132 offset:55296
	ds_read_b128 v[210:213], v132 offset:56320
	global_load_lds_dwordx4 v[232:233], off
	s_mov_b32 m0, s12
	s_nop 0
	global_load_lds_dwordx4 v[150:151], off
	s_barrier
;   #define STAGE(P,BASE,LD,br,kt) do{ const HALF* _u=(BASE)+(long)(br)*(((&(LD))==&lda)?lda_u:(LD))+(long)(kt)*G_BK; \
;     for(int _i=0;_i<2;++_i){ \
;       __builtin_amdgcn_global_load_lds((const unsigned*)(_u+(long)_i*(((&(LD))==&lda)?stepa:stepb)+((&(LD))==&lda?oa0:ob0)), \
;         (unsigned*)((char*)(P)+t5*16+_i*8192),16,0,0);}}while(0)
;   #define LDA(dst,b,h) for(int m=0;m<4;++m)for(int k=0;k<2;++k) \
;     dst[m][k]=*reinterpret_cast<const h8*>(la+(((b)*2+(h))*16384+m*2048+k*1024))
;   #define LDB(dst,b,h) for(int n=0;n<2;++n)for(int k=0;k<2;++k) \
;     dst[n][k]=*reinterpret_cast<const h8*>(lb+(((b)*2+(h))*16384+n*2048+k*1024))
;   #define MMA(ai,bj,At,Bt_) do{__builtin_amdgcn_s_setprio(1); \
;     for(int m=0;m<4;++m)for(int n=0;n<2;++n)for(int k=0;k<2;++k) \
;       acc[ai][bj][m][n]=__builtin_amdgcn_mfma_f32_16x16x32_f16(At[m][k],Bt_[n][k],acc[ai][bj][m][n],0,0,0); \
;     __builtin_amdgcn_s_setprio(0);}while(0)
;   #define WAIT_V(n) asm volatile("s_waitcnt vmcnt(" #n ")":::"memory")
;   #define WAIT_L(n) asm volatile("s_waitcnt lgkmcnt(" #n ")":::"memory")
;   #define BAR __builtin_amdgcn_s_barrier()
;   #define SCHED __builtin_amdgcn_sched_barrier(0)
;     ...
;     LDA(At,1,1); STAGE(SA(1,0),A,lda,0,t+3);
;     BAR; WAIT_L(0); MMA(1,0,At,B0); BAR; SCHED;
;     STAGE(SB(1,1),Bt,ldb,G_HALF,t+3);
;     WAIT_V(6); BAR; MMA(1,1,At,B1); BAR;
;   }
;   { LDB(B0,0,0); LDA(At,0,0); STAGE(SA(1,1),A,lda,G_HALF,nt-1);
;     BAR; WAIT_L(0); MMA(0,0,At,B0); BAR;
;     LDB(B1,0,1); BAR; WAIT_L(0); MMA(0,1,At,B1); BAR;
;     LDA(At,0,1); WAIT_V(4); BAR; WAIT_L(0); MMA(1,0,At,B0); MMA(1,1,At,B1); BAR; }
	s_waitcnt lgkmcnt(0)
	s_waitcnt lgkmcnt(0)
	v_mfma_f32_16x16x32_f16 v[60:63], v[176:179], v[158:161], v[60:63]
	v_mfma_f32_16x16x32_f16 v[56:59], v[176:179], v[166:169], v[56:59]
	v_mfma_f32_16x16x32_f16 v[52:55], v[190:193], v[158:161], v[52:55]
	v_mfma_f32_16x16x32_f16 v[48:51], v[190:193], v[166:169], v[48:51]
	v_mfma_f32_16x16x32_f16 v[44:47], v[198:201], v[158:161], v[44:47]
	v_mfma_f32_16x16x32_f16 v[40:43], v[198:201], v[166:169], v[40:43]
	v_mfma_f32_16x16x32_f16 v[36:39], v[206:209], v[158:161], v[36:39]
	v_mfma_f32_16x16x32_f16 v[32:35], v[206:209], v[166:169], v[32:35]
	v_mfma_f32_16x16x32_f16 v[60:63], v[186:189], v[162:165], v[60:63]
	v_mfma_f32_16x16x32_f16 v[56:59], v[186:189], v[170:173], v[56:59]
	v_mfma_f32_16x16x32_f16 v[52:55], v[194:197], v[162:165], v[52:55]
	v_mfma_f32_16x16x32_f16 v[48:51], v[194:197], v[170:173], v[48:51]
	v_mfma_f32_16x16x32_f16 v[44:47], v[202:205], v[162:165], v[44:47]
	v_mfma_f32_16x16x32_f16 v[40:43], v[202:205], v[170:173], v[40:43]
	v_mfma_f32_16x16x32_f16 v[36:39], v[210:213], v[162:165], v[36:39]
	v_mfma_f32_16x16x32_f16 v[32:35], v[210:213], v[170:173], v[32:35]
	s_barrier
	v_readfirstlane_b32 s12, v146
	v_lshl_add_u64 v[150:151], v[230:231], 0, s[56:57]
	s_mov_b32 m0, s12
	v_readfirstlane_b32 s12, v147
	global_load_lds_dwordx4 v[150:151], off
	v_lshl_add_u64 v[150:151], v[230:231], 0, s[52:53]
	s_mov_b32 m0, s12
	s_nop 0
	global_load_lds_dwordx4 v[150:151], off
	s_waitcnt vmcnt(6)
	s_barrier
	v_mfma_f32_16x16x32_f16 v[28:31], v[176:179], v[214:217], v[28:31]
	v_mfma_f32_16x16x32_f16 v[24:27], v[176:179], v[222:225], v[24:27]
	v_mfma_f32_16x16x32_f16 v[20:23], v[190:193], v[214:217], v[20:23]
	v_mfma_f32_16x16x32_f16 v[16:19], v[190:193], v[222:225], v[16:19]
	v_mfma_f32_16x16x32_f16 v[12:15], v[198:201], v[214:217], v[12:15]
	v_mfma_f32_16x16x32_f16 v[8:11], v[198:201], v[222:225], v[8:11]
	v_mfma_f32_16x16x32_f16 v[4:7], v[206:209], v[214:217], v[4:7]
	v_mfma_f32_16x16x32_f16 v[0:3], v[206:209], v[222:225], v[0:3]
	v_mfma_f32_16x16x32_f16 v[28:31], v[186:189], v[218:221], v[28:31]
	v_mfma_f32_16x16x32_f16 v[24:27], v[186:189], v[226:229], v[24:27]
	v_mfma_f32_16x16x32_f16 v[20:23], v[194:197], v[218:221], v[20:23]
	v_mfma_f32_16x16x32_f16 v[16:19], v[194:197], v[226:229], v[16:19]
	v_mfma_f32_16x16x32_f16 v[12:15], v[202:205], v[218:221], v[12:15]
	v_mfma_f32_16x16x32_f16 v[8:11], v[202:205], v[226:229], v[8:11]
	v_mfma_f32_16x16x32_f16 v[4:7], v[210:213], v[218:221], v[4:7]
	v_mfma_f32_16x16x32_f16 v[0:3], v[210:213], v[226:229], v[0:3]
	s_add_i32 s1, s1, 2
	s_add_u32 s8, s8, 0x100
	s_addc_u32 s9, s9, 0
	s_add_u32 s10, s10, 0x100
	s_addc_u32 s11, s11, 0
	s_cmp_lt_u32 s1, 12
	s_barrier
	s_cbranch_scc1 .LBB0_616
	v_lshl_add_u64 v[128:129], v[152:153], 1, s[6:7]
	s_mov_b64 s[6:7], 0x40780
	v_readfirstlane_b32 s1, v148
	v_lshl_add_u64 v[146:147], v[128:129], 0, s[6:7]
	s_mov_b32 m0, s1
	s_mov_b64 s[6:7], 0x60780
	v_readfirstlane_b32 s1, v149
	ds_read_b128 v[134:137], v133
	ds_read_b128 v[138:141], v133 offset:1024
	ds_read_b128 v[142:145], v133 offset:2048
	ds_read_b128 v[158:161], v133 offset:3072
	ds_read_b128 v[162:165], v132
	ds_read_b128 v[166:169], v132 offset:1024
	ds_read_b128 v[170:173], v132 offset:2048
	ds_read_b128 v[176:179], v132 offset:3072
	ds_read_b128 v[186:189], v132 offset:4096
	ds_read_b128 v[190:193], v132 offset:5120
	ds_read_b128 v[194:197], v132 offset:6144
	ds_read_b128 v[198:201], v132 offset:7168
	global_load_lds_dwordx4 v[146:147], off
	v_lshl_add_u64 v[128:129], v[128:129], 0, s[6:7]
	s_mov_b32 m0, s1
	s_nop 0
	global_load_lds_dwordx4 v[128:129], off
	s_barrier
	s_waitcnt lgkmcnt(0)
	s_waitcnt lgkmcnt(0)
	v_mfma_f32_16x16x32_f16 v[124:127], v[162:165], v[134:137], v[124:127]
	v_mfma_f32_16x16x32_f16 v[116:119], v[170:173], v[134:137], v[116:119]
	v_mfma_f32_16x16x32_f16 v[108:111], v[186:189], v[134:137], v[108:111]
	v_mfma_f32_16x16x32_f16 v[100:103], v[194:197], v[134:137], v[100:103]
	v_mfma_f32_16x16x32_f16 v[124:127], v[166:169], v[138:141], v[124:127]
	v_mfma_f32_16x16x32_f16 v[120:123], v[162:165], v[142:145], v[120:123]
	v_mfma_f32_16x16x32_f16 v[116:119], v[176:179], v[138:141], v[116:119]
	v_mfma_f32_16x16x32_f16 v[112:115], v[170:173], v[142:145], v[112:115]
	v_mfma_f32_16x16x32_f16 v[108:111], v[190:193], v[138:141], v[108:111]
	v_mfma_f32_16x16x32_f16 v[104:107], v[186:189], v[142:145], v[104:107]
	v_mfma_f32_16x16x32_f16 v[100:103], v[198:201], v[138:141], v[100:103]
	v_mfma_f32_16x16x32_f16 v[96:99], v[194:197], v[142:145], v[96:99]
	v_mfma_f32_16x16x32_f16 v[146:149], v[166:169], v[158:161], v[120:123]
	v_mfma_f32_16x16x32_f16 v[202:205], v[176:179], v[158:161], v[112:115]
	v_mfma_f32_16x16x32_f16 v[206:209], v[190:193], v[158:161], v[104:107]
	v_mfma_f32_16x16x32_f16 v[210:213], v[198:201], v[158:161], v[96:99]
	s_barrier
	s_nop 1
	ds_read_b128 v[96:99], v133 offset:16384
	ds_read_b128 v[104:107], v133 offset:17408
	ds_read_b128 v[112:115], v133 offset:18432
	ds_read_b128 v[120:123], v133 offset:19456
	s_barrier
	s_waitcnt lgkmcnt(0)
	s_waitcnt lgkmcnt(0)
	v_mfma_f32_16x16x32_f16 v[92:95], v[162:165], v[96:99], v[92:95]
	v_mfma_f32_16x16x32_f16 v[84:87], v[170:173], v[96:99], v[84:87]
	v_mfma_f32_16x16x32_f16 v[76:79], v[186:189], v[96:99], v[76:79]
	v_mfma_f32_16x16x32_f16 v[68:71], v[194:197], v[96:99], v[68:71]
	v_mfma_f32_16x16x32_f16 v[92:95], v[166:169], v[104:107], v[92:95]
	v_mfma_f32_16x16x32_f16 v[88:91], v[162:165], v[112:115], v[88:91]
	v_mfma_f32_16x16x32_f16 v[84:87], v[176:179], v[104:107], v[84:87]
	v_mfma_f32_16x16x32_f16 v[80:83], v[170:173], v[112:115], v[80:83]
	v_mfma_f32_16x16x32_f16 v[76:79], v[190:193], v[104:107], v[76:79]
	v_mfma_f32_16x16x32_f16 v[72:75], v[186:189], v[112:115], v[72:75]
	v_mfma_f32_16x16x32_f16 v[68:71], v[198:201], v[104:107], v[68:71]
	v_mfma_f32_16x16x32_f16 v[64:67], v[194:197], v[112:115], v[64:67]
	v_mfma_f32_16x16x32_f16 v[162:165], v[166:169], v[120:123], v[88:91]
	v_mfma_f32_16x16x32_f16 v[166:169], v[176:179], v[120:123], v[80:83]
	v_mfma_f32_16x16x32_f16 v[170:173], v[190:193], v[120:123], v[72:75]
	v_mfma_f32_16x16x32_f16 v[176:179], v[198:201], v[120:123], v[64:67]
	s_barrier
;   #define LDA(dst,b,h) for(int m=0;m<4;++m)for(int k=0;k<2;++k) \
;     dst[m][k]=*reinterpret_cast<const h8*>(la+(((b)*2+(h))*16384+m*2048+k*1024))
;   #define LDB(dst,b,h) for(int n=0;n<2;++n)for(int k=0;k<2;++k) \
;     dst[n][k]=*reinterpret_cast<const h8*>(lb+(((b)*2+(h))*16384+n*2048+k*1024))
;   #define MMA(ai,bj,At,Bt_) do{__builtin_amdgcn_s_setprio(1); \
;     for(int m=0;m<4;++m)for(int n=0;n<2;++n)for(int k=0;k<2;++k) \
;       acc[ai][bj][m][n]=__builtin_amdgcn_mfma_f32_16x16x32_f16(At[m][k],Bt_[n][k],acc[ai][bj][m][n],0,0,0); \
;     __builtin_amdgcn_s_setprio(0);}while(0)
;   #define WAIT_V(n) asm volatile("s_waitcnt vmcnt(" #n ")":::"memory")
;   #define WAIT_L(n) asm volatile("s_waitcnt lgkmcnt(" #n ")":::"memory")
;   #define BAR __builtin_amdgcn_s_barrier()
;     ...
;     LDB(B1,0,1); BAR; WAIT_L(0); MMA(0,1,At,B1); BAR;
;     LDA(At,0,1); WAIT_V(4); BAR; WAIT_L(0); MMA(1,0,At,B0); MMA(1,1,At,B1); BAR; }
;   { LDB(B0,1,0); LDA(At,1,0); WAIT_V(2); BAR; WAIT_L(0); MMA(0,0,At,B0); BAR;
;     LDB(B1,1,1); WAIT_V(0); BAR; WAIT_L(0); MMA(0,1,At,B1); BAR;
	s_nop 1
	ds_read_b128 v[64:67], v132 offset:16384
	ds_read_b128 v[72:75], v132 offset:17408
	ds_read_b128 v[80:83], v132 offset:18432
	ds_read_b128 v[88:91], v132 offset:19456
	ds_read_b128 v[186:189], v132 offset:20480
	ds_read_b128 v[190:193], v132 offset:21504
	ds_read_b128 v[194:197], v132 offset:22528
	ds_read_b128 v[198:201], v132 offset:23552
	s_waitcnt vmcnt(4)
	s_barrier
	s_waitcnt lgkmcnt(0)
	s_waitcnt lgkmcnt(0)
	v_mfma_f32_16x16x32_f16 v[60:63], v[64:67], v[134:137], v[60:63]
	v_mfma_f32_16x16x32_f16 v[52:55], v[80:83], v[134:137], v[52:55]
	v_mfma_f32_16x16x32_f16 v[44:47], v[186:189], v[134:137], v[44:47]
	v_mfma_f32_16x16x32_f16 v[36:39], v[194:197], v[134:137], v[36:39]
	v_mfma_f32_16x16x32_f16 v[60:63], v[72:75], v[138:141], v[60:63]
	v_mfma_f32_16x16x32_f16 v[56:59], v[64:67], v[142:145], v[56:59]
	v_mfma_f32_16x16x32_f16 v[52:55], v[88:91], v[138:141], v[52:55]
	v_mfma_f32_16x16x32_f16 v[48:51], v[80:83], v[142:145], v[48:51]
	v_mfma_f32_16x16x32_f16 v[44:47], v[190:193], v[138:141], v[44:47]
	v_mfma_f32_16x16x32_f16 v[40:43], v[186:189], v[142:145], v[40:43]
	v_mfma_f32_16x16x32_f16 v[36:39], v[198:201], v[138:141], v[36:39]
	v_mfma_f32_16x16x32_f16 v[32:35], v[194:197], v[142:145], v[32:35]
	v_mfma_f32_16x16x32_f16 v[214:217], v[72:75], v[158:161], v[56:59]
	v_mfma_f32_16x16x32_f16 v[218:221], v[88:91], v[158:161], v[48:51]
	v_mfma_f32_16x16x32_f16 v[222:225], v[190:193], v[158:161], v[40:43]
	v_mfma_f32_16x16x32_f16 v[134:137], v[198:201], v[158:161], v[32:35]
	v_mfma_f32_16x16x32_f16 v[28:31], v[64:67], v[96:99], v[28:31]
	v_mfma_f32_16x16x32_f16 v[20:23], v[80:83], v[96:99], v[20:23]
	v_mfma_f32_16x16x32_f16 v[12:15], v[186:189], v[96:99], v[12:15]
	v_mfma_f32_16x16x32_f16 v[4:7], v[194:197], v[96:99], v[4:7]
	v_mfma_f32_16x16x32_f16 v[28:31], v[72:75], v[104:107], v[28:31]
	v_mfma_f32_16x16x32_f16 v[24:27], v[64:67], v[112:115], v[24:27]
	v_mfma_f32_16x16x32_f16 v[20:23], v[88:91], v[104:107], v[20:23]
	v_mfma_f32_16x16x32_f16 v[16:19], v[80:83], v[112:115], v[16:19]
	v_mfma_f32_16x16x32_f16 v[12:15], v[190:193], v[104:107], v[12:15]
	v_mfma_f32_16x16x32_f16 v[8:11], v[186:189], v[112:115], v[8:11]
	v_mfma_f32_16x16x32_f16 v[4:7], v[198:201], v[104:107], v[4:7]
	v_mfma_f32_16x16x32_f16 v[0:3], v[194:197], v[112:115], v[0:3]
	v_mfma_f32_16x16x32_f16 v[138:141], v[72:75], v[120:123], v[24:27]
	v_mfma_f32_16x16x32_f16 v[142:145], v[88:91], v[120:123], v[16:19]
	v_mfma_f32_16x16x32_f16 v[158:161], v[190:193], v[120:123], v[8:11]
	v_mfma_f32_16x16x32_f16 v[186:189], v[198:201], v[120:123], v[0:3]
	s_barrier
	s_nop 1
	ds_read_b128 v[0:3], v133 offset:32768
	ds_read_b128 v[8:11], v133 offset:33792
	ds_read_b128 v[16:19], v133 offset:34816
	ds_read_b128 v[24:27], v133 offset:35840
	ds_read_b128 v[32:35], v132 offset:32768
	ds_read_b128 v[40:43], v132 offset:33792
	ds_read_b128 v[48:51], v132 offset:34816
	ds_read_b128 v[56:59], v132 offset:35840
	ds_read_b128 v[64:67], v132 offset:36864
	ds_read_b128 v[190:193], v132 offset:37888
	ds_read_b128 v[194:197], v132 offset:38912
	ds_read_b128 v[198:201], v132 offset:39936
	s_waitcnt vmcnt(2)
	s_barrier
	s_waitcnt lgkmcnt(0)
	s_waitcnt lgkmcnt(0)
	v_mfma_f32_16x16x32_f16 v[72:75], v[32:35], v[0:3], v[124:127]
	v_mfma_f32_16x16x32_f16 v[120:123], v[40:43], v[8:11], v[72:75]
	v_mfma_f32_16x16x32_f16 v[72:75], v[32:35], v[16:19], v[146:149]
	v_mfma_f32_16x16x32_f16 v[112:115], v[40:43], v[24:27], v[72:75]
	v_mfma_f32_16x16x32_f16 v[72:75], v[48:51], v[0:3], v[116:119]
	v_mfma_f32_16x16x32_f16 v[124:127], v[56:59], v[8:11], v[72:75]
	v_mfma_f32_16x16x32_f16 v[72:75], v[48:51], v[16:19], v[202:205]
	v_mfma_f32_16x16x32_f16 v[116:119], v[56:59], v[24:27], v[72:75]
	v_mfma_f32_16x16x32_f16 v[72:75], v[64:67], v[0:3], v[108:111]
	v_mfma_f32_16x16x32_f16 v[104:107], v[190:193], v[8:11], v[72:75]
	v_mfma_f32_16x16x32_f16 v[72:75], v[64:67], v[16:19], v[206:209]
	v_mfma_f32_16x16x32_f16 v[96:99], v[190:193], v[24:27], v[72:75]
	v_mfma_f32_16x16x32_f16 v[72:75], v[194:197], v[0:3], v[100:103]
	v_mfma_f32_16x16x32_f16 v[108:111], v[198:201], v[8:11], v[72:75]
	v_mfma_f32_16x16x32_f16 v[72:75], v[194:197], v[16:19], v[210:213]
	v_mfma_f32_16x16x32_f16 v[100:103], v[198:201], v[24:27], v[72:75]
	s_barrier
;   #define LDA(dst,b,h) for(int m=0;m<4;++m)for(int k=0;k<2;++k) \
;     dst[m][k]=*reinterpret_cast<const h8*>(la+(((b)*2+(h))*16384+m*2048+k*1024))
;   #define LDB(dst,b,h) for(int n=0;n<2;++n)for(int k=0;k<2;++k) \
;     dst[n][k]=*reinterpret_cast<const h8*>(lb+(((b)*2+(h))*16384+n*2048+k*1024))
;   #define MMA(ai,bj,At,Bt_) do{__builtin_amdgcn_s_setprio(1); \
;     for(int m=0;m<4;++m)for(int n=0;n<2;++n)for(int k=0;k<2;++k) \
;       acc[ai][bj][m][n]=__builtin_amdgcn_mfma_f32_16x16x32_f16(At[m][k],Bt_[n][k],acc[ai][bj][m][n],0,0,0); \
;     __builtin_amdgcn_s_setprio(0);}while(0)
;   #define WAIT_V(n) asm volatile("s_waitcnt vmcnt(" #n ")":::"memory")
;   #define WAIT_L(n) asm volatile("s_waitcnt lgkmcnt(" #n ")":::"memory")
;   #define BAR __builtin_amdgcn_s_barrier()
;     ...
;   { LDB(B0,1,0); LDA(At,1,0); WAIT_V(2); BAR; WAIT_L(0); MMA(0,0,At,B0); BAR;
;     LDB(B1,1,1); WAIT_V(0); BAR; WAIT_L(0); MMA(0,1,At,B1); BAR;
;     LDA(At,1,1); BAR; WAIT_L(0); MMA(1,0,At,B0); MMA(1,1,At,B1); BAR; }
;   if(wr==0)BAR;
	ds_read_b128 v[146:149], v133 offset:49152
	ds_read_b128 v[202:205], v133 offset:50176
	ds_read_b128 v[206:209], v133 offset:51200
	ds_read_b128 v[210:213], v133 offset:52224
	s_waitcnt vmcnt(0)
	s_barrier
	s_waitcnt lgkmcnt(0)
	s_waitcnt lgkmcnt(0)
	v_mfma_f32_16x16x32_f16 v[72:75], v[32:35], v[146:149], v[92:95]
	v_mfma_f32_16x16x32_f16 v[32:35], v[32:35], v[206:209], v[162:165]
	v_mfma_f32_16x16x32_f16 v[80:83], v[40:43], v[210:213], v[32:35]
	v_mfma_f32_16x16x32_f16 v[32:35], v[48:51], v[146:149], v[84:87]
	v_mfma_f32_16x16x32_f16 v[92:95], v[56:59], v[202:205], v[32:35]
	v_mfma_f32_16x16x32_f16 v[32:35], v[48:51], v[206:209], v[166:169]
	v_mfma_f32_16x16x32_f16 v[84:87], v[56:59], v[210:213], v[32:35]
	v_mfma_f32_16x16x32_f16 v[32:35], v[64:67], v[146:149], v[76:79]
	v_mfma_f32_16x16x32_f16 v[88:91], v[40:43], v[202:205], v[72:75]
	v_mfma_f32_16x16x32_f16 v[72:75], v[190:193], v[202:205], v[32:35]
	v_mfma_f32_16x16x32_f16 v[32:35], v[64:67], v[206:209], v[170:173]
	v_mfma_f32_16x16x32_f16 v[64:67], v[190:193], v[210:213], v[32:35]
	v_mfma_f32_16x16x32_f16 v[32:35], v[194:197], v[146:149], v[68:71]
	v_mfma_f32_16x16x32_f16 v[76:79], v[198:201], v[202:205], v[32:35]
	v_mfma_f32_16x16x32_f16 v[32:35], v[194:197], v[206:209], v[176:179]
	v_mfma_f32_16x16x32_f16 v[68:71], v[198:201], v[210:213], v[32:35]
	s_barrier
	ds_read_b128 v[162:165], v132 offset:49152
	ds_read_b128 v[166:169], v132 offset:50176
	ds_read_b128 v[170:173], v132 offset:51200
	ds_read_b128 v[176:179], v132 offset:52224
	ds_read_b128 v[190:193], v132 offset:53248
	ds_read_b128 v[194:197], v132 offset:54272
	ds_read_b128 v[198:201], v132 offset:55296
	ds_read_b128 v[226:229], v132 offset:56320
	s_barrier
	s_waitcnt lgkmcnt(0)
	s_waitcnt lgkmcnt(0)
	v_mfma_f32_16x16x32_f16 v[32:35], v[162:165], v[0:3], v[60:63]
	v_mfma_f32_16x16x32_f16 v[56:59], v[166:169], v[8:11], v[32:35]
	v_mfma_f32_16x16x32_f16 v[32:35], v[162:165], v[16:19], v[214:217]
	v_mfma_f32_16x16x32_f16 v[48:51], v[166:169], v[24:27], v[32:35]
	v_mfma_f32_16x16x32_f16 v[32:35], v[170:173], v[0:3], v[52:55]
	v_mfma_f32_16x16x32_f16 v[60:63], v[176:179], v[8:11], v[32:35]
	v_mfma_f32_16x16x32_f16 v[32:35], v[170:173], v[16:19], v[218:221]
	v_mfma_f32_16x16x32_f16 v[52:55], v[176:179], v[24:27], v[32:35]
	v_mfma_f32_16x16x32_f16 v[32:35], v[190:193], v[0:3], v[44:47]
	v_mfma_f32_16x16x32_f16 v[0:3], v[198:201], v[0:3], v[36:39]
	v_mfma_f32_16x16x32_f16 v[40:43], v[194:197], v[8:11], v[32:35]
	v_mfma_f32_16x16x32_f16 v[32:35], v[190:193], v[16:19], v[222:225]
	v_mfma_f32_16x16x32_f16 v[44:47], v[226:229], v[8:11], v[0:3]
	v_mfma_f32_16x16x32_f16 v[0:3], v[198:201], v[16:19], v[134:137]
	v_mfma_f32_16x16x32_f16 v[32:35], v[194:197], v[24:27], v[32:35]
	v_mfma_f32_16x16x32_f16 v[36:39], v[226:229], v[24:27], v[0:3]
	v_mfma_f32_16x16x32_f16 v[0:3], v[162:165], v[146:149], v[28:31]
	v_mfma_f32_16x16x32_f16 v[24:27], v[166:169], v[202:205], v[0:3]
	v_mfma_f32_16x16x32_f16 v[0:3], v[162:165], v[206:209], v[138:141]
	v_mfma_f32_16x16x32_f16 v[16:19], v[166:169], v[210:213], v[0:3]
	v_mfma_f32_16x16x32_f16 v[0:3], v[170:173], v[146:149], v[20:23]
	v_mfma_f32_16x16x32_f16 v[28:31], v[176:179], v[202:205], v[0:3]
	v_mfma_f32_16x16x32_f16 v[0:3], v[170:173], v[206:209], v[142:145]
	v_mfma_f32_16x16x32_f16 v[20:23], v[176:179], v[210:213], v[0:3]
	v_mfma_f32_16x16x32_f16 v[0:3], v[190:193], v[146:149], v[12:15]
	v_mfma_f32_16x16x32_f16 v[4:7], v[198:201], v[146:149], v[4:7]
	v_mfma_f32_16x16x32_f16 v[8:11], v[194:197], v[202:205], v[0:3]
	v_mfma_f32_16x16x32_f16 v[0:3], v[190:193], v[206:209], v[158:161]
	v_mfma_f32_16x16x32_f16 v[12:15], v[226:229], v[202:205], v[4:7]
	v_mfma_f32_16x16x32_f16 v[4:7], v[198:201], v[206:209], v[186:189]
	v_mfma_f32_16x16x32_f16 v[0:3], v[194:197], v[210:213], v[0:3]
	v_mfma_f32_16x16x32_f16 v[4:7], v[226:229], v[210:213], v[4:7]
	s_movk_i32 s1, 0x100
	v_cmp_gt_u32_e32 vcc, s1, v131
	s_barrier
	s_and_saveexec_b64 s[6:7], vcc
	s_cbranch_execz .LBB0_619
	s_barrier

;   #define STAGE(P,BASE,LD,br,kt) do{ const HALF* _u=(BASE)+(long)(br)*(((&(LD))==&lda)?lda_u:(LD))+(long)(kt)*G_BK; \
;     for(int _i=0;_i<2;++_i){ \
;       __builtin_amdgcn_global_load_lds((const unsigned*)(_u+(long)_i*(((&(LD))==&lda)?stepa:stepb)+((&(LD))==&lda?oa0:ob0)), \
;         (unsigned*)((char*)(P)+t5*16+_i*8192),16,0,0);}}while(0)
;   #define LDA(dst,b,h) for(int m=0;m<4;++m)for(int k=0;k<2;++k) \
;     dst[m][k]=*reinterpret_cast<const h8*>(la+(((b)*2+(h))*16384+m*2048+k*1024))
;   #define LDB(dst,b,h) for(int n=0;n<2;++n)for(int k=0;k<2;++k) \
;     dst[n][k]=*reinterpret_cast<const h8*>(lb+(((b)*2+(h))*16384+n*2048+k*1024))
;   #define MMA(ai,bj,At,Bt_) do{__builtin_amdgcn_s_setprio(1); \
;     for(int m=0;m<4;++m)for(int n=0;n<2;++n)for(int k=0;k<2;++k) \
;       acc[ai][bj][m][n]=__builtin_amdgcn_mfma_f32_16x16x32_f16(At[m][k],Bt_[n][k],acc[ai][bj][m][n],0,0,0); \
;     __builtin_amdgcn_s_setprio(0);}while(0)
;   #define WAIT_V(n) asm volatile("s_waitcnt vmcnt(" #n ")":::"memory")
;   #define WAIT_L(n) asm volatile("s_waitcnt lgkmcnt(" #n ")":::"memory")
;   #define BAR __builtin_amdgcn_s_barrier()
;   #define SCHED __builtin_amdgcn_sched_barrier(0)
;     ...
;     LDB(B0,0,0); SCHED; LDA(At,0,0); STAGE(SA(1,1),A,lda,G_HALF,t+1);
;     WAIT_L(8); BAR; WAIT_L(0); MMA(0,0,At,B0); BAR; SCHED;
;     LDB(B1,0,1); STAGE(SB(0,0),Bt,ldb,0,t+2);
;     BAR; WAIT_L(0); MMA(0,1,At,B1); BAR;
;     LDA(At,0,1); STAGE(SA(0,0),A,lda,0,t+2);
;     BAR; WAIT_L(0); MMA(1,0,At,B0); BAR; SCHED;
;     STAGE(SB(0,1),Bt,ldb,G_HALF,t+2);
;     WAIT_V(6); BAR; MMA(1,1,At,B1); BAR;
.LBB0_666:
	ds_read_b128 v[158:161], v133
	ds_read_b128 v[162:165], v133 offset:1024
	ds_read_b128 v[166:169], v133 offset:2048
	ds_read_b128 v[170:173], v133 offset:3072
	v_lshl_add_u64 v[150:151], s[10:11], 0, v[128:129]
	s_mov_b64 s[16:17], 0xdf60080
	v_add_u32_e32 v148, 0xc000, v136
	v_lshl_add_u64 v[214:215], v[150:151], 0, s[16:17]
	v_readfirstlane_b32 s16, v148
	s_mov_b32 m0, s16
	s_mov_b64 s[16:17], 0xdfb8080
	v_add_u32_e32 v149, 0xe000, v136
	ds_read_b128 v[176:179], v132
	ds_read_b128 v[186:189], v132 offset:1024
	ds_read_b128 v[190:193], v132 offset:2048
	ds_read_b128 v[194:197], v132 offset:3072
	ds_read_b128 v[198:201], v132 offset:4096
	ds_read_b128 v[202:205], v132 offset:5120
	ds_read_b128 v[206:209], v132 offset:6144
	ds_read_b128 v[210:213], v132 offset:7168
	global_load_lds_dwordx4 v[214:215], off
	v_lshl_add_u64 v[214:215], v[150:151], 0, s[16:17]
	v_readfirstlane_b32 s16, v149
	s_mov_b32 m0, s16
	s_nop 0
	global_load_lds_dwordx4 v[214:215], off
	s_waitcnt lgkmcnt(8)
	s_barrier
	s_waitcnt lgkmcnt(0)
	s_waitcnt lgkmcnt(0)
	v_mfma_f32_16x16x32_f16 v[124:127], v[176:179], v[158:161], v[124:127]
	v_mfma_f32_16x16x32_f16 v[120:123], v[176:179], v[166:169], v[120:123]
	v_mfma_f32_16x16x32_f16 v[116:119], v[190:193], v[158:161], v[116:119]
	v_mfma_f32_16x16x32_f16 v[112:115], v[190:193], v[166:169], v[112:115]
	v_mfma_f32_16x16x32_f16 v[108:111], v[198:201], v[158:161], v[108:111]
	v_mfma_f32_16x16x32_f16 v[104:107], v[198:201], v[166:169], v[104:107]
	v_mfma_f32_16x16x32_f16 v[100:103], v[206:209], v[158:161], v[100:103]
	v_mfma_f32_16x16x32_f16 v[96:99], v[206:209], v[166:169], v[96:99]
	v_mfma_f32_16x16x32_f16 v[124:127], v[186:189], v[162:165], v[124:127]
	v_mfma_f32_16x16x32_f16 v[120:123], v[186:189], v[170:173], v[120:123]
	v_mfma_f32_16x16x32_f16 v[116:119], v[194:197], v[162:165], v[116:119]
	v_mfma_f32_16x16x32_f16 v[112:115], v[194:197], v[170:173], v[112:115]
	v_mfma_f32_16x16x32_f16 v[108:111], v[202:205], v[162:165], v[108:111]
	v_mfma_f32_16x16x32_f16 v[104:107], v[202:205], v[170:173], v[104:107]
	v_mfma_f32_16x16x32_f16 v[100:103], v[210:213], v[162:165], v[100:103]
	v_mfma_f32_16x16x32_f16 v[96:99], v[210:213], v[170:173], v[96:99]
	s_barrier
	v_lshl_add_u64 v[230:231], s[8:9], 0, v[128:129]
	s_mov_b64 s[16:17], 0x3100100
	v_lshl_add_u64 v[232:233], v[230:231], 0, s[16:17]
	v_readfirstlane_b32 s16, v134
	s_mov_b32 m0, s16
	s_mov_b64 s[16:17], 0x3158100
	ds_read_b128 v[214:217], v133 offset:16384
	ds_read_b128 v[218:221], v133 offset:17408
	ds_read_b128 v[222:225], v133 offset:18432
	ds_read_b128 v[226:229], v133 offset:19456
	global_load_lds_dwordx4 v[232:233], off
	v_lshl_add_u64 v[232:233], v[230:231], 0, s[16:17]
	v_readfirstlane_b32 s16, v135
	s_mov_b32 m0, s16
	s_nop 0
	global_load_lds_dwordx4 v[232:233], off
	s_barrier
	s_waitcnt lgkmcnt(0)
	s_waitcnt lgkmcnt(0)
	v_mfma_f32_16x16x32_f16 v[92:95], v[176:179], v[214:217], v[92:95]
	v_mfma_f32_16x16x32_f16 v[88:91], v[176:179], v[222:225], v[88:91]
	v_mfma_f32_16x16x32_f16 v[84:87], v[190:193], v[214:217], v[84:87]
	v_mfma_f32_16x16x32_f16 v[80:83], v[190:193], v[222:225], v[80:83]
	v_mfma_f32_16x16x32_f16 v[76:79], v[198:201], v[214:217], v[76:79]
	v_mfma_f32_16x16x32_f16 v[72:75], v[198:201], v[222:225], v[72:75]
	v_mfma_f32_16x16x32_f16 v[68:71], v[206:209], v[214:217], v[68:71]
	v_mfma_f32_16x16x32_f16 v[64:67], v[206:209], v[222:225], v[64:67]
	v_mfma_f32_16x16x32_f16 v[92:95], v[186:189], v[218:221], v[92:95]
	v_mfma_f32_16x16x32_f16 v[88:91], v[186:189], v[226:229], v[88:91]
	v_mfma_f32_16x16x32_f16 v[84:87], v[194:197], v[218:221], v[84:87]
	v_mfma_f32_16x16x32_f16 v[80:83], v[194:197], v[226:229], v[80:83]
	v_mfma_f32_16x16x32_f16 v[76:79], v[202:205], v[218:221], v[76:79]
	v_mfma_f32_16x16x32_f16 v[72:75], v[202:205], v[226:229], v[72:75]
	v_mfma_f32_16x16x32_f16 v[68:71], v[210:213], v[218:221], v[68:71]
	v_mfma_f32_16x16x32_f16 v[64:67], v[210:213], v[226:229], v[64:67]
	v_readfirstlane_b32 s16, v136
	v_lshl_add_u64 v[232:233], v[150:151], 0, s[50:51]
	s_mov_b32 m0, s16
	s_mov_b64 s[16:17], 0xdf08100
	s_barrier
	ds_read_b128 v[176:179], v132 offset:16384
	ds_read_b128 v[186:189], v132 offset:17408
	ds_read_b128 v[190:193], v132 offset:18432
	ds_read_b128 v[194:197], v132 offset:19456
	ds_read_b128 v[198:201], v132 offset:20480
	ds_read_b128 v[202:205], v132 offset:21504
	ds_read_b128 v[206:209], v132 offset:22528
	ds_read_b128 v[210:213], v132 offset:23552
	global_load_lds_dwordx4 v[232:233], off
	v_lshl_add_u64 v[232:233], v[150:151], 0, s[16:17]
	v_readfirstlane_b32 s16, v137
	s_mov_b32 m0, s16
	s_nop 0
	global_load_lds_dwordx4 v[232:233], off
	s_barrier
	s_waitcnt lgkmcnt(0)
	s_waitcnt lgkmcnt(0)
	v_mfma_f32_16x16x32_f16 v[60:63], v[176:179], v[158:161], v[60:63]
	v_mfma_f32_16x16x32_f16 v[56:59], v[176:179], v[166:169], v[56:59]
	v_mfma_f32_16x16x32_f16 v[52:55], v[190:193], v[158:161], v[52:55]
	v_mfma_f32_16x16x32_f16 v[48:51], v[190:193], v[166:169], v[48:51]
	v_mfma_f32_16x16x32_f16 v[44:47], v[198:201], v[158:161], v[44:47]
	v_mfma_f32_16x16x32_f16 v[40:43], v[198:201], v[166:169], v[40:43]
	v_mfma_f32_16x16x32_f16 v[36:39], v[206:209], v[158:161], v[36:39]
	v_mfma_f32_16x16x32_f16 v[32:35], v[206:209], v[166:169], v[32:35]
	v_mfma_f32_16x16x32_f16 v[60:63], v[186:189], v[162:165], v[60:63]
	v_mfma_f32_16x16x32_f16 v[56:59], v[186:189], v[170:173], v[56:59]
	v_mfma_f32_16x16x32_f16 v[52:55], v[194:197], v[162:165], v[52:55]
	v_mfma_f32_16x16x32_f16 v[48:51], v[194:197], v[170:173], v[48:51]
	v_mfma_f32_16x16x32_f16 v[44:47], v[202:205], v[162:165], v[44:47]
	v_mfma_f32_16x16x32_f16 v[40:43], v[202:205], v[170:173], v[40:43]
	v_mfma_f32_16x16x32_f16 v[36:39], v[210:213], v[162:165], v[36:39]
	v_mfma_f32_16x16x32_f16 v[32:35], v[210:213], v[170:173], v[32:35]
	s_barrier
;   #define STAGE(P,BASE,LD,br,kt) do{ const HALF* _u=(BASE)+(long)(br)*(((&(LD))==&lda)?lda_u:(LD))+(long)(kt)*G_BK; \
;     for(int _i=0;_i<2;++_i){ \
;       __builtin_amdgcn_global_load_lds((const unsigned*)(_u+(long)_i*(((&(LD))==&lda)?stepa:stepb)+((&(LD))==&lda?oa0:ob0)), \
;         (unsigned*)((char*)(P)+t5*16+_i*8192),16,0,0);}}while(0)
;   #define LDA(dst,b,h) for(int m=0;m<4;++m)for(int k=0;k<2;++k) \
;     dst[m][k]=*reinterpret_cast<const h8*>(la+(((b)*2+(h))*16384+m*2048+k*1024))
;   #define LDB(dst,b,h) for(int n=0;n<2;++n)for(int k=0;k<2;++k) \
;     dst[n][k]=*reinterpret_cast<const h8*>(lb+(((b)*2+(h))*16384+n*2048+k*1024))
;   #define MMA(ai,bj,At,Bt_) do{__builtin_amdgcn_s_setprio(1); \
;     for(int m=0;m<4;++m)for(int n=0;n<2;++n)for(int k=0;k<2;++k) \
;       acc[ai][bj][m][n]=__builtin_amdgcn_mfma_f32_16x16x32_f16(At[m][k],Bt_[n][k],acc[ai][bj][m][n],0,0,0); \
;     __builtin_amdgcn_s_setprio(0);}while(0)
;   #define WAIT_V(n) asm volatile("s_waitcnt vmcnt(" #n ")":::"memory")
;   #define WAIT_L(n) asm volatile("s_waitcnt lgkmcnt(" #n ")":::"memory")
;   #define BAR __builtin_amdgcn_s_barrier()
;   #define SCHED __builtin_amdgcn_sched_barrier(0)
;     ...
;     STAGE(SB(0,1),Bt,ldb,G_HALF,t+2);
;     WAIT_V(6); BAR; MMA(1,1,At,B1); BAR;
;     LDB(B0,1,0); SCHED; LDA(At,1,0); STAGE(SA(0,1),A,lda,G_HALF,t+2);
;     WAIT_L(8); BAR; WAIT_L(0); MMA(0,0,At,B0); BAR; SCHED;
;     LDB(B1,1,1); STAGE(SB(1,0),Bt,ldb,0,t+3);
;     BAR; WAIT_L(0); MMA(0,1,At,B1); BAR;
;     LDA(At,1,1); STAGE(SA(1,0),A,lda,0,t+3);
;     BAR; WAIT_L(0); MMA(1,0,At,B0); BAR; SCHED;
	s_mov_b64 s[16:17], 0x31b0100
	v_lshl_add_u64 v[158:159], v[230:231], 0, s[16:17]
	v_readfirstlane_b32 s16, v138
	s_mov_b32 m0, s16
	s_mov_b64 s[16:17], 0x3208100
	global_load_lds_dwordx4 v[158:159], off
	v_lshl_add_u64 v[158:159], v[230:231], 0, s[16:17]
	v_readfirstlane_b32 s16, v139
	s_mov_b32 m0, s16
	s_nop 0
	global_load_lds_dwordx4 v[158:159], off
	s_waitcnt vmcnt(6)
	s_barrier
	v_mfma_f32_16x16x32_f16 v[28:31], v[176:179], v[214:217], v[28:31]
	v_mfma_f32_16x16x32_f16 v[24:27], v[176:179], v[222:225], v[24:27]
	v_mfma_f32_16x16x32_f16 v[20:23], v[190:193], v[214:217], v[20:23]
	v_mfma_f32_16x16x32_f16 v[16:19], v[190:193], v[222:225], v[16:19]
	v_mfma_f32_16x16x32_f16 v[12:15], v[198:201], v[214:217], v[12:15]
	v_mfma_f32_16x16x32_f16 v[8:11], v[198:201], v[222:225], v[8:11]
	v_mfma_f32_16x16x32_f16 v[4:7], v[206:209], v[214:217], v[4:7]
	v_mfma_f32_16x16x32_f16 v[0:3], v[206:209], v[222:225], v[0:3]
	v_mfma_f32_16x16x32_f16 v[28:31], v[186:189], v[218:221], v[28:31]
	v_mfma_f32_16x16x32_f16 v[24:27], v[186:189], v[226:229], v[24:27]
	v_mfma_f32_16x16x32_f16 v[20:23], v[194:197], v[218:221], v[20:23]
	v_mfma_f32_16x16x32_f16 v[16:19], v[194:197], v[226:229], v[16:19]
	v_mfma_f32_16x16x32_f16 v[12:15], v[202:205], v[218:221], v[12:15]
	v_mfma_f32_16x16x32_f16 v[8:11], v[202:205], v[226:229], v[8:11]
	v_mfma_f32_16x16x32_f16 v[4:7], v[210:213], v[218:221], v[4:7]
	v_mfma_f32_16x16x32_f16 v[0:3], v[210:213], v[226:229], v[0:3]
	s_barrier
	ds_read_b128 v[158:161], v133 offset:32768
	ds_read_b128 v[162:165], v133 offset:33792
	ds_read_b128 v[166:169], v133 offset:34816
	ds_read_b128 v[170:173], v133 offset:35840
	s_mov_b64 s[16:17], 0xdf60100
	v_lshl_add_u64 v[214:215], v[150:151], 0, s[16:17]
	v_readfirstlane_b32 s16, v140
	s_mov_b32 m0, s16
	s_mov_b64 s[16:17], 0xdfb8100
	ds_read_b128 v[176:179], v132 offset:32768
	ds_read_b128 v[186:189], v132 offset:33792
	ds_read_b128 v[190:193], v132 offset:34816
	ds_read_b128 v[194:197], v132 offset:35840
	ds_read_b128 v[198:201], v132 offset:36864
	ds_read_b128 v[202:205], v132 offset:37888
	ds_read_b128 v[206:209], v132 offset:38912
	ds_read_b128 v[210:213], v132 offset:39936
	global_load_lds_dwordx4 v[214:215], off
	v_lshl_add_u64 v[214:215], v[150:151], 0, s[16:17]
	v_readfirstlane_b32 s16, v141
	s_mov_b32 m0, s16
	s_nop 0
	global_load_lds_dwordx4 v[214:215], off
	s_waitcnt lgkmcnt(8)
	s_barrier
	s_waitcnt lgkmcnt(0)
	s_waitcnt lgkmcnt(0)
	v_mfma_f32_16x16x32_f16 v[124:127], v[176:179], v[158:161], v[124:127]
	v_mfma_f32_16x16x32_f16 v[120:123], v[176:179], v[166:169], v[120:123]
	v_mfma_f32_16x16x32_f16 v[116:119], v[190:193], v[158:161], v[116:119]
	v_mfma_f32_16x16x32_f16 v[112:115], v[190:193], v[166:169], v[112:115]
	v_mfma_f32_16x16x32_f16 v[108:111], v[198:201], v[158:161], v[108:111]
	v_mfma_f32_16x16x32_f16 v[104:107], v[198:201], v[166:169], v[104:107]
	v_mfma_f32_16x16x32_f16 v[100:103], v[206:209], v[158:161], v[100:103]
	v_mfma_f32_16x16x32_f16 v[96:99], v[206:209], v[166:169], v[96:99]
	v_mfma_f32_16x16x32_f16 v[124:127], v[186:189], v[162:165], v[124:127]
	v_mfma_f32_16x16x32_f16 v[120:123], v[186:189], v[170:173], v[120:123]
	v_mfma_f32_16x16x32_f16 v[116:119], v[194:197], v[162:165], v[116:119]
	v_mfma_f32_16x16x32_f16 v[112:115], v[194:197], v[170:173], v[112:115]
	v_mfma_f32_16x16x32_f16 v[108:111], v[202:205], v[162:165], v[108:111]
	v_mfma_f32_16x16x32_f16 v[104:107], v[202:205], v[170:173], v[104:107]
	v_mfma_f32_16x16x32_f16 v[100:103], v[210:213], v[162:165], v[100:103]
	v_mfma_f32_16x16x32_f16 v[96:99], v[210:213], v[170:173], v[96:99]
	s_barrier
	s_mov_b64 s[16:17], 0x3100180
	v_lshl_add_u64 v[232:233], v[230:231], 0, s[16:17]
	v_readfirstlane_b32 s16, v142
	s_mov_b32 m0, s16
	s_mov_b64 s[16:17], 0x3158180
	ds_read_b128 v[214:217], v133 offset:49152
	ds_read_b128 v[218:221], v133 offset:50176
	ds_read_b128 v[222:225], v133 offset:51200
	ds_read_b128 v[226:229], v133 offset:52224
	global_load_lds_dwordx4 v[232:233], off
	v_lshl_add_u64 v[232:233], v[230:231], 0, s[16:17]
	v_readfirstlane_b32 s16, v143
	s_mov_b32 m0, s16
	s_nop 0
	global_load_lds_dwordx4 v[232:233], off
	s_barrier
	s_waitcnt lgkmcnt(0)
	s_waitcnt lgkmcnt(0)
	v_mfma_f32_16x16x32_f16 v[92:95], v[176:179], v[214:217], v[92:95]
	v_mfma_f32_16x16x32_f16 v[88:91], v[176:179], v[222:225], v[88:91]
	v_mfma_f32_16x16x32_f16 v[84:87], v[190:193], v[214:217], v[84:87]
	v_mfma_f32_16x16x32_f16 v[80:83], v[190:193], v[222:225], v[80:83]
	v_mfma_f32_16x16x32_f16 v[76:79], v[198:201], v[214:217], v[76:79]
	v_mfma_f32_16x16x32_f16 v[72:75], v[198:201], v[222:225], v[72:75]
	v_mfma_f32_16x16x32_f16 v[68:71], v[206:209], v[214:217], v[68:71]
	v_mfma_f32_16x16x32_f16 v[64:67], v[206:209], v[222:225], v[64:67]
	v_mfma_f32_16x16x32_f16 v[92:95], v[186:189], v[218:221], v[92:95]
	v_mfma_f32_16x16x32_f16 v[88:91], v[186:189], v[226:229], v[88:91]
	v_mfma_f32_16x16x32_f16 v[84:87], v[194:197], v[218:221], v[84:87]
	v_mfma_f32_16x16x32_f16 v[80:83], v[194:197], v[226:229], v[80:83]
	v_mfma_f32_16x16x32_f16 v[76:79], v[202:205], v[218:221], v[76:79]
	v_mfma_f32_16x16x32_f16 v[72:75], v[202:205], v[226:229], v[72:75]
	v_mfma_f32_16x16x32_f16 v[68:71], v[210:213], v[218:221], v[68:71]
	v_mfma_f32_16x16x32_f16 v[64:67], v[210:213], v[226:229], v[64:67]
	v_readfirstlane_b32 s16, v144
	s_mov_b32 m0, s16
	s_mov_b64 s[16:17], 0xdf08180
	v_lshl_add_u64 v[232:233], v[150:151], 0, s[46:47]
	v_lshl_add_u64 v[150:151], v[150:151], 0, s[16:17]
	v_readfirstlane_b32 s16, v145
	s_barrier
;   #define STAGE(P,BASE,LD,br,kt) do{ const HALF* _u=(BASE)+(long)(br)*(((&(LD))==&lda)?lda_u:(LD))+(long)(kt)*G_BK; \
;     for(int _i=0;_i<2;++_i){ \
;       __builtin_amdgcn_global_load_lds((const unsigned*)(_u+(long)_i*(((&(LD))==&lda)?stepa:stepb)+((&(LD))==&lda?oa0:ob0)), \
;         (unsigned*)((char*)(P)+t5*16+_i*8192),16,0,0);}}while(0)
;   #define LDA(dst,b,h) for(int m=0;m<4;++m)for(int k=0;k<2;++k) \
;     dst[m][k]=*reinterpret_cast<const h8*>(la+(((b)*2+(h))*16384+m*2048+k*1024))
;   #define LDB(dst,b,h) for(int n=0;n<2;++n)for(int k=0;k<2;++k) \
;     dst[n][k]=*reinterpret_cast<const h8*>(lb+(((b)*2+(h))*16384+n*2048+k*1024))
;   #define MMA(ai,bj,At,Bt_) do{__builtin_amdgcn_s_setprio(1); \
;     for(int m=0;m<4;++m)for(int n=0;n<2;++n)for(int k=0;k<2;++k) \
;       acc[ai][bj][m][n]=__builtin_amdgcn_mfma_f32_16x16x32_f16(At[m][k],Bt_[n][k],acc[ai][bj][m][n],0,0,0); \
;     __builtin_amdgcn_s_setprio(0);}while(0)
;   #define WAIT_V(n) asm volatile("s_waitcnt vmcnt(" #n ")":::"memory")
;   #define WAIT_L(n) asm volatile("s_waitcnt lgkmcnt(" #n ")":::"memory")
;   #define BAR __builtin_amdgcn_s_barrier()
;   #define SCHED __builtin_amdgcn_sched_barrier(0)
;     ...
;     LDA(At,1,1); STAGE(SA(1,0),A,lda,0,t+3);
;     BAR; WAIT_L(0); MMA(1,0,At,B0); BAR; SCHED;
;     STAGE(SB(1,1),Bt,ldb,G_HALF,t+3);
;     WAIT_V(6); BAR; MMA(1,1,At,B1); BAR;
;   }
;   { LDB(B0,0,0); LDA(At,0,0); STAGE(SA(1,1),A,lda,G_HALF,nt-1);
;     BAR; WAIT_L(0); MMA(0,0,At,B0); BAR;
;     LDB(B1,0,1); BAR; WAIT_L(0); MMA(0,1,At,B1); BAR;
;     LDA(At,0,1); WAIT_V(4); BAR; WAIT_L(0); MMA(1,0,At,B0); MMA(1,1,At,B1); BAR; }
	ds_read_b128 v[176:179], v132 offset:49152
	ds_read_b128 v[186:189], v132 offset:50176
	ds_read_b128 v[190:193], v132 offset:51200
	ds_read_b128 v[194:197], v132 offset:52224
	ds_read_b128 v[198:201], v132 offset:53248
	ds_read_b128 v[202:205], v132 offset:54272
	ds_read_b128 v[206:209], v132 offset:55296
	ds_read_b128 v[210:213], v132 offset:56320
	global_load_lds_dwordx4 v[232:233], off
	s_mov_b32 m0, s16
	s_nop 0
	global_load_lds_dwordx4 v[150:151], off
	s_barrier
	s_waitcnt lgkmcnt(0)
	s_waitcnt lgkmcnt(0)
	v_mfma_f32_16x16x32_f16 v[60:63], v[176:179], v[158:161], v[60:63]
	v_mfma_f32_16x16x32_f16 v[56:59], v[176:179], v[166:169], v[56:59]
	v_mfma_f32_16x16x32_f16 v[52:55], v[190:193], v[158:161], v[52:55]
	v_mfma_f32_16x16x32_f16 v[48:51], v[190:193], v[166:169], v[48:51]
	v_mfma_f32_16x16x32_f16 v[44:47], v[198:201], v[158:161], v[44:47]
	v_mfma_f32_16x16x32_f16 v[40:43], v[198:201], v[166:169], v[40:43]
	v_mfma_f32_16x16x32_f16 v[36:39], v[206:209], v[158:161], v[36:39]
	v_mfma_f32_16x16x32_f16 v[32:35], v[206:209], v[166:169], v[32:35]
	v_mfma_f32_16x16x32_f16 v[60:63], v[186:189], v[162:165], v[60:63]
	v_mfma_f32_16x16x32_f16 v[56:59], v[186:189], v[170:173], v[56:59]
	v_mfma_f32_16x16x32_f16 v[52:55], v[194:197], v[162:165], v[52:55]
	v_mfma_f32_16x16x32_f16 v[48:51], v[194:197], v[170:173], v[48:51]
	v_mfma_f32_16x16x32_f16 v[44:47], v[202:205], v[162:165], v[44:47]
	v_mfma_f32_16x16x32_f16 v[40:43], v[202:205], v[170:173], v[40:43]
	v_mfma_f32_16x16x32_f16 v[36:39], v[210:213], v[162:165], v[36:39]
	v_mfma_f32_16x16x32_f16 v[32:35], v[210:213], v[170:173], v[32:35]
	s_barrier
	s_mov_b64 s[16:17], 0x31b0180
	v_lshl_add_u64 v[150:151], v[230:231], 0, s[16:17]
	v_readfirstlane_b32 s16, v146
	s_mov_b32 m0, s16
	s_mov_b64 s[16:17], 0x3208180
	global_load_lds_dwordx4 v[150:151], off
	v_lshl_add_u64 v[150:151], v[230:231], 0, s[16:17]
	v_readfirstlane_b32 s16, v147
	s_mov_b32 m0, s16
	s_nop 0
	global_load_lds_dwordx4 v[150:151], off
	s_waitcnt vmcnt(6)
	s_barrier
	v_mfma_f32_16x16x32_f16 v[28:31], v[176:179], v[214:217], v[28:31]
	v_mfma_f32_16x16x32_f16 v[24:27], v[176:179], v[222:225], v[24:27]
	v_mfma_f32_16x16x32_f16 v[20:23], v[190:193], v[214:217], v[20:23]
	v_mfma_f32_16x16x32_f16 v[16:19], v[190:193], v[222:225], v[16:19]
	v_mfma_f32_16x16x32_f16 v[12:15], v[198:201], v[214:217], v[12:15]
	v_mfma_f32_16x16x32_f16 v[8:11], v[198:201], v[222:225], v[8:11]
	v_mfma_f32_16x16x32_f16 v[4:7], v[206:209], v[214:217], v[4:7]
	v_mfma_f32_16x16x32_f16 v[0:3], v[206:209], v[222:225], v[0:3]
	v_mfma_f32_16x16x32_f16 v[28:31], v[186:189], v[218:221], v[28:31]
	v_mfma_f32_16x16x32_f16 v[24:27], v[186:189], v[226:229], v[24:27]
	v_mfma_f32_16x16x32_f16 v[20:23], v[194:197], v[218:221], v[20:23]
	v_mfma_f32_16x16x32_f16 v[16:19], v[194:197], v[226:229], v[16:19]
	v_mfma_f32_16x16x32_f16 v[12:15], v[202:205], v[218:221], v[12:15]
	v_mfma_f32_16x16x32_f16 v[8:11], v[202:205], v[226:229], v[8:11]
	v_mfma_f32_16x16x32_f16 v[4:7], v[210:213], v[218:221], v[4:7]
	v_mfma_f32_16x16x32_f16 v[0:3], v[210:213], v[226:229], v[0:3]
	s_add_i32 s15, s15, 2
	s_add_u32 s8, s8, 0x100
	s_addc_u32 s9, s9, 0
	s_add_u32 s10, s10, 0x100
	s_addc_u32 s11, s11, 0
	s_cmp_lt_u32 s15, 40
	s_barrier
	s_cbranch_scc1 .LBB0_666
	v_lshl_add_u64 v[128:129], v[152:153], 1, s[6:7]
	s_mov_b64 s[6:7], 0xb1580
	v_lshl_add_u64 v[146:147], v[128:129], 0, s[6:7]
	v_readfirstlane_b32 s6, v148
	s_mov_b32 m0, s6
	s_mov_b64 s[6:7], 0x109580
	v_lshl_add_u64 v[128:129], v[128:129], 0, s[6:7]
	v_readfirstlane_b32 s6, v149
	ds_read_b128 v[134:137], v133
	ds_read_b128 v[138:141], v133 offset:1024
	ds_read_b128 v[142:145], v133 offset:2048
	ds_read_b128 v[158:161], v133 offset:3072
	ds_read_b128 v[162:165], v132
	ds_read_b128 v[166:169], v132 offset:1024
	ds_read_b128 v[170:173], v132 offset:2048
	ds_read_b128 v[176:179], v132 offset:3072
	ds_read_b128 v[186:189], v132 offset:4096
	ds_read_b128 v[190:193], v132 offset:5120
	ds_read_b128 v[194:197], v132 offset:6144
	ds_read_b128 v[198:201], v132 offset:7168
	global_load_lds_dwordx4 v[146:147], off
	s_mov_b32 m0, s6
	s_nop 0
	global_load_lds_dwordx4 v[128:129], off
	s_barrier
	s_waitcnt lgkmcnt(0)
	s_waitcnt lgkmcnt(0)
	v_mfma_f32_16x16x32_f16 v[124:127], v[162:165], v[134:137], v[124:127]
	v_mfma_f32_16x16x32_f16 v[120:123], v[162:165], v[142:145], v[120:123]
	v_mfma_f32_16x16x32_f16 v[116:119], v[170:173], v[134:137], v[116:119]
	v_mfma_f32_16x16x32_f16 v[112:115], v[170:173], v[142:145], v[112:115]
	v_mfma_f32_16x16x32_f16 v[108:111], v[186:189], v[134:137], v[108:111]
	v_mfma_f32_16x16x32_f16 v[104:107], v[186:189], v[142:145], v[104:107]
	v_mfma_f32_16x16x32_f16 v[100:103], v[194:197], v[134:137], v[100:103]
	v_mfma_f32_16x16x32_f16 v[96:99], v[194:197], v[142:145], v[96:99]
	v_mfma_f32_16x16x32_f16 v[124:127], v[166:169], v[138:141], v[124:127]
	v_mfma_f32_16x16x32_f16 v[120:123], v[166:169], v[158:161], v[120:123]
	v_mfma_f32_16x16x32_f16 v[116:119], v[176:179], v[138:141], v[116:119]
	v_mfma_f32_16x16x32_f16 v[112:115], v[176:179], v[158:161], v[112:115]
	v_mfma_f32_16x16x32_f16 v[108:111], v[190:193], v[138:141], v[108:111]
	v_mfma_f32_16x16x32_f16 v[104:107], v[190:193], v[158:161], v[104:107]
	v_mfma_f32_16x16x32_f16 v[100:103], v[198:201], v[138:141], v[100:103]
	v_mfma_f32_16x16x32_f16 v[96:99], v[198:201], v[158:161], v[96:99]
	s_barrier
	ds_read_b128 v[146:149], v133 offset:16384
	ds_read_b128 v[202:205], v133 offset:17408
	ds_read_b128 v[206:209], v133 offset:18432
	ds_read_b128 v[210:213], v133 offset:19456
	s_barrier
;   #define LDA(dst,b,h) for(int m=0;m<4;++m)for(int k=0;k<2;++k) \
;     dst[m][k]=*reinterpret_cast<const h8*>(la+(((b)*2+(h))*16384+m*2048+k*1024))
;   #define LDB(dst,b,h) for(int n=0;n<2;++n)for(int k=0;k<2;++k) \
;     dst[n][k]=*reinterpret_cast<const h8*>(lb+(((b)*2+(h))*16384+n*2048+k*1024))
;   #define MMA(ai,bj,At,Bt_) do{__builtin_amdgcn_s_setprio(1); \
;     for(int m=0;m<4;++m)for(int n=0;n<2;++n)for(int k=0;k<2;++k) \
;       acc[ai][bj][m][n]=__builtin_amdgcn_mfma_f32_16x16x32_f16(At[m][k],Bt_[n][k],acc[ai][bj][m][n],0,0,0); \
;     __builtin_amdgcn_s_setprio(0);}while(0)
;   #define WAIT_V(n) asm volatile("s_waitcnt vmcnt(" #n ")":::"memory")
;   #define WAIT_L(n) asm volatile("s_waitcnt lgkmcnt(" #n ")":::"memory")
;   #define BAR __builtin_amdgcn_s_barrier()
;     ...
;     LDB(B1,0,1); BAR; WAIT_L(0); MMA(0,1,At,B1); BAR;
;     LDA(At,0,1); WAIT_V(4); BAR; WAIT_L(0); MMA(1,0,At,B0); MMA(1,1,At,B1); BAR; }
;   { LDB(B0,1,0); LDA(At,1,0); WAIT_V(2); BAR; WAIT_L(0); MMA(0,0,At,B0); BAR;
;     LDB(B1,1,1); WAIT_V(0); BAR; WAIT_L(0); MMA(0,1,At,B1); BAR;
	s_waitcnt lgkmcnt(0)
	s_waitcnt lgkmcnt(0)
	v_mfma_f32_16x16x32_f16 v[92:95], v[162:165], v[146:149], v[92:95]
	v_mfma_f32_16x16x32_f16 v[88:91], v[162:165], v[206:209], v[88:91]
	v_mfma_f32_16x16x32_f16 v[84:87], v[170:173], v[146:149], v[84:87]
	v_mfma_f32_16x16x32_f16 v[80:83], v[170:173], v[206:209], v[80:83]
	v_mfma_f32_16x16x32_f16 v[76:79], v[186:189], v[146:149], v[76:79]
	v_mfma_f32_16x16x32_f16 v[72:75], v[186:189], v[206:209], v[72:75]
	v_mfma_f32_16x16x32_f16 v[68:71], v[194:197], v[146:149], v[68:71]
	v_mfma_f32_16x16x32_f16 v[64:67], v[194:197], v[206:209], v[64:67]
	v_mfma_f32_16x16x32_f16 v[92:95], v[166:169], v[202:205], v[92:95]
	v_mfma_f32_16x16x32_f16 v[88:91], v[166:169], v[210:213], v[88:91]
	v_mfma_f32_16x16x32_f16 v[84:87], v[176:179], v[202:205], v[84:87]
	v_mfma_f32_16x16x32_f16 v[80:83], v[176:179], v[210:213], v[80:83]
	v_mfma_f32_16x16x32_f16 v[76:79], v[190:193], v[202:205], v[76:79]
	v_mfma_f32_16x16x32_f16 v[72:75], v[190:193], v[210:213], v[72:75]
	v_mfma_f32_16x16x32_f16 v[68:71], v[198:201], v[202:205], v[68:71]
	v_mfma_f32_16x16x32_f16 v[64:67], v[198:201], v[210:213], v[64:67]
	s_barrier
	ds_read_b128 v[162:165], v132 offset:16384
	ds_read_b128 v[166:169], v132 offset:17408
	ds_read_b128 v[170:173], v132 offset:18432
	ds_read_b128 v[176:179], v132 offset:19456
	ds_read_b128 v[186:189], v132 offset:20480
	ds_read_b128 v[190:193], v132 offset:21504
	ds_read_b128 v[194:197], v132 offset:22528
	ds_read_b128 v[198:201], v132 offset:23552
	s_waitcnt vmcnt(4)
	s_barrier
	s_waitcnt lgkmcnt(0)
	s_waitcnt lgkmcnt(0)
	v_mfma_f32_16x16x32_f16 v[60:63], v[162:165], v[134:137], v[60:63]
	v_mfma_f32_16x16x32_f16 v[56:59], v[162:165], v[142:145], v[56:59]
	v_mfma_f32_16x16x32_f16 v[52:55], v[170:173], v[134:137], v[52:55]
	v_mfma_f32_16x16x32_f16 v[48:51], v[170:173], v[142:145], v[48:51]
	v_mfma_f32_16x16x32_f16 v[44:47], v[186:189], v[134:137], v[44:47]
	v_mfma_f32_16x16x32_f16 v[40:43], v[186:189], v[142:145], v[40:43]
	v_mfma_f32_16x16x32_f16 v[36:39], v[194:197], v[134:137], v[36:39]
	v_mfma_f32_16x16x32_f16 v[32:35], v[194:197], v[142:145], v[32:35]
	v_mfma_f32_16x16x32_f16 v[60:63], v[166:169], v[138:141], v[60:63]
	v_mfma_f32_16x16x32_f16 v[56:59], v[166:169], v[158:161], v[56:59]
	v_mfma_f32_16x16x32_f16 v[52:55], v[176:179], v[138:141], v[52:55]
	v_mfma_f32_16x16x32_f16 v[48:51], v[176:179], v[158:161], v[48:51]
	v_mfma_f32_16x16x32_f16 v[44:47], v[190:193], v[138:141], v[44:47]
	v_mfma_f32_16x16x32_f16 v[40:43], v[190:193], v[158:161], v[40:43]
	v_mfma_f32_16x16x32_f16 v[36:39], v[198:201], v[138:141], v[36:39]
	v_mfma_f32_16x16x32_f16 v[32:35], v[198:201], v[158:161], v[32:35]
	v_mfma_f32_16x16x32_f16 v[28:31], v[162:165], v[146:149], v[28:31]
	v_mfma_f32_16x16x32_f16 v[24:27], v[162:165], v[206:209], v[24:27]
	v_mfma_f32_16x16x32_f16 v[20:23], v[170:173], v[146:149], v[20:23]
	v_mfma_f32_16x16x32_f16 v[16:19], v[170:173], v[206:209], v[16:19]
	v_mfma_f32_16x16x32_f16 v[12:15], v[186:189], v[146:149], v[12:15]
	v_mfma_f32_16x16x32_f16 v[8:11], v[186:189], v[206:209], v[8:11]
	v_mfma_f32_16x16x32_f16 v[4:7], v[194:197], v[146:149], v[4:7]
	v_mfma_f32_16x16x32_f16 v[0:3], v[194:197], v[206:209], v[0:3]
	v_mfma_f32_16x16x32_f16 v[28:31], v[166:169], v[202:205], v[28:31]
	v_mfma_f32_16x16x32_f16 v[24:27], v[166:169], v[210:213], v[24:27]
	v_mfma_f32_16x16x32_f16 v[20:23], v[176:179], v[202:205], v[20:23]
	v_mfma_f32_16x16x32_f16 v[16:19], v[176:179], v[210:213], v[16:19]
	v_mfma_f32_16x16x32_f16 v[12:15], v[190:193], v[202:205], v[12:15]
	v_mfma_f32_16x16x32_f16 v[8:11], v[190:193], v[210:213], v[8:11]
	v_mfma_f32_16x16x32_f16 v[4:7], v[198:201], v[202:205], v[4:7]
	v_mfma_f32_16x16x32_f16 v[0:3], v[198:201], v[210:213], v[0:3]
	s_barrier
	ds_read_b128 v[134:137], v133 offset:32768
	ds_read_b128 v[138:141], v133 offset:33792
	ds_read_b128 v[142:145], v133 offset:34816
	ds_read_b128 v[146:149], v133 offset:35840
	ds_read_b128 v[158:161], v132 offset:32768
	ds_read_b128 v[162:165], v132 offset:33792
	ds_read_b128 v[166:169], v132 offset:34816
	ds_read_b128 v[170:173], v132 offset:35840
	ds_read_b128 v[176:179], v132 offset:36864
	ds_read_b128 v[186:189], v132 offset:37888
	ds_read_b128 v[190:193], v132 offset:38912
	ds_read_b128 v[194:197], v132 offset:39936
	s_waitcnt vmcnt(2)
	s_barrier
;   #define LDA(dst,b,h) for(int m=0;m<4;++m)for(int k=0;k<2;++k) \
;     dst[m][k]=*reinterpret_cast<const h8*>(la+(((b)*2+(h))*16384+m*2048+k*1024))
;   #define LDB(dst,b,h) for(int n=0;n<2;++n)for(int k=0;k<2;++k) \
;     dst[n][k]=*reinterpret_cast<const h8*>(lb+(((b)*2+(h))*16384+n*2048+k*1024))
;   #define MMA(ai,bj,At,Bt_) do{__builtin_amdgcn_s_setprio(1); \
;     for(int m=0;m<4;++m)for(int n=0;n<2;++n)for(int k=0;k<2;++k) \
;       acc[ai][bj][m][n]=__builtin_amdgcn_mfma_f32_16x16x32_f16(At[m][k],Bt_[n][k],acc[ai][bj][m][n],0,0,0); \
;     __builtin_amdgcn_s_setprio(0);}while(0)
;   #define WAIT_V(n) asm volatile("s_waitcnt vmcnt(" #n ")":::"memory")
;   #define WAIT_L(n) asm volatile("s_waitcnt lgkmcnt(" #n ")":::"memory")
;   #define BAR __builtin_amdgcn_s_barrier()
;     ...
;   { LDB(B0,1,0); LDA(At,1,0); WAIT_V(2); BAR; WAIT_L(0); MMA(0,0,At,B0); BAR;
;     LDB(B1,1,1); WAIT_V(0); BAR; WAIT_L(0); MMA(0,1,At,B1); BAR;
;     LDA(At,1,1); BAR; WAIT_L(0); MMA(1,0,At,B0); MMA(1,1,At,B1); BAR; }
;   if(wr==0)BAR;
	s_waitcnt lgkmcnt(0)
	s_waitcnt lgkmcnt(0)
	v_mfma_f32_16x16x32_f16 v[124:127], v[158:161], v[134:137], v[124:127]
	v_mfma_f32_16x16x32_f16 v[120:123], v[158:161], v[142:145], v[120:123]
	v_mfma_f32_16x16x32_f16 v[116:119], v[166:169], v[134:137], v[116:119]
	v_mfma_f32_16x16x32_f16 v[112:115], v[166:169], v[142:145], v[112:115]
	v_mfma_f32_16x16x32_f16 v[108:111], v[176:179], v[134:137], v[108:111]
	v_mfma_f32_16x16x32_f16 v[104:107], v[176:179], v[142:145], v[104:107]
	v_mfma_f32_16x16x32_f16 v[100:103], v[190:193], v[134:137], v[100:103]
	v_mfma_f32_16x16x32_f16 v[96:99], v[190:193], v[142:145], v[96:99]
	v_mfma_f32_16x16x32_f16 v[124:127], v[162:165], v[138:141], v[124:127]
	v_mfma_f32_16x16x32_f16 v[120:123], v[162:165], v[146:149], v[120:123]
	v_mfma_f32_16x16x32_f16 v[116:119], v[170:173], v[138:141], v[116:119]
	v_mfma_f32_16x16x32_f16 v[112:115], v[170:173], v[146:149], v[112:115]
	v_mfma_f32_16x16x32_f16 v[108:111], v[186:189], v[138:141], v[108:111]
	v_mfma_f32_16x16x32_f16 v[104:107], v[186:189], v[146:149], v[104:107]
	v_mfma_f32_16x16x32_f16 v[100:103], v[194:197], v[138:141], v[100:103]
	v_mfma_f32_16x16x32_f16 v[96:99], v[194:197], v[146:149], v[96:99]
	s_barrier
	ds_read_b128 v[198:201], v133 offset:49152
	ds_read_b128 v[202:205], v133 offset:50176
	ds_read_b128 v[206:209], v133 offset:51200
	ds_read_b128 v[210:213], v133 offset:52224
	s_waitcnt vmcnt(0)
	s_barrier
	s_waitcnt lgkmcnt(0)
	s_waitcnt lgkmcnt(0)
	v_mfma_f32_16x16x32_f16 v[92:95], v[158:161], v[198:201], v[92:95]
	v_mfma_f32_16x16x32_f16 v[88:91], v[158:161], v[206:209], v[88:91]
	v_mfma_f32_16x16x32_f16 v[84:87], v[166:169], v[198:201], v[84:87]
	v_mfma_f32_16x16x32_f16 v[80:83], v[166:169], v[206:209], v[80:83]
	v_mfma_f32_16x16x32_f16 v[76:79], v[176:179], v[198:201], v[76:79]
	v_mfma_f32_16x16x32_f16 v[72:75], v[176:179], v[206:209], v[72:75]
	v_mfma_f32_16x16x32_f16 v[68:71], v[190:193], v[198:201], v[68:71]
	v_mfma_f32_16x16x32_f16 v[64:67], v[190:193], v[206:209], v[64:67]
	v_mfma_f32_16x16x32_f16 v[92:95], v[162:165], v[202:205], v[92:95]
	v_mfma_f32_16x16x32_f16 v[88:91], v[162:165], v[210:213], v[88:91]
	v_mfma_f32_16x16x32_f16 v[84:87], v[170:173], v[202:205], v[84:87]
	v_mfma_f32_16x16x32_f16 v[80:83], v[170:173], v[210:213], v[80:83]
	v_mfma_f32_16x16x32_f16 v[76:79], v[186:189], v[202:205], v[76:79]
	v_mfma_f32_16x16x32_f16 v[72:75], v[186:189], v[210:213], v[72:75]
	v_mfma_f32_16x16x32_f16 v[68:71], v[194:197], v[202:205], v[68:71]
	v_mfma_f32_16x16x32_f16 v[64:67], v[194:197], v[210:213], v[64:67]
	s_barrier
	ds_read_b128 v[158:161], v132 offset:49152
	ds_read_b128 v[162:165], v132 offset:50176
	ds_read_b128 v[166:169], v132 offset:51200
	ds_read_b128 v[170:173], v132 offset:52224
	ds_read_b128 v[176:179], v132 offset:53248
	ds_read_b128 v[186:189], v132 offset:54272
	ds_read_b128 v[190:193], v132 offset:55296
	ds_read_b128 v[194:197], v132 offset:56320
	s_barrier
	s_waitcnt lgkmcnt(0)
	s_waitcnt lgkmcnt(0)
	v_mfma_f32_16x16x32_f16 v[60:63], v[158:161], v[134:137], v[60:63]
	v_mfma_f32_16x16x32_f16 v[56:59], v[158:161], v[142:145], v[56:59]
	v_mfma_f32_16x16x32_f16 v[52:55], v[166:169], v[134:137], v[52:55]
	v_mfma_f32_16x16x32_f16 v[48:51], v[166:169], v[142:145], v[48:51]
	v_mfma_f32_16x16x32_f16 v[44:47], v[176:179], v[134:137], v[44:47]
	v_mfma_f32_16x16x32_f16 v[40:43], v[176:179], v[142:145], v[40:43]
	v_mfma_f32_16x16x32_f16 v[36:39], v[190:193], v[134:137], v[36:39]
	v_mfma_f32_16x16x32_f16 v[32:35], v[190:193], v[142:145], v[32:35]
	v_mfma_f32_16x16x32_f16 v[60:63], v[162:165], v[138:141], v[60:63]
	v_mfma_f32_16x16x32_f16 v[56:59], v[162:165], v[146:149], v[56:59]
	v_mfma_f32_16x16x32_f16 v[52:55], v[170:173], v[138:141], v[52:55]
	v_mfma_f32_16x16x32_f16 v[48:51], v[170:173], v[146:149], v[48:51]
	v_mfma_f32_16x16x32_f16 v[44:47], v[186:189], v[138:141], v[44:47]
	v_mfma_f32_16x16x32_f16 v[40:43], v[186:189], v[146:149], v[40:43]
	v_mfma_f32_16x16x32_f16 v[36:39], v[194:197], v[138:141], v[36:39]
	v_mfma_f32_16x16x32_f16 v[32:35], v[194:197], v[146:149], v[32:35]
	v_mfma_f32_16x16x32_f16 v[28:31], v[158:161], v[198:201], v[28:31]
	v_mfma_f32_16x16x32_f16 v[24:27], v[158:161], v[206:209], v[24:27]
	v_mfma_f32_16x16x32_f16 v[20:23], v[166:169], v[198:201], v[20:23]
	v_mfma_f32_16x16x32_f16 v[16:19], v[166:169], v[206:209], v[16:19]
	v_mfma_f32_16x16x32_f16 v[12:15], v[176:179], v[198:201], v[12:15]
	v_mfma_f32_16x16x32_f16 v[8:11], v[176:179], v[206:209], v[8:11]
	v_mfma_f32_16x16x32_f16 v[4:7], v[190:193], v[198:201], v[4:7]
	v_mfma_f32_16x16x32_f16 v[0:3], v[190:193], v[206:209], v[0:3]
	v_mfma_f32_16x16x32_f16 v[28:31], v[162:165], v[202:205], v[28:31]
	v_mfma_f32_16x16x32_f16 v[24:27], v[162:165], v[210:213], v[24:27]
	v_mfma_f32_16x16x32_f16 v[20:23], v[170:173], v[202:205], v[20:23]
	v_mfma_f32_16x16x32_f16 v[16:19], v[170:173], v[210:213], v[16:19]
	v_mfma_f32_16x16x32_f16 v[12:15], v[186:189], v[202:205], v[12:15]
	v_mfma_f32_16x16x32_f16 v[8:11], v[186:189], v[210:213], v[8:11]
	v_mfma_f32_16x16x32_f16 v[4:7], v[194:197], v[202:205], v[4:7]
	v_mfma_f32_16x16x32_f16 v[0:3], v[194:197], v[210:213], v[0:3]
	s_movk_i32 s6, 0x100
	v_cmp_gt_u32_e32 vcc, s6, v131
	s_barrier
	s_and_saveexec_b64 s[6:7], vcc
	s_cbranch_execz .LBB0_669
	s_barrier
